# GEMM K-loops: redundant s_waitcnt lgkmcnt(0) after the pre-MFMA barrier removed (the same wait precedes the barrier)
# speedup vs baseline: 1.0046x; 1.0046x over previous
;     __host__ __device__ bool next(int i, Unit& u) const { const bool ok = StaticOrder::next(i, u); u.pm = 0; u.pn = 0; return ok; }
; #define PG8_STAGE(bufoff, gbase, voff) do { _Pragma("unroll") for (int _i = 0; _i < 2; ++_i) \
;         __builtin_amdgcn_global_load_lds((const unsigned*)((const char*)(gbase) + (voff)[_i]), (PG8_LAS unsigned*)(lds + (bufoff) + ldsw + _i * 8192), 16, 0, 0); } while (0)
; #define PG8_WAIT_V(n) asm volatile("s_waitcnt vmcnt(" #n ")" ::: "memory")
; template <class Epi, class Sched, bool ALIGN_EPI = false, bool SP2 = false>
; __device__ __forceinline__ void gemm_phase(PG8_LAS unsigned char* lds, const Gemm g, const Sched& S, const Epi& E, const int wave_in) {
;     ...
;         const bool has_next = S.next(ui + 1, nxt);
;         const char* nA = has_next ? (const char*)g.A + (size_t)nxt.pm * tstepA : cA; const char* nB = has_next ? (const char*)g.Bt + (size_t)nxt.pn * tstepB : cB;
;         for (int t = 0; t < nt; t += 2) {
;             const bool last = (t == nt - 2);
;             const char* a1 = cA + (size_t)(t + 1) * kstep;
;             const char* a2 = last ? nA : cA + (size_t)(t + 2) * kstep; const char* b2 = last ? nB : cB + (size_t)(t + 2) * kstep;
;             const char* a3 = a2 + kstep; const char* b3 = b2 + kstep;
;             if (last && has_next) S.a_ready(nxt);
;             if constexpr (SP2) {
;             PG8_LDB(B0, 0, 0); PG8_LDB(B1, 0, 1); PG8_SCHED; PG8_LDA(At, 0, 0); PG8_STAGE(PG8_SA(1, 1), a1 + hstepA, voffA);
;             PG8_WAIT_V(8); PG8_WAIT_L(0); PG8_BAR; PG8_MMA(0, 0, At, B0); PG8_MMA(0, 1, At, B1); PG8_BAR; PG8_SCHED;
;             PG8_LDA(At, 0, 1); PG8_STAGE(PG8_SB(0, 0), b2, voffB); PG8_STAGE(PG8_SB(0, 1), b2 + hstepB, voffB); PG8_STAGE(PG8_SA(0, 0), a2, voffA);
;             PG8_WAIT_V(8); PG8_WAIT_L(0); PG8_BAR; PG8_MMA(1, 0, At, B0); PG8_MMA(1, 1, At, B1); PG8_BAR; PG8_SCHED;
;             PG8_LDB(B0, 1, 0); PG8_LDB(B1, 1, 1); PG8_SCHED; PG8_LDA(At, 1, 0); PG8_STAGE(PG8_SA(0, 1), a2 + hstepA, voffA);
;             PG8_WAIT_V(8); PG8_WAIT_L(0); PG8_BAR; PG8_MMA(0, 0, At, B0); PG8_MMA(0, 1, At, B1); PG8_BAR; PG8_SCHED;
;             PG8_LDA(At, 1, 1); PG8_STAGE(PG8_SB(1, 0), b3, voffB); PG8_STAGE(PG8_SB(1, 1), b3 + hstepB, voffB); PG8_STAGE(PG8_SA(1, 0), a3, voffA);
;             PG8_WAIT_V(8); PG8_WAIT_L(0); PG8_BAR; PG8_MMA(1, 0, At, B0); PG8_MMA(1, 1, At, B1); PG8_BAR; PG8_SCHED;
.LBB0_157:
	s_ashr_i32 s15, s14, 31
	s_lshl_b64 s[16:17], s[14:15], 20
	s_add_u32 s16, s28, s16
	s_addc_u32 s17, s29, s17
	s_and_b64 s[18:19], s[2:3], exec
	s_cselect_b32 s5, s17, s23
	s_cselect_b32 s15, s16, s22
	s_ashr_i32 s13, s12, 31
	s_lshl_b64 s[18:19], s[12:13], 20
	s_add_u32 s18, s30, s18
	s_addc_u32 s19, s31, s19
	s_and_b64 s[26:27], s[2:3], exec
	s_cselect_b32 s13, s19, s25
	s_cselect_b32 s46, s18, s24
	s_add_u32 s22, s22, 0x80080
	s_addc_u32 s23, s23, 0
	s_add_u32 s47, s24, 0x100
	v_mov_b32_e32 v0, 0
	s_addc_u32 s48, s25, 0
	s_mov_b32 s49, -2
	ds_read_b128 v[144:147], v151
	ds_read_b128 v[154:157], v151 offset:1024
	ds_read_b128 v[158:161], v151 offset:2048
	ds_read_b128 v[162:165], v151 offset:3072
	ds_read_b128 v[166:169], v152
	ds_read_b128 v[170:173], v152 offset:1024
	ds_read_b128 v[174:177], v152 offset:2048
	ds_read_b128 v[178:181], v152 offset:3072
	s_add_u32 s24, s22, 0xfff80080
	s_addc_u32 s25, s23, -1
	s_cmp_eq_u32 s49, 28
	s_cselect_b32 s27, s5, s25
	s_cselect_b32 s26, s15, s24
	s_cselect_b32 s25, s13, s48
	s_cselect_b32 s24, s46, s47
	v_lshl_add_u64 v[214:215], s[22:23], 0, v[136:137]
	s_add_i32 m0, s21, 0xc000
	ds_read_b128 v[182:185], v153
	ds_read_b128 v[186:189], v153 offset:1024
	ds_read_b128 v[190:193], v153 offset:2048
	ds_read_b128 v[194:197], v153 offset:3072
	ds_read_b128 v[198:201], v153 offset:4096
	ds_read_b128 v[202:205], v153 offset:5120
	ds_read_b128 v[206:209], v153 offset:6144
	ds_read_b128 v[210:213], v153 offset:7168
	global_load_lds_dwordx4 v[214:215], off
	v_lshl_add_u64 v[214:215], s[22:23], 0, v[138:139]
	s_add_i32 m0, s21, 0xe000
	s_nop 0
	global_load_lds_dwordx4 v[214:215], off
	s_waitcnt vmcnt(8)
	s_waitcnt lgkmcnt(0)
	s_barrier
	s_setprio 1
	v_mfma_f32_16x16x32_bf16 v[124:127], v[144:147], v[182:185], 0
	v_mfma_f32_16x16x32_bf16 v[120:123], v[158:161], v[182:185], 0
	v_mfma_f32_16x16x32_bf16 v[108:111], v[144:147], v[190:193], 0
	v_mfma_f32_16x16x32_bf16 v[104:107], v[158:161], v[190:193], 0
	v_mfma_f32_16x16x32_bf16 v[92:95], v[144:147], v[198:201], 0
	v_mfma_f32_16x16x32_bf16 v[88:91], v[158:161], v[198:201], 0
	v_mfma_f32_16x16x32_bf16 v[76:79], v[144:147], v[206:209], 0
	v_mfma_f32_16x16x32_bf16 v[72:75], v[158:161], v[206:209], 0
	v_mfma_f32_16x16x32_bf16 v[124:127], v[154:157], v[186:189], v[124:127]
	v_mfma_f32_16x16x32_bf16 v[120:123], v[162:165], v[186:189], v[120:123]
	v_mfma_f32_16x16x32_bf16 v[108:111], v[154:157], v[194:197], v[108:111]
	v_mfma_f32_16x16x32_bf16 v[104:107], v[162:165], v[194:197], v[104:107]
	v_mfma_f32_16x16x32_bf16 v[92:95], v[154:157], v[202:205], v[92:95]
	v_mfma_f32_16x16x32_bf16 v[88:91], v[162:165], v[202:205], v[88:91]
	v_mfma_f32_16x16x32_bf16 v[76:79], v[154:157], v[210:213], v[76:79]
	v_mfma_f32_16x16x32_bf16 v[72:75], v[162:165], v[210:213], v[72:75]
	v_mfma_f32_16x16x32_bf16 v[116:119], v[166:169], v[182:185], 0
	v_mfma_f32_16x16x32_bf16 v[112:115], v[174:177], v[182:185], 0
	v_mfma_f32_16x16x32_bf16 v[100:103], v[166:169], v[190:193], 0
	v_mfma_f32_16x16x32_bf16 v[96:99], v[174:177], v[190:193], 0
	v_mfma_f32_16x16x32_bf16 v[84:87], v[166:169], v[198:201], 0
	v_mfma_f32_16x16x32_bf16 v[80:83], v[174:177], v[198:201], 0
	v_mfma_f32_16x16x32_bf16 v[68:71], v[166:169], v[206:209], 0
	v_mfma_f32_16x16x32_bf16 v[64:67], v[174:177], v[206:209], 0
	v_mfma_f32_16x16x32_bf16 v[116:119], v[170:173], v[186:189], v[116:119]
	v_mfma_f32_16x16x32_bf16 v[112:115], v[178:181], v[186:189], v[112:115]
	v_mfma_f32_16x16x32_bf16 v[100:103], v[170:173], v[194:197], v[100:103]
	v_mfma_f32_16x16x32_bf16 v[96:99], v[178:181], v[194:197], v[96:99]
	v_mfma_f32_16x16x32_bf16 v[84:87], v[170:173], v[202:205], v[84:87]
	v_mfma_f32_16x16x32_bf16 v[80:83], v[178:181], v[202:205], v[80:83]
	v_mfma_f32_16x16x32_bf16 v[68:71], v[170:173], v[210:213], v[68:71]
	v_mfma_f32_16x16x32_bf16 v[64:67], v[178:181], v[210:213], v[64:67]
	s_setprio 0
	s_barrier
	s_add_i32 s50, s43, s34
	v_lshl_add_u64 v[214:215], s[24:25], 0, v[130:131]
	s_mov_b32 m0, s50
	ds_read_b128 v[182:185], v153 offset:16384
	ds_read_b128 v[186:189], v153 offset:17408
	ds_read_b128 v[190:193], v153 offset:18432
	ds_read_b128 v[194:197], v153 offset:19456
	ds_read_b128 v[198:201], v153 offset:20480
	ds_read_b128 v[202:205], v153 offset:21504
	ds_read_b128 v[206:209], v153 offset:22528
	ds_read_b128 v[210:213], v153 offset:23552
	global_load_lds_dwordx4 v[214:215], off
	s_add_i32 m0, s50, 0x2000
	s_add_u32 s50, s24, 0x80000
	v_lshl_add_u64 v[216:217], s[24:25], 0, v[134:135]
	s_addc_u32 s51, s25, 0
	s_add_i32 s52, s44, s34
	global_load_lds_dwordx4 v[216:217], off
	v_lshl_add_u64 v[218:219], s[50:51], 0, v[130:131]
	s_mov_b32 m0, s52
	v_lshl_add_u64 v[220:221], s[26:27], 0, v[132:133]
	global_load_lds_dwordx4 v[218:219], off
	v_lshl_add_u64 v[218:219], s[50:51], 0, v[134:135]
	s_add_i32 m0, s52, 0x2000
	s_nop 0
	global_load_lds_dwordx4 v[218:219], off
	v_lshl_add_u64 v[218:219], s[26:27], 0, v[128:129]
	s_mov_b32 m0, s21
	s_nop 0
	global_load_lds_dwordx4 v[218:219], off
	s_mov_b32 m0, s35
	s_nop 0
	global_load_lds_dwordx4 v[220:221], off
	s_waitcnt vmcnt(8)
	s_waitcnt lgkmcnt(0)
	s_barrier
; #define PG8_STAGE(bufoff, gbase, voff) do { _Pragma("unroll") for (int _i = 0; _i < 2; ++_i) \
;         __builtin_amdgcn_global_load_lds((const unsigned*)((const char*)(gbase) + (voff)[_i]), (PG8_LAS unsigned*)(lds + (bufoff) + ldsw + _i * 8192), 16, 0, 0); } while (0)
; #define PG8_LDA(dst, b, h) do { _Pragma("unroll") for (int m = 0; m < 4; ++m) _Pragma("unroll") for (int k = 0; k < 2; ++k) dst[m][k] = *(const PG8_LAS bf16x8*)(lds + PG8_SA(b, h) + aoff + m * 2048 + k * 1024); } while (0)
; #define PG8_WAIT_V(n) asm volatile("s_waitcnt vmcnt(" #n ")" ::: "memory")
; #define PG8_WAIT_L(n) asm volatile("s_waitcnt lgkmcnt(" #n ")" ::: "memory")
; #define PG8_BAR __builtin_amdgcn_s_barrier()
; template <class Epi, class Sched, bool ALIGN_EPI = false, bool SP2 = false>
; __device__ __forceinline__ void gemm_phase(PG8_LAS unsigned char* lds, const Gemm g, const Sched& S, const Epi& E, const int wave_in) {
;     ...
;         for (int t = 0; t < nt; t += 2) {
;             const bool last = (t == nt - 2);
;             const char* a1 = cA + (size_t)(t + 1) * kstep;
;             const char* a2 = last ? nA : cA + (size_t)(t + 2) * kstep; const char* b2 = last ? nB : cB + (size_t)(t + 2) * kstep;
;             const char* a3 = a2 + kstep; const char* b3 = b2 + kstep;
;             if (last && has_next) S.a_ready(nxt);
;             if constexpr (SP2) {
;             PG8_LDB(B0, 0, 0); PG8_LDB(B1, 0, 1); PG8_SCHED; PG8_LDA(At, 0, 0); PG8_STAGE(PG8_SA(1, 1), a1 + hstepA, voffA);
;             PG8_WAIT_V(8); PG8_WAIT_L(0); PG8_BAR; PG8_MMA(0, 0, At, B0); PG8_MMA(0, 1, At, B1); PG8_BAR; PG8_SCHED;
;             PG8_LDA(At, 0, 1); PG8_STAGE(PG8_SB(0, 0), b2, voffB); PG8_STAGE(PG8_SB(0, 1), b2 + hstepB, voffB); PG8_STAGE(PG8_SA(0, 0), a2, voffA);
;             PG8_WAIT_V(8); PG8_WAIT_L(0); PG8_BAR; PG8_MMA(1, 0, At, B0); PG8_MMA(1, 1, At, B1); PG8_BAR; PG8_SCHED;
;             PG8_LDB(B0, 1, 0); PG8_LDB(B1, 1, 1); PG8_SCHED; PG8_LDA(At, 1, 0); PG8_STAGE(PG8_SA(0, 1), a2 + hstepA, voffA);
;             PG8_WAIT_V(8); PG8_WAIT_L(0); PG8_BAR; PG8_MMA(0, 0, At, B0); PG8_MMA(0, 1, At, B1); PG8_BAR; PG8_SCHED;
;             PG8_LDA(At, 1, 1); PG8_STAGE(PG8_SB(1, 0), b3, voffB); PG8_STAGE(PG8_SB(1, 1), b3 + hstepB, voffB); PG8_STAGE(PG8_SA(1, 0), a3, voffA);
;             PG8_WAIT_V(8); PG8_WAIT_L(0); PG8_BAR; PG8_MMA(1, 0, At, B0); PG8_MMA(1, 1, At, B1); PG8_BAR; PG8_SCHED;
	s_setprio 1
	v_mfma_f32_16x16x32_bf16 v[60:63], v[144:147], v[182:185], 0
	v_mfma_f32_16x16x32_bf16 v[56:59], v[158:161], v[182:185], 0
	v_mfma_f32_16x16x32_bf16 v[44:47], v[144:147], v[190:193], 0
	v_mfma_f32_16x16x32_bf16 v[40:43], v[158:161], v[190:193], 0
	v_mfma_f32_16x16x32_bf16 v[28:31], v[144:147], v[198:201], 0
	v_mfma_f32_16x16x32_bf16 v[24:27], v[158:161], v[198:201], 0
	v_mfma_f32_16x16x32_bf16 v[12:15], v[144:147], v[206:209], 0
	v_mfma_f32_16x16x32_bf16 v[8:11], v[158:161], v[206:209], 0
	v_mfma_f32_16x16x32_bf16 v[60:63], v[154:157], v[186:189], v[60:63]
	v_mfma_f32_16x16x32_bf16 v[56:59], v[162:165], v[186:189], v[56:59]
	v_mfma_f32_16x16x32_bf16 v[44:47], v[154:157], v[194:197], v[44:47]
	v_mfma_f32_16x16x32_bf16 v[40:43], v[162:165], v[194:197], v[40:43]
	v_mfma_f32_16x16x32_bf16 v[28:31], v[154:157], v[202:205], v[28:31]
	v_mfma_f32_16x16x32_bf16 v[24:27], v[162:165], v[202:205], v[24:27]
	v_mfma_f32_16x16x32_bf16 v[12:15], v[154:157], v[210:213], v[12:15]
	v_mfma_f32_16x16x32_bf16 v[8:11], v[162:165], v[210:213], v[8:11]
	v_mfma_f32_16x16x32_bf16 v[52:55], v[166:169], v[182:185], 0
	v_mfma_f32_16x16x32_bf16 v[48:51], v[174:177], v[182:185], 0
	v_mfma_f32_16x16x32_bf16 v[36:39], v[166:169], v[190:193], 0
	v_mfma_f32_16x16x32_bf16 v[32:35], v[174:177], v[190:193], 0
	v_mfma_f32_16x16x32_bf16 v[20:23], v[166:169], v[198:201], 0
	v_mfma_f32_16x16x32_bf16 v[16:19], v[174:177], v[198:201], 0
	v_mfma_f32_16x16x32_bf16 v[4:7], v[166:169], v[206:209], 0
	v_mfma_f32_16x16x32_bf16 v[0:3], v[174:177], v[206:209], 0
	v_mfma_f32_16x16x32_bf16 v[52:55], v[170:173], v[186:189], v[52:55]
	v_mfma_f32_16x16x32_bf16 v[48:51], v[178:181], v[186:189], v[48:51]
	v_mfma_f32_16x16x32_bf16 v[36:39], v[170:173], v[194:197], v[36:39]
	v_mfma_f32_16x16x32_bf16 v[32:35], v[178:181], v[194:197], v[32:35]
	v_mfma_f32_16x16x32_bf16 v[20:23], v[170:173], v[202:205], v[20:23]
	v_mfma_f32_16x16x32_bf16 v[16:19], v[178:181], v[202:205], v[16:19]
	v_mfma_f32_16x16x32_bf16 v[4:7], v[170:173], v[210:213], v[4:7]
	v_mfma_f32_16x16x32_bf16 v[0:3], v[178:181], v[210:213], v[0:3]
	s_setprio 0
	s_barrier
	s_add_i32 s50, 0, 0x18000
	s_add_i32 s51, 0, 0x1c000
	v_add_u32_e32 v162, s50, v149
	v_add_u32_e32 v178, s51, v149
	ds_read_b128 v[144:147], v162
	ds_read_b128 v[154:157], v162 offset:1024
	ds_read_b128 v[158:161], v162 offset:2048
	ds_read_b128 v[162:165], v162 offset:3072
	ds_read_b128 v[166:169], v178
	ds_read_b128 v[170:173], v178 offset:1024
	ds_read_b128 v[174:177], v178 offset:2048
	ds_read_b128 v[178:181], v178 offset:3072
	s_add_u32 s26, s26, 0x80000
	s_addc_u32 s27, s27, 0
	s_mov_b32 m0, s36
	v_lshl_add_u64 v[222:223], s[26:27], 0, v[128:129]
	ds_read_b128 v[182:185], v153 offset:32768
	ds_read_b128 v[186:189], v153 offset:33792
	ds_read_b128 v[190:193], v153 offset:34816
	ds_read_b128 v[194:197], v153 offset:35840
	ds_read_b128 v[198:201], v153 offset:36864
	ds_read_b128 v[202:205], v153 offset:37888
	ds_read_b128 v[206:209], v153 offset:38912
	ds_read_b128 v[210:213], v153 offset:39936
	global_load_lds_dwordx4 v[222:223], off
	v_lshl_add_u64 v[222:223], s[26:27], 0, v[132:133]
	s_mov_b32 m0, s37
	s_nop 0
	global_load_lds_dwordx4 v[222:223], off
	s_waitcnt vmcnt(8)
	s_waitcnt lgkmcnt(0)
	s_barrier
	s_setprio 1
	v_mfma_f32_16x16x32_bf16 v[124:127], v[144:147], v[182:185], v[124:127]
	v_mfma_f32_16x16x32_bf16 v[120:123], v[158:161], v[182:185], v[120:123]
	v_mfma_f32_16x16x32_bf16 v[108:111], v[144:147], v[190:193], v[108:111]
	v_mfma_f32_16x16x32_bf16 v[104:107], v[158:161], v[190:193], v[104:107]
	v_mfma_f32_16x16x32_bf16 v[92:95], v[144:147], v[198:201], v[92:95]
	v_mfma_f32_16x16x32_bf16 v[88:91], v[158:161], v[198:201], v[88:91]
	v_mfma_f32_16x16x32_bf16 v[76:79], v[144:147], v[206:209], v[76:79]
	v_mfma_f32_16x16x32_bf16 v[72:75], v[158:161], v[206:209], v[72:75]
	v_mfma_f32_16x16x32_bf16 v[124:127], v[154:157], v[186:189], v[124:127]
	v_mfma_f32_16x16x32_bf16 v[120:123], v[162:165], v[186:189], v[120:123]
	v_mfma_f32_16x16x32_bf16 v[108:111], v[154:157], v[194:197], v[108:111]
	v_mfma_f32_16x16x32_bf16 v[104:107], v[162:165], v[194:197], v[104:107]
	v_mfma_f32_16x16x32_bf16 v[92:95], v[154:157], v[202:205], v[92:95]
	v_mfma_f32_16x16x32_bf16 v[88:91], v[162:165], v[202:205], v[88:91]
	v_mfma_f32_16x16x32_bf16 v[76:79], v[154:157], v[210:213], v[76:79]
	v_mfma_f32_16x16x32_bf16 v[72:75], v[162:165], v[210:213], v[72:75]
	v_mfma_f32_16x16x32_bf16 v[116:119], v[166:169], v[182:185], v[116:119]
	v_mfma_f32_16x16x32_bf16 v[112:115], v[174:177], v[182:185], v[112:115]
	v_mfma_f32_16x16x32_bf16 v[100:103], v[166:169], v[190:193], v[100:103]
	v_mfma_f32_16x16x32_bf16 v[96:99], v[174:177], v[190:193], v[96:99]
	v_mfma_f32_16x16x32_bf16 v[84:87], v[166:169], v[198:201], v[84:87]
	v_mfma_f32_16x16x32_bf16 v[80:83], v[174:177], v[198:201], v[80:83]
	v_mfma_f32_16x16x32_bf16 v[68:71], v[166:169], v[206:209], v[68:71]
	v_mfma_f32_16x16x32_bf16 v[64:67], v[174:177], v[206:209], v[64:67]
	v_mfma_f32_16x16x32_bf16 v[116:119], v[170:173], v[186:189], v[116:119]
	v_mfma_f32_16x16x32_bf16 v[112:115], v[178:181], v[186:189], v[112:115]
	v_mfma_f32_16x16x32_bf16 v[100:103], v[170:173], v[194:197], v[100:103]
	v_mfma_f32_16x16x32_bf16 v[96:99], v[178:181], v[194:197], v[96:99]
	v_mfma_f32_16x16x32_bf16 v[84:87], v[170:173], v[202:205], v[84:87]
	v_mfma_f32_16x16x32_bf16 v[80:83], v[178:181], v[202:205], v[80:83]
	v_mfma_f32_16x16x32_bf16 v[68:71], v[170:173], v[210:213], v[68:71]
	v_mfma_f32_16x16x32_bf16 v[64:67], v[178:181], v[210:213], v[64:67]
	s_setprio 0
	s_barrier
; #define PG8_STAGE(bufoff, gbase, voff) do { _Pragma("unroll") for (int _i = 0; _i < 2; ++_i) \
;         __builtin_amdgcn_global_load_lds((const unsigned*)((const char*)(gbase) + (voff)[_i]), (PG8_LAS unsigned*)(lds + (bufoff) + ldsw + _i * 8192), 16, 0, 0); } while (0)
; #define PG8_LDA(dst, b, h) do { _Pragma("unroll") for (int m = 0; m < 4; ++m) _Pragma("unroll") for (int k = 0; k < 2; ++k) dst[m][k] = *(const PG8_LAS bf16x8*)(lds + PG8_SA(b, h) + aoff + m * 2048 + k * 1024); } while (0)
; #define PG8_WAIT_V(n) asm volatile("s_waitcnt vmcnt(" #n ")" ::: "memory")
; #define PG8_WAIT_L(n) asm volatile("s_waitcnt lgkmcnt(" #n ")" ::: "memory")
; #define PG8_BAR __builtin_amdgcn_s_barrier()
; template <class Epi, class Sched, bool ALIGN_EPI = false, bool SP2 = false>
; __device__ __forceinline__ void gemm_phase(PG8_LAS unsigned char* lds, const Gemm g, const Sched& S, const Epi& E, const int wave_in) {
;     ...
;         for (int t = 0; t < nt; t += 2) {
;             const bool last = (t == nt - 2);
;             const char* a1 = cA + (size_t)(t + 1) * kstep;
;             const char* a2 = last ? nA : cA + (size_t)(t + 2) * kstep; const char* b2 = last ? nB : cB + (size_t)(t + 2) * kstep;
;             const char* a3 = a2 + kstep; const char* b3 = b2 + kstep;
;             if (last && has_next) S.a_ready(nxt);
;             if constexpr (SP2) {
;             PG8_LDB(B0, 0, 0); PG8_LDB(B1, 0, 1); PG8_SCHED; PG8_LDA(At, 0, 0); PG8_STAGE(PG8_SA(1, 1), a1 + hstepA, voffA);
;             PG8_WAIT_V(8); PG8_WAIT_L(0); PG8_BAR; PG8_MMA(0, 0, At, B0); PG8_MMA(0, 1, At, B1); PG8_BAR; PG8_SCHED;
;             PG8_LDA(At, 0, 1); PG8_STAGE(PG8_SB(0, 0), b2, voffB); PG8_STAGE(PG8_SB(0, 1), b2 + hstepB, voffB); PG8_STAGE(PG8_SA(0, 0), a2, voffA);
;             PG8_WAIT_V(8); PG8_WAIT_L(0); PG8_BAR; PG8_MMA(1, 0, At, B0); PG8_MMA(1, 1, At, B1); PG8_BAR; PG8_SCHED;
;             PG8_LDB(B0, 1, 0); PG8_LDB(B1, 1, 1); PG8_SCHED; PG8_LDA(At, 1, 0); PG8_STAGE(PG8_SA(0, 1), a2 + hstepA, voffA);
;             PG8_WAIT_V(8); PG8_WAIT_L(0); PG8_BAR; PG8_MMA(0, 0, At, B0); PG8_MMA(0, 1, At, B1); PG8_BAR; PG8_SCHED;
;             PG8_LDA(At, 1, 1); PG8_STAGE(PG8_SB(1, 0), b3, voffB); PG8_STAGE(PG8_SB(1, 1), b3 + hstepB, voffB); PG8_STAGE(PG8_SA(1, 0), a3, voffA);
;             PG8_WAIT_V(8); PG8_WAIT_L(0); PG8_BAR; PG8_MMA(1, 0, At, B0); PG8_MMA(1, 1, At, B1); PG8_BAR; PG8_SCHED;
	s_add_i32 s26, s50, s34
	v_lshl_add_u64 v[214:215], v[214:215], 0, s[8:9]
	s_mov_b32 m0, s26
	ds_read_b128 v[182:185], v153 offset:49152
	ds_read_b128 v[186:189], v153 offset:50176
	ds_read_b128 v[190:193], v153 offset:51200
	ds_read_b128 v[194:197], v153 offset:52224
	ds_read_b128 v[198:201], v153 offset:53248
	ds_read_b128 v[202:205], v153 offset:54272
	ds_read_b128 v[206:209], v153 offset:55296
	ds_read_b128 v[210:213], v153 offset:56320
	global_load_lds_dwordx4 v[214:215], off
	s_add_i32 m0, s26, 0x2000
	s_add_u32 s24, s24, 0x80080
	v_lshl_add_u64 v[214:215], v[216:217], 0, s[8:9]
	s_addc_u32 s25, s25, 0
	s_add_i32 s26, s51, s34
	global_load_lds_dwordx4 v[214:215], off
	v_lshl_add_u64 v[214:215], s[24:25], 0, v[130:131]
	s_mov_b32 m0, s26
	s_nop 0
	global_load_lds_dwordx4 v[214:215], off
	v_lshl_add_u64 v[214:215], s[24:25], 0, v[134:135]
	s_add_i32 m0, s26, 0x2000
	s_nop 0
	global_load_lds_dwordx4 v[214:215], off
	v_lshl_add_u64 v[214:215], v[218:219], 0, s[8:9]
	s_mov_b32 m0, s39
	s_nop 0
	global_load_lds_dwordx4 v[214:215], off
	v_lshl_add_u64 v[214:215], v[220:221], 0, s[8:9]
	s_mov_b32 m0, s40
	s_nop 0
	global_load_lds_dwordx4 v[214:215], off
	s_waitcnt vmcnt(8)
	s_waitcnt lgkmcnt(0)
	s_barrier
	s_setprio 1
	v_mfma_f32_16x16x32_bf16 v[60:63], v[144:147], v[182:185], v[60:63]
	v_mfma_f32_16x16x32_bf16 v[56:59], v[158:161], v[182:185], v[56:59]
	v_mfma_f32_16x16x32_bf16 v[44:47], v[144:147], v[190:193], v[44:47]
	v_mfma_f32_16x16x32_bf16 v[40:43], v[158:161], v[190:193], v[40:43]
	v_mfma_f32_16x16x32_bf16 v[28:31], v[144:147], v[198:201], v[28:31]
	v_mfma_f32_16x16x32_bf16 v[24:27], v[158:161], v[198:201], v[24:27]
	v_mfma_f32_16x16x32_bf16 v[12:15], v[144:147], v[206:209], v[12:15]
	v_mfma_f32_16x16x32_bf16 v[8:11], v[158:161], v[206:209], v[8:11]
	v_mfma_f32_16x16x32_bf16 v[60:63], v[154:157], v[186:189], v[60:63]
	v_mfma_f32_16x16x32_bf16 v[56:59], v[162:165], v[186:189], v[56:59]
	v_mfma_f32_16x16x32_bf16 v[44:47], v[154:157], v[194:197], v[44:47]
	v_mfma_f32_16x16x32_bf16 v[40:43], v[162:165], v[194:197], v[40:43]
	v_mfma_f32_16x16x32_bf16 v[28:31], v[154:157], v[202:205], v[28:31]
	v_mfma_f32_16x16x32_bf16 v[24:27], v[162:165], v[202:205], v[24:27]
	v_mfma_f32_16x16x32_bf16 v[12:15], v[154:157], v[210:213], v[12:15]
	v_mfma_f32_16x16x32_bf16 v[8:11], v[162:165], v[210:213], v[8:11]
	v_mfma_f32_16x16x32_bf16 v[52:55], v[166:169], v[182:185], v[52:55]
	v_mfma_f32_16x16x32_bf16 v[48:51], v[174:177], v[182:185], v[48:51]
	v_mfma_f32_16x16x32_bf16 v[36:39], v[166:169], v[190:193], v[36:39]
	v_mfma_f32_16x16x32_bf16 v[32:35], v[174:177], v[190:193], v[32:35]
	v_mfma_f32_16x16x32_bf16 v[20:23], v[166:169], v[198:201], v[20:23]
	v_mfma_f32_16x16x32_bf16 v[16:19], v[174:177], v[198:201], v[16:19]
	v_mfma_f32_16x16x32_bf16 v[4:7], v[166:169], v[206:209], v[4:7]
	v_mfma_f32_16x16x32_bf16 v[0:3], v[174:177], v[206:209], v[0:3]
	v_mfma_f32_16x16x32_bf16 v[52:55], v[170:173], v[186:189], v[52:55]
	v_mfma_f32_16x16x32_bf16 v[48:51], v[178:181], v[186:189], v[48:51]
	v_mfma_f32_16x16x32_bf16 v[36:39], v[170:173], v[194:197], v[36:39]
	v_mfma_f32_16x16x32_bf16 v[32:35], v[178:181], v[194:197], v[32:35]
	v_mfma_f32_16x16x32_bf16 v[20:23], v[170:173], v[202:205], v[20:23]
	v_mfma_f32_16x16x32_bf16 v[16:19], v[178:181], v[202:205], v[16:19]
	v_mfma_f32_16x16x32_bf16 v[4:7], v[170:173], v[210:213], v[4:7]
	v_mfma_f32_16x16x32_bf16 v[0:3], v[178:181], v[210:213], v[0:3]
	s_setprio 0
	s_barrier
	s_add_i32 s49, s49, 2
	s_add_u32 s22, s22, 0x100
	s_addc_u32 s23, s23, 0
	s_add_u32 s47, s47, 0x100
	s_addc_u32 s48, s48, 0
	s_cmp_gt_u32 s49, 29
	s_cbranch_scc0 .LBB0_158
	s_branch .Lkx_2
.LBB0_158:
	ds_read_b128 v[144:147], v151
	ds_read_b128 v[154:157], v151 offset:1024
	ds_read_b128 v[158:161], v151 offset:2048
	ds_read_b128 v[162:165], v151 offset:3072
	ds_read_b128 v[166:169], v152
	ds_read_b128 v[170:173], v152 offset:1024
	ds_read_b128 v[174:177], v152 offset:2048
	ds_read_b128 v[178:181], v152 offset:3072
	s_add_u32 s24, s22, 0xfff80080
	s_addc_u32 s25, s23, -1
	s_cmp_eq_u32 s49, 28
	s_cselect_b32 s27, s5, s25
	s_cselect_b32 s26, s15, s24
	s_cselect_b32 s25, s13, s48
	s_cselect_b32 s24, s46, s47
	v_lshl_add_u64 v[214:215], s[22:23], 0, v[136:137]
	s_add_i32 m0, s21, 0xc000
	ds_read_b128 v[182:185], v153
	ds_read_b128 v[186:189], v153 offset:1024
	ds_read_b128 v[190:193], v153 offset:2048
	ds_read_b128 v[194:197], v153 offset:3072
	ds_read_b128 v[198:201], v153 offset:4096
	ds_read_b128 v[202:205], v153 offset:5120
	ds_read_b128 v[206:209], v153 offset:6144
	ds_read_b128 v[210:213], v153 offset:7168
	global_load_lds_dwordx4 v[214:215], off
	v_lshl_add_u64 v[214:215], s[22:23], 0, v[138:139]
	s_add_i32 m0, s21, 0xe000
	s_nop 0
	global_load_lds_dwordx4 v[214:215], off
	s_waitcnt vmcnt(8)
	s_waitcnt lgkmcnt(0)
	s_barrier
; #define PG8_STAGE(bufoff, gbase, voff) do { _Pragma("unroll") for (int _i = 0; _i < 2; ++_i) \
;         __builtin_amdgcn_global_load_lds((const unsigned*)((const char*)(gbase) + (voff)[_i]), (PG8_LAS unsigned*)(lds + (bufoff) + ldsw + _i * 8192), 16, 0, 0); } while (0)
; #define PG8_LDA(dst, b, h) do { _Pragma("unroll") for (int m = 0; m < 4; ++m) _Pragma("unroll") for (int k = 0; k < 2; ++k) dst[m][k] = *(const PG8_LAS bf16x8*)(lds + PG8_SA(b, h) + aoff + m * 2048 + k * 1024); } while (0)
; #define PG8_WAIT_V(n) asm volatile("s_waitcnt vmcnt(" #n ")" ::: "memory")
; #define PG8_WAIT_L(n) asm volatile("s_waitcnt lgkmcnt(" #n ")" ::: "memory")
; #define PG8_BAR __builtin_amdgcn_s_barrier()
; template <class Epi, class Sched, bool ALIGN_EPI = false, bool SP2 = false>
; __device__ __forceinline__ void gemm_phase(PG8_LAS unsigned char* lds, const Gemm g, const Sched& S, const Epi& E, const int wave_in) {
;     ...
;         for (int t = 0; t < nt; t += 2) {
;             const bool last = (t == nt - 2);
;             const char* a1 = cA + (size_t)(t + 1) * kstep;
;             const char* a2 = last ? nA : cA + (size_t)(t + 2) * kstep; const char* b2 = last ? nB : cB + (size_t)(t + 2) * kstep;
;             const char* a3 = a2 + kstep; const char* b3 = b2 + kstep;
;             if (last && has_next) S.a_ready(nxt);
;             if constexpr (SP2) {
;             PG8_LDB(B0, 0, 0); PG8_LDB(B1, 0, 1); PG8_SCHED; PG8_LDA(At, 0, 0); PG8_STAGE(PG8_SA(1, 1), a1 + hstepA, voffA);
;             PG8_WAIT_V(8); PG8_WAIT_L(0); PG8_BAR; PG8_MMA(0, 0, At, B0); PG8_MMA(0, 1, At, B1); PG8_BAR; PG8_SCHED;
;             PG8_LDA(At, 0, 1); PG8_STAGE(PG8_SB(0, 0), b2, voffB); PG8_STAGE(PG8_SB(0, 1), b2 + hstepB, voffB); PG8_STAGE(PG8_SA(0, 0), a2, voffA);
;             PG8_WAIT_V(8); PG8_WAIT_L(0); PG8_BAR; PG8_MMA(1, 0, At, B0); PG8_MMA(1, 1, At, B1); PG8_BAR; PG8_SCHED;
;             PG8_LDB(B0, 1, 0); PG8_LDB(B1, 1, 1); PG8_SCHED; PG8_LDA(At, 1, 0); PG8_STAGE(PG8_SA(0, 1), a2 + hstepA, voffA);
;             PG8_WAIT_V(8); PG8_WAIT_L(0); PG8_BAR; PG8_MMA(0, 0, At, B0); PG8_MMA(0, 1, At, B1); PG8_BAR; PG8_SCHED;
;             PG8_LDA(At, 1, 1); PG8_STAGE(PG8_SB(1, 0), b3, voffB); PG8_STAGE(PG8_SB(1, 1), b3 + hstepB, voffB); PG8_STAGE(PG8_SA(1, 0), a3, voffA);
;             PG8_WAIT_V(8); PG8_WAIT_L(0); PG8_BAR; PG8_MMA(1, 0, At, B0); PG8_MMA(1, 1, At, B1); PG8_BAR; PG8_SCHED;
	s_setprio 1
	v_mfma_f32_16x16x32_bf16 v[124:127], v[144:147], v[182:185], v[124:127]
	v_mfma_f32_16x16x32_bf16 v[120:123], v[158:161], v[182:185], v[120:123]
	v_mfma_f32_16x16x32_bf16 v[108:111], v[144:147], v[190:193], v[108:111]
	v_mfma_f32_16x16x32_bf16 v[104:107], v[158:161], v[190:193], v[104:107]
	v_mfma_f32_16x16x32_bf16 v[92:95], v[144:147], v[198:201], v[92:95]
	v_mfma_f32_16x16x32_bf16 v[88:91], v[158:161], v[198:201], v[88:91]
	v_mfma_f32_16x16x32_bf16 v[76:79], v[144:147], v[206:209], v[76:79]
	v_mfma_f32_16x16x32_bf16 v[72:75], v[158:161], v[206:209], v[72:75]
	v_mfma_f32_16x16x32_bf16 v[124:127], v[154:157], v[186:189], v[124:127]
	v_mfma_f32_16x16x32_bf16 v[120:123], v[162:165], v[186:189], v[120:123]
	v_mfma_f32_16x16x32_bf16 v[108:111], v[154:157], v[194:197], v[108:111]
	v_mfma_f32_16x16x32_bf16 v[104:107], v[162:165], v[194:197], v[104:107]
	v_mfma_f32_16x16x32_bf16 v[92:95], v[154:157], v[202:205], v[92:95]
	v_mfma_f32_16x16x32_bf16 v[88:91], v[162:165], v[202:205], v[88:91]
	v_mfma_f32_16x16x32_bf16 v[76:79], v[154:157], v[210:213], v[76:79]
	v_mfma_f32_16x16x32_bf16 v[72:75], v[162:165], v[210:213], v[72:75]
	v_mfma_f32_16x16x32_bf16 v[116:119], v[166:169], v[182:185], v[116:119]
	v_mfma_f32_16x16x32_bf16 v[112:115], v[174:177], v[182:185], v[112:115]
	v_mfma_f32_16x16x32_bf16 v[100:103], v[166:169], v[190:193], v[100:103]
	v_mfma_f32_16x16x32_bf16 v[96:99], v[174:177], v[190:193], v[96:99]
	v_mfma_f32_16x16x32_bf16 v[84:87], v[166:169], v[198:201], v[84:87]
	v_mfma_f32_16x16x32_bf16 v[80:83], v[174:177], v[198:201], v[80:83]
	v_mfma_f32_16x16x32_bf16 v[68:71], v[166:169], v[206:209], v[68:71]
	v_mfma_f32_16x16x32_bf16 v[64:67], v[174:177], v[206:209], v[64:67]
	v_mfma_f32_16x16x32_bf16 v[116:119], v[170:173], v[186:189], v[116:119]
	v_mfma_f32_16x16x32_bf16 v[112:115], v[178:181], v[186:189], v[112:115]
	v_mfma_f32_16x16x32_bf16 v[100:103], v[170:173], v[194:197], v[100:103]
	v_mfma_f32_16x16x32_bf16 v[96:99], v[178:181], v[194:197], v[96:99]
	v_mfma_f32_16x16x32_bf16 v[84:87], v[170:173], v[202:205], v[84:87]
	v_mfma_f32_16x16x32_bf16 v[80:83], v[178:181], v[202:205], v[80:83]
	v_mfma_f32_16x16x32_bf16 v[68:71], v[170:173], v[210:213], v[68:71]
	v_mfma_f32_16x16x32_bf16 v[64:67], v[178:181], v[210:213], v[64:67]
	s_setprio 0
	s_barrier
	s_add_i32 s50, s43, s34
	v_lshl_add_u64 v[214:215], s[24:25], 0, v[130:131]
	s_mov_b32 m0, s50
	ds_read_b128 v[182:185], v153 offset:16384
	ds_read_b128 v[186:189], v153 offset:17408
	ds_read_b128 v[190:193], v153 offset:18432
	ds_read_b128 v[194:197], v153 offset:19456
	ds_read_b128 v[198:201], v153 offset:20480
	ds_read_b128 v[202:205], v153 offset:21504
	ds_read_b128 v[206:209], v153 offset:22528
	ds_read_b128 v[210:213], v153 offset:23552
	global_load_lds_dwordx4 v[214:215], off
	s_add_i32 m0, s50, 0x2000
	s_add_u32 s50, s24, 0x80000
	v_lshl_add_u64 v[216:217], s[24:25], 0, v[134:135]
	s_addc_u32 s51, s25, 0
	s_add_i32 s52, s44, s34
	global_load_lds_dwordx4 v[216:217], off
	v_lshl_add_u64 v[218:219], s[50:51], 0, v[130:131]
	s_mov_b32 m0, s52
	v_lshl_add_u64 v[220:221], s[26:27], 0, v[132:133]
	global_load_lds_dwordx4 v[218:219], off
	v_lshl_add_u64 v[218:219], s[50:51], 0, v[134:135]
	s_add_i32 m0, s52, 0x2000
	s_nop 0
	global_load_lds_dwordx4 v[218:219], off
	v_lshl_add_u64 v[218:219], s[26:27], 0, v[128:129]
	s_mov_b32 m0, s21
	s_nop 0
	global_load_lds_dwordx4 v[218:219], off
	s_mov_b32 m0, s35
	s_nop 0
	global_load_lds_dwordx4 v[220:221], off
	s_waitcnt vmcnt(8)
	s_waitcnt lgkmcnt(0)
	s_barrier
	s_setprio 1
	v_mfma_f32_16x16x32_bf16 v[60:63], v[144:147], v[182:185], v[60:63]
	v_mfma_f32_16x16x32_bf16 v[56:59], v[158:161], v[182:185], v[56:59]
	v_mfma_f32_16x16x32_bf16 v[44:47], v[144:147], v[190:193], v[44:47]
	v_mfma_f32_16x16x32_bf16 v[40:43], v[158:161], v[190:193], v[40:43]
	v_mfma_f32_16x16x32_bf16 v[28:31], v[144:147], v[198:201], v[28:31]
	v_mfma_f32_16x16x32_bf16 v[24:27], v[158:161], v[198:201], v[24:27]
	v_mfma_f32_16x16x32_bf16 v[12:15], v[144:147], v[206:209], v[12:15]
	v_mfma_f32_16x16x32_bf16 v[8:11], v[158:161], v[206:209], v[8:11]
	v_mfma_f32_16x16x32_bf16 v[60:63], v[154:157], v[186:189], v[60:63]
	v_mfma_f32_16x16x32_bf16 v[56:59], v[162:165], v[186:189], v[56:59]
	v_mfma_f32_16x16x32_bf16 v[44:47], v[154:157], v[194:197], v[44:47]
	v_mfma_f32_16x16x32_bf16 v[40:43], v[162:165], v[194:197], v[40:43]
	v_mfma_f32_16x16x32_bf16 v[28:31], v[154:157], v[202:205], v[28:31]
	v_mfma_f32_16x16x32_bf16 v[24:27], v[162:165], v[202:205], v[24:27]
	v_mfma_f32_16x16x32_bf16 v[12:15], v[154:157], v[210:213], v[12:15]
	v_mfma_f32_16x16x32_bf16 v[8:11], v[162:165], v[210:213], v[8:11]
	v_mfma_f32_16x16x32_bf16 v[52:55], v[166:169], v[182:185], v[52:55]
	v_mfma_f32_16x16x32_bf16 v[48:51], v[174:177], v[182:185], v[48:51]
	v_mfma_f32_16x16x32_bf16 v[36:39], v[166:169], v[190:193], v[36:39]
	v_mfma_f32_16x16x32_bf16 v[32:35], v[174:177], v[190:193], v[32:35]
	v_mfma_f32_16x16x32_bf16 v[20:23], v[166:169], v[198:201], v[20:23]
	v_mfma_f32_16x16x32_bf16 v[16:19], v[174:177], v[198:201], v[16:19]
	v_mfma_f32_16x16x32_bf16 v[4:7], v[166:169], v[206:209], v[4:7]
	v_mfma_f32_16x16x32_bf16 v[0:3], v[174:177], v[206:209], v[0:3]
	v_mfma_f32_16x16x32_bf16 v[52:55], v[170:173], v[186:189], v[52:55]
	v_mfma_f32_16x16x32_bf16 v[48:51], v[178:181], v[186:189], v[48:51]
	v_mfma_f32_16x16x32_bf16 v[36:39], v[170:173], v[194:197], v[36:39]
	v_mfma_f32_16x16x32_bf16 v[32:35], v[178:181], v[194:197], v[32:35]
	v_mfma_f32_16x16x32_bf16 v[20:23], v[170:173], v[202:205], v[20:23]
	v_mfma_f32_16x16x32_bf16 v[16:19], v[178:181], v[202:205], v[16:19]
	v_mfma_f32_16x16x32_bf16 v[4:7], v[170:173], v[210:213], v[4:7]
	v_mfma_f32_16x16x32_bf16 v[0:3], v[178:181], v[210:213], v[0:3]
	s_setprio 0
	s_barrier
; #define PG8_STAGE(bufoff, gbase, voff) do { _Pragma("unroll") for (int _i = 0; _i < 2; ++_i) \
;         __builtin_amdgcn_global_load_lds((const unsigned*)((const char*)(gbase) + (voff)[_i]), (PG8_LAS unsigned*)(lds + (bufoff) + ldsw + _i * 8192), 16, 0, 0); } while (0)
; #define PG8_LDA(dst, b, h) do { _Pragma("unroll") for (int m = 0; m < 4; ++m) _Pragma("unroll") for (int k = 0; k < 2; ++k) dst[m][k] = *(const PG8_LAS bf16x8*)(lds + PG8_SA(b, h) + aoff + m * 2048 + k * 1024); } while (0)
; #define PG8_WAIT_V(n) asm volatile("s_waitcnt vmcnt(" #n ")" ::: "memory")
; #define PG8_WAIT_L(n) asm volatile("s_waitcnt lgkmcnt(" #n ")" ::: "memory")
; #define PG8_BAR __builtin_amdgcn_s_barrier()
; template <class Epi, class Sched, bool ALIGN_EPI = false, bool SP2 = false>
; __device__ __forceinline__ void gemm_phase(PG8_LAS unsigned char* lds, const Gemm g, const Sched& S, const Epi& E, const int wave_in) {
;     ...
;         for (int t = 0; t < nt; t += 2) {
;             const bool last = (t == nt - 2);
;             const char* a1 = cA + (size_t)(t + 1) * kstep;
;             const char* a2 = last ? nA : cA + (size_t)(t + 2) * kstep; const char* b2 = last ? nB : cB + (size_t)(t + 2) * kstep;
;             const char* a3 = a2 + kstep; const char* b3 = b2 + kstep;
;             if (last && has_next) S.a_ready(nxt);
;             if constexpr (SP2) {
;             PG8_LDB(B0, 0, 0); PG8_LDB(B1, 0, 1); PG8_SCHED; PG8_LDA(At, 0, 0); PG8_STAGE(PG8_SA(1, 1), a1 + hstepA, voffA);
;             PG8_WAIT_V(8); PG8_WAIT_L(0); PG8_BAR; PG8_MMA(0, 0, At, B0); PG8_MMA(0, 1, At, B1); PG8_BAR; PG8_SCHED;
;             PG8_LDA(At, 0, 1); PG8_STAGE(PG8_SB(0, 0), b2, voffB); PG8_STAGE(PG8_SB(0, 1), b2 + hstepB, voffB); PG8_STAGE(PG8_SA(0, 0), a2, voffA);
;             PG8_WAIT_V(8); PG8_WAIT_L(0); PG8_BAR; PG8_MMA(1, 0, At, B0); PG8_MMA(1, 1, At, B1); PG8_BAR; PG8_SCHED;
;             PG8_LDB(B0, 1, 0); PG8_LDB(B1, 1, 1); PG8_SCHED; PG8_LDA(At, 1, 0); PG8_STAGE(PG8_SA(0, 1), a2 + hstepA, voffA);
;             PG8_WAIT_V(8); PG8_WAIT_L(0); PG8_BAR; PG8_MMA(0, 0, At, B0); PG8_MMA(0, 1, At, B1); PG8_BAR; PG8_SCHED;
;             PG8_LDA(At, 1, 1); PG8_STAGE(PG8_SB(1, 0), b3, voffB); PG8_STAGE(PG8_SB(1, 1), b3 + hstepB, voffB); PG8_STAGE(PG8_SA(1, 0), a3, voffA);
;             PG8_WAIT_V(8); PG8_WAIT_L(0); PG8_BAR; PG8_MMA(1, 0, At, B0); PG8_MMA(1, 1, At, B1); PG8_BAR; PG8_SCHED;
	s_add_i32 s50, 0, 0x18000
	s_add_i32 s51, 0, 0x1c000
	v_add_u32_e32 v162, s50, v149
	v_add_u32_e32 v178, s51, v149
	ds_read_b128 v[144:147], v162
	ds_read_b128 v[154:157], v162 offset:1024
	ds_read_b128 v[158:161], v162 offset:2048
	ds_read_b128 v[162:165], v162 offset:3072
	ds_read_b128 v[166:169], v178
	ds_read_b128 v[170:173], v178 offset:1024
	ds_read_b128 v[174:177], v178 offset:2048
	ds_read_b128 v[178:181], v178 offset:3072
	s_add_u32 s26, s26, 0x80000
	s_addc_u32 s27, s27, 0
	s_mov_b32 m0, s36
	v_lshl_add_u64 v[222:223], s[26:27], 0, v[128:129]
	ds_read_b128 v[182:185], v153 offset:32768
	ds_read_b128 v[186:189], v153 offset:33792
	ds_read_b128 v[190:193], v153 offset:34816
	ds_read_b128 v[194:197], v153 offset:35840
	ds_read_b128 v[198:201], v153 offset:36864
	ds_read_b128 v[202:205], v153 offset:37888
	ds_read_b128 v[206:209], v153 offset:38912
	ds_read_b128 v[210:213], v153 offset:39936
	global_load_lds_dwordx4 v[222:223], off
	v_lshl_add_u64 v[222:223], s[26:27], 0, v[132:133]
	s_mov_b32 m0, s37
	s_nop 0
	global_load_lds_dwordx4 v[222:223], off
	s_waitcnt vmcnt(8)
	s_waitcnt lgkmcnt(0)
	s_barrier
	s_setprio 1
	v_mfma_f32_16x16x32_bf16 v[124:127], v[144:147], v[182:185], v[124:127]
	v_mfma_f32_16x16x32_bf16 v[120:123], v[158:161], v[182:185], v[120:123]
	v_mfma_f32_16x16x32_bf16 v[108:111], v[144:147], v[190:193], v[108:111]
	v_mfma_f32_16x16x32_bf16 v[104:107], v[158:161], v[190:193], v[104:107]
	v_mfma_f32_16x16x32_bf16 v[92:95], v[144:147], v[198:201], v[92:95]
	v_mfma_f32_16x16x32_bf16 v[88:91], v[158:161], v[198:201], v[88:91]
	v_mfma_f32_16x16x32_bf16 v[76:79], v[144:147], v[206:209], v[76:79]
	v_mfma_f32_16x16x32_bf16 v[72:75], v[158:161], v[206:209], v[72:75]
	v_mfma_f32_16x16x32_bf16 v[124:127], v[154:157], v[186:189], v[124:127]
	v_mfma_f32_16x16x32_bf16 v[120:123], v[162:165], v[186:189], v[120:123]
	v_mfma_f32_16x16x32_bf16 v[108:111], v[154:157], v[194:197], v[108:111]
	v_mfma_f32_16x16x32_bf16 v[104:107], v[162:165], v[194:197], v[104:107]
	v_mfma_f32_16x16x32_bf16 v[92:95], v[154:157], v[202:205], v[92:95]
	v_mfma_f32_16x16x32_bf16 v[88:91], v[162:165], v[202:205], v[88:91]
	v_mfma_f32_16x16x32_bf16 v[76:79], v[154:157], v[210:213], v[76:79]
	v_mfma_f32_16x16x32_bf16 v[72:75], v[162:165], v[210:213], v[72:75]
	v_mfma_f32_16x16x32_bf16 v[116:119], v[166:169], v[182:185], v[116:119]
	v_mfma_f32_16x16x32_bf16 v[112:115], v[174:177], v[182:185], v[112:115]
	v_mfma_f32_16x16x32_bf16 v[100:103], v[166:169], v[190:193], v[100:103]
	v_mfma_f32_16x16x32_bf16 v[96:99], v[174:177], v[190:193], v[96:99]
	v_mfma_f32_16x16x32_bf16 v[84:87], v[166:169], v[198:201], v[84:87]
	v_mfma_f32_16x16x32_bf16 v[80:83], v[174:177], v[198:201], v[80:83]
	v_mfma_f32_16x16x32_bf16 v[68:71], v[166:169], v[206:209], v[68:71]
	v_mfma_f32_16x16x32_bf16 v[64:67], v[174:177], v[206:209], v[64:67]
	v_mfma_f32_16x16x32_bf16 v[116:119], v[170:173], v[186:189], v[116:119]
	v_mfma_f32_16x16x32_bf16 v[112:115], v[178:181], v[186:189], v[112:115]
	v_mfma_f32_16x16x32_bf16 v[100:103], v[170:173], v[194:197], v[100:103]
	v_mfma_f32_16x16x32_bf16 v[96:99], v[178:181], v[194:197], v[96:99]
	v_mfma_f32_16x16x32_bf16 v[84:87], v[170:173], v[202:205], v[84:87]
	v_mfma_f32_16x16x32_bf16 v[80:83], v[178:181], v[202:205], v[80:83]
	v_mfma_f32_16x16x32_bf16 v[68:71], v[170:173], v[210:213], v[68:71]
	v_mfma_f32_16x16x32_bf16 v[64:67], v[178:181], v[210:213], v[64:67]
	s_setprio 0
	s_barrier
	s_add_i32 s26, s50, s34
	v_lshl_add_u64 v[214:215], v[214:215], 0, s[8:9]
	s_mov_b32 m0, s26
	ds_read_b128 v[182:185], v153 offset:49152
	ds_read_b128 v[186:189], v153 offset:50176
	ds_read_b128 v[190:193], v153 offset:51200
	ds_read_b128 v[194:197], v153 offset:52224
	ds_read_b128 v[198:201], v153 offset:53248
	ds_read_b128 v[202:205], v153 offset:54272
	ds_read_b128 v[206:209], v153 offset:55296
	ds_read_b128 v[210:213], v153 offset:56320
	global_load_lds_dwordx4 v[214:215], off
	s_add_i32 m0, s26, 0x2000
	s_add_u32 s24, s24, 0x80080
	v_lshl_add_u64 v[214:215], v[216:217], 0, s[8:9]
	s_addc_u32 s25, s25, 0
	s_add_i32 s26, s51, s34
	global_load_lds_dwordx4 v[214:215], off
	v_lshl_add_u64 v[214:215], s[24:25], 0, v[130:131]
	s_mov_b32 m0, s26
	s_nop 0
	global_load_lds_dwordx4 v[214:215], off
	v_lshl_add_u64 v[214:215], s[24:25], 0, v[134:135]
	s_add_i32 m0, s26, 0x2000
	s_nop 0
	global_load_lds_dwordx4 v[214:215], off
	v_lshl_add_u64 v[214:215], v[218:219], 0, s[8:9]
	s_mov_b32 m0, s39
	s_nop 0
	global_load_lds_dwordx4 v[214:215], off
	v_lshl_add_u64 v[214:215], v[220:221], 0, s[8:9]
	s_mov_b32 m0, s40
	s_nop 0
	global_load_lds_dwordx4 v[214:215], off
	s_waitcnt vmcnt(8)
	s_waitcnt lgkmcnt(0)
	s_barrier
	s_setprio 1
	v_mfma_f32_16x16x32_bf16 v[60:63], v[144:147], v[182:185], v[60:63]
	v_mfma_f32_16x16x32_bf16 v[56:59], v[158:161], v[182:185], v[56:59]
	v_mfma_f32_16x16x32_bf16 v[44:47], v[144:147], v[190:193], v[44:47]
	v_mfma_f32_16x16x32_bf16 v[40:43], v[158:161], v[190:193], v[40:43]
	v_mfma_f32_16x16x32_bf16 v[28:31], v[144:147], v[198:201], v[28:31]
	v_mfma_f32_16x16x32_bf16 v[24:27], v[158:161], v[198:201], v[24:27]
	v_mfma_f32_16x16x32_bf16 v[12:15], v[144:147], v[206:209], v[12:15]
	v_mfma_f32_16x16x32_bf16 v[8:11], v[158:161], v[206:209], v[8:11]
	v_mfma_f32_16x16x32_bf16 v[60:63], v[154:157], v[186:189], v[60:63]
	v_mfma_f32_16x16x32_bf16 v[56:59], v[162:165], v[186:189], v[56:59]
	v_mfma_f32_16x16x32_bf16 v[44:47], v[154:157], v[194:197], v[44:47]
	v_mfma_f32_16x16x32_bf16 v[40:43], v[162:165], v[194:197], v[40:43]
	v_mfma_f32_16x16x32_bf16 v[28:31], v[154:157], v[202:205], v[28:31]
	v_mfma_f32_16x16x32_bf16 v[24:27], v[162:165], v[202:205], v[24:27]
	v_mfma_f32_16x16x32_bf16 v[12:15], v[154:157], v[210:213], v[12:15]
	v_mfma_f32_16x16x32_bf16 v[8:11], v[162:165], v[210:213], v[8:11]
	v_mfma_f32_16x16x32_bf16 v[52:55], v[166:169], v[182:185], v[52:55]
	v_mfma_f32_16x16x32_bf16 v[48:51], v[174:177], v[182:185], v[48:51]
	v_mfma_f32_16x16x32_bf16 v[36:39], v[166:169], v[190:193], v[36:39]
	v_mfma_f32_16x16x32_bf16 v[32:35], v[174:177], v[190:193], v[32:35]
	v_mfma_f32_16x16x32_bf16 v[20:23], v[166:169], v[198:201], v[20:23]
	v_mfma_f32_16x16x32_bf16 v[16:19], v[174:177], v[198:201], v[16:19]
	v_mfma_f32_16x16x32_bf16 v[4:7], v[166:169], v[206:209], v[4:7]
	v_mfma_f32_16x16x32_bf16 v[0:3], v[174:177], v[206:209], v[0:3]
	v_mfma_f32_16x16x32_bf16 v[52:55], v[170:173], v[186:189], v[52:55]
	v_mfma_f32_16x16x32_bf16 v[48:51], v[178:181], v[186:189], v[48:51]
	v_mfma_f32_16x16x32_bf16 v[36:39], v[170:173], v[194:197], v[36:39]
	v_mfma_f32_16x16x32_bf16 v[32:35], v[178:181], v[194:197], v[32:35]
	v_mfma_f32_16x16x32_bf16 v[20:23], v[170:173], v[202:205], v[20:23]
	v_mfma_f32_16x16x32_bf16 v[16:19], v[178:181], v[202:205], v[16:19]
	v_mfma_f32_16x16x32_bf16 v[4:7], v[170:173], v[210:213], v[4:7]
	v_mfma_f32_16x16x32_bf16 v[0:3], v[178:181], v[210:213], v[0:3]
	s_setprio 0
	s_barrier
	s_add_i32 s49, s49, 2
	s_add_u32 s22, s22, 0x100
	s_addc_u32 s23, s23, 0
	s_add_u32 s47, s47, 0x100
	s_addc_u32 s48, s48, 0
	s_cmp_gt_u32 s49, 29
	s_cbranch_scc0 .LBB0_158

;     __host__ __device__ bool next(int i, Unit& u) const { const bool ok = StaticOrder::next(i, u); u.pm = 0; u.pn = 0; return ok; }
; #define PG8_STAGE(bufoff, gbase, voff) do { _Pragma("unroll") for (int _i = 0; _i < 2; ++_i) \
;         __builtin_amdgcn_global_load_lds((const unsigned*)((const char*)(gbase) + (voff)[_i]), (PG8_LAS unsigned*)(lds + (bufoff) + ldsw + _i * 8192), 16, 0, 0); } while (0)
; #define PG8_WAIT_V(n) asm volatile("s_waitcnt vmcnt(" #n ")" ::: "memory")
; template <class Epi, class Sched, bool ALIGN_EPI = false, bool SP2 = false>
; __device__ __forceinline__ void gemm_phase(PG8_LAS unsigned char* lds, const Gemm g, const Sched& S, const Epi& E, const int wave_in) {
;     ...
;         const bool has_next = S.next(ui + 1, nxt);
;         const char* nA = has_next ? (const char*)g.A + (size_t)nxt.pm * tstepA : cA; const char* nB = has_next ? (const char*)g.Bt + (size_t)nxt.pn * tstepB : cB;
;         for (int t = 0; t < nt; t += 2) {
;             const bool last = (t == nt - 2);
;             const char* a1 = cA + (size_t)(t + 1) * kstep;
;             const char* a2 = last ? nA : cA + (size_t)(t + 2) * kstep; const char* b2 = last ? nB : cB + (size_t)(t + 2) * kstep;
;             const char* a3 = a2 + kstep; const char* b3 = b2 + kstep;
;             if (last && has_next) S.a_ready(nxt);
;             if constexpr (SP2) {
;             PG8_LDB(B0, 0, 0); PG8_LDB(B1, 0, 1); PG8_SCHED; PG8_LDA(At, 0, 0); PG8_STAGE(PG8_SA(1, 1), a1 + hstepA, voffA);
;             PG8_WAIT_V(8); PG8_WAIT_L(0); PG8_BAR; PG8_MMA(0, 0, At, B0); PG8_MMA(0, 1, At, B1); PG8_BAR; PG8_SCHED;
;             PG8_LDA(At, 0, 1); PG8_STAGE(PG8_SB(0, 0), b2, voffB); PG8_STAGE(PG8_SB(0, 1), b2 + hstepB, voffB); PG8_STAGE(PG8_SA(0, 0), a2, voffA);
;             PG8_WAIT_V(8); PG8_WAIT_L(0); PG8_BAR; PG8_MMA(1, 0, At, B0); PG8_MMA(1, 1, At, B1); PG8_BAR; PG8_SCHED;
;             PG8_LDB(B0, 1, 0); PG8_LDB(B1, 1, 1); PG8_SCHED; PG8_LDA(At, 1, 0); PG8_STAGE(PG8_SA(0, 1), a2 + hstepA, voffA);
;             PG8_WAIT_V(8); PG8_WAIT_L(0); PG8_BAR; PG8_MMA(0, 0, At, B0); PG8_MMA(0, 1, At, B1); PG8_BAR; PG8_SCHED;
;             PG8_LDA(At, 1, 1); PG8_STAGE(PG8_SB(1, 0), b3, voffB); PG8_STAGE(PG8_SB(1, 1), b3 + hstepB, voffB); PG8_STAGE(PG8_SA(1, 0), a3, voffA);
;             PG8_WAIT_V(8); PG8_WAIT_L(0); PG8_BAR; PG8_MMA(1, 0, At, B0); PG8_MMA(1, 1, At, B1); PG8_BAR; PG8_SCHED;
.LBB0_352:
	s_ashr_i32 s15, s14, 31
	s_lshl_b64 s[18:19], s[14:15], 20
	s_add_u32 s18, s30, s18
	s_addc_u32 s19, s31, s19
	s_and_b64 s[4:5], s[4:5], exec
	s_cselect_b32 s15, s19, s25
	s_cselect_b32 s21, s18, s24
	s_add_u32 s51, s24, 0x100
	v_mov_b32_e32 v0, 0
	s_addc_u32 s52, s25, 0
	s_mov_b32 s53, -2
	ds_read_b128 v[128:131], v168
	ds_read_b128 v[132:135], v168 offset:1024
	ds_read_b128 v[136:139], v168 offset:2048
	ds_read_b128 v[140:143], v168 offset:3072
	ds_read_b128 v[162:165], v169
	ds_read_b128 v[172:175], v169 offset:1024
	ds_read_b128 v[176:179], v169 offset:2048
	ds_read_b128 v[180:183], v169 offset:3072
	s_add_u32 s4, s22, 0x100
	s_addc_u32 s5, s23, 0
	s_cmp_eq_u32 s53, 28
	s_cselect_b32 s27, s17, s5
	s_cselect_b32 s26, s16, s4
	s_cselect_b32 s25, s15, s52
	s_cselect_b32 s24, s21, s51
	v_lshl_add_u64 v[216:217], s[22:23], 0, v[154:155]
	s_add_i32 m0, s37, 0xc000
	ds_read_b128 v[184:187], v170
	ds_read_b128 v[188:191], v170 offset:1024
	ds_read_b128 v[192:195], v170 offset:2048
	ds_read_b128 v[196:199], v170 offset:3072
	ds_read_b128 v[200:203], v170 offset:4096
	ds_read_b128 v[204:207], v170 offset:5120
	ds_read_b128 v[208:211], v170 offset:6144
	ds_read_b128 v[212:215], v170 offset:7168
	global_load_lds_dwordx4 v[216:217], off
	v_lshl_add_u64 v[216:217], s[22:23], 0, v[156:157]
	s_add_i32 m0, s37, 0xe000
	s_nop 0
	global_load_lds_dwordx4 v[216:217], off
	s_waitcnt vmcnt(8)
	s_waitcnt lgkmcnt(0)
	s_barrier
	s_setprio 1
	v_mfma_f32_16x16x32_bf16 v[124:127], v[128:131], v[184:187], 0
	v_mfma_f32_16x16x32_bf16 v[120:123], v[136:139], v[184:187], 0
	v_mfma_f32_16x16x32_bf16 v[116:119], v[128:131], v[192:195], 0
	v_mfma_f32_16x16x32_bf16 v[112:115], v[136:139], v[192:195], 0
	v_mfma_f32_16x16x32_bf16 v[92:95], v[128:131], v[200:203], 0
	v_mfma_f32_16x16x32_bf16 v[88:91], v[136:139], v[200:203], 0
	v_mfma_f32_16x16x32_bf16 v[84:87], v[128:131], v[208:211], 0
	v_mfma_f32_16x16x32_bf16 v[76:79], v[136:139], v[208:211], 0
	v_mfma_f32_16x16x32_bf16 v[124:127], v[132:135], v[188:191], v[124:127]
	v_mfma_f32_16x16x32_bf16 v[120:123], v[140:143], v[188:191], v[120:123]
	v_mfma_f32_16x16x32_bf16 v[116:119], v[132:135], v[196:199], v[116:119]
	v_mfma_f32_16x16x32_bf16 v[112:115], v[140:143], v[196:199], v[112:115]
	v_mfma_f32_16x16x32_bf16 v[92:95], v[132:135], v[204:207], v[92:95]
	v_mfma_f32_16x16x32_bf16 v[88:91], v[140:143], v[204:207], v[88:91]
	v_mfma_f32_16x16x32_bf16 v[84:87], v[132:135], v[212:215], v[84:87]
	v_mfma_f32_16x16x32_bf16 v[76:79], v[140:143], v[212:215], v[76:79]
	v_mfma_f32_16x16x32_bf16 v[108:111], v[162:165], v[184:187], 0
	v_mfma_f32_16x16x32_bf16 v[104:107], v[176:179], v[184:187], 0
	v_mfma_f32_16x16x32_bf16 v[100:103], v[162:165], v[192:195], 0
	v_mfma_f32_16x16x32_bf16 v[96:99], v[176:179], v[192:195], 0
	v_mfma_f32_16x16x32_bf16 v[80:83], v[162:165], v[200:203], 0
	v_mfma_f32_16x16x32_bf16 v[72:75], v[176:179], v[200:203], 0
	v_mfma_f32_16x16x32_bf16 v[68:71], v[162:165], v[208:211], 0
	v_mfma_f32_16x16x32_bf16 v[64:67], v[176:179], v[208:211], 0
	v_mfma_f32_16x16x32_bf16 v[108:111], v[172:175], v[188:191], v[108:111]
	v_mfma_f32_16x16x32_bf16 v[104:107], v[180:183], v[188:191], v[104:107]
	v_mfma_f32_16x16x32_bf16 v[100:103], v[172:175], v[196:199], v[100:103]
	v_mfma_f32_16x16x32_bf16 v[96:99], v[180:183], v[196:199], v[96:99]
	v_mfma_f32_16x16x32_bf16 v[80:83], v[172:175], v[204:207], v[80:83]
	v_mfma_f32_16x16x32_bf16 v[72:75], v[180:183], v[204:207], v[72:75]
	v_mfma_f32_16x16x32_bf16 v[68:71], v[172:175], v[212:215], v[68:71]
	v_mfma_f32_16x16x32_bf16 v[64:67], v[180:183], v[212:215], v[64:67]
	s_setprio 0
	s_barrier
	s_add_i32 s22, s47, s34
	v_lshl_add_u64 v[216:217], s[24:25], 0, v[148:149]
	s_mov_b32 m0, s22
	ds_read_b128 v[184:187], v170 offset:16384
	ds_read_b128 v[188:191], v170 offset:17408
	ds_read_b128 v[192:195], v170 offset:18432
	ds_read_b128 v[196:199], v170 offset:19456
	ds_read_b128 v[200:203], v170 offset:20480
	ds_read_b128 v[204:207], v170 offset:21504
	ds_read_b128 v[208:211], v170 offset:22528
	ds_read_b128 v[212:215], v170 offset:23552
	global_load_lds_dwordx4 v[216:217], off
	s_add_i32 m0, s22, 0x2000
	s_add_u32 s22, s24, 0x80000
	v_lshl_add_u64 v[218:219], s[24:25], 0, v[144:145]
	s_addc_u32 s23, s25, 0
	s_add_i32 s54, s48, s34
	global_load_lds_dwordx4 v[218:219], off
	v_lshl_add_u64 v[220:221], s[22:23], 0, v[148:149]
	s_mov_b32 m0, s54
	v_lshl_add_u64 v[222:223], s[26:27], 0, v[146:147]
	global_load_lds_dwordx4 v[220:221], off
	v_lshl_add_u64 v[220:221], s[22:23], 0, v[144:145]
	s_add_i32 m0, s54, 0x2000
	s_nop 0
	global_load_lds_dwordx4 v[220:221], off
	v_lshl_add_u64 v[220:221], s[26:27], 0, v[150:151]
	s_mov_b32 m0, s37
	s_nop 0
	global_load_lds_dwordx4 v[220:221], off
	s_mov_b32 m0, s38
	s_nop 0
	global_load_lds_dwordx4 v[222:223], off
	s_waitcnt vmcnt(8)
	s_waitcnt lgkmcnt(0)
	s_barrier
; #define PG8_STAGE(bufoff, gbase, voff) do { _Pragma("unroll") for (int _i = 0; _i < 2; ++_i) \
;         __builtin_amdgcn_global_load_lds((const unsigned*)((const char*)(gbase) + (voff)[_i]), (PG8_LAS unsigned*)(lds + (bufoff) + ldsw + _i * 8192), 16, 0, 0); } while (0)
; #define PG8_LDA(dst, b, h) do { _Pragma("unroll") for (int m = 0; m < 4; ++m) _Pragma("unroll") for (int k = 0; k < 2; ++k) dst[m][k] = *(const PG8_LAS bf16x8*)(lds + PG8_SA(b, h) + aoff + m * 2048 + k * 1024); } while (0)
; #define PG8_WAIT_V(n) asm volatile("s_waitcnt vmcnt(" #n ")" ::: "memory")
; #define PG8_WAIT_L(n) asm volatile("s_waitcnt lgkmcnt(" #n ")" ::: "memory")
; #define PG8_BAR __builtin_amdgcn_s_barrier()
; template <class Epi, class Sched, bool ALIGN_EPI = false, bool SP2 = false>
; __device__ __forceinline__ void gemm_phase(PG8_LAS unsigned char* lds, const Gemm g, const Sched& S, const Epi& E, const int wave_in) {
;     ...
;         for (int t = 0; t < nt; t += 2) {
;             const bool last = (t == nt - 2);
;             const char* a1 = cA + (size_t)(t + 1) * kstep;
;             const char* a2 = last ? nA : cA + (size_t)(t + 2) * kstep; const char* b2 = last ? nB : cB + (size_t)(t + 2) * kstep;
;             const char* a3 = a2 + kstep; const char* b3 = b2 + kstep;
;             if (last && has_next) S.a_ready(nxt);
;             if constexpr (SP2) {
;             PG8_LDB(B0, 0, 0); PG8_LDB(B1, 0, 1); PG8_SCHED; PG8_LDA(At, 0, 0); PG8_STAGE(PG8_SA(1, 1), a1 + hstepA, voffA);
;             PG8_WAIT_V(8); PG8_WAIT_L(0); PG8_BAR; PG8_MMA(0, 0, At, B0); PG8_MMA(0, 1, At, B1); PG8_BAR; PG8_SCHED;
;             PG8_LDA(At, 0, 1); PG8_STAGE(PG8_SB(0, 0), b2, voffB); PG8_STAGE(PG8_SB(0, 1), b2 + hstepB, voffB); PG8_STAGE(PG8_SA(0, 0), a2, voffA);
;             PG8_WAIT_V(8); PG8_WAIT_L(0); PG8_BAR; PG8_MMA(1, 0, At, B0); PG8_MMA(1, 1, At, B1); PG8_BAR; PG8_SCHED;
;             PG8_LDB(B0, 1, 0); PG8_LDB(B1, 1, 1); PG8_SCHED; PG8_LDA(At, 1, 0); PG8_STAGE(PG8_SA(0, 1), a2 + hstepA, voffA);
;             PG8_WAIT_V(8); PG8_WAIT_L(0); PG8_BAR; PG8_MMA(0, 0, At, B0); PG8_MMA(0, 1, At, B1); PG8_BAR; PG8_SCHED;
;             PG8_LDA(At, 1, 1); PG8_STAGE(PG8_SB(1, 0), b3, voffB); PG8_STAGE(PG8_SB(1, 1), b3 + hstepB, voffB); PG8_STAGE(PG8_SA(1, 0), a3, voffA);
;             PG8_WAIT_V(8); PG8_WAIT_L(0); PG8_BAR; PG8_MMA(1, 0, At, B0); PG8_MMA(1, 1, At, B1); PG8_BAR; PG8_SCHED;
	s_setprio 1
	v_mfma_f32_16x16x32_bf16 v[60:63], v[128:131], v[184:187], 0
	v_mfma_f32_16x16x32_bf16 v[56:59], v[136:139], v[184:187], 0
	v_mfma_f32_16x16x32_bf16 v[52:55], v[128:131], v[192:195], 0
	v_mfma_f32_16x16x32_bf16 v[44:47], v[136:139], v[192:195], 0
	v_mfma_f32_16x16x32_bf16 v[36:39], v[128:131], v[200:203], 0
	v_mfma_f32_16x16x32_bf16 v[28:31], v[136:139], v[200:203], 0
	v_mfma_f32_16x16x32_bf16 v[20:23], v[128:131], v[208:211], 0
	v_mfma_f32_16x16x32_bf16 v[12:15], v[136:139], v[208:211], 0
	v_mfma_f32_16x16x32_bf16 v[60:63], v[132:135], v[188:191], v[60:63]
	v_mfma_f32_16x16x32_bf16 v[56:59], v[140:143], v[188:191], v[56:59]
	v_mfma_f32_16x16x32_bf16 v[52:55], v[132:135], v[196:199], v[52:55]
	v_mfma_f32_16x16x32_bf16 v[44:47], v[140:143], v[196:199], v[44:47]
	v_mfma_f32_16x16x32_bf16 v[36:39], v[132:135], v[204:207], v[36:39]
	v_mfma_f32_16x16x32_bf16 v[28:31], v[140:143], v[204:207], v[28:31]
	v_mfma_f32_16x16x32_bf16 v[20:23], v[132:135], v[212:215], v[20:23]
	v_mfma_f32_16x16x32_bf16 v[12:15], v[140:143], v[212:215], v[12:15]
	v_mfma_f32_16x16x32_bf16 v[48:51], v[162:165], v[184:187], 0
	v_mfma_f32_16x16x32_bf16 v[40:43], v[176:179], v[184:187], 0
	v_mfma_f32_16x16x32_bf16 v[32:35], v[162:165], v[192:195], 0
	v_mfma_f32_16x16x32_bf16 v[24:27], v[176:179], v[192:195], 0
	v_mfma_f32_16x16x32_bf16 v[16:19], v[162:165], v[200:203], 0
	v_mfma_f32_16x16x32_bf16 v[8:11], v[176:179], v[200:203], 0
	v_mfma_f32_16x16x32_bf16 v[4:7], v[162:165], v[208:211], 0
	v_mfma_f32_16x16x32_bf16 v[0:3], v[176:179], v[208:211], 0
	v_mfma_f32_16x16x32_bf16 v[48:51], v[172:175], v[188:191], v[48:51]
	v_mfma_f32_16x16x32_bf16 v[40:43], v[180:183], v[188:191], v[40:43]
	v_mfma_f32_16x16x32_bf16 v[32:35], v[172:175], v[196:199], v[32:35]
	v_mfma_f32_16x16x32_bf16 v[24:27], v[180:183], v[196:199], v[24:27]
	v_mfma_f32_16x16x32_bf16 v[16:19], v[172:175], v[204:207], v[16:19]
	v_mfma_f32_16x16x32_bf16 v[8:11], v[180:183], v[204:207], v[8:11]
	v_mfma_f32_16x16x32_bf16 v[4:7], v[172:175], v[212:215], v[4:7]
	v_mfma_f32_16x16x32_bf16 v[0:3], v[180:183], v[212:215], v[0:3]
	s_setprio 0
	s_barrier
	s_add_i32 s54, 0, 0x18000
	s_add_i32 s55, 0, 0x1c000
	v_add_u32_e32 v140, s54, v166
	v_add_u32_e32 v171, s55, v166
	ds_read_b128 v[128:131], v140
	ds_read_b128 v[132:135], v140 offset:1024
	ds_read_b128 v[136:139], v140 offset:2048
	ds_read_b128 v[140:143], v140 offset:3072
	ds_read_b128 v[162:165], v171
	ds_read_b128 v[172:175], v171 offset:1024
	ds_read_b128 v[176:179], v171 offset:2048
	ds_read_b128 v[180:183], v171 offset:3072
	s_add_u32 s22, s26, 0x280000
	s_addc_u32 s23, s27, 0
	s_mov_b32 m0, s39
	v_lshl_add_u64 v[224:225], s[22:23], 0, v[150:151]
	ds_read_b128 v[184:187], v170 offset:32768
	ds_read_b128 v[188:191], v170 offset:33792
	ds_read_b128 v[192:195], v170 offset:34816
	ds_read_b128 v[196:199], v170 offset:35840
	ds_read_b128 v[200:203], v170 offset:36864
	ds_read_b128 v[204:207], v170 offset:37888
	ds_read_b128 v[208:211], v170 offset:38912
	ds_read_b128 v[212:215], v170 offset:39936
	global_load_lds_dwordx4 v[224:225], off
	v_lshl_add_u64 v[224:225], s[22:23], 0, v[146:147]
	s_mov_b32 m0, s40
	s_nop 0
	global_load_lds_dwordx4 v[224:225], off
	s_waitcnt vmcnt(8)
	s_waitcnt lgkmcnt(0)
	s_barrier
	s_setprio 1
	v_mfma_f32_16x16x32_bf16 v[124:127], v[128:131], v[184:187], v[124:127]
	v_mfma_f32_16x16x32_bf16 v[120:123], v[136:139], v[184:187], v[120:123]
	v_mfma_f32_16x16x32_bf16 v[116:119], v[128:131], v[192:195], v[116:119]
	v_mfma_f32_16x16x32_bf16 v[112:115], v[136:139], v[192:195], v[112:115]
	v_mfma_f32_16x16x32_bf16 v[92:95], v[128:131], v[200:203], v[92:95]
	v_mfma_f32_16x16x32_bf16 v[88:91], v[136:139], v[200:203], v[88:91]
	v_mfma_f32_16x16x32_bf16 v[84:87], v[128:131], v[208:211], v[84:87]
	v_mfma_f32_16x16x32_bf16 v[76:79], v[136:139], v[208:211], v[76:79]
	v_mfma_f32_16x16x32_bf16 v[124:127], v[132:135], v[188:191], v[124:127]
	v_mfma_f32_16x16x32_bf16 v[120:123], v[140:143], v[188:191], v[120:123]
	v_mfma_f32_16x16x32_bf16 v[116:119], v[132:135], v[196:199], v[116:119]
	v_mfma_f32_16x16x32_bf16 v[112:115], v[140:143], v[196:199], v[112:115]
	v_mfma_f32_16x16x32_bf16 v[92:95], v[132:135], v[204:207], v[92:95]
	v_mfma_f32_16x16x32_bf16 v[88:91], v[140:143], v[204:207], v[88:91]
	v_mfma_f32_16x16x32_bf16 v[84:87], v[132:135], v[212:215], v[84:87]
	v_mfma_f32_16x16x32_bf16 v[76:79], v[140:143], v[212:215], v[76:79]
	v_mfma_f32_16x16x32_bf16 v[108:111], v[162:165], v[184:187], v[108:111]
	v_mfma_f32_16x16x32_bf16 v[104:107], v[176:179], v[184:187], v[104:107]
	v_mfma_f32_16x16x32_bf16 v[100:103], v[162:165], v[192:195], v[100:103]
	v_mfma_f32_16x16x32_bf16 v[96:99], v[176:179], v[192:195], v[96:99]
	v_mfma_f32_16x16x32_bf16 v[80:83], v[162:165], v[200:203], v[80:83]
	v_mfma_f32_16x16x32_bf16 v[72:75], v[176:179], v[200:203], v[72:75]
	v_mfma_f32_16x16x32_bf16 v[68:71], v[162:165], v[208:211], v[68:71]
	v_mfma_f32_16x16x32_bf16 v[64:67], v[176:179], v[208:211], v[64:67]
	v_mfma_f32_16x16x32_bf16 v[108:111], v[172:175], v[188:191], v[108:111]
	v_mfma_f32_16x16x32_bf16 v[104:107], v[180:183], v[188:191], v[104:107]
	v_mfma_f32_16x16x32_bf16 v[100:103], v[172:175], v[196:199], v[100:103]
	v_mfma_f32_16x16x32_bf16 v[96:99], v[180:183], v[196:199], v[96:99]
	v_mfma_f32_16x16x32_bf16 v[80:83], v[172:175], v[204:207], v[80:83]
	v_mfma_f32_16x16x32_bf16 v[72:75], v[180:183], v[204:207], v[72:75]
	v_mfma_f32_16x16x32_bf16 v[68:71], v[172:175], v[212:215], v[68:71]
	v_mfma_f32_16x16x32_bf16 v[64:67], v[180:183], v[212:215], v[64:67]
	s_setprio 0
	s_barrier
; #define PG8_STAGE(bufoff, gbase, voff) do { _Pragma("unroll") for (int _i = 0; _i < 2; ++_i) \
;         __builtin_amdgcn_global_load_lds((const unsigned*)((const char*)(gbase) + (voff)[_i]), (PG8_LAS unsigned*)(lds + (bufoff) + ldsw + _i * 8192), 16, 0, 0); } while (0)
; #define PG8_LDA(dst, b, h) do { _Pragma("unroll") for (int m = 0; m < 4; ++m) _Pragma("unroll") for (int k = 0; k < 2; ++k) dst[m][k] = *(const PG8_LAS bf16x8*)(lds + PG8_SA(b, h) + aoff + m * 2048 + k * 1024); } while (0)
; #define PG8_WAIT_V(n) asm volatile("s_waitcnt vmcnt(" #n ")" ::: "memory")
; #define PG8_WAIT_L(n) asm volatile("s_waitcnt lgkmcnt(" #n ")" ::: "memory")
; #define PG8_BAR __builtin_amdgcn_s_barrier()
; template <class Epi, class Sched, bool ALIGN_EPI = false, bool SP2 = false>
; __device__ __forceinline__ void gemm_phase(PG8_LAS unsigned char* lds, const Gemm g, const Sched& S, const Epi& E, const int wave_in) {
;     ...
;         for (int t = 0; t < nt; t += 2) {
;             const bool last = (t == nt - 2);
;             const char* a1 = cA + (size_t)(t + 1) * kstep;
;             const char* a2 = last ? nA : cA + (size_t)(t + 2) * kstep; const char* b2 = last ? nB : cB + (size_t)(t + 2) * kstep;
;             const char* a3 = a2 + kstep; const char* b3 = b2 + kstep;
;             if (last && has_next) S.a_ready(nxt);
;             if constexpr (SP2) {
;             PG8_LDB(B0, 0, 0); PG8_LDB(B1, 0, 1); PG8_SCHED; PG8_LDA(At, 0, 0); PG8_STAGE(PG8_SA(1, 1), a1 + hstepA, voffA);
;             PG8_WAIT_V(8); PG8_WAIT_L(0); PG8_BAR; PG8_MMA(0, 0, At, B0); PG8_MMA(0, 1, At, B1); PG8_BAR; PG8_SCHED;
;             PG8_LDA(At, 0, 1); PG8_STAGE(PG8_SB(0, 0), b2, voffB); PG8_STAGE(PG8_SB(0, 1), b2 + hstepB, voffB); PG8_STAGE(PG8_SA(0, 0), a2, voffA);
;             PG8_WAIT_V(8); PG8_WAIT_L(0); PG8_BAR; PG8_MMA(1, 0, At, B0); PG8_MMA(1, 1, At, B1); PG8_BAR; PG8_SCHED;
;             PG8_LDB(B0, 1, 0); PG8_LDB(B1, 1, 1); PG8_SCHED; PG8_LDA(At, 1, 0); PG8_STAGE(PG8_SA(0, 1), a2 + hstepA, voffA);
;             PG8_WAIT_V(8); PG8_WAIT_L(0); PG8_BAR; PG8_MMA(0, 0, At, B0); PG8_MMA(0, 1, At, B1); PG8_BAR; PG8_SCHED;
;             PG8_LDA(At, 1, 1); PG8_STAGE(PG8_SB(1, 0), b3, voffB); PG8_STAGE(PG8_SB(1, 1), b3 + hstepB, voffB); PG8_STAGE(PG8_SA(1, 0), a3, voffA);
;             PG8_WAIT_V(8); PG8_WAIT_L(0); PG8_BAR; PG8_MMA(1, 0, At, B0); PG8_MMA(1, 1, At, B1); PG8_BAR; PG8_SCHED;
	s_add_i32 s22, s54, s34
	v_lshl_add_u64 v[216:217], v[216:217], 0, s[10:11]
	s_mov_b32 m0, s22
	ds_read_b128 v[184:187], v170 offset:49152
	ds_read_b128 v[188:191], v170 offset:50176
	ds_read_b128 v[192:195], v170 offset:51200
	ds_read_b128 v[196:199], v170 offset:52224
	ds_read_b128 v[200:203], v170 offset:53248
	ds_read_b128 v[204:207], v170 offset:54272
	ds_read_b128 v[208:211], v170 offset:55296
	ds_read_b128 v[212:215], v170 offset:56320
	global_load_lds_dwordx4 v[216:217], off
	s_add_i32 m0, s22, 0x2000
	s_add_u32 s22, s24, 0x80080
	v_lshl_add_u64 v[216:217], v[218:219], 0, s[10:11]
	s_addc_u32 s23, s25, 0
	s_add_i32 s24, s55, s34
	global_load_lds_dwordx4 v[216:217], off
	v_lshl_add_u64 v[216:217], s[22:23], 0, v[148:149]
	s_mov_b32 m0, s24
	s_nop 0
	global_load_lds_dwordx4 v[216:217], off
	v_lshl_add_u64 v[216:217], s[22:23], 0, v[144:145]
	s_add_i32 m0, s24, 0x2000
	s_nop 0
	global_load_lds_dwordx4 v[216:217], off
	v_lshl_add_u64 v[216:217], v[220:221], 0, s[10:11]
	s_mov_b32 m0, s44
	s_nop 0
	global_load_lds_dwordx4 v[216:217], off
	v_lshl_add_u64 v[216:217], v[222:223], 0, s[10:11]
	s_mov_b32 m0, s45
	s_nop 0
	global_load_lds_dwordx4 v[216:217], off
	s_waitcnt vmcnt(8)
	s_waitcnt lgkmcnt(0)
	s_barrier
	s_setprio 1
	v_mfma_f32_16x16x32_bf16 v[60:63], v[128:131], v[184:187], v[60:63]
	v_mfma_f32_16x16x32_bf16 v[56:59], v[136:139], v[184:187], v[56:59]
	v_mfma_f32_16x16x32_bf16 v[52:55], v[128:131], v[192:195], v[52:55]
	v_mfma_f32_16x16x32_bf16 v[44:47], v[136:139], v[192:195], v[44:47]
	v_mfma_f32_16x16x32_bf16 v[36:39], v[128:131], v[200:203], v[36:39]
	v_mfma_f32_16x16x32_bf16 v[28:31], v[136:139], v[200:203], v[28:31]
	v_mfma_f32_16x16x32_bf16 v[20:23], v[128:131], v[208:211], v[20:23]
	v_mfma_f32_16x16x32_bf16 v[12:15], v[136:139], v[208:211], v[12:15]
	v_mfma_f32_16x16x32_bf16 v[60:63], v[132:135], v[188:191], v[60:63]
	v_mfma_f32_16x16x32_bf16 v[56:59], v[140:143], v[188:191], v[56:59]
	v_mfma_f32_16x16x32_bf16 v[52:55], v[132:135], v[196:199], v[52:55]
	v_mfma_f32_16x16x32_bf16 v[44:47], v[140:143], v[196:199], v[44:47]
	v_mfma_f32_16x16x32_bf16 v[36:39], v[132:135], v[204:207], v[36:39]
	v_mfma_f32_16x16x32_bf16 v[28:31], v[140:143], v[204:207], v[28:31]
	v_mfma_f32_16x16x32_bf16 v[20:23], v[132:135], v[212:215], v[20:23]
	v_mfma_f32_16x16x32_bf16 v[12:15], v[140:143], v[212:215], v[12:15]
	v_mfma_f32_16x16x32_bf16 v[48:51], v[162:165], v[184:187], v[48:51]
	v_mfma_f32_16x16x32_bf16 v[40:43], v[176:179], v[184:187], v[40:43]
	v_mfma_f32_16x16x32_bf16 v[32:35], v[162:165], v[192:195], v[32:35]
	v_mfma_f32_16x16x32_bf16 v[24:27], v[176:179], v[192:195], v[24:27]
	v_mfma_f32_16x16x32_bf16 v[16:19], v[162:165], v[200:203], v[16:19]
	v_mfma_f32_16x16x32_bf16 v[8:11], v[176:179], v[200:203], v[8:11]
	v_mfma_f32_16x16x32_bf16 v[4:7], v[162:165], v[208:211], v[4:7]
	v_mfma_f32_16x16x32_bf16 v[0:3], v[176:179], v[208:211], v[0:3]
	v_mfma_f32_16x16x32_bf16 v[48:51], v[172:175], v[188:191], v[48:51]
	v_mfma_f32_16x16x32_bf16 v[40:43], v[180:183], v[188:191], v[40:43]
	v_mfma_f32_16x16x32_bf16 v[32:35], v[172:175], v[196:199], v[32:35]
	v_mfma_f32_16x16x32_bf16 v[24:27], v[180:183], v[196:199], v[24:27]
	v_mfma_f32_16x16x32_bf16 v[16:19], v[172:175], v[204:207], v[16:19]
	v_mfma_f32_16x16x32_bf16 v[8:11], v[180:183], v[204:207], v[8:11]
	v_mfma_f32_16x16x32_bf16 v[4:7], v[172:175], v[212:215], v[4:7]
	v_mfma_f32_16x16x32_bf16 v[0:3], v[180:183], v[212:215], v[0:3]
	s_setprio 0
	s_barrier
	s_add_i32 s53, s53, 2
	s_add_u32 s51, s51, 0x100
	s_addc_u32 s52, s52, 0
	s_cmp_gt_u32 s53, 29
	s_mov_b64 s[22:23], s[4:5]
	s_cbranch_scc0 .LBB0_353
	s_branch .Lkx_4
.LBB0_353:
	ds_read_b128 v[128:131], v168
	ds_read_b128 v[132:135], v168 offset:1024
	ds_read_b128 v[136:139], v168 offset:2048
	ds_read_b128 v[140:143], v168 offset:3072
	ds_read_b128 v[162:165], v169
	ds_read_b128 v[172:175], v169 offset:1024
	ds_read_b128 v[176:179], v169 offset:2048
	ds_read_b128 v[180:183], v169 offset:3072
	s_add_u32 s4, s22, 0x100
	s_addc_u32 s5, s23, 0
	s_cmp_eq_u32 s53, 28
	s_cselect_b32 s27, s17, s5
	s_cselect_b32 s26, s16, s4
	s_cselect_b32 s25, s15, s52
	s_cselect_b32 s24, s21, s51
	v_lshl_add_u64 v[216:217], s[22:23], 0, v[154:155]
	s_add_i32 m0, s37, 0xc000
	ds_read_b128 v[184:187], v170
	ds_read_b128 v[188:191], v170 offset:1024
	ds_read_b128 v[192:195], v170 offset:2048
	ds_read_b128 v[196:199], v170 offset:3072
	ds_read_b128 v[200:203], v170 offset:4096
	ds_read_b128 v[204:207], v170 offset:5120
	ds_read_b128 v[208:211], v170 offset:6144
	ds_read_b128 v[212:215], v170 offset:7168
	global_load_lds_dwordx4 v[216:217], off
	v_lshl_add_u64 v[216:217], s[22:23], 0, v[156:157]
	s_add_i32 m0, s37, 0xe000
	s_nop 0
	global_load_lds_dwordx4 v[216:217], off
	s_waitcnt vmcnt(8)
	s_waitcnt lgkmcnt(0)
	s_barrier
; #define PG8_STAGE(bufoff, gbase, voff) do { _Pragma("unroll") for (int _i = 0; _i < 2; ++_i) \
;         __builtin_amdgcn_global_load_lds((const unsigned*)((const char*)(gbase) + (voff)[_i]), (PG8_LAS unsigned*)(lds + (bufoff) + ldsw + _i * 8192), 16, 0, 0); } while (0)
; #define PG8_LDA(dst, b, h) do { _Pragma("unroll") for (int m = 0; m < 4; ++m) _Pragma("unroll") for (int k = 0; k < 2; ++k) dst[m][k] = *(const PG8_LAS bf16x8*)(lds + PG8_SA(b, h) + aoff + m * 2048 + k * 1024); } while (0)
; #define PG8_WAIT_V(n) asm volatile("s_waitcnt vmcnt(" #n ")" ::: "memory")
; #define PG8_WAIT_L(n) asm volatile("s_waitcnt lgkmcnt(" #n ")" ::: "memory")
; #define PG8_BAR __builtin_amdgcn_s_barrier()
; template <class Epi, class Sched, bool ALIGN_EPI = false, bool SP2 = false>
; __device__ __forceinline__ void gemm_phase(PG8_LAS unsigned char* lds, const Gemm g, const Sched& S, const Epi& E, const int wave_in) {
;     ...
;         for (int t = 0; t < nt; t += 2) {
;             const bool last = (t == nt - 2);
;             const char* a1 = cA + (size_t)(t + 1) * kstep;
;             const char* a2 = last ? nA : cA + (size_t)(t + 2) * kstep; const char* b2 = last ? nB : cB + (size_t)(t + 2) * kstep;
;             const char* a3 = a2 + kstep; const char* b3 = b2 + kstep;
;             if (last && has_next) S.a_ready(nxt);
;             if constexpr (SP2) {
;             PG8_LDB(B0, 0, 0); PG8_LDB(B1, 0, 1); PG8_SCHED; PG8_LDA(At, 0, 0); PG8_STAGE(PG8_SA(1, 1), a1 + hstepA, voffA);
;             PG8_WAIT_V(8); PG8_WAIT_L(0); PG8_BAR; PG8_MMA(0, 0, At, B0); PG8_MMA(0, 1, At, B1); PG8_BAR; PG8_SCHED;
;             PG8_LDA(At, 0, 1); PG8_STAGE(PG8_SB(0, 0), b2, voffB); PG8_STAGE(PG8_SB(0, 1), b2 + hstepB, voffB); PG8_STAGE(PG8_SA(0, 0), a2, voffA);
;             PG8_WAIT_V(8); PG8_WAIT_L(0); PG8_BAR; PG8_MMA(1, 0, At, B0); PG8_MMA(1, 1, At, B1); PG8_BAR; PG8_SCHED;
;             PG8_LDB(B0, 1, 0); PG8_LDB(B1, 1, 1); PG8_SCHED; PG8_LDA(At, 1, 0); PG8_STAGE(PG8_SA(0, 1), a2 + hstepA, voffA);
;             PG8_WAIT_V(8); PG8_WAIT_L(0); PG8_BAR; PG8_MMA(0, 0, At, B0); PG8_MMA(0, 1, At, B1); PG8_BAR; PG8_SCHED;
;             PG8_LDA(At, 1, 1); PG8_STAGE(PG8_SB(1, 0), b3, voffB); PG8_STAGE(PG8_SB(1, 1), b3 + hstepB, voffB); PG8_STAGE(PG8_SA(1, 0), a3, voffA);
;             PG8_WAIT_V(8); PG8_WAIT_L(0); PG8_BAR; PG8_MMA(1, 0, At, B0); PG8_MMA(1, 1, At, B1); PG8_BAR; PG8_SCHED;
	s_setprio 1
	v_mfma_f32_16x16x32_bf16 v[124:127], v[128:131], v[184:187], v[124:127]
	v_mfma_f32_16x16x32_bf16 v[120:123], v[136:139], v[184:187], v[120:123]
	v_mfma_f32_16x16x32_bf16 v[116:119], v[128:131], v[192:195], v[116:119]
	v_mfma_f32_16x16x32_bf16 v[112:115], v[136:139], v[192:195], v[112:115]
	v_mfma_f32_16x16x32_bf16 v[92:95], v[128:131], v[200:203], v[92:95]
	v_mfma_f32_16x16x32_bf16 v[88:91], v[136:139], v[200:203], v[88:91]
	v_mfma_f32_16x16x32_bf16 v[84:87], v[128:131], v[208:211], v[84:87]
	v_mfma_f32_16x16x32_bf16 v[76:79], v[136:139], v[208:211], v[76:79]
	v_mfma_f32_16x16x32_bf16 v[124:127], v[132:135], v[188:191], v[124:127]
	v_mfma_f32_16x16x32_bf16 v[120:123], v[140:143], v[188:191], v[120:123]
	v_mfma_f32_16x16x32_bf16 v[116:119], v[132:135], v[196:199], v[116:119]
	v_mfma_f32_16x16x32_bf16 v[112:115], v[140:143], v[196:199], v[112:115]
	v_mfma_f32_16x16x32_bf16 v[92:95], v[132:135], v[204:207], v[92:95]
	v_mfma_f32_16x16x32_bf16 v[88:91], v[140:143], v[204:207], v[88:91]
	v_mfma_f32_16x16x32_bf16 v[84:87], v[132:135], v[212:215], v[84:87]
	v_mfma_f32_16x16x32_bf16 v[76:79], v[140:143], v[212:215], v[76:79]
	v_mfma_f32_16x16x32_bf16 v[108:111], v[162:165], v[184:187], v[108:111]
	v_mfma_f32_16x16x32_bf16 v[104:107], v[176:179], v[184:187], v[104:107]
	v_mfma_f32_16x16x32_bf16 v[100:103], v[162:165], v[192:195], v[100:103]
	v_mfma_f32_16x16x32_bf16 v[96:99], v[176:179], v[192:195], v[96:99]
	v_mfma_f32_16x16x32_bf16 v[80:83], v[162:165], v[200:203], v[80:83]
	v_mfma_f32_16x16x32_bf16 v[72:75], v[176:179], v[200:203], v[72:75]
	v_mfma_f32_16x16x32_bf16 v[68:71], v[162:165], v[208:211], v[68:71]
	v_mfma_f32_16x16x32_bf16 v[64:67], v[176:179], v[208:211], v[64:67]
	v_mfma_f32_16x16x32_bf16 v[108:111], v[172:175], v[188:191], v[108:111]
	v_mfma_f32_16x16x32_bf16 v[104:107], v[180:183], v[188:191], v[104:107]
	v_mfma_f32_16x16x32_bf16 v[100:103], v[172:175], v[196:199], v[100:103]
	v_mfma_f32_16x16x32_bf16 v[96:99], v[180:183], v[196:199], v[96:99]
	v_mfma_f32_16x16x32_bf16 v[80:83], v[172:175], v[204:207], v[80:83]
	v_mfma_f32_16x16x32_bf16 v[72:75], v[180:183], v[204:207], v[72:75]
	v_mfma_f32_16x16x32_bf16 v[68:71], v[172:175], v[212:215], v[68:71]
	v_mfma_f32_16x16x32_bf16 v[64:67], v[180:183], v[212:215], v[64:67]
	s_setprio 0
	s_barrier
	s_add_i32 s22, s47, s34
	v_lshl_add_u64 v[216:217], s[24:25], 0, v[148:149]
	s_mov_b32 m0, s22
	ds_read_b128 v[184:187], v170 offset:16384
	ds_read_b128 v[188:191], v170 offset:17408
	ds_read_b128 v[192:195], v170 offset:18432
	ds_read_b128 v[196:199], v170 offset:19456
	ds_read_b128 v[200:203], v170 offset:20480
	ds_read_b128 v[204:207], v170 offset:21504
	ds_read_b128 v[208:211], v170 offset:22528
	ds_read_b128 v[212:215], v170 offset:23552
	global_load_lds_dwordx4 v[216:217], off
	s_add_i32 m0, s22, 0x2000
	s_add_u32 s22, s24, 0x80000
	v_lshl_add_u64 v[218:219], s[24:25], 0, v[144:145]
	s_addc_u32 s23, s25, 0
	s_add_i32 s54, s48, s34
	global_load_lds_dwordx4 v[218:219], off
	v_lshl_add_u64 v[220:221], s[22:23], 0, v[148:149]
	s_mov_b32 m0, s54
	v_lshl_add_u64 v[222:223], s[26:27], 0, v[146:147]
	global_load_lds_dwordx4 v[220:221], off
	v_lshl_add_u64 v[220:221], s[22:23], 0, v[144:145]
	s_add_i32 m0, s54, 0x2000
	s_nop 0
	global_load_lds_dwordx4 v[220:221], off
	v_lshl_add_u64 v[220:221], s[26:27], 0, v[150:151]
	s_mov_b32 m0, s37
	s_nop 0
	global_load_lds_dwordx4 v[220:221], off
	s_mov_b32 m0, s38
	s_nop 0
	global_load_lds_dwordx4 v[222:223], off
	s_waitcnt vmcnt(8)
	s_waitcnt lgkmcnt(0)
	s_barrier
	s_setprio 1
	v_mfma_f32_16x16x32_bf16 v[60:63], v[128:131], v[184:187], v[60:63]
	v_mfma_f32_16x16x32_bf16 v[56:59], v[136:139], v[184:187], v[56:59]
	v_mfma_f32_16x16x32_bf16 v[52:55], v[128:131], v[192:195], v[52:55]
	v_mfma_f32_16x16x32_bf16 v[44:47], v[136:139], v[192:195], v[44:47]
	v_mfma_f32_16x16x32_bf16 v[36:39], v[128:131], v[200:203], v[36:39]
	v_mfma_f32_16x16x32_bf16 v[28:31], v[136:139], v[200:203], v[28:31]
	v_mfma_f32_16x16x32_bf16 v[20:23], v[128:131], v[208:211], v[20:23]
	v_mfma_f32_16x16x32_bf16 v[12:15], v[136:139], v[208:211], v[12:15]
	v_mfma_f32_16x16x32_bf16 v[60:63], v[132:135], v[188:191], v[60:63]
	v_mfma_f32_16x16x32_bf16 v[56:59], v[140:143], v[188:191], v[56:59]
	v_mfma_f32_16x16x32_bf16 v[52:55], v[132:135], v[196:199], v[52:55]
	v_mfma_f32_16x16x32_bf16 v[44:47], v[140:143], v[196:199], v[44:47]
	v_mfma_f32_16x16x32_bf16 v[36:39], v[132:135], v[204:207], v[36:39]
	v_mfma_f32_16x16x32_bf16 v[28:31], v[140:143], v[204:207], v[28:31]
	v_mfma_f32_16x16x32_bf16 v[20:23], v[132:135], v[212:215], v[20:23]
	v_mfma_f32_16x16x32_bf16 v[12:15], v[140:143], v[212:215], v[12:15]
	v_mfma_f32_16x16x32_bf16 v[48:51], v[162:165], v[184:187], v[48:51]
	v_mfma_f32_16x16x32_bf16 v[40:43], v[176:179], v[184:187], v[40:43]
	v_mfma_f32_16x16x32_bf16 v[32:35], v[162:165], v[192:195], v[32:35]
	v_mfma_f32_16x16x32_bf16 v[24:27], v[176:179], v[192:195], v[24:27]
	v_mfma_f32_16x16x32_bf16 v[16:19], v[162:165], v[200:203], v[16:19]
	v_mfma_f32_16x16x32_bf16 v[8:11], v[176:179], v[200:203], v[8:11]
	v_mfma_f32_16x16x32_bf16 v[4:7], v[162:165], v[208:211], v[4:7]
	v_mfma_f32_16x16x32_bf16 v[0:3], v[176:179], v[208:211], v[0:3]
	v_mfma_f32_16x16x32_bf16 v[48:51], v[172:175], v[188:191], v[48:51]
	v_mfma_f32_16x16x32_bf16 v[40:43], v[180:183], v[188:191], v[40:43]
	v_mfma_f32_16x16x32_bf16 v[32:35], v[172:175], v[196:199], v[32:35]
	v_mfma_f32_16x16x32_bf16 v[24:27], v[180:183], v[196:199], v[24:27]
	v_mfma_f32_16x16x32_bf16 v[16:19], v[172:175], v[204:207], v[16:19]
	v_mfma_f32_16x16x32_bf16 v[8:11], v[180:183], v[204:207], v[8:11]
	v_mfma_f32_16x16x32_bf16 v[4:7], v[172:175], v[212:215], v[4:7]
	v_mfma_f32_16x16x32_bf16 v[0:3], v[180:183], v[212:215], v[0:3]
	s_setprio 0
	s_barrier
; #define PG8_STAGE(bufoff, gbase, voff) do { _Pragma("unroll") for (int _i = 0; _i < 2; ++_i) \
;         __builtin_amdgcn_global_load_lds((const unsigned*)((const char*)(gbase) + (voff)[_i]), (PG8_LAS unsigned*)(lds + (bufoff) + ldsw + _i * 8192), 16, 0, 0); } while (0)
; #define PG8_LDA(dst, b, h) do { _Pragma("unroll") for (int m = 0; m < 4; ++m) _Pragma("unroll") for (int k = 0; k < 2; ++k) dst[m][k] = *(const PG8_LAS bf16x8*)(lds + PG8_SA(b, h) + aoff + m * 2048 + k * 1024); } while (0)
; #define PG8_WAIT_V(n) asm volatile("s_waitcnt vmcnt(" #n ")" ::: "memory")
; #define PG8_WAIT_L(n) asm volatile("s_waitcnt lgkmcnt(" #n ")" ::: "memory")
; #define PG8_BAR __builtin_amdgcn_s_barrier()
; template <class Epi, class Sched, bool ALIGN_EPI = false, bool SP2 = false>
; __device__ __forceinline__ void gemm_phase(PG8_LAS unsigned char* lds, const Gemm g, const Sched& S, const Epi& E, const int wave_in) {
;     ...
;         for (int t = 0; t < nt; t += 2) {
;             const bool last = (t == nt - 2);
;             const char* a1 = cA + (size_t)(t + 1) * kstep;
;             const char* a2 = last ? nA : cA + (size_t)(t + 2) * kstep; const char* b2 = last ? nB : cB + (size_t)(t + 2) * kstep;
;             const char* a3 = a2 + kstep; const char* b3 = b2 + kstep;
;             if (last && has_next) S.a_ready(nxt);
;             if constexpr (SP2) {
;             PG8_LDB(B0, 0, 0); PG8_LDB(B1, 0, 1); PG8_SCHED; PG8_LDA(At, 0, 0); PG8_STAGE(PG8_SA(1, 1), a1 + hstepA, voffA);
;             PG8_WAIT_V(8); PG8_WAIT_L(0); PG8_BAR; PG8_MMA(0, 0, At, B0); PG8_MMA(0, 1, At, B1); PG8_BAR; PG8_SCHED;
;             PG8_LDA(At, 0, 1); PG8_STAGE(PG8_SB(0, 0), b2, voffB); PG8_STAGE(PG8_SB(0, 1), b2 + hstepB, voffB); PG8_STAGE(PG8_SA(0, 0), a2, voffA);
;             PG8_WAIT_V(8); PG8_WAIT_L(0); PG8_BAR; PG8_MMA(1, 0, At, B0); PG8_MMA(1, 1, At, B1); PG8_BAR; PG8_SCHED;
;             PG8_LDB(B0, 1, 0); PG8_LDB(B1, 1, 1); PG8_SCHED; PG8_LDA(At, 1, 0); PG8_STAGE(PG8_SA(0, 1), a2 + hstepA, voffA);
;             PG8_WAIT_V(8); PG8_WAIT_L(0); PG8_BAR; PG8_MMA(0, 0, At, B0); PG8_MMA(0, 1, At, B1); PG8_BAR; PG8_SCHED;
;             PG8_LDA(At, 1, 1); PG8_STAGE(PG8_SB(1, 0), b3, voffB); PG8_STAGE(PG8_SB(1, 1), b3 + hstepB, voffB); PG8_STAGE(PG8_SA(1, 0), a3, voffA);
;             PG8_WAIT_V(8); PG8_WAIT_L(0); PG8_BAR; PG8_MMA(1, 0, At, B0); PG8_MMA(1, 1, At, B1); PG8_BAR; PG8_SCHED;
	s_add_i32 s54, 0, 0x18000
	s_add_i32 s55, 0, 0x1c000
	v_add_u32_e32 v140, s54, v166
	v_add_u32_e32 v171, s55, v166
	ds_read_b128 v[128:131], v140
	ds_read_b128 v[132:135], v140 offset:1024
	ds_read_b128 v[136:139], v140 offset:2048
	ds_read_b128 v[140:143], v140 offset:3072
	ds_read_b128 v[162:165], v171
	ds_read_b128 v[172:175], v171 offset:1024
	ds_read_b128 v[176:179], v171 offset:2048
	ds_read_b128 v[180:183], v171 offset:3072
	s_add_u32 s22, s26, 0x280000
	s_addc_u32 s23, s27, 0
	s_mov_b32 m0, s39
	v_lshl_add_u64 v[224:225], s[22:23], 0, v[150:151]
	ds_read_b128 v[184:187], v170 offset:32768
	ds_read_b128 v[188:191], v170 offset:33792
	ds_read_b128 v[192:195], v170 offset:34816
	ds_read_b128 v[196:199], v170 offset:35840
	ds_read_b128 v[200:203], v170 offset:36864
	ds_read_b128 v[204:207], v170 offset:37888
	ds_read_b128 v[208:211], v170 offset:38912
	ds_read_b128 v[212:215], v170 offset:39936
	global_load_lds_dwordx4 v[224:225], off
	v_lshl_add_u64 v[224:225], s[22:23], 0, v[146:147]
	s_mov_b32 m0, s40
	s_nop 0
	global_load_lds_dwordx4 v[224:225], off
	s_waitcnt vmcnt(8)
	s_waitcnt lgkmcnt(0)
	s_barrier
	s_setprio 1
	v_mfma_f32_16x16x32_bf16 v[124:127], v[128:131], v[184:187], v[124:127]
	v_mfma_f32_16x16x32_bf16 v[120:123], v[136:139], v[184:187], v[120:123]
	v_mfma_f32_16x16x32_bf16 v[116:119], v[128:131], v[192:195], v[116:119]
	v_mfma_f32_16x16x32_bf16 v[112:115], v[136:139], v[192:195], v[112:115]
	v_mfma_f32_16x16x32_bf16 v[92:95], v[128:131], v[200:203], v[92:95]
	v_mfma_f32_16x16x32_bf16 v[88:91], v[136:139], v[200:203], v[88:91]
	v_mfma_f32_16x16x32_bf16 v[84:87], v[128:131], v[208:211], v[84:87]
	v_mfma_f32_16x16x32_bf16 v[76:79], v[136:139], v[208:211], v[76:79]
	v_mfma_f32_16x16x32_bf16 v[124:127], v[132:135], v[188:191], v[124:127]
	v_mfma_f32_16x16x32_bf16 v[120:123], v[140:143], v[188:191], v[120:123]
	v_mfma_f32_16x16x32_bf16 v[116:119], v[132:135], v[196:199], v[116:119]
	v_mfma_f32_16x16x32_bf16 v[112:115], v[140:143], v[196:199], v[112:115]
	v_mfma_f32_16x16x32_bf16 v[92:95], v[132:135], v[204:207], v[92:95]
	v_mfma_f32_16x16x32_bf16 v[88:91], v[140:143], v[204:207], v[88:91]
	v_mfma_f32_16x16x32_bf16 v[84:87], v[132:135], v[212:215], v[84:87]
	v_mfma_f32_16x16x32_bf16 v[76:79], v[140:143], v[212:215], v[76:79]
	v_mfma_f32_16x16x32_bf16 v[108:111], v[162:165], v[184:187], v[108:111]
	v_mfma_f32_16x16x32_bf16 v[104:107], v[176:179], v[184:187], v[104:107]
	v_mfma_f32_16x16x32_bf16 v[100:103], v[162:165], v[192:195], v[100:103]
	v_mfma_f32_16x16x32_bf16 v[96:99], v[176:179], v[192:195], v[96:99]
	v_mfma_f32_16x16x32_bf16 v[80:83], v[162:165], v[200:203], v[80:83]
	v_mfma_f32_16x16x32_bf16 v[72:75], v[176:179], v[200:203], v[72:75]
	v_mfma_f32_16x16x32_bf16 v[68:71], v[162:165], v[208:211], v[68:71]
	v_mfma_f32_16x16x32_bf16 v[64:67], v[176:179], v[208:211], v[64:67]
	v_mfma_f32_16x16x32_bf16 v[108:111], v[172:175], v[188:191], v[108:111]
	v_mfma_f32_16x16x32_bf16 v[104:107], v[180:183], v[188:191], v[104:107]
	v_mfma_f32_16x16x32_bf16 v[100:103], v[172:175], v[196:199], v[100:103]
	v_mfma_f32_16x16x32_bf16 v[96:99], v[180:183], v[196:199], v[96:99]
	v_mfma_f32_16x16x32_bf16 v[80:83], v[172:175], v[204:207], v[80:83]
	v_mfma_f32_16x16x32_bf16 v[72:75], v[180:183], v[204:207], v[72:75]
	v_mfma_f32_16x16x32_bf16 v[68:71], v[172:175], v[212:215], v[68:71]
	v_mfma_f32_16x16x32_bf16 v[64:67], v[180:183], v[212:215], v[64:67]
	s_setprio 0
	s_barrier
	s_add_i32 s22, s54, s34
	v_lshl_add_u64 v[216:217], v[216:217], 0, s[10:11]
	s_mov_b32 m0, s22
	ds_read_b128 v[184:187], v170 offset:49152
	ds_read_b128 v[188:191], v170 offset:50176
	ds_read_b128 v[192:195], v170 offset:51200
	ds_read_b128 v[196:199], v170 offset:52224
	ds_read_b128 v[200:203], v170 offset:53248
	ds_read_b128 v[204:207], v170 offset:54272
	ds_read_b128 v[208:211], v170 offset:55296
	ds_read_b128 v[212:215], v170 offset:56320
	global_load_lds_dwordx4 v[216:217], off
	s_add_i32 m0, s22, 0x2000
	s_add_u32 s22, s24, 0x80080
	v_lshl_add_u64 v[216:217], v[218:219], 0, s[10:11]
	s_addc_u32 s23, s25, 0
	s_add_i32 s24, s55, s34
	global_load_lds_dwordx4 v[216:217], off
	v_lshl_add_u64 v[216:217], s[22:23], 0, v[148:149]
	s_mov_b32 m0, s24
	s_nop 0
	global_load_lds_dwordx4 v[216:217], off
	v_lshl_add_u64 v[216:217], s[22:23], 0, v[144:145]
	s_add_i32 m0, s24, 0x2000
	s_nop 0
	global_load_lds_dwordx4 v[216:217], off
	v_lshl_add_u64 v[216:217], v[220:221], 0, s[10:11]
	s_mov_b32 m0, s44
	s_nop 0
	global_load_lds_dwordx4 v[216:217], off
	v_lshl_add_u64 v[216:217], v[222:223], 0, s[10:11]
	s_mov_b32 m0, s45
	s_nop 0
	global_load_lds_dwordx4 v[216:217], off
	s_waitcnt vmcnt(8)
	s_waitcnt lgkmcnt(0)
	s_barrier
	s_setprio 1
	v_mfma_f32_16x16x32_bf16 v[60:63], v[128:131], v[184:187], v[60:63]
	v_mfma_f32_16x16x32_bf16 v[56:59], v[136:139], v[184:187], v[56:59]
	v_mfma_f32_16x16x32_bf16 v[52:55], v[128:131], v[192:195], v[52:55]
	v_mfma_f32_16x16x32_bf16 v[44:47], v[136:139], v[192:195], v[44:47]
	v_mfma_f32_16x16x32_bf16 v[36:39], v[128:131], v[200:203], v[36:39]
	v_mfma_f32_16x16x32_bf16 v[28:31], v[136:139], v[200:203], v[28:31]
	v_mfma_f32_16x16x32_bf16 v[20:23], v[128:131], v[208:211], v[20:23]
	v_mfma_f32_16x16x32_bf16 v[12:15], v[136:139], v[208:211], v[12:15]
	v_mfma_f32_16x16x32_bf16 v[60:63], v[132:135], v[188:191], v[60:63]
	v_mfma_f32_16x16x32_bf16 v[56:59], v[140:143], v[188:191], v[56:59]
	v_mfma_f32_16x16x32_bf16 v[52:55], v[132:135], v[196:199], v[52:55]
	v_mfma_f32_16x16x32_bf16 v[44:47], v[140:143], v[196:199], v[44:47]
	v_mfma_f32_16x16x32_bf16 v[36:39], v[132:135], v[204:207], v[36:39]
	v_mfma_f32_16x16x32_bf16 v[28:31], v[140:143], v[204:207], v[28:31]
	v_mfma_f32_16x16x32_bf16 v[20:23], v[132:135], v[212:215], v[20:23]
	v_mfma_f32_16x16x32_bf16 v[12:15], v[140:143], v[212:215], v[12:15]
	v_mfma_f32_16x16x32_bf16 v[48:51], v[162:165], v[184:187], v[48:51]
	v_mfma_f32_16x16x32_bf16 v[40:43], v[176:179], v[184:187], v[40:43]
	v_mfma_f32_16x16x32_bf16 v[32:35], v[162:165], v[192:195], v[32:35]
	v_mfma_f32_16x16x32_bf16 v[24:27], v[176:179], v[192:195], v[24:27]
	v_mfma_f32_16x16x32_bf16 v[16:19], v[162:165], v[200:203], v[16:19]
	v_mfma_f32_16x16x32_bf16 v[8:11], v[176:179], v[200:203], v[8:11]
	v_mfma_f32_16x16x32_bf16 v[4:7], v[162:165], v[208:211], v[4:7]
	v_mfma_f32_16x16x32_bf16 v[0:3], v[176:179], v[208:211], v[0:3]
	v_mfma_f32_16x16x32_bf16 v[48:51], v[172:175], v[188:191], v[48:51]
	v_mfma_f32_16x16x32_bf16 v[40:43], v[180:183], v[188:191], v[40:43]
	v_mfma_f32_16x16x32_bf16 v[32:35], v[172:175], v[196:199], v[32:35]
	v_mfma_f32_16x16x32_bf16 v[24:27], v[180:183], v[196:199], v[24:27]
	v_mfma_f32_16x16x32_bf16 v[16:19], v[172:175], v[204:207], v[16:19]
	v_mfma_f32_16x16x32_bf16 v[8:11], v[180:183], v[204:207], v[8:11]
	v_mfma_f32_16x16x32_bf16 v[4:7], v[172:175], v[212:215], v[4:7]
	v_mfma_f32_16x16x32_bf16 v[0:3], v[180:183], v[212:215], v[0:3]
	s_setprio 0
	s_barrier
	s_add_i32 s53, s53, 2
	s_add_u32 s51, s51, 0x100
	s_addc_u32 s52, s52, 0
	s_cmp_gt_u32 s53, 29
	s_mov_b64 s[22:23], s[4:5]
	s_cbranch_scc0 .LBB0_353

;     __host__ __device__ bool next(int i, Unit& u) const { const bool ok = StaticOrder::next(i, u); u.pm = 0; u.pn = 0; return ok; }
; #define PG8_STAGE(bufoff, gbase, voff) do { _Pragma("unroll") for (int _i = 0; _i < 2; ++_i) \
;         __builtin_amdgcn_global_load_lds((const unsigned*)((const char*)(gbase) + (voff)[_i]), (PG8_LAS unsigned*)(lds + (bufoff) + ldsw + _i * 8192), 16, 0, 0); } while (0)
; #define PG8_WAIT_V(n) asm volatile("s_waitcnt vmcnt(" #n ")" ::: "memory")
; template <class Epi, class Sched, bool ALIGN_EPI = false, bool SP2 = false>
; __device__ __forceinline__ void gemm_phase(PG8_LAS unsigned char* lds, const Gemm g, const Sched& S, const Epi& E, const int wave_in) {
;     ...
;         const bool has_next = S.next(ui + 1, nxt);
;         const char* nA = has_next ? (const char*)g.A + (size_t)nxt.pm * tstepA : cA; const char* nB = has_next ? (const char*)g.Bt + (size_t)nxt.pn * tstepB : cB;
;         for (int t = 0; t < nt; t += 2) {
;             const bool last = (t == nt - 2);
;             const char* a1 = cA + (size_t)(t + 1) * kstep;
;             const char* a2 = last ? nA : cA + (size_t)(t + 2) * kstep; const char* b2 = last ? nB : cB + (size_t)(t + 2) * kstep;
;             const char* a3 = a2 + kstep; const char* b3 = b2 + kstep;
;             if (last && has_next) S.a_ready(nxt);
;             if constexpr (SP2) {
;             PG8_LDB(B0, 0, 0); PG8_LDB(B1, 0, 1); PG8_SCHED; PG8_LDA(At, 0, 0); PG8_STAGE(PG8_SA(1, 1), a1 + hstepA, voffA);
;             PG8_WAIT_V(8); PG8_WAIT_L(0); PG8_BAR; PG8_MMA(0, 0, At, B0); PG8_MMA(0, 1, At, B1); PG8_BAR; PG8_SCHED;
;             PG8_LDA(At, 0, 1); PG8_STAGE(PG8_SB(0, 0), b2, voffB); PG8_STAGE(PG8_SB(0, 1), b2 + hstepB, voffB); PG8_STAGE(PG8_SA(0, 0), a2, voffA);
;             PG8_WAIT_V(8); PG8_WAIT_L(0); PG8_BAR; PG8_MMA(1, 0, At, B0); PG8_MMA(1, 1, At, B1); PG8_BAR; PG8_SCHED;
;             PG8_LDB(B0, 1, 0); PG8_LDB(B1, 1, 1); PG8_SCHED; PG8_LDA(At, 1, 0); PG8_STAGE(PG8_SA(0, 1), a2 + hstepA, voffA);
;             PG8_WAIT_V(8); PG8_WAIT_L(0); PG8_BAR; PG8_MMA(0, 0, At, B0); PG8_MMA(0, 1, At, B1); PG8_BAR; PG8_SCHED;
;             PG8_LDA(At, 1, 1); PG8_STAGE(PG8_SB(1, 0), b3, voffB); PG8_STAGE(PG8_SB(1, 1), b3 + hstepB, voffB); PG8_STAGE(PG8_SA(1, 0), a3, voffA);
;             PG8_WAIT_V(8); PG8_WAIT_L(0); PG8_BAR; PG8_MMA(1, 0, At, B0); PG8_MMA(1, 1, At, B1); PG8_BAR; PG8_SCHED;
.LBB0_478:
	s_ashr_i32 s41, s40, 31
	s_lshl_b64 s[42:43], s[40:41], 20
	s_add_u32 s42, s52, s42
	s_addc_u32 s43, s53, s43
	s_and_b64 s[44:45], s[10:11], exec
	s_cselect_b32 s1, s43, s47
	s_cselect_b32 s13, s42, s46
	s_ashr_i32 s39, s38, 31
	s_lshl_b64 s[44:45], s[38:39], 20
	s_add_u32 s44, s54, s44
	s_addc_u32 s45, s55, s45
	s_and_b64 s[50:51], s[10:11], exec
	s_cselect_b32 s39, s45, s49
	s_cselect_b32 s41, s44, s48
	s_add_u32 s46, s46, 0x80080
	s_addc_u32 s47, s47, 0
	s_add_u32 s72, s48, 0x100
	v_mov_b32_e32 v0, 0
	s_addc_u32 s73, s49, 0
	s_mov_b32 s74, -2
	ds_read_b128 v[44:47], v189
	ds_read_b128 v[48:51], v189 offset:1024
	ds_read_b128 v[52:55], v189 offset:2048
	ds_read_b128 v[56:59], v189 offset:3072
	ds_read_b128 v[60:63], v197
	ds_read_b128 v[64:67], v197 offset:1024
	ds_read_b128 v[80:83], v197 offset:2048
	ds_read_b128 v[84:87], v197 offset:3072
	s_add_u32 s48, s46, 0xfff80080
	s_addc_u32 s49, s47, -1
	s_cmp_eq_u32 s74, 28
	s_cselect_b32 s51, s1, s49
	s_cselect_b32 s50, s13, s48
	s_cselect_b32 s49, s39, s73
	s_cselect_b32 s48, s41, s72
	v_lshl_add_u64 v[224:225], s[46:47], 0, v[206:207]
	s_add_i32 m0, s57, 0xc000
	ds_read_b128 v[88:91], v199
	ds_read_b128 v[92:95], v199 offset:1024
	ds_read_b128 v[96:99], v199 offset:2048
	ds_read_b128 v[100:103], v199 offset:3072
	ds_read_b128 v[176:179], v199 offset:4096
	ds_read_b128 v[212:215], v199 offset:5120
	ds_read_b128 v[216:219], v199 offset:6144
	ds_read_b128 v[220:223], v199 offset:7168
	global_load_lds_dwordx4 v[224:225], off
	v_lshl_add_u64 v[224:225], s[46:47], 0, v[208:209]
	s_add_i32 m0, s57, 0xe000
	s_nop 0
	global_load_lds_dwordx4 v[224:225], off
	s_waitcnt vmcnt(8)
	s_waitcnt lgkmcnt(0)
	s_barrier
	s_setprio 1
	v_mfma_f32_16x16x32_bf16 v[172:175], v[44:47], v[88:91], 0
	v_mfma_f32_16x16x32_bf16 v[164:167], v[52:55], v[88:91], 0
	v_mfma_f32_16x16x32_bf16 v[156:159], v[44:47], v[96:99], 0
	v_mfma_f32_16x16x32_bf16 v[148:151], v[52:55], v[96:99], 0
	v_mfma_f32_16x16x32_bf16 v[140:143], v[44:47], v[176:179], 0
	v_mfma_f32_16x16x32_bf16 v[132:135], v[52:55], v[176:179], 0
	v_mfma_f32_16x16x32_bf16 v[124:127], v[44:47], v[216:219], 0
	v_mfma_f32_16x16x32_bf16 v[120:123], v[52:55], v[216:219], 0
	v_mfma_f32_16x16x32_bf16 v[172:175], v[48:51], v[92:95], v[172:175]
	v_mfma_f32_16x16x32_bf16 v[164:167], v[56:59], v[92:95], v[164:167]
	v_mfma_f32_16x16x32_bf16 v[156:159], v[48:51], v[100:103], v[156:159]
	v_mfma_f32_16x16x32_bf16 v[148:151], v[56:59], v[100:103], v[148:151]
	v_mfma_f32_16x16x32_bf16 v[140:143], v[48:51], v[212:215], v[140:143]
	v_mfma_f32_16x16x32_bf16 v[132:135], v[56:59], v[212:215], v[132:135]
	v_mfma_f32_16x16x32_bf16 v[124:127], v[48:51], v[220:223], v[124:127]
	v_mfma_f32_16x16x32_bf16 v[120:123], v[56:59], v[220:223], v[120:123]
	v_mfma_f32_16x16x32_bf16 v[168:171], v[60:63], v[88:91], 0
	v_mfma_f32_16x16x32_bf16 v[88:91], v[80:83], v[88:91], 0
	v_mfma_f32_16x16x32_bf16 v[168:171], v[64:67], v[92:95], v[168:171]
	v_mfma_f32_16x16x32_bf16 v[88:91], v[84:87], v[92:95], v[88:91]
	v_mfma_f32_16x16x32_bf16 v[92:95], v[60:63], v[96:99], 0
	v_mfma_f32_16x16x32_bf16 v[96:99], v[80:83], v[96:99], 0
	v_mfma_f32_16x16x32_bf16 v[128:131], v[80:83], v[176:179], 0
	v_mfma_f32_16x16x32_bf16 v[116:119], v[60:63], v[216:219], 0
	v_mfma_f32_16x16x32_bf16 v[112:115], v[80:83], v[216:219], 0
	v_mfma_f32_16x16x32_bf16 v[92:95], v[64:67], v[100:103], v[92:95]
	v_mfma_f32_16x16x32_bf16 v[96:99], v[84:87], v[100:103], v[96:99]
	v_mfma_f32_16x16x32_bf16 v[100:103], v[60:63], v[176:179], 0
	v_mfma_f32_16x16x32_bf16 v[128:131], v[84:87], v[212:215], v[128:131]
	v_mfma_f32_16x16x32_bf16 v[116:119], v[64:67], v[220:223], v[116:119]
	v_mfma_f32_16x16x32_bf16 v[112:115], v[84:87], v[220:223], v[112:115]
	v_mfma_f32_16x16x32_bf16 v[100:103], v[64:67], v[212:215], v[100:103]
	s_setprio 0
	s_barrier
	s_add_i32 s75, s68, s56
	v_lshl_add_u64 v[232:233], s[48:49], 0, v[182:183]
	s_mov_b32 m0, s75
	ds_read_b128 v[136:139], v199 offset:16384
	ds_read_b128 v[144:147], v199 offset:17408
	ds_read_b128 v[152:155], v199 offset:18432
	ds_read_b128 v[160:163], v199 offset:19456
	ds_read_b128 v[176:179], v199 offset:20480
	ds_read_b128 v[212:215], v199 offset:21504
	ds_read_b128 v[216:219], v199 offset:22528
	ds_read_b128 v[220:223], v199 offset:23552
	global_load_lds_dwordx4 v[232:233], off
	s_add_i32 m0, s75, 0x2000
	s_add_u32 s76, s48, 0x80000
	v_lshl_add_u64 v[234:235], s[48:49], 0, v[186:187]
	s_addc_u32 s77, s49, 0
	s_add_i32 s75, s69, s56
	global_load_lds_dwordx4 v[234:235], off
	v_lshl_add_u64 v[224:225], s[76:77], 0, v[182:183]
	s_mov_b32 m0, s75
	v_lshl_add_u64 v[236:237], s[50:51], 0, v[180:181]
	global_load_lds_dwordx4 v[224:225], off
	v_lshl_add_u64 v[224:225], s[76:77], 0, v[186:187]
	s_add_i32 m0, s75, 0x2000
	v_lshl_add_u64 v[238:239], s[50:51], 0, v[184:185]
	global_load_lds_dwordx4 v[224:225], off
	s_mov_b32 m0, s57
	s_nop 0
	global_load_lds_dwordx4 v[236:237], off
	s_mov_b32 m0, s58
	s_nop 0
	global_load_lds_dwordx4 v[238:239], off
	s_waitcnt vmcnt(8)
	s_waitcnt lgkmcnt(0)
	s_barrier
; #define PG8_STAGE(bufoff, gbase, voff) do { _Pragma("unroll") for (int _i = 0; _i < 2; ++_i) \
;         __builtin_amdgcn_global_load_lds((const unsigned*)((const char*)(gbase) + (voff)[_i]), (PG8_LAS unsigned*)(lds + (bufoff) + ldsw + _i * 8192), 16, 0, 0); } while (0)
; #define PG8_LDA(dst, b, h) do { _Pragma("unroll") for (int m = 0; m < 4; ++m) _Pragma("unroll") for (int k = 0; k < 2; ++k) dst[m][k] = *(const PG8_LAS bf16x8*)(lds + PG8_SA(b, h) + aoff + m * 2048 + k * 1024); } while (0)
; #define PG8_WAIT_V(n) asm volatile("s_waitcnt vmcnt(" #n ")" ::: "memory")
; #define PG8_WAIT_L(n) asm volatile("s_waitcnt lgkmcnt(" #n ")" ::: "memory")
; #define PG8_BAR __builtin_amdgcn_s_barrier()
; template <class Epi, class Sched, bool ALIGN_EPI = false, bool SP2 = false>
; __device__ __forceinline__ void gemm_phase(PG8_LAS unsigned char* lds, const Gemm g, const Sched& S, const Epi& E, const int wave_in) {
;     ...
;         for (int t = 0; t < nt; t += 2) {
;             const bool last = (t == nt - 2);
;             const char* a1 = cA + (size_t)(t + 1) * kstep;
;             const char* a2 = last ? nA : cA + (size_t)(t + 2) * kstep; const char* b2 = last ? nB : cB + (size_t)(t + 2) * kstep;
;             const char* a3 = a2 + kstep; const char* b3 = b2 + kstep;
;             if (last && has_next) S.a_ready(nxt);
;             if constexpr (SP2) {
;             PG8_LDB(B0, 0, 0); PG8_LDB(B1, 0, 1); PG8_SCHED; PG8_LDA(At, 0, 0); PG8_STAGE(PG8_SA(1, 1), a1 + hstepA, voffA);
;             PG8_WAIT_V(8); PG8_WAIT_L(0); PG8_BAR; PG8_MMA(0, 0, At, B0); PG8_MMA(0, 1, At, B1); PG8_BAR; PG8_SCHED;
;             PG8_LDA(At, 0, 1); PG8_STAGE(PG8_SB(0, 0), b2, voffB); PG8_STAGE(PG8_SB(0, 1), b2 + hstepB, voffB); PG8_STAGE(PG8_SA(0, 0), a2, voffA);
;             PG8_WAIT_V(8); PG8_WAIT_L(0); PG8_BAR; PG8_MMA(1, 0, At, B0); PG8_MMA(1, 1, At, B1); PG8_BAR; PG8_SCHED;
;             PG8_LDB(B0, 1, 0); PG8_LDB(B1, 1, 1); PG8_SCHED; PG8_LDA(At, 1, 0); PG8_STAGE(PG8_SA(0, 1), a2 + hstepA, voffA);
;             PG8_WAIT_V(8); PG8_WAIT_L(0); PG8_BAR; PG8_MMA(0, 0, At, B0); PG8_MMA(0, 1, At, B1); PG8_BAR; PG8_SCHED;
;             PG8_LDA(At, 1, 1); PG8_STAGE(PG8_SB(1, 0), b3, voffB); PG8_STAGE(PG8_SB(1, 1), b3 + hstepB, voffB); PG8_STAGE(PG8_SA(1, 0), a3, voffA);
;             PG8_WAIT_V(8); PG8_WAIT_L(0); PG8_BAR; PG8_MMA(1, 0, At, B0); PG8_MMA(1, 1, At, B1); PG8_BAR; PG8_SCHED;
	s_setprio 1
	v_mfma_f32_16x16x32_bf16 v[108:111], v[44:47], v[136:139], 0
	v_mfma_f32_16x16x32_bf16 v[76:79], v[52:55], v[136:139], 0
	v_mfma_f32_16x16x32_bf16 v[68:71], v[44:47], v[152:155], 0
	v_mfma_f32_16x16x32_bf16 v[36:39], v[52:55], v[152:155], 0
	v_mfma_f32_16x16x32_bf16 v[28:31], v[44:47], v[176:179], 0
	v_mfma_f32_16x16x32_bf16 v[20:23], v[52:55], v[176:179], 0
	v_mfma_f32_16x16x32_bf16 v[12:15], v[44:47], v[216:219], 0
	v_mfma_f32_16x16x32_bf16 v[8:11], v[52:55], v[216:219], 0
	v_mfma_f32_16x16x32_bf16 v[108:111], v[48:51], v[144:147], v[108:111]
	v_mfma_f32_16x16x32_bf16 v[76:79], v[56:59], v[144:147], v[76:79]
	v_mfma_f32_16x16x32_bf16 v[68:71], v[48:51], v[160:163], v[68:71]
	v_mfma_f32_16x16x32_bf16 v[36:39], v[56:59], v[160:163], v[36:39]
	v_mfma_f32_16x16x32_bf16 v[28:31], v[48:51], v[212:215], v[28:31]
	v_mfma_f32_16x16x32_bf16 v[20:23], v[56:59], v[212:215], v[20:23]
	v_mfma_f32_16x16x32_bf16 v[12:15], v[48:51], v[220:223], v[12:15]
	v_mfma_f32_16x16x32_bf16 v[8:11], v[56:59], v[220:223], v[8:11]
	v_mfma_f32_16x16x32_bf16 v[40:43], v[60:63], v[152:155], 0
	v_mfma_f32_16x16x32_bf16 v[32:35], v[80:83], v[152:155], 0
	v_mfma_f32_16x16x32_bf16 v[24:27], v[60:63], v[176:179], 0
	v_mfma_f32_16x16x32_bf16 v[16:19], v[80:83], v[176:179], 0
	v_mfma_f32_16x16x32_bf16 v[4:7], v[60:63], v[216:219], 0
	v_mfma_f32_16x16x32_bf16 v[0:3], v[80:83], v[216:219], 0
	v_mfma_f32_16x16x32_bf16 v[44:47], v[60:63], v[136:139], 0
	v_mfma_f32_16x16x32_bf16 v[48:51], v[80:83], v[136:139], 0
	v_mfma_f32_16x16x32_bf16 v[40:43], v[64:67], v[160:163], v[40:43]
	v_mfma_f32_16x16x32_bf16 v[32:35], v[84:87], v[160:163], v[32:35]
	v_mfma_f32_16x16x32_bf16 v[24:27], v[64:67], v[212:215], v[24:27]
	v_mfma_f32_16x16x32_bf16 v[16:19], v[84:87], v[212:215], v[16:19]
	v_mfma_f32_16x16x32_bf16 v[4:7], v[64:67], v[220:223], v[4:7]
	v_mfma_f32_16x16x32_bf16 v[0:3], v[84:87], v[220:223], v[0:3]
	v_mfma_f32_16x16x32_bf16 v[44:47], v[64:67], v[144:147], v[44:47]
	v_mfma_f32_16x16x32_bf16 v[48:51], v[84:87], v[144:147], v[48:51]
	s_setprio 0
	s_barrier
	s_add_i32 s75, 0, 0x18000
	s_add_i32 s76, 0, 0x1c000
	v_add_u32_e32 v64, s75, v195
	v_add_u32_e32 v72, s76, v195
	ds_read_b128 v[52:55], v64
	ds_read_b128 v[56:59], v64 offset:1024
	ds_read_b128 v[60:63], v64 offset:2048
	ds_read_b128 v[64:67], v64 offset:3072
	ds_read_b128 v[80:83], v72
	ds_read_b128 v[84:87], v72 offset:1024
	ds_read_b128 v[176:179], v72 offset:2048
	ds_read_b128 v[212:215], v72 offset:3072
	s_add_u32 s50, s50, 0x80000
	s_addc_u32 s51, s51, 0
	s_mov_b32 m0, s59
	v_lshl_add_u64 v[152:153], s[50:51], 0, v[180:181]
	ds_read_b128 v[72:75], v199 offset:32768
	ds_read_b128 v[104:107], v199 offset:33792
	ds_read_b128 v[136:139], v199 offset:34816
	ds_read_b128 v[144:147], v199 offset:35840
	ds_read_b128 v[216:219], v199 offset:36864
	ds_read_b128 v[220:223], v199 offset:37888
	ds_read_b128 v[224:227], v199 offset:38912
	ds_read_b128 v[228:231], v199 offset:39936
	global_load_lds_dwordx4 v[152:153], off
	v_lshl_add_u64 v[152:153], s[50:51], 0, v[184:185]
	s_mov_b32 m0, s60
	s_nop 0
	global_load_lds_dwordx4 v[152:153], off
	s_waitcnt vmcnt(8)
	s_waitcnt lgkmcnt(0)
	s_barrier
	s_setprio 1
	v_mfma_f32_16x16x32_bf16 v[152:155], v[52:55], v[72:75], v[172:175]
	v_mfma_f32_16x16x32_bf16 v[172:175], v[56:59], v[104:107], v[152:155]
	v_mfma_f32_16x16x32_bf16 v[152:155], v[60:63], v[72:75], v[164:167]
	v_mfma_f32_16x16x32_bf16 v[164:167], v[64:67], v[104:107], v[152:155]
	v_mfma_f32_16x16x32_bf16 v[152:155], v[52:55], v[136:139], v[156:159]
	v_mfma_f32_16x16x32_bf16 v[148:151], v[60:63], v[136:139], v[148:151]
	v_mfma_f32_16x16x32_bf16 v[140:143], v[52:55], v[216:219], v[140:143]
	v_mfma_f32_16x16x32_bf16 v[132:135], v[60:63], v[216:219], v[132:135]
	v_mfma_f32_16x16x32_bf16 v[124:127], v[52:55], v[224:227], v[124:127]
	v_mfma_f32_16x16x32_bf16 v[120:123], v[60:63], v[224:227], v[120:123]
	v_mfma_f32_16x16x32_bf16 v[156:159], v[56:59], v[144:147], v[152:155]
	v_mfma_f32_16x16x32_bf16 v[148:151], v[64:67], v[144:147], v[148:151]
	v_mfma_f32_16x16x32_bf16 v[140:143], v[56:59], v[220:223], v[140:143]
	v_mfma_f32_16x16x32_bf16 v[132:135], v[64:67], v[220:223], v[132:135]
	v_mfma_f32_16x16x32_bf16 v[124:127], v[56:59], v[228:231], v[124:127]
	v_mfma_f32_16x16x32_bf16 v[120:123], v[64:67], v[228:231], v[120:123]
	v_mfma_f32_16x16x32_bf16 v[152:155], v[80:83], v[72:75], v[168:171]
	v_mfma_f32_16x16x32_bf16 v[72:75], v[176:179], v[72:75], v[88:91]
	v_mfma_f32_16x16x32_bf16 v[160:163], v[212:215], v[104:107], v[72:75]
	v_mfma_f32_16x16x32_bf16 v[72:75], v[80:83], v[136:139], v[92:95]
	v_mfma_f32_16x16x32_bf16 v[168:171], v[84:87], v[104:107], v[152:155]
	v_mfma_f32_16x16x32_bf16 v[152:155], v[84:87], v[144:147], v[72:75]
	v_mfma_f32_16x16x32_bf16 v[72:75], v[176:179], v[136:139], v[96:99]
	v_mfma_f32_16x16x32_bf16 v[144:147], v[212:215], v[144:147], v[72:75]
	v_mfma_f32_16x16x32_bf16 v[72:75], v[80:83], v[216:219], v[100:103]
	v_mfma_f32_16x16x32_bf16 v[136:139], v[84:87], v[220:223], v[72:75]
	v_mfma_f32_16x16x32_bf16 v[72:75], v[176:179], v[216:219], v[128:131]
	v_mfma_f32_16x16x32_bf16 v[128:131], v[212:215], v[220:223], v[72:75]
	v_mfma_f32_16x16x32_bf16 v[72:75], v[80:83], v[224:227], v[116:119]
	v_mfma_f32_16x16x32_bf16 v[116:119], v[84:87], v[228:231], v[72:75]
	v_mfma_f32_16x16x32_bf16 v[72:75], v[176:179], v[224:227], v[112:115]
	v_mfma_f32_16x16x32_bf16 v[112:115], v[212:215], v[228:231], v[72:75]
	s_setprio 0
	s_barrier
; #define PG8_STAGE(bufoff, gbase, voff) do { _Pragma("unroll") for (int _i = 0; _i < 2; ++_i) \
;         __builtin_amdgcn_global_load_lds((const unsigned*)((const char*)(gbase) + (voff)[_i]), (PG8_LAS unsigned*)(lds + (bufoff) + ldsw + _i * 8192), 16, 0, 0); } while (0)
; #define PG8_LDA(dst, b, h) do { _Pragma("unroll") for (int m = 0; m < 4; ++m) _Pragma("unroll") for (int k = 0; k < 2; ++k) dst[m][k] = *(const PG8_LAS bf16x8*)(lds + PG8_SA(b, h) + aoff + m * 2048 + k * 1024); } while (0)
; #define PG8_WAIT_V(n) asm volatile("s_waitcnt vmcnt(" #n ")" ::: "memory")
; #define PG8_WAIT_L(n) asm volatile("s_waitcnt lgkmcnt(" #n ")" ::: "memory")
; #define PG8_BAR __builtin_amdgcn_s_barrier()
; template <class Epi, class Sched, bool ALIGN_EPI = false, bool SP2 = false>
; __device__ __forceinline__ void gemm_phase(PG8_LAS unsigned char* lds, const Gemm g, const Sched& S, const Epi& E, const int wave_in) {
;     ...
;         for (int t = 0; t < nt; t += 2) {
;             const bool last = (t == nt - 2);
;             const char* a1 = cA + (size_t)(t + 1) * kstep;
;             const char* a2 = last ? nA : cA + (size_t)(t + 2) * kstep; const char* b2 = last ? nB : cB + (size_t)(t + 2) * kstep;
;             const char* a3 = a2 + kstep; const char* b3 = b2 + kstep;
;             if (last && has_next) S.a_ready(nxt);
;             if constexpr (SP2) {
;             PG8_LDB(B0, 0, 0); PG8_LDB(B1, 0, 1); PG8_SCHED; PG8_LDA(At, 0, 0); PG8_STAGE(PG8_SA(1, 1), a1 + hstepA, voffA);
;             PG8_WAIT_V(8); PG8_WAIT_L(0); PG8_BAR; PG8_MMA(0, 0, At, B0); PG8_MMA(0, 1, At, B1); PG8_BAR; PG8_SCHED;
;             PG8_LDA(At, 0, 1); PG8_STAGE(PG8_SB(0, 0), b2, voffB); PG8_STAGE(PG8_SB(0, 1), b2 + hstepB, voffB); PG8_STAGE(PG8_SA(0, 0), a2, voffA);
;             PG8_WAIT_V(8); PG8_WAIT_L(0); PG8_BAR; PG8_MMA(1, 0, At, B0); PG8_MMA(1, 1, At, B1); PG8_BAR; PG8_SCHED;
;             PG8_LDB(B0, 1, 0); PG8_LDB(B1, 1, 1); PG8_SCHED; PG8_LDA(At, 1, 0); PG8_STAGE(PG8_SA(0, 1), a2 + hstepA, voffA);
;             PG8_WAIT_V(8); PG8_WAIT_L(0); PG8_BAR; PG8_MMA(0, 0, At, B0); PG8_MMA(0, 1, At, B1); PG8_BAR; PG8_SCHED;
;             PG8_LDA(At, 1, 1); PG8_STAGE(PG8_SB(1, 0), b3, voffB); PG8_STAGE(PG8_SB(1, 1), b3 + hstepB, voffB); PG8_STAGE(PG8_SA(1, 0), a3, voffA);
;             PG8_WAIT_V(8); PG8_WAIT_L(0); PG8_BAR; PG8_MMA(1, 0, At, B0); PG8_MMA(1, 1, At, B1); PG8_BAR; PG8_SCHED;
	s_add_i32 s50, s75, s56
	v_lshl_add_u64 v[104:105], v[232:233], 0, s[22:23]
	s_mov_b32 m0, s50
	s_nop 1
	ds_read_b128 v[72:75], v199 offset:49152
	ds_read_b128 v[88:91], v199 offset:50176
	ds_read_b128 v[92:95], v199 offset:51200
	ds_read_b128 v[96:99], v199 offset:52224
	ds_read_b128 v[100:103], v199 offset:53248
	ds_read_b128 v[216:219], v199 offset:54272
	ds_read_b128 v[220:223], v199 offset:55296
	ds_read_b128 v[224:227], v199 offset:56320
	global_load_lds_dwordx4 v[104:105], off
	s_add_i32 m0, s50, 0x2000
	s_add_u32 s48, s48, 0x80080
	v_lshl_add_u64 v[104:105], v[234:235], 0, s[22:23]
	s_addc_u32 s49, s49, 0
	s_add_i32 s50, s76, s56
	global_load_lds_dwordx4 v[104:105], off
	v_lshl_add_u64 v[104:105], s[48:49], 0, v[182:183]
	s_mov_b32 m0, s50
	s_nop 0
	global_load_lds_dwordx4 v[104:105], off
	v_lshl_add_u64 v[104:105], s[48:49], 0, v[186:187]
	s_add_i32 m0, s50, 0x2000
	s_nop 0
	global_load_lds_dwordx4 v[104:105], off
	v_lshl_add_u64 v[104:105], v[236:237], 0, s[22:23]
	s_mov_b32 m0, s63
	s_nop 0
	global_load_lds_dwordx4 v[104:105], off
	v_lshl_add_u64 v[104:105], v[238:239], 0, s[22:23]
	s_mov_b32 m0, s64
	s_nop 0
	global_load_lds_dwordx4 v[104:105], off
	s_waitcnt vmcnt(8)
	s_waitcnt lgkmcnt(0)
	s_barrier
	s_setprio 1
	v_mfma_f32_16x16x32_bf16 v[104:107], v[52:55], v[72:75], v[108:111]
	v_mfma_f32_16x16x32_bf16 v[76:79], v[60:63], v[72:75], v[76:79]
	v_mfma_f32_16x16x32_bf16 v[68:71], v[52:55], v[92:95], v[68:71]
	v_mfma_f32_16x16x32_bf16 v[36:39], v[60:63], v[92:95], v[36:39]
	v_mfma_f32_16x16x32_bf16 v[28:31], v[52:55], v[100:103], v[28:31]
	v_mfma_f32_16x16x32_bf16 v[20:23], v[60:63], v[100:103], v[20:23]
	v_mfma_f32_16x16x32_bf16 v[12:15], v[52:55], v[220:223], v[12:15]
	v_mfma_f32_16x16x32_bf16 v[8:11], v[60:63], v[220:223], v[8:11]
	v_mfma_f32_16x16x32_bf16 v[108:111], v[56:59], v[88:91], v[104:107]
	v_mfma_f32_16x16x32_bf16 v[76:79], v[64:67], v[88:91], v[76:79]
	v_mfma_f32_16x16x32_bf16 v[68:71], v[56:59], v[96:99], v[68:71]
	v_mfma_f32_16x16x32_bf16 v[36:39], v[64:67], v[96:99], v[36:39]
	v_mfma_f32_16x16x32_bf16 v[28:31], v[56:59], v[216:219], v[28:31]
	v_mfma_f32_16x16x32_bf16 v[20:23], v[64:67], v[216:219], v[20:23]
	v_mfma_f32_16x16x32_bf16 v[12:15], v[56:59], v[224:227], v[12:15]
	v_mfma_f32_16x16x32_bf16 v[8:11], v[64:67], v[224:227], v[8:11]
	v_mfma_f32_16x16x32_bf16 v[44:47], v[80:83], v[72:75], v[44:47]
	v_mfma_f32_16x16x32_bf16 v[104:107], v[84:87], v[88:91], v[44:47]
	v_mfma_f32_16x16x32_bf16 v[44:47], v[176:179], v[72:75], v[48:51]
	v_mfma_f32_16x16x32_bf16 v[40:43], v[80:83], v[92:95], v[40:43]
	v_mfma_f32_16x16x32_bf16 v[32:35], v[176:179], v[92:95], v[32:35]
	v_mfma_f32_16x16x32_bf16 v[24:27], v[80:83], v[100:103], v[24:27]
	v_mfma_f32_16x16x32_bf16 v[16:19], v[176:179], v[100:103], v[16:19]
	v_mfma_f32_16x16x32_bf16 v[4:7], v[80:83], v[220:223], v[4:7]
	v_mfma_f32_16x16x32_bf16 v[0:3], v[176:179], v[220:223], v[0:3]
	v_mfma_f32_16x16x32_bf16 v[72:75], v[212:215], v[88:91], v[44:47]
	v_mfma_f32_16x16x32_bf16 v[40:43], v[84:87], v[96:99], v[40:43]
	v_mfma_f32_16x16x32_bf16 v[32:35], v[212:215], v[96:99], v[32:35]
	v_mfma_f32_16x16x32_bf16 v[24:27], v[84:87], v[216:219], v[24:27]
	v_mfma_f32_16x16x32_bf16 v[16:19], v[212:215], v[216:219], v[16:19]
	v_mfma_f32_16x16x32_bf16 v[4:7], v[84:87], v[224:227], v[4:7]
	v_mfma_f32_16x16x32_bf16 v[0:3], v[212:215], v[224:227], v[0:3]
	s_setprio 0
	s_barrier
	s_add_i32 s74, s74, 2
	s_add_u32 s46, s46, 0x100
	s_addc_u32 s47, s47, 0
	s_add_u32 s72, s72, 0x100
	s_addc_u32 s73, s73, 0
	s_cmp_gt_u32 s74, 29
	s_cbranch_scc0 .LBB0_479
	s_branch .Lkx_6
.LBB0_479:
	ds_read_b128 v[44:47], v189
	ds_read_b128 v[48:51], v189 offset:1024
	ds_read_b128 v[52:55], v189 offset:2048
	ds_read_b128 v[56:59], v189 offset:3072
	ds_read_b128 v[60:63], v197
	ds_read_b128 v[64:67], v197 offset:1024
	ds_read_b128 v[80:83], v197 offset:2048
	ds_read_b128 v[84:87], v197 offset:3072
	s_add_u32 s48, s46, 0xfff80080
	s_addc_u32 s49, s47, -1
	s_cmp_eq_u32 s74, 28
	s_cselect_b32 s51, s1, s49
	s_cselect_b32 s50, s13, s48
	s_cselect_b32 s49, s39, s73
	s_cselect_b32 s48, s41, s72
	v_lshl_add_u64 v[224:225], s[46:47], 0, v[206:207]
	s_add_i32 m0, s57, 0xc000
	ds_read_b128 v[88:91], v199
	ds_read_b128 v[92:95], v199 offset:1024
	ds_read_b128 v[96:99], v199 offset:2048
	ds_read_b128 v[100:103], v199 offset:3072
	ds_read_b128 v[176:179], v199 offset:4096
	ds_read_b128 v[212:215], v199 offset:5120
	ds_read_b128 v[216:219], v199 offset:6144
	ds_read_b128 v[220:223], v199 offset:7168
	global_load_lds_dwordx4 v[224:225], off
	v_lshl_add_u64 v[224:225], s[46:47], 0, v[208:209]
	s_add_i32 m0, s57, 0xe000
	s_nop 0
	global_load_lds_dwordx4 v[224:225], off
	s_waitcnt vmcnt(8)
	s_waitcnt lgkmcnt(0)
	s_barrier
; #define PG8_STAGE(bufoff, gbase, voff) do { _Pragma("unroll") for (int _i = 0; _i < 2; ++_i) \
;         __builtin_amdgcn_global_load_lds((const unsigned*)((const char*)(gbase) + (voff)[_i]), (PG8_LAS unsigned*)(lds + (bufoff) + ldsw + _i * 8192), 16, 0, 0); } while (0)
; #define PG8_LDA(dst, b, h) do { _Pragma("unroll") for (int m = 0; m < 4; ++m) _Pragma("unroll") for (int k = 0; k < 2; ++k) dst[m][k] = *(const PG8_LAS bf16x8*)(lds + PG8_SA(b, h) + aoff + m * 2048 + k * 1024); } while (0)
; #define PG8_WAIT_V(n) asm volatile("s_waitcnt vmcnt(" #n ")" ::: "memory")
; #define PG8_WAIT_L(n) asm volatile("s_waitcnt lgkmcnt(" #n ")" ::: "memory")
; #define PG8_BAR __builtin_amdgcn_s_barrier()
; template <class Epi, class Sched, bool ALIGN_EPI = false, bool SP2 = false>
; __device__ __forceinline__ void gemm_phase(PG8_LAS unsigned char* lds, const Gemm g, const Sched& S, const Epi& E, const int wave_in) {
;     ...
;         for (int t = 0; t < nt; t += 2) {
;             const bool last = (t == nt - 2);
;             const char* a1 = cA + (size_t)(t + 1) * kstep;
;             const char* a2 = last ? nA : cA + (size_t)(t + 2) * kstep; const char* b2 = last ? nB : cB + (size_t)(t + 2) * kstep;
;             const char* a3 = a2 + kstep; const char* b3 = b2 + kstep;
;             if (last && has_next) S.a_ready(nxt);
;             if constexpr (SP2) {
;             PG8_LDB(B0, 0, 0); PG8_LDB(B1, 0, 1); PG8_SCHED; PG8_LDA(At, 0, 0); PG8_STAGE(PG8_SA(1, 1), a1 + hstepA, voffA);
;             PG8_WAIT_V(8); PG8_WAIT_L(0); PG8_BAR; PG8_MMA(0, 0, At, B0); PG8_MMA(0, 1, At, B1); PG8_BAR; PG8_SCHED;
;             PG8_LDA(At, 0, 1); PG8_STAGE(PG8_SB(0, 0), b2, voffB); PG8_STAGE(PG8_SB(0, 1), b2 + hstepB, voffB); PG8_STAGE(PG8_SA(0, 0), a2, voffA);
;             PG8_WAIT_V(8); PG8_WAIT_L(0); PG8_BAR; PG8_MMA(1, 0, At, B0); PG8_MMA(1, 1, At, B1); PG8_BAR; PG8_SCHED;
;             PG8_LDB(B0, 1, 0); PG8_LDB(B1, 1, 1); PG8_SCHED; PG8_LDA(At, 1, 0); PG8_STAGE(PG8_SA(0, 1), a2 + hstepA, voffA);
;             PG8_WAIT_V(8); PG8_WAIT_L(0); PG8_BAR; PG8_MMA(0, 0, At, B0); PG8_MMA(0, 1, At, B1); PG8_BAR; PG8_SCHED;
;             PG8_LDA(At, 1, 1); PG8_STAGE(PG8_SB(1, 0), b3, voffB); PG8_STAGE(PG8_SB(1, 1), b3 + hstepB, voffB); PG8_STAGE(PG8_SA(1, 0), a3, voffA);
;             PG8_WAIT_V(8); PG8_WAIT_L(0); PG8_BAR; PG8_MMA(1, 0, At, B0); PG8_MMA(1, 1, At, B1); PG8_BAR; PG8_SCHED;
	s_setprio 1
	v_mfma_f32_16x16x32_bf16 v[172:175], v[44:47], v[88:91], v[172:175]
	v_mfma_f32_16x16x32_bf16 v[164:167], v[52:55], v[88:91], v[164:167]
	v_mfma_f32_16x16x32_bf16 v[156:159], v[44:47], v[96:99], v[156:159]
	v_mfma_f32_16x16x32_bf16 v[148:151], v[52:55], v[96:99], v[148:151]
	v_mfma_f32_16x16x32_bf16 v[140:143], v[44:47], v[176:179], v[140:143]
	v_mfma_f32_16x16x32_bf16 v[132:135], v[52:55], v[176:179], v[132:135]
	v_mfma_f32_16x16x32_bf16 v[124:127], v[44:47], v[216:219], v[124:127]
	v_mfma_f32_16x16x32_bf16 v[120:123], v[52:55], v[216:219], v[120:123]
	v_mfma_f32_16x16x32_bf16 v[172:175], v[48:51], v[92:95], v[172:175]
	v_mfma_f32_16x16x32_bf16 v[164:167], v[56:59], v[92:95], v[164:167]
	v_mfma_f32_16x16x32_bf16 v[156:159], v[48:51], v[100:103], v[156:159]
	v_mfma_f32_16x16x32_bf16 v[148:151], v[56:59], v[100:103], v[148:151]
	v_mfma_f32_16x16x32_bf16 v[140:143], v[48:51], v[212:215], v[140:143]
	v_mfma_f32_16x16x32_bf16 v[132:135], v[56:59], v[212:215], v[132:135]
	v_mfma_f32_16x16x32_bf16 v[124:127], v[48:51], v[220:223], v[124:127]
	v_mfma_f32_16x16x32_bf16 v[120:123], v[56:59], v[220:223], v[120:123]
	v_mfma_f32_16x16x32_bf16 v[168:171], v[60:63], v[88:91], v[168:171]
	v_mfma_f32_16x16x32_bf16 v[88:91], v[80:83], v[88:91], v[160:163]
	v_mfma_f32_16x16x32_bf16 v[168:171], v[64:67], v[92:95], v[168:171]
	v_mfma_f32_16x16x32_bf16 v[88:91], v[84:87], v[92:95], v[88:91]
	v_mfma_f32_16x16x32_bf16 v[92:95], v[60:63], v[96:99], v[152:155]
	v_mfma_f32_16x16x32_bf16 v[96:99], v[80:83], v[96:99], v[144:147]
	v_mfma_f32_16x16x32_bf16 v[128:131], v[80:83], v[176:179], v[128:131]
	v_mfma_f32_16x16x32_bf16 v[116:119], v[60:63], v[216:219], v[116:119]
	v_mfma_f32_16x16x32_bf16 v[112:115], v[80:83], v[216:219], v[112:115]
	v_mfma_f32_16x16x32_bf16 v[92:95], v[64:67], v[100:103], v[92:95]
	v_mfma_f32_16x16x32_bf16 v[96:99], v[84:87], v[100:103], v[96:99]
	v_mfma_f32_16x16x32_bf16 v[100:103], v[60:63], v[176:179], v[136:139]
	v_mfma_f32_16x16x32_bf16 v[128:131], v[84:87], v[212:215], v[128:131]
	v_mfma_f32_16x16x32_bf16 v[116:119], v[64:67], v[220:223], v[116:119]
	v_mfma_f32_16x16x32_bf16 v[112:115], v[84:87], v[220:223], v[112:115]
	v_mfma_f32_16x16x32_bf16 v[100:103], v[64:67], v[212:215], v[100:103]
	s_setprio 0
	s_barrier
	s_add_i32 s75, s68, s56
	v_lshl_add_u64 v[232:233], s[48:49], 0, v[182:183]
	s_mov_b32 m0, s75
	ds_read_b128 v[136:139], v199 offset:16384
	ds_read_b128 v[144:147], v199 offset:17408
	ds_read_b128 v[152:155], v199 offset:18432
	ds_read_b128 v[160:163], v199 offset:19456
	ds_read_b128 v[176:179], v199 offset:20480
	ds_read_b128 v[212:215], v199 offset:21504
	ds_read_b128 v[216:219], v199 offset:22528
	ds_read_b128 v[220:223], v199 offset:23552
	global_load_lds_dwordx4 v[232:233], off
	s_add_i32 m0, s75, 0x2000
	s_add_u32 s76, s48, 0x80000
	v_lshl_add_u64 v[234:235], s[48:49], 0, v[186:187]
	s_addc_u32 s77, s49, 0
	s_add_i32 s75, s69, s56
	global_load_lds_dwordx4 v[234:235], off
	v_lshl_add_u64 v[224:225], s[76:77], 0, v[182:183]
	s_mov_b32 m0, s75
	v_lshl_add_u64 v[236:237], s[50:51], 0, v[180:181]
	global_load_lds_dwordx4 v[224:225], off
	v_lshl_add_u64 v[224:225], s[76:77], 0, v[186:187]
	s_add_i32 m0, s75, 0x2000
	v_lshl_add_u64 v[238:239], s[50:51], 0, v[184:185]
	global_load_lds_dwordx4 v[224:225], off
	s_mov_b32 m0, s57
	s_nop 0
	global_load_lds_dwordx4 v[236:237], off
	s_mov_b32 m0, s58
	s_nop 0
	global_load_lds_dwordx4 v[238:239], off
	s_waitcnt vmcnt(8)
	s_waitcnt lgkmcnt(0)
	s_barrier
	s_setprio 1
	v_mfma_f32_16x16x32_bf16 v[108:111], v[44:47], v[136:139], v[108:111]
	v_mfma_f32_16x16x32_bf16 v[76:79], v[52:55], v[136:139], v[76:79]
	v_mfma_f32_16x16x32_bf16 v[68:71], v[44:47], v[152:155], v[68:71]
	v_mfma_f32_16x16x32_bf16 v[36:39], v[52:55], v[152:155], v[36:39]
	v_mfma_f32_16x16x32_bf16 v[28:31], v[44:47], v[176:179], v[28:31]
	v_mfma_f32_16x16x32_bf16 v[20:23], v[52:55], v[176:179], v[20:23]
	v_mfma_f32_16x16x32_bf16 v[12:15], v[44:47], v[216:219], v[12:15]
	v_mfma_f32_16x16x32_bf16 v[8:11], v[52:55], v[216:219], v[8:11]
	v_mfma_f32_16x16x32_bf16 v[108:111], v[48:51], v[144:147], v[108:111]
	v_mfma_f32_16x16x32_bf16 v[76:79], v[56:59], v[144:147], v[76:79]
	v_mfma_f32_16x16x32_bf16 v[68:71], v[48:51], v[160:163], v[68:71]
	v_mfma_f32_16x16x32_bf16 v[36:39], v[56:59], v[160:163], v[36:39]
	v_mfma_f32_16x16x32_bf16 v[28:31], v[48:51], v[212:215], v[28:31]
	v_mfma_f32_16x16x32_bf16 v[20:23], v[56:59], v[212:215], v[20:23]
	v_mfma_f32_16x16x32_bf16 v[12:15], v[48:51], v[220:223], v[12:15]
	v_mfma_f32_16x16x32_bf16 v[8:11], v[56:59], v[220:223], v[8:11]
	v_mfma_f32_16x16x32_bf16 v[40:43], v[60:63], v[152:155], v[40:43]
	v_mfma_f32_16x16x32_bf16 v[32:35], v[80:83], v[152:155], v[32:35]
	v_mfma_f32_16x16x32_bf16 v[24:27], v[60:63], v[176:179], v[24:27]
	v_mfma_f32_16x16x32_bf16 v[16:19], v[80:83], v[176:179], v[16:19]
	v_mfma_f32_16x16x32_bf16 v[4:7], v[60:63], v[216:219], v[4:7]
	v_mfma_f32_16x16x32_bf16 v[0:3], v[80:83], v[216:219], v[0:3]
	v_mfma_f32_16x16x32_bf16 v[44:47], v[60:63], v[136:139], v[104:107]
	v_mfma_f32_16x16x32_bf16 v[48:51], v[80:83], v[136:139], v[72:75]
	v_mfma_f32_16x16x32_bf16 v[40:43], v[64:67], v[160:163], v[40:43]
	v_mfma_f32_16x16x32_bf16 v[32:35], v[84:87], v[160:163], v[32:35]
	v_mfma_f32_16x16x32_bf16 v[24:27], v[64:67], v[212:215], v[24:27]
	v_mfma_f32_16x16x32_bf16 v[16:19], v[84:87], v[212:215], v[16:19]
	v_mfma_f32_16x16x32_bf16 v[4:7], v[64:67], v[220:223], v[4:7]
	v_mfma_f32_16x16x32_bf16 v[0:3], v[84:87], v[220:223], v[0:3]
	v_mfma_f32_16x16x32_bf16 v[44:47], v[64:67], v[144:147], v[44:47]
	v_mfma_f32_16x16x32_bf16 v[48:51], v[84:87], v[144:147], v[48:51]
	s_setprio 0
	s_barrier
; #define PG8_STAGE(bufoff, gbase, voff) do { _Pragma("unroll") for (int _i = 0; _i < 2; ++_i) \
;         __builtin_amdgcn_global_load_lds((const unsigned*)((const char*)(gbase) + (voff)[_i]), (PG8_LAS unsigned*)(lds + (bufoff) + ldsw + _i * 8192), 16, 0, 0); } while (0)
; #define PG8_LDA(dst, b, h) do { _Pragma("unroll") for (int m = 0; m < 4; ++m) _Pragma("unroll") for (int k = 0; k < 2; ++k) dst[m][k] = *(const PG8_LAS bf16x8*)(lds + PG8_SA(b, h) + aoff + m * 2048 + k * 1024); } while (0)
; #define PG8_WAIT_V(n) asm volatile("s_waitcnt vmcnt(" #n ")" ::: "memory")
; #define PG8_WAIT_L(n) asm volatile("s_waitcnt lgkmcnt(" #n ")" ::: "memory")
; #define PG8_BAR __builtin_amdgcn_s_barrier()
; template <class Epi, class Sched, bool ALIGN_EPI = false, bool SP2 = false>
; __device__ __forceinline__ void gemm_phase(PG8_LAS unsigned char* lds, const Gemm g, const Sched& S, const Epi& E, const int wave_in) {
;     ...
;         for (int t = 0; t < nt; t += 2) {
;             const bool last = (t == nt - 2);
;             const char* a1 = cA + (size_t)(t + 1) * kstep;
;             const char* a2 = last ? nA : cA + (size_t)(t + 2) * kstep; const char* b2 = last ? nB : cB + (size_t)(t + 2) * kstep;
;             const char* a3 = a2 + kstep; const char* b3 = b2 + kstep;
;             if (last && has_next) S.a_ready(nxt);
;             if constexpr (SP2) {
;             PG8_LDB(B0, 0, 0); PG8_LDB(B1, 0, 1); PG8_SCHED; PG8_LDA(At, 0, 0); PG8_STAGE(PG8_SA(1, 1), a1 + hstepA, voffA);
;             PG8_WAIT_V(8); PG8_WAIT_L(0); PG8_BAR; PG8_MMA(0, 0, At, B0); PG8_MMA(0, 1, At, B1); PG8_BAR; PG8_SCHED;
;             PG8_LDA(At, 0, 1); PG8_STAGE(PG8_SB(0, 0), b2, voffB); PG8_STAGE(PG8_SB(0, 1), b2 + hstepB, voffB); PG8_STAGE(PG8_SA(0, 0), a2, voffA);
;             PG8_WAIT_V(8); PG8_WAIT_L(0); PG8_BAR; PG8_MMA(1, 0, At, B0); PG8_MMA(1, 1, At, B1); PG8_BAR; PG8_SCHED;
;             PG8_LDB(B0, 1, 0); PG8_LDB(B1, 1, 1); PG8_SCHED; PG8_LDA(At, 1, 0); PG8_STAGE(PG8_SA(0, 1), a2 + hstepA, voffA);
;             PG8_WAIT_V(8); PG8_WAIT_L(0); PG8_BAR; PG8_MMA(0, 0, At, B0); PG8_MMA(0, 1, At, B1); PG8_BAR; PG8_SCHED;
;             PG8_LDA(At, 1, 1); PG8_STAGE(PG8_SB(1, 0), b3, voffB); PG8_STAGE(PG8_SB(1, 1), b3 + hstepB, voffB); PG8_STAGE(PG8_SA(1, 0), a3, voffA);
;             PG8_WAIT_V(8); PG8_WAIT_L(0); PG8_BAR; PG8_MMA(1, 0, At, B0); PG8_MMA(1, 1, At, B1); PG8_BAR; PG8_SCHED;
	s_add_i32 s75, 0, 0x18000
	s_add_i32 s76, 0, 0x1c000
	v_add_u32_e32 v64, s75, v195
	v_add_u32_e32 v72, s76, v195
	ds_read_b128 v[52:55], v64
	ds_read_b128 v[56:59], v64 offset:1024
	ds_read_b128 v[60:63], v64 offset:2048
	ds_read_b128 v[64:67], v64 offset:3072
	ds_read_b128 v[80:83], v72
	ds_read_b128 v[84:87], v72 offset:1024
	ds_read_b128 v[176:179], v72 offset:2048
	ds_read_b128 v[212:215], v72 offset:3072
	s_add_u32 s50, s50, 0x80000
	s_addc_u32 s51, s51, 0
	s_mov_b32 m0, s59
	v_lshl_add_u64 v[152:153], s[50:51], 0, v[180:181]
	ds_read_b128 v[72:75], v199 offset:32768
	ds_read_b128 v[104:107], v199 offset:33792
	ds_read_b128 v[136:139], v199 offset:34816
	ds_read_b128 v[144:147], v199 offset:35840
	ds_read_b128 v[216:219], v199 offset:36864
	ds_read_b128 v[220:223], v199 offset:37888
	ds_read_b128 v[224:227], v199 offset:38912
	ds_read_b128 v[228:231], v199 offset:39936
	global_load_lds_dwordx4 v[152:153], off
	v_lshl_add_u64 v[152:153], s[50:51], 0, v[184:185]
	s_mov_b32 m0, s60
	s_nop 0
	global_load_lds_dwordx4 v[152:153], off
	s_waitcnt vmcnt(8)
	s_waitcnt lgkmcnt(0)
	s_barrier
	s_setprio 1
	v_mfma_f32_16x16x32_bf16 v[152:155], v[52:55], v[72:75], v[172:175]
	v_mfma_f32_16x16x32_bf16 v[172:175], v[56:59], v[104:107], v[152:155]
	v_mfma_f32_16x16x32_bf16 v[152:155], v[60:63], v[72:75], v[164:167]
	v_mfma_f32_16x16x32_bf16 v[164:167], v[64:67], v[104:107], v[152:155]
	v_mfma_f32_16x16x32_bf16 v[152:155], v[52:55], v[136:139], v[156:159]
	v_mfma_f32_16x16x32_bf16 v[148:151], v[60:63], v[136:139], v[148:151]
	v_mfma_f32_16x16x32_bf16 v[140:143], v[52:55], v[216:219], v[140:143]
	v_mfma_f32_16x16x32_bf16 v[132:135], v[60:63], v[216:219], v[132:135]
	v_mfma_f32_16x16x32_bf16 v[124:127], v[52:55], v[224:227], v[124:127]
	v_mfma_f32_16x16x32_bf16 v[120:123], v[60:63], v[224:227], v[120:123]
	v_mfma_f32_16x16x32_bf16 v[156:159], v[56:59], v[144:147], v[152:155]
	v_mfma_f32_16x16x32_bf16 v[148:151], v[64:67], v[144:147], v[148:151]
	v_mfma_f32_16x16x32_bf16 v[140:143], v[56:59], v[220:223], v[140:143]
	v_mfma_f32_16x16x32_bf16 v[132:135], v[64:67], v[220:223], v[132:135]
	v_mfma_f32_16x16x32_bf16 v[124:127], v[56:59], v[228:231], v[124:127]
	v_mfma_f32_16x16x32_bf16 v[120:123], v[64:67], v[228:231], v[120:123]
	v_mfma_f32_16x16x32_bf16 v[152:155], v[80:83], v[72:75], v[168:171]
	v_mfma_f32_16x16x32_bf16 v[72:75], v[176:179], v[72:75], v[88:91]
	v_mfma_f32_16x16x32_bf16 v[160:163], v[212:215], v[104:107], v[72:75]
	v_mfma_f32_16x16x32_bf16 v[72:75], v[80:83], v[136:139], v[92:95]
	v_mfma_f32_16x16x32_bf16 v[168:171], v[84:87], v[104:107], v[152:155]
	v_mfma_f32_16x16x32_bf16 v[152:155], v[84:87], v[144:147], v[72:75]
	v_mfma_f32_16x16x32_bf16 v[72:75], v[176:179], v[136:139], v[96:99]
	v_mfma_f32_16x16x32_bf16 v[144:147], v[212:215], v[144:147], v[72:75]
	v_mfma_f32_16x16x32_bf16 v[72:75], v[80:83], v[216:219], v[100:103]
	v_mfma_f32_16x16x32_bf16 v[136:139], v[84:87], v[220:223], v[72:75]
	v_mfma_f32_16x16x32_bf16 v[72:75], v[176:179], v[216:219], v[128:131]
	v_mfma_f32_16x16x32_bf16 v[128:131], v[212:215], v[220:223], v[72:75]
	v_mfma_f32_16x16x32_bf16 v[72:75], v[80:83], v[224:227], v[116:119]
	v_mfma_f32_16x16x32_bf16 v[116:119], v[84:87], v[228:231], v[72:75]
	v_mfma_f32_16x16x32_bf16 v[72:75], v[176:179], v[224:227], v[112:115]
	v_mfma_f32_16x16x32_bf16 v[112:115], v[212:215], v[228:231], v[72:75]
	s_setprio 0
	s_barrier
	s_add_i32 s50, s75, s56
	v_lshl_add_u64 v[104:105], v[232:233], 0, s[22:23]
	s_mov_b32 m0, s50
	s_nop 1
	ds_read_b128 v[72:75], v199 offset:49152
	ds_read_b128 v[88:91], v199 offset:50176
	ds_read_b128 v[92:95], v199 offset:51200
	ds_read_b128 v[96:99], v199 offset:52224
	ds_read_b128 v[100:103], v199 offset:53248
	ds_read_b128 v[216:219], v199 offset:54272
	ds_read_b128 v[220:223], v199 offset:55296
	ds_read_b128 v[224:227], v199 offset:56320
	global_load_lds_dwordx4 v[104:105], off
	s_add_i32 m0, s50, 0x2000
	s_add_u32 s48, s48, 0x80080
	v_lshl_add_u64 v[104:105], v[234:235], 0, s[22:23]
	s_addc_u32 s49, s49, 0
	s_add_i32 s50, s76, s56
	global_load_lds_dwordx4 v[104:105], off
	v_lshl_add_u64 v[104:105], s[48:49], 0, v[182:183]
	s_mov_b32 m0, s50
	s_nop 0
	global_load_lds_dwordx4 v[104:105], off
	v_lshl_add_u64 v[104:105], s[48:49], 0, v[186:187]
	s_add_i32 m0, s50, 0x2000
	s_nop 0
	global_load_lds_dwordx4 v[104:105], off
	v_lshl_add_u64 v[104:105], v[236:237], 0, s[22:23]
	s_mov_b32 m0, s63
	s_nop 0
	global_load_lds_dwordx4 v[104:105], off
	v_lshl_add_u64 v[104:105], v[238:239], 0, s[22:23]
	s_mov_b32 m0, s64
	s_nop 0
	global_load_lds_dwordx4 v[104:105], off
	s_waitcnt vmcnt(8)
	s_waitcnt lgkmcnt(0)
	s_barrier
	s_setprio 1
	v_mfma_f32_16x16x32_bf16 v[104:107], v[52:55], v[72:75], v[108:111]
	v_mfma_f32_16x16x32_bf16 v[76:79], v[60:63], v[72:75], v[76:79]
	v_mfma_f32_16x16x32_bf16 v[68:71], v[52:55], v[92:95], v[68:71]
	v_mfma_f32_16x16x32_bf16 v[36:39], v[60:63], v[92:95], v[36:39]
	v_mfma_f32_16x16x32_bf16 v[28:31], v[52:55], v[100:103], v[28:31]
	v_mfma_f32_16x16x32_bf16 v[20:23], v[60:63], v[100:103], v[20:23]
	v_mfma_f32_16x16x32_bf16 v[12:15], v[52:55], v[220:223], v[12:15]
	v_mfma_f32_16x16x32_bf16 v[8:11], v[60:63], v[220:223], v[8:11]
	v_mfma_f32_16x16x32_bf16 v[108:111], v[56:59], v[88:91], v[104:107]
	v_mfma_f32_16x16x32_bf16 v[76:79], v[64:67], v[88:91], v[76:79]
	v_mfma_f32_16x16x32_bf16 v[68:71], v[56:59], v[96:99], v[68:71]
	v_mfma_f32_16x16x32_bf16 v[36:39], v[64:67], v[96:99], v[36:39]
	v_mfma_f32_16x16x32_bf16 v[28:31], v[56:59], v[216:219], v[28:31]
	v_mfma_f32_16x16x32_bf16 v[20:23], v[64:67], v[216:219], v[20:23]
	v_mfma_f32_16x16x32_bf16 v[12:15], v[56:59], v[224:227], v[12:15]
	v_mfma_f32_16x16x32_bf16 v[8:11], v[64:67], v[224:227], v[8:11]
	v_mfma_f32_16x16x32_bf16 v[44:47], v[80:83], v[72:75], v[44:47]
	v_mfma_f32_16x16x32_bf16 v[104:107], v[84:87], v[88:91], v[44:47]
	v_mfma_f32_16x16x32_bf16 v[44:47], v[176:179], v[72:75], v[48:51]
	v_mfma_f32_16x16x32_bf16 v[40:43], v[80:83], v[92:95], v[40:43]
	v_mfma_f32_16x16x32_bf16 v[32:35], v[176:179], v[92:95], v[32:35]
	v_mfma_f32_16x16x32_bf16 v[24:27], v[80:83], v[100:103], v[24:27]
	v_mfma_f32_16x16x32_bf16 v[16:19], v[176:179], v[100:103], v[16:19]
	v_mfma_f32_16x16x32_bf16 v[4:7], v[80:83], v[220:223], v[4:7]
	v_mfma_f32_16x16x32_bf16 v[0:3], v[176:179], v[220:223], v[0:3]
	v_mfma_f32_16x16x32_bf16 v[72:75], v[212:215], v[88:91], v[44:47]
	v_mfma_f32_16x16x32_bf16 v[40:43], v[84:87], v[96:99], v[40:43]
	v_mfma_f32_16x16x32_bf16 v[32:35], v[212:215], v[96:99], v[32:35]
	v_mfma_f32_16x16x32_bf16 v[24:27], v[84:87], v[216:219], v[24:27]
	v_mfma_f32_16x16x32_bf16 v[16:19], v[212:215], v[216:219], v[16:19]
	v_mfma_f32_16x16x32_bf16 v[4:7], v[84:87], v[224:227], v[4:7]
	v_mfma_f32_16x16x32_bf16 v[0:3], v[212:215], v[224:227], v[0:3]
	s_setprio 0
	s_barrier
	s_add_i32 s74, s74, 2
	s_add_u32 s46, s46, 0x100
	s_addc_u32 s47, s47, 0
	s_add_u32 s72, s72, 0x100
	s_addc_u32 s73, s73, 0
	s_cmp_gt_u32 s74, 29
	s_cbranch_scc0 .LBB0_479

;     __host__ __device__ bool next(int i, Unit& u) const { const bool ok = StaticOrder::next(i, u); u.pm = 0; u.pn = 0; return ok; }
; #define PG8_STAGE(bufoff, gbase, voff) do { _Pragma("unroll") for (int _i = 0; _i < 2; ++_i) \
;         __builtin_amdgcn_global_load_lds((const unsigned*)((const char*)(gbase) + (voff)[_i]), (PG8_LAS unsigned*)(lds + (bufoff) + ldsw + _i * 8192), 16, 0, 0); } while (0)
; #define PG8_WAIT_V(n) asm volatile("s_waitcnt vmcnt(" #n ")" ::: "memory")
; template <class Epi, class Sched, bool ALIGN_EPI = false, bool SP2 = false>
; __device__ __forceinline__ void gemm_phase(PG8_LAS unsigned char* lds, const Gemm g, const Sched& S, const Epi& E, const int wave_in) {
;     ...
;         const bool has_next = S.next(ui + 1, nxt);
;         const char* nA = has_next ? (const char*)g.A + (size_t)nxt.pm * tstepA : cA; const char* nB = has_next ? (const char*)g.Bt + (size_t)nxt.pn * tstepB : cB;
;         for (int t = 0; t < nt; t += 2) {
;             const bool last = (t == nt - 2);
;             const char* a1 = cA + (size_t)(t + 1) * kstep;
;             const char* a2 = last ? nA : cA + (size_t)(t + 2) * kstep; const char* b2 = last ? nB : cB + (size_t)(t + 2) * kstep;
;             const char* a3 = a2 + kstep; const char* b3 = b2 + kstep;
;             if (last && has_next) S.a_ready(nxt);
;             if constexpr (SP2) {
;             PG8_LDB(B0, 0, 0); PG8_LDB(B1, 0, 1); PG8_SCHED; PG8_LDA(At, 0, 0); PG8_STAGE(PG8_SA(1, 1), a1 + hstepA, voffA);
;             PG8_WAIT_V(8); PG8_WAIT_L(0); PG8_BAR; PG8_MMA(0, 0, At, B0); PG8_MMA(0, 1, At, B1); PG8_BAR; PG8_SCHED;
;             PG8_LDA(At, 0, 1); PG8_STAGE(PG8_SB(0, 0), b2, voffB); PG8_STAGE(PG8_SB(0, 1), b2 + hstepB, voffB); PG8_STAGE(PG8_SA(0, 0), a2, voffA);
;             PG8_WAIT_V(8); PG8_WAIT_L(0); PG8_BAR; PG8_MMA(1, 0, At, B0); PG8_MMA(1, 1, At, B1); PG8_BAR; PG8_SCHED;
;             PG8_LDB(B0, 1, 0); PG8_LDB(B1, 1, 1); PG8_SCHED; PG8_LDA(At, 1, 0); PG8_STAGE(PG8_SA(0, 1), a2 + hstepA, voffA);
;             PG8_WAIT_V(8); PG8_WAIT_L(0); PG8_BAR; PG8_MMA(0, 0, At, B0); PG8_MMA(0, 1, At, B1); PG8_BAR; PG8_SCHED;
;             PG8_LDA(At, 1, 1); PG8_STAGE(PG8_SB(1, 0), b3, voffB); PG8_STAGE(PG8_SB(1, 1), b3 + hstepB, voffB); PG8_STAGE(PG8_SA(1, 0), a3, voffA);
;             PG8_WAIT_V(8); PG8_WAIT_L(0); PG8_BAR; PG8_MMA(1, 0, At, B0); PG8_MMA(1, 1, At, B1); PG8_BAR; PG8_SCHED;
.LBB0_634:
	s_add_u32 s17, s20, 0x100
	v_mov_b32_e32 v0, 0
	s_addc_u32 s52, s21, 0
	s_mov_b32 s53, -2
	ds_read_b128 v[64:67], v230
	ds_read_b128 v[68:71], v230 offset:1024
	ds_read_b128 v[72:75], v230 offset:2048
	ds_read_b128 v[76:79], v230 offset:3072
	ds_read_b128 v[144:147], v231
	ds_read_b128 v[148:151], v231 offset:1024
	ds_read_b128 v[170:173], v231 offset:2048
	ds_read_b128 v[174:177], v231 offset:3072
	s_add_u32 s20, s18, 0x100
	s_addc_u32 s21, s19, 0
	s_cmpk_eq_i32 s53, 0x52
	s_cselect_b32 s25, s5, s21
	s_cselect_b32 s24, s4, s20
	s_cselect_b32 s23, s15, s52
	s_cselect_b32 s22, s14, s17
	v_lshl_add_u64 v[210:211], s[18:19], 0, v[162:163]
	s_add_i32 m0, s35, 0xc000
	ds_read_b128 v[178:181], v232
	ds_read_b128 v[182:185], v232 offset:1024
	ds_read_b128 v[186:189], v232 offset:2048
	ds_read_b128 v[190:193], v232 offset:3072
	ds_read_b128 v[194:197], v232 offset:4096
	ds_read_b128 v[198:201], v232 offset:5120
	ds_read_b128 v[202:205], v232 offset:6144
	ds_read_b128 v[206:209], v232 offset:7168
	global_load_lds_dwordx4 v[210:211], off
	v_lshl_add_u64 v[210:211], s[18:19], 0, v[164:165]
	s_add_i32 m0, s35, 0xe000
	s_nop 0
	global_load_lds_dwordx4 v[210:211], off
	s_waitcnt vmcnt(8)
	s_waitcnt lgkmcnt(0)
	s_barrier
	s_setprio 1
	v_mfma_f32_16x16x32_bf16 v[140:143], v[64:67], v[178:181], 0
	v_mfma_f32_16x16x32_bf16 v[136:139], v[72:75], v[178:181], 0
	v_mfma_f32_16x16x32_bf16 v[128:131], v[64:67], v[186:189], 0
	v_mfma_f32_16x16x32_bf16 v[120:123], v[72:75], v[186:189], 0
	v_mfma_f32_16x16x32_bf16 v[116:119], v[64:67], v[194:197], 0
	v_mfma_f32_16x16x32_bf16 v[112:115], v[72:75], v[194:197], 0
	v_mfma_f32_16x16x32_bf16 v[100:103], v[64:67], v[202:205], 0
	v_mfma_f32_16x16x32_bf16 v[96:99], v[72:75], v[202:205], 0
	v_mfma_f32_16x16x32_bf16 v[140:143], v[68:71], v[182:185], v[140:143]
	v_mfma_f32_16x16x32_bf16 v[136:139], v[76:79], v[182:185], v[136:139]
	v_mfma_f32_16x16x32_bf16 v[128:131], v[68:71], v[190:193], v[128:131]
	v_mfma_f32_16x16x32_bf16 v[120:123], v[76:79], v[190:193], v[120:123]
	v_mfma_f32_16x16x32_bf16 v[116:119], v[68:71], v[198:201], v[116:119]
	v_mfma_f32_16x16x32_bf16 v[112:115], v[76:79], v[198:201], v[112:115]
	v_mfma_f32_16x16x32_bf16 v[100:103], v[68:71], v[206:209], v[100:103]
	v_mfma_f32_16x16x32_bf16 v[96:99], v[76:79], v[206:209], v[96:99]
	v_mfma_f32_16x16x32_bf16 v[132:135], v[144:147], v[178:181], 0
	v_mfma_f32_16x16x32_bf16 v[124:127], v[170:173], v[178:181], 0
	v_mfma_f32_16x16x32_bf16 v[108:111], v[144:147], v[186:189], 0
	v_mfma_f32_16x16x32_bf16 v[104:107], v[170:173], v[186:189], 0
	v_mfma_f32_16x16x32_bf16 v[92:95], v[144:147], v[194:197], 0
	v_mfma_f32_16x16x32_bf16 v[88:91], v[170:173], v[194:197], 0
	v_mfma_f32_16x16x32_bf16 v[84:87], v[144:147], v[202:205], 0
	v_mfma_f32_16x16x32_bf16 v[80:83], v[170:173], v[202:205], 0
	v_mfma_f32_16x16x32_bf16 v[132:135], v[148:151], v[182:185], v[132:135]
	v_mfma_f32_16x16x32_bf16 v[124:127], v[174:177], v[182:185], v[124:127]
	v_mfma_f32_16x16x32_bf16 v[108:111], v[148:151], v[190:193], v[108:111]
	v_mfma_f32_16x16x32_bf16 v[104:107], v[174:177], v[190:193], v[104:107]
	v_mfma_f32_16x16x32_bf16 v[92:95], v[148:151], v[198:201], v[92:95]
	v_mfma_f32_16x16x32_bf16 v[88:91], v[174:177], v[198:201], v[88:91]
	v_mfma_f32_16x16x32_bf16 v[84:87], v[148:151], v[206:209], v[84:87]
	v_mfma_f32_16x16x32_bf16 v[80:83], v[174:177], v[206:209], v[80:83]
	s_setprio 0
	s_barrier
	s_add_i32 s18, s45, s30
	v_lshl_add_u64 v[210:211], s[22:23], 0, v[156:157]
	s_mov_b32 m0, s18
	ds_read_b128 v[178:181], v232 offset:16384
	ds_read_b128 v[182:185], v232 offset:17408
	ds_read_b128 v[186:189], v232 offset:18432
	ds_read_b128 v[190:193], v232 offset:19456
	ds_read_b128 v[194:197], v232 offset:20480
	ds_read_b128 v[198:201], v232 offset:21504
	ds_read_b128 v[202:205], v232 offset:22528
	ds_read_b128 v[206:209], v232 offset:23552
	global_load_lds_dwordx4 v[210:211], off
	s_add_i32 m0, s18, 0x2000
	s_add_u32 s18, s22, 0x158000
	v_lshl_add_u64 v[212:213], s[22:23], 0, v[152:153]
	s_addc_u32 s19, s23, 0
	s_add_i32 s54, s46, s30
	global_load_lds_dwordx4 v[212:213], off
	v_lshl_add_u64 v[214:215], s[18:19], 0, v[156:157]
	s_mov_b32 m0, s54
	v_lshl_add_u64 v[216:217], s[24:25], 0, v[154:155]
	global_load_lds_dwordx4 v[214:215], off
	v_lshl_add_u64 v[214:215], s[18:19], 0, v[152:153]
	s_add_i32 m0, s54, 0x2000
	s_nop 0
	global_load_lds_dwordx4 v[214:215], off
	v_lshl_add_u64 v[214:215], s[24:25], 0, v[158:159]
	s_mov_b32 m0, s35
	s_nop 0
	global_load_lds_dwordx4 v[214:215], off
	s_mov_b32 m0, s36
	s_nop 0
	global_load_lds_dwordx4 v[216:217], off
	s_waitcnt vmcnt(8)
	s_waitcnt lgkmcnt(0)
	s_barrier
; #define PG8_STAGE(bufoff, gbase, voff) do { _Pragma("unroll") for (int _i = 0; _i < 2; ++_i) \
;         __builtin_amdgcn_global_load_lds((const unsigned*)((const char*)(gbase) + (voff)[_i]), (PG8_LAS unsigned*)(lds + (bufoff) + ldsw + _i * 8192), 16, 0, 0); } while (0)
; #define PG8_LDA(dst, b, h) do { _Pragma("unroll") for (int m = 0; m < 4; ++m) _Pragma("unroll") for (int k = 0; k < 2; ++k) dst[m][k] = *(const PG8_LAS bf16x8*)(lds + PG8_SA(b, h) + aoff + m * 2048 + k * 1024); } while (0)
; #define PG8_WAIT_V(n) asm volatile("s_waitcnt vmcnt(" #n ")" ::: "memory")
; #define PG8_WAIT_L(n) asm volatile("s_waitcnt lgkmcnt(" #n ")" ::: "memory")
; #define PG8_BAR __builtin_amdgcn_s_barrier()
; template <class Epi, class Sched, bool ALIGN_EPI = false, bool SP2 = false>
; __device__ __forceinline__ void gemm_phase(PG8_LAS unsigned char* lds, const Gemm g, const Sched& S, const Epi& E, const int wave_in) {
;     ...
;         for (int t = 0; t < nt; t += 2) {
;             const bool last = (t == nt - 2);
;             const char* a1 = cA + (size_t)(t + 1) * kstep;
;             const char* a2 = last ? nA : cA + (size_t)(t + 2) * kstep; const char* b2 = last ? nB : cB + (size_t)(t + 2) * kstep;
;             const char* a3 = a2 + kstep; const char* b3 = b2 + kstep;
;             if (last && has_next) S.a_ready(nxt);
;             if constexpr (SP2) {
;             PG8_LDB(B0, 0, 0); PG8_LDB(B1, 0, 1); PG8_SCHED; PG8_LDA(At, 0, 0); PG8_STAGE(PG8_SA(1, 1), a1 + hstepA, voffA);
;             PG8_WAIT_V(8); PG8_WAIT_L(0); PG8_BAR; PG8_MMA(0, 0, At, B0); PG8_MMA(0, 1, At, B1); PG8_BAR; PG8_SCHED;
;             PG8_LDA(At, 0, 1); PG8_STAGE(PG8_SB(0, 0), b2, voffB); PG8_STAGE(PG8_SB(0, 1), b2 + hstepB, voffB); PG8_STAGE(PG8_SA(0, 0), a2, voffA);
;             PG8_WAIT_V(8); PG8_WAIT_L(0); PG8_BAR; PG8_MMA(1, 0, At, B0); PG8_MMA(1, 1, At, B1); PG8_BAR; PG8_SCHED;
;             PG8_LDB(B0, 1, 0); PG8_LDB(B1, 1, 1); PG8_SCHED; PG8_LDA(At, 1, 0); PG8_STAGE(PG8_SA(0, 1), a2 + hstepA, voffA);
;             PG8_WAIT_V(8); PG8_WAIT_L(0); PG8_BAR; PG8_MMA(0, 0, At, B0); PG8_MMA(0, 1, At, B1); PG8_BAR; PG8_SCHED;
;             PG8_LDA(At, 1, 1); PG8_STAGE(PG8_SB(1, 0), b3, voffB); PG8_STAGE(PG8_SB(1, 1), b3 + hstepB, voffB); PG8_STAGE(PG8_SA(1, 0), a3, voffA);
;             PG8_WAIT_V(8); PG8_WAIT_L(0); PG8_BAR; PG8_MMA(1, 0, At, B0); PG8_MMA(1, 1, At, B1); PG8_BAR; PG8_SCHED;
	s_setprio 1
	v_mfma_f32_16x16x32_bf16 v[60:63], v[64:67], v[178:181], 0
	v_mfma_f32_16x16x32_bf16 v[56:59], v[72:75], v[178:181], 0
	v_mfma_f32_16x16x32_bf16 v[48:51], v[64:67], v[186:189], 0
	v_mfma_f32_16x16x32_bf16 v[40:43], v[72:75], v[186:189], 0
	v_mfma_f32_16x16x32_bf16 v[32:35], v[64:67], v[194:197], 0
	v_mfma_f32_16x16x32_bf16 v[24:27], v[72:75], v[194:197], 0
	v_mfma_f32_16x16x32_bf16 v[16:19], v[64:67], v[202:205], 0
	v_mfma_f32_16x16x32_bf16 v[8:11], v[72:75], v[202:205], 0
	v_mfma_f32_16x16x32_bf16 v[60:63], v[68:71], v[182:185], v[60:63]
	v_mfma_f32_16x16x32_bf16 v[56:59], v[76:79], v[182:185], v[56:59]
	v_mfma_f32_16x16x32_bf16 v[48:51], v[68:71], v[190:193], v[48:51]
	v_mfma_f32_16x16x32_bf16 v[40:43], v[76:79], v[190:193], v[40:43]
	v_mfma_f32_16x16x32_bf16 v[32:35], v[68:71], v[198:201], v[32:35]
	v_mfma_f32_16x16x32_bf16 v[24:27], v[76:79], v[198:201], v[24:27]
	v_mfma_f32_16x16x32_bf16 v[16:19], v[68:71], v[206:209], v[16:19]
	v_mfma_f32_16x16x32_bf16 v[8:11], v[76:79], v[206:209], v[8:11]
	v_mfma_f32_16x16x32_bf16 v[52:55], v[144:147], v[178:181], 0
	v_mfma_f32_16x16x32_bf16 v[44:47], v[170:173], v[178:181], 0
	v_mfma_f32_16x16x32_bf16 v[36:39], v[144:147], v[186:189], 0
	v_mfma_f32_16x16x32_bf16 v[28:31], v[170:173], v[186:189], 0
	v_mfma_f32_16x16x32_bf16 v[20:23], v[144:147], v[194:197], 0
	v_mfma_f32_16x16x32_bf16 v[12:15], v[170:173], v[194:197], 0
	v_mfma_f32_16x16x32_bf16 v[4:7], v[144:147], v[202:205], 0
	v_mfma_f32_16x16x32_bf16 v[0:3], v[170:173], v[202:205], 0
	v_mfma_f32_16x16x32_bf16 v[52:55], v[148:151], v[182:185], v[52:55]
	v_mfma_f32_16x16x32_bf16 v[44:47], v[174:177], v[182:185], v[44:47]
	v_mfma_f32_16x16x32_bf16 v[36:39], v[148:151], v[190:193], v[36:39]
	v_mfma_f32_16x16x32_bf16 v[28:31], v[174:177], v[190:193], v[28:31]
	v_mfma_f32_16x16x32_bf16 v[20:23], v[148:151], v[198:201], v[20:23]
	v_mfma_f32_16x16x32_bf16 v[12:15], v[174:177], v[198:201], v[12:15]
	v_mfma_f32_16x16x32_bf16 v[4:7], v[148:151], v[206:209], v[4:7]
	v_mfma_f32_16x16x32_bf16 v[0:3], v[174:177], v[206:209], v[0:3]
	s_setprio 0
	s_barrier
	s_add_i32 s54, 0, 0x18000
	s_add_i32 s55, 0, 0x1c000
	v_add_u32_e32 v76, s54, v228
	v_add_u32_e32 v174, s55, v228
	ds_read_b128 v[64:67], v76
	ds_read_b128 v[68:71], v76 offset:1024
	ds_read_b128 v[72:75], v76 offset:2048
	ds_read_b128 v[76:79], v76 offset:3072
	ds_read_b128 v[144:147], v174
	ds_read_b128 v[148:151], v174 offset:1024
	ds_read_b128 v[170:173], v174 offset:2048
	ds_read_b128 v[174:177], v174 offset:3072
	s_add_u32 s18, s24, 0x158000
	s_addc_u32 s19, s25, 0
	s_mov_b32 m0, s37
	v_lshl_add_u64 v[218:219], s[18:19], 0, v[158:159]
	ds_read_b128 v[178:181], v232 offset:32768
	ds_read_b128 v[182:185], v232 offset:33792
	ds_read_b128 v[186:189], v232 offset:34816
	ds_read_b128 v[190:193], v232 offset:35840
	ds_read_b128 v[194:197], v232 offset:36864
	ds_read_b128 v[198:201], v232 offset:37888
	ds_read_b128 v[202:205], v232 offset:38912
	ds_read_b128 v[206:209], v232 offset:39936
	global_load_lds_dwordx4 v[218:219], off
	v_lshl_add_u64 v[218:219], s[18:19], 0, v[154:155]
	s_mov_b32 m0, s38
	s_nop 0
	global_load_lds_dwordx4 v[218:219], off
	s_waitcnt vmcnt(8)
	s_waitcnt lgkmcnt(0)
	s_barrier
	s_setprio 1
	v_mfma_f32_16x16x32_bf16 v[140:143], v[64:67], v[178:181], v[140:143]
	v_mfma_f32_16x16x32_bf16 v[136:139], v[72:75], v[178:181], v[136:139]
	v_mfma_f32_16x16x32_bf16 v[128:131], v[64:67], v[186:189], v[128:131]
	v_mfma_f32_16x16x32_bf16 v[120:123], v[72:75], v[186:189], v[120:123]
	v_mfma_f32_16x16x32_bf16 v[116:119], v[64:67], v[194:197], v[116:119]
	v_mfma_f32_16x16x32_bf16 v[112:115], v[72:75], v[194:197], v[112:115]
	v_mfma_f32_16x16x32_bf16 v[100:103], v[64:67], v[202:205], v[100:103]
	v_mfma_f32_16x16x32_bf16 v[96:99], v[72:75], v[202:205], v[96:99]
	v_mfma_f32_16x16x32_bf16 v[140:143], v[68:71], v[182:185], v[140:143]
	v_mfma_f32_16x16x32_bf16 v[136:139], v[76:79], v[182:185], v[136:139]
	v_mfma_f32_16x16x32_bf16 v[128:131], v[68:71], v[190:193], v[128:131]
	v_mfma_f32_16x16x32_bf16 v[120:123], v[76:79], v[190:193], v[120:123]
	v_mfma_f32_16x16x32_bf16 v[116:119], v[68:71], v[198:201], v[116:119]
	v_mfma_f32_16x16x32_bf16 v[112:115], v[76:79], v[198:201], v[112:115]
	v_mfma_f32_16x16x32_bf16 v[100:103], v[68:71], v[206:209], v[100:103]
	v_mfma_f32_16x16x32_bf16 v[96:99], v[76:79], v[206:209], v[96:99]
	v_mfma_f32_16x16x32_bf16 v[132:135], v[144:147], v[178:181], v[132:135]
	v_mfma_f32_16x16x32_bf16 v[124:127], v[170:173], v[178:181], v[124:127]
	v_mfma_f32_16x16x32_bf16 v[108:111], v[144:147], v[186:189], v[108:111]
	v_mfma_f32_16x16x32_bf16 v[104:107], v[170:173], v[186:189], v[104:107]
	v_mfma_f32_16x16x32_bf16 v[92:95], v[144:147], v[194:197], v[92:95]
	v_mfma_f32_16x16x32_bf16 v[88:91], v[170:173], v[194:197], v[88:91]
	v_mfma_f32_16x16x32_bf16 v[84:87], v[144:147], v[202:205], v[84:87]
	v_mfma_f32_16x16x32_bf16 v[80:83], v[170:173], v[202:205], v[80:83]
	v_mfma_f32_16x16x32_bf16 v[132:135], v[148:151], v[182:185], v[132:135]
	v_mfma_f32_16x16x32_bf16 v[124:127], v[174:177], v[182:185], v[124:127]
	v_mfma_f32_16x16x32_bf16 v[108:111], v[148:151], v[190:193], v[108:111]
	v_mfma_f32_16x16x32_bf16 v[104:107], v[174:177], v[190:193], v[104:107]
	v_mfma_f32_16x16x32_bf16 v[92:95], v[148:151], v[198:201], v[92:95]
	v_mfma_f32_16x16x32_bf16 v[88:91], v[174:177], v[198:201], v[88:91]
	v_mfma_f32_16x16x32_bf16 v[84:87], v[148:151], v[206:209], v[84:87]
	v_mfma_f32_16x16x32_bf16 v[80:83], v[174:177], v[206:209], v[80:83]
	s_setprio 0
	s_barrier
; #define PG8_STAGE(bufoff, gbase, voff) do { _Pragma("unroll") for (int _i = 0; _i < 2; ++_i) \
;         __builtin_amdgcn_global_load_lds((const unsigned*)((const char*)(gbase) + (voff)[_i]), (PG8_LAS unsigned*)(lds + (bufoff) + ldsw + _i * 8192), 16, 0, 0); } while (0)
; #define PG8_LDA(dst, b, h) do { _Pragma("unroll") for (int m = 0; m < 4; ++m) _Pragma("unroll") for (int k = 0; k < 2; ++k) dst[m][k] = *(const PG8_LAS bf16x8*)(lds + PG8_SA(b, h) + aoff + m * 2048 + k * 1024); } while (0)
; #define PG8_WAIT_V(n) asm volatile("s_waitcnt vmcnt(" #n ")" ::: "memory")
; #define PG8_WAIT_L(n) asm volatile("s_waitcnt lgkmcnt(" #n ")" ::: "memory")
; #define PG8_BAR __builtin_amdgcn_s_barrier()
; template <class Epi, class Sched, bool ALIGN_EPI = false, bool SP2 = false>
; __device__ __forceinline__ void gemm_phase(PG8_LAS unsigned char* lds, const Gemm g, const Sched& S, const Epi& E, const int wave_in) {
;     ...
;         for (int t = 0; t < nt; t += 2) {
;             const bool last = (t == nt - 2);
;             const char* a1 = cA + (size_t)(t + 1) * kstep;
;             const char* a2 = last ? nA : cA + (size_t)(t + 2) * kstep; const char* b2 = last ? nB : cB + (size_t)(t + 2) * kstep;
;             const char* a3 = a2 + kstep; const char* b3 = b2 + kstep;
;             if (last && has_next) S.a_ready(nxt);
;             if constexpr (SP2) {
;             PG8_LDB(B0, 0, 0); PG8_LDB(B1, 0, 1); PG8_SCHED; PG8_LDA(At, 0, 0); PG8_STAGE(PG8_SA(1, 1), a1 + hstepA, voffA);
;             PG8_WAIT_V(8); PG8_WAIT_L(0); PG8_BAR; PG8_MMA(0, 0, At, B0); PG8_MMA(0, 1, At, B1); PG8_BAR; PG8_SCHED;
;             PG8_LDA(At, 0, 1); PG8_STAGE(PG8_SB(0, 0), b2, voffB); PG8_STAGE(PG8_SB(0, 1), b2 + hstepB, voffB); PG8_STAGE(PG8_SA(0, 0), a2, voffA);
;             PG8_WAIT_V(8); PG8_WAIT_L(0); PG8_BAR; PG8_MMA(1, 0, At, B0); PG8_MMA(1, 1, At, B1); PG8_BAR; PG8_SCHED;
;             PG8_LDB(B0, 1, 0); PG8_LDB(B1, 1, 1); PG8_SCHED; PG8_LDA(At, 1, 0); PG8_STAGE(PG8_SA(0, 1), a2 + hstepA, voffA);
;             PG8_WAIT_V(8); PG8_WAIT_L(0); PG8_BAR; PG8_MMA(0, 0, At, B0); PG8_MMA(0, 1, At, B1); PG8_BAR; PG8_SCHED;
;             PG8_LDA(At, 1, 1); PG8_STAGE(PG8_SB(1, 0), b3, voffB); PG8_STAGE(PG8_SB(1, 1), b3 + hstepB, voffB); PG8_STAGE(PG8_SA(1, 0), a3, voffA);
;             PG8_WAIT_V(8); PG8_WAIT_L(0); PG8_BAR; PG8_MMA(1, 0, At, B0); PG8_MMA(1, 1, At, B1); PG8_BAR; PG8_SCHED;
	s_add_i32 s18, s54, s30
	v_lshl_add_u64 v[210:211], v[210:211], 0, s[6:7]
	s_mov_b32 m0, s18
	ds_read_b128 v[178:181], v232 offset:49152
	ds_read_b128 v[182:185], v232 offset:50176
	ds_read_b128 v[186:189], v232 offset:51200
	ds_read_b128 v[190:193], v232 offset:52224
	ds_read_b128 v[194:197], v232 offset:53248
	ds_read_b128 v[198:201], v232 offset:54272
	ds_read_b128 v[202:205], v232 offset:55296
	ds_read_b128 v[206:209], v232 offset:56320
	global_load_lds_dwordx4 v[210:211], off
	s_add_i32 m0, s18, 0x2000
	s_add_u32 s18, s22, 0x158080
	v_lshl_add_u64 v[210:211], v[212:213], 0, s[6:7]
	s_addc_u32 s19, s23, 0
	s_add_i32 s22, s55, s30
	global_load_lds_dwordx4 v[210:211], off
	v_lshl_add_u64 v[210:211], s[18:19], 0, v[156:157]
	s_mov_b32 m0, s22
	s_nop 0
	global_load_lds_dwordx4 v[210:211], off
	v_lshl_add_u64 v[210:211], s[18:19], 0, v[152:153]
	s_add_i32 m0, s22, 0x2000
	s_nop 0
	global_load_lds_dwordx4 v[210:211], off
	v_lshl_add_u64 v[210:211], v[214:215], 0, s[6:7]
	s_mov_b32 m0, s42
	s_nop 0
	global_load_lds_dwordx4 v[210:211], off
	v_lshl_add_u64 v[210:211], v[216:217], 0, s[6:7]
	s_mov_b32 m0, s43
	s_nop 0
	global_load_lds_dwordx4 v[210:211], off
	s_waitcnt vmcnt(8)
	s_waitcnt lgkmcnt(0)
	s_barrier
	s_setprio 1
	v_mfma_f32_16x16x32_bf16 v[60:63], v[64:67], v[178:181], v[60:63]
	v_mfma_f32_16x16x32_bf16 v[56:59], v[72:75], v[178:181], v[56:59]
	v_mfma_f32_16x16x32_bf16 v[48:51], v[64:67], v[186:189], v[48:51]
	v_mfma_f32_16x16x32_bf16 v[40:43], v[72:75], v[186:189], v[40:43]
	v_mfma_f32_16x16x32_bf16 v[32:35], v[64:67], v[194:197], v[32:35]
	v_mfma_f32_16x16x32_bf16 v[24:27], v[72:75], v[194:197], v[24:27]
	v_mfma_f32_16x16x32_bf16 v[16:19], v[64:67], v[202:205], v[16:19]
	v_mfma_f32_16x16x32_bf16 v[8:11], v[72:75], v[202:205], v[8:11]
	v_mfma_f32_16x16x32_bf16 v[60:63], v[68:71], v[182:185], v[60:63]
	v_mfma_f32_16x16x32_bf16 v[56:59], v[76:79], v[182:185], v[56:59]
	v_mfma_f32_16x16x32_bf16 v[48:51], v[68:71], v[190:193], v[48:51]
	v_mfma_f32_16x16x32_bf16 v[40:43], v[76:79], v[190:193], v[40:43]
	v_mfma_f32_16x16x32_bf16 v[32:35], v[68:71], v[198:201], v[32:35]
	v_mfma_f32_16x16x32_bf16 v[24:27], v[76:79], v[198:201], v[24:27]
	v_mfma_f32_16x16x32_bf16 v[16:19], v[68:71], v[206:209], v[16:19]
	v_mfma_f32_16x16x32_bf16 v[8:11], v[76:79], v[206:209], v[8:11]
	v_mfma_f32_16x16x32_bf16 v[52:55], v[144:147], v[178:181], v[52:55]
	v_mfma_f32_16x16x32_bf16 v[44:47], v[170:173], v[178:181], v[44:47]
	v_mfma_f32_16x16x32_bf16 v[36:39], v[144:147], v[186:189], v[36:39]
	v_mfma_f32_16x16x32_bf16 v[28:31], v[170:173], v[186:189], v[28:31]
	v_mfma_f32_16x16x32_bf16 v[20:23], v[144:147], v[194:197], v[20:23]
	v_mfma_f32_16x16x32_bf16 v[12:15], v[170:173], v[194:197], v[12:15]
	v_mfma_f32_16x16x32_bf16 v[4:7], v[144:147], v[202:205], v[4:7]
	v_mfma_f32_16x16x32_bf16 v[0:3], v[170:173], v[202:205], v[0:3]
	v_mfma_f32_16x16x32_bf16 v[52:55], v[148:151], v[182:185], v[52:55]
	v_mfma_f32_16x16x32_bf16 v[44:47], v[174:177], v[182:185], v[44:47]
	v_mfma_f32_16x16x32_bf16 v[36:39], v[148:151], v[190:193], v[36:39]
	v_mfma_f32_16x16x32_bf16 v[28:31], v[174:177], v[190:193], v[28:31]
	v_mfma_f32_16x16x32_bf16 v[20:23], v[148:151], v[198:201], v[20:23]
	v_mfma_f32_16x16x32_bf16 v[12:15], v[174:177], v[198:201], v[12:15]
	v_mfma_f32_16x16x32_bf16 v[4:7], v[148:151], v[206:209], v[4:7]
	v_mfma_f32_16x16x32_bf16 v[0:3], v[174:177], v[206:209], v[0:3]
	s_setprio 0
	s_barrier
	s_add_i32 s53, s53, 2
	s_add_u32 s17, s17, 0x100
	s_addc_u32 s52, s52, 0
	s_cmpk_gt_u32 s53, 0x53
	s_mov_b64 s[18:19], s[20:21]
	s_cbranch_scc0 .LBB0_635
	s_branch .Lkx_8
.LBB0_635:
	ds_read_b128 v[64:67], v230
	ds_read_b128 v[68:71], v230 offset:1024
	ds_read_b128 v[72:75], v230 offset:2048
	ds_read_b128 v[76:79], v230 offset:3072
	ds_read_b128 v[144:147], v231
	ds_read_b128 v[148:151], v231 offset:1024
	ds_read_b128 v[170:173], v231 offset:2048
	ds_read_b128 v[174:177], v231 offset:3072
	s_add_u32 s20, s18, 0x100
	s_addc_u32 s21, s19, 0
	s_cmpk_eq_i32 s53, 0x52
	s_cselect_b32 s25, s5, s21
	s_cselect_b32 s24, s4, s20
	s_cselect_b32 s23, s15, s52
	s_cselect_b32 s22, s14, s17
	v_lshl_add_u64 v[210:211], s[18:19], 0, v[162:163]
	s_add_i32 m0, s35, 0xc000
	ds_read_b128 v[178:181], v232
	ds_read_b128 v[182:185], v232 offset:1024
	ds_read_b128 v[186:189], v232 offset:2048
	ds_read_b128 v[190:193], v232 offset:3072
	ds_read_b128 v[194:197], v232 offset:4096
	ds_read_b128 v[198:201], v232 offset:5120
	ds_read_b128 v[202:205], v232 offset:6144
	ds_read_b128 v[206:209], v232 offset:7168
	global_load_lds_dwordx4 v[210:211], off
	v_lshl_add_u64 v[210:211], s[18:19], 0, v[164:165]
	s_add_i32 m0, s35, 0xe000
	s_nop 0
	global_load_lds_dwordx4 v[210:211], off
	s_waitcnt vmcnt(8)
	s_waitcnt lgkmcnt(0)
	s_barrier
; #define PG8_STAGE(bufoff, gbase, voff) do { _Pragma("unroll") for (int _i = 0; _i < 2; ++_i) \
;         __builtin_amdgcn_global_load_lds((const unsigned*)((const char*)(gbase) + (voff)[_i]), (PG8_LAS unsigned*)(lds + (bufoff) + ldsw + _i * 8192), 16, 0, 0); } while (0)
; #define PG8_LDA(dst, b, h) do { _Pragma("unroll") for (int m = 0; m < 4; ++m) _Pragma("unroll") for (int k = 0; k < 2; ++k) dst[m][k] = *(const PG8_LAS bf16x8*)(lds + PG8_SA(b, h) + aoff + m * 2048 + k * 1024); } while (0)
; #define PG8_WAIT_V(n) asm volatile("s_waitcnt vmcnt(" #n ")" ::: "memory")
; #define PG8_WAIT_L(n) asm volatile("s_waitcnt lgkmcnt(" #n ")" ::: "memory")
; #define PG8_BAR __builtin_amdgcn_s_barrier()
; template <class Epi, class Sched, bool ALIGN_EPI = false, bool SP2 = false>
; __device__ __forceinline__ void gemm_phase(PG8_LAS unsigned char* lds, const Gemm g, const Sched& S, const Epi& E, const int wave_in) {
;     ...
;         for (int t = 0; t < nt; t += 2) {
;             const bool last = (t == nt - 2);
;             const char* a1 = cA + (size_t)(t + 1) * kstep;
;             const char* a2 = last ? nA : cA + (size_t)(t + 2) * kstep; const char* b2 = last ? nB : cB + (size_t)(t + 2) * kstep;
;             const char* a3 = a2 + kstep; const char* b3 = b2 + kstep;
;             if (last && has_next) S.a_ready(nxt);
;             if constexpr (SP2) {
;             PG8_LDB(B0, 0, 0); PG8_LDB(B1, 0, 1); PG8_SCHED; PG8_LDA(At, 0, 0); PG8_STAGE(PG8_SA(1, 1), a1 + hstepA, voffA);
;             PG8_WAIT_V(8); PG8_WAIT_L(0); PG8_BAR; PG8_MMA(0, 0, At, B0); PG8_MMA(0, 1, At, B1); PG8_BAR; PG8_SCHED;
;             PG8_LDA(At, 0, 1); PG8_STAGE(PG8_SB(0, 0), b2, voffB); PG8_STAGE(PG8_SB(0, 1), b2 + hstepB, voffB); PG8_STAGE(PG8_SA(0, 0), a2, voffA);
;             PG8_WAIT_V(8); PG8_WAIT_L(0); PG8_BAR; PG8_MMA(1, 0, At, B0); PG8_MMA(1, 1, At, B1); PG8_BAR; PG8_SCHED;
;             PG8_LDB(B0, 1, 0); PG8_LDB(B1, 1, 1); PG8_SCHED; PG8_LDA(At, 1, 0); PG8_STAGE(PG8_SA(0, 1), a2 + hstepA, voffA);
;             PG8_WAIT_V(8); PG8_WAIT_L(0); PG8_BAR; PG8_MMA(0, 0, At, B0); PG8_MMA(0, 1, At, B1); PG8_BAR; PG8_SCHED;
;             PG8_LDA(At, 1, 1); PG8_STAGE(PG8_SB(1, 0), b3, voffB); PG8_STAGE(PG8_SB(1, 1), b3 + hstepB, voffB); PG8_STAGE(PG8_SA(1, 0), a3, voffA);
;             PG8_WAIT_V(8); PG8_WAIT_L(0); PG8_BAR; PG8_MMA(1, 0, At, B0); PG8_MMA(1, 1, At, B1); PG8_BAR; PG8_SCHED;
	s_setprio 1
	v_mfma_f32_16x16x32_bf16 v[140:143], v[64:67], v[178:181], v[140:143]
	v_mfma_f32_16x16x32_bf16 v[136:139], v[72:75], v[178:181], v[136:139]
	v_mfma_f32_16x16x32_bf16 v[128:131], v[64:67], v[186:189], v[128:131]
	v_mfma_f32_16x16x32_bf16 v[120:123], v[72:75], v[186:189], v[120:123]
	v_mfma_f32_16x16x32_bf16 v[116:119], v[64:67], v[194:197], v[116:119]
	v_mfma_f32_16x16x32_bf16 v[112:115], v[72:75], v[194:197], v[112:115]
	v_mfma_f32_16x16x32_bf16 v[100:103], v[64:67], v[202:205], v[100:103]
	v_mfma_f32_16x16x32_bf16 v[96:99], v[72:75], v[202:205], v[96:99]
	v_mfma_f32_16x16x32_bf16 v[140:143], v[68:71], v[182:185], v[140:143]
	v_mfma_f32_16x16x32_bf16 v[136:139], v[76:79], v[182:185], v[136:139]
	v_mfma_f32_16x16x32_bf16 v[128:131], v[68:71], v[190:193], v[128:131]
	v_mfma_f32_16x16x32_bf16 v[120:123], v[76:79], v[190:193], v[120:123]
	v_mfma_f32_16x16x32_bf16 v[116:119], v[68:71], v[198:201], v[116:119]
	v_mfma_f32_16x16x32_bf16 v[112:115], v[76:79], v[198:201], v[112:115]
	v_mfma_f32_16x16x32_bf16 v[100:103], v[68:71], v[206:209], v[100:103]
	v_mfma_f32_16x16x32_bf16 v[96:99], v[76:79], v[206:209], v[96:99]
	v_mfma_f32_16x16x32_bf16 v[132:135], v[144:147], v[178:181], v[132:135]
	v_mfma_f32_16x16x32_bf16 v[124:127], v[170:173], v[178:181], v[124:127]
	v_mfma_f32_16x16x32_bf16 v[108:111], v[144:147], v[186:189], v[108:111]
	v_mfma_f32_16x16x32_bf16 v[104:107], v[170:173], v[186:189], v[104:107]
	v_mfma_f32_16x16x32_bf16 v[92:95], v[144:147], v[194:197], v[92:95]
	v_mfma_f32_16x16x32_bf16 v[88:91], v[170:173], v[194:197], v[88:91]
	v_mfma_f32_16x16x32_bf16 v[84:87], v[144:147], v[202:205], v[84:87]
	v_mfma_f32_16x16x32_bf16 v[80:83], v[170:173], v[202:205], v[80:83]
	v_mfma_f32_16x16x32_bf16 v[132:135], v[148:151], v[182:185], v[132:135]
	v_mfma_f32_16x16x32_bf16 v[124:127], v[174:177], v[182:185], v[124:127]
	v_mfma_f32_16x16x32_bf16 v[108:111], v[148:151], v[190:193], v[108:111]
	v_mfma_f32_16x16x32_bf16 v[104:107], v[174:177], v[190:193], v[104:107]
	v_mfma_f32_16x16x32_bf16 v[92:95], v[148:151], v[198:201], v[92:95]
	v_mfma_f32_16x16x32_bf16 v[88:91], v[174:177], v[198:201], v[88:91]
	v_mfma_f32_16x16x32_bf16 v[84:87], v[148:151], v[206:209], v[84:87]
	v_mfma_f32_16x16x32_bf16 v[80:83], v[174:177], v[206:209], v[80:83]
	s_setprio 0
	s_barrier
	s_add_i32 s18, s45, s30
	v_lshl_add_u64 v[210:211], s[22:23], 0, v[156:157]
	s_mov_b32 m0, s18
	ds_read_b128 v[178:181], v232 offset:16384
	ds_read_b128 v[182:185], v232 offset:17408
	ds_read_b128 v[186:189], v232 offset:18432
	ds_read_b128 v[190:193], v232 offset:19456
	ds_read_b128 v[194:197], v232 offset:20480
	ds_read_b128 v[198:201], v232 offset:21504
	ds_read_b128 v[202:205], v232 offset:22528
	ds_read_b128 v[206:209], v232 offset:23552
	global_load_lds_dwordx4 v[210:211], off
	s_add_i32 m0, s18, 0x2000
	s_add_u32 s18, s22, 0x158000
	v_lshl_add_u64 v[212:213], s[22:23], 0, v[152:153]
	s_addc_u32 s19, s23, 0
	s_add_i32 s54, s46, s30
	global_load_lds_dwordx4 v[212:213], off
	v_lshl_add_u64 v[214:215], s[18:19], 0, v[156:157]
	s_mov_b32 m0, s54
	v_lshl_add_u64 v[216:217], s[24:25], 0, v[154:155]
	global_load_lds_dwordx4 v[214:215], off
	v_lshl_add_u64 v[214:215], s[18:19], 0, v[152:153]
	s_add_i32 m0, s54, 0x2000
	s_nop 0
	global_load_lds_dwordx4 v[214:215], off
	v_lshl_add_u64 v[214:215], s[24:25], 0, v[158:159]
	s_mov_b32 m0, s35
	s_nop 0
	global_load_lds_dwordx4 v[214:215], off
	s_mov_b32 m0, s36
	s_nop 0
	global_load_lds_dwordx4 v[216:217], off
	s_waitcnt vmcnt(8)
	s_waitcnt lgkmcnt(0)
	s_barrier
	s_setprio 1
	v_mfma_f32_16x16x32_bf16 v[60:63], v[64:67], v[178:181], v[60:63]
	v_mfma_f32_16x16x32_bf16 v[56:59], v[72:75], v[178:181], v[56:59]
	v_mfma_f32_16x16x32_bf16 v[48:51], v[64:67], v[186:189], v[48:51]
	v_mfma_f32_16x16x32_bf16 v[40:43], v[72:75], v[186:189], v[40:43]
	v_mfma_f32_16x16x32_bf16 v[32:35], v[64:67], v[194:197], v[32:35]
	v_mfma_f32_16x16x32_bf16 v[24:27], v[72:75], v[194:197], v[24:27]
	v_mfma_f32_16x16x32_bf16 v[16:19], v[64:67], v[202:205], v[16:19]
	v_mfma_f32_16x16x32_bf16 v[8:11], v[72:75], v[202:205], v[8:11]
	v_mfma_f32_16x16x32_bf16 v[60:63], v[68:71], v[182:185], v[60:63]
	v_mfma_f32_16x16x32_bf16 v[56:59], v[76:79], v[182:185], v[56:59]
	v_mfma_f32_16x16x32_bf16 v[48:51], v[68:71], v[190:193], v[48:51]
	v_mfma_f32_16x16x32_bf16 v[40:43], v[76:79], v[190:193], v[40:43]
	v_mfma_f32_16x16x32_bf16 v[32:35], v[68:71], v[198:201], v[32:35]
	v_mfma_f32_16x16x32_bf16 v[24:27], v[76:79], v[198:201], v[24:27]
	v_mfma_f32_16x16x32_bf16 v[16:19], v[68:71], v[206:209], v[16:19]
	v_mfma_f32_16x16x32_bf16 v[8:11], v[76:79], v[206:209], v[8:11]
	v_mfma_f32_16x16x32_bf16 v[52:55], v[144:147], v[178:181], v[52:55]
	v_mfma_f32_16x16x32_bf16 v[44:47], v[170:173], v[178:181], v[44:47]
	v_mfma_f32_16x16x32_bf16 v[36:39], v[144:147], v[186:189], v[36:39]
	v_mfma_f32_16x16x32_bf16 v[28:31], v[170:173], v[186:189], v[28:31]
	v_mfma_f32_16x16x32_bf16 v[20:23], v[144:147], v[194:197], v[20:23]
	v_mfma_f32_16x16x32_bf16 v[12:15], v[170:173], v[194:197], v[12:15]
	v_mfma_f32_16x16x32_bf16 v[4:7], v[144:147], v[202:205], v[4:7]
	v_mfma_f32_16x16x32_bf16 v[0:3], v[170:173], v[202:205], v[0:3]
	v_mfma_f32_16x16x32_bf16 v[52:55], v[148:151], v[182:185], v[52:55]
	v_mfma_f32_16x16x32_bf16 v[44:47], v[174:177], v[182:185], v[44:47]
	v_mfma_f32_16x16x32_bf16 v[36:39], v[148:151], v[190:193], v[36:39]
	v_mfma_f32_16x16x32_bf16 v[28:31], v[174:177], v[190:193], v[28:31]
	v_mfma_f32_16x16x32_bf16 v[20:23], v[148:151], v[198:201], v[20:23]
	v_mfma_f32_16x16x32_bf16 v[12:15], v[174:177], v[198:201], v[12:15]
	v_mfma_f32_16x16x32_bf16 v[4:7], v[148:151], v[206:209], v[4:7]
	v_mfma_f32_16x16x32_bf16 v[0:3], v[174:177], v[206:209], v[0:3]
	s_setprio 0
	s_barrier
; #define PG8_STAGE(bufoff, gbase, voff) do { _Pragma("unroll") for (int _i = 0; _i < 2; ++_i) \
;         __builtin_amdgcn_global_load_lds((const unsigned*)((const char*)(gbase) + (voff)[_i]), (PG8_LAS unsigned*)(lds + (bufoff) + ldsw + _i * 8192), 16, 0, 0); } while (0)
; #define PG8_LDA(dst, b, h) do { _Pragma("unroll") for (int m = 0; m < 4; ++m) _Pragma("unroll") for (int k = 0; k < 2; ++k) dst[m][k] = *(const PG8_LAS bf16x8*)(lds + PG8_SA(b, h) + aoff + m * 2048 + k * 1024); } while (0)
; #define PG8_WAIT_V(n) asm volatile("s_waitcnt vmcnt(" #n ")" ::: "memory")
; #define PG8_WAIT_L(n) asm volatile("s_waitcnt lgkmcnt(" #n ")" ::: "memory")
; #define PG8_BAR __builtin_amdgcn_s_barrier()
; template <class Epi, class Sched, bool ALIGN_EPI = false, bool SP2 = false>
; __device__ __forceinline__ void gemm_phase(PG8_LAS unsigned char* lds, const Gemm g, const Sched& S, const Epi& E, const int wave_in) {
;     ...
;         for (int t = 0; t < nt; t += 2) {
;             const bool last = (t == nt - 2);
;             const char* a1 = cA + (size_t)(t + 1) * kstep;
;             const char* a2 = last ? nA : cA + (size_t)(t + 2) * kstep; const char* b2 = last ? nB : cB + (size_t)(t + 2) * kstep;
;             const char* a3 = a2 + kstep; const char* b3 = b2 + kstep;
;             if (last && has_next) S.a_ready(nxt);
;             if constexpr (SP2) {
;             PG8_LDB(B0, 0, 0); PG8_LDB(B1, 0, 1); PG8_SCHED; PG8_LDA(At, 0, 0); PG8_STAGE(PG8_SA(1, 1), a1 + hstepA, voffA);
;             PG8_WAIT_V(8); PG8_WAIT_L(0); PG8_BAR; PG8_MMA(0, 0, At, B0); PG8_MMA(0, 1, At, B1); PG8_BAR; PG8_SCHED;
;             PG8_LDA(At, 0, 1); PG8_STAGE(PG8_SB(0, 0), b2, voffB); PG8_STAGE(PG8_SB(0, 1), b2 + hstepB, voffB); PG8_STAGE(PG8_SA(0, 0), a2, voffA);
;             PG8_WAIT_V(8); PG8_WAIT_L(0); PG8_BAR; PG8_MMA(1, 0, At, B0); PG8_MMA(1, 1, At, B1); PG8_BAR; PG8_SCHED;
;             PG8_LDB(B0, 1, 0); PG8_LDB(B1, 1, 1); PG8_SCHED; PG8_LDA(At, 1, 0); PG8_STAGE(PG8_SA(0, 1), a2 + hstepA, voffA);
;             PG8_WAIT_V(8); PG8_WAIT_L(0); PG8_BAR; PG8_MMA(0, 0, At, B0); PG8_MMA(0, 1, At, B1); PG8_BAR; PG8_SCHED;
;             PG8_LDA(At, 1, 1); PG8_STAGE(PG8_SB(1, 0), b3, voffB); PG8_STAGE(PG8_SB(1, 1), b3 + hstepB, voffB); PG8_STAGE(PG8_SA(1, 0), a3, voffA);
;             PG8_WAIT_V(8); PG8_WAIT_L(0); PG8_BAR; PG8_MMA(1, 0, At, B0); PG8_MMA(1, 1, At, B1); PG8_BAR; PG8_SCHED;
	s_add_i32 s54, 0, 0x18000
	s_add_i32 s55, 0, 0x1c000
	v_add_u32_e32 v76, s54, v228
	v_add_u32_e32 v174, s55, v228
	ds_read_b128 v[64:67], v76
	ds_read_b128 v[68:71], v76 offset:1024
	ds_read_b128 v[72:75], v76 offset:2048
	ds_read_b128 v[76:79], v76 offset:3072
	ds_read_b128 v[144:147], v174
	ds_read_b128 v[148:151], v174 offset:1024
	ds_read_b128 v[170:173], v174 offset:2048
	ds_read_b128 v[174:177], v174 offset:3072
	s_add_u32 s18, s24, 0x158000
	s_addc_u32 s19, s25, 0
	s_mov_b32 m0, s37
	v_lshl_add_u64 v[218:219], s[18:19], 0, v[158:159]
	ds_read_b128 v[178:181], v232 offset:32768
	ds_read_b128 v[182:185], v232 offset:33792
	ds_read_b128 v[186:189], v232 offset:34816
	ds_read_b128 v[190:193], v232 offset:35840
	ds_read_b128 v[194:197], v232 offset:36864
	ds_read_b128 v[198:201], v232 offset:37888
	ds_read_b128 v[202:205], v232 offset:38912
	ds_read_b128 v[206:209], v232 offset:39936
	global_load_lds_dwordx4 v[218:219], off
	v_lshl_add_u64 v[218:219], s[18:19], 0, v[154:155]
	s_mov_b32 m0, s38
	s_nop 0
	global_load_lds_dwordx4 v[218:219], off
	s_waitcnt vmcnt(8)
	s_waitcnt lgkmcnt(0)
	s_barrier
	s_setprio 1
	v_mfma_f32_16x16x32_bf16 v[140:143], v[64:67], v[178:181], v[140:143]
	v_mfma_f32_16x16x32_bf16 v[136:139], v[72:75], v[178:181], v[136:139]
	v_mfma_f32_16x16x32_bf16 v[128:131], v[64:67], v[186:189], v[128:131]
	v_mfma_f32_16x16x32_bf16 v[120:123], v[72:75], v[186:189], v[120:123]
	v_mfma_f32_16x16x32_bf16 v[116:119], v[64:67], v[194:197], v[116:119]
	v_mfma_f32_16x16x32_bf16 v[112:115], v[72:75], v[194:197], v[112:115]
	v_mfma_f32_16x16x32_bf16 v[100:103], v[64:67], v[202:205], v[100:103]
	v_mfma_f32_16x16x32_bf16 v[96:99], v[72:75], v[202:205], v[96:99]
	v_mfma_f32_16x16x32_bf16 v[140:143], v[68:71], v[182:185], v[140:143]
	v_mfma_f32_16x16x32_bf16 v[136:139], v[76:79], v[182:185], v[136:139]
	v_mfma_f32_16x16x32_bf16 v[128:131], v[68:71], v[190:193], v[128:131]
	v_mfma_f32_16x16x32_bf16 v[120:123], v[76:79], v[190:193], v[120:123]
	v_mfma_f32_16x16x32_bf16 v[116:119], v[68:71], v[198:201], v[116:119]
	v_mfma_f32_16x16x32_bf16 v[112:115], v[76:79], v[198:201], v[112:115]
	v_mfma_f32_16x16x32_bf16 v[100:103], v[68:71], v[206:209], v[100:103]
	v_mfma_f32_16x16x32_bf16 v[96:99], v[76:79], v[206:209], v[96:99]
	v_mfma_f32_16x16x32_bf16 v[132:135], v[144:147], v[178:181], v[132:135]
	v_mfma_f32_16x16x32_bf16 v[124:127], v[170:173], v[178:181], v[124:127]
	v_mfma_f32_16x16x32_bf16 v[108:111], v[144:147], v[186:189], v[108:111]
	v_mfma_f32_16x16x32_bf16 v[104:107], v[170:173], v[186:189], v[104:107]
	v_mfma_f32_16x16x32_bf16 v[92:95], v[144:147], v[194:197], v[92:95]
	v_mfma_f32_16x16x32_bf16 v[88:91], v[170:173], v[194:197], v[88:91]
	v_mfma_f32_16x16x32_bf16 v[84:87], v[144:147], v[202:205], v[84:87]
	v_mfma_f32_16x16x32_bf16 v[80:83], v[170:173], v[202:205], v[80:83]
	v_mfma_f32_16x16x32_bf16 v[132:135], v[148:151], v[182:185], v[132:135]
	v_mfma_f32_16x16x32_bf16 v[124:127], v[174:177], v[182:185], v[124:127]
	v_mfma_f32_16x16x32_bf16 v[108:111], v[148:151], v[190:193], v[108:111]
	v_mfma_f32_16x16x32_bf16 v[104:107], v[174:177], v[190:193], v[104:107]
	v_mfma_f32_16x16x32_bf16 v[92:95], v[148:151], v[198:201], v[92:95]
	v_mfma_f32_16x16x32_bf16 v[88:91], v[174:177], v[198:201], v[88:91]
	v_mfma_f32_16x16x32_bf16 v[84:87], v[148:151], v[206:209], v[84:87]
	v_mfma_f32_16x16x32_bf16 v[80:83], v[174:177], v[206:209], v[80:83]
	s_setprio 0
	s_barrier
	s_add_i32 s18, s54, s30
	v_lshl_add_u64 v[210:211], v[210:211], 0, s[6:7]
	s_mov_b32 m0, s18
	ds_read_b128 v[178:181], v232 offset:49152
	ds_read_b128 v[182:185], v232 offset:50176
	ds_read_b128 v[186:189], v232 offset:51200
	ds_read_b128 v[190:193], v232 offset:52224
	ds_read_b128 v[194:197], v232 offset:53248
	ds_read_b128 v[198:201], v232 offset:54272
	ds_read_b128 v[202:205], v232 offset:55296
	ds_read_b128 v[206:209], v232 offset:56320
	global_load_lds_dwordx4 v[210:211], off
	s_add_i32 m0, s18, 0x2000
	s_add_u32 s18, s22, 0x158080
	v_lshl_add_u64 v[210:211], v[212:213], 0, s[6:7]
	s_addc_u32 s19, s23, 0
	s_add_i32 s22, s55, s30
	global_load_lds_dwordx4 v[210:211], off
	v_lshl_add_u64 v[210:211], s[18:19], 0, v[156:157]
	s_mov_b32 m0, s22
	s_nop 0
	global_load_lds_dwordx4 v[210:211], off
	v_lshl_add_u64 v[210:211], s[18:19], 0, v[152:153]
	s_add_i32 m0, s22, 0x2000
	s_nop 0
	global_load_lds_dwordx4 v[210:211], off
	v_lshl_add_u64 v[210:211], v[214:215], 0, s[6:7]
	s_mov_b32 m0, s42
	s_nop 0
	global_load_lds_dwordx4 v[210:211], off
	v_lshl_add_u64 v[210:211], v[216:217], 0, s[6:7]
	s_mov_b32 m0, s43
	s_nop 0
	global_load_lds_dwordx4 v[210:211], off
	s_waitcnt vmcnt(8)
	s_waitcnt lgkmcnt(0)
	s_barrier
	s_setprio 1
	v_mfma_f32_16x16x32_bf16 v[60:63], v[64:67], v[178:181], v[60:63]
	v_mfma_f32_16x16x32_bf16 v[56:59], v[72:75], v[178:181], v[56:59]
	v_mfma_f32_16x16x32_bf16 v[48:51], v[64:67], v[186:189], v[48:51]
	v_mfma_f32_16x16x32_bf16 v[40:43], v[72:75], v[186:189], v[40:43]
	v_mfma_f32_16x16x32_bf16 v[32:35], v[64:67], v[194:197], v[32:35]
	v_mfma_f32_16x16x32_bf16 v[24:27], v[72:75], v[194:197], v[24:27]
	v_mfma_f32_16x16x32_bf16 v[16:19], v[64:67], v[202:205], v[16:19]
	v_mfma_f32_16x16x32_bf16 v[8:11], v[72:75], v[202:205], v[8:11]
	v_mfma_f32_16x16x32_bf16 v[60:63], v[68:71], v[182:185], v[60:63]
	v_mfma_f32_16x16x32_bf16 v[56:59], v[76:79], v[182:185], v[56:59]
	v_mfma_f32_16x16x32_bf16 v[48:51], v[68:71], v[190:193], v[48:51]
	v_mfma_f32_16x16x32_bf16 v[40:43], v[76:79], v[190:193], v[40:43]
	v_mfma_f32_16x16x32_bf16 v[32:35], v[68:71], v[198:201], v[32:35]
	v_mfma_f32_16x16x32_bf16 v[24:27], v[76:79], v[198:201], v[24:27]
	v_mfma_f32_16x16x32_bf16 v[16:19], v[68:71], v[206:209], v[16:19]
	v_mfma_f32_16x16x32_bf16 v[8:11], v[76:79], v[206:209], v[8:11]
	v_mfma_f32_16x16x32_bf16 v[52:55], v[144:147], v[178:181], v[52:55]
	v_mfma_f32_16x16x32_bf16 v[44:47], v[170:173], v[178:181], v[44:47]
	v_mfma_f32_16x16x32_bf16 v[36:39], v[144:147], v[186:189], v[36:39]
	v_mfma_f32_16x16x32_bf16 v[28:31], v[170:173], v[186:189], v[28:31]
	v_mfma_f32_16x16x32_bf16 v[20:23], v[144:147], v[194:197], v[20:23]
	v_mfma_f32_16x16x32_bf16 v[12:15], v[170:173], v[194:197], v[12:15]
	v_mfma_f32_16x16x32_bf16 v[4:7], v[144:147], v[202:205], v[4:7]
	v_mfma_f32_16x16x32_bf16 v[0:3], v[170:173], v[202:205], v[0:3]
	v_mfma_f32_16x16x32_bf16 v[52:55], v[148:151], v[182:185], v[52:55]
	v_mfma_f32_16x16x32_bf16 v[44:47], v[174:177], v[182:185], v[44:47]
	v_mfma_f32_16x16x32_bf16 v[36:39], v[148:151], v[190:193], v[36:39]
	v_mfma_f32_16x16x32_bf16 v[28:31], v[174:177], v[190:193], v[28:31]
	v_mfma_f32_16x16x32_bf16 v[20:23], v[148:151], v[198:201], v[20:23]
	v_mfma_f32_16x16x32_bf16 v[12:15], v[174:177], v[198:201], v[12:15]
	v_mfma_f32_16x16x32_bf16 v[4:7], v[148:151], v[206:209], v[4:7]
	v_mfma_f32_16x16x32_bf16 v[0:3], v[174:177], v[206:209], v[0:3]
	s_setprio 0
	s_barrier
	s_add_i32 s53, s53, 2
	s_add_u32 s17, s17, 0x100
	s_addc_u32 s52, s52, 0
	s_cmpk_gt_u32 s53, 0x53
	s_mov_b64 s[18:19], s[20:21]
	s_cbranch_scc0 .LBB0_635

;     __host__ __device__ bool next(int i, Unit& u) const { const bool ok = StaticOrder::next(i, u); u.pm = 0; u.pn = 0; return ok; }
; #define PG8_STAGE(bufoff, gbase, voff) do { _Pragma("unroll") for (int _i = 0; _i < 2; ++_i) \
;         __builtin_amdgcn_global_load_lds((const unsigned*)((const char*)(gbase) + (voff)[_i]), (PG8_LAS unsigned*)(lds + (bufoff) + ldsw + _i * 8192), 16, 0, 0); } while (0)
; #define PG8_LDA(dst, b, h) do { _Pragma("unroll") for (int m = 0; m < 4; ++m) _Pragma("unroll") for (int k = 0; k < 2; ++k) dst[m][k] = *(const PG8_LAS bf16x8*)(lds + PG8_SA(b, h) + aoff + m * 2048 + k * 1024); } while (0)
; #define PG8_LDB(dst, b, h) do { _Pragma("unroll") for (int n = 0; n < 2; ++n) _Pragma("unroll") for (int k = 0; k < 2; ++k) dst[n][k] = *(const PG8_LAS bf16x8*)(lds + PG8_SB(b, h) + boff + n * 2048 + k * 1024); } while (0)
; #define PG8_WAIT_V(n) asm volatile("s_waitcnt vmcnt(" #n ")" ::: "memory")
; #define PG8_BAR __builtin_amdgcn_s_barrier()
; template <class Epi, class Sched, bool ALIGN_EPI = false, bool SP2 = false>
; __device__ __forceinline__ void gemm_phase(PG8_LAS unsigned char* lds, const Gemm g, const Sched& S, const Epi& E, const int wave_in) {
;     ...
;         const bool has_next = S.next(ui + 1, nxt);
;         const char* nA = has_next ? (const char*)g.A + (size_t)nxt.pm * tstepA : cA; const char* nB = has_next ? (const char*)g.Bt + (size_t)nxt.pn * tstepB : cB;
;         for (int t = 0; t < nt; t += 2) {
;             const bool last = (t == nt - 2);
;             const char* a1 = cA + (size_t)(t + 1) * kstep;
;             const char* a2 = last ? nA : cA + (size_t)(t + 2) * kstep; const char* b2 = last ? nB : cB + (size_t)(t + 2) * kstep;
;             const char* a3 = a2 + kstep; const char* b3 = b2 + kstep;
;             if (last && has_next) S.a_ready(nxt);
;             if constexpr (SP2) {
;             PG8_LDB(B0, 0, 0); PG8_LDB(B1, 0, 1); PG8_SCHED; PG8_LDA(At, 0, 0); PG8_STAGE(PG8_SA(1, 1), a1 + hstepA, voffA);
;             PG8_WAIT_V(8); PG8_WAIT_L(0); PG8_BAR; PG8_MMA(0, 0, At, B0); PG8_MMA(0, 1, At, B1); PG8_BAR; PG8_SCHED;
;             PG8_LDA(At, 0, 1); PG8_STAGE(PG8_SB(0, 0), b2, voffB); PG8_STAGE(PG8_SB(0, 1), b2 + hstepB, voffB); PG8_STAGE(PG8_SA(0, 0), a2, voffA);
;             PG8_WAIT_V(8); PG8_WAIT_L(0); PG8_BAR; PG8_MMA(1, 0, At, B0); PG8_MMA(1, 1, At, B1); PG8_BAR; PG8_SCHED;
.LBB0_1092:
	s_ashr_i32 s15, s14, 31
	s_lshl_b64 s[18:19], s[14:15], 21
	s_add_u32 s18, s30, s18
	s_addc_u32 s19, s31, s19
	s_and_b64 s[4:5], s[4:5], exec
	s_cselect_b32 s15, s19, s25
	s_cselect_b32 s21, s18, s24
	s_add_u32 s53, s24, 0x100
	v_mov_b32_e32 v0, 0
	s_addc_u32 s54, s25, 0
	s_mov_b32 s55, -2
	ds_read_b128 v[128:131], v214
	ds_read_b128 v[132:135], v214 offset:1024
	ds_read_b128 v[136:139], v214 offset:2048
	ds_read_b128 v[140:143], v214 offset:3072
	ds_read_b128 v[162:165], v215
	ds_read_b128 v[166:169], v215 offset:1024
	ds_read_b128 v[170:173], v215 offset:2048
	ds_read_b128 v[174:177], v215 offset:3072
	s_add_u32 s4, s22, 0x100
	s_addc_u32 s5, s23, 0
	s_cmp_eq_u32 s55, 60
	s_cselect_b32 s27, s17, s5
	s_cselect_b32 s26, s16, s4
	s_cselect_b32 s25, s15, s54
	s_cselect_b32 s24, s21, s53
	v_lshl_add_u64 v[210:211], s[22:23], 0, v[154:155]
	s_add_i32 m0, s37, 0xc000
	ds_read_b128 v[178:181], v216
	ds_read_b128 v[182:185], v216 offset:1024
	ds_read_b128 v[186:189], v216 offset:2048
	ds_read_b128 v[190:193], v216 offset:3072
	ds_read_b128 v[194:197], v216 offset:4096
	ds_read_b128 v[198:201], v216 offset:5120
	ds_read_b128 v[202:205], v216 offset:6144
	ds_read_b128 v[206:209], v216 offset:7168
	global_load_lds_dwordx4 v[210:211], off
	v_lshl_add_u64 v[210:211], s[22:23], 0, v[156:157]
	s_add_i32 m0, s37, 0xe000
	s_nop 0
	global_load_lds_dwordx4 v[210:211], off
	s_waitcnt vmcnt(8)
	s_waitcnt lgkmcnt(0)
	s_barrier
	s_setprio 1
	v_mfma_f32_16x16x32_bf16 v[124:127], v[128:131], v[178:181], 0
	v_mfma_f32_16x16x32_bf16 v[120:123], v[136:139], v[178:181], 0
	v_mfma_f32_16x16x32_bf16 v[112:115], v[128:131], v[186:189], 0
	v_mfma_f32_16x16x32_bf16 v[104:107], v[136:139], v[186:189], 0
	v_mfma_f32_16x16x32_bf16 v[100:103], v[128:131], v[194:197], 0
	v_mfma_f32_16x16x32_bf16 v[96:99], v[136:139], v[194:197], 0
	v_mfma_f32_16x16x32_bf16 v[76:79], v[128:131], v[202:205], 0
	v_mfma_f32_16x16x32_bf16 v[72:75], v[136:139], v[202:205], 0
	v_mfma_f32_16x16x32_bf16 v[124:127], v[132:135], v[182:185], v[124:127]
	v_mfma_f32_16x16x32_bf16 v[120:123], v[140:143], v[182:185], v[120:123]
	v_mfma_f32_16x16x32_bf16 v[112:115], v[132:135], v[190:193], v[112:115]
	v_mfma_f32_16x16x32_bf16 v[104:107], v[140:143], v[190:193], v[104:107]
	v_mfma_f32_16x16x32_bf16 v[100:103], v[132:135], v[198:201], v[100:103]
	v_mfma_f32_16x16x32_bf16 v[96:99], v[140:143], v[198:201], v[96:99]
	v_mfma_f32_16x16x32_bf16 v[76:79], v[132:135], v[206:209], v[76:79]
	v_mfma_f32_16x16x32_bf16 v[72:75], v[140:143], v[206:209], v[72:75]
	v_mfma_f32_16x16x32_bf16 v[116:119], v[162:165], v[178:181], 0
	v_mfma_f32_16x16x32_bf16 v[108:111], v[170:173], v[178:181], 0
	v_mfma_f32_16x16x32_bf16 v[92:95], v[162:165], v[186:189], 0
	v_mfma_f32_16x16x32_bf16 v[88:91], v[170:173], v[186:189], 0
	v_mfma_f32_16x16x32_bf16 v[84:87], v[162:165], v[194:197], 0
	v_mfma_f32_16x16x32_bf16 v[80:83], v[170:173], v[194:197], 0
	v_mfma_f32_16x16x32_bf16 v[68:71], v[162:165], v[202:205], 0
	v_mfma_f32_16x16x32_bf16 v[64:67], v[170:173], v[202:205], 0
	v_mfma_f32_16x16x32_bf16 v[116:119], v[166:169], v[182:185], v[116:119]
	v_mfma_f32_16x16x32_bf16 v[108:111], v[174:177], v[182:185], v[108:111]
	v_mfma_f32_16x16x32_bf16 v[92:95], v[166:169], v[190:193], v[92:95]
	v_mfma_f32_16x16x32_bf16 v[88:91], v[174:177], v[190:193], v[88:91]
	v_mfma_f32_16x16x32_bf16 v[84:87], v[166:169], v[198:201], v[84:87]
	v_mfma_f32_16x16x32_bf16 v[80:83], v[174:177], v[198:201], v[80:83]
	v_mfma_f32_16x16x32_bf16 v[68:71], v[166:169], v[206:209], v[68:71]
	v_mfma_f32_16x16x32_bf16 v[64:67], v[174:177], v[206:209], v[64:67]
	s_setprio 0
	s_barrier
	s_add_i32 s22, s47, s34
	v_lshl_add_u64 v[210:211], s[24:25], 0, v[148:149]
	s_mov_b32 m0, s22
	ds_read_b128 v[178:181], v216 offset:16384
	ds_read_b128 v[182:185], v216 offset:17408
	ds_read_b128 v[186:189], v216 offset:18432
	ds_read_b128 v[190:193], v216 offset:19456
	ds_read_b128 v[194:197], v216 offset:20480
	ds_read_b128 v[198:201], v216 offset:21504
	ds_read_b128 v[202:205], v216 offset:22528
	ds_read_b128 v[206:209], v216 offset:23552
	global_load_lds_dwordx4 v[210:211], off
	s_add_i32 m0, s22, 0x2000
	s_add_u32 s22, s24, 0x100000
	v_lshl_add_u64 v[218:219], s[24:25], 0, v[144:145]
	s_addc_u32 s23, s25, 0
	s_add_i32 s56, s48, s34
	global_load_lds_dwordx4 v[218:219], off
	v_lshl_add_u64 v[220:221], s[22:23], 0, v[148:149]
	s_mov_b32 m0, s56
	v_lshl_add_u64 v[222:223], s[26:27], 0, v[146:147]
	global_load_lds_dwordx4 v[220:221], off
	v_lshl_add_u64 v[220:221], s[22:23], 0, v[144:145]
	s_add_i32 m0, s56, 0x2000
	s_nop 0
	global_load_lds_dwordx4 v[220:221], off
	v_lshl_add_u64 v[220:221], s[26:27], 0, v[150:151]
	s_mov_b32 m0, s37
	s_nop 0
	global_load_lds_dwordx4 v[220:221], off
	s_mov_b32 m0, s38
	s_nop 0
	global_load_lds_dwordx4 v[222:223], off
	s_waitcnt vmcnt(8)
	s_waitcnt lgkmcnt(0)
	s_barrier
; #define PG8_STAGE(bufoff, gbase, voff) do { _Pragma("unroll") for (int _i = 0; _i < 2; ++_i) \
;         __builtin_amdgcn_global_load_lds((const unsigned*)((const char*)(gbase) + (voff)[_i]), (PG8_LAS unsigned*)(lds + (bufoff) + ldsw + _i * 8192), 16, 0, 0); } while (0)
; #define PG8_LDA(dst, b, h) do { _Pragma("unroll") for (int m = 0; m < 4; ++m) _Pragma("unroll") for (int k = 0; k < 2; ++k) dst[m][k] = *(const PG8_LAS bf16x8*)(lds + PG8_SA(b, h) + aoff + m * 2048 + k * 1024); } while (0)
; #define PG8_LDB(dst, b, h) do { _Pragma("unroll") for (int n = 0; n < 2; ++n) _Pragma("unroll") for (int k = 0; k < 2; ++k) dst[n][k] = *(const PG8_LAS bf16x8*)(lds + PG8_SB(b, h) + boff + n * 2048 + k * 1024); } while (0)
; #define PG8_MMA(ai, bj, At, Bt) do { __builtin_amdgcn_s_setprio(1); _Pragma("unroll") for (int m = 0; m < 4; ++m) _Pragma("unroll") for (int n = 0; n < 2; ++n) _Pragma("unroll") for (int k = 0; k < 2; ++k) \
;         acc[ai][bj][m][n] = __builtin_amdgcn_mfma_f32_16x16x32_bf16(Bt[n][k], At[m][k], acc[ai][bj][m][n], 0, 0, 0); __builtin_amdgcn_s_setprio(0); } while (0)
; #define PG8_WAIT_V(n) asm volatile("s_waitcnt vmcnt(" #n ")" ::: "memory")
; #define PG8_WAIT_L(n) asm volatile("s_waitcnt lgkmcnt(" #n ")" ::: "memory")
; #define PG8_BAR __builtin_amdgcn_s_barrier()
; #define PG8_SCHED __builtin_amdgcn_sched_barrier(0)
; template <class Epi, class Sched, bool ALIGN_EPI = false, bool SP2 = false>
; __device__ __forceinline__ void gemm_phase(PG8_LAS unsigned char* lds, const Gemm g, const Sched& S, const Epi& E, const int wave_in) {
;     ...
;             PG8_WAIT_V(8); PG8_WAIT_L(0); PG8_BAR; PG8_MMA(1, 0, At, B0); PG8_MMA(1, 1, At, B1); PG8_BAR; PG8_SCHED;
;             PG8_LDB(B0, 1, 0); PG8_LDB(B1, 1, 1); PG8_SCHED; PG8_LDA(At, 1, 0); PG8_STAGE(PG8_SA(0, 1), a2 + hstepA, voffA);
;             PG8_WAIT_V(8); PG8_WAIT_L(0); PG8_BAR; PG8_MMA(0, 0, At, B0); PG8_MMA(0, 1, At, B1); PG8_BAR; PG8_SCHED;
	s_setprio 1
	v_mfma_f32_16x16x32_bf16 v[60:63], v[128:131], v[178:181], 0
	v_mfma_f32_16x16x32_bf16 v[56:59], v[136:139], v[178:181], 0
	v_mfma_f32_16x16x32_bf16 v[48:51], v[128:131], v[186:189], 0
	v_mfma_f32_16x16x32_bf16 v[40:43], v[136:139], v[186:189], 0
	v_mfma_f32_16x16x32_bf16 v[32:35], v[128:131], v[194:197], 0
	v_mfma_f32_16x16x32_bf16 v[24:27], v[136:139], v[194:197], 0
	v_mfma_f32_16x16x32_bf16 v[16:19], v[128:131], v[202:205], 0
	v_mfma_f32_16x16x32_bf16 v[8:11], v[136:139], v[202:205], 0
	v_mfma_f32_16x16x32_bf16 v[60:63], v[132:135], v[182:185], v[60:63]
	v_mfma_f32_16x16x32_bf16 v[56:59], v[140:143], v[182:185], v[56:59]
	v_mfma_f32_16x16x32_bf16 v[48:51], v[132:135], v[190:193], v[48:51]
	v_mfma_f32_16x16x32_bf16 v[40:43], v[140:143], v[190:193], v[40:43]
	v_mfma_f32_16x16x32_bf16 v[32:35], v[132:135], v[198:201], v[32:35]
	v_mfma_f32_16x16x32_bf16 v[24:27], v[140:143], v[198:201], v[24:27]
	v_mfma_f32_16x16x32_bf16 v[16:19], v[132:135], v[206:209], v[16:19]
	v_mfma_f32_16x16x32_bf16 v[8:11], v[140:143], v[206:209], v[8:11]
	v_mfma_f32_16x16x32_bf16 v[52:55], v[162:165], v[178:181], 0
	v_mfma_f32_16x16x32_bf16 v[44:47], v[170:173], v[178:181], 0
	v_mfma_f32_16x16x32_bf16 v[36:39], v[162:165], v[186:189], 0
	v_mfma_f32_16x16x32_bf16 v[28:31], v[170:173], v[186:189], 0
	v_mfma_f32_16x16x32_bf16 v[20:23], v[162:165], v[194:197], 0
	v_mfma_f32_16x16x32_bf16 v[12:15], v[170:173], v[194:197], 0
	v_mfma_f32_16x16x32_bf16 v[4:7], v[162:165], v[202:205], 0
	v_mfma_f32_16x16x32_bf16 v[0:3], v[170:173], v[202:205], 0
	v_mfma_f32_16x16x32_bf16 v[52:55], v[166:169], v[182:185], v[52:55]
	v_mfma_f32_16x16x32_bf16 v[44:47], v[174:177], v[182:185], v[44:47]
	v_mfma_f32_16x16x32_bf16 v[36:39], v[166:169], v[190:193], v[36:39]
	v_mfma_f32_16x16x32_bf16 v[28:31], v[174:177], v[190:193], v[28:31]
	v_mfma_f32_16x16x32_bf16 v[20:23], v[166:169], v[198:201], v[20:23]
	v_mfma_f32_16x16x32_bf16 v[12:15], v[174:177], v[198:201], v[12:15]
	v_mfma_f32_16x16x32_bf16 v[4:7], v[166:169], v[206:209], v[4:7]
	v_mfma_f32_16x16x32_bf16 v[0:3], v[174:177], v[206:209], v[0:3]
	s_setprio 0
	s_barrier
	s_add_i32 s56, 0, 0x18000
	s_add_i32 s57, 0, 0x1c000
	v_add_u32_e32 v140, s56, v212
	v_add_u32_e32 v174, s57, v212
	ds_read_b128 v[128:131], v140
	ds_read_b128 v[132:135], v140 offset:1024
	ds_read_b128 v[136:139], v140 offset:2048
	ds_read_b128 v[140:143], v140 offset:3072
	ds_read_b128 v[162:165], v174
	ds_read_b128 v[166:169], v174 offset:1024
	ds_read_b128 v[170:173], v174 offset:2048
	ds_read_b128 v[174:177], v174 offset:3072
	s_add_u32 s22, s26, 0x310000
	s_addc_u32 s23, s27, 0
	s_mov_b32 m0, s39
	v_lshl_add_u64 v[224:225], s[22:23], 0, v[150:151]
	ds_read_b128 v[178:181], v216 offset:32768
	ds_read_b128 v[182:185], v216 offset:33792
	ds_read_b128 v[186:189], v216 offset:34816
	ds_read_b128 v[190:193], v216 offset:35840
	ds_read_b128 v[194:197], v216 offset:36864
	ds_read_b128 v[198:201], v216 offset:37888
	ds_read_b128 v[202:205], v216 offset:38912
	ds_read_b128 v[206:209], v216 offset:39936
	global_load_lds_dwordx4 v[224:225], off
	v_lshl_add_u64 v[224:225], s[22:23], 0, v[146:147]
	s_mov_b32 m0, s40
	s_nop 0
	global_load_lds_dwordx4 v[224:225], off
	s_waitcnt vmcnt(8)
	s_waitcnt lgkmcnt(0)
	s_barrier
	s_setprio 1
	v_mfma_f32_16x16x32_bf16 v[124:127], v[128:131], v[178:181], v[124:127]
	v_mfma_f32_16x16x32_bf16 v[120:123], v[136:139], v[178:181], v[120:123]
	v_mfma_f32_16x16x32_bf16 v[112:115], v[128:131], v[186:189], v[112:115]
	v_mfma_f32_16x16x32_bf16 v[104:107], v[136:139], v[186:189], v[104:107]
	v_mfma_f32_16x16x32_bf16 v[100:103], v[128:131], v[194:197], v[100:103]
	v_mfma_f32_16x16x32_bf16 v[96:99], v[136:139], v[194:197], v[96:99]
	v_mfma_f32_16x16x32_bf16 v[76:79], v[128:131], v[202:205], v[76:79]
	v_mfma_f32_16x16x32_bf16 v[72:75], v[136:139], v[202:205], v[72:75]
	v_mfma_f32_16x16x32_bf16 v[124:127], v[132:135], v[182:185], v[124:127]
	v_mfma_f32_16x16x32_bf16 v[120:123], v[140:143], v[182:185], v[120:123]
	v_mfma_f32_16x16x32_bf16 v[112:115], v[132:135], v[190:193], v[112:115]
	v_mfma_f32_16x16x32_bf16 v[104:107], v[140:143], v[190:193], v[104:107]
	v_mfma_f32_16x16x32_bf16 v[100:103], v[132:135], v[198:201], v[100:103]
	v_mfma_f32_16x16x32_bf16 v[96:99], v[140:143], v[198:201], v[96:99]
	v_mfma_f32_16x16x32_bf16 v[76:79], v[132:135], v[206:209], v[76:79]
	v_mfma_f32_16x16x32_bf16 v[72:75], v[140:143], v[206:209], v[72:75]
	v_mfma_f32_16x16x32_bf16 v[116:119], v[162:165], v[178:181], v[116:119]
	v_mfma_f32_16x16x32_bf16 v[108:111], v[170:173], v[178:181], v[108:111]
	v_mfma_f32_16x16x32_bf16 v[92:95], v[162:165], v[186:189], v[92:95]
	v_mfma_f32_16x16x32_bf16 v[88:91], v[170:173], v[186:189], v[88:91]
	v_mfma_f32_16x16x32_bf16 v[84:87], v[162:165], v[194:197], v[84:87]
	v_mfma_f32_16x16x32_bf16 v[80:83], v[170:173], v[194:197], v[80:83]
	v_mfma_f32_16x16x32_bf16 v[68:71], v[162:165], v[202:205], v[68:71]
	v_mfma_f32_16x16x32_bf16 v[64:67], v[170:173], v[202:205], v[64:67]
	v_mfma_f32_16x16x32_bf16 v[116:119], v[166:169], v[182:185], v[116:119]
	v_mfma_f32_16x16x32_bf16 v[108:111], v[174:177], v[182:185], v[108:111]
	v_mfma_f32_16x16x32_bf16 v[92:95], v[166:169], v[190:193], v[92:95]
	v_mfma_f32_16x16x32_bf16 v[88:91], v[174:177], v[190:193], v[88:91]
	v_mfma_f32_16x16x32_bf16 v[84:87], v[166:169], v[198:201], v[84:87]
	v_mfma_f32_16x16x32_bf16 v[80:83], v[174:177], v[198:201], v[80:83]
	v_mfma_f32_16x16x32_bf16 v[68:71], v[166:169], v[206:209], v[68:71]
	v_mfma_f32_16x16x32_bf16 v[64:67], v[174:177], v[206:209], v[64:67]
	s_setprio 0
	s_barrier
; #define PG8_STAGE(bufoff, gbase, voff) do { _Pragma("unroll") for (int _i = 0; _i < 2; ++_i) \
;         __builtin_amdgcn_global_load_lds((const unsigned*)((const char*)(gbase) + (voff)[_i]), (PG8_LAS unsigned*)(lds + (bufoff) + ldsw + _i * 8192), 16, 0, 0); } while (0)
; #define PG8_LDA(dst, b, h) do { _Pragma("unroll") for (int m = 0; m < 4; ++m) _Pragma("unroll") for (int k = 0; k < 2; ++k) dst[m][k] = *(const PG8_LAS bf16x8*)(lds + PG8_SA(b, h) + aoff + m * 2048 + k * 1024); } while (0)
; #define PG8_LDB(dst, b, h) do { _Pragma("unroll") for (int n = 0; n < 2; ++n) _Pragma("unroll") for (int k = 0; k < 2; ++k) dst[n][k] = *(const PG8_LAS bf16x8*)(lds + PG8_SB(b, h) + boff + n * 2048 + k * 1024); } while (0)
; #define PG8_MMA(ai, bj, At, Bt) do { __builtin_amdgcn_s_setprio(1); _Pragma("unroll") for (int m = 0; m < 4; ++m) _Pragma("unroll") for (int n = 0; n < 2; ++n) _Pragma("unroll") for (int k = 0; k < 2; ++k) \
;         acc[ai][bj][m][n] = __builtin_amdgcn_mfma_f32_16x16x32_bf16(Bt[n][k], At[m][k], acc[ai][bj][m][n], 0, 0, 0); __builtin_amdgcn_s_setprio(0); } while (0)
; #define PG8_BAR __builtin_amdgcn_s_barrier()
; template <class Epi, class Sched, bool ALIGN_EPI = false, bool SP2 = false>
; __device__ __forceinline__ void gemm_phase(PG8_LAS unsigned char* lds, const Gemm g, const Sched& S, const Epi& E, const int wave_in) {
;     ...
;             PG8_LDB(B0, 0, 0); PG8_LDB(B1, 0, 1); PG8_SCHED; PG8_LDA(At, 0, 0); PG8_STAGE(PG8_SA(1, 1), a1 + hstepA, voffA);
;             PG8_WAIT_V(8); PG8_WAIT_L(0); PG8_BAR; PG8_MMA(0, 0, At, B0); PG8_MMA(0, 1, At, B1); PG8_BAR; PG8_SCHED;
;             PG8_LDA(At, 0, 1); PG8_STAGE(PG8_SB(0, 0), b2, voffB); PG8_STAGE(PG8_SB(0, 1), b2 + hstepB, voffB); PG8_STAGE(PG8_SA(0, 0), a2, voffA);
;             PG8_WAIT_V(8); PG8_WAIT_L(0); PG8_BAR; PG8_MMA(1, 0, At, B0); PG8_MMA(1, 1, At, B1); PG8_BAR; PG8_SCHED;
;             PG8_LDB(B0, 1, 0); PG8_LDB(B1, 1, 1); PG8_SCHED; PG8_LDA(At, 1, 0); PG8_STAGE(PG8_SA(0, 1), a2 + hstepA, voffA);
;             PG8_WAIT_V(8); PG8_WAIT_L(0); PG8_BAR; PG8_MMA(0, 0, At, B0); PG8_MMA(0, 1, At, B1); PG8_BAR; PG8_SCHED;
;             PG8_LDA(At, 1, 1); PG8_STAGE(PG8_SB(1, 0), b3, voffB); PG8_STAGE(PG8_SB(1, 1), b3 + hstepB, voffB); PG8_STAGE(PG8_SA(1, 0), a3, voffA);
;             PG8_WAIT_V(8); PG8_WAIT_L(0); PG8_BAR; PG8_MMA(1, 0, At, B0); PG8_MMA(1, 1, At, B1); PG8_BAR; PG8_SCHED;
	s_add_i32 s22, s56, s34
	v_lshl_add_u64 v[210:211], v[210:211], 0, s[6:7]
	s_mov_b32 m0, s22
	ds_read_b128 v[178:181], v216 offset:49152
	ds_read_b128 v[182:185], v216 offset:50176
	ds_read_b128 v[186:189], v216 offset:51200
	ds_read_b128 v[190:193], v216 offset:52224
	ds_read_b128 v[194:197], v216 offset:53248
	ds_read_b128 v[198:201], v216 offset:54272
	ds_read_b128 v[202:205], v216 offset:55296
	ds_read_b128 v[206:209], v216 offset:56320
	global_load_lds_dwordx4 v[210:211], off
	s_add_i32 m0, s22, 0x2000
	s_add_u32 s22, s24, 0x100080
	v_lshl_add_u64 v[210:211], v[218:219], 0, s[6:7]
	s_addc_u32 s23, s25, 0
	s_add_i32 s24, s57, s34
	global_load_lds_dwordx4 v[210:211], off
	v_lshl_add_u64 v[210:211], s[22:23], 0, v[148:149]
	s_mov_b32 m0, s24
	s_nop 0
	global_load_lds_dwordx4 v[210:211], off
	v_lshl_add_u64 v[210:211], s[22:23], 0, v[144:145]
	s_add_i32 m0, s24, 0x2000
	s_nop 0
	global_load_lds_dwordx4 v[210:211], off
	v_lshl_add_u64 v[210:211], v[220:221], 0, s[6:7]
	s_mov_b32 m0, s44
	s_nop 0
	global_load_lds_dwordx4 v[210:211], off
	v_lshl_add_u64 v[210:211], v[222:223], 0, s[6:7]
	s_mov_b32 m0, s45
	s_nop 0
	global_load_lds_dwordx4 v[210:211], off
	s_waitcnt vmcnt(8)
	s_waitcnt lgkmcnt(0)
	s_barrier
	s_setprio 1
	v_mfma_f32_16x16x32_bf16 v[60:63], v[128:131], v[178:181], v[60:63]
	v_mfma_f32_16x16x32_bf16 v[56:59], v[136:139], v[178:181], v[56:59]
	v_mfma_f32_16x16x32_bf16 v[48:51], v[128:131], v[186:189], v[48:51]
	v_mfma_f32_16x16x32_bf16 v[40:43], v[136:139], v[186:189], v[40:43]
	v_mfma_f32_16x16x32_bf16 v[32:35], v[128:131], v[194:197], v[32:35]
	v_mfma_f32_16x16x32_bf16 v[24:27], v[136:139], v[194:197], v[24:27]
	v_mfma_f32_16x16x32_bf16 v[16:19], v[128:131], v[202:205], v[16:19]
	v_mfma_f32_16x16x32_bf16 v[8:11], v[136:139], v[202:205], v[8:11]
	v_mfma_f32_16x16x32_bf16 v[60:63], v[132:135], v[182:185], v[60:63]
	v_mfma_f32_16x16x32_bf16 v[56:59], v[140:143], v[182:185], v[56:59]
	v_mfma_f32_16x16x32_bf16 v[48:51], v[132:135], v[190:193], v[48:51]
	v_mfma_f32_16x16x32_bf16 v[40:43], v[140:143], v[190:193], v[40:43]
	v_mfma_f32_16x16x32_bf16 v[32:35], v[132:135], v[198:201], v[32:35]
	v_mfma_f32_16x16x32_bf16 v[24:27], v[140:143], v[198:201], v[24:27]
	v_mfma_f32_16x16x32_bf16 v[16:19], v[132:135], v[206:209], v[16:19]
	v_mfma_f32_16x16x32_bf16 v[8:11], v[140:143], v[206:209], v[8:11]
	v_mfma_f32_16x16x32_bf16 v[52:55], v[162:165], v[178:181], v[52:55]
	v_mfma_f32_16x16x32_bf16 v[44:47], v[170:173], v[178:181], v[44:47]
	v_mfma_f32_16x16x32_bf16 v[36:39], v[162:165], v[186:189], v[36:39]
	v_mfma_f32_16x16x32_bf16 v[28:31], v[170:173], v[186:189], v[28:31]
	v_mfma_f32_16x16x32_bf16 v[20:23], v[162:165], v[194:197], v[20:23]
	v_mfma_f32_16x16x32_bf16 v[12:15], v[170:173], v[194:197], v[12:15]
	v_mfma_f32_16x16x32_bf16 v[4:7], v[162:165], v[202:205], v[4:7]
	v_mfma_f32_16x16x32_bf16 v[0:3], v[170:173], v[202:205], v[0:3]
	v_mfma_f32_16x16x32_bf16 v[52:55], v[166:169], v[182:185], v[52:55]
	v_mfma_f32_16x16x32_bf16 v[44:47], v[174:177], v[182:185], v[44:47]
	v_mfma_f32_16x16x32_bf16 v[36:39], v[166:169], v[190:193], v[36:39]
	v_mfma_f32_16x16x32_bf16 v[28:31], v[174:177], v[190:193], v[28:31]
	v_mfma_f32_16x16x32_bf16 v[20:23], v[166:169], v[198:201], v[20:23]
	v_mfma_f32_16x16x32_bf16 v[12:15], v[174:177], v[198:201], v[12:15]
	v_mfma_f32_16x16x32_bf16 v[4:7], v[166:169], v[206:209], v[4:7]
	v_mfma_f32_16x16x32_bf16 v[0:3], v[174:177], v[206:209], v[0:3]
	s_setprio 0
	s_barrier
	s_add_i32 s55, s55, 2
	s_add_u32 s53, s53, 0x100
	s_addc_u32 s54, s54, 0
	s_cmp_gt_u32 s55, 61
	s_mov_b64 s[22:23], s[4:5]
	s_cbranch_scc0 .LBB0_1093
	s_branch .Lkx_12
.LBB0_1093:
	ds_read_b128 v[128:131], v214
	ds_read_b128 v[132:135], v214 offset:1024
	ds_read_b128 v[136:139], v214 offset:2048
	ds_read_b128 v[140:143], v214 offset:3072
	ds_read_b128 v[162:165], v215
	ds_read_b128 v[166:169], v215 offset:1024
	ds_read_b128 v[170:173], v215 offset:2048
	ds_read_b128 v[174:177], v215 offset:3072
	s_add_u32 s4, s22, 0x100
	s_addc_u32 s5, s23, 0
	s_cmp_eq_u32 s55, 60
	s_cselect_b32 s27, s17, s5
	s_cselect_b32 s26, s16, s4
	s_cselect_b32 s25, s15, s54
	s_cselect_b32 s24, s21, s53
	v_lshl_add_u64 v[210:211], s[22:23], 0, v[154:155]
	s_add_i32 m0, s37, 0xc000
	ds_read_b128 v[178:181], v216
	ds_read_b128 v[182:185], v216 offset:1024
	ds_read_b128 v[186:189], v216 offset:2048
	ds_read_b128 v[190:193], v216 offset:3072
	ds_read_b128 v[194:197], v216 offset:4096
	ds_read_b128 v[198:201], v216 offset:5120
	ds_read_b128 v[202:205], v216 offset:6144
	ds_read_b128 v[206:209], v216 offset:7168
	global_load_lds_dwordx4 v[210:211], off
	v_lshl_add_u64 v[210:211], s[22:23], 0, v[156:157]
	s_add_i32 m0, s37, 0xe000
	s_nop 0
	global_load_lds_dwordx4 v[210:211], off
	s_waitcnt vmcnt(8)
	s_waitcnt lgkmcnt(0)
	s_barrier
; #define PG8_STAGE(bufoff, gbase, voff) do { _Pragma("unroll") for (int _i = 0; _i < 2; ++_i) \
;         __builtin_amdgcn_global_load_lds((const unsigned*)((const char*)(gbase) + (voff)[_i]), (PG8_LAS unsigned*)(lds + (bufoff) + ldsw + _i * 8192), 16, 0, 0); } while (0)
; #define PG8_LDA(dst, b, h) do { _Pragma("unroll") for (int m = 0; m < 4; ++m) _Pragma("unroll") for (int k = 0; k < 2; ++k) dst[m][k] = *(const PG8_LAS bf16x8*)(lds + PG8_SA(b, h) + aoff + m * 2048 + k * 1024); } while (0)
; #define PG8_MMA(ai, bj, At, Bt) do { __builtin_amdgcn_s_setprio(1); _Pragma("unroll") for (int m = 0; m < 4; ++m) _Pragma("unroll") for (int n = 0; n < 2; ++n) _Pragma("unroll") for (int k = 0; k < 2; ++k) \
;         acc[ai][bj][m][n] = __builtin_amdgcn_mfma_f32_16x16x32_bf16(Bt[n][k], At[m][k], acc[ai][bj][m][n], 0, 0, 0); __builtin_amdgcn_s_setprio(0); } while (0)
; #define PG8_WAIT_V(n) asm volatile("s_waitcnt vmcnt(" #n ")" ::: "memory")
; #define PG8_WAIT_L(n) asm volatile("s_waitcnt lgkmcnt(" #n ")" ::: "memory")
; #define PG8_BAR __builtin_amdgcn_s_barrier()
; #define PG8_SCHED __builtin_amdgcn_sched_barrier(0)
; template <class Epi, class Sched, bool ALIGN_EPI = false, bool SP2 = false>
; __device__ __forceinline__ void gemm_phase(PG8_LAS unsigned char* lds, const Gemm g, const Sched& S, const Epi& E, const int wave_in) {
;     ...
;             PG8_WAIT_V(8); PG8_WAIT_L(0); PG8_BAR; PG8_MMA(0, 0, At, B0); PG8_MMA(0, 1, At, B1); PG8_BAR; PG8_SCHED;
;             PG8_LDA(At, 0, 1); PG8_STAGE(PG8_SB(0, 0), b2, voffB); PG8_STAGE(PG8_SB(0, 1), b2 + hstepB, voffB); PG8_STAGE(PG8_SA(0, 0), a2, voffA);
;             PG8_WAIT_V(8); PG8_WAIT_L(0); PG8_BAR; PG8_MMA(1, 0, At, B0); PG8_MMA(1, 1, At, B1); PG8_BAR; PG8_SCHED;
	s_setprio 1
	v_mfma_f32_16x16x32_bf16 v[124:127], v[128:131], v[178:181], v[124:127]
	v_mfma_f32_16x16x32_bf16 v[120:123], v[136:139], v[178:181], v[120:123]
	v_mfma_f32_16x16x32_bf16 v[112:115], v[128:131], v[186:189], v[112:115]
	v_mfma_f32_16x16x32_bf16 v[104:107], v[136:139], v[186:189], v[104:107]
	v_mfma_f32_16x16x32_bf16 v[100:103], v[128:131], v[194:197], v[100:103]
	v_mfma_f32_16x16x32_bf16 v[96:99], v[136:139], v[194:197], v[96:99]
	v_mfma_f32_16x16x32_bf16 v[76:79], v[128:131], v[202:205], v[76:79]
	v_mfma_f32_16x16x32_bf16 v[72:75], v[136:139], v[202:205], v[72:75]
	v_mfma_f32_16x16x32_bf16 v[124:127], v[132:135], v[182:185], v[124:127]
	v_mfma_f32_16x16x32_bf16 v[120:123], v[140:143], v[182:185], v[120:123]
	v_mfma_f32_16x16x32_bf16 v[112:115], v[132:135], v[190:193], v[112:115]
	v_mfma_f32_16x16x32_bf16 v[104:107], v[140:143], v[190:193], v[104:107]
	v_mfma_f32_16x16x32_bf16 v[100:103], v[132:135], v[198:201], v[100:103]
	v_mfma_f32_16x16x32_bf16 v[96:99], v[140:143], v[198:201], v[96:99]
	v_mfma_f32_16x16x32_bf16 v[76:79], v[132:135], v[206:209], v[76:79]
	v_mfma_f32_16x16x32_bf16 v[72:75], v[140:143], v[206:209], v[72:75]
	v_mfma_f32_16x16x32_bf16 v[116:119], v[162:165], v[178:181], v[116:119]
	v_mfma_f32_16x16x32_bf16 v[108:111], v[170:173], v[178:181], v[108:111]
	v_mfma_f32_16x16x32_bf16 v[92:95], v[162:165], v[186:189], v[92:95]
	v_mfma_f32_16x16x32_bf16 v[88:91], v[170:173], v[186:189], v[88:91]
	v_mfma_f32_16x16x32_bf16 v[84:87], v[162:165], v[194:197], v[84:87]
	v_mfma_f32_16x16x32_bf16 v[80:83], v[170:173], v[194:197], v[80:83]
	v_mfma_f32_16x16x32_bf16 v[68:71], v[162:165], v[202:205], v[68:71]
	v_mfma_f32_16x16x32_bf16 v[64:67], v[170:173], v[202:205], v[64:67]
	v_mfma_f32_16x16x32_bf16 v[116:119], v[166:169], v[182:185], v[116:119]
	v_mfma_f32_16x16x32_bf16 v[108:111], v[174:177], v[182:185], v[108:111]
	v_mfma_f32_16x16x32_bf16 v[92:95], v[166:169], v[190:193], v[92:95]
	v_mfma_f32_16x16x32_bf16 v[88:91], v[174:177], v[190:193], v[88:91]
	v_mfma_f32_16x16x32_bf16 v[84:87], v[166:169], v[198:201], v[84:87]
	v_mfma_f32_16x16x32_bf16 v[80:83], v[174:177], v[198:201], v[80:83]
	v_mfma_f32_16x16x32_bf16 v[68:71], v[166:169], v[206:209], v[68:71]
	v_mfma_f32_16x16x32_bf16 v[64:67], v[174:177], v[206:209], v[64:67]
	s_setprio 0
	s_barrier
	s_add_i32 s22, s47, s34
	v_lshl_add_u64 v[210:211], s[24:25], 0, v[148:149]
	s_mov_b32 m0, s22
	ds_read_b128 v[178:181], v216 offset:16384
	ds_read_b128 v[182:185], v216 offset:17408
	ds_read_b128 v[186:189], v216 offset:18432
	ds_read_b128 v[190:193], v216 offset:19456
	ds_read_b128 v[194:197], v216 offset:20480
	ds_read_b128 v[198:201], v216 offset:21504
	ds_read_b128 v[202:205], v216 offset:22528
	ds_read_b128 v[206:209], v216 offset:23552
	global_load_lds_dwordx4 v[210:211], off
	s_add_i32 m0, s22, 0x2000
	s_add_u32 s22, s24, 0x100000
	v_lshl_add_u64 v[218:219], s[24:25], 0, v[144:145]
	s_addc_u32 s23, s25, 0
	s_add_i32 s56, s48, s34
	global_load_lds_dwordx4 v[218:219], off
	v_lshl_add_u64 v[220:221], s[22:23], 0, v[148:149]
	s_mov_b32 m0, s56
	v_lshl_add_u64 v[222:223], s[26:27], 0, v[146:147]
	global_load_lds_dwordx4 v[220:221], off
	v_lshl_add_u64 v[220:221], s[22:23], 0, v[144:145]
	s_add_i32 m0, s56, 0x2000
	s_nop 0
	global_load_lds_dwordx4 v[220:221], off
	v_lshl_add_u64 v[220:221], s[26:27], 0, v[150:151]
	s_mov_b32 m0, s37
	s_nop 0
	global_load_lds_dwordx4 v[220:221], off
	s_mov_b32 m0, s38
	s_nop 0
	global_load_lds_dwordx4 v[222:223], off
	s_waitcnt vmcnt(8)
	s_waitcnt lgkmcnt(0)
	s_barrier
	s_setprio 1
	v_mfma_f32_16x16x32_bf16 v[60:63], v[128:131], v[178:181], v[60:63]
	v_mfma_f32_16x16x32_bf16 v[56:59], v[136:139], v[178:181], v[56:59]
	v_mfma_f32_16x16x32_bf16 v[48:51], v[128:131], v[186:189], v[48:51]
	v_mfma_f32_16x16x32_bf16 v[40:43], v[136:139], v[186:189], v[40:43]
	v_mfma_f32_16x16x32_bf16 v[32:35], v[128:131], v[194:197], v[32:35]
	v_mfma_f32_16x16x32_bf16 v[24:27], v[136:139], v[194:197], v[24:27]
	v_mfma_f32_16x16x32_bf16 v[16:19], v[128:131], v[202:205], v[16:19]
	v_mfma_f32_16x16x32_bf16 v[8:11], v[136:139], v[202:205], v[8:11]
	v_mfma_f32_16x16x32_bf16 v[60:63], v[132:135], v[182:185], v[60:63]
	v_mfma_f32_16x16x32_bf16 v[56:59], v[140:143], v[182:185], v[56:59]
	v_mfma_f32_16x16x32_bf16 v[48:51], v[132:135], v[190:193], v[48:51]
	v_mfma_f32_16x16x32_bf16 v[40:43], v[140:143], v[190:193], v[40:43]
	v_mfma_f32_16x16x32_bf16 v[32:35], v[132:135], v[198:201], v[32:35]
	v_mfma_f32_16x16x32_bf16 v[24:27], v[140:143], v[198:201], v[24:27]
	v_mfma_f32_16x16x32_bf16 v[16:19], v[132:135], v[206:209], v[16:19]
	v_mfma_f32_16x16x32_bf16 v[8:11], v[140:143], v[206:209], v[8:11]
	v_mfma_f32_16x16x32_bf16 v[52:55], v[162:165], v[178:181], v[52:55]
	v_mfma_f32_16x16x32_bf16 v[44:47], v[170:173], v[178:181], v[44:47]
	v_mfma_f32_16x16x32_bf16 v[36:39], v[162:165], v[186:189], v[36:39]
	v_mfma_f32_16x16x32_bf16 v[28:31], v[170:173], v[186:189], v[28:31]
	v_mfma_f32_16x16x32_bf16 v[20:23], v[162:165], v[194:197], v[20:23]
	v_mfma_f32_16x16x32_bf16 v[12:15], v[170:173], v[194:197], v[12:15]
	v_mfma_f32_16x16x32_bf16 v[4:7], v[162:165], v[202:205], v[4:7]
	v_mfma_f32_16x16x32_bf16 v[0:3], v[170:173], v[202:205], v[0:3]
	v_mfma_f32_16x16x32_bf16 v[52:55], v[166:169], v[182:185], v[52:55]
	v_mfma_f32_16x16x32_bf16 v[44:47], v[174:177], v[182:185], v[44:47]
	v_mfma_f32_16x16x32_bf16 v[36:39], v[166:169], v[190:193], v[36:39]
	v_mfma_f32_16x16x32_bf16 v[28:31], v[174:177], v[190:193], v[28:31]
	v_mfma_f32_16x16x32_bf16 v[20:23], v[166:169], v[198:201], v[20:23]
	v_mfma_f32_16x16x32_bf16 v[12:15], v[174:177], v[198:201], v[12:15]
	v_mfma_f32_16x16x32_bf16 v[4:7], v[166:169], v[206:209], v[4:7]
	v_mfma_f32_16x16x32_bf16 v[0:3], v[174:177], v[206:209], v[0:3]
	s_setprio 0
	s_barrier
; #define PG8_STAGE(bufoff, gbase, voff) do { _Pragma("unroll") for (int _i = 0; _i < 2; ++_i) \
;         __builtin_amdgcn_global_load_lds((const unsigned*)((const char*)(gbase) + (voff)[_i]), (PG8_LAS unsigned*)(lds + (bufoff) + ldsw + _i * 8192), 16, 0, 0); } while (0)
; #define PG8_LDA(dst, b, h) do { _Pragma("unroll") for (int m = 0; m < 4; ++m) _Pragma("unroll") for (int k = 0; k < 2; ++k) dst[m][k] = *(const PG8_LAS bf16x8*)(lds + PG8_SA(b, h) + aoff + m * 2048 + k * 1024); } while (0)
; #define PG8_LDB(dst, b, h) do { _Pragma("unroll") for (int n = 0; n < 2; ++n) _Pragma("unroll") for (int k = 0; k < 2; ++k) dst[n][k] = *(const PG8_LAS bf16x8*)(lds + PG8_SB(b, h) + boff + n * 2048 + k * 1024); } while (0)
; #define PG8_MMA(ai, bj, At, Bt) do { __builtin_amdgcn_s_setprio(1); _Pragma("unroll") for (int m = 0; m < 4; ++m) _Pragma("unroll") for (int n = 0; n < 2; ++n) _Pragma("unroll") for (int k = 0; k < 2; ++k) \
;         acc[ai][bj][m][n] = __builtin_amdgcn_mfma_f32_16x16x32_bf16(Bt[n][k], At[m][k], acc[ai][bj][m][n], 0, 0, 0); __builtin_amdgcn_s_setprio(0); } while (0)
; #define PG8_WAIT_V(n) asm volatile("s_waitcnt vmcnt(" #n ")" ::: "memory")
; #define PG8_WAIT_L(n) asm volatile("s_waitcnt lgkmcnt(" #n ")" ::: "memory")
; #define PG8_BAR __builtin_amdgcn_s_barrier()
; #define PG8_SCHED __builtin_amdgcn_sched_barrier(0)
; template <class Epi, class Sched, bool ALIGN_EPI = false, bool SP2 = false>
; __device__ __forceinline__ void gemm_phase(PG8_LAS unsigned char* lds, const Gemm g, const Sched& S, const Epi& E, const int wave_in) {
;     ...
;             PG8_LDB(B0, 1, 0); PG8_LDB(B1, 1, 1); PG8_SCHED; PG8_LDA(At, 1, 0); PG8_STAGE(PG8_SA(0, 1), a2 + hstepA, voffA);
;             PG8_WAIT_V(8); PG8_WAIT_L(0); PG8_BAR; PG8_MMA(0, 0, At, B0); PG8_MMA(0, 1, At, B1); PG8_BAR; PG8_SCHED;
;             PG8_LDA(At, 1, 1); PG8_STAGE(PG8_SB(1, 0), b3, voffB); PG8_STAGE(PG8_SB(1, 1), b3 + hstepB, voffB); PG8_STAGE(PG8_SA(1, 0), a3, voffA);
;             PG8_WAIT_V(8); PG8_WAIT_L(0); PG8_BAR; PG8_MMA(1, 0, At, B0); PG8_MMA(1, 1, At, B1); PG8_BAR; PG8_SCHED;
	s_add_i32 s56, 0, 0x18000
	s_add_i32 s57, 0, 0x1c000
	v_add_u32_e32 v140, s56, v212
	v_add_u32_e32 v174, s57, v212
	ds_read_b128 v[128:131], v140
	ds_read_b128 v[132:135], v140 offset:1024
	ds_read_b128 v[136:139], v140 offset:2048
	ds_read_b128 v[140:143], v140 offset:3072
	ds_read_b128 v[162:165], v174
	ds_read_b128 v[166:169], v174 offset:1024
	ds_read_b128 v[170:173], v174 offset:2048
	ds_read_b128 v[174:177], v174 offset:3072
	s_add_u32 s22, s26, 0x310000
	s_addc_u32 s23, s27, 0
	s_mov_b32 m0, s39
	v_lshl_add_u64 v[224:225], s[22:23], 0, v[150:151]
	ds_read_b128 v[178:181], v216 offset:32768
	ds_read_b128 v[182:185], v216 offset:33792
	ds_read_b128 v[186:189], v216 offset:34816
	ds_read_b128 v[190:193], v216 offset:35840
	ds_read_b128 v[194:197], v216 offset:36864
	ds_read_b128 v[198:201], v216 offset:37888
	ds_read_b128 v[202:205], v216 offset:38912
	ds_read_b128 v[206:209], v216 offset:39936
	global_load_lds_dwordx4 v[224:225], off
	v_lshl_add_u64 v[224:225], s[22:23], 0, v[146:147]
	s_mov_b32 m0, s40
	s_nop 0
	global_load_lds_dwordx4 v[224:225], off
	s_waitcnt vmcnt(8)
	s_waitcnt lgkmcnt(0)
	s_barrier
	s_setprio 1
	v_mfma_f32_16x16x32_bf16 v[124:127], v[128:131], v[178:181], v[124:127]
	v_mfma_f32_16x16x32_bf16 v[120:123], v[136:139], v[178:181], v[120:123]
	v_mfma_f32_16x16x32_bf16 v[112:115], v[128:131], v[186:189], v[112:115]
	v_mfma_f32_16x16x32_bf16 v[104:107], v[136:139], v[186:189], v[104:107]
	v_mfma_f32_16x16x32_bf16 v[100:103], v[128:131], v[194:197], v[100:103]
	v_mfma_f32_16x16x32_bf16 v[96:99], v[136:139], v[194:197], v[96:99]
	v_mfma_f32_16x16x32_bf16 v[76:79], v[128:131], v[202:205], v[76:79]
	v_mfma_f32_16x16x32_bf16 v[72:75], v[136:139], v[202:205], v[72:75]
	v_mfma_f32_16x16x32_bf16 v[124:127], v[132:135], v[182:185], v[124:127]
	v_mfma_f32_16x16x32_bf16 v[120:123], v[140:143], v[182:185], v[120:123]
	v_mfma_f32_16x16x32_bf16 v[112:115], v[132:135], v[190:193], v[112:115]
	v_mfma_f32_16x16x32_bf16 v[104:107], v[140:143], v[190:193], v[104:107]
	v_mfma_f32_16x16x32_bf16 v[100:103], v[132:135], v[198:201], v[100:103]
	v_mfma_f32_16x16x32_bf16 v[96:99], v[140:143], v[198:201], v[96:99]
	v_mfma_f32_16x16x32_bf16 v[76:79], v[132:135], v[206:209], v[76:79]
	v_mfma_f32_16x16x32_bf16 v[72:75], v[140:143], v[206:209], v[72:75]
	v_mfma_f32_16x16x32_bf16 v[116:119], v[162:165], v[178:181], v[116:119]
	v_mfma_f32_16x16x32_bf16 v[108:111], v[170:173], v[178:181], v[108:111]
	v_mfma_f32_16x16x32_bf16 v[92:95], v[162:165], v[186:189], v[92:95]
	v_mfma_f32_16x16x32_bf16 v[88:91], v[170:173], v[186:189], v[88:91]
	v_mfma_f32_16x16x32_bf16 v[84:87], v[162:165], v[194:197], v[84:87]
	v_mfma_f32_16x16x32_bf16 v[80:83], v[170:173], v[194:197], v[80:83]
	v_mfma_f32_16x16x32_bf16 v[68:71], v[162:165], v[202:205], v[68:71]
	v_mfma_f32_16x16x32_bf16 v[64:67], v[170:173], v[202:205], v[64:67]
	v_mfma_f32_16x16x32_bf16 v[116:119], v[166:169], v[182:185], v[116:119]
	v_mfma_f32_16x16x32_bf16 v[108:111], v[174:177], v[182:185], v[108:111]
	v_mfma_f32_16x16x32_bf16 v[92:95], v[166:169], v[190:193], v[92:95]
	v_mfma_f32_16x16x32_bf16 v[88:91], v[174:177], v[190:193], v[88:91]
	v_mfma_f32_16x16x32_bf16 v[84:87], v[166:169], v[198:201], v[84:87]
	v_mfma_f32_16x16x32_bf16 v[80:83], v[174:177], v[198:201], v[80:83]
	v_mfma_f32_16x16x32_bf16 v[68:71], v[166:169], v[206:209], v[68:71]
	v_mfma_f32_16x16x32_bf16 v[64:67], v[174:177], v[206:209], v[64:67]
	s_setprio 0
	s_barrier
	s_add_i32 s22, s56, s34
	v_lshl_add_u64 v[210:211], v[210:211], 0, s[6:7]
	s_mov_b32 m0, s22
	ds_read_b128 v[178:181], v216 offset:49152
	ds_read_b128 v[182:185], v216 offset:50176
	ds_read_b128 v[186:189], v216 offset:51200
	ds_read_b128 v[190:193], v216 offset:52224
	ds_read_b128 v[194:197], v216 offset:53248
	ds_read_b128 v[198:201], v216 offset:54272
	ds_read_b128 v[202:205], v216 offset:55296
	ds_read_b128 v[206:209], v216 offset:56320
	global_load_lds_dwordx4 v[210:211], off
	s_add_i32 m0, s22, 0x2000
	s_add_u32 s22, s24, 0x100080
	v_lshl_add_u64 v[210:211], v[218:219], 0, s[6:7]
	s_addc_u32 s23, s25, 0
	s_add_i32 s24, s57, s34
	global_load_lds_dwordx4 v[210:211], off
	v_lshl_add_u64 v[210:211], s[22:23], 0, v[148:149]
	s_mov_b32 m0, s24
	s_nop 0
	global_load_lds_dwordx4 v[210:211], off
	v_lshl_add_u64 v[210:211], s[22:23], 0, v[144:145]
	s_add_i32 m0, s24, 0x2000
	s_nop 0
	global_load_lds_dwordx4 v[210:211], off
	v_lshl_add_u64 v[210:211], v[220:221], 0, s[6:7]
	s_mov_b32 m0, s44
	s_nop 0
	global_load_lds_dwordx4 v[210:211], off
	v_lshl_add_u64 v[210:211], v[222:223], 0, s[6:7]
	s_mov_b32 m0, s45
	s_nop 0
	global_load_lds_dwordx4 v[210:211], off
	s_waitcnt vmcnt(8)
	s_waitcnt lgkmcnt(0)
	s_barrier
	s_setprio 1
	v_mfma_f32_16x16x32_bf16 v[60:63], v[128:131], v[178:181], v[60:63]
	v_mfma_f32_16x16x32_bf16 v[56:59], v[136:139], v[178:181], v[56:59]
	v_mfma_f32_16x16x32_bf16 v[48:51], v[128:131], v[186:189], v[48:51]
	v_mfma_f32_16x16x32_bf16 v[40:43], v[136:139], v[186:189], v[40:43]
	v_mfma_f32_16x16x32_bf16 v[32:35], v[128:131], v[194:197], v[32:35]
	v_mfma_f32_16x16x32_bf16 v[24:27], v[136:139], v[194:197], v[24:27]
	v_mfma_f32_16x16x32_bf16 v[16:19], v[128:131], v[202:205], v[16:19]
	v_mfma_f32_16x16x32_bf16 v[8:11], v[136:139], v[202:205], v[8:11]
	v_mfma_f32_16x16x32_bf16 v[60:63], v[132:135], v[182:185], v[60:63]
	v_mfma_f32_16x16x32_bf16 v[56:59], v[140:143], v[182:185], v[56:59]
	v_mfma_f32_16x16x32_bf16 v[48:51], v[132:135], v[190:193], v[48:51]
	v_mfma_f32_16x16x32_bf16 v[40:43], v[140:143], v[190:193], v[40:43]
	v_mfma_f32_16x16x32_bf16 v[32:35], v[132:135], v[198:201], v[32:35]
	v_mfma_f32_16x16x32_bf16 v[24:27], v[140:143], v[198:201], v[24:27]
	v_mfma_f32_16x16x32_bf16 v[16:19], v[132:135], v[206:209], v[16:19]
	v_mfma_f32_16x16x32_bf16 v[8:11], v[140:143], v[206:209], v[8:11]
	v_mfma_f32_16x16x32_bf16 v[52:55], v[162:165], v[178:181], v[52:55]
	v_mfma_f32_16x16x32_bf16 v[44:47], v[170:173], v[178:181], v[44:47]
	v_mfma_f32_16x16x32_bf16 v[36:39], v[162:165], v[186:189], v[36:39]
	v_mfma_f32_16x16x32_bf16 v[28:31], v[170:173], v[186:189], v[28:31]
	v_mfma_f32_16x16x32_bf16 v[20:23], v[162:165], v[194:197], v[20:23]
	v_mfma_f32_16x16x32_bf16 v[12:15], v[170:173], v[194:197], v[12:15]
	v_mfma_f32_16x16x32_bf16 v[4:7], v[162:165], v[202:205], v[4:7]
	v_mfma_f32_16x16x32_bf16 v[0:3], v[170:173], v[202:205], v[0:3]
	v_mfma_f32_16x16x32_bf16 v[52:55], v[166:169], v[182:185], v[52:55]
	v_mfma_f32_16x16x32_bf16 v[44:47], v[174:177], v[182:185], v[44:47]
	v_mfma_f32_16x16x32_bf16 v[36:39], v[166:169], v[190:193], v[36:39]
	v_mfma_f32_16x16x32_bf16 v[28:31], v[174:177], v[190:193], v[28:31]
	v_mfma_f32_16x16x32_bf16 v[20:23], v[166:169], v[198:201], v[20:23]
	v_mfma_f32_16x16x32_bf16 v[12:15], v[174:177], v[198:201], v[12:15]
	v_mfma_f32_16x16x32_bf16 v[4:7], v[166:169], v[206:209], v[4:7]
	v_mfma_f32_16x16x32_bf16 v[0:3], v[174:177], v[206:209], v[0:3]
	s_setprio 0
	s_barrier
	s_add_i32 s55, s55, 2
	s_add_u32 s53, s53, 0x100
	s_addc_u32 s54, s54, 0
	s_cmp_gt_u32 s55, 61
	s_mov_b64 s[22:23], s[4:5]
	s_cbranch_scc0 .LBB0_1093

;     __host__ __device__ bool next(int i, Unit& u) const { const bool ok = StaticOrder::next(i, u); u.pm = 0; u.pn = 0; return ok; }
; #define PG8_STAGE(bufoff, gbase, voff) do { _Pragma("unroll") for (int _i = 0; _i < 2; ++_i) \
;         __builtin_amdgcn_global_load_lds((const unsigned*)((const char*)(gbase) + (voff)[_i]), (PG8_LAS unsigned*)(lds + (bufoff) + ldsw + _i * 8192), 16, 0, 0); } while (0)
; #define PG8_LDA(dst, b, h) do { _Pragma("unroll") for (int m = 0; m < 4; ++m) _Pragma("unroll") for (int k = 0; k < 2; ++k) dst[m][k] = *(const PG8_LAS bf16x8*)(lds + PG8_SA(b, h) + aoff + m * 2048 + k * 1024); } while (0)
; #define PG8_LDB(dst, b, h) do { _Pragma("unroll") for (int n = 0; n < 2; ++n) _Pragma("unroll") for (int k = 0; k < 2; ++k) dst[n][k] = *(const PG8_LAS bf16x8*)(lds + PG8_SB(b, h) + boff + n * 2048 + k * 1024); } while (0)
; #define PG8_WAIT_V(n) asm volatile("s_waitcnt vmcnt(" #n ")" ::: "memory")
; #define PG8_BAR __builtin_amdgcn_s_barrier()
; template <class Epi, class Sched, bool ALIGN_EPI = false, bool SP2 = false>
; __device__ __forceinline__ void gemm_phase(PG8_LAS unsigned char* lds, const Gemm g, const Sched& S, const Epi& E, const int wave_in) {
;     ...
;         const bool has_next = S.next(ui + 1, nxt);
;         const char* nA = has_next ? (const char*)g.A + (size_t)nxt.pm * tstepA : cA; const char* nB = has_next ? (const char*)g.Bt + (size_t)nxt.pn * tstepB : cB;
;         for (int t = 0; t < nt; t += 2) {
;             const bool last = (t == nt - 2);
;             const char* a1 = cA + (size_t)(t + 1) * kstep;
;             const char* a2 = last ? nA : cA + (size_t)(t + 2) * kstep; const char* b2 = last ? nB : cB + (size_t)(t + 2) * kstep;
;             const char* a3 = a2 + kstep; const char* b3 = b2 + kstep;
;             if (last && has_next) S.a_ready(nxt);
;             if constexpr (SP2) {
;             PG8_LDB(B0, 0, 0); PG8_LDB(B1, 0, 1); PG8_SCHED; PG8_LDA(At, 0, 0); PG8_STAGE(PG8_SA(1, 1), a1 + hstepA, voffA);
;             PG8_WAIT_V(8); PG8_WAIT_L(0); PG8_BAR; PG8_MMA(0, 0, At, B0); PG8_MMA(0, 1, At, B1); PG8_BAR; PG8_SCHED;
;             PG8_LDA(At, 0, 1); PG8_STAGE(PG8_SB(0, 0), b2, voffB); PG8_STAGE(PG8_SB(0, 1), b2 + hstepB, voffB); PG8_STAGE(PG8_SA(0, 0), a2, voffA);
;             PG8_WAIT_V(8); PG8_WAIT_L(0); PG8_BAR; PG8_MMA(1, 0, At, B0); PG8_MMA(1, 1, At, B1); PG8_BAR; PG8_SCHED;
.LBB0_1374:
	s_add_u32 s17, s20, 0x100
	v_mov_b32_e32 v0, 0
	s_addc_u32 s53, s21, 0
	s_mov_b32 s54, -2
	ds_read_b128 v[128:131], v214
	ds_read_b128 v[132:135], v214 offset:1024
	ds_read_b128 v[136:139], v214 offset:2048
	ds_read_b128 v[140:143], v214 offset:3072
	ds_read_b128 v[162:165], v215
	ds_read_b128 v[166:169], v215 offset:1024
	ds_read_b128 v[170:173], v215 offset:2048
	ds_read_b128 v[174:177], v215 offset:3072
	s_add_u32 s20, s18, 0x100
	s_addc_u32 s21, s19, 0
	s_cmpk_eq_i32 s54, 0x52
	s_cselect_b32 s25, s5, s21
	s_cselect_b32 s24, s4, s20
	s_cselect_b32 s23, s15, s53
	s_cselect_b32 s22, s14, s17
	v_lshl_add_u64 v[210:211], s[18:19], 0, v[154:155]
	s_add_i32 m0, s35, 0xc000
	ds_read_b128 v[178:181], v216
	ds_read_b128 v[182:185], v216 offset:1024
	ds_read_b128 v[186:189], v216 offset:2048
	ds_read_b128 v[190:193], v216 offset:3072
	ds_read_b128 v[194:197], v216 offset:4096
	ds_read_b128 v[198:201], v216 offset:5120
	ds_read_b128 v[202:205], v216 offset:6144
	ds_read_b128 v[206:209], v216 offset:7168
	global_load_lds_dwordx4 v[210:211], off
	v_lshl_add_u64 v[210:211], s[18:19], 0, v[156:157]
	s_add_i32 m0, s35, 0xe000
	s_nop 0
	global_load_lds_dwordx4 v[210:211], off
	s_waitcnt vmcnt(8)
	s_waitcnt lgkmcnt(0)
	s_barrier
	s_setprio 1
	v_mfma_f32_16x16x32_bf16 v[124:127], v[128:131], v[178:181], 0
	v_mfma_f32_16x16x32_bf16 v[120:123], v[136:139], v[178:181], 0
	v_mfma_f32_16x16x32_bf16 v[112:115], v[128:131], v[186:189], 0
	v_mfma_f32_16x16x32_bf16 v[104:107], v[136:139], v[186:189], 0
	v_mfma_f32_16x16x32_bf16 v[100:103], v[128:131], v[194:197], 0
	v_mfma_f32_16x16x32_bf16 v[96:99], v[136:139], v[194:197], 0
	v_mfma_f32_16x16x32_bf16 v[76:79], v[128:131], v[202:205], 0
	v_mfma_f32_16x16x32_bf16 v[72:75], v[136:139], v[202:205], 0
	v_mfma_f32_16x16x32_bf16 v[124:127], v[132:135], v[182:185], v[124:127]
	v_mfma_f32_16x16x32_bf16 v[120:123], v[140:143], v[182:185], v[120:123]
	v_mfma_f32_16x16x32_bf16 v[112:115], v[132:135], v[190:193], v[112:115]
	v_mfma_f32_16x16x32_bf16 v[104:107], v[140:143], v[190:193], v[104:107]
	v_mfma_f32_16x16x32_bf16 v[100:103], v[132:135], v[198:201], v[100:103]
	v_mfma_f32_16x16x32_bf16 v[96:99], v[140:143], v[198:201], v[96:99]
	v_mfma_f32_16x16x32_bf16 v[76:79], v[132:135], v[206:209], v[76:79]
	v_mfma_f32_16x16x32_bf16 v[72:75], v[140:143], v[206:209], v[72:75]
	v_mfma_f32_16x16x32_bf16 v[116:119], v[162:165], v[178:181], 0
	v_mfma_f32_16x16x32_bf16 v[108:111], v[170:173], v[178:181], 0
	v_mfma_f32_16x16x32_bf16 v[92:95], v[162:165], v[186:189], 0
	v_mfma_f32_16x16x32_bf16 v[88:91], v[170:173], v[186:189], 0
	v_mfma_f32_16x16x32_bf16 v[84:87], v[162:165], v[194:197], 0
	v_mfma_f32_16x16x32_bf16 v[80:83], v[170:173], v[194:197], 0
	v_mfma_f32_16x16x32_bf16 v[68:71], v[162:165], v[202:205], 0
	v_mfma_f32_16x16x32_bf16 v[64:67], v[170:173], v[202:205], 0
	v_mfma_f32_16x16x32_bf16 v[116:119], v[166:169], v[182:185], v[116:119]
	v_mfma_f32_16x16x32_bf16 v[108:111], v[174:177], v[182:185], v[108:111]
	v_mfma_f32_16x16x32_bf16 v[92:95], v[166:169], v[190:193], v[92:95]
	v_mfma_f32_16x16x32_bf16 v[88:91], v[174:177], v[190:193], v[88:91]
	v_mfma_f32_16x16x32_bf16 v[84:87], v[166:169], v[198:201], v[84:87]
	v_mfma_f32_16x16x32_bf16 v[80:83], v[174:177], v[198:201], v[80:83]
	v_mfma_f32_16x16x32_bf16 v[68:71], v[166:169], v[206:209], v[68:71]
	v_mfma_f32_16x16x32_bf16 v[64:67], v[174:177], v[206:209], v[64:67]
	s_setprio 0
	s_barrier
	s_add_i32 s18, s45, s30
	v_lshl_add_u64 v[210:211], s[22:23], 0, v[148:149]
	s_mov_b32 m0, s18
	ds_read_b128 v[178:181], v216 offset:16384
	ds_read_b128 v[182:185], v216 offset:17408
	ds_read_b128 v[186:189], v216 offset:18432
	ds_read_b128 v[190:193], v216 offset:19456
	ds_read_b128 v[194:197], v216 offset:20480
	ds_read_b128 v[198:201], v216 offset:21504
	ds_read_b128 v[202:205], v216 offset:22528
	ds_read_b128 v[206:209], v216 offset:23552
	global_load_lds_dwordx4 v[210:211], off
	s_add_i32 m0, s18, 0x2000
	s_add_u32 s18, s22, 0x158000
	v_lshl_add_u64 v[218:219], s[22:23], 0, v[144:145]
	s_addc_u32 s19, s23, 0
	s_add_i32 s55, s46, s30
	global_load_lds_dwordx4 v[218:219], off
	v_lshl_add_u64 v[220:221], s[18:19], 0, v[148:149]
	s_mov_b32 m0, s55
	v_lshl_add_u64 v[222:223], s[24:25], 0, v[146:147]
	global_load_lds_dwordx4 v[220:221], off
	v_lshl_add_u64 v[220:221], s[18:19], 0, v[144:145]
	s_add_i32 m0, s55, 0x2000
	s_nop 0
	global_load_lds_dwordx4 v[220:221], off
	v_lshl_add_u64 v[220:221], s[24:25], 0, v[150:151]
	s_mov_b32 m0, s35
	s_nop 0
	global_load_lds_dwordx4 v[220:221], off
	s_mov_b32 m0, s36
	s_nop 0
	global_load_lds_dwordx4 v[222:223], off
	s_waitcnt vmcnt(8)
	s_waitcnt lgkmcnt(0)
	s_barrier
; #define PG8_STAGE(bufoff, gbase, voff) do { _Pragma("unroll") for (int _i = 0; _i < 2; ++_i) \
;         __builtin_amdgcn_global_load_lds((const unsigned*)((const char*)(gbase) + (voff)[_i]), (PG8_LAS unsigned*)(lds + (bufoff) + ldsw + _i * 8192), 16, 0, 0); } while (0)
; #define PG8_LDA(dst, b, h) do { _Pragma("unroll") for (int m = 0; m < 4; ++m) _Pragma("unroll") for (int k = 0; k < 2; ++k) dst[m][k] = *(const PG8_LAS bf16x8*)(lds + PG8_SA(b, h) + aoff + m * 2048 + k * 1024); } while (0)
; #define PG8_LDB(dst, b, h) do { _Pragma("unroll") for (int n = 0; n < 2; ++n) _Pragma("unroll") for (int k = 0; k < 2; ++k) dst[n][k] = *(const PG8_LAS bf16x8*)(lds + PG8_SB(b, h) + boff + n * 2048 + k * 1024); } while (0)
; #define PG8_MMA(ai, bj, At, Bt) do { __builtin_amdgcn_s_setprio(1); _Pragma("unroll") for (int m = 0; m < 4; ++m) _Pragma("unroll") for (int n = 0; n < 2; ++n) _Pragma("unroll") for (int k = 0; k < 2; ++k) \
;         acc[ai][bj][m][n] = __builtin_amdgcn_mfma_f32_16x16x32_bf16(Bt[n][k], At[m][k], acc[ai][bj][m][n], 0, 0, 0); __builtin_amdgcn_s_setprio(0); } while (0)
; #define PG8_WAIT_V(n) asm volatile("s_waitcnt vmcnt(" #n ")" ::: "memory")
; #define PG8_WAIT_L(n) asm volatile("s_waitcnt lgkmcnt(" #n ")" ::: "memory")
; #define PG8_BAR __builtin_amdgcn_s_barrier()
; #define PG8_SCHED __builtin_amdgcn_sched_barrier(0)
; template <class Epi, class Sched, bool ALIGN_EPI = false, bool SP2 = false>
; __device__ __forceinline__ void gemm_phase(PG8_LAS unsigned char* lds, const Gemm g, const Sched& S, const Epi& E, const int wave_in) {
;     ...
;             PG8_WAIT_V(8); PG8_WAIT_L(0); PG8_BAR; PG8_MMA(1, 0, At, B0); PG8_MMA(1, 1, At, B1); PG8_BAR; PG8_SCHED;
;             PG8_LDB(B0, 1, 0); PG8_LDB(B1, 1, 1); PG8_SCHED; PG8_LDA(At, 1, 0); PG8_STAGE(PG8_SA(0, 1), a2 + hstepA, voffA);
;             PG8_WAIT_V(8); PG8_WAIT_L(0); PG8_BAR; PG8_MMA(0, 0, At, B0); PG8_MMA(0, 1, At, B1); PG8_BAR; PG8_SCHED;
	s_setprio 1
	v_mfma_f32_16x16x32_bf16 v[60:63], v[128:131], v[178:181], 0
	v_mfma_f32_16x16x32_bf16 v[56:59], v[136:139], v[178:181], 0
	v_mfma_f32_16x16x32_bf16 v[48:51], v[128:131], v[186:189], 0
	v_mfma_f32_16x16x32_bf16 v[40:43], v[136:139], v[186:189], 0
	v_mfma_f32_16x16x32_bf16 v[32:35], v[128:131], v[194:197], 0
	v_mfma_f32_16x16x32_bf16 v[24:27], v[136:139], v[194:197], 0
	v_mfma_f32_16x16x32_bf16 v[16:19], v[128:131], v[202:205], 0
	v_mfma_f32_16x16x32_bf16 v[8:11], v[136:139], v[202:205], 0
	v_mfma_f32_16x16x32_bf16 v[60:63], v[132:135], v[182:185], v[60:63]
	v_mfma_f32_16x16x32_bf16 v[56:59], v[140:143], v[182:185], v[56:59]
	v_mfma_f32_16x16x32_bf16 v[48:51], v[132:135], v[190:193], v[48:51]
	v_mfma_f32_16x16x32_bf16 v[40:43], v[140:143], v[190:193], v[40:43]
	v_mfma_f32_16x16x32_bf16 v[32:35], v[132:135], v[198:201], v[32:35]
	v_mfma_f32_16x16x32_bf16 v[24:27], v[140:143], v[198:201], v[24:27]
	v_mfma_f32_16x16x32_bf16 v[16:19], v[132:135], v[206:209], v[16:19]
	v_mfma_f32_16x16x32_bf16 v[8:11], v[140:143], v[206:209], v[8:11]
	v_mfma_f32_16x16x32_bf16 v[52:55], v[162:165], v[178:181], 0
	v_mfma_f32_16x16x32_bf16 v[44:47], v[170:173], v[178:181], 0
	v_mfma_f32_16x16x32_bf16 v[36:39], v[162:165], v[186:189], 0
	v_mfma_f32_16x16x32_bf16 v[28:31], v[170:173], v[186:189], 0
	v_mfma_f32_16x16x32_bf16 v[20:23], v[162:165], v[194:197], 0
	v_mfma_f32_16x16x32_bf16 v[12:15], v[170:173], v[194:197], 0
	v_mfma_f32_16x16x32_bf16 v[4:7], v[162:165], v[202:205], 0
	v_mfma_f32_16x16x32_bf16 v[0:3], v[170:173], v[202:205], 0
	v_mfma_f32_16x16x32_bf16 v[52:55], v[166:169], v[182:185], v[52:55]
	v_mfma_f32_16x16x32_bf16 v[44:47], v[174:177], v[182:185], v[44:47]
	v_mfma_f32_16x16x32_bf16 v[36:39], v[166:169], v[190:193], v[36:39]
	v_mfma_f32_16x16x32_bf16 v[28:31], v[174:177], v[190:193], v[28:31]
	v_mfma_f32_16x16x32_bf16 v[20:23], v[166:169], v[198:201], v[20:23]
	v_mfma_f32_16x16x32_bf16 v[12:15], v[174:177], v[198:201], v[12:15]
	v_mfma_f32_16x16x32_bf16 v[4:7], v[166:169], v[206:209], v[4:7]
	v_mfma_f32_16x16x32_bf16 v[0:3], v[174:177], v[206:209], v[0:3]
	s_setprio 0
	s_barrier
	s_add_i32 s55, 0, 0x18000
	s_add_i32 s56, 0, 0x1c000
	v_add_u32_e32 v140, s55, v212
	v_add_u32_e32 v174, s56, v212
	ds_read_b128 v[128:131], v140
	ds_read_b128 v[132:135], v140 offset:1024
	ds_read_b128 v[136:139], v140 offset:2048
	ds_read_b128 v[140:143], v140 offset:3072
	ds_read_b128 v[162:165], v174
	ds_read_b128 v[166:169], v174 offset:1024
	ds_read_b128 v[170:173], v174 offset:2048
	ds_read_b128 v[174:177], v174 offset:3072
	s_add_u32 s18, s24, 0x158000
	s_addc_u32 s19, s25, 0
	s_mov_b32 m0, s37
	v_lshl_add_u64 v[224:225], s[18:19], 0, v[150:151]
	ds_read_b128 v[178:181], v216 offset:32768
	ds_read_b128 v[182:185], v216 offset:33792
	ds_read_b128 v[186:189], v216 offset:34816
	ds_read_b128 v[190:193], v216 offset:35840
	ds_read_b128 v[194:197], v216 offset:36864
	ds_read_b128 v[198:201], v216 offset:37888
	ds_read_b128 v[202:205], v216 offset:38912
	ds_read_b128 v[206:209], v216 offset:39936
	global_load_lds_dwordx4 v[224:225], off
	v_lshl_add_u64 v[224:225], s[18:19], 0, v[146:147]
	s_mov_b32 m0, s38
	s_nop 0
	global_load_lds_dwordx4 v[224:225], off
	s_waitcnt vmcnt(8)
	s_waitcnt lgkmcnt(0)
	s_barrier
	s_setprio 1
	v_mfma_f32_16x16x32_bf16 v[124:127], v[128:131], v[178:181], v[124:127]
	v_mfma_f32_16x16x32_bf16 v[120:123], v[136:139], v[178:181], v[120:123]
	v_mfma_f32_16x16x32_bf16 v[112:115], v[128:131], v[186:189], v[112:115]
	v_mfma_f32_16x16x32_bf16 v[104:107], v[136:139], v[186:189], v[104:107]
	v_mfma_f32_16x16x32_bf16 v[100:103], v[128:131], v[194:197], v[100:103]
	v_mfma_f32_16x16x32_bf16 v[96:99], v[136:139], v[194:197], v[96:99]
	v_mfma_f32_16x16x32_bf16 v[76:79], v[128:131], v[202:205], v[76:79]
	v_mfma_f32_16x16x32_bf16 v[72:75], v[136:139], v[202:205], v[72:75]
	v_mfma_f32_16x16x32_bf16 v[124:127], v[132:135], v[182:185], v[124:127]
	v_mfma_f32_16x16x32_bf16 v[120:123], v[140:143], v[182:185], v[120:123]
	v_mfma_f32_16x16x32_bf16 v[112:115], v[132:135], v[190:193], v[112:115]
	v_mfma_f32_16x16x32_bf16 v[104:107], v[140:143], v[190:193], v[104:107]
	v_mfma_f32_16x16x32_bf16 v[100:103], v[132:135], v[198:201], v[100:103]
	v_mfma_f32_16x16x32_bf16 v[96:99], v[140:143], v[198:201], v[96:99]
	v_mfma_f32_16x16x32_bf16 v[76:79], v[132:135], v[206:209], v[76:79]
	v_mfma_f32_16x16x32_bf16 v[72:75], v[140:143], v[206:209], v[72:75]
	v_mfma_f32_16x16x32_bf16 v[116:119], v[162:165], v[178:181], v[116:119]
	v_mfma_f32_16x16x32_bf16 v[108:111], v[170:173], v[178:181], v[108:111]
	v_mfma_f32_16x16x32_bf16 v[92:95], v[162:165], v[186:189], v[92:95]
	v_mfma_f32_16x16x32_bf16 v[88:91], v[170:173], v[186:189], v[88:91]
	v_mfma_f32_16x16x32_bf16 v[84:87], v[162:165], v[194:197], v[84:87]
	v_mfma_f32_16x16x32_bf16 v[80:83], v[170:173], v[194:197], v[80:83]
	v_mfma_f32_16x16x32_bf16 v[68:71], v[162:165], v[202:205], v[68:71]
	v_mfma_f32_16x16x32_bf16 v[64:67], v[170:173], v[202:205], v[64:67]
	v_mfma_f32_16x16x32_bf16 v[116:119], v[166:169], v[182:185], v[116:119]
	v_mfma_f32_16x16x32_bf16 v[108:111], v[174:177], v[182:185], v[108:111]
	v_mfma_f32_16x16x32_bf16 v[92:95], v[166:169], v[190:193], v[92:95]
	v_mfma_f32_16x16x32_bf16 v[88:91], v[174:177], v[190:193], v[88:91]
	v_mfma_f32_16x16x32_bf16 v[84:87], v[166:169], v[198:201], v[84:87]
	v_mfma_f32_16x16x32_bf16 v[80:83], v[174:177], v[198:201], v[80:83]
	v_mfma_f32_16x16x32_bf16 v[68:71], v[166:169], v[206:209], v[68:71]
	v_mfma_f32_16x16x32_bf16 v[64:67], v[174:177], v[206:209], v[64:67]
	s_setprio 0
	s_barrier
; #define PG8_STAGE(bufoff, gbase, voff) do { _Pragma("unroll") for (int _i = 0; _i < 2; ++_i) \
;         __builtin_amdgcn_global_load_lds((const unsigned*)((const char*)(gbase) + (voff)[_i]), (PG8_LAS unsigned*)(lds + (bufoff) + ldsw + _i * 8192), 16, 0, 0); } while (0)
; #define PG8_LDA(dst, b, h) do { _Pragma("unroll") for (int m = 0; m < 4; ++m) _Pragma("unroll") for (int k = 0; k < 2; ++k) dst[m][k] = *(const PG8_LAS bf16x8*)(lds + PG8_SA(b, h) + aoff + m * 2048 + k * 1024); } while (0)
; #define PG8_LDB(dst, b, h) do { _Pragma("unroll") for (int n = 0; n < 2; ++n) _Pragma("unroll") for (int k = 0; k < 2; ++k) dst[n][k] = *(const PG8_LAS bf16x8*)(lds + PG8_SB(b, h) + boff + n * 2048 + k * 1024); } while (0)
; #define PG8_MMA(ai, bj, At, Bt) do { __builtin_amdgcn_s_setprio(1); _Pragma("unroll") for (int m = 0; m < 4; ++m) _Pragma("unroll") for (int n = 0; n < 2; ++n) _Pragma("unroll") for (int k = 0; k < 2; ++k) \
;         acc[ai][bj][m][n] = __builtin_amdgcn_mfma_f32_16x16x32_bf16(Bt[n][k], At[m][k], acc[ai][bj][m][n], 0, 0, 0); __builtin_amdgcn_s_setprio(0); } while (0)
; #define PG8_BAR __builtin_amdgcn_s_barrier()
; template <class Epi, class Sched, bool ALIGN_EPI = false, bool SP2 = false>
; __device__ __forceinline__ void gemm_phase(PG8_LAS unsigned char* lds, const Gemm g, const Sched& S, const Epi& E, const int wave_in) {
;     ...
;             PG8_LDB(B0, 0, 0); PG8_LDB(B1, 0, 1); PG8_SCHED; PG8_LDA(At, 0, 0); PG8_STAGE(PG8_SA(1, 1), a1 + hstepA, voffA);
;             PG8_WAIT_V(8); PG8_WAIT_L(0); PG8_BAR; PG8_MMA(0, 0, At, B0); PG8_MMA(0, 1, At, B1); PG8_BAR; PG8_SCHED;
;             PG8_LDA(At, 0, 1); PG8_STAGE(PG8_SB(0, 0), b2, voffB); PG8_STAGE(PG8_SB(0, 1), b2 + hstepB, voffB); PG8_STAGE(PG8_SA(0, 0), a2, voffA);
;             PG8_WAIT_V(8); PG8_WAIT_L(0); PG8_BAR; PG8_MMA(1, 0, At, B0); PG8_MMA(1, 1, At, B1); PG8_BAR; PG8_SCHED;
;             PG8_LDB(B0, 1, 0); PG8_LDB(B1, 1, 1); PG8_SCHED; PG8_LDA(At, 1, 0); PG8_STAGE(PG8_SA(0, 1), a2 + hstepA, voffA);
;             PG8_WAIT_V(8); PG8_WAIT_L(0); PG8_BAR; PG8_MMA(0, 0, At, B0); PG8_MMA(0, 1, At, B1); PG8_BAR; PG8_SCHED;
;             PG8_LDA(At, 1, 1); PG8_STAGE(PG8_SB(1, 0), b3, voffB); PG8_STAGE(PG8_SB(1, 1), b3 + hstepB, voffB); PG8_STAGE(PG8_SA(1, 0), a3, voffA);
;             PG8_WAIT_V(8); PG8_WAIT_L(0); PG8_BAR; PG8_MMA(1, 0, At, B0); PG8_MMA(1, 1, At, B1); PG8_BAR; PG8_SCHED;
	s_add_i32 s18, s55, s30
	v_lshl_add_u64 v[210:211], v[210:211], 0, s[6:7]
	s_mov_b32 m0, s18
	ds_read_b128 v[178:181], v216 offset:49152
	ds_read_b128 v[182:185], v216 offset:50176
	ds_read_b128 v[186:189], v216 offset:51200
	ds_read_b128 v[190:193], v216 offset:52224
	ds_read_b128 v[194:197], v216 offset:53248
	ds_read_b128 v[198:201], v216 offset:54272
	ds_read_b128 v[202:205], v216 offset:55296
	ds_read_b128 v[206:209], v216 offset:56320
	global_load_lds_dwordx4 v[210:211], off
	s_add_i32 m0, s18, 0x2000
	s_add_u32 s18, s22, 0x158080
	v_lshl_add_u64 v[210:211], v[218:219], 0, s[6:7]
	s_addc_u32 s19, s23, 0
	s_add_i32 s22, s56, s30
	global_load_lds_dwordx4 v[210:211], off
	v_lshl_add_u64 v[210:211], s[18:19], 0, v[148:149]
	s_mov_b32 m0, s22
	s_nop 0
	global_load_lds_dwordx4 v[210:211], off
	v_lshl_add_u64 v[210:211], s[18:19], 0, v[144:145]
	s_add_i32 m0, s22, 0x2000
	s_nop 0
	global_load_lds_dwordx4 v[210:211], off
	v_lshl_add_u64 v[210:211], v[220:221], 0, s[6:7]
	s_mov_b32 m0, s42
	s_nop 0
	global_load_lds_dwordx4 v[210:211], off
	v_lshl_add_u64 v[210:211], v[222:223], 0, s[6:7]
	s_mov_b32 m0, s43
	s_nop 0
	global_load_lds_dwordx4 v[210:211], off
	s_waitcnt vmcnt(8)
	s_waitcnt lgkmcnt(0)
	s_barrier
	s_setprio 1
	v_mfma_f32_16x16x32_bf16 v[60:63], v[128:131], v[178:181], v[60:63]
	v_mfma_f32_16x16x32_bf16 v[56:59], v[136:139], v[178:181], v[56:59]
	v_mfma_f32_16x16x32_bf16 v[48:51], v[128:131], v[186:189], v[48:51]
	v_mfma_f32_16x16x32_bf16 v[40:43], v[136:139], v[186:189], v[40:43]
	v_mfma_f32_16x16x32_bf16 v[32:35], v[128:131], v[194:197], v[32:35]
	v_mfma_f32_16x16x32_bf16 v[24:27], v[136:139], v[194:197], v[24:27]
	v_mfma_f32_16x16x32_bf16 v[16:19], v[128:131], v[202:205], v[16:19]
	v_mfma_f32_16x16x32_bf16 v[8:11], v[136:139], v[202:205], v[8:11]
	v_mfma_f32_16x16x32_bf16 v[60:63], v[132:135], v[182:185], v[60:63]
	v_mfma_f32_16x16x32_bf16 v[56:59], v[140:143], v[182:185], v[56:59]
	v_mfma_f32_16x16x32_bf16 v[48:51], v[132:135], v[190:193], v[48:51]
	v_mfma_f32_16x16x32_bf16 v[40:43], v[140:143], v[190:193], v[40:43]
	v_mfma_f32_16x16x32_bf16 v[32:35], v[132:135], v[198:201], v[32:35]
	v_mfma_f32_16x16x32_bf16 v[24:27], v[140:143], v[198:201], v[24:27]
	v_mfma_f32_16x16x32_bf16 v[16:19], v[132:135], v[206:209], v[16:19]
	v_mfma_f32_16x16x32_bf16 v[8:11], v[140:143], v[206:209], v[8:11]
	v_mfma_f32_16x16x32_bf16 v[52:55], v[162:165], v[178:181], v[52:55]
	v_mfma_f32_16x16x32_bf16 v[44:47], v[170:173], v[178:181], v[44:47]
	v_mfma_f32_16x16x32_bf16 v[36:39], v[162:165], v[186:189], v[36:39]
	v_mfma_f32_16x16x32_bf16 v[28:31], v[170:173], v[186:189], v[28:31]
	v_mfma_f32_16x16x32_bf16 v[20:23], v[162:165], v[194:197], v[20:23]
	v_mfma_f32_16x16x32_bf16 v[12:15], v[170:173], v[194:197], v[12:15]
	v_mfma_f32_16x16x32_bf16 v[4:7], v[162:165], v[202:205], v[4:7]
	v_mfma_f32_16x16x32_bf16 v[0:3], v[170:173], v[202:205], v[0:3]
	v_mfma_f32_16x16x32_bf16 v[52:55], v[166:169], v[182:185], v[52:55]
	v_mfma_f32_16x16x32_bf16 v[44:47], v[174:177], v[182:185], v[44:47]
	v_mfma_f32_16x16x32_bf16 v[36:39], v[166:169], v[190:193], v[36:39]
	v_mfma_f32_16x16x32_bf16 v[28:31], v[174:177], v[190:193], v[28:31]
	v_mfma_f32_16x16x32_bf16 v[20:23], v[166:169], v[198:201], v[20:23]
	v_mfma_f32_16x16x32_bf16 v[12:15], v[174:177], v[198:201], v[12:15]
	v_mfma_f32_16x16x32_bf16 v[4:7], v[166:169], v[206:209], v[4:7]
	v_mfma_f32_16x16x32_bf16 v[0:3], v[174:177], v[206:209], v[0:3]
	s_setprio 0
	s_barrier
	s_add_i32 s54, s54, 2
	s_add_u32 s17, s17, 0x100
	s_addc_u32 s53, s53, 0
	s_cmpk_gt_u32 s54, 0x53
	s_mov_b64 s[18:19], s[20:21]
	s_cbranch_scc0 .LBB0_1375
	s_branch .Lkx_16
.LBB0_1375:
	ds_read_b128 v[128:131], v214
	ds_read_b128 v[132:135], v214 offset:1024
	ds_read_b128 v[136:139], v214 offset:2048
	ds_read_b128 v[140:143], v214 offset:3072
	ds_read_b128 v[162:165], v215
	ds_read_b128 v[166:169], v215 offset:1024
	ds_read_b128 v[170:173], v215 offset:2048
	ds_read_b128 v[174:177], v215 offset:3072
	s_add_u32 s20, s18, 0x100
	s_addc_u32 s21, s19, 0
	s_cmpk_eq_i32 s54, 0x52
	s_cselect_b32 s25, s5, s21
	s_cselect_b32 s24, s4, s20
	s_cselect_b32 s23, s15, s53
	s_cselect_b32 s22, s14, s17
	v_lshl_add_u64 v[210:211], s[18:19], 0, v[154:155]
	s_add_i32 m0, s35, 0xc000
	ds_read_b128 v[178:181], v216
	ds_read_b128 v[182:185], v216 offset:1024
	ds_read_b128 v[186:189], v216 offset:2048
	ds_read_b128 v[190:193], v216 offset:3072
	ds_read_b128 v[194:197], v216 offset:4096
	ds_read_b128 v[198:201], v216 offset:5120
	ds_read_b128 v[202:205], v216 offset:6144
	ds_read_b128 v[206:209], v216 offset:7168
	global_load_lds_dwordx4 v[210:211], off
	v_lshl_add_u64 v[210:211], s[18:19], 0, v[156:157]
	s_add_i32 m0, s35, 0xe000
	s_nop 0
	global_load_lds_dwordx4 v[210:211], off
	s_waitcnt vmcnt(8)
	s_waitcnt lgkmcnt(0)
	s_barrier
; #define PG8_STAGE(bufoff, gbase, voff) do { _Pragma("unroll") for (int _i = 0; _i < 2; ++_i) \
;         __builtin_amdgcn_global_load_lds((const unsigned*)((const char*)(gbase) + (voff)[_i]), (PG8_LAS unsigned*)(lds + (bufoff) + ldsw + _i * 8192), 16, 0, 0); } while (0)
; #define PG8_LDA(dst, b, h) do { _Pragma("unroll") for (int m = 0; m < 4; ++m) _Pragma("unroll") for (int k = 0; k < 2; ++k) dst[m][k] = *(const PG8_LAS bf16x8*)(lds + PG8_SA(b, h) + aoff + m * 2048 + k * 1024); } while (0)
; #define PG8_MMA(ai, bj, At, Bt) do { __builtin_amdgcn_s_setprio(1); _Pragma("unroll") for (int m = 0; m < 4; ++m) _Pragma("unroll") for (int n = 0; n < 2; ++n) _Pragma("unroll") for (int k = 0; k < 2; ++k) \
;         acc[ai][bj][m][n] = __builtin_amdgcn_mfma_f32_16x16x32_bf16(Bt[n][k], At[m][k], acc[ai][bj][m][n], 0, 0, 0); __builtin_amdgcn_s_setprio(0); } while (0)
; #define PG8_WAIT_V(n) asm volatile("s_waitcnt vmcnt(" #n ")" ::: "memory")
; #define PG8_WAIT_L(n) asm volatile("s_waitcnt lgkmcnt(" #n ")" ::: "memory")
; #define PG8_BAR __builtin_amdgcn_s_barrier()
; #define PG8_SCHED __builtin_amdgcn_sched_barrier(0)
; template <class Epi, class Sched, bool ALIGN_EPI = false, bool SP2 = false>
; __device__ __forceinline__ void gemm_phase(PG8_LAS unsigned char* lds, const Gemm g, const Sched& S, const Epi& E, const int wave_in) {
;     ...
;             PG8_WAIT_V(8); PG8_WAIT_L(0); PG8_BAR; PG8_MMA(0, 0, At, B0); PG8_MMA(0, 1, At, B1); PG8_BAR; PG8_SCHED;
;             PG8_LDA(At, 0, 1); PG8_STAGE(PG8_SB(0, 0), b2, voffB); PG8_STAGE(PG8_SB(0, 1), b2 + hstepB, voffB); PG8_STAGE(PG8_SA(0, 0), a2, voffA);
;             PG8_WAIT_V(8); PG8_WAIT_L(0); PG8_BAR; PG8_MMA(1, 0, At, B0); PG8_MMA(1, 1, At, B1); PG8_BAR; PG8_SCHED;
	s_setprio 1
	v_mfma_f32_16x16x32_bf16 v[124:127], v[128:131], v[178:181], v[124:127]
	v_mfma_f32_16x16x32_bf16 v[120:123], v[136:139], v[178:181], v[120:123]
	v_mfma_f32_16x16x32_bf16 v[112:115], v[128:131], v[186:189], v[112:115]
	v_mfma_f32_16x16x32_bf16 v[104:107], v[136:139], v[186:189], v[104:107]
	v_mfma_f32_16x16x32_bf16 v[100:103], v[128:131], v[194:197], v[100:103]
	v_mfma_f32_16x16x32_bf16 v[96:99], v[136:139], v[194:197], v[96:99]
	v_mfma_f32_16x16x32_bf16 v[76:79], v[128:131], v[202:205], v[76:79]
	v_mfma_f32_16x16x32_bf16 v[72:75], v[136:139], v[202:205], v[72:75]
	v_mfma_f32_16x16x32_bf16 v[124:127], v[132:135], v[182:185], v[124:127]
	v_mfma_f32_16x16x32_bf16 v[120:123], v[140:143], v[182:185], v[120:123]
	v_mfma_f32_16x16x32_bf16 v[112:115], v[132:135], v[190:193], v[112:115]
	v_mfma_f32_16x16x32_bf16 v[104:107], v[140:143], v[190:193], v[104:107]
	v_mfma_f32_16x16x32_bf16 v[100:103], v[132:135], v[198:201], v[100:103]
	v_mfma_f32_16x16x32_bf16 v[96:99], v[140:143], v[198:201], v[96:99]
	v_mfma_f32_16x16x32_bf16 v[76:79], v[132:135], v[206:209], v[76:79]
	v_mfma_f32_16x16x32_bf16 v[72:75], v[140:143], v[206:209], v[72:75]
	v_mfma_f32_16x16x32_bf16 v[116:119], v[162:165], v[178:181], v[116:119]
	v_mfma_f32_16x16x32_bf16 v[108:111], v[170:173], v[178:181], v[108:111]
	v_mfma_f32_16x16x32_bf16 v[92:95], v[162:165], v[186:189], v[92:95]
	v_mfma_f32_16x16x32_bf16 v[88:91], v[170:173], v[186:189], v[88:91]
	v_mfma_f32_16x16x32_bf16 v[84:87], v[162:165], v[194:197], v[84:87]
	v_mfma_f32_16x16x32_bf16 v[80:83], v[170:173], v[194:197], v[80:83]
	v_mfma_f32_16x16x32_bf16 v[68:71], v[162:165], v[202:205], v[68:71]
	v_mfma_f32_16x16x32_bf16 v[64:67], v[170:173], v[202:205], v[64:67]
	v_mfma_f32_16x16x32_bf16 v[116:119], v[166:169], v[182:185], v[116:119]
	v_mfma_f32_16x16x32_bf16 v[108:111], v[174:177], v[182:185], v[108:111]
	v_mfma_f32_16x16x32_bf16 v[92:95], v[166:169], v[190:193], v[92:95]
	v_mfma_f32_16x16x32_bf16 v[88:91], v[174:177], v[190:193], v[88:91]
	v_mfma_f32_16x16x32_bf16 v[84:87], v[166:169], v[198:201], v[84:87]
	v_mfma_f32_16x16x32_bf16 v[80:83], v[174:177], v[198:201], v[80:83]
	v_mfma_f32_16x16x32_bf16 v[68:71], v[166:169], v[206:209], v[68:71]
	v_mfma_f32_16x16x32_bf16 v[64:67], v[174:177], v[206:209], v[64:67]
	s_setprio 0
	s_barrier
	s_add_i32 s18, s45, s30
	v_lshl_add_u64 v[210:211], s[22:23], 0, v[148:149]
	s_mov_b32 m0, s18
	ds_read_b128 v[178:181], v216 offset:16384
	ds_read_b128 v[182:185], v216 offset:17408
	ds_read_b128 v[186:189], v216 offset:18432
	ds_read_b128 v[190:193], v216 offset:19456
	ds_read_b128 v[194:197], v216 offset:20480
	ds_read_b128 v[198:201], v216 offset:21504
	ds_read_b128 v[202:205], v216 offset:22528
	ds_read_b128 v[206:209], v216 offset:23552
	global_load_lds_dwordx4 v[210:211], off
	s_add_i32 m0, s18, 0x2000
	s_add_u32 s18, s22, 0x158000
	v_lshl_add_u64 v[218:219], s[22:23], 0, v[144:145]
	s_addc_u32 s19, s23, 0
	s_add_i32 s55, s46, s30
	global_load_lds_dwordx4 v[218:219], off
	v_lshl_add_u64 v[220:221], s[18:19], 0, v[148:149]
	s_mov_b32 m0, s55
	v_lshl_add_u64 v[222:223], s[24:25], 0, v[146:147]
	global_load_lds_dwordx4 v[220:221], off
	v_lshl_add_u64 v[220:221], s[18:19], 0, v[144:145]
	s_add_i32 m0, s55, 0x2000
	s_nop 0
	global_load_lds_dwordx4 v[220:221], off
	v_lshl_add_u64 v[220:221], s[24:25], 0, v[150:151]
	s_mov_b32 m0, s35
	s_nop 0
	global_load_lds_dwordx4 v[220:221], off
	s_mov_b32 m0, s36
	s_nop 0
	global_load_lds_dwordx4 v[222:223], off
	s_waitcnt vmcnt(8)
	s_waitcnt lgkmcnt(0)
	s_barrier
	s_setprio 1
	v_mfma_f32_16x16x32_bf16 v[60:63], v[128:131], v[178:181], v[60:63]
	v_mfma_f32_16x16x32_bf16 v[56:59], v[136:139], v[178:181], v[56:59]
	v_mfma_f32_16x16x32_bf16 v[48:51], v[128:131], v[186:189], v[48:51]
	v_mfma_f32_16x16x32_bf16 v[40:43], v[136:139], v[186:189], v[40:43]
	v_mfma_f32_16x16x32_bf16 v[32:35], v[128:131], v[194:197], v[32:35]
	v_mfma_f32_16x16x32_bf16 v[24:27], v[136:139], v[194:197], v[24:27]
	v_mfma_f32_16x16x32_bf16 v[16:19], v[128:131], v[202:205], v[16:19]
	v_mfma_f32_16x16x32_bf16 v[8:11], v[136:139], v[202:205], v[8:11]
	v_mfma_f32_16x16x32_bf16 v[60:63], v[132:135], v[182:185], v[60:63]
	v_mfma_f32_16x16x32_bf16 v[56:59], v[140:143], v[182:185], v[56:59]
	v_mfma_f32_16x16x32_bf16 v[48:51], v[132:135], v[190:193], v[48:51]
	v_mfma_f32_16x16x32_bf16 v[40:43], v[140:143], v[190:193], v[40:43]
	v_mfma_f32_16x16x32_bf16 v[32:35], v[132:135], v[198:201], v[32:35]
	v_mfma_f32_16x16x32_bf16 v[24:27], v[140:143], v[198:201], v[24:27]
	v_mfma_f32_16x16x32_bf16 v[16:19], v[132:135], v[206:209], v[16:19]
	v_mfma_f32_16x16x32_bf16 v[8:11], v[140:143], v[206:209], v[8:11]
	v_mfma_f32_16x16x32_bf16 v[52:55], v[162:165], v[178:181], v[52:55]
	v_mfma_f32_16x16x32_bf16 v[44:47], v[170:173], v[178:181], v[44:47]
	v_mfma_f32_16x16x32_bf16 v[36:39], v[162:165], v[186:189], v[36:39]
	v_mfma_f32_16x16x32_bf16 v[28:31], v[170:173], v[186:189], v[28:31]
	v_mfma_f32_16x16x32_bf16 v[20:23], v[162:165], v[194:197], v[20:23]
	v_mfma_f32_16x16x32_bf16 v[12:15], v[170:173], v[194:197], v[12:15]
	v_mfma_f32_16x16x32_bf16 v[4:7], v[162:165], v[202:205], v[4:7]
	v_mfma_f32_16x16x32_bf16 v[0:3], v[170:173], v[202:205], v[0:3]
	v_mfma_f32_16x16x32_bf16 v[52:55], v[166:169], v[182:185], v[52:55]
	v_mfma_f32_16x16x32_bf16 v[44:47], v[174:177], v[182:185], v[44:47]
	v_mfma_f32_16x16x32_bf16 v[36:39], v[166:169], v[190:193], v[36:39]
	v_mfma_f32_16x16x32_bf16 v[28:31], v[174:177], v[190:193], v[28:31]
	v_mfma_f32_16x16x32_bf16 v[20:23], v[166:169], v[198:201], v[20:23]
	v_mfma_f32_16x16x32_bf16 v[12:15], v[174:177], v[198:201], v[12:15]
	v_mfma_f32_16x16x32_bf16 v[4:7], v[166:169], v[206:209], v[4:7]
	v_mfma_f32_16x16x32_bf16 v[0:3], v[174:177], v[206:209], v[0:3]
	s_setprio 0
	s_barrier
; #define PG8_STAGE(bufoff, gbase, voff) do { _Pragma("unroll") for (int _i = 0; _i < 2; ++_i) \
;         __builtin_amdgcn_global_load_lds((const unsigned*)((const char*)(gbase) + (voff)[_i]), (PG8_LAS unsigned*)(lds + (bufoff) + ldsw + _i * 8192), 16, 0, 0); } while (0)
; #define PG8_LDA(dst, b, h) do { _Pragma("unroll") for (int m = 0; m < 4; ++m) _Pragma("unroll") for (int k = 0; k < 2; ++k) dst[m][k] = *(const PG8_LAS bf16x8*)(lds + PG8_SA(b, h) + aoff + m * 2048 + k * 1024); } while (0)
; #define PG8_LDB(dst, b, h) do { _Pragma("unroll") for (int n = 0; n < 2; ++n) _Pragma("unroll") for (int k = 0; k < 2; ++k) dst[n][k] = *(const PG8_LAS bf16x8*)(lds + PG8_SB(b, h) + boff + n * 2048 + k * 1024); } while (0)
; #define PG8_MMA(ai, bj, At, Bt) do { __builtin_amdgcn_s_setprio(1); _Pragma("unroll") for (int m = 0; m < 4; ++m) _Pragma("unroll") for (int n = 0; n < 2; ++n) _Pragma("unroll") for (int k = 0; k < 2; ++k) \
;         acc[ai][bj][m][n] = __builtin_amdgcn_mfma_f32_16x16x32_bf16(Bt[n][k], At[m][k], acc[ai][bj][m][n], 0, 0, 0); __builtin_amdgcn_s_setprio(0); } while (0)
; #define PG8_WAIT_V(n) asm volatile("s_waitcnt vmcnt(" #n ")" ::: "memory")
; #define PG8_WAIT_L(n) asm volatile("s_waitcnt lgkmcnt(" #n ")" ::: "memory")
; #define PG8_BAR __builtin_amdgcn_s_barrier()
; #define PG8_SCHED __builtin_amdgcn_sched_barrier(0)
; template <class Epi, class Sched, bool ALIGN_EPI = false, bool SP2 = false>
; __device__ __forceinline__ void gemm_phase(PG8_LAS unsigned char* lds, const Gemm g, const Sched& S, const Epi& E, const int wave_in) {
;     ...
;             PG8_LDB(B0, 1, 0); PG8_LDB(B1, 1, 1); PG8_SCHED; PG8_LDA(At, 1, 0); PG8_STAGE(PG8_SA(0, 1), a2 + hstepA, voffA);
;             PG8_WAIT_V(8); PG8_WAIT_L(0); PG8_BAR; PG8_MMA(0, 0, At, B0); PG8_MMA(0, 1, At, B1); PG8_BAR; PG8_SCHED;
;             PG8_LDA(At, 1, 1); PG8_STAGE(PG8_SB(1, 0), b3, voffB); PG8_STAGE(PG8_SB(1, 1), b3 + hstepB, voffB); PG8_STAGE(PG8_SA(1, 0), a3, voffA);
;             PG8_WAIT_V(8); PG8_WAIT_L(0); PG8_BAR; PG8_MMA(1, 0, At, B0); PG8_MMA(1, 1, At, B1); PG8_BAR; PG8_SCHED;
	s_add_i32 s55, 0, 0x18000
	s_add_i32 s56, 0, 0x1c000
	v_add_u32_e32 v140, s55, v212
	v_add_u32_e32 v174, s56, v212
	ds_read_b128 v[128:131], v140
	ds_read_b128 v[132:135], v140 offset:1024
	ds_read_b128 v[136:139], v140 offset:2048
	ds_read_b128 v[140:143], v140 offset:3072
	ds_read_b128 v[162:165], v174
	ds_read_b128 v[166:169], v174 offset:1024
	ds_read_b128 v[170:173], v174 offset:2048
	ds_read_b128 v[174:177], v174 offset:3072
	s_add_u32 s18, s24, 0x158000
	s_addc_u32 s19, s25, 0
	s_mov_b32 m0, s37
	v_lshl_add_u64 v[224:225], s[18:19], 0, v[150:151]
	ds_read_b128 v[178:181], v216 offset:32768
	ds_read_b128 v[182:185], v216 offset:33792
	ds_read_b128 v[186:189], v216 offset:34816
	ds_read_b128 v[190:193], v216 offset:35840
	ds_read_b128 v[194:197], v216 offset:36864
	ds_read_b128 v[198:201], v216 offset:37888
	ds_read_b128 v[202:205], v216 offset:38912
	ds_read_b128 v[206:209], v216 offset:39936
	global_load_lds_dwordx4 v[224:225], off
	v_lshl_add_u64 v[224:225], s[18:19], 0, v[146:147]
	s_mov_b32 m0, s38
	s_nop 0
	global_load_lds_dwordx4 v[224:225], off
	s_waitcnt vmcnt(8)
	s_waitcnt lgkmcnt(0)
	s_barrier
	s_setprio 1
	v_mfma_f32_16x16x32_bf16 v[124:127], v[128:131], v[178:181], v[124:127]
	v_mfma_f32_16x16x32_bf16 v[120:123], v[136:139], v[178:181], v[120:123]
	v_mfma_f32_16x16x32_bf16 v[112:115], v[128:131], v[186:189], v[112:115]
	v_mfma_f32_16x16x32_bf16 v[104:107], v[136:139], v[186:189], v[104:107]
	v_mfma_f32_16x16x32_bf16 v[100:103], v[128:131], v[194:197], v[100:103]
	v_mfma_f32_16x16x32_bf16 v[96:99], v[136:139], v[194:197], v[96:99]
	v_mfma_f32_16x16x32_bf16 v[76:79], v[128:131], v[202:205], v[76:79]
	v_mfma_f32_16x16x32_bf16 v[72:75], v[136:139], v[202:205], v[72:75]
	v_mfma_f32_16x16x32_bf16 v[124:127], v[132:135], v[182:185], v[124:127]
	v_mfma_f32_16x16x32_bf16 v[120:123], v[140:143], v[182:185], v[120:123]
	v_mfma_f32_16x16x32_bf16 v[112:115], v[132:135], v[190:193], v[112:115]
	v_mfma_f32_16x16x32_bf16 v[104:107], v[140:143], v[190:193], v[104:107]
	v_mfma_f32_16x16x32_bf16 v[100:103], v[132:135], v[198:201], v[100:103]
	v_mfma_f32_16x16x32_bf16 v[96:99], v[140:143], v[198:201], v[96:99]
	v_mfma_f32_16x16x32_bf16 v[76:79], v[132:135], v[206:209], v[76:79]
	v_mfma_f32_16x16x32_bf16 v[72:75], v[140:143], v[206:209], v[72:75]
	v_mfma_f32_16x16x32_bf16 v[116:119], v[162:165], v[178:181], v[116:119]
	v_mfma_f32_16x16x32_bf16 v[108:111], v[170:173], v[178:181], v[108:111]
	v_mfma_f32_16x16x32_bf16 v[92:95], v[162:165], v[186:189], v[92:95]
	v_mfma_f32_16x16x32_bf16 v[88:91], v[170:173], v[186:189], v[88:91]
	v_mfma_f32_16x16x32_bf16 v[84:87], v[162:165], v[194:197], v[84:87]
	v_mfma_f32_16x16x32_bf16 v[80:83], v[170:173], v[194:197], v[80:83]
	v_mfma_f32_16x16x32_bf16 v[68:71], v[162:165], v[202:205], v[68:71]
	v_mfma_f32_16x16x32_bf16 v[64:67], v[170:173], v[202:205], v[64:67]
	v_mfma_f32_16x16x32_bf16 v[116:119], v[166:169], v[182:185], v[116:119]
	v_mfma_f32_16x16x32_bf16 v[108:111], v[174:177], v[182:185], v[108:111]
	v_mfma_f32_16x16x32_bf16 v[92:95], v[166:169], v[190:193], v[92:95]
	v_mfma_f32_16x16x32_bf16 v[88:91], v[174:177], v[190:193], v[88:91]
	v_mfma_f32_16x16x32_bf16 v[84:87], v[166:169], v[198:201], v[84:87]
	v_mfma_f32_16x16x32_bf16 v[80:83], v[174:177], v[198:201], v[80:83]
	v_mfma_f32_16x16x32_bf16 v[68:71], v[166:169], v[206:209], v[68:71]
	v_mfma_f32_16x16x32_bf16 v[64:67], v[174:177], v[206:209], v[64:67]
	s_setprio 0
	s_barrier
	s_add_i32 s18, s55, s30
	v_lshl_add_u64 v[210:211], v[210:211], 0, s[6:7]
	s_mov_b32 m0, s18
	ds_read_b128 v[178:181], v216 offset:49152
	ds_read_b128 v[182:185], v216 offset:50176
	ds_read_b128 v[186:189], v216 offset:51200
	ds_read_b128 v[190:193], v216 offset:52224
	ds_read_b128 v[194:197], v216 offset:53248
	ds_read_b128 v[198:201], v216 offset:54272
	ds_read_b128 v[202:205], v216 offset:55296
	ds_read_b128 v[206:209], v216 offset:56320
	global_load_lds_dwordx4 v[210:211], off
	s_add_i32 m0, s18, 0x2000
	s_add_u32 s18, s22, 0x158080
	v_lshl_add_u64 v[210:211], v[218:219], 0, s[6:7]
	s_addc_u32 s19, s23, 0
	s_add_i32 s22, s56, s30
	global_load_lds_dwordx4 v[210:211], off
	v_lshl_add_u64 v[210:211], s[18:19], 0, v[148:149]
	s_mov_b32 m0, s22
	s_nop 0
	global_load_lds_dwordx4 v[210:211], off
	v_lshl_add_u64 v[210:211], s[18:19], 0, v[144:145]
	s_add_i32 m0, s22, 0x2000
	s_nop 0
	global_load_lds_dwordx4 v[210:211], off
	v_lshl_add_u64 v[210:211], v[220:221], 0, s[6:7]
	s_mov_b32 m0, s42
	s_nop 0
	global_load_lds_dwordx4 v[210:211], off
	v_lshl_add_u64 v[210:211], v[222:223], 0, s[6:7]
	s_mov_b32 m0, s43
	s_nop 0
	global_load_lds_dwordx4 v[210:211], off
	s_waitcnt vmcnt(8)
	s_waitcnt lgkmcnt(0)
	s_barrier
	s_setprio 1
	v_mfma_f32_16x16x32_bf16 v[60:63], v[128:131], v[178:181], v[60:63]
	v_mfma_f32_16x16x32_bf16 v[56:59], v[136:139], v[178:181], v[56:59]
	v_mfma_f32_16x16x32_bf16 v[48:51], v[128:131], v[186:189], v[48:51]
	v_mfma_f32_16x16x32_bf16 v[40:43], v[136:139], v[186:189], v[40:43]
	v_mfma_f32_16x16x32_bf16 v[32:35], v[128:131], v[194:197], v[32:35]
	v_mfma_f32_16x16x32_bf16 v[24:27], v[136:139], v[194:197], v[24:27]
	v_mfma_f32_16x16x32_bf16 v[16:19], v[128:131], v[202:205], v[16:19]
	v_mfma_f32_16x16x32_bf16 v[8:11], v[136:139], v[202:205], v[8:11]
	v_mfma_f32_16x16x32_bf16 v[60:63], v[132:135], v[182:185], v[60:63]
	v_mfma_f32_16x16x32_bf16 v[56:59], v[140:143], v[182:185], v[56:59]
	v_mfma_f32_16x16x32_bf16 v[48:51], v[132:135], v[190:193], v[48:51]
	v_mfma_f32_16x16x32_bf16 v[40:43], v[140:143], v[190:193], v[40:43]
	v_mfma_f32_16x16x32_bf16 v[32:35], v[132:135], v[198:201], v[32:35]
	v_mfma_f32_16x16x32_bf16 v[24:27], v[140:143], v[198:201], v[24:27]
	v_mfma_f32_16x16x32_bf16 v[16:19], v[132:135], v[206:209], v[16:19]
	v_mfma_f32_16x16x32_bf16 v[8:11], v[140:143], v[206:209], v[8:11]
	v_mfma_f32_16x16x32_bf16 v[52:55], v[162:165], v[178:181], v[52:55]
	v_mfma_f32_16x16x32_bf16 v[44:47], v[170:173], v[178:181], v[44:47]
	v_mfma_f32_16x16x32_bf16 v[36:39], v[162:165], v[186:189], v[36:39]
	v_mfma_f32_16x16x32_bf16 v[28:31], v[170:173], v[186:189], v[28:31]
	v_mfma_f32_16x16x32_bf16 v[20:23], v[162:165], v[194:197], v[20:23]
	v_mfma_f32_16x16x32_bf16 v[12:15], v[170:173], v[194:197], v[12:15]
	v_mfma_f32_16x16x32_bf16 v[4:7], v[162:165], v[202:205], v[4:7]
	v_mfma_f32_16x16x32_bf16 v[0:3], v[170:173], v[202:205], v[0:3]
	v_mfma_f32_16x16x32_bf16 v[52:55], v[166:169], v[182:185], v[52:55]
	v_mfma_f32_16x16x32_bf16 v[44:47], v[174:177], v[182:185], v[44:47]
	v_mfma_f32_16x16x32_bf16 v[36:39], v[166:169], v[190:193], v[36:39]
	v_mfma_f32_16x16x32_bf16 v[28:31], v[174:177], v[190:193], v[28:31]
	v_mfma_f32_16x16x32_bf16 v[20:23], v[166:169], v[198:201], v[20:23]
	v_mfma_f32_16x16x32_bf16 v[12:15], v[174:177], v[198:201], v[12:15]
	v_mfma_f32_16x16x32_bf16 v[4:7], v[166:169], v[206:209], v[4:7]
	v_mfma_f32_16x16x32_bf16 v[0:3], v[174:177], v[206:209], v[0:3]
	s_setprio 0
	s_barrier
	s_add_i32 s54, s54, 2
	s_add_u32 s17, s17, 0x100
	s_addc_u32 s53, s53, 0
	s_cmpk_gt_u32 s54, 0x53
	s_mov_b64 s[18:19], s[20:21]
	s_cbranch_scc0 .LBB0_1375

;     __host__ __device__ bool next(int i, Unit& u) const { const bool ok = StaticOrder::next(i, u); u.pm = 0; u.pn = 0; return ok; }
; #define PG8_STAGE(bufoff, gbase, voff) do { _Pragma("unroll") for (int _i = 0; _i < 2; ++_i) \
;         __builtin_amdgcn_global_load_lds((const unsigned*)((const char*)(gbase) + (voff)[_i]), (PG8_LAS unsigned*)(lds + (bufoff) + ldsw + _i * 8192), 16, 0, 0); } while (0)
; #define PG8_LDA(dst, b, h) do { _Pragma("unroll") for (int m = 0; m < 4; ++m) _Pragma("unroll") for (int k = 0; k < 2; ++k) dst[m][k] = *(const PG8_LAS bf16x8*)(lds + PG8_SA(b, h) + aoff + m * 2048 + k * 1024); } while (0)
; #define PG8_LDB(dst, b, h) do { _Pragma("unroll") for (int n = 0; n < 2; ++n) _Pragma("unroll") for (int k = 0; k < 2; ++k) dst[n][k] = *(const PG8_LAS bf16x8*)(lds + PG8_SB(b, h) + boff + n * 2048 + k * 1024); } while (0)
; #define PG8_WAIT_V(n) asm volatile("s_waitcnt vmcnt(" #n ")" ::: "memory")
; #define PG8_BAR __builtin_amdgcn_s_barrier()
; template <class Epi, class Sched, bool ALIGN_EPI = false, bool SP2 = false>
; __device__ __forceinline__ void gemm_phase(PG8_LAS unsigned char* lds, const Gemm g, const Sched& S, const Epi& E, const int wave_in) {
;     ...
;         const bool has_next = S.next(ui + 1, nxt);
;         const char* nA = has_next ? (const char*)g.A + (size_t)nxt.pm * tstepA : cA; const char* nB = has_next ? (const char*)g.Bt + (size_t)nxt.pn * tstepB : cB;
;         for (int t = 0; t < nt; t += 2) {
;             const bool last = (t == nt - 2);
;             const char* a1 = cA + (size_t)(t + 1) * kstep;
;             const char* a2 = last ? nA : cA + (size_t)(t + 2) * kstep; const char* b2 = last ? nB : cB + (size_t)(t + 2) * kstep;
;             const char* a3 = a2 + kstep; const char* b3 = b2 + kstep;
;             if (last && has_next) S.a_ready(nxt);
;             if constexpr (SP2) {
;             PG8_LDB(B0, 0, 0); PG8_LDB(B1, 0, 1); PG8_SCHED; PG8_LDA(At, 0, 0); PG8_STAGE(PG8_SA(1, 1), a1 + hstepA, voffA);
;             PG8_WAIT_V(8); PG8_WAIT_L(0); PG8_BAR; PG8_MMA(0, 0, At, B0); PG8_MMA(0, 1, At, B1); PG8_BAR; PG8_SCHED;
;             PG8_LDA(At, 0, 1); PG8_STAGE(PG8_SB(0, 0), b2, voffB); PG8_STAGE(PG8_SB(0, 1), b2 + hstepB, voffB); PG8_STAGE(PG8_SA(0, 0), a2, voffA);
;             PG8_WAIT_V(8); PG8_WAIT_L(0); PG8_BAR; PG8_MMA(1, 0, At, B0); PG8_MMA(1, 1, At, B1); PG8_BAR; PG8_SCHED;
.LBB0_1512:
	s_ashr_i32 s13, s12, 31
	s_lshl_b64 s[14:15], s[12:13], 20
	s_add_u32 s14, s26, s14
	s_addc_u32 s15, s27, s15
	s_and_b64 s[16:17], s[2:3], exec
	s_cselect_b32 s13, s15, s21
	s_cselect_b32 s46, s14, s20
	s_ashr_i32 s11, s10, 31
	s_lshl_b64 s[16:17], s[10:11], 20
	s_add_u32 s16, s28, s16
	s_addc_u32 s17, s29, s17
	s_and_b64 s[24:25], s[2:3], exec
	s_cselect_b32 s11, s17, s23
	s_cselect_b32 s47, s16, s22
	s_add_u32 s20, s20, 0x80080
	s_addc_u32 s21, s21, 0
	s_add_u32 s48, s22, 0x100
	v_mov_b32_e32 v0, 0
	s_addc_u32 s49, s23, 0
	s_mov_b32 s50, -2
	ds_read_b128 v[144:147], v151
	ds_read_b128 v[154:157], v151 offset:1024
	ds_read_b128 v[158:161], v151 offset:2048
	ds_read_b128 v[162:165], v151 offset:3072
	ds_read_b128 v[166:169], v152
	ds_read_b128 v[170:173], v152 offset:1024
	ds_read_b128 v[174:177], v152 offset:2048
	ds_read_b128 v[178:181], v152 offset:3072
	s_add_u32 s22, s20, 0xfff80080
	s_addc_u32 s23, s21, -1
	s_cmp_eq_u32 s50, 28
	s_cselect_b32 s25, s13, s23
	s_cselect_b32 s24, s46, s22
	s_cselect_b32 s23, s11, s49
	s_cselect_b32 s22, s47, s48
	v_lshl_add_u64 v[214:215], s[20:21], 0, v[136:137]
	s_add_i32 m0, s19, 0xc000
	ds_read_b128 v[182:185], v153
	ds_read_b128 v[186:189], v153 offset:1024
	ds_read_b128 v[190:193], v153 offset:2048
	ds_read_b128 v[194:197], v153 offset:3072
	ds_read_b128 v[198:201], v153 offset:4096
	ds_read_b128 v[202:205], v153 offset:5120
	ds_read_b128 v[206:209], v153 offset:6144
	ds_read_b128 v[210:213], v153 offset:7168
	global_load_lds_dwordx4 v[214:215], off
	v_lshl_add_u64 v[214:215], s[20:21], 0, v[138:139]
	s_add_i32 m0, s19, 0xe000
	s_nop 0
	global_load_lds_dwordx4 v[214:215], off
	s_waitcnt vmcnt(8)
	s_waitcnt lgkmcnt(0)
	s_barrier
	s_setprio 1
	v_mfma_f32_16x16x32_bf16 v[124:127], v[144:147], v[182:185], 0
	v_mfma_f32_16x16x32_bf16 v[120:123], v[158:161], v[182:185], 0
	v_mfma_f32_16x16x32_bf16 v[116:119], v[144:147], v[190:193], 0
	v_mfma_f32_16x16x32_bf16 v[108:111], v[158:161], v[190:193], 0
	v_mfma_f32_16x16x32_bf16 v[100:103], v[144:147], v[198:201], 0
	v_mfma_f32_16x16x32_bf16 v[92:95], v[158:161], v[198:201], 0
	v_mfma_f32_16x16x32_bf16 v[84:87], v[144:147], v[206:209], 0
	v_mfma_f32_16x16x32_bf16 v[76:79], v[158:161], v[206:209], 0
	v_mfma_f32_16x16x32_bf16 v[124:127], v[154:157], v[186:189], v[124:127]
	v_mfma_f32_16x16x32_bf16 v[120:123], v[162:165], v[186:189], v[120:123]
	v_mfma_f32_16x16x32_bf16 v[116:119], v[154:157], v[194:197], v[116:119]
	v_mfma_f32_16x16x32_bf16 v[108:111], v[162:165], v[194:197], v[108:111]
	v_mfma_f32_16x16x32_bf16 v[100:103], v[154:157], v[202:205], v[100:103]
	v_mfma_f32_16x16x32_bf16 v[92:95], v[162:165], v[202:205], v[92:95]
	v_mfma_f32_16x16x32_bf16 v[84:87], v[154:157], v[210:213], v[84:87]
	v_mfma_f32_16x16x32_bf16 v[76:79], v[162:165], v[210:213], v[76:79]
	v_mfma_f32_16x16x32_bf16 v[112:115], v[166:169], v[182:185], 0
	v_mfma_f32_16x16x32_bf16 v[104:107], v[174:177], v[182:185], 0
	v_mfma_f32_16x16x32_bf16 v[96:99], v[166:169], v[190:193], 0
	v_mfma_f32_16x16x32_bf16 v[88:91], v[174:177], v[190:193], 0
	v_mfma_f32_16x16x32_bf16 v[80:83], v[166:169], v[198:201], 0
	v_mfma_f32_16x16x32_bf16 v[72:75], v[174:177], v[198:201], 0
	v_mfma_f32_16x16x32_bf16 v[68:71], v[166:169], v[206:209], 0
	v_mfma_f32_16x16x32_bf16 v[64:67], v[174:177], v[206:209], 0
	v_mfma_f32_16x16x32_bf16 v[112:115], v[170:173], v[186:189], v[112:115]
	v_mfma_f32_16x16x32_bf16 v[104:107], v[178:181], v[186:189], v[104:107]
	v_mfma_f32_16x16x32_bf16 v[96:99], v[170:173], v[194:197], v[96:99]
	v_mfma_f32_16x16x32_bf16 v[88:91], v[178:181], v[194:197], v[88:91]
	v_mfma_f32_16x16x32_bf16 v[80:83], v[170:173], v[202:205], v[80:83]
	v_mfma_f32_16x16x32_bf16 v[72:75], v[178:181], v[202:205], v[72:75]
	v_mfma_f32_16x16x32_bf16 v[68:71], v[170:173], v[210:213], v[68:71]
	v_mfma_f32_16x16x32_bf16 v[64:67], v[178:181], v[210:213], v[64:67]
	s_setprio 0
	s_barrier
	s_add_i32 s51, s42, s30
	v_lshl_add_u64 v[214:215], s[22:23], 0, v[132:133]
	s_mov_b32 m0, s51
	ds_read_b128 v[182:185], v153 offset:16384
	ds_read_b128 v[186:189], v153 offset:17408
	ds_read_b128 v[190:193], v153 offset:18432
	ds_read_b128 v[194:197], v153 offset:19456
	ds_read_b128 v[198:201], v153 offset:20480
	ds_read_b128 v[202:205], v153 offset:21504
	ds_read_b128 v[206:209], v153 offset:22528
	ds_read_b128 v[210:213], v153 offset:23552
	global_load_lds_dwordx4 v[214:215], off
	s_add_i32 m0, s51, 0x2000
	s_add_u32 s52, s22, 0x80000
	v_lshl_add_u64 v[216:217], s[22:23], 0, v[128:129]
	s_addc_u32 s53, s23, 0
	s_add_i32 s51, s43, s30
	global_load_lds_dwordx4 v[216:217], off
	v_lshl_add_u64 v[218:219], s[52:53], 0, v[132:133]
	s_mov_b32 m0, s51
	v_lshl_add_u64 v[220:221], s[24:25], 0, v[130:131]
	global_load_lds_dwordx4 v[218:219], off
	v_lshl_add_u64 v[218:219], s[52:53], 0, v[128:129]
	s_add_i32 m0, s51, 0x2000
	s_nop 0
	global_load_lds_dwordx4 v[218:219], off
	v_lshl_add_u64 v[218:219], s[24:25], 0, v[134:135]
	s_mov_b32 m0, s19
	s_nop 0
	global_load_lds_dwordx4 v[218:219], off
	s_mov_b32 m0, s35
	s_nop 0
	global_load_lds_dwordx4 v[220:221], off
	s_waitcnt vmcnt(8)
	s_waitcnt lgkmcnt(0)
	s_barrier
; #define PG8_STAGE(bufoff, gbase, voff) do { _Pragma("unroll") for (int _i = 0; _i < 2; ++_i) \
;         __builtin_amdgcn_global_load_lds((const unsigned*)((const char*)(gbase) + (voff)[_i]), (PG8_LAS unsigned*)(lds + (bufoff) + ldsw + _i * 8192), 16, 0, 0); } while (0)
; #define PG8_LDA(dst, b, h) do { _Pragma("unroll") for (int m = 0; m < 4; ++m) _Pragma("unroll") for (int k = 0; k < 2; ++k) dst[m][k] = *(const PG8_LAS bf16x8*)(lds + PG8_SA(b, h) + aoff + m * 2048 + k * 1024); } while (0)
; #define PG8_LDB(dst, b, h) do { _Pragma("unroll") for (int n = 0; n < 2; ++n) _Pragma("unroll") for (int k = 0; k < 2; ++k) dst[n][k] = *(const PG8_LAS bf16x8*)(lds + PG8_SB(b, h) + boff + n * 2048 + k * 1024); } while (0)
; #define PG8_MMA(ai, bj, At, Bt) do { __builtin_amdgcn_s_setprio(1); _Pragma("unroll") for (int m = 0; m < 4; ++m) _Pragma("unroll") for (int n = 0; n < 2; ++n) _Pragma("unroll") for (int k = 0; k < 2; ++k) \
;         acc[ai][bj][m][n] = __builtin_amdgcn_mfma_f32_16x16x32_bf16(Bt[n][k], At[m][k], acc[ai][bj][m][n], 0, 0, 0); __builtin_amdgcn_s_setprio(0); } while (0)
; #define PG8_WAIT_V(n) asm volatile("s_waitcnt vmcnt(" #n ")" ::: "memory")
; #define PG8_WAIT_L(n) asm volatile("s_waitcnt lgkmcnt(" #n ")" ::: "memory")
; #define PG8_BAR __builtin_amdgcn_s_barrier()
; #define PG8_SCHED __builtin_amdgcn_sched_barrier(0)
; template <class Epi, class Sched, bool ALIGN_EPI = false, bool SP2 = false>
; __device__ __forceinline__ void gemm_phase(PG8_LAS unsigned char* lds, const Gemm g, const Sched& S, const Epi& E, const int wave_in) {
;     ...
;             PG8_WAIT_V(8); PG8_WAIT_L(0); PG8_BAR; PG8_MMA(1, 0, At, B0); PG8_MMA(1, 1, At, B1); PG8_BAR; PG8_SCHED;
;             PG8_LDB(B0, 1, 0); PG8_LDB(B1, 1, 1); PG8_SCHED; PG8_LDA(At, 1, 0); PG8_STAGE(PG8_SA(0, 1), a2 + hstepA, voffA);
;             PG8_WAIT_V(8); PG8_WAIT_L(0); PG8_BAR; PG8_MMA(0, 0, At, B0); PG8_MMA(0, 1, At, B1); PG8_BAR; PG8_SCHED;
	s_setprio 1
	v_mfma_f32_16x16x32_bf16 v[60:63], v[144:147], v[182:185], 0
	v_mfma_f32_16x16x32_bf16 v[56:59], v[158:161], v[182:185], 0
	v_mfma_f32_16x16x32_bf16 v[52:55], v[144:147], v[190:193], 0
	v_mfma_f32_16x16x32_bf16 v[44:47], v[158:161], v[190:193], 0
	v_mfma_f32_16x16x32_bf16 v[36:39], v[144:147], v[198:201], 0
	v_mfma_f32_16x16x32_bf16 v[28:31], v[158:161], v[198:201], 0
	v_mfma_f32_16x16x32_bf16 v[20:23], v[144:147], v[206:209], 0
	v_mfma_f32_16x16x32_bf16 v[12:15], v[158:161], v[206:209], 0
	v_mfma_f32_16x16x32_bf16 v[60:63], v[154:157], v[186:189], v[60:63]
	v_mfma_f32_16x16x32_bf16 v[56:59], v[162:165], v[186:189], v[56:59]
	v_mfma_f32_16x16x32_bf16 v[52:55], v[154:157], v[194:197], v[52:55]
	v_mfma_f32_16x16x32_bf16 v[44:47], v[162:165], v[194:197], v[44:47]
	v_mfma_f32_16x16x32_bf16 v[36:39], v[154:157], v[202:205], v[36:39]
	v_mfma_f32_16x16x32_bf16 v[28:31], v[162:165], v[202:205], v[28:31]
	v_mfma_f32_16x16x32_bf16 v[20:23], v[154:157], v[210:213], v[20:23]
	v_mfma_f32_16x16x32_bf16 v[12:15], v[162:165], v[210:213], v[12:15]
	v_mfma_f32_16x16x32_bf16 v[48:51], v[166:169], v[182:185], 0
	v_mfma_f32_16x16x32_bf16 v[40:43], v[174:177], v[182:185], 0
	v_mfma_f32_16x16x32_bf16 v[32:35], v[166:169], v[190:193], 0
	v_mfma_f32_16x16x32_bf16 v[24:27], v[174:177], v[190:193], 0
	v_mfma_f32_16x16x32_bf16 v[16:19], v[166:169], v[198:201], 0
	v_mfma_f32_16x16x32_bf16 v[8:11], v[174:177], v[198:201], 0
	v_mfma_f32_16x16x32_bf16 v[4:7], v[166:169], v[206:209], 0
	v_mfma_f32_16x16x32_bf16 v[0:3], v[174:177], v[206:209], 0
	v_mfma_f32_16x16x32_bf16 v[48:51], v[170:173], v[186:189], v[48:51]
	v_mfma_f32_16x16x32_bf16 v[40:43], v[178:181], v[186:189], v[40:43]
	v_mfma_f32_16x16x32_bf16 v[32:35], v[170:173], v[194:197], v[32:35]
	v_mfma_f32_16x16x32_bf16 v[24:27], v[178:181], v[194:197], v[24:27]
	v_mfma_f32_16x16x32_bf16 v[16:19], v[170:173], v[202:205], v[16:19]
	v_mfma_f32_16x16x32_bf16 v[8:11], v[178:181], v[202:205], v[8:11]
	v_mfma_f32_16x16x32_bf16 v[4:7], v[170:173], v[210:213], v[4:7]
	v_mfma_f32_16x16x32_bf16 v[0:3], v[178:181], v[210:213], v[0:3]
	s_setprio 0
	s_barrier
	s_add_i32 s51, 0, 0x18000
	s_add_i32 s52, 0, 0x1c000
	v_add_u32_e32 v162, s51, v149
	v_add_u32_e32 v178, s52, v149
	ds_read_b128 v[144:147], v162
	ds_read_b128 v[154:157], v162 offset:1024
	ds_read_b128 v[158:161], v162 offset:2048
	ds_read_b128 v[162:165], v162 offset:3072
	ds_read_b128 v[166:169], v178
	ds_read_b128 v[170:173], v178 offset:1024
	ds_read_b128 v[174:177], v178 offset:2048
	ds_read_b128 v[178:181], v178 offset:3072
	s_add_u32 s24, s24, 0x80000
	s_addc_u32 s25, s25, 0
	s_mov_b32 m0, s36
	v_lshl_add_u64 v[222:223], s[24:25], 0, v[134:135]
	ds_read_b128 v[182:185], v153 offset:32768
	ds_read_b128 v[186:189], v153 offset:33792
	ds_read_b128 v[190:193], v153 offset:34816
	ds_read_b128 v[194:197], v153 offset:35840
	ds_read_b128 v[198:201], v153 offset:36864
	ds_read_b128 v[202:205], v153 offset:37888
	ds_read_b128 v[206:209], v153 offset:38912
	ds_read_b128 v[210:213], v153 offset:39936
	global_load_lds_dwordx4 v[222:223], off
	v_lshl_add_u64 v[222:223], s[24:25], 0, v[130:131]
	s_mov_b32 m0, s37
	s_nop 0
	global_load_lds_dwordx4 v[222:223], off
	s_waitcnt vmcnt(8)
	s_waitcnt lgkmcnt(0)
	s_barrier
	s_setprio 1
	v_mfma_f32_16x16x32_bf16 v[124:127], v[144:147], v[182:185], v[124:127]
	v_mfma_f32_16x16x32_bf16 v[120:123], v[158:161], v[182:185], v[120:123]
	v_mfma_f32_16x16x32_bf16 v[116:119], v[144:147], v[190:193], v[116:119]
	v_mfma_f32_16x16x32_bf16 v[108:111], v[158:161], v[190:193], v[108:111]
	v_mfma_f32_16x16x32_bf16 v[100:103], v[144:147], v[198:201], v[100:103]
	v_mfma_f32_16x16x32_bf16 v[92:95], v[158:161], v[198:201], v[92:95]
	v_mfma_f32_16x16x32_bf16 v[84:87], v[144:147], v[206:209], v[84:87]
	v_mfma_f32_16x16x32_bf16 v[76:79], v[158:161], v[206:209], v[76:79]
	v_mfma_f32_16x16x32_bf16 v[124:127], v[154:157], v[186:189], v[124:127]
	v_mfma_f32_16x16x32_bf16 v[120:123], v[162:165], v[186:189], v[120:123]
	v_mfma_f32_16x16x32_bf16 v[116:119], v[154:157], v[194:197], v[116:119]
	v_mfma_f32_16x16x32_bf16 v[108:111], v[162:165], v[194:197], v[108:111]
	v_mfma_f32_16x16x32_bf16 v[100:103], v[154:157], v[202:205], v[100:103]
	v_mfma_f32_16x16x32_bf16 v[92:95], v[162:165], v[202:205], v[92:95]
	v_mfma_f32_16x16x32_bf16 v[84:87], v[154:157], v[210:213], v[84:87]
	v_mfma_f32_16x16x32_bf16 v[76:79], v[162:165], v[210:213], v[76:79]
	v_mfma_f32_16x16x32_bf16 v[112:115], v[166:169], v[182:185], v[112:115]
	v_mfma_f32_16x16x32_bf16 v[104:107], v[174:177], v[182:185], v[104:107]
	v_mfma_f32_16x16x32_bf16 v[96:99], v[166:169], v[190:193], v[96:99]
	v_mfma_f32_16x16x32_bf16 v[88:91], v[174:177], v[190:193], v[88:91]
	v_mfma_f32_16x16x32_bf16 v[80:83], v[166:169], v[198:201], v[80:83]
	v_mfma_f32_16x16x32_bf16 v[72:75], v[174:177], v[198:201], v[72:75]
	v_mfma_f32_16x16x32_bf16 v[68:71], v[166:169], v[206:209], v[68:71]
	v_mfma_f32_16x16x32_bf16 v[64:67], v[174:177], v[206:209], v[64:67]
	v_mfma_f32_16x16x32_bf16 v[112:115], v[170:173], v[186:189], v[112:115]
	v_mfma_f32_16x16x32_bf16 v[104:107], v[178:181], v[186:189], v[104:107]
	v_mfma_f32_16x16x32_bf16 v[96:99], v[170:173], v[194:197], v[96:99]
	v_mfma_f32_16x16x32_bf16 v[88:91], v[178:181], v[194:197], v[88:91]
	v_mfma_f32_16x16x32_bf16 v[80:83], v[170:173], v[202:205], v[80:83]
	v_mfma_f32_16x16x32_bf16 v[72:75], v[178:181], v[202:205], v[72:75]
	v_mfma_f32_16x16x32_bf16 v[68:71], v[170:173], v[210:213], v[68:71]
	v_mfma_f32_16x16x32_bf16 v[64:67], v[178:181], v[210:213], v[64:67]
	s_setprio 0
	s_barrier
; #define PG8_STAGE(bufoff, gbase, voff) do { _Pragma("unroll") for (int _i = 0; _i < 2; ++_i) \
;         __builtin_amdgcn_global_load_lds((const unsigned*)((const char*)(gbase) + (voff)[_i]), (PG8_LAS unsigned*)(lds + (bufoff) + ldsw + _i * 8192), 16, 0, 0); } while (0)
; #define PG8_LDA(dst, b, h) do { _Pragma("unroll") for (int m = 0; m < 4; ++m) _Pragma("unroll") for (int k = 0; k < 2; ++k) dst[m][k] = *(const PG8_LAS bf16x8*)(lds + PG8_SA(b, h) + aoff + m * 2048 + k * 1024); } while (0)
; #define PG8_LDB(dst, b, h) do { _Pragma("unroll") for (int n = 0; n < 2; ++n) _Pragma("unroll") for (int k = 0; k < 2; ++k) dst[n][k] = *(const PG8_LAS bf16x8*)(lds + PG8_SB(b, h) + boff + n * 2048 + k * 1024); } while (0)
; #define PG8_MMA(ai, bj, At, Bt) do { __builtin_amdgcn_s_setprio(1); _Pragma("unroll") for (int m = 0; m < 4; ++m) _Pragma("unroll") for (int n = 0; n < 2; ++n) _Pragma("unroll") for (int k = 0; k < 2; ++k) \
;         acc[ai][bj][m][n] = __builtin_amdgcn_mfma_f32_16x16x32_bf16(Bt[n][k], At[m][k], acc[ai][bj][m][n], 0, 0, 0); __builtin_amdgcn_s_setprio(0); } while (0)
; #define PG8_BAR __builtin_amdgcn_s_barrier()
; template <class Epi, class Sched, bool ALIGN_EPI = false, bool SP2 = false>
; __device__ __forceinline__ void gemm_phase(PG8_LAS unsigned char* lds, const Gemm g, const Sched& S, const Epi& E, const int wave_in) {
;     ...
;             PG8_LDB(B0, 0, 0); PG8_LDB(B1, 0, 1); PG8_SCHED; PG8_LDA(At, 0, 0); PG8_STAGE(PG8_SA(1, 1), a1 + hstepA, voffA);
;             PG8_WAIT_V(8); PG8_WAIT_L(0); PG8_BAR; PG8_MMA(0, 0, At, B0); PG8_MMA(0, 1, At, B1); PG8_BAR; PG8_SCHED;
;             PG8_LDA(At, 0, 1); PG8_STAGE(PG8_SB(0, 0), b2, voffB); PG8_STAGE(PG8_SB(0, 1), b2 + hstepB, voffB); PG8_STAGE(PG8_SA(0, 0), a2, voffA);
;             PG8_WAIT_V(8); PG8_WAIT_L(0); PG8_BAR; PG8_MMA(1, 0, At, B0); PG8_MMA(1, 1, At, B1); PG8_BAR; PG8_SCHED;
;             PG8_LDB(B0, 1, 0); PG8_LDB(B1, 1, 1); PG8_SCHED; PG8_LDA(At, 1, 0); PG8_STAGE(PG8_SA(0, 1), a2 + hstepA, voffA);
;             PG8_WAIT_V(8); PG8_WAIT_L(0); PG8_BAR; PG8_MMA(0, 0, At, B0); PG8_MMA(0, 1, At, B1); PG8_BAR; PG8_SCHED;
;             PG8_LDA(At, 1, 1); PG8_STAGE(PG8_SB(1, 0), b3, voffB); PG8_STAGE(PG8_SB(1, 1), b3 + hstepB, voffB); PG8_STAGE(PG8_SA(1, 0), a3, voffA);
;             PG8_WAIT_V(8); PG8_WAIT_L(0); PG8_BAR; PG8_MMA(1, 0, At, B0); PG8_MMA(1, 1, At, B1); PG8_BAR; PG8_SCHED;
	s_add_i32 s24, s51, s30
	v_lshl_add_u64 v[214:215], v[214:215], 0, s[6:7]
	s_mov_b32 m0, s24
	ds_read_b128 v[182:185], v153 offset:49152
	ds_read_b128 v[186:189], v153 offset:50176
	ds_read_b128 v[190:193], v153 offset:51200
	ds_read_b128 v[194:197], v153 offset:52224
	ds_read_b128 v[198:201], v153 offset:53248
	ds_read_b128 v[202:205], v153 offset:54272
	ds_read_b128 v[206:209], v153 offset:55296
	ds_read_b128 v[210:213], v153 offset:56320
	global_load_lds_dwordx4 v[214:215], off
	s_add_i32 m0, s24, 0x2000
	s_add_u32 s22, s22, 0x80080
	v_lshl_add_u64 v[214:215], v[216:217], 0, s[6:7]
	s_addc_u32 s23, s23, 0
	s_add_i32 s24, s52, s30
	global_load_lds_dwordx4 v[214:215], off
	v_lshl_add_u64 v[214:215], s[22:23], 0, v[132:133]
	s_mov_b32 m0, s24
	s_nop 0
	global_load_lds_dwordx4 v[214:215], off
	v_lshl_add_u64 v[214:215], s[22:23], 0, v[128:129]
	s_add_i32 m0, s24, 0x2000
	s_nop 0
	global_load_lds_dwordx4 v[214:215], off
	v_lshl_add_u64 v[214:215], v[218:219], 0, s[6:7]
	s_mov_b32 m0, s39
	s_nop 0
	global_load_lds_dwordx4 v[214:215], off
	v_lshl_add_u64 v[214:215], v[220:221], 0, s[6:7]
	s_mov_b32 m0, s40
	s_nop 0
	global_load_lds_dwordx4 v[214:215], off
	s_waitcnt vmcnt(8)
	s_waitcnt lgkmcnt(0)
	s_barrier
	s_setprio 1
	v_mfma_f32_16x16x32_bf16 v[60:63], v[144:147], v[182:185], v[60:63]
	v_mfma_f32_16x16x32_bf16 v[56:59], v[158:161], v[182:185], v[56:59]
	v_mfma_f32_16x16x32_bf16 v[52:55], v[144:147], v[190:193], v[52:55]
	v_mfma_f32_16x16x32_bf16 v[44:47], v[158:161], v[190:193], v[44:47]
	v_mfma_f32_16x16x32_bf16 v[36:39], v[144:147], v[198:201], v[36:39]
	v_mfma_f32_16x16x32_bf16 v[28:31], v[158:161], v[198:201], v[28:31]
	v_mfma_f32_16x16x32_bf16 v[20:23], v[144:147], v[206:209], v[20:23]
	v_mfma_f32_16x16x32_bf16 v[12:15], v[158:161], v[206:209], v[12:15]
	v_mfma_f32_16x16x32_bf16 v[60:63], v[154:157], v[186:189], v[60:63]
	v_mfma_f32_16x16x32_bf16 v[56:59], v[162:165], v[186:189], v[56:59]
	v_mfma_f32_16x16x32_bf16 v[52:55], v[154:157], v[194:197], v[52:55]
	v_mfma_f32_16x16x32_bf16 v[44:47], v[162:165], v[194:197], v[44:47]
	v_mfma_f32_16x16x32_bf16 v[36:39], v[154:157], v[202:205], v[36:39]
	v_mfma_f32_16x16x32_bf16 v[28:31], v[162:165], v[202:205], v[28:31]
	v_mfma_f32_16x16x32_bf16 v[20:23], v[154:157], v[210:213], v[20:23]
	v_mfma_f32_16x16x32_bf16 v[12:15], v[162:165], v[210:213], v[12:15]
	v_mfma_f32_16x16x32_bf16 v[48:51], v[166:169], v[182:185], v[48:51]
	v_mfma_f32_16x16x32_bf16 v[40:43], v[174:177], v[182:185], v[40:43]
	v_mfma_f32_16x16x32_bf16 v[32:35], v[166:169], v[190:193], v[32:35]
	v_mfma_f32_16x16x32_bf16 v[24:27], v[174:177], v[190:193], v[24:27]
	v_mfma_f32_16x16x32_bf16 v[16:19], v[166:169], v[198:201], v[16:19]
	v_mfma_f32_16x16x32_bf16 v[8:11], v[174:177], v[198:201], v[8:11]
	v_mfma_f32_16x16x32_bf16 v[4:7], v[166:169], v[206:209], v[4:7]
	v_mfma_f32_16x16x32_bf16 v[0:3], v[174:177], v[206:209], v[0:3]
	v_mfma_f32_16x16x32_bf16 v[48:51], v[170:173], v[186:189], v[48:51]
	v_mfma_f32_16x16x32_bf16 v[40:43], v[178:181], v[186:189], v[40:43]
	v_mfma_f32_16x16x32_bf16 v[32:35], v[170:173], v[194:197], v[32:35]
	v_mfma_f32_16x16x32_bf16 v[24:27], v[178:181], v[194:197], v[24:27]
	v_mfma_f32_16x16x32_bf16 v[16:19], v[170:173], v[202:205], v[16:19]
	v_mfma_f32_16x16x32_bf16 v[8:11], v[178:181], v[202:205], v[8:11]
	v_mfma_f32_16x16x32_bf16 v[4:7], v[170:173], v[210:213], v[4:7]
	v_mfma_f32_16x16x32_bf16 v[0:3], v[178:181], v[210:213], v[0:3]
	s_setprio 0
	s_barrier
	s_add_i32 s50, s50, 2
	s_add_u32 s20, s20, 0x100
	s_addc_u32 s21, s21, 0
	s_add_u32 s48, s48, 0x100
	s_addc_u32 s49, s49, 0
	s_cmp_gt_u32 s50, 29
	s_cbranch_scc0 .LBB0_1513
	s_branch .Lkx_18
.LBB0_1513:
	ds_read_b128 v[144:147], v151
	ds_read_b128 v[154:157], v151 offset:1024
	ds_read_b128 v[158:161], v151 offset:2048
	ds_read_b128 v[162:165], v151 offset:3072
	ds_read_b128 v[166:169], v152
	ds_read_b128 v[170:173], v152 offset:1024
	ds_read_b128 v[174:177], v152 offset:2048
	ds_read_b128 v[178:181], v152 offset:3072
	s_add_u32 s22, s20, 0xfff80080
	s_addc_u32 s23, s21, -1
	s_cmp_eq_u32 s50, 28
	s_cselect_b32 s25, s13, s23
	s_cselect_b32 s24, s46, s22
	s_cselect_b32 s23, s11, s49
	s_cselect_b32 s22, s47, s48
	v_lshl_add_u64 v[214:215], s[20:21], 0, v[136:137]
	s_add_i32 m0, s19, 0xc000
	ds_read_b128 v[182:185], v153
	ds_read_b128 v[186:189], v153 offset:1024
	ds_read_b128 v[190:193], v153 offset:2048
	ds_read_b128 v[194:197], v153 offset:3072
	ds_read_b128 v[198:201], v153 offset:4096
	ds_read_b128 v[202:205], v153 offset:5120
	ds_read_b128 v[206:209], v153 offset:6144
	ds_read_b128 v[210:213], v153 offset:7168
	global_load_lds_dwordx4 v[214:215], off
	v_lshl_add_u64 v[214:215], s[20:21], 0, v[138:139]
	s_add_i32 m0, s19, 0xe000
	s_nop 0
	global_load_lds_dwordx4 v[214:215], off
	s_waitcnt vmcnt(8)
	s_waitcnt lgkmcnt(0)
	s_barrier
; #define PG8_STAGE(bufoff, gbase, voff) do { _Pragma("unroll") for (int _i = 0; _i < 2; ++_i) \
;         __builtin_amdgcn_global_load_lds((const unsigned*)((const char*)(gbase) + (voff)[_i]), (PG8_LAS unsigned*)(lds + (bufoff) + ldsw + _i * 8192), 16, 0, 0); } while (0)
; #define PG8_LDA(dst, b, h) do { _Pragma("unroll") for (int m = 0; m < 4; ++m) _Pragma("unroll") for (int k = 0; k < 2; ++k) dst[m][k] = *(const PG8_LAS bf16x8*)(lds + PG8_SA(b, h) + aoff + m * 2048 + k * 1024); } while (0)
; #define PG8_MMA(ai, bj, At, Bt) do { __builtin_amdgcn_s_setprio(1); _Pragma("unroll") for (int m = 0; m < 4; ++m) _Pragma("unroll") for (int n = 0; n < 2; ++n) _Pragma("unroll") for (int k = 0; k < 2; ++k) \
;         acc[ai][bj][m][n] = __builtin_amdgcn_mfma_f32_16x16x32_bf16(Bt[n][k], At[m][k], acc[ai][bj][m][n], 0, 0, 0); __builtin_amdgcn_s_setprio(0); } while (0)
; #define PG8_WAIT_V(n) asm volatile("s_waitcnt vmcnt(" #n ")" ::: "memory")
; #define PG8_WAIT_L(n) asm volatile("s_waitcnt lgkmcnt(" #n ")" ::: "memory")
; #define PG8_BAR __builtin_amdgcn_s_barrier()
; #define PG8_SCHED __builtin_amdgcn_sched_barrier(0)
; template <class Epi, class Sched, bool ALIGN_EPI = false, bool SP2 = false>
; __device__ __forceinline__ void gemm_phase(PG8_LAS unsigned char* lds, const Gemm g, const Sched& S, const Epi& E, const int wave_in) {
;     ...
;             PG8_WAIT_V(8); PG8_WAIT_L(0); PG8_BAR; PG8_MMA(0, 0, At, B0); PG8_MMA(0, 1, At, B1); PG8_BAR; PG8_SCHED;
;             PG8_LDA(At, 0, 1); PG8_STAGE(PG8_SB(0, 0), b2, voffB); PG8_STAGE(PG8_SB(0, 1), b2 + hstepB, voffB); PG8_STAGE(PG8_SA(0, 0), a2, voffA);
;             PG8_WAIT_V(8); PG8_WAIT_L(0); PG8_BAR; PG8_MMA(1, 0, At, B0); PG8_MMA(1, 1, At, B1); PG8_BAR; PG8_SCHED;
	s_setprio 1
	v_mfma_f32_16x16x32_bf16 v[124:127], v[144:147], v[182:185], v[124:127]
	v_mfma_f32_16x16x32_bf16 v[120:123], v[158:161], v[182:185], v[120:123]
	v_mfma_f32_16x16x32_bf16 v[116:119], v[144:147], v[190:193], v[116:119]
	v_mfma_f32_16x16x32_bf16 v[108:111], v[158:161], v[190:193], v[108:111]
	v_mfma_f32_16x16x32_bf16 v[100:103], v[144:147], v[198:201], v[100:103]
	v_mfma_f32_16x16x32_bf16 v[92:95], v[158:161], v[198:201], v[92:95]
	v_mfma_f32_16x16x32_bf16 v[84:87], v[144:147], v[206:209], v[84:87]
	v_mfma_f32_16x16x32_bf16 v[76:79], v[158:161], v[206:209], v[76:79]
	v_mfma_f32_16x16x32_bf16 v[124:127], v[154:157], v[186:189], v[124:127]
	v_mfma_f32_16x16x32_bf16 v[120:123], v[162:165], v[186:189], v[120:123]
	v_mfma_f32_16x16x32_bf16 v[116:119], v[154:157], v[194:197], v[116:119]
	v_mfma_f32_16x16x32_bf16 v[108:111], v[162:165], v[194:197], v[108:111]
	v_mfma_f32_16x16x32_bf16 v[100:103], v[154:157], v[202:205], v[100:103]
	v_mfma_f32_16x16x32_bf16 v[92:95], v[162:165], v[202:205], v[92:95]
	v_mfma_f32_16x16x32_bf16 v[84:87], v[154:157], v[210:213], v[84:87]
	v_mfma_f32_16x16x32_bf16 v[76:79], v[162:165], v[210:213], v[76:79]
	v_mfma_f32_16x16x32_bf16 v[112:115], v[166:169], v[182:185], v[112:115]
	v_mfma_f32_16x16x32_bf16 v[104:107], v[174:177], v[182:185], v[104:107]
	v_mfma_f32_16x16x32_bf16 v[96:99], v[166:169], v[190:193], v[96:99]
	v_mfma_f32_16x16x32_bf16 v[88:91], v[174:177], v[190:193], v[88:91]
	v_mfma_f32_16x16x32_bf16 v[80:83], v[166:169], v[198:201], v[80:83]
	v_mfma_f32_16x16x32_bf16 v[72:75], v[174:177], v[198:201], v[72:75]
	v_mfma_f32_16x16x32_bf16 v[68:71], v[166:169], v[206:209], v[68:71]
	v_mfma_f32_16x16x32_bf16 v[64:67], v[174:177], v[206:209], v[64:67]
	v_mfma_f32_16x16x32_bf16 v[112:115], v[170:173], v[186:189], v[112:115]
	v_mfma_f32_16x16x32_bf16 v[104:107], v[178:181], v[186:189], v[104:107]
	v_mfma_f32_16x16x32_bf16 v[96:99], v[170:173], v[194:197], v[96:99]
	v_mfma_f32_16x16x32_bf16 v[88:91], v[178:181], v[194:197], v[88:91]
	v_mfma_f32_16x16x32_bf16 v[80:83], v[170:173], v[202:205], v[80:83]
	v_mfma_f32_16x16x32_bf16 v[72:75], v[178:181], v[202:205], v[72:75]
	v_mfma_f32_16x16x32_bf16 v[68:71], v[170:173], v[210:213], v[68:71]
	v_mfma_f32_16x16x32_bf16 v[64:67], v[178:181], v[210:213], v[64:67]
	s_setprio 0
	s_barrier
	s_add_i32 s51, s42, s30
	v_lshl_add_u64 v[214:215], s[22:23], 0, v[132:133]
	s_mov_b32 m0, s51
	ds_read_b128 v[182:185], v153 offset:16384
	ds_read_b128 v[186:189], v153 offset:17408
	ds_read_b128 v[190:193], v153 offset:18432
	ds_read_b128 v[194:197], v153 offset:19456
	ds_read_b128 v[198:201], v153 offset:20480
	ds_read_b128 v[202:205], v153 offset:21504
	ds_read_b128 v[206:209], v153 offset:22528
	ds_read_b128 v[210:213], v153 offset:23552
	global_load_lds_dwordx4 v[214:215], off
	s_add_i32 m0, s51, 0x2000
	s_add_u32 s52, s22, 0x80000
	v_lshl_add_u64 v[216:217], s[22:23], 0, v[128:129]
	s_addc_u32 s53, s23, 0
	s_add_i32 s51, s43, s30
	global_load_lds_dwordx4 v[216:217], off
	v_lshl_add_u64 v[218:219], s[52:53], 0, v[132:133]
	s_mov_b32 m0, s51
	v_lshl_add_u64 v[220:221], s[24:25], 0, v[130:131]
	global_load_lds_dwordx4 v[218:219], off
	v_lshl_add_u64 v[218:219], s[52:53], 0, v[128:129]
	s_add_i32 m0, s51, 0x2000
	s_nop 0
	global_load_lds_dwordx4 v[218:219], off
	v_lshl_add_u64 v[218:219], s[24:25], 0, v[134:135]
	s_mov_b32 m0, s19
	s_nop 0
	global_load_lds_dwordx4 v[218:219], off
	s_mov_b32 m0, s35
	s_nop 0
	global_load_lds_dwordx4 v[220:221], off
	s_waitcnt vmcnt(8)
	s_waitcnt lgkmcnt(0)
	s_barrier
	s_setprio 1
	v_mfma_f32_16x16x32_bf16 v[60:63], v[144:147], v[182:185], v[60:63]
	v_mfma_f32_16x16x32_bf16 v[56:59], v[158:161], v[182:185], v[56:59]
	v_mfma_f32_16x16x32_bf16 v[52:55], v[144:147], v[190:193], v[52:55]
	v_mfma_f32_16x16x32_bf16 v[44:47], v[158:161], v[190:193], v[44:47]
	v_mfma_f32_16x16x32_bf16 v[36:39], v[144:147], v[198:201], v[36:39]
	v_mfma_f32_16x16x32_bf16 v[28:31], v[158:161], v[198:201], v[28:31]
	v_mfma_f32_16x16x32_bf16 v[20:23], v[144:147], v[206:209], v[20:23]
	v_mfma_f32_16x16x32_bf16 v[12:15], v[158:161], v[206:209], v[12:15]
	v_mfma_f32_16x16x32_bf16 v[60:63], v[154:157], v[186:189], v[60:63]
	v_mfma_f32_16x16x32_bf16 v[56:59], v[162:165], v[186:189], v[56:59]
	v_mfma_f32_16x16x32_bf16 v[52:55], v[154:157], v[194:197], v[52:55]
	v_mfma_f32_16x16x32_bf16 v[44:47], v[162:165], v[194:197], v[44:47]
	v_mfma_f32_16x16x32_bf16 v[36:39], v[154:157], v[202:205], v[36:39]
	v_mfma_f32_16x16x32_bf16 v[28:31], v[162:165], v[202:205], v[28:31]
	v_mfma_f32_16x16x32_bf16 v[20:23], v[154:157], v[210:213], v[20:23]
	v_mfma_f32_16x16x32_bf16 v[12:15], v[162:165], v[210:213], v[12:15]
	v_mfma_f32_16x16x32_bf16 v[48:51], v[166:169], v[182:185], v[48:51]
	v_mfma_f32_16x16x32_bf16 v[40:43], v[174:177], v[182:185], v[40:43]
	v_mfma_f32_16x16x32_bf16 v[32:35], v[166:169], v[190:193], v[32:35]
	v_mfma_f32_16x16x32_bf16 v[24:27], v[174:177], v[190:193], v[24:27]
	v_mfma_f32_16x16x32_bf16 v[16:19], v[166:169], v[198:201], v[16:19]
	v_mfma_f32_16x16x32_bf16 v[8:11], v[174:177], v[198:201], v[8:11]
	v_mfma_f32_16x16x32_bf16 v[4:7], v[166:169], v[206:209], v[4:7]
	v_mfma_f32_16x16x32_bf16 v[0:3], v[174:177], v[206:209], v[0:3]
	v_mfma_f32_16x16x32_bf16 v[48:51], v[170:173], v[186:189], v[48:51]
	v_mfma_f32_16x16x32_bf16 v[40:43], v[178:181], v[186:189], v[40:43]
	v_mfma_f32_16x16x32_bf16 v[32:35], v[170:173], v[194:197], v[32:35]
	v_mfma_f32_16x16x32_bf16 v[24:27], v[178:181], v[194:197], v[24:27]
	v_mfma_f32_16x16x32_bf16 v[16:19], v[170:173], v[202:205], v[16:19]
	v_mfma_f32_16x16x32_bf16 v[8:11], v[178:181], v[202:205], v[8:11]
	v_mfma_f32_16x16x32_bf16 v[4:7], v[170:173], v[210:213], v[4:7]
	v_mfma_f32_16x16x32_bf16 v[0:3], v[178:181], v[210:213], v[0:3]
	s_setprio 0
	s_barrier
; #define PG8_STAGE(bufoff, gbase, voff) do { _Pragma("unroll") for (int _i = 0; _i < 2; ++_i) \
;         __builtin_amdgcn_global_load_lds((const unsigned*)((const char*)(gbase) + (voff)[_i]), (PG8_LAS unsigned*)(lds + (bufoff) + ldsw + _i * 8192), 16, 0, 0); } while (0)
; #define PG8_LDA(dst, b, h) do { _Pragma("unroll") for (int m = 0; m < 4; ++m) _Pragma("unroll") for (int k = 0; k < 2; ++k) dst[m][k] = *(const PG8_LAS bf16x8*)(lds + PG8_SA(b, h) + aoff + m * 2048 + k * 1024); } while (0)
; #define PG8_LDB(dst, b, h) do { _Pragma("unroll") for (int n = 0; n < 2; ++n) _Pragma("unroll") for (int k = 0; k < 2; ++k) dst[n][k] = *(const PG8_LAS bf16x8*)(lds + PG8_SB(b, h) + boff + n * 2048 + k * 1024); } while (0)
; #define PG8_MMA(ai, bj, At, Bt) do { __builtin_amdgcn_s_setprio(1); _Pragma("unroll") for (int m = 0; m < 4; ++m) _Pragma("unroll") for (int n = 0; n < 2; ++n) _Pragma("unroll") for (int k = 0; k < 2; ++k) \
;         acc[ai][bj][m][n] = __builtin_amdgcn_mfma_f32_16x16x32_bf16(Bt[n][k], At[m][k], acc[ai][bj][m][n], 0, 0, 0); __builtin_amdgcn_s_setprio(0); } while (0)
; #define PG8_WAIT_V(n) asm volatile("s_waitcnt vmcnt(" #n ")" ::: "memory")
; #define PG8_WAIT_L(n) asm volatile("s_waitcnt lgkmcnt(" #n ")" ::: "memory")
; #define PG8_BAR __builtin_amdgcn_s_barrier()
; #define PG8_SCHED __builtin_amdgcn_sched_barrier(0)
; template <class Epi, class Sched, bool ALIGN_EPI = false, bool SP2 = false>
; __device__ __forceinline__ void gemm_phase(PG8_LAS unsigned char* lds, const Gemm g, const Sched& S, const Epi& E, const int wave_in) {
;     ...
;             PG8_LDB(B0, 1, 0); PG8_LDB(B1, 1, 1); PG8_SCHED; PG8_LDA(At, 1, 0); PG8_STAGE(PG8_SA(0, 1), a2 + hstepA, voffA);
;             PG8_WAIT_V(8); PG8_WAIT_L(0); PG8_BAR; PG8_MMA(0, 0, At, B0); PG8_MMA(0, 1, At, B1); PG8_BAR; PG8_SCHED;
	s_add_i32 s51, 0, 0x18000
	s_add_i32 s52, 0, 0x1c000
	v_add_u32_e32 v162, s51, v149
	v_add_u32_e32 v178, s52, v149
	ds_read_b128 v[144:147], v162
	ds_read_b128 v[154:157], v162 offset:1024
	ds_read_b128 v[158:161], v162 offset:2048
	ds_read_b128 v[162:165], v162 offset:3072
	ds_read_b128 v[166:169], v178
	ds_read_b128 v[170:173], v178 offset:1024
	ds_read_b128 v[174:177], v178 offset:2048
	ds_read_b128 v[178:181], v178 offset:3072
	s_add_u32 s24, s24, 0x80000
	s_addc_u32 s25, s25, 0
	s_mov_b32 m0, s36
	v_lshl_add_u64 v[222:223], s[24:25], 0, v[134:135]
	ds_read_b128 v[182:185], v153 offset:32768
	ds_read_b128 v[186:189], v153 offset:33792
	ds_read_b128 v[190:193], v153 offset:34816
	ds_read_b128 v[194:197], v153 offset:35840
	ds_read_b128 v[198:201], v153 offset:36864
	ds_read_b128 v[202:205], v153 offset:37888
	ds_read_b128 v[206:209], v153 offset:38912
	ds_read_b128 v[210:213], v153 offset:39936
	global_load_lds_dwordx4 v[222:223], off
	v_lshl_add_u64 v[222:223], s[24:25], 0, v[130:131]
	s_mov_b32 m0, s37
	s_nop 0
	global_load_lds_dwordx4 v[222:223], off
	s_waitcnt vmcnt(8)
	s_waitcnt lgkmcnt(0)
	s_barrier
	s_setprio 1
	v_mfma_f32_16x16x32_bf16 v[124:127], v[144:147], v[182:185], v[124:127]
	v_mfma_f32_16x16x32_bf16 v[120:123], v[158:161], v[182:185], v[120:123]
	v_mfma_f32_16x16x32_bf16 v[116:119], v[144:147], v[190:193], v[116:119]
	v_mfma_f32_16x16x32_bf16 v[108:111], v[158:161], v[190:193], v[108:111]
	v_mfma_f32_16x16x32_bf16 v[100:103], v[144:147], v[198:201], v[100:103]
	v_mfma_f32_16x16x32_bf16 v[92:95], v[158:161], v[198:201], v[92:95]
	v_mfma_f32_16x16x32_bf16 v[84:87], v[144:147], v[206:209], v[84:87]
	v_mfma_f32_16x16x32_bf16 v[76:79], v[158:161], v[206:209], v[76:79]
	v_mfma_f32_16x16x32_bf16 v[124:127], v[154:157], v[186:189], v[124:127]
	v_mfma_f32_16x16x32_bf16 v[120:123], v[162:165], v[186:189], v[120:123]
	v_mfma_f32_16x16x32_bf16 v[116:119], v[154:157], v[194:197], v[116:119]
	v_mfma_f32_16x16x32_bf16 v[108:111], v[162:165], v[194:197], v[108:111]
	v_mfma_f32_16x16x32_bf16 v[100:103], v[154:157], v[202:205], v[100:103]
	v_mfma_f32_16x16x32_bf16 v[92:95], v[162:165], v[202:205], v[92:95]
	v_mfma_f32_16x16x32_bf16 v[84:87], v[154:157], v[210:213], v[84:87]
	v_mfma_f32_16x16x32_bf16 v[76:79], v[162:165], v[210:213], v[76:79]
	v_mfma_f32_16x16x32_bf16 v[112:115], v[166:169], v[182:185], v[112:115]
	v_mfma_f32_16x16x32_bf16 v[104:107], v[174:177], v[182:185], v[104:107]
	v_mfma_f32_16x16x32_bf16 v[96:99], v[166:169], v[190:193], v[96:99]
	v_mfma_f32_16x16x32_bf16 v[88:91], v[174:177], v[190:193], v[88:91]
	v_mfma_f32_16x16x32_bf16 v[80:83], v[166:169], v[198:201], v[80:83]
	v_mfma_f32_16x16x32_bf16 v[72:75], v[174:177], v[198:201], v[72:75]
	v_mfma_f32_16x16x32_bf16 v[68:71], v[166:169], v[206:209], v[68:71]
	v_mfma_f32_16x16x32_bf16 v[64:67], v[174:177], v[206:209], v[64:67]
	v_mfma_f32_16x16x32_bf16 v[112:115], v[170:173], v[186:189], v[112:115]
	v_mfma_f32_16x16x32_bf16 v[104:107], v[178:181], v[186:189], v[104:107]
	v_mfma_f32_16x16x32_bf16 v[96:99], v[170:173], v[194:197], v[96:99]
	v_mfma_f32_16x16x32_bf16 v[88:91], v[178:181], v[194:197], v[88:91]
	v_mfma_f32_16x16x32_bf16 v[80:83], v[170:173], v[202:205], v[80:83]
	v_mfma_f32_16x16x32_bf16 v[72:75], v[178:181], v[202:205], v[72:75]
	v_mfma_f32_16x16x32_bf16 v[68:71], v[170:173], v[210:213], v[68:71]
	v_mfma_f32_16x16x32_bf16 v[64:67], v[178:181], v[210:213], v[64:67]
	s_setprio 0
	s_barrier
; #define PG8_STAGE(bufoff, gbase, voff) do { _Pragma("unroll") for (int _i = 0; _i < 2; ++_i) \
;         __builtin_amdgcn_global_load_lds((const unsigned*)((const char*)(gbase) + (voff)[_i]), (PG8_LAS unsigned*)(lds + (bufoff) + ldsw + _i * 8192), 16, 0, 0); } while (0)
; #define PG8_LDA(dst, b, h) do { _Pragma("unroll") for (int m = 0; m < 4; ++m) _Pragma("unroll") for (int k = 0; k < 2; ++k) dst[m][k] = *(const PG8_LAS bf16x8*)(lds + PG8_SA(b, h) + aoff + m * 2048 + k * 1024); } while (0)
; #define PG8_MMA(ai, bj, At, Bt) do { __builtin_amdgcn_s_setprio(1); _Pragma("unroll") for (int m = 0; m < 4; ++m) _Pragma("unroll") for (int n = 0; n < 2; ++n) _Pragma("unroll") for (int k = 0; k < 2; ++k) \
;         acc[ai][bj][m][n] = __builtin_amdgcn_mfma_f32_16x16x32_bf16(Bt[n][k], At[m][k], acc[ai][bj][m][n], 0, 0, 0); __builtin_amdgcn_s_setprio(0); } while (0)
; #define PG8_WAIT_V(n) asm volatile("s_waitcnt vmcnt(" #n ")" ::: "memory")
; #define PG8_WAIT_L(n) asm volatile("s_waitcnt lgkmcnt(" #n ")" ::: "memory")
; #define PG8_BAR __builtin_amdgcn_s_barrier()
; #define PG8_SCHED __builtin_amdgcn_sched_barrier(0)
; template <class Epi, class Sched, bool ALIGN_EPI = false, bool SP2 = false>
; __device__ __forceinline__ void gemm_phase(PG8_LAS unsigned char* lds, const Gemm g, const Sched& S, const Epi& E, const int wave_in) {
;     ...
;             PG8_LDA(At, 1, 1); PG8_STAGE(PG8_SB(1, 0), b3, voffB); PG8_STAGE(PG8_SB(1, 1), b3 + hstepB, voffB); PG8_STAGE(PG8_SA(1, 0), a3, voffA);
;             PG8_WAIT_V(8); PG8_WAIT_L(0); PG8_BAR; PG8_MMA(1, 0, At, B0); PG8_MMA(1, 1, At, B1); PG8_BAR; PG8_SCHED;
	s_add_i32 s24, s51, s30
	v_lshl_add_u64 v[214:215], v[214:215], 0, s[6:7]
	s_mov_b32 m0, s24
	ds_read_b128 v[182:185], v153 offset:49152
	ds_read_b128 v[186:189], v153 offset:50176
	ds_read_b128 v[190:193], v153 offset:51200
	ds_read_b128 v[194:197], v153 offset:52224
	ds_read_b128 v[198:201], v153 offset:53248
	ds_read_b128 v[202:205], v153 offset:54272
	ds_read_b128 v[206:209], v153 offset:55296
	ds_read_b128 v[210:213], v153 offset:56320
	global_load_lds_dwordx4 v[214:215], off
	s_add_i32 m0, s24, 0x2000
	s_add_u32 s22, s22, 0x80080
	v_lshl_add_u64 v[214:215], v[216:217], 0, s[6:7]
	s_addc_u32 s23, s23, 0
	s_add_i32 s24, s52, s30
	global_load_lds_dwordx4 v[214:215], off
	v_lshl_add_u64 v[214:215], s[22:23], 0, v[132:133]
	s_mov_b32 m0, s24
	s_nop 0
	global_load_lds_dwordx4 v[214:215], off
	v_lshl_add_u64 v[214:215], s[22:23], 0, v[128:129]
	s_add_i32 m0, s24, 0x2000
	s_nop 0
	global_load_lds_dwordx4 v[214:215], off
	v_lshl_add_u64 v[214:215], v[218:219], 0, s[6:7]
	s_mov_b32 m0, s39
	s_nop 0
	global_load_lds_dwordx4 v[214:215], off
	v_lshl_add_u64 v[214:215], v[220:221], 0, s[6:7]
	s_mov_b32 m0, s40
	s_nop 0
	global_load_lds_dwordx4 v[214:215], off
	s_waitcnt vmcnt(8)
	s_waitcnt lgkmcnt(0)
	s_barrier
	s_setprio 1
	v_mfma_f32_16x16x32_bf16 v[60:63], v[144:147], v[182:185], v[60:63]
	v_mfma_f32_16x16x32_bf16 v[56:59], v[158:161], v[182:185], v[56:59]
	v_mfma_f32_16x16x32_bf16 v[52:55], v[144:147], v[190:193], v[52:55]
	v_mfma_f32_16x16x32_bf16 v[44:47], v[158:161], v[190:193], v[44:47]
	v_mfma_f32_16x16x32_bf16 v[36:39], v[144:147], v[198:201], v[36:39]
	v_mfma_f32_16x16x32_bf16 v[28:31], v[158:161], v[198:201], v[28:31]
	v_mfma_f32_16x16x32_bf16 v[20:23], v[144:147], v[206:209], v[20:23]
	v_mfma_f32_16x16x32_bf16 v[12:15], v[158:161], v[206:209], v[12:15]
	v_mfma_f32_16x16x32_bf16 v[60:63], v[154:157], v[186:189], v[60:63]
	v_mfma_f32_16x16x32_bf16 v[56:59], v[162:165], v[186:189], v[56:59]
	v_mfma_f32_16x16x32_bf16 v[52:55], v[154:157], v[194:197], v[52:55]
	v_mfma_f32_16x16x32_bf16 v[44:47], v[162:165], v[194:197], v[44:47]
	v_mfma_f32_16x16x32_bf16 v[36:39], v[154:157], v[202:205], v[36:39]
	v_mfma_f32_16x16x32_bf16 v[28:31], v[162:165], v[202:205], v[28:31]
	v_mfma_f32_16x16x32_bf16 v[20:23], v[154:157], v[210:213], v[20:23]
	v_mfma_f32_16x16x32_bf16 v[12:15], v[162:165], v[210:213], v[12:15]
	v_mfma_f32_16x16x32_bf16 v[48:51], v[166:169], v[182:185], v[48:51]
	v_mfma_f32_16x16x32_bf16 v[40:43], v[174:177], v[182:185], v[40:43]
	v_mfma_f32_16x16x32_bf16 v[32:35], v[166:169], v[190:193], v[32:35]
	v_mfma_f32_16x16x32_bf16 v[24:27], v[174:177], v[190:193], v[24:27]
	v_mfma_f32_16x16x32_bf16 v[16:19], v[166:169], v[198:201], v[16:19]
	v_mfma_f32_16x16x32_bf16 v[8:11], v[174:177], v[198:201], v[8:11]
	v_mfma_f32_16x16x32_bf16 v[4:7], v[166:169], v[206:209], v[4:7]
	v_mfma_f32_16x16x32_bf16 v[0:3], v[174:177], v[206:209], v[0:3]
	v_mfma_f32_16x16x32_bf16 v[48:51], v[170:173], v[186:189], v[48:51]
	v_mfma_f32_16x16x32_bf16 v[40:43], v[178:181], v[186:189], v[40:43]
	v_mfma_f32_16x16x32_bf16 v[32:35], v[170:173], v[194:197], v[32:35]
	v_mfma_f32_16x16x32_bf16 v[24:27], v[178:181], v[194:197], v[24:27]
	v_mfma_f32_16x16x32_bf16 v[16:19], v[170:173], v[202:205], v[16:19]
	v_mfma_f32_16x16x32_bf16 v[8:11], v[178:181], v[202:205], v[8:11]
	v_mfma_f32_16x16x32_bf16 v[4:7], v[170:173], v[210:213], v[4:7]
	v_mfma_f32_16x16x32_bf16 v[0:3], v[178:181], v[210:213], v[0:3]
	s_setprio 0
	s_barrier
	s_add_i32 s50, s50, 2
	s_add_u32 s20, s20, 0x100
	s_addc_u32 s21, s21, 0
	s_add_u32 s48, s48, 0x100
	s_addc_u32 s49, s49, 0
	s_cmp_gt_u32 s50, 29
	s_cbranch_scc0 .LBB0_1513

;     __host__ __device__ bool next(int i, Unit& u) const { const bool ok = StaticOrder::next(i, u); u.pm = 0; u.pn = 0; return ok; }
; #define PG8_STAGE(bufoff, gbase, voff) do { _Pragma("unroll") for (int _i = 0; _i < 2; ++_i) \
;         __builtin_amdgcn_global_load_lds((const unsigned*)((const char*)(gbase) + (voff)[_i]), (PG8_LAS unsigned*)(lds + (bufoff) + ldsw + _i * 8192), 16, 0, 0); } while (0)
; #define PG8_LDA(dst, b, h) do { _Pragma("unroll") for (int m = 0; m < 4; ++m) _Pragma("unroll") for (int k = 0; k < 2; ++k) dst[m][k] = *(const PG8_LAS bf16x8*)(lds + PG8_SA(b, h) + aoff + m * 2048 + k * 1024); } while (0)
; #define PG8_LDB(dst, b, h) do { _Pragma("unroll") for (int n = 0; n < 2; ++n) _Pragma("unroll") for (int k = 0; k < 2; ++k) dst[n][k] = *(const PG8_LAS bf16x8*)(lds + PG8_SB(b, h) + boff + n * 2048 + k * 1024); } while (0)
; #define PG8_WAIT_V(n) asm volatile("s_waitcnt vmcnt(" #n ")" ::: "memory")
; #define PG8_BAR __builtin_amdgcn_s_barrier()
; template <class Epi, class Sched, bool ALIGN_EPI = false, bool SP2 = false>
; __device__ __forceinline__ void gemm_phase(PG8_LAS unsigned char* lds, const Gemm g, const Sched& S, const Epi& E, const int wave_in) {
;     ...
;         const bool has_next = S.next(ui + 1, nxt);
;         const char* nA = has_next ? (const char*)g.A + (size_t)nxt.pm * tstepA : cA; const char* nB = has_next ? (const char*)g.Bt + (size_t)nxt.pn * tstepB : cB;
;         for (int t = 0; t < nt; t += 2) {
;             const bool last = (t == nt - 2);
;             const char* a1 = cA + (size_t)(t + 1) * kstep;
;             const char* a2 = last ? nA : cA + (size_t)(t + 2) * kstep; const char* b2 = last ? nB : cB + (size_t)(t + 2) * kstep;
;             const char* a3 = a2 + kstep; const char* b3 = b2 + kstep;
;             if (last && has_next) S.a_ready(nxt);
;             if constexpr (SP2) {
;             PG8_LDB(B0, 0, 0); PG8_LDB(B1, 0, 1); PG8_SCHED; PG8_LDA(At, 0, 0); PG8_STAGE(PG8_SA(1, 1), a1 + hstepA, voffA);
;             PG8_WAIT_V(8); PG8_WAIT_L(0); PG8_BAR; PG8_MMA(0, 0, At, B0); PG8_MMA(0, 1, At, B1); PG8_BAR; PG8_SCHED;
;             PG8_LDA(At, 0, 1); PG8_STAGE(PG8_SB(0, 0), b2, voffB); PG8_STAGE(PG8_SB(0, 1), b2 + hstepB, voffB); PG8_STAGE(PG8_SA(0, 0), a2, voffA);
;             PG8_WAIT_V(8); PG8_WAIT_L(0); PG8_BAR; PG8_MMA(1, 0, At, B0); PG8_MMA(1, 1, At, B1); PG8_BAR; PG8_SCHED;
.LBB0_1824:
	s_ashr_i32 s19, s18, 31
	s_lshl_b64 s[20:21], s[18:19], 20
	s_add_u32 s20, s34, s20
	s_addc_u32 s21, s35, s21
	s_and_b64 s[22:23], s[2:3], exec
	s_cselect_b32 s19, s21, s27
	s_cselect_b32 s25, s20, s26
	s_ashr_i32 s17, s16, 31
	s_lshl_b64 s[22:23], s[16:17], 20
	s_add_u32 s22, s36, s22
	s_addc_u32 s23, s37, s23
	s_and_b64 s[30:31], s[2:3], exec
	s_cselect_b32 s17, s23, s29
	s_cselect_b32 s58, s22, s28
	s_add_u32 s26, s26, 0x80080
	s_addc_u32 s27, s27, 0
	s_add_u32 s59, s28, 0x100
	v_mov_b32_e32 v0, 0
	s_addc_u32 s60, s29, 0
	s_mov_b32 s61, -2
	s_waitcnt vmcnt(0)
	ds_read_b128 v[128:131], v214
	ds_read_b128 v[132:135], v214 offset:1024
	ds_read_b128 v[136:139], v214 offset:2048
	ds_read_b128 v[140:143], v214 offset:3072
	ds_read_b128 v[162:165], v215
	ds_read_b128 v[166:169], v215 offset:1024
	ds_read_b128 v[170:173], v215 offset:2048
	ds_read_b128 v[174:177], v215 offset:3072
	s_add_u32 s28, s26, 0xfff80080
	s_addc_u32 s29, s27, -1
	s_cmp_eq_u32 s61, 28
	s_cselect_b32 s31, s19, s29
	s_cselect_b32 s30, s25, s28
	s_cselect_b32 s29, s17, s60
	s_cselect_b32 s28, s58, s59
	v_lshl_add_u64 v[210:211], s[26:27], 0, v[154:155]
	s_add_i32 m0, s41, 0xc000
	ds_read_b128 v[178:181], v216
	ds_read_b128 v[182:185], v216 offset:1024
	ds_read_b128 v[186:189], v216 offset:2048
	ds_read_b128 v[190:193], v216 offset:3072
	ds_read_b128 v[194:197], v216 offset:4096
	ds_read_b128 v[198:201], v216 offset:5120
	ds_read_b128 v[202:205], v216 offset:6144
	ds_read_b128 v[206:209], v216 offset:7168
	global_load_lds_dwordx4 v[210:211], off
	v_lshl_add_u64 v[210:211], s[26:27], 0, v[156:157]
	s_add_i32 m0, s41, 0xe000
	s_nop 0
	global_load_lds_dwordx4 v[210:211], off
	s_waitcnt vmcnt(8)
	s_waitcnt lgkmcnt(0)
	s_barrier
	s_setprio 1
	v_mfma_f32_16x16x32_bf16 v[124:127], v[128:131], v[178:181], 0
	v_mfma_f32_16x16x32_bf16 v[120:123], v[136:139], v[178:181], 0
	v_mfma_f32_16x16x32_bf16 v[112:115], v[128:131], v[186:189], 0
	v_mfma_f32_16x16x32_bf16 v[104:107], v[136:139], v[186:189], 0
	v_mfma_f32_16x16x32_bf16 v[100:103], v[128:131], v[194:197], 0
	v_mfma_f32_16x16x32_bf16 v[96:99], v[136:139], v[194:197], 0
	v_mfma_f32_16x16x32_bf16 v[76:79], v[128:131], v[202:205], 0
	v_mfma_f32_16x16x32_bf16 v[72:75], v[136:139], v[202:205], 0
	v_mfma_f32_16x16x32_bf16 v[124:127], v[132:135], v[182:185], v[124:127]
	v_mfma_f32_16x16x32_bf16 v[120:123], v[140:143], v[182:185], v[120:123]
	v_mfma_f32_16x16x32_bf16 v[112:115], v[132:135], v[190:193], v[112:115]
	v_mfma_f32_16x16x32_bf16 v[104:107], v[140:143], v[190:193], v[104:107]
	v_mfma_f32_16x16x32_bf16 v[100:103], v[132:135], v[198:201], v[100:103]
	v_mfma_f32_16x16x32_bf16 v[96:99], v[140:143], v[198:201], v[96:99]
	v_mfma_f32_16x16x32_bf16 v[76:79], v[132:135], v[206:209], v[76:79]
	v_mfma_f32_16x16x32_bf16 v[72:75], v[140:143], v[206:209], v[72:75]
	v_mfma_f32_16x16x32_bf16 v[116:119], v[162:165], v[178:181], 0
	v_mfma_f32_16x16x32_bf16 v[108:111], v[170:173], v[178:181], 0
	v_mfma_f32_16x16x32_bf16 v[92:95], v[162:165], v[186:189], 0
	v_mfma_f32_16x16x32_bf16 v[88:91], v[170:173], v[186:189], 0
	v_mfma_f32_16x16x32_bf16 v[84:87], v[162:165], v[194:197], 0
	v_mfma_f32_16x16x32_bf16 v[80:83], v[170:173], v[194:197], 0
	v_mfma_f32_16x16x32_bf16 v[68:71], v[162:165], v[202:205], 0
	v_mfma_f32_16x16x32_bf16 v[64:67], v[170:173], v[202:205], 0
	v_mfma_f32_16x16x32_bf16 v[116:119], v[166:169], v[182:185], v[116:119]
	v_mfma_f32_16x16x32_bf16 v[108:111], v[174:177], v[182:185], v[108:111]
	v_mfma_f32_16x16x32_bf16 v[92:95], v[166:169], v[190:193], v[92:95]
	v_mfma_f32_16x16x32_bf16 v[88:91], v[174:177], v[190:193], v[88:91]
	v_mfma_f32_16x16x32_bf16 v[84:87], v[166:169], v[198:201], v[84:87]
	v_mfma_f32_16x16x32_bf16 v[80:83], v[174:177], v[198:201], v[80:83]
	v_mfma_f32_16x16x32_bf16 v[68:71], v[166:169], v[206:209], v[68:71]
	v_mfma_f32_16x16x32_bf16 v[64:67], v[174:177], v[206:209], v[64:67]
	s_setprio 0
	s_barrier
	s_add_i32 s62, s51, s38
	v_lshl_add_u64 v[210:211], s[28:29], 0, v[148:149]
	s_mov_b32 m0, s62
	ds_read_b128 v[178:181], v216 offset:16384
	ds_read_b128 v[182:185], v216 offset:17408
	ds_read_b128 v[186:189], v216 offset:18432
	ds_read_b128 v[190:193], v216 offset:19456
	ds_read_b128 v[194:197], v216 offset:20480
	ds_read_b128 v[198:201], v216 offset:21504
	ds_read_b128 v[202:205], v216 offset:22528
	ds_read_b128 v[206:209], v216 offset:23552
	global_load_lds_dwordx4 v[210:211], off
	s_add_i32 m0, s62, 0x2000
	s_add_u32 s62, s28, 0x80000
	v_lshl_add_u64 v[218:219], s[28:29], 0, v[144:145]
	s_addc_u32 s63, s29, 0
	s_add_i32 s64, s52, s38
	global_load_lds_dwordx4 v[218:219], off
	v_lshl_add_u64 v[220:221], s[62:63], 0, v[148:149]
	s_mov_b32 m0, s64
	v_lshl_add_u64 v[222:223], s[30:31], 0, v[146:147]
	global_load_lds_dwordx4 v[220:221], off
	v_lshl_add_u64 v[220:221], s[62:63], 0, v[144:145]
	s_add_i32 m0, s64, 0x2000
	s_nop 0
	global_load_lds_dwordx4 v[220:221], off
	v_lshl_add_u64 v[220:221], s[30:31], 0, v[150:151]
	s_mov_b32 m0, s41
	s_nop 0
	global_load_lds_dwordx4 v[220:221], off
	s_mov_b32 m0, s42
	s_nop 0
	global_load_lds_dwordx4 v[222:223], off
	s_waitcnt vmcnt(8)
	s_waitcnt lgkmcnt(0)
	s_barrier
; #define PG8_STAGE(bufoff, gbase, voff) do { _Pragma("unroll") for (int _i = 0; _i < 2; ++_i) \
;         __builtin_amdgcn_global_load_lds((const unsigned*)((const char*)(gbase) + (voff)[_i]), (PG8_LAS unsigned*)(lds + (bufoff) + ldsw + _i * 8192), 16, 0, 0); } while (0)
; #define PG8_LDA(dst, b, h) do { _Pragma("unroll") for (int m = 0; m < 4; ++m) _Pragma("unroll") for (int k = 0; k < 2; ++k) dst[m][k] = *(const PG8_LAS bf16x8*)(lds + PG8_SA(b, h) + aoff + m * 2048 + k * 1024); } while (0)
; #define PG8_LDB(dst, b, h) do { _Pragma("unroll") for (int n = 0; n < 2; ++n) _Pragma("unroll") for (int k = 0; k < 2; ++k) dst[n][k] = *(const PG8_LAS bf16x8*)(lds + PG8_SB(b, h) + boff + n * 2048 + k * 1024); } while (0)
; #define PG8_MMA(ai, bj, At, Bt) do { __builtin_amdgcn_s_setprio(1); _Pragma("unroll") for (int m = 0; m < 4; ++m) _Pragma("unroll") for (int n = 0; n < 2; ++n) _Pragma("unroll") for (int k = 0; k < 2; ++k) \
;         acc[ai][bj][m][n] = __builtin_amdgcn_mfma_f32_16x16x32_bf16(Bt[n][k], At[m][k], acc[ai][bj][m][n], 0, 0, 0); __builtin_amdgcn_s_setprio(0); } while (0)
; #define PG8_WAIT_V(n) asm volatile("s_waitcnt vmcnt(" #n ")" ::: "memory")
; #define PG8_WAIT_L(n) asm volatile("s_waitcnt lgkmcnt(" #n ")" ::: "memory")
; #define PG8_BAR __builtin_amdgcn_s_barrier()
; #define PG8_SCHED __builtin_amdgcn_sched_barrier(0)
; template <class Epi, class Sched, bool ALIGN_EPI = false, bool SP2 = false>
; __device__ __forceinline__ void gemm_phase(PG8_LAS unsigned char* lds, const Gemm g, const Sched& S, const Epi& E, const int wave_in) {
;     ...
;             PG8_WAIT_V(8); PG8_WAIT_L(0); PG8_BAR; PG8_MMA(1, 0, At, B0); PG8_MMA(1, 1, At, B1); PG8_BAR; PG8_SCHED;
;             PG8_LDB(B0, 1, 0); PG8_LDB(B1, 1, 1); PG8_SCHED; PG8_LDA(At, 1, 0); PG8_STAGE(PG8_SA(0, 1), a2 + hstepA, voffA);
;             PG8_WAIT_V(8); PG8_WAIT_L(0); PG8_BAR; PG8_MMA(0, 0, At, B0); PG8_MMA(0, 1, At, B1); PG8_BAR; PG8_SCHED;
	s_setprio 1
	v_mfma_f32_16x16x32_bf16 v[60:63], v[128:131], v[178:181], 0
	v_mfma_f32_16x16x32_bf16 v[56:59], v[136:139], v[178:181], 0
	v_mfma_f32_16x16x32_bf16 v[48:51], v[128:131], v[186:189], 0
	v_mfma_f32_16x16x32_bf16 v[40:43], v[136:139], v[186:189], 0
	v_mfma_f32_16x16x32_bf16 v[32:35], v[128:131], v[194:197], 0
	v_mfma_f32_16x16x32_bf16 v[24:27], v[136:139], v[194:197], 0
	v_mfma_f32_16x16x32_bf16 v[16:19], v[128:131], v[202:205], 0
	v_mfma_f32_16x16x32_bf16 v[8:11], v[136:139], v[202:205], 0
	v_mfma_f32_16x16x32_bf16 v[60:63], v[132:135], v[182:185], v[60:63]
	v_mfma_f32_16x16x32_bf16 v[56:59], v[140:143], v[182:185], v[56:59]
	v_mfma_f32_16x16x32_bf16 v[48:51], v[132:135], v[190:193], v[48:51]
	v_mfma_f32_16x16x32_bf16 v[40:43], v[140:143], v[190:193], v[40:43]
	v_mfma_f32_16x16x32_bf16 v[32:35], v[132:135], v[198:201], v[32:35]
	v_mfma_f32_16x16x32_bf16 v[24:27], v[140:143], v[198:201], v[24:27]
	v_mfma_f32_16x16x32_bf16 v[16:19], v[132:135], v[206:209], v[16:19]
	v_mfma_f32_16x16x32_bf16 v[8:11], v[140:143], v[206:209], v[8:11]
	v_mfma_f32_16x16x32_bf16 v[52:55], v[162:165], v[178:181], 0
	v_mfma_f32_16x16x32_bf16 v[44:47], v[170:173], v[178:181], 0
	v_mfma_f32_16x16x32_bf16 v[36:39], v[162:165], v[186:189], 0
	v_mfma_f32_16x16x32_bf16 v[28:31], v[170:173], v[186:189], 0
	v_mfma_f32_16x16x32_bf16 v[20:23], v[162:165], v[194:197], 0
	v_mfma_f32_16x16x32_bf16 v[12:15], v[170:173], v[194:197], 0
	v_mfma_f32_16x16x32_bf16 v[4:7], v[162:165], v[202:205], 0
	v_mfma_f32_16x16x32_bf16 v[0:3], v[170:173], v[202:205], 0
	v_mfma_f32_16x16x32_bf16 v[52:55], v[166:169], v[182:185], v[52:55]
	v_mfma_f32_16x16x32_bf16 v[44:47], v[174:177], v[182:185], v[44:47]
	v_mfma_f32_16x16x32_bf16 v[36:39], v[166:169], v[190:193], v[36:39]
	v_mfma_f32_16x16x32_bf16 v[28:31], v[174:177], v[190:193], v[28:31]
	v_mfma_f32_16x16x32_bf16 v[20:23], v[166:169], v[198:201], v[20:23]
	v_mfma_f32_16x16x32_bf16 v[12:15], v[174:177], v[198:201], v[12:15]
	v_mfma_f32_16x16x32_bf16 v[4:7], v[166:169], v[206:209], v[4:7]
	v_mfma_f32_16x16x32_bf16 v[0:3], v[174:177], v[206:209], v[0:3]
	s_setprio 0
	s_barrier
	s_add_i32 s62, 0, 0x18000
	s_add_i32 s63, 0, 0x1c000
	v_add_u32_e32 v140, s62, v212
	v_add_u32_e32 v174, s63, v212
	ds_read_b128 v[128:131], v140
	ds_read_b128 v[132:135], v140 offset:1024
	ds_read_b128 v[136:139], v140 offset:2048
	ds_read_b128 v[140:143], v140 offset:3072
	ds_read_b128 v[162:165], v174
	ds_read_b128 v[166:169], v174 offset:1024
	ds_read_b128 v[170:173], v174 offset:2048
	ds_read_b128 v[174:177], v174 offset:3072
	s_add_u32 s30, s30, 0x80000
	s_addc_u32 s31, s31, 0
	s_mov_b32 m0, s43
	v_lshl_add_u64 v[224:225], s[30:31], 0, v[150:151]
	ds_read_b128 v[178:181], v216 offset:32768
	ds_read_b128 v[182:185], v216 offset:33792
	ds_read_b128 v[186:189], v216 offset:34816
	ds_read_b128 v[190:193], v216 offset:35840
	ds_read_b128 v[194:197], v216 offset:36864
	ds_read_b128 v[198:201], v216 offset:37888
	ds_read_b128 v[202:205], v216 offset:38912
	ds_read_b128 v[206:209], v216 offset:39936
	global_load_lds_dwordx4 v[224:225], off
	v_lshl_add_u64 v[224:225], s[30:31], 0, v[146:147]
	s_mov_b32 m0, s44
	s_nop 0
	global_load_lds_dwordx4 v[224:225], off
	s_waitcnt vmcnt(8)
	s_waitcnt lgkmcnt(0)
	s_barrier
	s_setprio 1
	v_mfma_f32_16x16x32_bf16 v[124:127], v[128:131], v[178:181], v[124:127]
	v_mfma_f32_16x16x32_bf16 v[120:123], v[136:139], v[178:181], v[120:123]
	v_mfma_f32_16x16x32_bf16 v[112:115], v[128:131], v[186:189], v[112:115]
	v_mfma_f32_16x16x32_bf16 v[104:107], v[136:139], v[186:189], v[104:107]
	v_mfma_f32_16x16x32_bf16 v[100:103], v[128:131], v[194:197], v[100:103]
	v_mfma_f32_16x16x32_bf16 v[96:99], v[136:139], v[194:197], v[96:99]
	v_mfma_f32_16x16x32_bf16 v[76:79], v[128:131], v[202:205], v[76:79]
	v_mfma_f32_16x16x32_bf16 v[72:75], v[136:139], v[202:205], v[72:75]
	v_mfma_f32_16x16x32_bf16 v[124:127], v[132:135], v[182:185], v[124:127]
	v_mfma_f32_16x16x32_bf16 v[120:123], v[140:143], v[182:185], v[120:123]
	v_mfma_f32_16x16x32_bf16 v[112:115], v[132:135], v[190:193], v[112:115]
	v_mfma_f32_16x16x32_bf16 v[104:107], v[140:143], v[190:193], v[104:107]
	v_mfma_f32_16x16x32_bf16 v[100:103], v[132:135], v[198:201], v[100:103]
	v_mfma_f32_16x16x32_bf16 v[96:99], v[140:143], v[198:201], v[96:99]
	v_mfma_f32_16x16x32_bf16 v[76:79], v[132:135], v[206:209], v[76:79]
	v_mfma_f32_16x16x32_bf16 v[72:75], v[140:143], v[206:209], v[72:75]
	v_mfma_f32_16x16x32_bf16 v[116:119], v[162:165], v[178:181], v[116:119]
	v_mfma_f32_16x16x32_bf16 v[108:111], v[170:173], v[178:181], v[108:111]
	v_mfma_f32_16x16x32_bf16 v[92:95], v[162:165], v[186:189], v[92:95]
	v_mfma_f32_16x16x32_bf16 v[88:91], v[170:173], v[186:189], v[88:91]
	v_mfma_f32_16x16x32_bf16 v[84:87], v[162:165], v[194:197], v[84:87]
	v_mfma_f32_16x16x32_bf16 v[80:83], v[170:173], v[194:197], v[80:83]
	v_mfma_f32_16x16x32_bf16 v[68:71], v[162:165], v[202:205], v[68:71]
	v_mfma_f32_16x16x32_bf16 v[64:67], v[170:173], v[202:205], v[64:67]
	v_mfma_f32_16x16x32_bf16 v[116:119], v[166:169], v[182:185], v[116:119]
	v_mfma_f32_16x16x32_bf16 v[108:111], v[174:177], v[182:185], v[108:111]
	v_mfma_f32_16x16x32_bf16 v[92:95], v[166:169], v[190:193], v[92:95]
	v_mfma_f32_16x16x32_bf16 v[88:91], v[174:177], v[190:193], v[88:91]
	v_mfma_f32_16x16x32_bf16 v[84:87], v[166:169], v[198:201], v[84:87]
	v_mfma_f32_16x16x32_bf16 v[80:83], v[174:177], v[198:201], v[80:83]
	v_mfma_f32_16x16x32_bf16 v[68:71], v[166:169], v[206:209], v[68:71]
	v_mfma_f32_16x16x32_bf16 v[64:67], v[174:177], v[206:209], v[64:67]
	s_setprio 0
	s_barrier
; #define PG8_STAGE(bufoff, gbase, voff) do { _Pragma("unroll") for (int _i = 0; _i < 2; ++_i) \
;         __builtin_amdgcn_global_load_lds((const unsigned*)((const char*)(gbase) + (voff)[_i]), (PG8_LAS unsigned*)(lds + (bufoff) + ldsw + _i * 8192), 16, 0, 0); } while (0)
; #define PG8_LDA(dst, b, h) do { _Pragma("unroll") for (int m = 0; m < 4; ++m) _Pragma("unroll") for (int k = 0; k < 2; ++k) dst[m][k] = *(const PG8_LAS bf16x8*)(lds + PG8_SA(b, h) + aoff + m * 2048 + k * 1024); } while (0)
; #define PG8_LDB(dst, b, h) do { _Pragma("unroll") for (int n = 0; n < 2; ++n) _Pragma("unroll") for (int k = 0; k < 2; ++k) dst[n][k] = *(const PG8_LAS bf16x8*)(lds + PG8_SB(b, h) + boff + n * 2048 + k * 1024); } while (0)
; #define PG8_MMA(ai, bj, At, Bt) do { __builtin_amdgcn_s_setprio(1); _Pragma("unroll") for (int m = 0; m < 4; ++m) _Pragma("unroll") for (int n = 0; n < 2; ++n) _Pragma("unroll") for (int k = 0; k < 2; ++k) \
;         acc[ai][bj][m][n] = __builtin_amdgcn_mfma_f32_16x16x32_bf16(Bt[n][k], At[m][k], acc[ai][bj][m][n], 0, 0, 0); __builtin_amdgcn_s_setprio(0); } while (0)
; #define PG8_BAR __builtin_amdgcn_s_barrier()
; template <class Epi, class Sched, bool ALIGN_EPI = false, bool SP2 = false>
; __device__ __forceinline__ void gemm_phase(PG8_LAS unsigned char* lds, const Gemm g, const Sched& S, const Epi& E, const int wave_in) {
;     ...
;             PG8_LDB(B0, 0, 0); PG8_LDB(B1, 0, 1); PG8_SCHED; PG8_LDA(At, 0, 0); PG8_STAGE(PG8_SA(1, 1), a1 + hstepA, voffA);
;             PG8_WAIT_V(8); PG8_WAIT_L(0); PG8_BAR; PG8_MMA(0, 0, At, B0); PG8_MMA(0, 1, At, B1); PG8_BAR; PG8_SCHED;
;             PG8_LDA(At, 0, 1); PG8_STAGE(PG8_SB(0, 0), b2, voffB); PG8_STAGE(PG8_SB(0, 1), b2 + hstepB, voffB); PG8_STAGE(PG8_SA(0, 0), a2, voffA);
;             PG8_WAIT_V(8); PG8_WAIT_L(0); PG8_BAR; PG8_MMA(1, 0, At, B0); PG8_MMA(1, 1, At, B1); PG8_BAR; PG8_SCHED;
;             PG8_LDB(B0, 1, 0); PG8_LDB(B1, 1, 1); PG8_SCHED; PG8_LDA(At, 1, 0); PG8_STAGE(PG8_SA(0, 1), a2 + hstepA, voffA);
;             PG8_WAIT_V(8); PG8_WAIT_L(0); PG8_BAR; PG8_MMA(0, 0, At, B0); PG8_MMA(0, 1, At, B1); PG8_BAR; PG8_SCHED;
;             PG8_LDA(At, 1, 1); PG8_STAGE(PG8_SB(1, 0), b3, voffB); PG8_STAGE(PG8_SB(1, 1), b3 + hstepB, voffB); PG8_STAGE(PG8_SA(1, 0), a3, voffA);
;             PG8_WAIT_V(8); PG8_WAIT_L(0); PG8_BAR; PG8_MMA(1, 0, At, B0); PG8_MMA(1, 1, At, B1); PG8_BAR; PG8_SCHED;
	s_add_i32 s30, s62, s38
	v_lshl_add_u64 v[210:211], v[210:211], 0, s[6:7]
	s_mov_b32 m0, s30
	ds_read_b128 v[178:181], v216 offset:49152
	ds_read_b128 v[182:185], v216 offset:50176
	ds_read_b128 v[186:189], v216 offset:51200
	ds_read_b128 v[190:193], v216 offset:52224
	ds_read_b128 v[194:197], v216 offset:53248
	ds_read_b128 v[198:201], v216 offset:54272
	ds_read_b128 v[202:205], v216 offset:55296
	ds_read_b128 v[206:209], v216 offset:56320
	global_load_lds_dwordx4 v[210:211], off
	s_add_i32 m0, s30, 0x2000
	s_add_u32 s28, s28, 0x80080
	v_lshl_add_u64 v[210:211], v[218:219], 0, s[6:7]
	s_addc_u32 s29, s29, 0
	s_add_i32 s30, s63, s38
	global_load_lds_dwordx4 v[210:211], off
	v_lshl_add_u64 v[210:211], s[28:29], 0, v[148:149]
	s_mov_b32 m0, s30
	s_nop 0
	global_load_lds_dwordx4 v[210:211], off
	v_lshl_add_u64 v[210:211], s[28:29], 0, v[144:145]
	s_add_i32 m0, s30, 0x2000
	s_nop 0
	global_load_lds_dwordx4 v[210:211], off
	v_lshl_add_u64 v[210:211], v[220:221], 0, s[6:7]
	s_mov_b32 m0, s48
	s_nop 0
	global_load_lds_dwordx4 v[210:211], off
	v_lshl_add_u64 v[210:211], v[222:223], 0, s[6:7]
	s_mov_b32 m0, s49
	s_nop 0
	global_load_lds_dwordx4 v[210:211], off
	s_waitcnt vmcnt(8)
	s_waitcnt lgkmcnt(0)
	s_barrier
	s_setprio 1
	v_mfma_f32_16x16x32_bf16 v[60:63], v[128:131], v[178:181], v[60:63]
	v_mfma_f32_16x16x32_bf16 v[56:59], v[136:139], v[178:181], v[56:59]
	v_mfma_f32_16x16x32_bf16 v[48:51], v[128:131], v[186:189], v[48:51]
	v_mfma_f32_16x16x32_bf16 v[40:43], v[136:139], v[186:189], v[40:43]
	v_mfma_f32_16x16x32_bf16 v[32:35], v[128:131], v[194:197], v[32:35]
	v_mfma_f32_16x16x32_bf16 v[24:27], v[136:139], v[194:197], v[24:27]
	v_mfma_f32_16x16x32_bf16 v[16:19], v[128:131], v[202:205], v[16:19]
	v_mfma_f32_16x16x32_bf16 v[8:11], v[136:139], v[202:205], v[8:11]
	v_mfma_f32_16x16x32_bf16 v[60:63], v[132:135], v[182:185], v[60:63]
	v_mfma_f32_16x16x32_bf16 v[56:59], v[140:143], v[182:185], v[56:59]
	v_mfma_f32_16x16x32_bf16 v[48:51], v[132:135], v[190:193], v[48:51]
	v_mfma_f32_16x16x32_bf16 v[40:43], v[140:143], v[190:193], v[40:43]
	v_mfma_f32_16x16x32_bf16 v[32:35], v[132:135], v[198:201], v[32:35]
	v_mfma_f32_16x16x32_bf16 v[24:27], v[140:143], v[198:201], v[24:27]
	v_mfma_f32_16x16x32_bf16 v[16:19], v[132:135], v[206:209], v[16:19]
	v_mfma_f32_16x16x32_bf16 v[8:11], v[140:143], v[206:209], v[8:11]
	v_mfma_f32_16x16x32_bf16 v[52:55], v[162:165], v[178:181], v[52:55]
	v_mfma_f32_16x16x32_bf16 v[44:47], v[170:173], v[178:181], v[44:47]
	v_mfma_f32_16x16x32_bf16 v[36:39], v[162:165], v[186:189], v[36:39]
	v_mfma_f32_16x16x32_bf16 v[28:31], v[170:173], v[186:189], v[28:31]
	v_mfma_f32_16x16x32_bf16 v[20:23], v[162:165], v[194:197], v[20:23]
	v_mfma_f32_16x16x32_bf16 v[12:15], v[170:173], v[194:197], v[12:15]
	v_mfma_f32_16x16x32_bf16 v[4:7], v[162:165], v[202:205], v[4:7]
	v_mfma_f32_16x16x32_bf16 v[0:3], v[170:173], v[202:205], v[0:3]
	v_mfma_f32_16x16x32_bf16 v[52:55], v[166:169], v[182:185], v[52:55]
	v_mfma_f32_16x16x32_bf16 v[44:47], v[174:177], v[182:185], v[44:47]
	v_mfma_f32_16x16x32_bf16 v[36:39], v[166:169], v[190:193], v[36:39]
	v_mfma_f32_16x16x32_bf16 v[28:31], v[174:177], v[190:193], v[28:31]
	v_mfma_f32_16x16x32_bf16 v[20:23], v[166:169], v[198:201], v[20:23]
	v_mfma_f32_16x16x32_bf16 v[12:15], v[174:177], v[198:201], v[12:15]
	v_mfma_f32_16x16x32_bf16 v[4:7], v[166:169], v[206:209], v[4:7]
	v_mfma_f32_16x16x32_bf16 v[0:3], v[174:177], v[206:209], v[0:3]
	s_setprio 0
	s_barrier
	s_add_i32 s61, s61, 2
	s_add_u32 s26, s26, 0x100
	s_addc_u32 s27, s27, 0
	s_add_u32 s59, s59, 0x100
	s_addc_u32 s60, s60, 0
	s_cmp_gt_u32 s61, 29
	s_cbranch_scc0 .LBB0_1825
	s_branch .Lkx_20
.LBB0_1825:
	ds_read_b128 v[128:131], v214
	ds_read_b128 v[132:135], v214 offset:1024
	ds_read_b128 v[136:139], v214 offset:2048
	ds_read_b128 v[140:143], v214 offset:3072
	ds_read_b128 v[162:165], v215
	ds_read_b128 v[166:169], v215 offset:1024
	ds_read_b128 v[170:173], v215 offset:2048
	ds_read_b128 v[174:177], v215 offset:3072
	s_add_u32 s28, s26, 0xfff80080
	s_addc_u32 s29, s27, -1
	s_cmp_eq_u32 s61, 28
	s_cselect_b32 s31, s19, s29
	s_cselect_b32 s30, s25, s28
	s_cselect_b32 s29, s17, s60
	s_cselect_b32 s28, s58, s59
	v_lshl_add_u64 v[210:211], s[26:27], 0, v[154:155]
	s_add_i32 m0, s41, 0xc000
	ds_read_b128 v[178:181], v216
	ds_read_b128 v[182:185], v216 offset:1024
	ds_read_b128 v[186:189], v216 offset:2048
	ds_read_b128 v[190:193], v216 offset:3072
	ds_read_b128 v[194:197], v216 offset:4096
	ds_read_b128 v[198:201], v216 offset:5120
	ds_read_b128 v[202:205], v216 offset:6144
	ds_read_b128 v[206:209], v216 offset:7168
	global_load_lds_dwordx4 v[210:211], off
	v_lshl_add_u64 v[210:211], s[26:27], 0, v[156:157]
	s_add_i32 m0, s41, 0xe000
	s_nop 0
	global_load_lds_dwordx4 v[210:211], off
	s_waitcnt vmcnt(8)
	s_waitcnt lgkmcnt(0)
	s_barrier
; #define PG8_STAGE(bufoff, gbase, voff) do { _Pragma("unroll") for (int _i = 0; _i < 2; ++_i) \
;         __builtin_amdgcn_global_load_lds((const unsigned*)((const char*)(gbase) + (voff)[_i]), (PG8_LAS unsigned*)(lds + (bufoff) + ldsw + _i * 8192), 16, 0, 0); } while (0)
; #define PG8_LDA(dst, b, h) do { _Pragma("unroll") for (int m = 0; m < 4; ++m) _Pragma("unroll") for (int k = 0; k < 2; ++k) dst[m][k] = *(const PG8_LAS bf16x8*)(lds + PG8_SA(b, h) + aoff + m * 2048 + k * 1024); } while (0)
; #define PG8_MMA(ai, bj, At, Bt) do { __builtin_amdgcn_s_setprio(1); _Pragma("unroll") for (int m = 0; m < 4; ++m) _Pragma("unroll") for (int n = 0; n < 2; ++n) _Pragma("unroll") for (int k = 0; k < 2; ++k) \
;         acc[ai][bj][m][n] = __builtin_amdgcn_mfma_f32_16x16x32_bf16(Bt[n][k], At[m][k], acc[ai][bj][m][n], 0, 0, 0); __builtin_amdgcn_s_setprio(0); } while (0)
; #define PG8_WAIT_V(n) asm volatile("s_waitcnt vmcnt(" #n ")" ::: "memory")
; #define PG8_WAIT_L(n) asm volatile("s_waitcnt lgkmcnt(" #n ")" ::: "memory")
; #define PG8_BAR __builtin_amdgcn_s_barrier()
; #define PG8_SCHED __builtin_amdgcn_sched_barrier(0)
; template <class Epi, class Sched, bool ALIGN_EPI = false, bool SP2 = false>
; __device__ __forceinline__ void gemm_phase(PG8_LAS unsigned char* lds, const Gemm g, const Sched& S, const Epi& E, const int wave_in) {
;     ...
;             PG8_WAIT_V(8); PG8_WAIT_L(0); PG8_BAR; PG8_MMA(0, 0, At, B0); PG8_MMA(0, 1, At, B1); PG8_BAR; PG8_SCHED;
;             PG8_LDA(At, 0, 1); PG8_STAGE(PG8_SB(0, 0), b2, voffB); PG8_STAGE(PG8_SB(0, 1), b2 + hstepB, voffB); PG8_STAGE(PG8_SA(0, 0), a2, voffA);
;             PG8_WAIT_V(8); PG8_WAIT_L(0); PG8_BAR; PG8_MMA(1, 0, At, B0); PG8_MMA(1, 1, At, B1); PG8_BAR; PG8_SCHED;
	s_setprio 1
	v_mfma_f32_16x16x32_bf16 v[124:127], v[128:131], v[178:181], v[124:127]
	v_mfma_f32_16x16x32_bf16 v[120:123], v[136:139], v[178:181], v[120:123]
	v_mfma_f32_16x16x32_bf16 v[112:115], v[128:131], v[186:189], v[112:115]
	v_mfma_f32_16x16x32_bf16 v[104:107], v[136:139], v[186:189], v[104:107]
	v_mfma_f32_16x16x32_bf16 v[100:103], v[128:131], v[194:197], v[100:103]
	v_mfma_f32_16x16x32_bf16 v[96:99], v[136:139], v[194:197], v[96:99]
	v_mfma_f32_16x16x32_bf16 v[76:79], v[128:131], v[202:205], v[76:79]
	v_mfma_f32_16x16x32_bf16 v[72:75], v[136:139], v[202:205], v[72:75]
	v_mfma_f32_16x16x32_bf16 v[124:127], v[132:135], v[182:185], v[124:127]
	v_mfma_f32_16x16x32_bf16 v[120:123], v[140:143], v[182:185], v[120:123]
	v_mfma_f32_16x16x32_bf16 v[112:115], v[132:135], v[190:193], v[112:115]
	v_mfma_f32_16x16x32_bf16 v[104:107], v[140:143], v[190:193], v[104:107]
	v_mfma_f32_16x16x32_bf16 v[100:103], v[132:135], v[198:201], v[100:103]
	v_mfma_f32_16x16x32_bf16 v[96:99], v[140:143], v[198:201], v[96:99]
	v_mfma_f32_16x16x32_bf16 v[76:79], v[132:135], v[206:209], v[76:79]
	v_mfma_f32_16x16x32_bf16 v[72:75], v[140:143], v[206:209], v[72:75]
	v_mfma_f32_16x16x32_bf16 v[116:119], v[162:165], v[178:181], v[116:119]
	v_mfma_f32_16x16x32_bf16 v[108:111], v[170:173], v[178:181], v[108:111]
	v_mfma_f32_16x16x32_bf16 v[92:95], v[162:165], v[186:189], v[92:95]
	v_mfma_f32_16x16x32_bf16 v[88:91], v[170:173], v[186:189], v[88:91]
	v_mfma_f32_16x16x32_bf16 v[84:87], v[162:165], v[194:197], v[84:87]
	v_mfma_f32_16x16x32_bf16 v[80:83], v[170:173], v[194:197], v[80:83]
	v_mfma_f32_16x16x32_bf16 v[68:71], v[162:165], v[202:205], v[68:71]
	v_mfma_f32_16x16x32_bf16 v[64:67], v[170:173], v[202:205], v[64:67]
	v_mfma_f32_16x16x32_bf16 v[116:119], v[166:169], v[182:185], v[116:119]
	v_mfma_f32_16x16x32_bf16 v[108:111], v[174:177], v[182:185], v[108:111]
	v_mfma_f32_16x16x32_bf16 v[92:95], v[166:169], v[190:193], v[92:95]
	v_mfma_f32_16x16x32_bf16 v[88:91], v[174:177], v[190:193], v[88:91]
	v_mfma_f32_16x16x32_bf16 v[84:87], v[166:169], v[198:201], v[84:87]
	v_mfma_f32_16x16x32_bf16 v[80:83], v[174:177], v[198:201], v[80:83]
	v_mfma_f32_16x16x32_bf16 v[68:71], v[166:169], v[206:209], v[68:71]
	v_mfma_f32_16x16x32_bf16 v[64:67], v[174:177], v[206:209], v[64:67]
	s_setprio 0
	s_barrier
	s_add_i32 s62, s51, s38
	v_lshl_add_u64 v[210:211], s[28:29], 0, v[148:149]
	s_mov_b32 m0, s62
	ds_read_b128 v[178:181], v216 offset:16384
	ds_read_b128 v[182:185], v216 offset:17408
	ds_read_b128 v[186:189], v216 offset:18432
	ds_read_b128 v[190:193], v216 offset:19456
	ds_read_b128 v[194:197], v216 offset:20480
	ds_read_b128 v[198:201], v216 offset:21504
	ds_read_b128 v[202:205], v216 offset:22528
	ds_read_b128 v[206:209], v216 offset:23552
	global_load_lds_dwordx4 v[210:211], off
	s_add_i32 m0, s62, 0x2000
	s_add_u32 s62, s28, 0x80000
	v_lshl_add_u64 v[218:219], s[28:29], 0, v[144:145]
	s_addc_u32 s63, s29, 0
	s_add_i32 s64, s52, s38
	global_load_lds_dwordx4 v[218:219], off
	v_lshl_add_u64 v[220:221], s[62:63], 0, v[148:149]
	s_mov_b32 m0, s64
	v_lshl_add_u64 v[222:223], s[30:31], 0, v[146:147]
	global_load_lds_dwordx4 v[220:221], off
	v_lshl_add_u64 v[220:221], s[62:63], 0, v[144:145]
	s_add_i32 m0, s64, 0x2000
	s_nop 0
	global_load_lds_dwordx4 v[220:221], off
	v_lshl_add_u64 v[220:221], s[30:31], 0, v[150:151]
	s_mov_b32 m0, s41
	s_nop 0
	global_load_lds_dwordx4 v[220:221], off
	s_mov_b32 m0, s42
	s_nop 0
	global_load_lds_dwordx4 v[222:223], off
	s_waitcnt vmcnt(8)
	s_waitcnt lgkmcnt(0)
	s_barrier
	s_setprio 1
	v_mfma_f32_16x16x32_bf16 v[60:63], v[128:131], v[178:181], v[60:63]
	v_mfma_f32_16x16x32_bf16 v[56:59], v[136:139], v[178:181], v[56:59]
	v_mfma_f32_16x16x32_bf16 v[48:51], v[128:131], v[186:189], v[48:51]
	v_mfma_f32_16x16x32_bf16 v[40:43], v[136:139], v[186:189], v[40:43]
	v_mfma_f32_16x16x32_bf16 v[32:35], v[128:131], v[194:197], v[32:35]
	v_mfma_f32_16x16x32_bf16 v[24:27], v[136:139], v[194:197], v[24:27]
	v_mfma_f32_16x16x32_bf16 v[16:19], v[128:131], v[202:205], v[16:19]
	v_mfma_f32_16x16x32_bf16 v[8:11], v[136:139], v[202:205], v[8:11]
	v_mfma_f32_16x16x32_bf16 v[60:63], v[132:135], v[182:185], v[60:63]
	v_mfma_f32_16x16x32_bf16 v[56:59], v[140:143], v[182:185], v[56:59]
	v_mfma_f32_16x16x32_bf16 v[48:51], v[132:135], v[190:193], v[48:51]
	v_mfma_f32_16x16x32_bf16 v[40:43], v[140:143], v[190:193], v[40:43]
	v_mfma_f32_16x16x32_bf16 v[32:35], v[132:135], v[198:201], v[32:35]
	v_mfma_f32_16x16x32_bf16 v[24:27], v[140:143], v[198:201], v[24:27]
	v_mfma_f32_16x16x32_bf16 v[16:19], v[132:135], v[206:209], v[16:19]
	v_mfma_f32_16x16x32_bf16 v[8:11], v[140:143], v[206:209], v[8:11]
	v_mfma_f32_16x16x32_bf16 v[52:55], v[162:165], v[178:181], v[52:55]
	v_mfma_f32_16x16x32_bf16 v[44:47], v[170:173], v[178:181], v[44:47]
	v_mfma_f32_16x16x32_bf16 v[36:39], v[162:165], v[186:189], v[36:39]
	v_mfma_f32_16x16x32_bf16 v[28:31], v[170:173], v[186:189], v[28:31]
	v_mfma_f32_16x16x32_bf16 v[20:23], v[162:165], v[194:197], v[20:23]
	v_mfma_f32_16x16x32_bf16 v[12:15], v[170:173], v[194:197], v[12:15]
	v_mfma_f32_16x16x32_bf16 v[4:7], v[162:165], v[202:205], v[4:7]
	v_mfma_f32_16x16x32_bf16 v[0:3], v[170:173], v[202:205], v[0:3]
	v_mfma_f32_16x16x32_bf16 v[52:55], v[166:169], v[182:185], v[52:55]
	v_mfma_f32_16x16x32_bf16 v[44:47], v[174:177], v[182:185], v[44:47]
	v_mfma_f32_16x16x32_bf16 v[36:39], v[166:169], v[190:193], v[36:39]
	v_mfma_f32_16x16x32_bf16 v[28:31], v[174:177], v[190:193], v[28:31]
	v_mfma_f32_16x16x32_bf16 v[20:23], v[166:169], v[198:201], v[20:23]
	v_mfma_f32_16x16x32_bf16 v[12:15], v[174:177], v[198:201], v[12:15]
	v_mfma_f32_16x16x32_bf16 v[4:7], v[166:169], v[206:209], v[4:7]
	v_mfma_f32_16x16x32_bf16 v[0:3], v[174:177], v[206:209], v[0:3]
	s_setprio 0
	s_barrier
; #define PG8_STAGE(bufoff, gbase, voff) do { _Pragma("unroll") for (int _i = 0; _i < 2; ++_i) \
;         __builtin_amdgcn_global_load_lds((const unsigned*)((const char*)(gbase) + (voff)[_i]), (PG8_LAS unsigned*)(lds + (bufoff) + ldsw + _i * 8192), 16, 0, 0); } while (0)
; #define PG8_LDA(dst, b, h) do { _Pragma("unroll") for (int m = 0; m < 4; ++m) _Pragma("unroll") for (int k = 0; k < 2; ++k) dst[m][k] = *(const PG8_LAS bf16x8*)(lds + PG8_SA(b, h) + aoff + m * 2048 + k * 1024); } while (0)
; #define PG8_LDB(dst, b, h) do { _Pragma("unroll") for (int n = 0; n < 2; ++n) _Pragma("unroll") for (int k = 0; k < 2; ++k) dst[n][k] = *(const PG8_LAS bf16x8*)(lds + PG8_SB(b, h) + boff + n * 2048 + k * 1024); } while (0)
; #define PG8_MMA(ai, bj, At, Bt) do { __builtin_amdgcn_s_setprio(1); _Pragma("unroll") for (int m = 0; m < 4; ++m) _Pragma("unroll") for (int n = 0; n < 2; ++n) _Pragma("unroll") for (int k = 0; k < 2; ++k) \
;         acc[ai][bj][m][n] = __builtin_amdgcn_mfma_f32_16x16x32_bf16(Bt[n][k], At[m][k], acc[ai][bj][m][n], 0, 0, 0); __builtin_amdgcn_s_setprio(0); } while (0)
; #define PG8_WAIT_V(n) asm volatile("s_waitcnt vmcnt(" #n ")" ::: "memory")
; #define PG8_WAIT_L(n) asm volatile("s_waitcnt lgkmcnt(" #n ")" ::: "memory")
; #define PG8_BAR __builtin_amdgcn_s_barrier()
; #define PG8_SCHED __builtin_amdgcn_sched_barrier(0)
; template <class Epi, class Sched, bool ALIGN_EPI = false, bool SP2 = false>
; __device__ __forceinline__ void gemm_phase(PG8_LAS unsigned char* lds, const Gemm g, const Sched& S, const Epi& E, const int wave_in) {
;     ...
;             PG8_LDB(B0, 1, 0); PG8_LDB(B1, 1, 1); PG8_SCHED; PG8_LDA(At, 1, 0); PG8_STAGE(PG8_SA(0, 1), a2 + hstepA, voffA);
;             PG8_WAIT_V(8); PG8_WAIT_L(0); PG8_BAR; PG8_MMA(0, 0, At, B0); PG8_MMA(0, 1, At, B1); PG8_BAR; PG8_SCHED;
	s_add_i32 s62, 0, 0x18000
	s_add_i32 s63, 0, 0x1c000
	v_add_u32_e32 v140, s62, v212
	v_add_u32_e32 v174, s63, v212
	ds_read_b128 v[128:131], v140
	ds_read_b128 v[132:135], v140 offset:1024
	ds_read_b128 v[136:139], v140 offset:2048
	ds_read_b128 v[140:143], v140 offset:3072
	ds_read_b128 v[162:165], v174
	ds_read_b128 v[166:169], v174 offset:1024
	ds_read_b128 v[170:173], v174 offset:2048
	ds_read_b128 v[174:177], v174 offset:3072
	s_add_u32 s30, s30, 0x80000
	s_addc_u32 s31, s31, 0
	s_mov_b32 m0, s43
	v_lshl_add_u64 v[224:225], s[30:31], 0, v[150:151]
	ds_read_b128 v[178:181], v216 offset:32768
	ds_read_b128 v[182:185], v216 offset:33792
	ds_read_b128 v[186:189], v216 offset:34816
	ds_read_b128 v[190:193], v216 offset:35840
	ds_read_b128 v[194:197], v216 offset:36864
	ds_read_b128 v[198:201], v216 offset:37888
	ds_read_b128 v[202:205], v216 offset:38912
	ds_read_b128 v[206:209], v216 offset:39936
	global_load_lds_dwordx4 v[224:225], off
	v_lshl_add_u64 v[224:225], s[30:31], 0, v[146:147]
	s_mov_b32 m0, s44
	s_nop 0
	global_load_lds_dwordx4 v[224:225], off
	s_waitcnt vmcnt(8)
	s_waitcnt lgkmcnt(0)
	s_barrier
	s_setprio 1
	v_mfma_f32_16x16x32_bf16 v[124:127], v[128:131], v[178:181], v[124:127]
	v_mfma_f32_16x16x32_bf16 v[120:123], v[136:139], v[178:181], v[120:123]
	v_mfma_f32_16x16x32_bf16 v[112:115], v[128:131], v[186:189], v[112:115]
	v_mfma_f32_16x16x32_bf16 v[104:107], v[136:139], v[186:189], v[104:107]
	v_mfma_f32_16x16x32_bf16 v[100:103], v[128:131], v[194:197], v[100:103]
	v_mfma_f32_16x16x32_bf16 v[96:99], v[136:139], v[194:197], v[96:99]
	v_mfma_f32_16x16x32_bf16 v[76:79], v[128:131], v[202:205], v[76:79]
	v_mfma_f32_16x16x32_bf16 v[72:75], v[136:139], v[202:205], v[72:75]
	v_mfma_f32_16x16x32_bf16 v[124:127], v[132:135], v[182:185], v[124:127]
	v_mfma_f32_16x16x32_bf16 v[120:123], v[140:143], v[182:185], v[120:123]
	v_mfma_f32_16x16x32_bf16 v[112:115], v[132:135], v[190:193], v[112:115]
	v_mfma_f32_16x16x32_bf16 v[104:107], v[140:143], v[190:193], v[104:107]
	v_mfma_f32_16x16x32_bf16 v[100:103], v[132:135], v[198:201], v[100:103]
	v_mfma_f32_16x16x32_bf16 v[96:99], v[140:143], v[198:201], v[96:99]
	v_mfma_f32_16x16x32_bf16 v[76:79], v[132:135], v[206:209], v[76:79]
	v_mfma_f32_16x16x32_bf16 v[72:75], v[140:143], v[206:209], v[72:75]
	v_mfma_f32_16x16x32_bf16 v[116:119], v[162:165], v[178:181], v[116:119]
	v_mfma_f32_16x16x32_bf16 v[108:111], v[170:173], v[178:181], v[108:111]
	v_mfma_f32_16x16x32_bf16 v[92:95], v[162:165], v[186:189], v[92:95]
	v_mfma_f32_16x16x32_bf16 v[88:91], v[170:173], v[186:189], v[88:91]
	v_mfma_f32_16x16x32_bf16 v[84:87], v[162:165], v[194:197], v[84:87]
	v_mfma_f32_16x16x32_bf16 v[80:83], v[170:173], v[194:197], v[80:83]
	v_mfma_f32_16x16x32_bf16 v[68:71], v[162:165], v[202:205], v[68:71]
	v_mfma_f32_16x16x32_bf16 v[64:67], v[170:173], v[202:205], v[64:67]
	v_mfma_f32_16x16x32_bf16 v[116:119], v[166:169], v[182:185], v[116:119]
	v_mfma_f32_16x16x32_bf16 v[108:111], v[174:177], v[182:185], v[108:111]
	v_mfma_f32_16x16x32_bf16 v[92:95], v[166:169], v[190:193], v[92:95]
	v_mfma_f32_16x16x32_bf16 v[88:91], v[174:177], v[190:193], v[88:91]
	v_mfma_f32_16x16x32_bf16 v[84:87], v[166:169], v[198:201], v[84:87]
	v_mfma_f32_16x16x32_bf16 v[80:83], v[174:177], v[198:201], v[80:83]
	v_mfma_f32_16x16x32_bf16 v[68:71], v[166:169], v[206:209], v[68:71]
	v_mfma_f32_16x16x32_bf16 v[64:67], v[174:177], v[206:209], v[64:67]
	s_setprio 0
	s_barrier
; #define PG8_STAGE(bufoff, gbase, voff) do { _Pragma("unroll") for (int _i = 0; _i < 2; ++_i) \
;         __builtin_amdgcn_global_load_lds((const unsigned*)((const char*)(gbase) + (voff)[_i]), (PG8_LAS unsigned*)(lds + (bufoff) + ldsw + _i * 8192), 16, 0, 0); } while (0)
; #define PG8_LDA(dst, b, h) do { _Pragma("unroll") for (int m = 0; m < 4; ++m) _Pragma("unroll") for (int k = 0; k < 2; ++k) dst[m][k] = *(const PG8_LAS bf16x8*)(lds + PG8_SA(b, h) + aoff + m * 2048 + k * 1024); } while (0)
; #define PG8_MMA(ai, bj, At, Bt) do { __builtin_amdgcn_s_setprio(1); _Pragma("unroll") for (int m = 0; m < 4; ++m) _Pragma("unroll") for (int n = 0; n < 2; ++n) _Pragma("unroll") for (int k = 0; k < 2; ++k) \
;         acc[ai][bj][m][n] = __builtin_amdgcn_mfma_f32_16x16x32_bf16(Bt[n][k], At[m][k], acc[ai][bj][m][n], 0, 0, 0); __builtin_amdgcn_s_setprio(0); } while (0)
; #define PG8_WAIT_V(n) asm volatile("s_waitcnt vmcnt(" #n ")" ::: "memory")
; #define PG8_WAIT_L(n) asm volatile("s_waitcnt lgkmcnt(" #n ")" ::: "memory")
; #define PG8_BAR __builtin_amdgcn_s_barrier()
; #define PG8_SCHED __builtin_amdgcn_sched_barrier(0)
; template <class Epi, class Sched, bool ALIGN_EPI = false, bool SP2 = false>
; __device__ __forceinline__ void gemm_phase(PG8_LAS unsigned char* lds, const Gemm g, const Sched& S, const Epi& E, const int wave_in) {
;     ...
;             PG8_LDA(At, 1, 1); PG8_STAGE(PG8_SB(1, 0), b3, voffB); PG8_STAGE(PG8_SB(1, 1), b3 + hstepB, voffB); PG8_STAGE(PG8_SA(1, 0), a3, voffA);
;             PG8_WAIT_V(8); PG8_WAIT_L(0); PG8_BAR; PG8_MMA(1, 0, At, B0); PG8_MMA(1, 1, At, B1); PG8_BAR; PG8_SCHED;
	s_add_i32 s30, s62, s38
	v_lshl_add_u64 v[210:211], v[210:211], 0, s[6:7]
	s_mov_b32 m0, s30
	ds_read_b128 v[178:181], v216 offset:49152
	ds_read_b128 v[182:185], v216 offset:50176
	ds_read_b128 v[186:189], v216 offset:51200
	ds_read_b128 v[190:193], v216 offset:52224
	ds_read_b128 v[194:197], v216 offset:53248
	ds_read_b128 v[198:201], v216 offset:54272
	ds_read_b128 v[202:205], v216 offset:55296
	ds_read_b128 v[206:209], v216 offset:56320
	global_load_lds_dwordx4 v[210:211], off
	s_add_i32 m0, s30, 0x2000
	s_add_u32 s28, s28, 0x80080
	v_lshl_add_u64 v[210:211], v[218:219], 0, s[6:7]
	s_addc_u32 s29, s29, 0
	s_add_i32 s30, s63, s38
	global_load_lds_dwordx4 v[210:211], off
	v_lshl_add_u64 v[210:211], s[28:29], 0, v[148:149]
	s_mov_b32 m0, s30
	s_nop 0
	global_load_lds_dwordx4 v[210:211], off
	v_lshl_add_u64 v[210:211], s[28:29], 0, v[144:145]
	s_add_i32 m0, s30, 0x2000
	s_nop 0
	global_load_lds_dwordx4 v[210:211], off
	v_lshl_add_u64 v[210:211], v[220:221], 0, s[6:7]
	s_mov_b32 m0, s48
	s_nop 0
	global_load_lds_dwordx4 v[210:211], off
	v_lshl_add_u64 v[210:211], v[222:223], 0, s[6:7]
	s_mov_b32 m0, s49
	s_nop 0
	global_load_lds_dwordx4 v[210:211], off
	s_waitcnt vmcnt(8)
	s_waitcnt lgkmcnt(0)
	s_barrier
	s_setprio 1
	v_mfma_f32_16x16x32_bf16 v[60:63], v[128:131], v[178:181], v[60:63]
	v_mfma_f32_16x16x32_bf16 v[56:59], v[136:139], v[178:181], v[56:59]
	v_mfma_f32_16x16x32_bf16 v[48:51], v[128:131], v[186:189], v[48:51]
	v_mfma_f32_16x16x32_bf16 v[40:43], v[136:139], v[186:189], v[40:43]
	v_mfma_f32_16x16x32_bf16 v[32:35], v[128:131], v[194:197], v[32:35]
	v_mfma_f32_16x16x32_bf16 v[24:27], v[136:139], v[194:197], v[24:27]
	v_mfma_f32_16x16x32_bf16 v[16:19], v[128:131], v[202:205], v[16:19]
	v_mfma_f32_16x16x32_bf16 v[8:11], v[136:139], v[202:205], v[8:11]
	v_mfma_f32_16x16x32_bf16 v[60:63], v[132:135], v[182:185], v[60:63]
	v_mfma_f32_16x16x32_bf16 v[56:59], v[140:143], v[182:185], v[56:59]
	v_mfma_f32_16x16x32_bf16 v[48:51], v[132:135], v[190:193], v[48:51]
	v_mfma_f32_16x16x32_bf16 v[40:43], v[140:143], v[190:193], v[40:43]
	v_mfma_f32_16x16x32_bf16 v[32:35], v[132:135], v[198:201], v[32:35]
	v_mfma_f32_16x16x32_bf16 v[24:27], v[140:143], v[198:201], v[24:27]
	v_mfma_f32_16x16x32_bf16 v[16:19], v[132:135], v[206:209], v[16:19]
	v_mfma_f32_16x16x32_bf16 v[8:11], v[140:143], v[206:209], v[8:11]
	v_mfma_f32_16x16x32_bf16 v[52:55], v[162:165], v[178:181], v[52:55]
	v_mfma_f32_16x16x32_bf16 v[44:47], v[170:173], v[178:181], v[44:47]
	v_mfma_f32_16x16x32_bf16 v[36:39], v[162:165], v[186:189], v[36:39]
	v_mfma_f32_16x16x32_bf16 v[28:31], v[170:173], v[186:189], v[28:31]
	v_mfma_f32_16x16x32_bf16 v[20:23], v[162:165], v[194:197], v[20:23]
	v_mfma_f32_16x16x32_bf16 v[12:15], v[170:173], v[194:197], v[12:15]
	v_mfma_f32_16x16x32_bf16 v[4:7], v[162:165], v[202:205], v[4:7]
	v_mfma_f32_16x16x32_bf16 v[0:3], v[170:173], v[202:205], v[0:3]
	v_mfma_f32_16x16x32_bf16 v[52:55], v[166:169], v[182:185], v[52:55]
	v_mfma_f32_16x16x32_bf16 v[44:47], v[174:177], v[182:185], v[44:47]
	v_mfma_f32_16x16x32_bf16 v[36:39], v[166:169], v[190:193], v[36:39]
	v_mfma_f32_16x16x32_bf16 v[28:31], v[174:177], v[190:193], v[28:31]
	v_mfma_f32_16x16x32_bf16 v[20:23], v[166:169], v[198:201], v[20:23]
	v_mfma_f32_16x16x32_bf16 v[12:15], v[174:177], v[198:201], v[12:15]
	v_mfma_f32_16x16x32_bf16 v[4:7], v[166:169], v[206:209], v[4:7]
	v_mfma_f32_16x16x32_bf16 v[0:3], v[174:177], v[206:209], v[0:3]
	s_setprio 0
	s_barrier
	s_add_i32 s61, s61, 2
	s_add_u32 s26, s26, 0x100
	s_addc_u32 s27, s27, 0
	s_add_u32 s59, s59, 0x100
	s_addc_u32 s60, s60, 0
	s_cmp_gt_u32 s61, 29
	s_cbranch_scc0 .LBB0_1825

;     __host__ __device__ bool next(int i, Unit& u) const { const bool ok = StaticOrder::next(i, u); u.pm = 0; u.pn = 0; return ok; }
; #define PG8_STAGE(bufoff, gbase, voff) do { _Pragma("unroll") for (int _i = 0; _i < 2; ++_i) \
;         __builtin_amdgcn_global_load_lds((const unsigned*)((const char*)(gbase) + (voff)[_i]), (PG8_LAS unsigned*)(lds + (bufoff) + ldsw + _i * 8192), 16, 0, 0); } while (0)
; #define PG8_LDA(dst, b, h) do { _Pragma("unroll") for (int m = 0; m < 4; ++m) _Pragma("unroll") for (int k = 0; k < 2; ++k) dst[m][k] = *(const PG8_LAS bf16x8*)(lds + PG8_SA(b, h) + aoff + m * 2048 + k * 1024); } while (0)
; #define PG8_LDB(dst, b, h) do { _Pragma("unroll") for (int n = 0; n < 2; ++n) _Pragma("unroll") for (int k = 0; k < 2; ++k) dst[n][k] = *(const PG8_LAS bf16x8*)(lds + PG8_SB(b, h) + boff + n * 2048 + k * 1024); } while (0)
; #define PG8_WAIT_V(n) asm volatile("s_waitcnt vmcnt(" #n ")" ::: "memory")
; #define PG8_BAR __builtin_amdgcn_s_barrier()
; template <class Epi, class Sched, bool ALIGN_EPI = false, bool SP2 = false>
; __device__ __forceinline__ void gemm_phase(PG8_LAS unsigned char* lds, const Gemm g, const Sched& S, const Epi& E, const int wave_in) {
;     ...
;         const bool has_next = S.next(ui + 1, nxt);
;         const char* nA = has_next ? (const char*)g.A + (size_t)nxt.pm * tstepA : cA; const char* nB = has_next ? (const char*)g.Bt + (size_t)nxt.pn * tstepB : cB;
;         for (int t = 0; t < nt; t += 2) {
;             const bool last = (t == nt - 2);
;             const char* a1 = cA + (size_t)(t + 1) * kstep;
;             const char* a2 = last ? nA : cA + (size_t)(t + 2) * kstep; const char* b2 = last ? nB : cB + (size_t)(t + 2) * kstep;
;             const char* a3 = a2 + kstep; const char* b3 = b2 + kstep;
;             if (last && has_next) S.a_ready(nxt);
;             if constexpr (SP2) {
;             PG8_LDB(B0, 0, 0); PG8_LDB(B1, 0, 1); PG8_SCHED; PG8_LDA(At, 0, 0); PG8_STAGE(PG8_SA(1, 1), a1 + hstepA, voffA);
;             PG8_WAIT_V(8); PG8_WAIT_L(0); PG8_BAR; PG8_MMA(0, 0, At, B0); PG8_MMA(0, 1, At, B1); PG8_BAR; PG8_SCHED;
;             PG8_LDA(At, 0, 1); PG8_STAGE(PG8_SB(0, 0), b2, voffB); PG8_STAGE(PG8_SB(0, 1), b2 + hstepB, voffB); PG8_STAGE(PG8_SA(0, 0), a2, voffA);
;             PG8_WAIT_V(8); PG8_WAIT_L(0); PG8_BAR; PG8_MMA(1, 0, At, B0); PG8_MMA(1, 1, At, B1); PG8_BAR; PG8_SCHED;
.LBB0_1950:
	s_ashr_i32 s41, s40, 31
	s_lshl_b64 s[42:43], s[40:41], 20
	s_add_u32 s42, s52, s42
	s_addc_u32 s43, s53, s43
	s_and_b64 s[44:45], s[10:11], exec
	s_cselect_b32 s1, s43, s47
	s_cselect_b32 s13, s42, s46
	s_ashr_i32 s39, s38, 31
	s_lshl_b64 s[44:45], s[38:39], 20
	s_add_u32 s44, s54, s44
	s_addc_u32 s45, s55, s45
	s_and_b64 s[50:51], s[10:11], exec
	s_cselect_b32 s39, s45, s49
	s_cselect_b32 s41, s44, s48
	s_add_u32 s46, s46, 0x80080
	s_addc_u32 s47, s47, 0
	s_add_u32 s72, s48, 0x100
	v_mov_b32_e32 v0, 0
	s_addc_u32 s73, s49, 0
	s_mov_b32 s74, -2
	s_waitcnt vmcnt(0)
	ds_read_b128 v[44:47], v189
	ds_read_b128 v[48:51], v189 offset:1024
	ds_read_b128 v[52:55], v189 offset:2048
	ds_read_b128 v[56:59], v189 offset:3072
	ds_read_b128 v[60:63], v197
	ds_read_b128 v[64:67], v197 offset:1024
	ds_read_b128 v[80:83], v197 offset:2048
	ds_read_b128 v[84:87], v197 offset:3072
	s_add_u32 s48, s46, 0xfff80080
	s_addc_u32 s49, s47, -1
	s_cmp_eq_u32 s74, 28
	s_cselect_b32 s51, s1, s49
	s_cselect_b32 s50, s13, s48
	s_cselect_b32 s49, s39, s73
	s_cselect_b32 s48, s41, s72
	v_lshl_add_u64 v[224:225], s[46:47], 0, v[206:207]
	s_add_i32 m0, s57, 0xc000
	ds_read_b128 v[88:91], v199
	ds_read_b128 v[92:95], v199 offset:1024
	ds_read_b128 v[96:99], v199 offset:2048
	ds_read_b128 v[100:103], v199 offset:3072
	ds_read_b128 v[176:179], v199 offset:4096
	ds_read_b128 v[212:215], v199 offset:5120
	ds_read_b128 v[216:219], v199 offset:6144
	ds_read_b128 v[220:223], v199 offset:7168
	global_load_lds_dwordx4 v[224:225], off
	v_lshl_add_u64 v[224:225], s[46:47], 0, v[208:209]
	s_add_i32 m0, s57, 0xe000
	s_nop 0
	global_load_lds_dwordx4 v[224:225], off
	s_waitcnt vmcnt(8)
	s_waitcnt lgkmcnt(0)
	s_barrier
	s_setprio 1
	v_mfma_f32_16x16x32_bf16 v[172:175], v[44:47], v[88:91], 0
	v_mfma_f32_16x16x32_bf16 v[164:167], v[52:55], v[88:91], 0
	v_mfma_f32_16x16x32_bf16 v[156:159], v[44:47], v[96:99], 0
	v_mfma_f32_16x16x32_bf16 v[148:151], v[52:55], v[96:99], 0
	v_mfma_f32_16x16x32_bf16 v[140:143], v[44:47], v[176:179], 0
	v_mfma_f32_16x16x32_bf16 v[132:135], v[52:55], v[176:179], 0
	v_mfma_f32_16x16x32_bf16 v[124:127], v[44:47], v[216:219], 0
	v_mfma_f32_16x16x32_bf16 v[120:123], v[52:55], v[216:219], 0
	v_mfma_f32_16x16x32_bf16 v[172:175], v[48:51], v[92:95], v[172:175]
	v_mfma_f32_16x16x32_bf16 v[164:167], v[56:59], v[92:95], v[164:167]
	v_mfma_f32_16x16x32_bf16 v[156:159], v[48:51], v[100:103], v[156:159]
	v_mfma_f32_16x16x32_bf16 v[148:151], v[56:59], v[100:103], v[148:151]
	v_mfma_f32_16x16x32_bf16 v[140:143], v[48:51], v[212:215], v[140:143]
	v_mfma_f32_16x16x32_bf16 v[132:135], v[56:59], v[212:215], v[132:135]
	v_mfma_f32_16x16x32_bf16 v[124:127], v[48:51], v[220:223], v[124:127]
	v_mfma_f32_16x16x32_bf16 v[120:123], v[56:59], v[220:223], v[120:123]
	v_mfma_f32_16x16x32_bf16 v[168:171], v[60:63], v[88:91], 0
	v_mfma_f32_16x16x32_bf16 v[88:91], v[80:83], v[88:91], 0
	v_mfma_f32_16x16x32_bf16 v[168:171], v[64:67], v[92:95], v[168:171]
	v_mfma_f32_16x16x32_bf16 v[88:91], v[84:87], v[92:95], v[88:91]
	v_mfma_f32_16x16x32_bf16 v[92:95], v[60:63], v[96:99], 0
	v_mfma_f32_16x16x32_bf16 v[96:99], v[80:83], v[96:99], 0
	v_mfma_f32_16x16x32_bf16 v[128:131], v[80:83], v[176:179], 0
	v_mfma_f32_16x16x32_bf16 v[116:119], v[60:63], v[216:219], 0
	v_mfma_f32_16x16x32_bf16 v[112:115], v[80:83], v[216:219], 0
	v_mfma_f32_16x16x32_bf16 v[92:95], v[64:67], v[100:103], v[92:95]
	v_mfma_f32_16x16x32_bf16 v[96:99], v[84:87], v[100:103], v[96:99]
	v_mfma_f32_16x16x32_bf16 v[100:103], v[60:63], v[176:179], 0
	v_mfma_f32_16x16x32_bf16 v[128:131], v[84:87], v[212:215], v[128:131]
	v_mfma_f32_16x16x32_bf16 v[116:119], v[64:67], v[220:223], v[116:119]
	v_mfma_f32_16x16x32_bf16 v[112:115], v[84:87], v[220:223], v[112:115]
	v_mfma_f32_16x16x32_bf16 v[100:103], v[64:67], v[212:215], v[100:103]
	s_setprio 0
	s_barrier
	s_add_i32 s75, s68, s56
	v_lshl_add_u64 v[232:233], s[48:49], 0, v[182:183]
	s_mov_b32 m0, s75
	ds_read_b128 v[136:139], v199 offset:16384
	ds_read_b128 v[144:147], v199 offset:17408
	ds_read_b128 v[152:155], v199 offset:18432
	ds_read_b128 v[160:163], v199 offset:19456
	ds_read_b128 v[176:179], v199 offset:20480
	ds_read_b128 v[212:215], v199 offset:21504
	ds_read_b128 v[216:219], v199 offset:22528
	ds_read_b128 v[220:223], v199 offset:23552
	global_load_lds_dwordx4 v[232:233], off
	s_add_i32 m0, s75, 0x2000
	s_add_u32 s76, s48, 0x80000
	v_lshl_add_u64 v[234:235], s[48:49], 0, v[186:187]
	s_addc_u32 s77, s49, 0
	s_add_i32 s75, s69, s56
	global_load_lds_dwordx4 v[234:235], off
	v_lshl_add_u64 v[224:225], s[76:77], 0, v[182:183]
	s_mov_b32 m0, s75
	v_lshl_add_u64 v[236:237], s[50:51], 0, v[180:181]
	global_load_lds_dwordx4 v[224:225], off
	v_lshl_add_u64 v[224:225], s[76:77], 0, v[186:187]
	s_add_i32 m0, s75, 0x2000
	v_lshl_add_u64 v[238:239], s[50:51], 0, v[184:185]
	global_load_lds_dwordx4 v[224:225], off
	s_mov_b32 m0, s57
	s_nop 0
	global_load_lds_dwordx4 v[236:237], off
	s_mov_b32 m0, s58
	s_nop 0
	global_load_lds_dwordx4 v[238:239], off
	s_waitcnt vmcnt(8)
	s_waitcnt lgkmcnt(0)
	s_barrier
; #define PG8_STAGE(bufoff, gbase, voff) do { _Pragma("unroll") for (int _i = 0; _i < 2; ++_i) \
;         __builtin_amdgcn_global_load_lds((const unsigned*)((const char*)(gbase) + (voff)[_i]), (PG8_LAS unsigned*)(lds + (bufoff) + ldsw + _i * 8192), 16, 0, 0); } while (0)
; #define PG8_LDA(dst, b, h) do { _Pragma("unroll") for (int m = 0; m < 4; ++m) _Pragma("unroll") for (int k = 0; k < 2; ++k) dst[m][k] = *(const PG8_LAS bf16x8*)(lds + PG8_SA(b, h) + aoff + m * 2048 + k * 1024); } while (0)
; #define PG8_LDB(dst, b, h) do { _Pragma("unroll") for (int n = 0; n < 2; ++n) _Pragma("unroll") for (int k = 0; k < 2; ++k) dst[n][k] = *(const PG8_LAS bf16x8*)(lds + PG8_SB(b, h) + boff + n * 2048 + k * 1024); } while (0)
; #define PG8_MMA(ai, bj, At, Bt) do { __builtin_amdgcn_s_setprio(1); _Pragma("unroll") for (int m = 0; m < 4; ++m) _Pragma("unroll") for (int n = 0; n < 2; ++n) _Pragma("unroll") for (int k = 0; k < 2; ++k) \
;         acc[ai][bj][m][n] = __builtin_amdgcn_mfma_f32_16x16x32_bf16(Bt[n][k], At[m][k], acc[ai][bj][m][n], 0, 0, 0); __builtin_amdgcn_s_setprio(0); } while (0)
; #define PG8_WAIT_V(n) asm volatile("s_waitcnt vmcnt(" #n ")" ::: "memory")
; #define PG8_WAIT_L(n) asm volatile("s_waitcnt lgkmcnt(" #n ")" ::: "memory")
; #define PG8_BAR __builtin_amdgcn_s_barrier()
; #define PG8_SCHED __builtin_amdgcn_sched_barrier(0)
; template <class Epi, class Sched, bool ALIGN_EPI = false, bool SP2 = false>
; __device__ __forceinline__ void gemm_phase(PG8_LAS unsigned char* lds, const Gemm g, const Sched& S, const Epi& E, const int wave_in) {
;     ...
;             PG8_WAIT_V(8); PG8_WAIT_L(0); PG8_BAR; PG8_MMA(1, 0, At, B0); PG8_MMA(1, 1, At, B1); PG8_BAR; PG8_SCHED;
;             PG8_LDB(B0, 1, 0); PG8_LDB(B1, 1, 1); PG8_SCHED; PG8_LDA(At, 1, 0); PG8_STAGE(PG8_SA(0, 1), a2 + hstepA, voffA);
;             PG8_WAIT_V(8); PG8_WAIT_L(0); PG8_BAR; PG8_MMA(0, 0, At, B0); PG8_MMA(0, 1, At, B1); PG8_BAR; PG8_SCHED;
	s_setprio 1
	v_mfma_f32_16x16x32_bf16 v[108:111], v[44:47], v[136:139], 0
	v_mfma_f32_16x16x32_bf16 v[76:79], v[52:55], v[136:139], 0
	v_mfma_f32_16x16x32_bf16 v[68:71], v[44:47], v[152:155], 0
	v_mfma_f32_16x16x32_bf16 v[36:39], v[52:55], v[152:155], 0
	v_mfma_f32_16x16x32_bf16 v[28:31], v[44:47], v[176:179], 0
	v_mfma_f32_16x16x32_bf16 v[20:23], v[52:55], v[176:179], 0
	v_mfma_f32_16x16x32_bf16 v[12:15], v[44:47], v[216:219], 0
	v_mfma_f32_16x16x32_bf16 v[8:11], v[52:55], v[216:219], 0
	v_mfma_f32_16x16x32_bf16 v[108:111], v[48:51], v[144:147], v[108:111]
	v_mfma_f32_16x16x32_bf16 v[76:79], v[56:59], v[144:147], v[76:79]
	v_mfma_f32_16x16x32_bf16 v[68:71], v[48:51], v[160:163], v[68:71]
	v_mfma_f32_16x16x32_bf16 v[36:39], v[56:59], v[160:163], v[36:39]
	v_mfma_f32_16x16x32_bf16 v[28:31], v[48:51], v[212:215], v[28:31]
	v_mfma_f32_16x16x32_bf16 v[20:23], v[56:59], v[212:215], v[20:23]
	v_mfma_f32_16x16x32_bf16 v[12:15], v[48:51], v[220:223], v[12:15]
	v_mfma_f32_16x16x32_bf16 v[8:11], v[56:59], v[220:223], v[8:11]
	v_mfma_f32_16x16x32_bf16 v[40:43], v[60:63], v[152:155], 0
	v_mfma_f32_16x16x32_bf16 v[32:35], v[80:83], v[152:155], 0
	v_mfma_f32_16x16x32_bf16 v[24:27], v[60:63], v[176:179], 0
	v_mfma_f32_16x16x32_bf16 v[16:19], v[80:83], v[176:179], 0
	v_mfma_f32_16x16x32_bf16 v[4:7], v[60:63], v[216:219], 0
	v_mfma_f32_16x16x32_bf16 v[0:3], v[80:83], v[216:219], 0
	v_mfma_f32_16x16x32_bf16 v[44:47], v[60:63], v[136:139], 0
	v_mfma_f32_16x16x32_bf16 v[48:51], v[80:83], v[136:139], 0
	v_mfma_f32_16x16x32_bf16 v[40:43], v[64:67], v[160:163], v[40:43]
	v_mfma_f32_16x16x32_bf16 v[32:35], v[84:87], v[160:163], v[32:35]
	v_mfma_f32_16x16x32_bf16 v[24:27], v[64:67], v[212:215], v[24:27]
	v_mfma_f32_16x16x32_bf16 v[16:19], v[84:87], v[212:215], v[16:19]
	v_mfma_f32_16x16x32_bf16 v[4:7], v[64:67], v[220:223], v[4:7]
	v_mfma_f32_16x16x32_bf16 v[0:3], v[84:87], v[220:223], v[0:3]
	v_mfma_f32_16x16x32_bf16 v[44:47], v[64:67], v[144:147], v[44:47]
	v_mfma_f32_16x16x32_bf16 v[48:51], v[84:87], v[144:147], v[48:51]
	s_setprio 0
	s_barrier
	s_add_i32 s75, 0, 0x18000
	s_add_i32 s76, 0, 0x1c000
	v_add_u32_e32 v64, s75, v195
	v_add_u32_e32 v72, s76, v195
	ds_read_b128 v[52:55], v64
	ds_read_b128 v[56:59], v64 offset:1024
	ds_read_b128 v[60:63], v64 offset:2048
	ds_read_b128 v[64:67], v64 offset:3072
	ds_read_b128 v[80:83], v72
	ds_read_b128 v[84:87], v72 offset:1024
	ds_read_b128 v[176:179], v72 offset:2048
	ds_read_b128 v[212:215], v72 offset:3072
	s_add_u32 s50, s50, 0x80000
	s_addc_u32 s51, s51, 0
	s_mov_b32 m0, s59
	v_lshl_add_u64 v[152:153], s[50:51], 0, v[180:181]
	ds_read_b128 v[72:75], v199 offset:32768
	ds_read_b128 v[104:107], v199 offset:33792
	ds_read_b128 v[136:139], v199 offset:34816
	ds_read_b128 v[144:147], v199 offset:35840
	ds_read_b128 v[216:219], v199 offset:36864
	ds_read_b128 v[220:223], v199 offset:37888
	ds_read_b128 v[224:227], v199 offset:38912
	ds_read_b128 v[228:231], v199 offset:39936
	global_load_lds_dwordx4 v[152:153], off
	v_lshl_add_u64 v[152:153], s[50:51], 0, v[184:185]
	s_mov_b32 m0, s60
	s_nop 0
	global_load_lds_dwordx4 v[152:153], off
	s_waitcnt vmcnt(8)
	s_waitcnt lgkmcnt(0)
	s_barrier
	s_setprio 1
	v_mfma_f32_16x16x32_bf16 v[152:155], v[52:55], v[72:75], v[172:175]
	v_mfma_f32_16x16x32_bf16 v[172:175], v[56:59], v[104:107], v[152:155]
	v_mfma_f32_16x16x32_bf16 v[152:155], v[60:63], v[72:75], v[164:167]
	v_mfma_f32_16x16x32_bf16 v[164:167], v[64:67], v[104:107], v[152:155]
	v_mfma_f32_16x16x32_bf16 v[152:155], v[52:55], v[136:139], v[156:159]
	v_mfma_f32_16x16x32_bf16 v[148:151], v[60:63], v[136:139], v[148:151]
	v_mfma_f32_16x16x32_bf16 v[140:143], v[52:55], v[216:219], v[140:143]
	v_mfma_f32_16x16x32_bf16 v[132:135], v[60:63], v[216:219], v[132:135]
	v_mfma_f32_16x16x32_bf16 v[124:127], v[52:55], v[224:227], v[124:127]
	v_mfma_f32_16x16x32_bf16 v[120:123], v[60:63], v[224:227], v[120:123]
	v_mfma_f32_16x16x32_bf16 v[156:159], v[56:59], v[144:147], v[152:155]
	v_mfma_f32_16x16x32_bf16 v[148:151], v[64:67], v[144:147], v[148:151]
	v_mfma_f32_16x16x32_bf16 v[140:143], v[56:59], v[220:223], v[140:143]
	v_mfma_f32_16x16x32_bf16 v[132:135], v[64:67], v[220:223], v[132:135]
	v_mfma_f32_16x16x32_bf16 v[124:127], v[56:59], v[228:231], v[124:127]
	v_mfma_f32_16x16x32_bf16 v[120:123], v[64:67], v[228:231], v[120:123]
	v_mfma_f32_16x16x32_bf16 v[152:155], v[80:83], v[72:75], v[168:171]
	v_mfma_f32_16x16x32_bf16 v[72:75], v[176:179], v[72:75], v[88:91]
	v_mfma_f32_16x16x32_bf16 v[160:163], v[212:215], v[104:107], v[72:75]
	v_mfma_f32_16x16x32_bf16 v[72:75], v[80:83], v[136:139], v[92:95]
	v_mfma_f32_16x16x32_bf16 v[168:171], v[84:87], v[104:107], v[152:155]
	v_mfma_f32_16x16x32_bf16 v[152:155], v[84:87], v[144:147], v[72:75]
	v_mfma_f32_16x16x32_bf16 v[72:75], v[176:179], v[136:139], v[96:99]
	v_mfma_f32_16x16x32_bf16 v[144:147], v[212:215], v[144:147], v[72:75]
	v_mfma_f32_16x16x32_bf16 v[72:75], v[80:83], v[216:219], v[100:103]
	v_mfma_f32_16x16x32_bf16 v[136:139], v[84:87], v[220:223], v[72:75]
	v_mfma_f32_16x16x32_bf16 v[72:75], v[176:179], v[216:219], v[128:131]
	v_mfma_f32_16x16x32_bf16 v[128:131], v[212:215], v[220:223], v[72:75]
	v_mfma_f32_16x16x32_bf16 v[72:75], v[80:83], v[224:227], v[116:119]
	v_mfma_f32_16x16x32_bf16 v[116:119], v[84:87], v[228:231], v[72:75]
	v_mfma_f32_16x16x32_bf16 v[72:75], v[176:179], v[224:227], v[112:115]
	v_mfma_f32_16x16x32_bf16 v[112:115], v[212:215], v[228:231], v[72:75]
	s_setprio 0
	s_barrier
; #define PG8_STAGE(bufoff, gbase, voff) do { _Pragma("unroll") for (int _i = 0; _i < 2; ++_i) \
;         __builtin_amdgcn_global_load_lds((const unsigned*)((const char*)(gbase) + (voff)[_i]), (PG8_LAS unsigned*)(lds + (bufoff) + ldsw + _i * 8192), 16, 0, 0); } while (0)
; #define PG8_LDA(dst, b, h) do { _Pragma("unroll") for (int m = 0; m < 4; ++m) _Pragma("unroll") for (int k = 0; k < 2; ++k) dst[m][k] = *(const PG8_LAS bf16x8*)(lds + PG8_SA(b, h) + aoff + m * 2048 + k * 1024); } while (0)
; #define PG8_MMA(ai, bj, At, Bt) do { __builtin_amdgcn_s_setprio(1); _Pragma("unroll") for (int m = 0; m < 4; ++m) _Pragma("unroll") for (int n = 0; n < 2; ++n) _Pragma("unroll") for (int k = 0; k < 2; ++k) \
;         acc[ai][bj][m][n] = __builtin_amdgcn_mfma_f32_16x16x32_bf16(Bt[n][k], At[m][k], acc[ai][bj][m][n], 0, 0, 0); __builtin_amdgcn_s_setprio(0); } while (0)
; #define PG8_WAIT_V(n) asm volatile("s_waitcnt vmcnt(" #n ")" ::: "memory")
; #define PG8_WAIT_L(n) asm volatile("s_waitcnt lgkmcnt(" #n ")" ::: "memory")
; #define PG8_BAR __builtin_amdgcn_s_barrier()
; #define PG8_SCHED __builtin_amdgcn_sched_barrier(0)
; template <class Epi, class Sched, bool ALIGN_EPI = false, bool SP2 = false>
; __device__ __forceinline__ void gemm_phase(PG8_LAS unsigned char* lds, const Gemm g, const Sched& S, const Epi& E, const int wave_in) {
;     ...
;             PG8_LDA(At, 1, 1); PG8_STAGE(PG8_SB(1, 0), b3, voffB); PG8_STAGE(PG8_SB(1, 1), b3 + hstepB, voffB); PG8_STAGE(PG8_SA(1, 0), a3, voffA);
;             PG8_WAIT_V(8); PG8_WAIT_L(0); PG8_BAR; PG8_MMA(1, 0, At, B0); PG8_MMA(1, 1, At, B1); PG8_BAR; PG8_SCHED;
	s_add_i32 s50, s75, s56
	v_lshl_add_u64 v[104:105], v[232:233], 0, s[22:23]
	s_mov_b32 m0, s50
	s_nop 1
	ds_read_b128 v[72:75], v199 offset:49152
	ds_read_b128 v[88:91], v199 offset:50176
	ds_read_b128 v[92:95], v199 offset:51200
	ds_read_b128 v[96:99], v199 offset:52224
	ds_read_b128 v[100:103], v199 offset:53248
	ds_read_b128 v[216:219], v199 offset:54272
	ds_read_b128 v[220:223], v199 offset:55296
	ds_read_b128 v[224:227], v199 offset:56320
	global_load_lds_dwordx4 v[104:105], off
	s_add_i32 m0, s50, 0x2000
	s_add_u32 s48, s48, 0x80080
	v_lshl_add_u64 v[104:105], v[234:235], 0, s[22:23]
	s_addc_u32 s49, s49, 0
	s_add_i32 s50, s76, s56
	global_load_lds_dwordx4 v[104:105], off
	v_lshl_add_u64 v[104:105], s[48:49], 0, v[182:183]
	s_mov_b32 m0, s50
	s_nop 0
	global_load_lds_dwordx4 v[104:105], off
	v_lshl_add_u64 v[104:105], s[48:49], 0, v[186:187]
	s_add_i32 m0, s50, 0x2000
	s_nop 0
	global_load_lds_dwordx4 v[104:105], off
	v_lshl_add_u64 v[104:105], v[236:237], 0, s[22:23]
	s_mov_b32 m0, s63
	s_nop 0
	global_load_lds_dwordx4 v[104:105], off
	v_lshl_add_u64 v[104:105], v[238:239], 0, s[22:23]
	s_mov_b32 m0, s64
	s_nop 0
	global_load_lds_dwordx4 v[104:105], off
	s_waitcnt vmcnt(8)
	s_waitcnt lgkmcnt(0)
	s_barrier
	s_setprio 1
	v_mfma_f32_16x16x32_bf16 v[104:107], v[52:55], v[72:75], v[108:111]
	v_mfma_f32_16x16x32_bf16 v[76:79], v[60:63], v[72:75], v[76:79]
	v_mfma_f32_16x16x32_bf16 v[68:71], v[52:55], v[92:95], v[68:71]
	v_mfma_f32_16x16x32_bf16 v[36:39], v[60:63], v[92:95], v[36:39]
	v_mfma_f32_16x16x32_bf16 v[28:31], v[52:55], v[100:103], v[28:31]
	v_mfma_f32_16x16x32_bf16 v[20:23], v[60:63], v[100:103], v[20:23]
	v_mfma_f32_16x16x32_bf16 v[12:15], v[52:55], v[220:223], v[12:15]
	v_mfma_f32_16x16x32_bf16 v[8:11], v[60:63], v[220:223], v[8:11]
	v_mfma_f32_16x16x32_bf16 v[108:111], v[56:59], v[88:91], v[104:107]
	v_mfma_f32_16x16x32_bf16 v[76:79], v[64:67], v[88:91], v[76:79]
	v_mfma_f32_16x16x32_bf16 v[68:71], v[56:59], v[96:99], v[68:71]
	v_mfma_f32_16x16x32_bf16 v[36:39], v[64:67], v[96:99], v[36:39]
	v_mfma_f32_16x16x32_bf16 v[28:31], v[56:59], v[216:219], v[28:31]
	v_mfma_f32_16x16x32_bf16 v[20:23], v[64:67], v[216:219], v[20:23]
	v_mfma_f32_16x16x32_bf16 v[12:15], v[56:59], v[224:227], v[12:15]
	v_mfma_f32_16x16x32_bf16 v[8:11], v[64:67], v[224:227], v[8:11]
	v_mfma_f32_16x16x32_bf16 v[44:47], v[80:83], v[72:75], v[44:47]
	v_mfma_f32_16x16x32_bf16 v[104:107], v[84:87], v[88:91], v[44:47]
	v_mfma_f32_16x16x32_bf16 v[44:47], v[176:179], v[72:75], v[48:51]
	v_mfma_f32_16x16x32_bf16 v[40:43], v[80:83], v[92:95], v[40:43]
	v_mfma_f32_16x16x32_bf16 v[32:35], v[176:179], v[92:95], v[32:35]
	v_mfma_f32_16x16x32_bf16 v[24:27], v[80:83], v[100:103], v[24:27]
	v_mfma_f32_16x16x32_bf16 v[16:19], v[176:179], v[100:103], v[16:19]
	v_mfma_f32_16x16x32_bf16 v[4:7], v[80:83], v[220:223], v[4:7]
	v_mfma_f32_16x16x32_bf16 v[0:3], v[176:179], v[220:223], v[0:3]
	v_mfma_f32_16x16x32_bf16 v[72:75], v[212:215], v[88:91], v[44:47]
	v_mfma_f32_16x16x32_bf16 v[40:43], v[84:87], v[96:99], v[40:43]
	v_mfma_f32_16x16x32_bf16 v[32:35], v[212:215], v[96:99], v[32:35]
	v_mfma_f32_16x16x32_bf16 v[24:27], v[84:87], v[216:219], v[24:27]
	v_mfma_f32_16x16x32_bf16 v[16:19], v[212:215], v[216:219], v[16:19]
	v_mfma_f32_16x16x32_bf16 v[4:7], v[84:87], v[224:227], v[4:7]
	v_mfma_f32_16x16x32_bf16 v[0:3], v[212:215], v[224:227], v[0:3]
	s_setprio 0
	s_barrier
	s_add_i32 s74, s74, 2
	s_add_u32 s46, s46, 0x100
	s_addc_u32 s47, s47, 0
	s_add_u32 s72, s72, 0x100
	s_addc_u32 s73, s73, 0
	s_cmp_gt_u32 s74, 29
	s_cbranch_scc0 .LBB0_1951
	s_branch .Lkx_22

;     __host__ __device__ bool next(int i, Unit& u) const { const bool ok = StaticOrder::next(i, u); u.pm = 0; u.pn = 0; return ok; }
; #define PG8_STAGE(bufoff, gbase, voff) do { _Pragma("unroll") for (int _i = 0; _i < 2; ++_i) \
;         __builtin_amdgcn_global_load_lds((const unsigned*)((const char*)(gbase) + (voff)[_i]), (PG8_LAS unsigned*)(lds + (bufoff) + ldsw + _i * 8192), 16, 0, 0); } while (0)
; #define PG8_LDA(dst, b, h) do { _Pragma("unroll") for (int m = 0; m < 4; ++m) _Pragma("unroll") for (int k = 0; k < 2; ++k) dst[m][k] = *(const PG8_LAS bf16x8*)(lds + PG8_SA(b, h) + aoff + m * 2048 + k * 1024); } while (0)
; #define PG8_LDB(dst, b, h) do { _Pragma("unroll") for (int n = 0; n < 2; ++n) _Pragma("unroll") for (int k = 0; k < 2; ++k) dst[n][k] = *(const PG8_LAS bf16x8*)(lds + PG8_SB(b, h) + boff + n * 2048 + k * 1024); } while (0)
; #define PG8_WAIT_V(n) asm volatile("s_waitcnt vmcnt(" #n ")" ::: "memory")
; #define PG8_BAR __builtin_amdgcn_s_barrier()
; template <class Epi, class Sched, bool ALIGN_EPI = false, bool SP2 = false>
; __device__ __forceinline__ void gemm_phase(PG8_LAS unsigned char* lds, const Gemm g, const Sched& S, const Epi& E, const int wave_in) {
;     ...
;         const bool has_next = S.next(ui + 1, nxt);
;         const char* nA = has_next ? (const char*)g.A + (size_t)nxt.pm * tstepA : cA; const char* nB = has_next ? (const char*)g.Bt + (size_t)nxt.pn * tstepB : cB;
;         for (int t = 0; t < nt; t += 2) {
;             const bool last = (t == nt - 2);
;             const char* a1 = cA + (size_t)(t + 1) * kstep;
;             const char* a2 = last ? nA : cA + (size_t)(t + 2) * kstep; const char* b2 = last ? nB : cB + (size_t)(t + 2) * kstep;
;             const char* a3 = a2 + kstep; const char* b3 = b2 + kstep;
;             if (last && has_next) S.a_ready(nxt);
;             if constexpr (SP2) {
;             PG8_LDB(B0, 0, 0); PG8_LDB(B1, 0, 1); PG8_SCHED; PG8_LDA(At, 0, 0); PG8_STAGE(PG8_SA(1, 1), a1 + hstepA, voffA);
;             PG8_WAIT_V(8); PG8_WAIT_L(0); PG8_BAR; PG8_MMA(0, 0, At, B0); PG8_MMA(0, 1, At, B1); PG8_BAR; PG8_SCHED;
;             PG8_LDA(At, 0, 1); PG8_STAGE(PG8_SB(0, 0), b2, voffB); PG8_STAGE(PG8_SB(0, 1), b2 + hstepB, voffB); PG8_STAGE(PG8_SA(0, 0), a2, voffA);
;             PG8_WAIT_V(8); PG8_WAIT_L(0); PG8_BAR; PG8_MMA(1, 0, At, B0); PG8_MMA(1, 1, At, B1); PG8_BAR; PG8_SCHED;
.LBB0_2106:
	s_add_u32 s21, s24, 0x100
	v_mov_b32_e32 v0, 0
	s_addc_u32 s58, s25, 0
	s_mov_b32 s59, -2
	s_waitcnt vmcnt(0)
	ds_read_b128 v[128:131], v214
	ds_read_b128 v[132:135], v214 offset:1024
	ds_read_b128 v[136:139], v214 offset:2048
	ds_read_b128 v[140:143], v214 offset:3072
	ds_read_b128 v[162:165], v215
	ds_read_b128 v[166:169], v215 offset:1024
	ds_read_b128 v[170:173], v215 offset:2048
	ds_read_b128 v[174:177], v215 offset:3072
	s_add_u32 s24, s22, 0x100
	s_addc_u32 s25, s23, 0
	s_cmpk_eq_i32 s59, 0x52
	s_cselect_b32 s29, s5, s25
	s_cselect_b32 s28, s4, s24
	s_cselect_b32 s27, s19, s58
	s_cselect_b32 s26, s18, s21
	v_lshl_add_u64 v[210:211], s[22:23], 0, v[154:155]
	s_add_i32 m0, s39, 0xc000
	ds_read_b128 v[178:181], v216
	ds_read_b128 v[182:185], v216 offset:1024
	ds_read_b128 v[186:189], v216 offset:2048
	ds_read_b128 v[190:193], v216 offset:3072
	ds_read_b128 v[194:197], v216 offset:4096
	ds_read_b128 v[198:201], v216 offset:5120
	ds_read_b128 v[202:205], v216 offset:6144
	ds_read_b128 v[206:209], v216 offset:7168
	global_load_lds_dwordx4 v[210:211], off
	v_lshl_add_u64 v[210:211], s[22:23], 0, v[156:157]
	s_add_i32 m0, s39, 0xe000
	s_nop 0
	global_load_lds_dwordx4 v[210:211], off
	s_waitcnt vmcnt(8)
	s_waitcnt lgkmcnt(0)
	s_barrier
	s_setprio 1
	v_mfma_f32_16x16x32_bf16 v[124:127], v[128:131], v[178:181], 0
	v_mfma_f32_16x16x32_bf16 v[120:123], v[136:139], v[178:181], 0
	v_mfma_f32_16x16x32_bf16 v[112:115], v[128:131], v[186:189], 0
	v_mfma_f32_16x16x32_bf16 v[104:107], v[136:139], v[186:189], 0
	v_mfma_f32_16x16x32_bf16 v[100:103], v[128:131], v[194:197], 0
	v_mfma_f32_16x16x32_bf16 v[96:99], v[136:139], v[194:197], 0
	v_mfma_f32_16x16x32_bf16 v[76:79], v[128:131], v[202:205], 0
	v_mfma_f32_16x16x32_bf16 v[72:75], v[136:139], v[202:205], 0
	v_mfma_f32_16x16x32_bf16 v[124:127], v[132:135], v[182:185], v[124:127]
	v_mfma_f32_16x16x32_bf16 v[120:123], v[140:143], v[182:185], v[120:123]
	v_mfma_f32_16x16x32_bf16 v[112:115], v[132:135], v[190:193], v[112:115]
	v_mfma_f32_16x16x32_bf16 v[104:107], v[140:143], v[190:193], v[104:107]
	v_mfma_f32_16x16x32_bf16 v[100:103], v[132:135], v[198:201], v[100:103]
	v_mfma_f32_16x16x32_bf16 v[96:99], v[140:143], v[198:201], v[96:99]
	v_mfma_f32_16x16x32_bf16 v[76:79], v[132:135], v[206:209], v[76:79]
	v_mfma_f32_16x16x32_bf16 v[72:75], v[140:143], v[206:209], v[72:75]
	v_mfma_f32_16x16x32_bf16 v[116:119], v[162:165], v[178:181], 0
	v_mfma_f32_16x16x32_bf16 v[108:111], v[170:173], v[178:181], 0
	v_mfma_f32_16x16x32_bf16 v[92:95], v[162:165], v[186:189], 0
	v_mfma_f32_16x16x32_bf16 v[88:91], v[170:173], v[186:189], 0
	v_mfma_f32_16x16x32_bf16 v[84:87], v[162:165], v[194:197], 0
	v_mfma_f32_16x16x32_bf16 v[80:83], v[170:173], v[194:197], 0
	v_mfma_f32_16x16x32_bf16 v[68:71], v[162:165], v[202:205], 0
	v_mfma_f32_16x16x32_bf16 v[64:67], v[170:173], v[202:205], 0
	v_mfma_f32_16x16x32_bf16 v[116:119], v[166:169], v[182:185], v[116:119]
	v_mfma_f32_16x16x32_bf16 v[108:111], v[174:177], v[182:185], v[108:111]
	v_mfma_f32_16x16x32_bf16 v[92:95], v[166:169], v[190:193], v[92:95]
	v_mfma_f32_16x16x32_bf16 v[88:91], v[174:177], v[190:193], v[88:91]
	v_mfma_f32_16x16x32_bf16 v[84:87], v[166:169], v[198:201], v[84:87]
	v_mfma_f32_16x16x32_bf16 v[80:83], v[174:177], v[198:201], v[80:83]
	v_mfma_f32_16x16x32_bf16 v[68:71], v[166:169], v[206:209], v[68:71]
	v_mfma_f32_16x16x32_bf16 v[64:67], v[174:177], v[206:209], v[64:67]
	s_setprio 0
	s_barrier
	s_add_i32 s22, s49, s36
	v_lshl_add_u64 v[210:211], s[26:27], 0, v[148:149]
	s_mov_b32 m0, s22
	ds_read_b128 v[178:181], v216 offset:16384
	ds_read_b128 v[182:185], v216 offset:17408
	ds_read_b128 v[186:189], v216 offset:18432
	ds_read_b128 v[190:193], v216 offset:19456
	ds_read_b128 v[194:197], v216 offset:20480
	ds_read_b128 v[198:201], v216 offset:21504
	ds_read_b128 v[202:205], v216 offset:22528
	ds_read_b128 v[206:209], v216 offset:23552
	global_load_lds_dwordx4 v[210:211], off
	s_add_i32 m0, s22, 0x2000
	s_add_u32 s22, s26, 0x158000
	v_lshl_add_u64 v[218:219], s[26:27], 0, v[144:145]
	s_addc_u32 s23, s27, 0
	s_add_i32 s60, s50, s36
	global_load_lds_dwordx4 v[218:219], off
	v_lshl_add_u64 v[220:221], s[22:23], 0, v[148:149]
	s_mov_b32 m0, s60
	v_lshl_add_u64 v[222:223], s[28:29], 0, v[146:147]
	global_load_lds_dwordx4 v[220:221], off
	v_lshl_add_u64 v[220:221], s[22:23], 0, v[144:145]
	s_add_i32 m0, s60, 0x2000
	s_nop 0
	global_load_lds_dwordx4 v[220:221], off
	v_lshl_add_u64 v[220:221], s[28:29], 0, v[150:151]
	s_mov_b32 m0, s39
	s_nop 0
	global_load_lds_dwordx4 v[220:221], off
	s_mov_b32 m0, s40
	s_nop 0
	global_load_lds_dwordx4 v[222:223], off
	s_waitcnt vmcnt(8)
	s_waitcnt lgkmcnt(0)
	s_barrier
; #define PG8_STAGE(bufoff, gbase, voff) do { _Pragma("unroll") for (int _i = 0; _i < 2; ++_i) \
;         __builtin_amdgcn_global_load_lds((const unsigned*)((const char*)(gbase) + (voff)[_i]), (PG8_LAS unsigned*)(lds + (bufoff) + ldsw + _i * 8192), 16, 0, 0); } while (0)
; #define PG8_LDA(dst, b, h) do { _Pragma("unroll") for (int m = 0; m < 4; ++m) _Pragma("unroll") for (int k = 0; k < 2; ++k) dst[m][k] = *(const PG8_LAS bf16x8*)(lds + PG8_SA(b, h) + aoff + m * 2048 + k * 1024); } while (0)
; #define PG8_LDB(dst, b, h) do { _Pragma("unroll") for (int n = 0; n < 2; ++n) _Pragma("unroll") for (int k = 0; k < 2; ++k) dst[n][k] = *(const PG8_LAS bf16x8*)(lds + PG8_SB(b, h) + boff + n * 2048 + k * 1024); } while (0)
; #define PG8_MMA(ai, bj, At, Bt) do { __builtin_amdgcn_s_setprio(1); _Pragma("unroll") for (int m = 0; m < 4; ++m) _Pragma("unroll") for (int n = 0; n < 2; ++n) _Pragma("unroll") for (int k = 0; k < 2; ++k) \
;         acc[ai][bj][m][n] = __builtin_amdgcn_mfma_f32_16x16x32_bf16(Bt[n][k], At[m][k], acc[ai][bj][m][n], 0, 0, 0); __builtin_amdgcn_s_setprio(0); } while (0)
; #define PG8_WAIT_V(n) asm volatile("s_waitcnt vmcnt(" #n ")" ::: "memory")
; #define PG8_WAIT_L(n) asm volatile("s_waitcnt lgkmcnt(" #n ")" ::: "memory")
; #define PG8_BAR __builtin_amdgcn_s_barrier()
; #define PG8_SCHED __builtin_amdgcn_sched_barrier(0)
; template <class Epi, class Sched, bool ALIGN_EPI = false, bool SP2 = false>
; __device__ __forceinline__ void gemm_phase(PG8_LAS unsigned char* lds, const Gemm g, const Sched& S, const Epi& E, const int wave_in) {
;     ...
;             PG8_WAIT_V(8); PG8_WAIT_L(0); PG8_BAR; PG8_MMA(0, 0, At, B0); PG8_MMA(0, 1, At, B1); PG8_BAR; PG8_SCHED;
;             PG8_LDA(At, 0, 1); PG8_STAGE(PG8_SB(0, 0), b2, voffB); PG8_STAGE(PG8_SB(0, 1), b2 + hstepB, voffB); PG8_STAGE(PG8_SA(0, 0), a2, voffA);
;             PG8_WAIT_V(8); PG8_WAIT_L(0); PG8_BAR; PG8_MMA(1, 0, At, B0); PG8_MMA(1, 1, At, B1); PG8_BAR; PG8_SCHED;
;             PG8_LDB(B0, 1, 0); PG8_LDB(B1, 1, 1); PG8_SCHED; PG8_LDA(At, 1, 0); PG8_STAGE(PG8_SA(0, 1), a2 + hstepA, voffA);
;             PG8_WAIT_V(8); PG8_WAIT_L(0); PG8_BAR; PG8_MMA(0, 0, At, B0); PG8_MMA(0, 1, At, B1); PG8_BAR; PG8_SCHED;
	s_setprio 1
	v_mfma_f32_16x16x32_bf16 v[60:63], v[128:131], v[178:181], 0
	v_mfma_f32_16x16x32_bf16 v[56:59], v[136:139], v[178:181], 0
	v_mfma_f32_16x16x32_bf16 v[48:51], v[128:131], v[186:189], 0
	v_mfma_f32_16x16x32_bf16 v[40:43], v[136:139], v[186:189], 0
	v_mfma_f32_16x16x32_bf16 v[32:35], v[128:131], v[194:197], 0
	v_mfma_f32_16x16x32_bf16 v[24:27], v[136:139], v[194:197], 0
	v_mfma_f32_16x16x32_bf16 v[16:19], v[128:131], v[202:205], 0
	v_mfma_f32_16x16x32_bf16 v[8:11], v[136:139], v[202:205], 0
	v_mfma_f32_16x16x32_bf16 v[60:63], v[132:135], v[182:185], v[60:63]
	v_mfma_f32_16x16x32_bf16 v[56:59], v[140:143], v[182:185], v[56:59]
	v_mfma_f32_16x16x32_bf16 v[48:51], v[132:135], v[190:193], v[48:51]
	v_mfma_f32_16x16x32_bf16 v[40:43], v[140:143], v[190:193], v[40:43]
	v_mfma_f32_16x16x32_bf16 v[32:35], v[132:135], v[198:201], v[32:35]
	v_mfma_f32_16x16x32_bf16 v[24:27], v[140:143], v[198:201], v[24:27]
	v_mfma_f32_16x16x32_bf16 v[16:19], v[132:135], v[206:209], v[16:19]
	v_mfma_f32_16x16x32_bf16 v[8:11], v[140:143], v[206:209], v[8:11]
	v_mfma_f32_16x16x32_bf16 v[52:55], v[162:165], v[178:181], 0
	v_mfma_f32_16x16x32_bf16 v[44:47], v[170:173], v[178:181], 0
	v_mfma_f32_16x16x32_bf16 v[36:39], v[162:165], v[186:189], 0
	v_mfma_f32_16x16x32_bf16 v[28:31], v[170:173], v[186:189], 0
	v_mfma_f32_16x16x32_bf16 v[20:23], v[162:165], v[194:197], 0
	v_mfma_f32_16x16x32_bf16 v[12:15], v[170:173], v[194:197], 0
	v_mfma_f32_16x16x32_bf16 v[4:7], v[162:165], v[202:205], 0
	v_mfma_f32_16x16x32_bf16 v[0:3], v[170:173], v[202:205], 0
	v_mfma_f32_16x16x32_bf16 v[52:55], v[166:169], v[182:185], v[52:55]
	v_mfma_f32_16x16x32_bf16 v[44:47], v[174:177], v[182:185], v[44:47]
	v_mfma_f32_16x16x32_bf16 v[36:39], v[166:169], v[190:193], v[36:39]
	v_mfma_f32_16x16x32_bf16 v[28:31], v[174:177], v[190:193], v[28:31]
	v_mfma_f32_16x16x32_bf16 v[20:23], v[166:169], v[198:201], v[20:23]
	v_mfma_f32_16x16x32_bf16 v[12:15], v[174:177], v[198:201], v[12:15]
	v_mfma_f32_16x16x32_bf16 v[4:7], v[166:169], v[206:209], v[4:7]
	v_mfma_f32_16x16x32_bf16 v[0:3], v[174:177], v[206:209], v[0:3]
	s_setprio 0
	s_barrier
	s_add_i32 s60, 0, 0x18000
	s_add_i32 s61, 0, 0x1c000
	v_add_u32_e32 v140, s60, v212
	v_add_u32_e32 v174, s61, v212
	ds_read_b128 v[128:131], v140
	ds_read_b128 v[132:135], v140 offset:1024
	ds_read_b128 v[136:139], v140 offset:2048
	ds_read_b128 v[140:143], v140 offset:3072
	ds_read_b128 v[162:165], v174
	ds_read_b128 v[166:169], v174 offset:1024
	ds_read_b128 v[170:173], v174 offset:2048
	ds_read_b128 v[174:177], v174 offset:3072
	s_add_u32 s22, s28, 0x158000
	s_addc_u32 s23, s29, 0
	s_mov_b32 m0, s41
	v_lshl_add_u64 v[224:225], s[22:23], 0, v[150:151]
	ds_read_b128 v[178:181], v216 offset:32768
	ds_read_b128 v[182:185], v216 offset:33792
	ds_read_b128 v[186:189], v216 offset:34816
	ds_read_b128 v[190:193], v216 offset:35840
	ds_read_b128 v[194:197], v216 offset:36864
	ds_read_b128 v[198:201], v216 offset:37888
	ds_read_b128 v[202:205], v216 offset:38912
	ds_read_b128 v[206:209], v216 offset:39936
	global_load_lds_dwordx4 v[224:225], off
	v_lshl_add_u64 v[224:225], s[22:23], 0, v[146:147]
	s_mov_b32 m0, s42
	s_nop 0
	global_load_lds_dwordx4 v[224:225], off
	s_waitcnt vmcnt(8)
	s_waitcnt lgkmcnt(0)
	s_barrier
	s_setprio 1
	v_mfma_f32_16x16x32_bf16 v[124:127], v[128:131], v[178:181], v[124:127]
	v_mfma_f32_16x16x32_bf16 v[120:123], v[136:139], v[178:181], v[120:123]
	v_mfma_f32_16x16x32_bf16 v[112:115], v[128:131], v[186:189], v[112:115]
	v_mfma_f32_16x16x32_bf16 v[104:107], v[136:139], v[186:189], v[104:107]
	v_mfma_f32_16x16x32_bf16 v[100:103], v[128:131], v[194:197], v[100:103]
	v_mfma_f32_16x16x32_bf16 v[96:99], v[136:139], v[194:197], v[96:99]
	v_mfma_f32_16x16x32_bf16 v[76:79], v[128:131], v[202:205], v[76:79]
	v_mfma_f32_16x16x32_bf16 v[72:75], v[136:139], v[202:205], v[72:75]
	v_mfma_f32_16x16x32_bf16 v[124:127], v[132:135], v[182:185], v[124:127]
	v_mfma_f32_16x16x32_bf16 v[120:123], v[140:143], v[182:185], v[120:123]
	v_mfma_f32_16x16x32_bf16 v[112:115], v[132:135], v[190:193], v[112:115]
	v_mfma_f32_16x16x32_bf16 v[104:107], v[140:143], v[190:193], v[104:107]
	v_mfma_f32_16x16x32_bf16 v[100:103], v[132:135], v[198:201], v[100:103]
	v_mfma_f32_16x16x32_bf16 v[96:99], v[140:143], v[198:201], v[96:99]
	v_mfma_f32_16x16x32_bf16 v[76:79], v[132:135], v[206:209], v[76:79]
	v_mfma_f32_16x16x32_bf16 v[72:75], v[140:143], v[206:209], v[72:75]
	v_mfma_f32_16x16x32_bf16 v[116:119], v[162:165], v[178:181], v[116:119]
	v_mfma_f32_16x16x32_bf16 v[108:111], v[170:173], v[178:181], v[108:111]
	v_mfma_f32_16x16x32_bf16 v[92:95], v[162:165], v[186:189], v[92:95]
	v_mfma_f32_16x16x32_bf16 v[88:91], v[170:173], v[186:189], v[88:91]
	v_mfma_f32_16x16x32_bf16 v[84:87], v[162:165], v[194:197], v[84:87]
	v_mfma_f32_16x16x32_bf16 v[80:83], v[170:173], v[194:197], v[80:83]
	v_mfma_f32_16x16x32_bf16 v[68:71], v[162:165], v[202:205], v[68:71]
	v_mfma_f32_16x16x32_bf16 v[64:67], v[170:173], v[202:205], v[64:67]
	v_mfma_f32_16x16x32_bf16 v[116:119], v[166:169], v[182:185], v[116:119]
	v_mfma_f32_16x16x32_bf16 v[108:111], v[174:177], v[182:185], v[108:111]
	v_mfma_f32_16x16x32_bf16 v[92:95], v[166:169], v[190:193], v[92:95]
	v_mfma_f32_16x16x32_bf16 v[88:91], v[174:177], v[190:193], v[88:91]
	v_mfma_f32_16x16x32_bf16 v[84:87], v[166:169], v[198:201], v[84:87]
	v_mfma_f32_16x16x32_bf16 v[80:83], v[174:177], v[198:201], v[80:83]
	v_mfma_f32_16x16x32_bf16 v[68:71], v[166:169], v[206:209], v[68:71]
	v_mfma_f32_16x16x32_bf16 v[64:67], v[174:177], v[206:209], v[64:67]
	s_setprio 0
	s_barrier
; #define PG8_STAGE(bufoff, gbase, voff) do { _Pragma("unroll") for (int _i = 0; _i < 2; ++_i) \
;         __builtin_amdgcn_global_load_lds((const unsigned*)((const char*)(gbase) + (voff)[_i]), (PG8_LAS unsigned*)(lds + (bufoff) + ldsw + _i * 8192), 16, 0, 0); } while (0)
; #define PG8_LDA(dst, b, h) do { _Pragma("unroll") for (int m = 0; m < 4; ++m) _Pragma("unroll") for (int k = 0; k < 2; ++k) dst[m][k] = *(const PG8_LAS bf16x8*)(lds + PG8_SA(b, h) + aoff + m * 2048 + k * 1024); } while (0)
; #define PG8_LDB(dst, b, h) do { _Pragma("unroll") for (int n = 0; n < 2; ++n) _Pragma("unroll") for (int k = 0; k < 2; ++k) dst[n][k] = *(const PG8_LAS bf16x8*)(lds + PG8_SB(b, h) + boff + n * 2048 + k * 1024); } while (0)
; #define PG8_WAIT_V(n) asm volatile("s_waitcnt vmcnt(" #n ")" ::: "memory")
; #define PG8_WAIT_L(n) asm volatile("s_waitcnt lgkmcnt(" #n ")" ::: "memory")
; #define PG8_BAR __builtin_amdgcn_s_barrier()
; template <class Epi, class Sched, bool ALIGN_EPI = false, bool SP2 = false>
; __device__ __forceinline__ void gemm_phase(PG8_LAS unsigned char* lds, const Gemm g, const Sched& S, const Epi& E, const int wave_in) {
;     ...
;         for (int t = 0; t < nt; t += 2) {
;             const bool last = (t == nt - 2);
;             const char* a1 = cA + (size_t)(t + 1) * kstep;
;             const char* a2 = last ? nA : cA + (size_t)(t + 2) * kstep; const char* b2 = last ? nB : cB + (size_t)(t + 2) * kstep;
;             const char* a3 = a2 + kstep; const char* b3 = b2 + kstep;
;             if (last && has_next) S.a_ready(nxt);
;             if constexpr (SP2) {
;             PG8_LDB(B0, 0, 0); PG8_LDB(B1, 0, 1); PG8_SCHED; PG8_LDA(At, 0, 0); PG8_STAGE(PG8_SA(1, 1), a1 + hstepA, voffA);
;             PG8_WAIT_V(8); PG8_WAIT_L(0); PG8_BAR; PG8_MMA(0, 0, At, B0); PG8_MMA(0, 1, At, B1); PG8_BAR; PG8_SCHED;
;             PG8_LDA(At, 0, 1); PG8_STAGE(PG8_SB(0, 0), b2, voffB); PG8_STAGE(PG8_SB(0, 1), b2 + hstepB, voffB); PG8_STAGE(PG8_SA(0, 0), a2, voffA);
;             PG8_WAIT_V(8); PG8_WAIT_L(0); PG8_BAR; PG8_MMA(1, 0, At, B0); PG8_MMA(1, 1, At, B1); PG8_BAR; PG8_SCHED;
;     ...
;             PG8_LDA(At, 1, 1); PG8_STAGE(PG8_SB(1, 0), b3, voffB); PG8_STAGE(PG8_SB(1, 1), b3 + hstepB, voffB); PG8_STAGE(PG8_SA(1, 0), a3, voffA);
;             PG8_WAIT_V(8); PG8_WAIT_L(0); PG8_BAR; PG8_MMA(1, 0, At, B0); PG8_MMA(1, 1, At, B1); PG8_BAR; PG8_SCHED;
	s_add_i32 s22, s60, s36
	v_lshl_add_u64 v[210:211], v[210:211], 0, s[6:7]
	s_mov_b32 m0, s22
	ds_read_b128 v[178:181], v216 offset:49152
	ds_read_b128 v[182:185], v216 offset:50176
	ds_read_b128 v[186:189], v216 offset:51200
	ds_read_b128 v[190:193], v216 offset:52224
	ds_read_b128 v[194:197], v216 offset:53248
	ds_read_b128 v[198:201], v216 offset:54272
	ds_read_b128 v[202:205], v216 offset:55296
	ds_read_b128 v[206:209], v216 offset:56320
	global_load_lds_dwordx4 v[210:211], off
	s_add_i32 m0, s22, 0x2000
	s_add_u32 s22, s26, 0x158080
	v_lshl_add_u64 v[210:211], v[218:219], 0, s[6:7]
	s_addc_u32 s23, s27, 0
	s_add_i32 s26, s61, s36
	global_load_lds_dwordx4 v[210:211], off
	v_lshl_add_u64 v[210:211], s[22:23], 0, v[148:149]
	s_mov_b32 m0, s26
	s_nop 0
	global_load_lds_dwordx4 v[210:211], off
	v_lshl_add_u64 v[210:211], s[22:23], 0, v[144:145]
	s_add_i32 m0, s26, 0x2000
	s_nop 0
	global_load_lds_dwordx4 v[210:211], off
	v_lshl_add_u64 v[210:211], v[220:221], 0, s[6:7]
	s_mov_b32 m0, s46
	s_nop 0
	global_load_lds_dwordx4 v[210:211], off
	v_lshl_add_u64 v[210:211], v[222:223], 0, s[6:7]
	s_mov_b32 m0, s47
	s_nop 0
	global_load_lds_dwordx4 v[210:211], off
	s_waitcnt vmcnt(8)
	s_waitcnt lgkmcnt(0)
	s_barrier
	s_setprio 1
	v_mfma_f32_16x16x32_bf16 v[60:63], v[128:131], v[178:181], v[60:63]
	v_mfma_f32_16x16x32_bf16 v[56:59], v[136:139], v[178:181], v[56:59]
	v_mfma_f32_16x16x32_bf16 v[48:51], v[128:131], v[186:189], v[48:51]
	v_mfma_f32_16x16x32_bf16 v[40:43], v[136:139], v[186:189], v[40:43]
	v_mfma_f32_16x16x32_bf16 v[32:35], v[128:131], v[194:197], v[32:35]
	v_mfma_f32_16x16x32_bf16 v[24:27], v[136:139], v[194:197], v[24:27]
	v_mfma_f32_16x16x32_bf16 v[16:19], v[128:131], v[202:205], v[16:19]
	v_mfma_f32_16x16x32_bf16 v[8:11], v[136:139], v[202:205], v[8:11]
	v_mfma_f32_16x16x32_bf16 v[60:63], v[132:135], v[182:185], v[60:63]
	v_mfma_f32_16x16x32_bf16 v[56:59], v[140:143], v[182:185], v[56:59]
	v_mfma_f32_16x16x32_bf16 v[48:51], v[132:135], v[190:193], v[48:51]
	v_mfma_f32_16x16x32_bf16 v[40:43], v[140:143], v[190:193], v[40:43]
	v_mfma_f32_16x16x32_bf16 v[32:35], v[132:135], v[198:201], v[32:35]
	v_mfma_f32_16x16x32_bf16 v[24:27], v[140:143], v[198:201], v[24:27]
	v_mfma_f32_16x16x32_bf16 v[16:19], v[132:135], v[206:209], v[16:19]
	v_mfma_f32_16x16x32_bf16 v[8:11], v[140:143], v[206:209], v[8:11]
	v_mfma_f32_16x16x32_bf16 v[52:55], v[162:165], v[178:181], v[52:55]
	v_mfma_f32_16x16x32_bf16 v[44:47], v[170:173], v[178:181], v[44:47]
	v_mfma_f32_16x16x32_bf16 v[36:39], v[162:165], v[186:189], v[36:39]
	v_mfma_f32_16x16x32_bf16 v[28:31], v[170:173], v[186:189], v[28:31]
	v_mfma_f32_16x16x32_bf16 v[20:23], v[162:165], v[194:197], v[20:23]
	v_mfma_f32_16x16x32_bf16 v[12:15], v[170:173], v[194:197], v[12:15]
	v_mfma_f32_16x16x32_bf16 v[4:7], v[162:165], v[202:205], v[4:7]
	v_mfma_f32_16x16x32_bf16 v[0:3], v[170:173], v[202:205], v[0:3]
	v_mfma_f32_16x16x32_bf16 v[52:55], v[166:169], v[182:185], v[52:55]
	v_mfma_f32_16x16x32_bf16 v[44:47], v[174:177], v[182:185], v[44:47]
	v_mfma_f32_16x16x32_bf16 v[36:39], v[166:169], v[190:193], v[36:39]
	v_mfma_f32_16x16x32_bf16 v[28:31], v[174:177], v[190:193], v[28:31]
	v_mfma_f32_16x16x32_bf16 v[20:23], v[166:169], v[198:201], v[20:23]
	v_mfma_f32_16x16x32_bf16 v[12:15], v[174:177], v[198:201], v[12:15]
	v_mfma_f32_16x16x32_bf16 v[4:7], v[166:169], v[206:209], v[4:7]
	v_mfma_f32_16x16x32_bf16 v[0:3], v[174:177], v[206:209], v[0:3]
	s_setprio 0
	s_barrier
	s_add_i32 s59, s59, 2
	s_add_u32 s21, s21, 0x100
	s_addc_u32 s58, s58, 0
	s_cmpk_gt_u32 s59, 0x53
	s_mov_b64 s[22:23], s[24:25]
	s_cbranch_scc0 .LBB0_2107
	s_branch .Lkx_24
.LBB0_2107:
	ds_read_b128 v[128:131], v214
	ds_read_b128 v[132:135], v214 offset:1024
	ds_read_b128 v[136:139], v214 offset:2048
	ds_read_b128 v[140:143], v214 offset:3072
	ds_read_b128 v[162:165], v215
	ds_read_b128 v[166:169], v215 offset:1024
	ds_read_b128 v[170:173], v215 offset:2048
	ds_read_b128 v[174:177], v215 offset:3072
	s_add_u32 s24, s22, 0x100
	s_addc_u32 s25, s23, 0
	s_cmpk_eq_i32 s59, 0x52
	s_cselect_b32 s29, s5, s25
	s_cselect_b32 s28, s4, s24
	s_cselect_b32 s27, s19, s58
	s_cselect_b32 s26, s18, s21
	v_lshl_add_u64 v[210:211], s[22:23], 0, v[154:155]
	s_add_i32 m0, s39, 0xc000
	ds_read_b128 v[178:181], v216
	ds_read_b128 v[182:185], v216 offset:1024
	ds_read_b128 v[186:189], v216 offset:2048
	ds_read_b128 v[190:193], v216 offset:3072
	ds_read_b128 v[194:197], v216 offset:4096
	ds_read_b128 v[198:201], v216 offset:5120
	ds_read_b128 v[202:205], v216 offset:6144
	ds_read_b128 v[206:209], v216 offset:7168
	global_load_lds_dwordx4 v[210:211], off
	v_lshl_add_u64 v[210:211], s[22:23], 0, v[156:157]
	s_add_i32 m0, s39, 0xe000
	s_nop 0
	global_load_lds_dwordx4 v[210:211], off
	s_waitcnt vmcnt(8)
	s_waitcnt lgkmcnt(0)
	s_barrier
; #define PG8_STAGE(bufoff, gbase, voff) do { _Pragma("unroll") for (int _i = 0; _i < 2; ++_i) \
;         __builtin_amdgcn_global_load_lds((const unsigned*)((const char*)(gbase) + (voff)[_i]), (PG8_LAS unsigned*)(lds + (bufoff) + ldsw + _i * 8192), 16, 0, 0); } while (0)
; #define PG8_LDA(dst, b, h) do { _Pragma("unroll") for (int m = 0; m < 4; ++m) _Pragma("unroll") for (int k = 0; k < 2; ++k) dst[m][k] = *(const PG8_LAS bf16x8*)(lds + PG8_SA(b, h) + aoff + m * 2048 + k * 1024); } while (0)
; #define PG8_LDB(dst, b, h) do { _Pragma("unroll") for (int n = 0; n < 2; ++n) _Pragma("unroll") for (int k = 0; k < 2; ++k) dst[n][k] = *(const PG8_LAS bf16x8*)(lds + PG8_SB(b, h) + boff + n * 2048 + k * 1024); } while (0)
; #define PG8_MMA(ai, bj, At, Bt) do { __builtin_amdgcn_s_setprio(1); _Pragma("unroll") for (int m = 0; m < 4; ++m) _Pragma("unroll") for (int n = 0; n < 2; ++n) _Pragma("unroll") for (int k = 0; k < 2; ++k) \
;         acc[ai][bj][m][n] = __builtin_amdgcn_mfma_f32_16x16x32_bf16(Bt[n][k], At[m][k], acc[ai][bj][m][n], 0, 0, 0); __builtin_amdgcn_s_setprio(0); } while (0)
; #define PG8_WAIT_V(n) asm volatile("s_waitcnt vmcnt(" #n ")" ::: "memory")
; #define PG8_WAIT_L(n) asm volatile("s_waitcnt lgkmcnt(" #n ")" ::: "memory")
; #define PG8_BAR __builtin_amdgcn_s_barrier()
; #define PG8_SCHED __builtin_amdgcn_sched_barrier(0)
; template <class Epi, class Sched, bool ALIGN_EPI = false, bool SP2 = false>
; __device__ __forceinline__ void gemm_phase(PG8_LAS unsigned char* lds, const Gemm g, const Sched& S, const Epi& E, const int wave_in) {
;     ...
;             PG8_LDB(B0, 0, 0); PG8_LDB(B1, 0, 1); PG8_SCHED; PG8_LDA(At, 0, 0); PG8_STAGE(PG8_SA(1, 1), a1 + hstepA, voffA);
;             PG8_WAIT_V(8); PG8_WAIT_L(0); PG8_BAR; PG8_MMA(0, 0, At, B0); PG8_MMA(0, 1, At, B1); PG8_BAR; PG8_SCHED;
;             PG8_LDA(At, 0, 1); PG8_STAGE(PG8_SB(0, 0), b2, voffB); PG8_STAGE(PG8_SB(0, 1), b2 + hstepB, voffB); PG8_STAGE(PG8_SA(0, 0), a2, voffA);
;             PG8_WAIT_V(8); PG8_WAIT_L(0); PG8_BAR; PG8_MMA(1, 0, At, B0); PG8_MMA(1, 1, At, B1); PG8_BAR; PG8_SCHED;
	s_setprio 1
	v_mfma_f32_16x16x32_bf16 v[124:127], v[128:131], v[178:181], v[124:127]
	v_mfma_f32_16x16x32_bf16 v[120:123], v[136:139], v[178:181], v[120:123]
	v_mfma_f32_16x16x32_bf16 v[112:115], v[128:131], v[186:189], v[112:115]
	v_mfma_f32_16x16x32_bf16 v[104:107], v[136:139], v[186:189], v[104:107]
	v_mfma_f32_16x16x32_bf16 v[100:103], v[128:131], v[194:197], v[100:103]
	v_mfma_f32_16x16x32_bf16 v[96:99], v[136:139], v[194:197], v[96:99]
	v_mfma_f32_16x16x32_bf16 v[76:79], v[128:131], v[202:205], v[76:79]
	v_mfma_f32_16x16x32_bf16 v[72:75], v[136:139], v[202:205], v[72:75]
	v_mfma_f32_16x16x32_bf16 v[124:127], v[132:135], v[182:185], v[124:127]
	v_mfma_f32_16x16x32_bf16 v[120:123], v[140:143], v[182:185], v[120:123]
	v_mfma_f32_16x16x32_bf16 v[112:115], v[132:135], v[190:193], v[112:115]
	v_mfma_f32_16x16x32_bf16 v[104:107], v[140:143], v[190:193], v[104:107]
	v_mfma_f32_16x16x32_bf16 v[100:103], v[132:135], v[198:201], v[100:103]
	v_mfma_f32_16x16x32_bf16 v[96:99], v[140:143], v[198:201], v[96:99]
	v_mfma_f32_16x16x32_bf16 v[76:79], v[132:135], v[206:209], v[76:79]
	v_mfma_f32_16x16x32_bf16 v[72:75], v[140:143], v[206:209], v[72:75]
	v_mfma_f32_16x16x32_bf16 v[116:119], v[162:165], v[178:181], v[116:119]
	v_mfma_f32_16x16x32_bf16 v[108:111], v[170:173], v[178:181], v[108:111]
	v_mfma_f32_16x16x32_bf16 v[92:95], v[162:165], v[186:189], v[92:95]
	v_mfma_f32_16x16x32_bf16 v[88:91], v[170:173], v[186:189], v[88:91]
	v_mfma_f32_16x16x32_bf16 v[84:87], v[162:165], v[194:197], v[84:87]
	v_mfma_f32_16x16x32_bf16 v[80:83], v[170:173], v[194:197], v[80:83]
	v_mfma_f32_16x16x32_bf16 v[68:71], v[162:165], v[202:205], v[68:71]
	v_mfma_f32_16x16x32_bf16 v[64:67], v[170:173], v[202:205], v[64:67]
	v_mfma_f32_16x16x32_bf16 v[116:119], v[166:169], v[182:185], v[116:119]
	v_mfma_f32_16x16x32_bf16 v[108:111], v[174:177], v[182:185], v[108:111]
	v_mfma_f32_16x16x32_bf16 v[92:95], v[166:169], v[190:193], v[92:95]
	v_mfma_f32_16x16x32_bf16 v[88:91], v[174:177], v[190:193], v[88:91]
	v_mfma_f32_16x16x32_bf16 v[84:87], v[166:169], v[198:201], v[84:87]
	v_mfma_f32_16x16x32_bf16 v[80:83], v[174:177], v[198:201], v[80:83]
	v_mfma_f32_16x16x32_bf16 v[68:71], v[166:169], v[206:209], v[68:71]
	v_mfma_f32_16x16x32_bf16 v[64:67], v[174:177], v[206:209], v[64:67]
	s_setprio 0
	s_barrier
	s_add_i32 s22, s49, s36
	v_lshl_add_u64 v[210:211], s[26:27], 0, v[148:149]
	s_mov_b32 m0, s22
	ds_read_b128 v[178:181], v216 offset:16384
	ds_read_b128 v[182:185], v216 offset:17408
	ds_read_b128 v[186:189], v216 offset:18432
	ds_read_b128 v[190:193], v216 offset:19456
	ds_read_b128 v[194:197], v216 offset:20480
	ds_read_b128 v[198:201], v216 offset:21504
	ds_read_b128 v[202:205], v216 offset:22528
	ds_read_b128 v[206:209], v216 offset:23552
	global_load_lds_dwordx4 v[210:211], off
	s_add_i32 m0, s22, 0x2000
	s_add_u32 s22, s26, 0x158000
	v_lshl_add_u64 v[218:219], s[26:27], 0, v[144:145]
	s_addc_u32 s23, s27, 0
	s_add_i32 s60, s50, s36
	global_load_lds_dwordx4 v[218:219], off
	v_lshl_add_u64 v[220:221], s[22:23], 0, v[148:149]
	s_mov_b32 m0, s60
	v_lshl_add_u64 v[222:223], s[28:29], 0, v[146:147]
	global_load_lds_dwordx4 v[220:221], off
	v_lshl_add_u64 v[220:221], s[22:23], 0, v[144:145]
	s_add_i32 m0, s60, 0x2000
	s_nop 0
	global_load_lds_dwordx4 v[220:221], off
	v_lshl_add_u64 v[220:221], s[28:29], 0, v[150:151]
	s_mov_b32 m0, s39
	s_nop 0
	global_load_lds_dwordx4 v[220:221], off
	s_mov_b32 m0, s40
	s_nop 0
	global_load_lds_dwordx4 v[222:223], off
	s_waitcnt vmcnt(8)
	s_waitcnt lgkmcnt(0)
	s_barrier
	s_setprio 1
	v_mfma_f32_16x16x32_bf16 v[60:63], v[128:131], v[178:181], v[60:63]
	v_mfma_f32_16x16x32_bf16 v[56:59], v[136:139], v[178:181], v[56:59]
	v_mfma_f32_16x16x32_bf16 v[48:51], v[128:131], v[186:189], v[48:51]
	v_mfma_f32_16x16x32_bf16 v[40:43], v[136:139], v[186:189], v[40:43]
	v_mfma_f32_16x16x32_bf16 v[32:35], v[128:131], v[194:197], v[32:35]
	v_mfma_f32_16x16x32_bf16 v[24:27], v[136:139], v[194:197], v[24:27]
	v_mfma_f32_16x16x32_bf16 v[16:19], v[128:131], v[202:205], v[16:19]
	v_mfma_f32_16x16x32_bf16 v[8:11], v[136:139], v[202:205], v[8:11]
	v_mfma_f32_16x16x32_bf16 v[60:63], v[132:135], v[182:185], v[60:63]
	v_mfma_f32_16x16x32_bf16 v[56:59], v[140:143], v[182:185], v[56:59]
	v_mfma_f32_16x16x32_bf16 v[48:51], v[132:135], v[190:193], v[48:51]
	v_mfma_f32_16x16x32_bf16 v[40:43], v[140:143], v[190:193], v[40:43]
	v_mfma_f32_16x16x32_bf16 v[32:35], v[132:135], v[198:201], v[32:35]
	v_mfma_f32_16x16x32_bf16 v[24:27], v[140:143], v[198:201], v[24:27]
	v_mfma_f32_16x16x32_bf16 v[16:19], v[132:135], v[206:209], v[16:19]
	v_mfma_f32_16x16x32_bf16 v[8:11], v[140:143], v[206:209], v[8:11]
	v_mfma_f32_16x16x32_bf16 v[52:55], v[162:165], v[178:181], v[52:55]
	v_mfma_f32_16x16x32_bf16 v[44:47], v[170:173], v[178:181], v[44:47]
	v_mfma_f32_16x16x32_bf16 v[36:39], v[162:165], v[186:189], v[36:39]
	v_mfma_f32_16x16x32_bf16 v[28:31], v[170:173], v[186:189], v[28:31]
	v_mfma_f32_16x16x32_bf16 v[20:23], v[162:165], v[194:197], v[20:23]
	v_mfma_f32_16x16x32_bf16 v[12:15], v[170:173], v[194:197], v[12:15]
	v_mfma_f32_16x16x32_bf16 v[4:7], v[162:165], v[202:205], v[4:7]
	v_mfma_f32_16x16x32_bf16 v[0:3], v[170:173], v[202:205], v[0:3]
	v_mfma_f32_16x16x32_bf16 v[52:55], v[166:169], v[182:185], v[52:55]
	v_mfma_f32_16x16x32_bf16 v[44:47], v[174:177], v[182:185], v[44:47]
	v_mfma_f32_16x16x32_bf16 v[36:39], v[166:169], v[190:193], v[36:39]
	v_mfma_f32_16x16x32_bf16 v[28:31], v[174:177], v[190:193], v[28:31]
	v_mfma_f32_16x16x32_bf16 v[20:23], v[166:169], v[198:201], v[20:23]
	v_mfma_f32_16x16x32_bf16 v[12:15], v[174:177], v[198:201], v[12:15]
	v_mfma_f32_16x16x32_bf16 v[4:7], v[166:169], v[206:209], v[4:7]
	v_mfma_f32_16x16x32_bf16 v[0:3], v[174:177], v[206:209], v[0:3]
	s_setprio 0
	s_barrier
; #define PG8_STAGE(bufoff, gbase, voff) do { _Pragma("unroll") for (int _i = 0; _i < 2; ++_i) \
;         __builtin_amdgcn_global_load_lds((const unsigned*)((const char*)(gbase) + (voff)[_i]), (PG8_LAS unsigned*)(lds + (bufoff) + ldsw + _i * 8192), 16, 0, 0); } while (0)
; #define PG8_LDA(dst, b, h) do { _Pragma("unroll") for (int m = 0; m < 4; ++m) _Pragma("unroll") for (int k = 0; k < 2; ++k) dst[m][k] = *(const PG8_LAS bf16x8*)(lds + PG8_SA(b, h) + aoff + m * 2048 + k * 1024); } while (0)
; #define PG8_LDB(dst, b, h) do { _Pragma("unroll") for (int n = 0; n < 2; ++n) _Pragma("unroll") for (int k = 0; k < 2; ++k) dst[n][k] = *(const PG8_LAS bf16x8*)(lds + PG8_SB(b, h) + boff + n * 2048 + k * 1024); } while (0)
; #define PG8_MMA(ai, bj, At, Bt) do { __builtin_amdgcn_s_setprio(1); _Pragma("unroll") for (int m = 0; m < 4; ++m) _Pragma("unroll") for (int n = 0; n < 2; ++n) _Pragma("unroll") for (int k = 0; k < 2; ++k) \
;         acc[ai][bj][m][n] = __builtin_amdgcn_mfma_f32_16x16x32_bf16(Bt[n][k], At[m][k], acc[ai][bj][m][n], 0, 0, 0); __builtin_amdgcn_s_setprio(0); } while (0)
; #define PG8_WAIT_V(n) asm volatile("s_waitcnt vmcnt(" #n ")" ::: "memory")
; #define PG8_WAIT_L(n) asm volatile("s_waitcnt lgkmcnt(" #n ")" ::: "memory")
; #define PG8_BAR __builtin_amdgcn_s_barrier()
; #define PG8_SCHED __builtin_amdgcn_sched_barrier(0)
; template <class Epi, class Sched, bool ALIGN_EPI = false, bool SP2 = false>
; __device__ __forceinline__ void gemm_phase(PG8_LAS unsigned char* lds, const Gemm g, const Sched& S, const Epi& E, const int wave_in) {
;     ...
;             PG8_LDB(B0, 1, 0); PG8_LDB(B1, 1, 1); PG8_SCHED; PG8_LDA(At, 1, 0); PG8_STAGE(PG8_SA(0, 1), a2 + hstepA, voffA);
;             PG8_WAIT_V(8); PG8_WAIT_L(0); PG8_BAR; PG8_MMA(0, 0, At, B0); PG8_MMA(0, 1, At, B1); PG8_BAR; PG8_SCHED;
;             PG8_LDA(At, 1, 1); PG8_STAGE(PG8_SB(1, 0), b3, voffB); PG8_STAGE(PG8_SB(1, 1), b3 + hstepB, voffB); PG8_STAGE(PG8_SA(1, 0), a3, voffA);
;             PG8_WAIT_V(8); PG8_WAIT_L(0); PG8_BAR; PG8_MMA(1, 0, At, B0); PG8_MMA(1, 1, At, B1); PG8_BAR; PG8_SCHED;
	s_add_i32 s60, 0, 0x18000
	s_add_i32 s61, 0, 0x1c000
	v_add_u32_e32 v140, s60, v212
	v_add_u32_e32 v174, s61, v212
	ds_read_b128 v[128:131], v140
	ds_read_b128 v[132:135], v140 offset:1024
	ds_read_b128 v[136:139], v140 offset:2048
	ds_read_b128 v[140:143], v140 offset:3072
	ds_read_b128 v[162:165], v174
	ds_read_b128 v[166:169], v174 offset:1024
	ds_read_b128 v[170:173], v174 offset:2048
	ds_read_b128 v[174:177], v174 offset:3072
	s_add_u32 s22, s28, 0x158000
	s_addc_u32 s23, s29, 0
	s_mov_b32 m0, s41
	v_lshl_add_u64 v[224:225], s[22:23], 0, v[150:151]
	ds_read_b128 v[178:181], v216 offset:32768
	ds_read_b128 v[182:185], v216 offset:33792
	ds_read_b128 v[186:189], v216 offset:34816
	ds_read_b128 v[190:193], v216 offset:35840
	ds_read_b128 v[194:197], v216 offset:36864
	ds_read_b128 v[198:201], v216 offset:37888
	ds_read_b128 v[202:205], v216 offset:38912
	ds_read_b128 v[206:209], v216 offset:39936
	global_load_lds_dwordx4 v[224:225], off
	v_lshl_add_u64 v[224:225], s[22:23], 0, v[146:147]
	s_mov_b32 m0, s42
	s_nop 0
	global_load_lds_dwordx4 v[224:225], off
	s_waitcnt vmcnt(8)
	s_waitcnt lgkmcnt(0)
	s_barrier
	s_setprio 1
	v_mfma_f32_16x16x32_bf16 v[124:127], v[128:131], v[178:181], v[124:127]
	v_mfma_f32_16x16x32_bf16 v[120:123], v[136:139], v[178:181], v[120:123]
	v_mfma_f32_16x16x32_bf16 v[112:115], v[128:131], v[186:189], v[112:115]
	v_mfma_f32_16x16x32_bf16 v[104:107], v[136:139], v[186:189], v[104:107]
	v_mfma_f32_16x16x32_bf16 v[100:103], v[128:131], v[194:197], v[100:103]
	v_mfma_f32_16x16x32_bf16 v[96:99], v[136:139], v[194:197], v[96:99]
	v_mfma_f32_16x16x32_bf16 v[76:79], v[128:131], v[202:205], v[76:79]
	v_mfma_f32_16x16x32_bf16 v[72:75], v[136:139], v[202:205], v[72:75]
	v_mfma_f32_16x16x32_bf16 v[124:127], v[132:135], v[182:185], v[124:127]
	v_mfma_f32_16x16x32_bf16 v[120:123], v[140:143], v[182:185], v[120:123]
	v_mfma_f32_16x16x32_bf16 v[112:115], v[132:135], v[190:193], v[112:115]
	v_mfma_f32_16x16x32_bf16 v[104:107], v[140:143], v[190:193], v[104:107]
	v_mfma_f32_16x16x32_bf16 v[100:103], v[132:135], v[198:201], v[100:103]
	v_mfma_f32_16x16x32_bf16 v[96:99], v[140:143], v[198:201], v[96:99]
	v_mfma_f32_16x16x32_bf16 v[76:79], v[132:135], v[206:209], v[76:79]
	v_mfma_f32_16x16x32_bf16 v[72:75], v[140:143], v[206:209], v[72:75]
	v_mfma_f32_16x16x32_bf16 v[116:119], v[162:165], v[178:181], v[116:119]
	v_mfma_f32_16x16x32_bf16 v[108:111], v[170:173], v[178:181], v[108:111]
	v_mfma_f32_16x16x32_bf16 v[92:95], v[162:165], v[186:189], v[92:95]
	v_mfma_f32_16x16x32_bf16 v[88:91], v[170:173], v[186:189], v[88:91]
	v_mfma_f32_16x16x32_bf16 v[84:87], v[162:165], v[194:197], v[84:87]
	v_mfma_f32_16x16x32_bf16 v[80:83], v[170:173], v[194:197], v[80:83]
	v_mfma_f32_16x16x32_bf16 v[68:71], v[162:165], v[202:205], v[68:71]
	v_mfma_f32_16x16x32_bf16 v[64:67], v[170:173], v[202:205], v[64:67]
	v_mfma_f32_16x16x32_bf16 v[116:119], v[166:169], v[182:185], v[116:119]
	v_mfma_f32_16x16x32_bf16 v[108:111], v[174:177], v[182:185], v[108:111]
	v_mfma_f32_16x16x32_bf16 v[92:95], v[166:169], v[190:193], v[92:95]
	v_mfma_f32_16x16x32_bf16 v[88:91], v[174:177], v[190:193], v[88:91]
	v_mfma_f32_16x16x32_bf16 v[84:87], v[166:169], v[198:201], v[84:87]
	v_mfma_f32_16x16x32_bf16 v[80:83], v[174:177], v[198:201], v[80:83]
	v_mfma_f32_16x16x32_bf16 v[68:71], v[166:169], v[206:209], v[68:71]
	v_mfma_f32_16x16x32_bf16 v[64:67], v[174:177], v[206:209], v[64:67]
	s_setprio 0
	s_barrier
	s_add_i32 s22, s60, s36
	v_lshl_add_u64 v[210:211], v[210:211], 0, s[6:7]
	s_mov_b32 m0, s22
	ds_read_b128 v[178:181], v216 offset:49152
	ds_read_b128 v[182:185], v216 offset:50176
	ds_read_b128 v[186:189], v216 offset:51200
	ds_read_b128 v[190:193], v216 offset:52224
	ds_read_b128 v[194:197], v216 offset:53248
	ds_read_b128 v[198:201], v216 offset:54272
	ds_read_b128 v[202:205], v216 offset:55296
	ds_read_b128 v[206:209], v216 offset:56320
	global_load_lds_dwordx4 v[210:211], off
	s_add_i32 m0, s22, 0x2000
	s_add_u32 s22, s26, 0x158080
	v_lshl_add_u64 v[210:211], v[218:219], 0, s[6:7]
	s_addc_u32 s23, s27, 0
	s_add_i32 s26, s61, s36
	global_load_lds_dwordx4 v[210:211], off
	v_lshl_add_u64 v[210:211], s[22:23], 0, v[148:149]
	s_mov_b32 m0, s26
	s_nop 0
	global_load_lds_dwordx4 v[210:211], off
	v_lshl_add_u64 v[210:211], s[22:23], 0, v[144:145]
	s_add_i32 m0, s26, 0x2000
	s_nop 0
	global_load_lds_dwordx4 v[210:211], off
	v_lshl_add_u64 v[210:211], v[220:221], 0, s[6:7]
	s_mov_b32 m0, s46
	s_nop 0
	global_load_lds_dwordx4 v[210:211], off
	v_lshl_add_u64 v[210:211], v[222:223], 0, s[6:7]
	s_mov_b32 m0, s47
	s_nop 0
	global_load_lds_dwordx4 v[210:211], off
	s_waitcnt vmcnt(8)
	s_waitcnt lgkmcnt(0)
	s_barrier
	s_setprio 1
	v_mfma_f32_16x16x32_bf16 v[60:63], v[128:131], v[178:181], v[60:63]
	v_mfma_f32_16x16x32_bf16 v[56:59], v[136:139], v[178:181], v[56:59]
	v_mfma_f32_16x16x32_bf16 v[48:51], v[128:131], v[186:189], v[48:51]
	v_mfma_f32_16x16x32_bf16 v[40:43], v[136:139], v[186:189], v[40:43]
	v_mfma_f32_16x16x32_bf16 v[32:35], v[128:131], v[194:197], v[32:35]
	v_mfma_f32_16x16x32_bf16 v[24:27], v[136:139], v[194:197], v[24:27]
	v_mfma_f32_16x16x32_bf16 v[16:19], v[128:131], v[202:205], v[16:19]
	v_mfma_f32_16x16x32_bf16 v[8:11], v[136:139], v[202:205], v[8:11]
	v_mfma_f32_16x16x32_bf16 v[60:63], v[132:135], v[182:185], v[60:63]
	v_mfma_f32_16x16x32_bf16 v[56:59], v[140:143], v[182:185], v[56:59]
	v_mfma_f32_16x16x32_bf16 v[48:51], v[132:135], v[190:193], v[48:51]
	v_mfma_f32_16x16x32_bf16 v[40:43], v[140:143], v[190:193], v[40:43]
	v_mfma_f32_16x16x32_bf16 v[32:35], v[132:135], v[198:201], v[32:35]
	v_mfma_f32_16x16x32_bf16 v[24:27], v[140:143], v[198:201], v[24:27]
	v_mfma_f32_16x16x32_bf16 v[16:19], v[132:135], v[206:209], v[16:19]
	v_mfma_f32_16x16x32_bf16 v[8:11], v[140:143], v[206:209], v[8:11]
	v_mfma_f32_16x16x32_bf16 v[52:55], v[162:165], v[178:181], v[52:55]
	v_mfma_f32_16x16x32_bf16 v[44:47], v[170:173], v[178:181], v[44:47]
	v_mfma_f32_16x16x32_bf16 v[36:39], v[162:165], v[186:189], v[36:39]
	v_mfma_f32_16x16x32_bf16 v[28:31], v[170:173], v[186:189], v[28:31]
	v_mfma_f32_16x16x32_bf16 v[20:23], v[162:165], v[194:197], v[20:23]
	v_mfma_f32_16x16x32_bf16 v[12:15], v[170:173], v[194:197], v[12:15]
	v_mfma_f32_16x16x32_bf16 v[4:7], v[162:165], v[202:205], v[4:7]
	v_mfma_f32_16x16x32_bf16 v[0:3], v[170:173], v[202:205], v[0:3]
	v_mfma_f32_16x16x32_bf16 v[52:55], v[166:169], v[182:185], v[52:55]
	v_mfma_f32_16x16x32_bf16 v[44:47], v[174:177], v[182:185], v[44:47]
	v_mfma_f32_16x16x32_bf16 v[36:39], v[166:169], v[190:193], v[36:39]
	v_mfma_f32_16x16x32_bf16 v[28:31], v[174:177], v[190:193], v[28:31]
	v_mfma_f32_16x16x32_bf16 v[20:23], v[166:169], v[198:201], v[20:23]
	v_mfma_f32_16x16x32_bf16 v[12:15], v[174:177], v[198:201], v[12:15]
	v_mfma_f32_16x16x32_bf16 v[4:7], v[166:169], v[206:209], v[4:7]
	v_mfma_f32_16x16x32_bf16 v[0:3], v[174:177], v[206:209], v[0:3]
	s_setprio 0
	s_barrier
	s_add_i32 s59, s59, 2
	s_add_u32 s21, s21, 0x100
	s_addc_u32 s58, s58, 0
	s_cmpk_gt_u32 s59, 0x53
	s_mov_b64 s[22:23], s[24:25]
	s_cbranch_scc0 .LBB0_2107

;     __host__ __device__ bool next(int i, Unit& u) const { const bool ok = StaticOrder::next(i, u); u.pm = 0; u.pn = 0; return ok; }
; #define PG8_STAGE(bufoff, gbase, voff) do { _Pragma("unroll") for (int _i = 0; _i < 2; ++_i) \
;         __builtin_amdgcn_global_load_lds((const unsigned*)((const char*)(gbase) + (voff)[_i]), (PG8_LAS unsigned*)(lds + (bufoff) + ldsw + _i * 8192), 16, 0, 0); } while (0)
; #define PG8_LDA(dst, b, h) do { _Pragma("unroll") for (int m = 0; m < 4; ++m) _Pragma("unroll") for (int k = 0; k < 2; ++k) dst[m][k] = *(const PG8_LAS bf16x8*)(lds + PG8_SA(b, h) + aoff + m * 2048 + k * 1024); } while (0)
; #define PG8_LDB(dst, b, h) do { _Pragma("unroll") for (int n = 0; n < 2; ++n) _Pragma("unroll") for (int k = 0; k < 2; ++k) dst[n][k] = *(const PG8_LAS bf16x8*)(lds + PG8_SB(b, h) + boff + n * 2048 + k * 1024); } while (0)
; #define PG8_WAIT_V(n) asm volatile("s_waitcnt vmcnt(" #n ")" ::: "memory")
; #define PG8_BAR __builtin_amdgcn_s_barrier()
; template <class Epi, class Sched, bool ALIGN_EPI = false, bool SP2 = false>
; __device__ __forceinline__ void gemm_phase(PG8_LAS unsigned char* lds, const Gemm g, const Sched& S, const Epi& E, const int wave_in) {
;     ...
;         const bool has_next = S.next(ui + 1, nxt);
;         const char* nA = has_next ? (const char*)g.A + (size_t)nxt.pm * tstepA : cA; const char* nB = has_next ? (const char*)g.Bt + (size_t)nxt.pn * tstepB : cB;
;         for (int t = 0; t < nt; t += 2) {
;             const bool last = (t == nt - 2);
;             const char* a1 = cA + (size_t)(t + 1) * kstep;
;             const char* a2 = last ? nA : cA + (size_t)(t + 2) * kstep; const char* b2 = last ? nB : cB + (size_t)(t + 2) * kstep;
;             const char* a3 = a2 + kstep; const char* b3 = b2 + kstep;
;             if (last && has_next) S.a_ready(nxt);
;             if constexpr (SP2) {
;             PG8_LDB(B0, 0, 0); PG8_LDB(B1, 0, 1); PG8_SCHED; PG8_LDA(At, 0, 0); PG8_STAGE(PG8_SA(1, 1), a1 + hstepA, voffA);
;             PG8_WAIT_V(8); PG8_WAIT_L(0); PG8_BAR; PG8_MMA(0, 0, At, B0); PG8_MMA(0, 1, At, B1); PG8_BAR; PG8_SCHED;
;             PG8_LDA(At, 0, 1); PG8_STAGE(PG8_SB(0, 0), b2, voffB); PG8_STAGE(PG8_SB(0, 1), b2 + hstepB, voffB); PG8_STAGE(PG8_SA(0, 0), a2, voffA);
;             PG8_WAIT_V(8); PG8_WAIT_L(0); PG8_BAR; PG8_MMA(1, 0, At, B0); PG8_MMA(1, 1, At, B1); PG8_BAR; PG8_SCHED;
.LBB0_2247:
	s_ashr_i32 s15, s14, 31
	s_lshl_b64 s[16:17], s[14:15], 20
	s_add_u32 s16, s28, s16
	s_addc_u32 s17, s29, s17
	s_and_b64 s[18:19], s[2:3], exec
	s_cselect_b32 s5, s17, s23
	s_cselect_b32 s15, s16, s22
	s_ashr_i32 s13, s12, 31
	s_lshl_b64 s[18:19], s[12:13], 20
	s_add_u32 s18, s30, s18
	s_addc_u32 s19, s31, s19
	s_and_b64 s[26:27], s[2:3], exec
	s_cselect_b32 s13, s19, s25
	s_cselect_b32 s47, s18, s24
	s_add_u32 s22, s22, 0x80080
	s_addc_u32 s23, s23, 0
	s_add_u32 s48, s24, 0x100
	v_mov_b32_e32 v0, 0
	s_addc_u32 s49, s25, 0
	s_mov_b32 s50, -2
	ds_read_b128 v[144:147], v151
	ds_read_b128 v[154:157], v151 offset:1024
	ds_read_b128 v[158:161], v151 offset:2048
	ds_read_b128 v[162:165], v151 offset:3072
	ds_read_b128 v[166:169], v152
	ds_read_b128 v[170:173], v152 offset:1024
	ds_read_b128 v[174:177], v152 offset:2048
	ds_read_b128 v[178:181], v152 offset:3072
	s_add_u32 s24, s22, 0xfff80080
	s_addc_u32 s25, s23, -1
	s_cmp_eq_u32 s50, 28
	s_cselect_b32 s27, s5, s25
	s_cselect_b32 s26, s15, s24
	s_cselect_b32 s25, s13, s49
	s_cselect_b32 s24, s47, s48
	v_lshl_add_u64 v[214:215], s[22:23], 0, v[136:137]
	s_add_i32 m0, s21, 0xc000
	ds_read_b128 v[182:185], v153
	ds_read_b128 v[186:189], v153 offset:1024
	ds_read_b128 v[190:193], v153 offset:2048
	ds_read_b128 v[194:197], v153 offset:3072
	ds_read_b128 v[198:201], v153 offset:4096
	ds_read_b128 v[202:205], v153 offset:5120
	ds_read_b128 v[206:209], v153 offset:6144
	ds_read_b128 v[210:213], v153 offset:7168
	global_load_lds_dwordx4 v[214:215], off
	v_lshl_add_u64 v[214:215], s[22:23], 0, v[138:139]
	s_add_i32 m0, s21, 0xe000
	s_nop 0
	global_load_lds_dwordx4 v[214:215], off
	s_waitcnt vmcnt(8)
	s_waitcnt lgkmcnt(0)
	s_barrier
	s_setprio 1
	v_mfma_f32_16x16x32_bf16 v[124:127], v[144:147], v[182:185], 0
	v_mfma_f32_16x16x32_bf16 v[120:123], v[158:161], v[182:185], 0
	v_mfma_f32_16x16x32_bf16 v[108:111], v[144:147], v[190:193], 0
	v_mfma_f32_16x16x32_bf16 v[104:107], v[158:161], v[190:193], 0
	v_mfma_f32_16x16x32_bf16 v[92:95], v[144:147], v[198:201], 0
	v_mfma_f32_16x16x32_bf16 v[88:91], v[158:161], v[198:201], 0
	v_mfma_f32_16x16x32_bf16 v[76:79], v[144:147], v[206:209], 0
	v_mfma_f32_16x16x32_bf16 v[72:75], v[158:161], v[206:209], 0
	v_mfma_f32_16x16x32_bf16 v[124:127], v[154:157], v[186:189], v[124:127]
	v_mfma_f32_16x16x32_bf16 v[120:123], v[162:165], v[186:189], v[120:123]
	v_mfma_f32_16x16x32_bf16 v[108:111], v[154:157], v[194:197], v[108:111]
	v_mfma_f32_16x16x32_bf16 v[104:107], v[162:165], v[194:197], v[104:107]
	v_mfma_f32_16x16x32_bf16 v[92:95], v[154:157], v[202:205], v[92:95]
	v_mfma_f32_16x16x32_bf16 v[88:91], v[162:165], v[202:205], v[88:91]
	v_mfma_f32_16x16x32_bf16 v[76:79], v[154:157], v[210:213], v[76:79]
	v_mfma_f32_16x16x32_bf16 v[72:75], v[162:165], v[210:213], v[72:75]
	v_mfma_f32_16x16x32_bf16 v[116:119], v[166:169], v[182:185], 0
	v_mfma_f32_16x16x32_bf16 v[112:115], v[174:177], v[182:185], 0
	v_mfma_f32_16x16x32_bf16 v[100:103], v[166:169], v[190:193], 0
	v_mfma_f32_16x16x32_bf16 v[96:99], v[174:177], v[190:193], 0
	v_mfma_f32_16x16x32_bf16 v[84:87], v[166:169], v[198:201], 0
	v_mfma_f32_16x16x32_bf16 v[80:83], v[174:177], v[198:201], 0
	v_mfma_f32_16x16x32_bf16 v[68:71], v[166:169], v[206:209], 0
	v_mfma_f32_16x16x32_bf16 v[64:67], v[174:177], v[206:209], 0
	v_mfma_f32_16x16x32_bf16 v[116:119], v[170:173], v[186:189], v[116:119]
	v_mfma_f32_16x16x32_bf16 v[112:115], v[178:181], v[186:189], v[112:115]
	v_mfma_f32_16x16x32_bf16 v[100:103], v[170:173], v[194:197], v[100:103]
	v_mfma_f32_16x16x32_bf16 v[96:99], v[178:181], v[194:197], v[96:99]
	v_mfma_f32_16x16x32_bf16 v[84:87], v[170:173], v[202:205], v[84:87]
	v_mfma_f32_16x16x32_bf16 v[80:83], v[178:181], v[202:205], v[80:83]
	v_mfma_f32_16x16x32_bf16 v[68:71], v[170:173], v[210:213], v[68:71]
	v_mfma_f32_16x16x32_bf16 v[64:67], v[178:181], v[210:213], v[64:67]
	s_setprio 0
	s_barrier
	s_add_i32 s51, s44, s34
	v_lshl_add_u64 v[214:215], s[24:25], 0, v[130:131]
	s_mov_b32 m0, s51
	ds_read_b128 v[182:185], v153 offset:16384
	ds_read_b128 v[186:189], v153 offset:17408
	ds_read_b128 v[190:193], v153 offset:18432
	ds_read_b128 v[194:197], v153 offset:19456
	ds_read_b128 v[198:201], v153 offset:20480
	ds_read_b128 v[202:205], v153 offset:21504
	ds_read_b128 v[206:209], v153 offset:22528
	ds_read_b128 v[210:213], v153 offset:23552
	global_load_lds_dwordx4 v[214:215], off
	s_add_i32 m0, s51, 0x2000
	s_add_u32 s52, s24, 0x80000
	v_lshl_add_u64 v[216:217], s[24:25], 0, v[134:135]
	s_addc_u32 s53, s25, 0
	s_add_i32 s51, s45, s34
	global_load_lds_dwordx4 v[216:217], off
	v_lshl_add_u64 v[218:219], s[52:53], 0, v[130:131]
	s_mov_b32 m0, s51
	v_lshl_add_u64 v[220:221], s[26:27], 0, v[132:133]
	global_load_lds_dwordx4 v[218:219], off
	v_lshl_add_u64 v[218:219], s[52:53], 0, v[134:135]
	s_add_i32 m0, s51, 0x2000
	s_nop 0
	global_load_lds_dwordx4 v[218:219], off
	v_lshl_add_u64 v[218:219], s[26:27], 0, v[128:129]
	s_mov_b32 m0, s21
	s_nop 0
	global_load_lds_dwordx4 v[218:219], off
	s_mov_b32 m0, s35
	s_nop 0
	global_load_lds_dwordx4 v[220:221], off
	s_waitcnt vmcnt(8)
	s_waitcnt lgkmcnt(0)
	s_barrier
; #define PG8_STAGE(bufoff, gbase, voff) do { _Pragma("unroll") for (int _i = 0; _i < 2; ++_i) \
;         __builtin_amdgcn_global_load_lds((const unsigned*)((const char*)(gbase) + (voff)[_i]), (PG8_LAS unsigned*)(lds + (bufoff) + ldsw + _i * 8192), 16, 0, 0); } while (0)
; #define PG8_LDA(dst, b, h) do { _Pragma("unroll") for (int m = 0; m < 4; ++m) _Pragma("unroll") for (int k = 0; k < 2; ++k) dst[m][k] = *(const PG8_LAS bf16x8*)(lds + PG8_SA(b, h) + aoff + m * 2048 + k * 1024); } while (0)
; #define PG8_LDB(dst, b, h) do { _Pragma("unroll") for (int n = 0; n < 2; ++n) _Pragma("unroll") for (int k = 0; k < 2; ++k) dst[n][k] = *(const PG8_LAS bf16x8*)(lds + PG8_SB(b, h) + boff + n * 2048 + k * 1024); } while (0)
; #define PG8_MMA(ai, bj, At, Bt) do { __builtin_amdgcn_s_setprio(1); _Pragma("unroll") for (int m = 0; m < 4; ++m) _Pragma("unroll") for (int n = 0; n < 2; ++n) _Pragma("unroll") for (int k = 0; k < 2; ++k) \
;         acc[ai][bj][m][n] = __builtin_amdgcn_mfma_f32_16x16x32_bf16(Bt[n][k], At[m][k], acc[ai][bj][m][n], 0, 0, 0); __builtin_amdgcn_s_setprio(0); } while (0)
; #define PG8_WAIT_V(n) asm volatile("s_waitcnt vmcnt(" #n ")" ::: "memory")
; #define PG8_WAIT_L(n) asm volatile("s_waitcnt lgkmcnt(" #n ")" ::: "memory")
; #define PG8_BAR __builtin_amdgcn_s_barrier()
; #define PG8_SCHED __builtin_amdgcn_sched_barrier(0)
; template <class Epi, class Sched, bool ALIGN_EPI = false, bool SP2 = false>
; __device__ __forceinline__ void gemm_phase(PG8_LAS unsigned char* lds, const Gemm g, const Sched& S, const Epi& E, const int wave_in) {
;     ...
;             PG8_WAIT_V(8); PG8_WAIT_L(0); PG8_BAR; PG8_MMA(0, 0, At, B0); PG8_MMA(0, 1, At, B1); PG8_BAR; PG8_SCHED;
;             PG8_LDA(At, 0, 1); PG8_STAGE(PG8_SB(0, 0), b2, voffB); PG8_STAGE(PG8_SB(0, 1), b2 + hstepB, voffB); PG8_STAGE(PG8_SA(0, 0), a2, voffA);
;             PG8_WAIT_V(8); PG8_WAIT_L(0); PG8_BAR; PG8_MMA(1, 0, At, B0); PG8_MMA(1, 1, At, B1); PG8_BAR; PG8_SCHED;
;             PG8_LDB(B0, 1, 0); PG8_LDB(B1, 1, 1); PG8_SCHED; PG8_LDA(At, 1, 0); PG8_STAGE(PG8_SA(0, 1), a2 + hstepA, voffA);
;             PG8_WAIT_V(8); PG8_WAIT_L(0); PG8_BAR; PG8_MMA(0, 0, At, B0); PG8_MMA(0, 1, At, B1); PG8_BAR; PG8_SCHED;
	s_setprio 1
	v_mfma_f32_16x16x32_bf16 v[60:63], v[144:147], v[182:185], 0
	v_mfma_f32_16x16x32_bf16 v[56:59], v[158:161], v[182:185], 0
	v_mfma_f32_16x16x32_bf16 v[44:47], v[144:147], v[190:193], 0
	v_mfma_f32_16x16x32_bf16 v[40:43], v[158:161], v[190:193], 0
	v_mfma_f32_16x16x32_bf16 v[28:31], v[144:147], v[198:201], 0
	v_mfma_f32_16x16x32_bf16 v[24:27], v[158:161], v[198:201], 0
	v_mfma_f32_16x16x32_bf16 v[12:15], v[144:147], v[206:209], 0
	v_mfma_f32_16x16x32_bf16 v[8:11], v[158:161], v[206:209], 0
	v_mfma_f32_16x16x32_bf16 v[60:63], v[154:157], v[186:189], v[60:63]
	v_mfma_f32_16x16x32_bf16 v[56:59], v[162:165], v[186:189], v[56:59]
	v_mfma_f32_16x16x32_bf16 v[44:47], v[154:157], v[194:197], v[44:47]
	v_mfma_f32_16x16x32_bf16 v[40:43], v[162:165], v[194:197], v[40:43]
	v_mfma_f32_16x16x32_bf16 v[28:31], v[154:157], v[202:205], v[28:31]
	v_mfma_f32_16x16x32_bf16 v[24:27], v[162:165], v[202:205], v[24:27]
	v_mfma_f32_16x16x32_bf16 v[12:15], v[154:157], v[210:213], v[12:15]
	v_mfma_f32_16x16x32_bf16 v[8:11], v[162:165], v[210:213], v[8:11]
	v_mfma_f32_16x16x32_bf16 v[52:55], v[166:169], v[182:185], 0
	v_mfma_f32_16x16x32_bf16 v[48:51], v[174:177], v[182:185], 0
	v_mfma_f32_16x16x32_bf16 v[36:39], v[166:169], v[190:193], 0
	v_mfma_f32_16x16x32_bf16 v[32:35], v[174:177], v[190:193], 0
	v_mfma_f32_16x16x32_bf16 v[20:23], v[166:169], v[198:201], 0
	v_mfma_f32_16x16x32_bf16 v[16:19], v[174:177], v[198:201], 0
	v_mfma_f32_16x16x32_bf16 v[4:7], v[166:169], v[206:209], 0
	v_mfma_f32_16x16x32_bf16 v[0:3], v[174:177], v[206:209], 0
	v_mfma_f32_16x16x32_bf16 v[52:55], v[170:173], v[186:189], v[52:55]
	v_mfma_f32_16x16x32_bf16 v[48:51], v[178:181], v[186:189], v[48:51]
	v_mfma_f32_16x16x32_bf16 v[36:39], v[170:173], v[194:197], v[36:39]
	v_mfma_f32_16x16x32_bf16 v[32:35], v[178:181], v[194:197], v[32:35]
	v_mfma_f32_16x16x32_bf16 v[20:23], v[170:173], v[202:205], v[20:23]
	v_mfma_f32_16x16x32_bf16 v[16:19], v[178:181], v[202:205], v[16:19]
	v_mfma_f32_16x16x32_bf16 v[4:7], v[170:173], v[210:213], v[4:7]
	v_mfma_f32_16x16x32_bf16 v[0:3], v[178:181], v[210:213], v[0:3]
	s_setprio 0
	s_barrier
	s_add_i32 s51, 0, 0x18000
	s_add_i32 s52, 0, 0x1c000
	v_add_u32_e32 v162, s51, v149
	v_add_u32_e32 v178, s52, v149
	ds_read_b128 v[144:147], v162
	ds_read_b128 v[154:157], v162 offset:1024
	ds_read_b128 v[158:161], v162 offset:2048
	ds_read_b128 v[162:165], v162 offset:3072
	ds_read_b128 v[166:169], v178
	ds_read_b128 v[170:173], v178 offset:1024
	ds_read_b128 v[174:177], v178 offset:2048
	ds_read_b128 v[178:181], v178 offset:3072
	s_add_u32 s26, s26, 0x80000
	s_addc_u32 s27, s27, 0
	s_mov_b32 m0, s36
	v_lshl_add_u64 v[222:223], s[26:27], 0, v[128:129]
	ds_read_b128 v[182:185], v153 offset:32768
	ds_read_b128 v[186:189], v153 offset:33792
	ds_read_b128 v[190:193], v153 offset:34816
	ds_read_b128 v[194:197], v153 offset:35840
	ds_read_b128 v[198:201], v153 offset:36864
	ds_read_b128 v[202:205], v153 offset:37888
	ds_read_b128 v[206:209], v153 offset:38912
	ds_read_b128 v[210:213], v153 offset:39936
	global_load_lds_dwordx4 v[222:223], off
	v_lshl_add_u64 v[222:223], s[26:27], 0, v[132:133]
	s_mov_b32 m0, s37
	s_nop 0
	global_load_lds_dwordx4 v[222:223], off
	s_waitcnt vmcnt(8)
	s_waitcnt lgkmcnt(0)
	s_barrier
	s_setprio 1
	v_mfma_f32_16x16x32_bf16 v[124:127], v[144:147], v[182:185], v[124:127]
	v_mfma_f32_16x16x32_bf16 v[120:123], v[158:161], v[182:185], v[120:123]
	v_mfma_f32_16x16x32_bf16 v[108:111], v[144:147], v[190:193], v[108:111]
	v_mfma_f32_16x16x32_bf16 v[104:107], v[158:161], v[190:193], v[104:107]
	v_mfma_f32_16x16x32_bf16 v[92:95], v[144:147], v[198:201], v[92:95]
	v_mfma_f32_16x16x32_bf16 v[88:91], v[158:161], v[198:201], v[88:91]
	v_mfma_f32_16x16x32_bf16 v[76:79], v[144:147], v[206:209], v[76:79]
	v_mfma_f32_16x16x32_bf16 v[72:75], v[158:161], v[206:209], v[72:75]
	v_mfma_f32_16x16x32_bf16 v[124:127], v[154:157], v[186:189], v[124:127]
	v_mfma_f32_16x16x32_bf16 v[120:123], v[162:165], v[186:189], v[120:123]
	v_mfma_f32_16x16x32_bf16 v[108:111], v[154:157], v[194:197], v[108:111]
	v_mfma_f32_16x16x32_bf16 v[104:107], v[162:165], v[194:197], v[104:107]
	v_mfma_f32_16x16x32_bf16 v[92:95], v[154:157], v[202:205], v[92:95]
	v_mfma_f32_16x16x32_bf16 v[88:91], v[162:165], v[202:205], v[88:91]
	v_mfma_f32_16x16x32_bf16 v[76:79], v[154:157], v[210:213], v[76:79]
	v_mfma_f32_16x16x32_bf16 v[72:75], v[162:165], v[210:213], v[72:75]
	v_mfma_f32_16x16x32_bf16 v[116:119], v[166:169], v[182:185], v[116:119]
	v_mfma_f32_16x16x32_bf16 v[112:115], v[174:177], v[182:185], v[112:115]
	v_mfma_f32_16x16x32_bf16 v[100:103], v[166:169], v[190:193], v[100:103]
	v_mfma_f32_16x16x32_bf16 v[96:99], v[174:177], v[190:193], v[96:99]
	v_mfma_f32_16x16x32_bf16 v[84:87], v[166:169], v[198:201], v[84:87]
	v_mfma_f32_16x16x32_bf16 v[80:83], v[174:177], v[198:201], v[80:83]
	v_mfma_f32_16x16x32_bf16 v[68:71], v[166:169], v[206:209], v[68:71]
	v_mfma_f32_16x16x32_bf16 v[64:67], v[174:177], v[206:209], v[64:67]
	v_mfma_f32_16x16x32_bf16 v[116:119], v[170:173], v[186:189], v[116:119]
	v_mfma_f32_16x16x32_bf16 v[112:115], v[178:181], v[186:189], v[112:115]
	v_mfma_f32_16x16x32_bf16 v[100:103], v[170:173], v[194:197], v[100:103]
	v_mfma_f32_16x16x32_bf16 v[96:99], v[178:181], v[194:197], v[96:99]
	v_mfma_f32_16x16x32_bf16 v[84:87], v[170:173], v[202:205], v[84:87]
	v_mfma_f32_16x16x32_bf16 v[80:83], v[178:181], v[202:205], v[80:83]
	v_mfma_f32_16x16x32_bf16 v[68:71], v[170:173], v[210:213], v[68:71]
	v_mfma_f32_16x16x32_bf16 v[64:67], v[178:181], v[210:213], v[64:67]
	s_setprio 0
	s_barrier
; #define PG8_STAGE(bufoff, gbase, voff) do { _Pragma("unroll") for (int _i = 0; _i < 2; ++_i) \
;         __builtin_amdgcn_global_load_lds((const unsigned*)((const char*)(gbase) + (voff)[_i]), (PG8_LAS unsigned*)(lds + (bufoff) + ldsw + _i * 8192), 16, 0, 0); } while (0)
; #define PG8_LDA(dst, b, h) do { _Pragma("unroll") for (int m = 0; m < 4; ++m) _Pragma("unroll") for (int k = 0; k < 2; ++k) dst[m][k] = *(const PG8_LAS bf16x8*)(lds + PG8_SA(b, h) + aoff + m * 2048 + k * 1024); } while (0)
; #define PG8_LDB(dst, b, h) do { _Pragma("unroll") for (int n = 0; n < 2; ++n) _Pragma("unroll") for (int k = 0; k < 2; ++k) dst[n][k] = *(const PG8_LAS bf16x8*)(lds + PG8_SB(b, h) + boff + n * 2048 + k * 1024); } while (0)
; #define PG8_WAIT_V(n) asm volatile("s_waitcnt vmcnt(" #n ")" ::: "memory")
; #define PG8_WAIT_L(n) asm volatile("s_waitcnt lgkmcnt(" #n ")" ::: "memory")
; #define PG8_BAR __builtin_amdgcn_s_barrier()
; template <class Epi, class Sched, bool ALIGN_EPI = false, bool SP2 = false>
; __device__ __forceinline__ void gemm_phase(PG8_LAS unsigned char* lds, const Gemm g, const Sched& S, const Epi& E, const int wave_in) {
;     ...
;         for (int t = 0; t < nt; t += 2) {
;             const bool last = (t == nt - 2);
;             const char* a1 = cA + (size_t)(t + 1) * kstep;
;             const char* a2 = last ? nA : cA + (size_t)(t + 2) * kstep; const char* b2 = last ? nB : cB + (size_t)(t + 2) * kstep;
;             const char* a3 = a2 + kstep; const char* b3 = b2 + kstep;
;             if (last && has_next) S.a_ready(nxt);
;             if constexpr (SP2) {
;             PG8_LDB(B0, 0, 0); PG8_LDB(B1, 0, 1); PG8_SCHED; PG8_LDA(At, 0, 0); PG8_STAGE(PG8_SA(1, 1), a1 + hstepA, voffA);
;             PG8_WAIT_V(8); PG8_WAIT_L(0); PG8_BAR; PG8_MMA(0, 0, At, B0); PG8_MMA(0, 1, At, B1); PG8_BAR; PG8_SCHED;
;             PG8_LDA(At, 0, 1); PG8_STAGE(PG8_SB(0, 0), b2, voffB); PG8_STAGE(PG8_SB(0, 1), b2 + hstepB, voffB); PG8_STAGE(PG8_SA(0, 0), a2, voffA);
;             PG8_WAIT_V(8); PG8_WAIT_L(0); PG8_BAR; PG8_MMA(1, 0, At, B0); PG8_MMA(1, 1, At, B1); PG8_BAR; PG8_SCHED;
;     ...
;             PG8_LDA(At, 1, 1); PG8_STAGE(PG8_SB(1, 0), b3, voffB); PG8_STAGE(PG8_SB(1, 1), b3 + hstepB, voffB); PG8_STAGE(PG8_SA(1, 0), a3, voffA);
;             PG8_WAIT_V(8); PG8_WAIT_L(0); PG8_BAR; PG8_MMA(1, 0, At, B0); PG8_MMA(1, 1, At, B1); PG8_BAR; PG8_SCHED;
	s_add_i32 s26, s51, s34
	v_lshl_add_u64 v[214:215], v[214:215], 0, s[8:9]
	s_mov_b32 m0, s26
	ds_read_b128 v[182:185], v153 offset:49152
	ds_read_b128 v[186:189], v153 offset:50176
	ds_read_b128 v[190:193], v153 offset:51200
	ds_read_b128 v[194:197], v153 offset:52224
	ds_read_b128 v[198:201], v153 offset:53248
	ds_read_b128 v[202:205], v153 offset:54272
	ds_read_b128 v[206:209], v153 offset:55296
	ds_read_b128 v[210:213], v153 offset:56320
	global_load_lds_dwordx4 v[214:215], off
	s_add_i32 m0, s26, 0x2000
	s_add_u32 s24, s24, 0x80080
	v_lshl_add_u64 v[214:215], v[216:217], 0, s[8:9]
	s_addc_u32 s25, s25, 0
	s_add_i32 s26, s52, s34
	global_load_lds_dwordx4 v[214:215], off
	v_lshl_add_u64 v[214:215], s[24:25], 0, v[130:131]
	s_mov_b32 m0, s26
	s_nop 0
	global_load_lds_dwordx4 v[214:215], off
	v_lshl_add_u64 v[214:215], s[24:25], 0, v[134:135]
	s_add_i32 m0, s26, 0x2000
	s_nop 0
	global_load_lds_dwordx4 v[214:215], off
	v_lshl_add_u64 v[214:215], v[218:219], 0, s[8:9]
	s_mov_b32 m0, s39
	s_nop 0
	global_load_lds_dwordx4 v[214:215], off
	v_lshl_add_u64 v[214:215], v[220:221], 0, s[8:9]
	s_mov_b32 m0, s40
	s_nop 0
	global_load_lds_dwordx4 v[214:215], off
	s_waitcnt vmcnt(8)
	s_waitcnt lgkmcnt(0)
	s_barrier
	s_setprio 1
	v_mfma_f32_16x16x32_bf16 v[60:63], v[144:147], v[182:185], v[60:63]
	v_mfma_f32_16x16x32_bf16 v[56:59], v[158:161], v[182:185], v[56:59]
	v_mfma_f32_16x16x32_bf16 v[44:47], v[144:147], v[190:193], v[44:47]
	v_mfma_f32_16x16x32_bf16 v[40:43], v[158:161], v[190:193], v[40:43]
	v_mfma_f32_16x16x32_bf16 v[28:31], v[144:147], v[198:201], v[28:31]
	v_mfma_f32_16x16x32_bf16 v[24:27], v[158:161], v[198:201], v[24:27]
	v_mfma_f32_16x16x32_bf16 v[12:15], v[144:147], v[206:209], v[12:15]
	v_mfma_f32_16x16x32_bf16 v[8:11], v[158:161], v[206:209], v[8:11]
	v_mfma_f32_16x16x32_bf16 v[60:63], v[154:157], v[186:189], v[60:63]
	v_mfma_f32_16x16x32_bf16 v[56:59], v[162:165], v[186:189], v[56:59]
	v_mfma_f32_16x16x32_bf16 v[44:47], v[154:157], v[194:197], v[44:47]
	v_mfma_f32_16x16x32_bf16 v[40:43], v[162:165], v[194:197], v[40:43]
	v_mfma_f32_16x16x32_bf16 v[28:31], v[154:157], v[202:205], v[28:31]
	v_mfma_f32_16x16x32_bf16 v[24:27], v[162:165], v[202:205], v[24:27]
	v_mfma_f32_16x16x32_bf16 v[12:15], v[154:157], v[210:213], v[12:15]
	v_mfma_f32_16x16x32_bf16 v[8:11], v[162:165], v[210:213], v[8:11]
	v_mfma_f32_16x16x32_bf16 v[52:55], v[166:169], v[182:185], v[52:55]
	v_mfma_f32_16x16x32_bf16 v[48:51], v[174:177], v[182:185], v[48:51]
	v_mfma_f32_16x16x32_bf16 v[36:39], v[166:169], v[190:193], v[36:39]
	v_mfma_f32_16x16x32_bf16 v[32:35], v[174:177], v[190:193], v[32:35]
	v_mfma_f32_16x16x32_bf16 v[20:23], v[166:169], v[198:201], v[20:23]
	v_mfma_f32_16x16x32_bf16 v[16:19], v[174:177], v[198:201], v[16:19]
	v_mfma_f32_16x16x32_bf16 v[4:7], v[166:169], v[206:209], v[4:7]
	v_mfma_f32_16x16x32_bf16 v[0:3], v[174:177], v[206:209], v[0:3]
	v_mfma_f32_16x16x32_bf16 v[52:55], v[170:173], v[186:189], v[52:55]
	v_mfma_f32_16x16x32_bf16 v[48:51], v[178:181], v[186:189], v[48:51]
	v_mfma_f32_16x16x32_bf16 v[36:39], v[170:173], v[194:197], v[36:39]
	v_mfma_f32_16x16x32_bf16 v[32:35], v[178:181], v[194:197], v[32:35]
	v_mfma_f32_16x16x32_bf16 v[20:23], v[170:173], v[202:205], v[20:23]
	v_mfma_f32_16x16x32_bf16 v[16:19], v[178:181], v[202:205], v[16:19]
	v_mfma_f32_16x16x32_bf16 v[4:7], v[170:173], v[210:213], v[4:7]
	v_mfma_f32_16x16x32_bf16 v[0:3], v[178:181], v[210:213], v[0:3]
	s_setprio 0
	s_barrier
	s_add_i32 s50, s50, 2
	s_add_u32 s22, s22, 0x100
	s_addc_u32 s23, s23, 0
	s_add_u32 s48, s48, 0x100
	s_addc_u32 s49, s49, 0
	s_cmp_gt_u32 s50, 29
	s_cbranch_scc0 .LBB0_2248
	s_branch .Lkx_26
.LBB0_2248:
	ds_read_b128 v[144:147], v151
	ds_read_b128 v[154:157], v151 offset:1024
	ds_read_b128 v[158:161], v151 offset:2048
	ds_read_b128 v[162:165], v151 offset:3072
	ds_read_b128 v[166:169], v152
	ds_read_b128 v[170:173], v152 offset:1024
	ds_read_b128 v[174:177], v152 offset:2048
	ds_read_b128 v[178:181], v152 offset:3072
	s_add_u32 s24, s22, 0xfff80080
	s_addc_u32 s25, s23, -1
	s_cmp_eq_u32 s50, 28
	s_cselect_b32 s27, s5, s25
	s_cselect_b32 s26, s15, s24
	s_cselect_b32 s25, s13, s49
	s_cselect_b32 s24, s47, s48
	v_lshl_add_u64 v[214:215], s[22:23], 0, v[136:137]
	s_add_i32 m0, s21, 0xc000
	ds_read_b128 v[182:185], v153
	ds_read_b128 v[186:189], v153 offset:1024
	ds_read_b128 v[190:193], v153 offset:2048
	ds_read_b128 v[194:197], v153 offset:3072
	ds_read_b128 v[198:201], v153 offset:4096
	ds_read_b128 v[202:205], v153 offset:5120
	ds_read_b128 v[206:209], v153 offset:6144
	ds_read_b128 v[210:213], v153 offset:7168
	global_load_lds_dwordx4 v[214:215], off
	v_lshl_add_u64 v[214:215], s[22:23], 0, v[138:139]
	s_add_i32 m0, s21, 0xe000
	s_nop 0
	global_load_lds_dwordx4 v[214:215], off
	s_waitcnt vmcnt(8)
	s_waitcnt lgkmcnt(0)
	s_barrier
; #define PG8_STAGE(bufoff, gbase, voff) do { _Pragma("unroll") for (int _i = 0; _i < 2; ++_i) \
;         __builtin_amdgcn_global_load_lds((const unsigned*)((const char*)(gbase) + (voff)[_i]), (PG8_LAS unsigned*)(lds + (bufoff) + ldsw + _i * 8192), 16, 0, 0); } while (0)
; #define PG8_LDA(dst, b, h) do { _Pragma("unroll") for (int m = 0; m < 4; ++m) _Pragma("unroll") for (int k = 0; k < 2; ++k) dst[m][k] = *(const PG8_LAS bf16x8*)(lds + PG8_SA(b, h) + aoff + m * 2048 + k * 1024); } while (0)
; #define PG8_LDB(dst, b, h) do { _Pragma("unroll") for (int n = 0; n < 2; ++n) _Pragma("unroll") for (int k = 0; k < 2; ++k) dst[n][k] = *(const PG8_LAS bf16x8*)(lds + PG8_SB(b, h) + boff + n * 2048 + k * 1024); } while (0)
; #define PG8_MMA(ai, bj, At, Bt) do { __builtin_amdgcn_s_setprio(1); _Pragma("unroll") for (int m = 0; m < 4; ++m) _Pragma("unroll") for (int n = 0; n < 2; ++n) _Pragma("unroll") for (int k = 0; k < 2; ++k) \
;         acc[ai][bj][m][n] = __builtin_amdgcn_mfma_f32_16x16x32_bf16(Bt[n][k], At[m][k], acc[ai][bj][m][n], 0, 0, 0); __builtin_amdgcn_s_setprio(0); } while (0)
; #define PG8_WAIT_V(n) asm volatile("s_waitcnt vmcnt(" #n ")" ::: "memory")
; #define PG8_WAIT_L(n) asm volatile("s_waitcnt lgkmcnt(" #n ")" ::: "memory")
; #define PG8_BAR __builtin_amdgcn_s_barrier()
; #define PG8_SCHED __builtin_amdgcn_sched_barrier(0)
; template <class Epi, class Sched, bool ALIGN_EPI = false, bool SP2 = false>
; __device__ __forceinline__ void gemm_phase(PG8_LAS unsigned char* lds, const Gemm g, const Sched& S, const Epi& E, const int wave_in) {
;     ...
;             PG8_LDB(B0, 0, 0); PG8_LDB(B1, 0, 1); PG8_SCHED; PG8_LDA(At, 0, 0); PG8_STAGE(PG8_SA(1, 1), a1 + hstepA, voffA);
;             PG8_WAIT_V(8); PG8_WAIT_L(0); PG8_BAR; PG8_MMA(0, 0, At, B0); PG8_MMA(0, 1, At, B1); PG8_BAR; PG8_SCHED;
;             PG8_LDA(At, 0, 1); PG8_STAGE(PG8_SB(0, 0), b2, voffB); PG8_STAGE(PG8_SB(0, 1), b2 + hstepB, voffB); PG8_STAGE(PG8_SA(0, 0), a2, voffA);
;             PG8_WAIT_V(8); PG8_WAIT_L(0); PG8_BAR; PG8_MMA(1, 0, At, B0); PG8_MMA(1, 1, At, B1); PG8_BAR; PG8_SCHED;
	s_setprio 1
	v_mfma_f32_16x16x32_bf16 v[124:127], v[144:147], v[182:185], v[124:127]
	v_mfma_f32_16x16x32_bf16 v[120:123], v[158:161], v[182:185], v[120:123]
	v_mfma_f32_16x16x32_bf16 v[108:111], v[144:147], v[190:193], v[108:111]
	v_mfma_f32_16x16x32_bf16 v[104:107], v[158:161], v[190:193], v[104:107]
	v_mfma_f32_16x16x32_bf16 v[92:95], v[144:147], v[198:201], v[92:95]
	v_mfma_f32_16x16x32_bf16 v[88:91], v[158:161], v[198:201], v[88:91]
	v_mfma_f32_16x16x32_bf16 v[76:79], v[144:147], v[206:209], v[76:79]
	v_mfma_f32_16x16x32_bf16 v[72:75], v[158:161], v[206:209], v[72:75]
	v_mfma_f32_16x16x32_bf16 v[124:127], v[154:157], v[186:189], v[124:127]
	v_mfma_f32_16x16x32_bf16 v[120:123], v[162:165], v[186:189], v[120:123]
	v_mfma_f32_16x16x32_bf16 v[108:111], v[154:157], v[194:197], v[108:111]
	v_mfma_f32_16x16x32_bf16 v[104:107], v[162:165], v[194:197], v[104:107]
	v_mfma_f32_16x16x32_bf16 v[92:95], v[154:157], v[202:205], v[92:95]
	v_mfma_f32_16x16x32_bf16 v[88:91], v[162:165], v[202:205], v[88:91]
	v_mfma_f32_16x16x32_bf16 v[76:79], v[154:157], v[210:213], v[76:79]
	v_mfma_f32_16x16x32_bf16 v[72:75], v[162:165], v[210:213], v[72:75]
	v_mfma_f32_16x16x32_bf16 v[116:119], v[166:169], v[182:185], v[116:119]
	v_mfma_f32_16x16x32_bf16 v[112:115], v[174:177], v[182:185], v[112:115]
	v_mfma_f32_16x16x32_bf16 v[100:103], v[166:169], v[190:193], v[100:103]
	v_mfma_f32_16x16x32_bf16 v[96:99], v[174:177], v[190:193], v[96:99]
	v_mfma_f32_16x16x32_bf16 v[84:87], v[166:169], v[198:201], v[84:87]
	v_mfma_f32_16x16x32_bf16 v[80:83], v[174:177], v[198:201], v[80:83]
	v_mfma_f32_16x16x32_bf16 v[68:71], v[166:169], v[206:209], v[68:71]
	v_mfma_f32_16x16x32_bf16 v[64:67], v[174:177], v[206:209], v[64:67]
	v_mfma_f32_16x16x32_bf16 v[116:119], v[170:173], v[186:189], v[116:119]
	v_mfma_f32_16x16x32_bf16 v[112:115], v[178:181], v[186:189], v[112:115]
	v_mfma_f32_16x16x32_bf16 v[100:103], v[170:173], v[194:197], v[100:103]
	v_mfma_f32_16x16x32_bf16 v[96:99], v[178:181], v[194:197], v[96:99]
	v_mfma_f32_16x16x32_bf16 v[84:87], v[170:173], v[202:205], v[84:87]
	v_mfma_f32_16x16x32_bf16 v[80:83], v[178:181], v[202:205], v[80:83]
	v_mfma_f32_16x16x32_bf16 v[68:71], v[170:173], v[210:213], v[68:71]
	v_mfma_f32_16x16x32_bf16 v[64:67], v[178:181], v[210:213], v[64:67]
	s_setprio 0
	s_barrier
	s_add_i32 s51, s44, s34
	v_lshl_add_u64 v[214:215], s[24:25], 0, v[130:131]
	s_mov_b32 m0, s51
	ds_read_b128 v[182:185], v153 offset:16384
	ds_read_b128 v[186:189], v153 offset:17408
	ds_read_b128 v[190:193], v153 offset:18432
	ds_read_b128 v[194:197], v153 offset:19456
	ds_read_b128 v[198:201], v153 offset:20480
	ds_read_b128 v[202:205], v153 offset:21504
	ds_read_b128 v[206:209], v153 offset:22528
	ds_read_b128 v[210:213], v153 offset:23552
	global_load_lds_dwordx4 v[214:215], off
	s_add_i32 m0, s51, 0x2000
	s_add_u32 s52, s24, 0x80000
	v_lshl_add_u64 v[216:217], s[24:25], 0, v[134:135]
	s_addc_u32 s53, s25, 0
	s_add_i32 s51, s45, s34
	global_load_lds_dwordx4 v[216:217], off
	v_lshl_add_u64 v[218:219], s[52:53], 0, v[130:131]
	s_mov_b32 m0, s51
	v_lshl_add_u64 v[220:221], s[26:27], 0, v[132:133]
	global_load_lds_dwordx4 v[218:219], off
	v_lshl_add_u64 v[218:219], s[52:53], 0, v[134:135]
	s_add_i32 m0, s51, 0x2000
	s_nop 0
	global_load_lds_dwordx4 v[218:219], off
	v_lshl_add_u64 v[218:219], s[26:27], 0, v[128:129]
	s_mov_b32 m0, s21
	s_nop 0
	global_load_lds_dwordx4 v[218:219], off
	s_mov_b32 m0, s35
	s_nop 0
	global_load_lds_dwordx4 v[220:221], off
	s_waitcnt vmcnt(8)
	s_waitcnt lgkmcnt(0)
	s_barrier
	s_setprio 1
	v_mfma_f32_16x16x32_bf16 v[60:63], v[144:147], v[182:185], v[60:63]
	v_mfma_f32_16x16x32_bf16 v[56:59], v[158:161], v[182:185], v[56:59]
	v_mfma_f32_16x16x32_bf16 v[44:47], v[144:147], v[190:193], v[44:47]
	v_mfma_f32_16x16x32_bf16 v[40:43], v[158:161], v[190:193], v[40:43]
	v_mfma_f32_16x16x32_bf16 v[28:31], v[144:147], v[198:201], v[28:31]
	v_mfma_f32_16x16x32_bf16 v[24:27], v[158:161], v[198:201], v[24:27]
	v_mfma_f32_16x16x32_bf16 v[12:15], v[144:147], v[206:209], v[12:15]
	v_mfma_f32_16x16x32_bf16 v[8:11], v[158:161], v[206:209], v[8:11]
	v_mfma_f32_16x16x32_bf16 v[60:63], v[154:157], v[186:189], v[60:63]
	v_mfma_f32_16x16x32_bf16 v[56:59], v[162:165], v[186:189], v[56:59]
	v_mfma_f32_16x16x32_bf16 v[44:47], v[154:157], v[194:197], v[44:47]
	v_mfma_f32_16x16x32_bf16 v[40:43], v[162:165], v[194:197], v[40:43]
	v_mfma_f32_16x16x32_bf16 v[28:31], v[154:157], v[202:205], v[28:31]
	v_mfma_f32_16x16x32_bf16 v[24:27], v[162:165], v[202:205], v[24:27]
	v_mfma_f32_16x16x32_bf16 v[12:15], v[154:157], v[210:213], v[12:15]
	v_mfma_f32_16x16x32_bf16 v[8:11], v[162:165], v[210:213], v[8:11]
	v_mfma_f32_16x16x32_bf16 v[52:55], v[166:169], v[182:185], v[52:55]
	v_mfma_f32_16x16x32_bf16 v[48:51], v[174:177], v[182:185], v[48:51]
	v_mfma_f32_16x16x32_bf16 v[36:39], v[166:169], v[190:193], v[36:39]
	v_mfma_f32_16x16x32_bf16 v[32:35], v[174:177], v[190:193], v[32:35]
	v_mfma_f32_16x16x32_bf16 v[20:23], v[166:169], v[198:201], v[20:23]
	v_mfma_f32_16x16x32_bf16 v[16:19], v[174:177], v[198:201], v[16:19]
	v_mfma_f32_16x16x32_bf16 v[4:7], v[166:169], v[206:209], v[4:7]
	v_mfma_f32_16x16x32_bf16 v[0:3], v[174:177], v[206:209], v[0:3]
	v_mfma_f32_16x16x32_bf16 v[52:55], v[170:173], v[186:189], v[52:55]
	v_mfma_f32_16x16x32_bf16 v[48:51], v[178:181], v[186:189], v[48:51]
	v_mfma_f32_16x16x32_bf16 v[36:39], v[170:173], v[194:197], v[36:39]
	v_mfma_f32_16x16x32_bf16 v[32:35], v[178:181], v[194:197], v[32:35]
	v_mfma_f32_16x16x32_bf16 v[20:23], v[170:173], v[202:205], v[20:23]
	v_mfma_f32_16x16x32_bf16 v[16:19], v[178:181], v[202:205], v[16:19]
	v_mfma_f32_16x16x32_bf16 v[4:7], v[170:173], v[210:213], v[4:7]
	v_mfma_f32_16x16x32_bf16 v[0:3], v[178:181], v[210:213], v[0:3]
	s_setprio 0
	s_barrier
; #define PG8_STAGE(bufoff, gbase, voff) do { _Pragma("unroll") for (int _i = 0; _i < 2; ++_i) \
;         __builtin_amdgcn_global_load_lds((const unsigned*)((const char*)(gbase) + (voff)[_i]), (PG8_LAS unsigned*)(lds + (bufoff) + ldsw + _i * 8192), 16, 0, 0); } while (0)
; #define PG8_LDA(dst, b, h) do { _Pragma("unroll") for (int m = 0; m < 4; ++m) _Pragma("unroll") for (int k = 0; k < 2; ++k) dst[m][k] = *(const PG8_LAS bf16x8*)(lds + PG8_SA(b, h) + aoff + m * 2048 + k * 1024); } while (0)
; #define PG8_LDB(dst, b, h) do { _Pragma("unroll") for (int n = 0; n < 2; ++n) _Pragma("unroll") for (int k = 0; k < 2; ++k) dst[n][k] = *(const PG8_LAS bf16x8*)(lds + PG8_SB(b, h) + boff + n * 2048 + k * 1024); } while (0)
; #define PG8_MMA(ai, bj, At, Bt) do { __builtin_amdgcn_s_setprio(1); _Pragma("unroll") for (int m = 0; m < 4; ++m) _Pragma("unroll") for (int n = 0; n < 2; ++n) _Pragma("unroll") for (int k = 0; k < 2; ++k) \
;         acc[ai][bj][m][n] = __builtin_amdgcn_mfma_f32_16x16x32_bf16(Bt[n][k], At[m][k], acc[ai][bj][m][n], 0, 0, 0); __builtin_amdgcn_s_setprio(0); } while (0)
; #define PG8_WAIT_V(n) asm volatile("s_waitcnt vmcnt(" #n ")" ::: "memory")
; #define PG8_WAIT_L(n) asm volatile("s_waitcnt lgkmcnt(" #n ")" ::: "memory")
; #define PG8_BAR __builtin_amdgcn_s_barrier()
; #define PG8_SCHED __builtin_amdgcn_sched_barrier(0)
; template <class Epi, class Sched, bool ALIGN_EPI = false, bool SP2 = false>
; __device__ __forceinline__ void gemm_phase(PG8_LAS unsigned char* lds, const Gemm g, const Sched& S, const Epi& E, const int wave_in) {
;     ...
;             PG8_LDB(B0, 1, 0); PG8_LDB(B1, 1, 1); PG8_SCHED; PG8_LDA(At, 1, 0); PG8_STAGE(PG8_SA(0, 1), a2 + hstepA, voffA);
;             PG8_WAIT_V(8); PG8_WAIT_L(0); PG8_BAR; PG8_MMA(0, 0, At, B0); PG8_MMA(0, 1, At, B1); PG8_BAR; PG8_SCHED;
	s_add_i32 s51, 0, 0x18000
	s_add_i32 s52, 0, 0x1c000
	v_add_u32_e32 v162, s51, v149
	v_add_u32_e32 v178, s52, v149
	ds_read_b128 v[144:147], v162
	ds_read_b128 v[154:157], v162 offset:1024
	ds_read_b128 v[158:161], v162 offset:2048
	ds_read_b128 v[162:165], v162 offset:3072
	ds_read_b128 v[166:169], v178
	ds_read_b128 v[170:173], v178 offset:1024
	ds_read_b128 v[174:177], v178 offset:2048
	ds_read_b128 v[178:181], v178 offset:3072
	s_add_u32 s26, s26, 0x80000
	s_addc_u32 s27, s27, 0
	s_mov_b32 m0, s36
	v_lshl_add_u64 v[222:223], s[26:27], 0, v[128:129]
	ds_read_b128 v[182:185], v153 offset:32768
	ds_read_b128 v[186:189], v153 offset:33792
	ds_read_b128 v[190:193], v153 offset:34816
	ds_read_b128 v[194:197], v153 offset:35840
	ds_read_b128 v[198:201], v153 offset:36864
	ds_read_b128 v[202:205], v153 offset:37888
	ds_read_b128 v[206:209], v153 offset:38912
	ds_read_b128 v[210:213], v153 offset:39936
	global_load_lds_dwordx4 v[222:223], off
	v_lshl_add_u64 v[222:223], s[26:27], 0, v[132:133]
	s_mov_b32 m0, s37
	s_nop 0
	global_load_lds_dwordx4 v[222:223], off
	s_waitcnt vmcnt(8)
	s_waitcnt lgkmcnt(0)
	s_barrier
	s_setprio 1
	v_mfma_f32_16x16x32_bf16 v[124:127], v[144:147], v[182:185], v[124:127]
	v_mfma_f32_16x16x32_bf16 v[120:123], v[158:161], v[182:185], v[120:123]
	v_mfma_f32_16x16x32_bf16 v[108:111], v[144:147], v[190:193], v[108:111]
	v_mfma_f32_16x16x32_bf16 v[104:107], v[158:161], v[190:193], v[104:107]
	v_mfma_f32_16x16x32_bf16 v[92:95], v[144:147], v[198:201], v[92:95]
	v_mfma_f32_16x16x32_bf16 v[88:91], v[158:161], v[198:201], v[88:91]
	v_mfma_f32_16x16x32_bf16 v[76:79], v[144:147], v[206:209], v[76:79]
	v_mfma_f32_16x16x32_bf16 v[72:75], v[158:161], v[206:209], v[72:75]
	v_mfma_f32_16x16x32_bf16 v[124:127], v[154:157], v[186:189], v[124:127]
	v_mfma_f32_16x16x32_bf16 v[120:123], v[162:165], v[186:189], v[120:123]
	v_mfma_f32_16x16x32_bf16 v[108:111], v[154:157], v[194:197], v[108:111]
	v_mfma_f32_16x16x32_bf16 v[104:107], v[162:165], v[194:197], v[104:107]
	v_mfma_f32_16x16x32_bf16 v[92:95], v[154:157], v[202:205], v[92:95]
	v_mfma_f32_16x16x32_bf16 v[88:91], v[162:165], v[202:205], v[88:91]
	v_mfma_f32_16x16x32_bf16 v[76:79], v[154:157], v[210:213], v[76:79]
	v_mfma_f32_16x16x32_bf16 v[72:75], v[162:165], v[210:213], v[72:75]
	v_mfma_f32_16x16x32_bf16 v[116:119], v[166:169], v[182:185], v[116:119]
	v_mfma_f32_16x16x32_bf16 v[112:115], v[174:177], v[182:185], v[112:115]
	v_mfma_f32_16x16x32_bf16 v[100:103], v[166:169], v[190:193], v[100:103]
	v_mfma_f32_16x16x32_bf16 v[96:99], v[174:177], v[190:193], v[96:99]
	v_mfma_f32_16x16x32_bf16 v[84:87], v[166:169], v[198:201], v[84:87]
	v_mfma_f32_16x16x32_bf16 v[80:83], v[174:177], v[198:201], v[80:83]
	v_mfma_f32_16x16x32_bf16 v[68:71], v[166:169], v[206:209], v[68:71]
	v_mfma_f32_16x16x32_bf16 v[64:67], v[174:177], v[206:209], v[64:67]
	v_mfma_f32_16x16x32_bf16 v[116:119], v[170:173], v[186:189], v[116:119]
	v_mfma_f32_16x16x32_bf16 v[112:115], v[178:181], v[186:189], v[112:115]
	v_mfma_f32_16x16x32_bf16 v[100:103], v[170:173], v[194:197], v[100:103]
	v_mfma_f32_16x16x32_bf16 v[96:99], v[178:181], v[194:197], v[96:99]
	v_mfma_f32_16x16x32_bf16 v[84:87], v[170:173], v[202:205], v[84:87]
	v_mfma_f32_16x16x32_bf16 v[80:83], v[178:181], v[202:205], v[80:83]
	v_mfma_f32_16x16x32_bf16 v[68:71], v[170:173], v[210:213], v[68:71]
	v_mfma_f32_16x16x32_bf16 v[64:67], v[178:181], v[210:213], v[64:67]
	s_setprio 0
	s_barrier
; #define PG8_STAGE(bufoff, gbase, voff) do { _Pragma("unroll") for (int _i = 0; _i < 2; ++_i) \
;         __builtin_amdgcn_global_load_lds((const unsigned*)((const char*)(gbase) + (voff)[_i]), (PG8_LAS unsigned*)(lds + (bufoff) + ldsw + _i * 8192), 16, 0, 0); } while (0)
; #define PG8_LDA(dst, b, h) do { _Pragma("unroll") for (int m = 0; m < 4; ++m) _Pragma("unroll") for (int k = 0; k < 2; ++k) dst[m][k] = *(const PG8_LAS bf16x8*)(lds + PG8_SA(b, h) + aoff + m * 2048 + k * 1024); } while (0)
; #define PG8_MMA(ai, bj, At, Bt) do { __builtin_amdgcn_s_setprio(1); _Pragma("unroll") for (int m = 0; m < 4; ++m) _Pragma("unroll") for (int n = 0; n < 2; ++n) _Pragma("unroll") for (int k = 0; k < 2; ++k) \
;         acc[ai][bj][m][n] = __builtin_amdgcn_mfma_f32_16x16x32_bf16(Bt[n][k], At[m][k], acc[ai][bj][m][n], 0, 0, 0); __builtin_amdgcn_s_setprio(0); } while (0)
; #define PG8_WAIT_V(n) asm volatile("s_waitcnt vmcnt(" #n ")" ::: "memory")
; #define PG8_WAIT_L(n) asm volatile("s_waitcnt lgkmcnt(" #n ")" ::: "memory")
; #define PG8_BAR __builtin_amdgcn_s_barrier()
; #define PG8_SCHED __builtin_amdgcn_sched_barrier(0)
; template <class Epi, class Sched, bool ALIGN_EPI = false, bool SP2 = false>
; __device__ __forceinline__ void gemm_phase(PG8_LAS unsigned char* lds, const Gemm g, const Sched& S, const Epi& E, const int wave_in) {
;     ...
;         for (int t = 0; t < nt; t += 2) {
;             const bool last = (t == nt - 2);
;             const char* a1 = cA + (size_t)(t + 1) * kstep;
;     ...
;             PG8_LDA(At, 1, 1); PG8_STAGE(PG8_SB(1, 0), b3, voffB); PG8_STAGE(PG8_SB(1, 1), b3 + hstepB, voffB); PG8_STAGE(PG8_SA(1, 0), a3, voffA);
;             PG8_WAIT_V(8); PG8_WAIT_L(0); PG8_BAR; PG8_MMA(1, 0, At, B0); PG8_MMA(1, 1, At, B1); PG8_BAR; PG8_SCHED;
	s_add_i32 s26, s51, s34
	v_lshl_add_u64 v[214:215], v[214:215], 0, s[8:9]
	s_mov_b32 m0, s26
	ds_read_b128 v[182:185], v153 offset:49152
	ds_read_b128 v[186:189], v153 offset:50176
	ds_read_b128 v[190:193], v153 offset:51200
	ds_read_b128 v[194:197], v153 offset:52224
	ds_read_b128 v[198:201], v153 offset:53248
	ds_read_b128 v[202:205], v153 offset:54272
	ds_read_b128 v[206:209], v153 offset:55296
	ds_read_b128 v[210:213], v153 offset:56320
	global_load_lds_dwordx4 v[214:215], off
	s_add_i32 m0, s26, 0x2000
	s_add_u32 s24, s24, 0x80080
	v_lshl_add_u64 v[214:215], v[216:217], 0, s[8:9]
	s_addc_u32 s25, s25, 0
	s_add_i32 s26, s52, s34
	global_load_lds_dwordx4 v[214:215], off
	v_lshl_add_u64 v[214:215], s[24:25], 0, v[130:131]
	s_mov_b32 m0, s26
	s_nop 0
	global_load_lds_dwordx4 v[214:215], off
	v_lshl_add_u64 v[214:215], s[24:25], 0, v[134:135]
	s_add_i32 m0, s26, 0x2000
	s_nop 0
	global_load_lds_dwordx4 v[214:215], off
	v_lshl_add_u64 v[214:215], v[218:219], 0, s[8:9]
	s_mov_b32 m0, s39
	s_nop 0
	global_load_lds_dwordx4 v[214:215], off
	v_lshl_add_u64 v[214:215], v[220:221], 0, s[8:9]
	s_mov_b32 m0, s40
	s_nop 0
	global_load_lds_dwordx4 v[214:215], off
	s_waitcnt vmcnt(8)
	s_waitcnt lgkmcnt(0)
	s_barrier
	s_setprio 1
	v_mfma_f32_16x16x32_bf16 v[60:63], v[144:147], v[182:185], v[60:63]
	v_mfma_f32_16x16x32_bf16 v[56:59], v[158:161], v[182:185], v[56:59]
	v_mfma_f32_16x16x32_bf16 v[44:47], v[144:147], v[190:193], v[44:47]
	v_mfma_f32_16x16x32_bf16 v[40:43], v[158:161], v[190:193], v[40:43]
	v_mfma_f32_16x16x32_bf16 v[28:31], v[144:147], v[198:201], v[28:31]
	v_mfma_f32_16x16x32_bf16 v[24:27], v[158:161], v[198:201], v[24:27]
	v_mfma_f32_16x16x32_bf16 v[12:15], v[144:147], v[206:209], v[12:15]
	v_mfma_f32_16x16x32_bf16 v[8:11], v[158:161], v[206:209], v[8:11]
	v_mfma_f32_16x16x32_bf16 v[60:63], v[154:157], v[186:189], v[60:63]
	v_mfma_f32_16x16x32_bf16 v[56:59], v[162:165], v[186:189], v[56:59]
	v_mfma_f32_16x16x32_bf16 v[44:47], v[154:157], v[194:197], v[44:47]
	v_mfma_f32_16x16x32_bf16 v[40:43], v[162:165], v[194:197], v[40:43]
	v_mfma_f32_16x16x32_bf16 v[28:31], v[154:157], v[202:205], v[28:31]
	v_mfma_f32_16x16x32_bf16 v[24:27], v[162:165], v[202:205], v[24:27]
	v_mfma_f32_16x16x32_bf16 v[12:15], v[154:157], v[210:213], v[12:15]
	v_mfma_f32_16x16x32_bf16 v[8:11], v[162:165], v[210:213], v[8:11]
	v_mfma_f32_16x16x32_bf16 v[52:55], v[166:169], v[182:185], v[52:55]
	v_mfma_f32_16x16x32_bf16 v[48:51], v[174:177], v[182:185], v[48:51]
	v_mfma_f32_16x16x32_bf16 v[36:39], v[166:169], v[190:193], v[36:39]
	v_mfma_f32_16x16x32_bf16 v[32:35], v[174:177], v[190:193], v[32:35]
	v_mfma_f32_16x16x32_bf16 v[20:23], v[166:169], v[198:201], v[20:23]
	v_mfma_f32_16x16x32_bf16 v[16:19], v[174:177], v[198:201], v[16:19]
	v_mfma_f32_16x16x32_bf16 v[4:7], v[166:169], v[206:209], v[4:7]
	v_mfma_f32_16x16x32_bf16 v[0:3], v[174:177], v[206:209], v[0:3]
	v_mfma_f32_16x16x32_bf16 v[52:55], v[170:173], v[186:189], v[52:55]
	v_mfma_f32_16x16x32_bf16 v[48:51], v[178:181], v[186:189], v[48:51]
	v_mfma_f32_16x16x32_bf16 v[36:39], v[170:173], v[194:197], v[36:39]
	v_mfma_f32_16x16x32_bf16 v[32:35], v[178:181], v[194:197], v[32:35]
	v_mfma_f32_16x16x32_bf16 v[20:23], v[170:173], v[202:205], v[20:23]
	v_mfma_f32_16x16x32_bf16 v[16:19], v[178:181], v[202:205], v[16:19]
	v_mfma_f32_16x16x32_bf16 v[4:7], v[170:173], v[210:213], v[4:7]
	v_mfma_f32_16x16x32_bf16 v[0:3], v[178:181], v[210:213], v[0:3]
	s_setprio 0
	s_barrier
	s_add_i32 s50, s50, 2
	s_add_u32 s22, s22, 0x100
	s_addc_u32 s23, s23, 0
	s_add_u32 s48, s48, 0x100
	s_addc_u32 s49, s49, 0
	s_cmp_gt_u32 s50, 29
	s_cbranch_scc0 .LBB0_2248

;     __host__ __device__ bool next(int i, Unit& u) const { const bool ok = StaticOrder::next(i, u); u.pm = 0; u.pn = 0; return ok; }
; #define PG8_STAGE(bufoff, gbase, voff) do { _Pragma("unroll") for (int _i = 0; _i < 2; ++_i) \
;         __builtin_amdgcn_global_load_lds((const unsigned*)((const char*)(gbase) + (voff)[_i]), (PG8_LAS unsigned*)(lds + (bufoff) + ldsw + _i * 8192), 16, 0, 0); } while (0)
; #define PG8_LDA(dst, b, h) do { _Pragma("unroll") for (int m = 0; m < 4; ++m) _Pragma("unroll") for (int k = 0; k < 2; ++k) dst[m][k] = *(const PG8_LAS bf16x8*)(lds + PG8_SA(b, h) + aoff + m * 2048 + k * 1024); } while (0)
; #define PG8_LDB(dst, b, h) do { _Pragma("unroll") for (int n = 0; n < 2; ++n) _Pragma("unroll") for (int k = 0; k < 2; ++k) dst[n][k] = *(const PG8_LAS bf16x8*)(lds + PG8_SB(b, h) + boff + n * 2048 + k * 1024); } while (0)
; #define PG8_WAIT_V(n) asm volatile("s_waitcnt vmcnt(" #n ")" ::: "memory")
; #define PG8_BAR __builtin_amdgcn_s_barrier()
; template <class Epi, class Sched, bool ALIGN_EPI = false, bool SP2 = false>
; __device__ __forceinline__ void gemm_phase(PG8_LAS unsigned char* lds, const Gemm g, const Sched& S, const Epi& E, const int wave_in) {
;     ...
;         const bool has_next = S.next(ui + 1, nxt);
;         const char* nA = has_next ? (const char*)g.A + (size_t)nxt.pm * tstepA : cA; const char* nB = has_next ? (const char*)g.Bt + (size_t)nxt.pn * tstepB : cB;
;         for (int t = 0; t < nt; t += 2) {
;             const bool last = (t == nt - 2);
;             const char* a1 = cA + (size_t)(t + 1) * kstep;
;             const char* a2 = last ? nA : cA + (size_t)(t + 2) * kstep; const char* b2 = last ? nB : cB + (size_t)(t + 2) * kstep;
;             const char* a3 = a2 + kstep; const char* b3 = b2 + kstep;
;             if (last && has_next) S.a_ready(nxt);
;             if constexpr (SP2) {
;             PG8_LDB(B0, 0, 0); PG8_LDB(B1, 0, 1); PG8_SCHED; PG8_LDA(At, 0, 0); PG8_STAGE(PG8_SA(1, 1), a1 + hstepA, voffA);
;             PG8_WAIT_V(8); PG8_WAIT_L(0); PG8_BAR; PG8_MMA(0, 0, At, B0); PG8_MMA(0, 1, At, B1); PG8_BAR; PG8_SCHED;
;             PG8_LDA(At, 0, 1); PG8_STAGE(PG8_SB(0, 0), b2, voffB); PG8_STAGE(PG8_SB(0, 1), b2 + hstepB, voffB); PG8_STAGE(PG8_SA(0, 0), a2, voffA);
;             PG8_WAIT_V(8); PG8_WAIT_L(0); PG8_BAR; PG8_MMA(1, 0, At, B0); PG8_MMA(1, 1, At, B1); PG8_BAR; PG8_SCHED;
.LBB0_2450:
	s_ashr_i32 s19, s18, 31
	s_lshl_b64 s[22:23], s[18:19], 20
	s_add_u32 s22, s37, s22
	s_addc_u32 s23, s38, s23
	s_and_b64 s[4:5], s[4:5], exec
	s_cselect_b32 s19, s23, s29
	s_cselect_b32 s25, s22, s28
	s_add_u32 s58, s28, 0x100
	v_mov_b32_e32 v0, 0
	s_addc_u32 s59, s29, 0
	s_mov_b32 s60, -2
	s_waitcnt vmcnt(0)
	ds_read_b128 v[128:131], v170
	ds_read_b128 v[132:135], v170 offset:1024
	ds_read_b128 v[136:139], v170 offset:2048
	ds_read_b128 v[140:143], v170 offset:3072
	ds_read_b128 v[162:165], v171
	ds_read_b128 v[174:177], v171 offset:1024
	ds_read_b128 v[178:181], v171 offset:2048
	ds_read_b128 v[182:185], v171 offset:3072
	s_add_u32 s4, s26, 0x100
	s_addc_u32 s5, s27, 0
	s_cmp_eq_u32 s60, 28
	s_cselect_b32 s31, s21, s5
	s_cselect_b32 s30, s20, s4
	s_cselect_b32 s29, s19, s59
	s_cselect_b32 s28, s25, s58
	v_lshl_add_u64 v[166:167], s[26:27], 0, v[154:155]
	s_add_i32 m0, s40, 0xc000
	ds_read_b128 v[186:189], v172
	ds_read_b128 v[190:193], v172 offset:1024
	ds_read_b128 v[194:197], v172 offset:2048
	ds_read_b128 v[198:201], v172 offset:3072
	ds_read_b128 v[202:205], v172 offset:4096
	ds_read_b128 v[206:209], v172 offset:5120
	ds_read_b128 v[210:213], v172 offset:6144
	ds_read_b128 v[214:217], v172 offset:7168
	global_load_lds_dwordx4 v[166:167], off
	v_lshl_add_u64 v[166:167], s[26:27], 0, v[156:157]
	s_add_i32 m0, s40, 0xe000
	s_nop 0
	global_load_lds_dwordx4 v[166:167], off
	s_waitcnt vmcnt(8)
	s_waitcnt lgkmcnt(0)
	s_barrier
	s_setprio 1
	v_mfma_f32_16x16x32_bf16 v[124:127], v[128:131], v[186:189], 0
	v_mfma_f32_16x16x32_bf16 v[120:123], v[136:139], v[186:189], 0
	v_mfma_f32_16x16x32_bf16 v[112:115], v[128:131], v[194:197], 0
	v_mfma_f32_16x16x32_bf16 v[104:107], v[136:139], v[194:197], 0
	v_mfma_f32_16x16x32_bf16 v[96:99], v[128:131], v[202:205], 0
	v_mfma_f32_16x16x32_bf16 v[88:91], v[136:139], v[202:205], 0
	v_mfma_f32_16x16x32_bf16 v[80:83], v[128:131], v[210:213], 0
	v_mfma_f32_16x16x32_bf16 v[72:75], v[136:139], v[210:213], 0
	v_mfma_f32_16x16x32_bf16 v[124:127], v[132:135], v[190:193], v[124:127]
	v_mfma_f32_16x16x32_bf16 v[120:123], v[140:143], v[190:193], v[120:123]
	v_mfma_f32_16x16x32_bf16 v[112:115], v[132:135], v[198:201], v[112:115]
	v_mfma_f32_16x16x32_bf16 v[104:107], v[140:143], v[198:201], v[104:107]
	v_mfma_f32_16x16x32_bf16 v[96:99], v[132:135], v[206:209], v[96:99]
	v_mfma_f32_16x16x32_bf16 v[88:91], v[140:143], v[206:209], v[88:91]
	v_mfma_f32_16x16x32_bf16 v[80:83], v[132:135], v[214:217], v[80:83]
	v_mfma_f32_16x16x32_bf16 v[72:75], v[140:143], v[214:217], v[72:75]
	v_mfma_f32_16x16x32_bf16 v[116:119], v[162:165], v[186:189], 0
	v_mfma_f32_16x16x32_bf16 v[108:111], v[178:181], v[186:189], 0
	v_mfma_f32_16x16x32_bf16 v[100:103], v[162:165], v[194:197], 0
	v_mfma_f32_16x16x32_bf16 v[92:95], v[178:181], v[194:197], 0
	v_mfma_f32_16x16x32_bf16 v[84:87], v[162:165], v[202:205], 0
	v_mfma_f32_16x16x32_bf16 v[76:79], v[178:181], v[202:205], 0
	v_mfma_f32_16x16x32_bf16 v[68:71], v[162:165], v[210:213], 0
	v_mfma_f32_16x16x32_bf16 v[64:67], v[178:181], v[210:213], 0
	v_mfma_f32_16x16x32_bf16 v[116:119], v[174:177], v[190:193], v[116:119]
	v_mfma_f32_16x16x32_bf16 v[108:111], v[182:185], v[190:193], v[108:111]
	v_mfma_f32_16x16x32_bf16 v[100:103], v[174:177], v[198:201], v[100:103]
	v_mfma_f32_16x16x32_bf16 v[92:95], v[182:185], v[198:201], v[92:95]
	v_mfma_f32_16x16x32_bf16 v[84:87], v[174:177], v[206:209], v[84:87]
	v_mfma_f32_16x16x32_bf16 v[76:79], v[182:185], v[206:209], v[76:79]
	v_mfma_f32_16x16x32_bf16 v[68:71], v[174:177], v[214:217], v[68:71]
	v_mfma_f32_16x16x32_bf16 v[64:67], v[182:185], v[214:217], v[64:67]
	s_setprio 0
	s_barrier
	s_add_i32 s26, s50, s39
	v_lshl_add_u64 v[166:167], s[28:29], 0, v[146:147]
	s_mov_b32 m0, s26
	ds_read_b128 v[186:189], v172 offset:16384
	ds_read_b128 v[190:193], v172 offset:17408
	ds_read_b128 v[194:197], v172 offset:18432
	ds_read_b128 v[198:201], v172 offset:19456
	ds_read_b128 v[202:205], v172 offset:20480
	ds_read_b128 v[206:209], v172 offset:21504
	ds_read_b128 v[210:213], v172 offset:22528
	ds_read_b128 v[214:217], v172 offset:23552
	global_load_lds_dwordx4 v[166:167], off
	s_add_i32 m0, s26, 0x2000
	s_add_u32 s26, s28, 0x80000
	v_lshl_add_u64 v[218:219], s[28:29], 0, v[150:151]
	s_addc_u32 s27, s29, 0
	s_add_i32 s61, s51, s39
	global_load_lds_dwordx4 v[218:219], off
	v_lshl_add_u64 v[220:221], s[26:27], 0, v[146:147]
	s_mov_b32 m0, s61
	v_lshl_add_u64 v[222:223], s[30:31], 0, v[148:149]
	global_load_lds_dwordx4 v[220:221], off
	v_lshl_add_u64 v[220:221], s[26:27], 0, v[150:151]
	s_add_i32 m0, s61, 0x2000
	s_nop 0
	global_load_lds_dwordx4 v[220:221], off
	v_lshl_add_u64 v[220:221], s[30:31], 0, v[144:145]
	s_mov_b32 m0, s40
	s_nop 0
	global_load_lds_dwordx4 v[220:221], off
	s_mov_b32 m0, s41
	s_nop 0
	global_load_lds_dwordx4 v[222:223], off
	s_waitcnt vmcnt(8)
	s_waitcnt lgkmcnt(0)
	s_barrier
; #define PG8_STAGE(bufoff, gbase, voff) do { _Pragma("unroll") for (int _i = 0; _i < 2; ++_i) \
;         __builtin_amdgcn_global_load_lds((const unsigned*)((const char*)(gbase) + (voff)[_i]), (PG8_LAS unsigned*)(lds + (bufoff) + ldsw + _i * 8192), 16, 0, 0); } while (0)
; #define PG8_LDA(dst, b, h) do { _Pragma("unroll") for (int m = 0; m < 4; ++m) _Pragma("unroll") for (int k = 0; k < 2; ++k) dst[m][k] = *(const PG8_LAS bf16x8*)(lds + PG8_SA(b, h) + aoff + m * 2048 + k * 1024); } while (0)
; #define PG8_LDB(dst, b, h) do { _Pragma("unroll") for (int n = 0; n < 2; ++n) _Pragma("unroll") for (int k = 0; k < 2; ++k) dst[n][k] = *(const PG8_LAS bf16x8*)(lds + PG8_SB(b, h) + boff + n * 2048 + k * 1024); } while (0)
; #define PG8_MMA(ai, bj, At, Bt) do { __builtin_amdgcn_s_setprio(1); _Pragma("unroll") for (int m = 0; m < 4; ++m) _Pragma("unroll") for (int n = 0; n < 2; ++n) _Pragma("unroll") for (int k = 0; k < 2; ++k) \
;         acc[ai][bj][m][n] = __builtin_amdgcn_mfma_f32_16x16x32_bf16(Bt[n][k], At[m][k], acc[ai][bj][m][n], 0, 0, 0); __builtin_amdgcn_s_setprio(0); } while (0)
; #define PG8_WAIT_V(n) asm volatile("s_waitcnt vmcnt(" #n ")" ::: "memory")
; #define PG8_WAIT_L(n) asm volatile("s_waitcnt lgkmcnt(" #n ")" ::: "memory")
; #define PG8_BAR __builtin_amdgcn_s_barrier()
; #define PG8_SCHED __builtin_amdgcn_sched_barrier(0)
; template <class Epi, class Sched, bool ALIGN_EPI = false, bool SP2 = false>
; __device__ __forceinline__ void gemm_phase(PG8_LAS unsigned char* lds, const Gemm g, const Sched& S, const Epi& E, const int wave_in) {
;     ...
;             PG8_WAIT_V(8); PG8_WAIT_L(0); PG8_BAR; PG8_MMA(0, 0, At, B0); PG8_MMA(0, 1, At, B1); PG8_BAR; PG8_SCHED;
;             PG8_LDA(At, 0, 1); PG8_STAGE(PG8_SB(0, 0), b2, voffB); PG8_STAGE(PG8_SB(0, 1), b2 + hstepB, voffB); PG8_STAGE(PG8_SA(0, 0), a2, voffA);
;             PG8_WAIT_V(8); PG8_WAIT_L(0); PG8_BAR; PG8_MMA(1, 0, At, B0); PG8_MMA(1, 1, At, B1); PG8_BAR; PG8_SCHED;
;             PG8_LDB(B0, 1, 0); PG8_LDB(B1, 1, 1); PG8_SCHED; PG8_LDA(At, 1, 0); PG8_STAGE(PG8_SA(0, 1), a2 + hstepA, voffA);
;             PG8_WAIT_V(8); PG8_WAIT_L(0); PG8_BAR; PG8_MMA(0, 0, At, B0); PG8_MMA(0, 1, At, B1); PG8_BAR; PG8_SCHED;
	s_setprio 1
	v_mfma_f32_16x16x32_bf16 v[60:63], v[128:131], v[186:189], 0
	v_mfma_f32_16x16x32_bf16 v[56:59], v[136:139], v[186:189], 0
	v_mfma_f32_16x16x32_bf16 v[48:51], v[128:131], v[194:197], 0
	v_mfma_f32_16x16x32_bf16 v[40:43], v[136:139], v[194:197], 0
	v_mfma_f32_16x16x32_bf16 v[32:35], v[128:131], v[202:205], 0
	v_mfma_f32_16x16x32_bf16 v[24:27], v[136:139], v[202:205], 0
	v_mfma_f32_16x16x32_bf16 v[16:19], v[128:131], v[210:213], 0
	v_mfma_f32_16x16x32_bf16 v[8:11], v[136:139], v[210:213], 0
	v_mfma_f32_16x16x32_bf16 v[60:63], v[132:135], v[190:193], v[60:63]
	v_mfma_f32_16x16x32_bf16 v[56:59], v[140:143], v[190:193], v[56:59]
	v_mfma_f32_16x16x32_bf16 v[48:51], v[132:135], v[198:201], v[48:51]
	v_mfma_f32_16x16x32_bf16 v[40:43], v[140:143], v[198:201], v[40:43]
	v_mfma_f32_16x16x32_bf16 v[32:35], v[132:135], v[206:209], v[32:35]
	v_mfma_f32_16x16x32_bf16 v[24:27], v[140:143], v[206:209], v[24:27]
	v_mfma_f32_16x16x32_bf16 v[16:19], v[132:135], v[214:217], v[16:19]
	v_mfma_f32_16x16x32_bf16 v[8:11], v[140:143], v[214:217], v[8:11]
	v_mfma_f32_16x16x32_bf16 v[52:55], v[162:165], v[186:189], 0
	v_mfma_f32_16x16x32_bf16 v[44:47], v[178:181], v[186:189], 0
	v_mfma_f32_16x16x32_bf16 v[36:39], v[162:165], v[194:197], 0
	v_mfma_f32_16x16x32_bf16 v[28:31], v[178:181], v[194:197], 0
	v_mfma_f32_16x16x32_bf16 v[20:23], v[162:165], v[202:205], 0
	v_mfma_f32_16x16x32_bf16 v[12:15], v[178:181], v[202:205], 0
	v_mfma_f32_16x16x32_bf16 v[4:7], v[162:165], v[210:213], 0
	v_mfma_f32_16x16x32_bf16 v[0:3], v[178:181], v[210:213], 0
	v_mfma_f32_16x16x32_bf16 v[52:55], v[174:177], v[190:193], v[52:55]
	v_mfma_f32_16x16x32_bf16 v[44:47], v[182:185], v[190:193], v[44:47]
	v_mfma_f32_16x16x32_bf16 v[36:39], v[174:177], v[198:201], v[36:39]
	v_mfma_f32_16x16x32_bf16 v[28:31], v[182:185], v[198:201], v[28:31]
	v_mfma_f32_16x16x32_bf16 v[20:23], v[174:177], v[206:209], v[20:23]
	v_mfma_f32_16x16x32_bf16 v[12:15], v[182:185], v[206:209], v[12:15]
	v_mfma_f32_16x16x32_bf16 v[4:7], v[174:177], v[214:217], v[4:7]
	v_mfma_f32_16x16x32_bf16 v[0:3], v[182:185], v[214:217], v[0:3]
	s_setprio 0
	s_barrier
	s_add_i32 s61, 0, 0x18000
	s_add_i32 s62, 0, 0x1c000
	v_add_u32_e32 v140, s61, v168
	v_add_u32_e32 v173, s62, v168
	ds_read_b128 v[128:131], v140
	ds_read_b128 v[132:135], v140 offset:1024
	ds_read_b128 v[136:139], v140 offset:2048
	ds_read_b128 v[140:143], v140 offset:3072
	ds_read_b128 v[162:165], v173
	ds_read_b128 v[174:177], v173 offset:1024
	ds_read_b128 v[178:181], v173 offset:2048
	ds_read_b128 v[182:185], v173 offset:3072
	s_add_u32 s26, s30, 0x280000
	s_addc_u32 s27, s31, 0
	s_mov_b32 m0, s42
	v_lshl_add_u64 v[224:225], s[26:27], 0, v[144:145]
	ds_read_b128 v[186:189], v172 offset:32768
	ds_read_b128 v[190:193], v172 offset:33792
	ds_read_b128 v[194:197], v172 offset:34816
	ds_read_b128 v[198:201], v172 offset:35840
	ds_read_b128 v[202:205], v172 offset:36864
	ds_read_b128 v[206:209], v172 offset:37888
	ds_read_b128 v[210:213], v172 offset:38912
	ds_read_b128 v[214:217], v172 offset:39936
	global_load_lds_dwordx4 v[224:225], off
	v_lshl_add_u64 v[224:225], s[26:27], 0, v[148:149]
	s_mov_b32 m0, s43
	s_nop 0
	global_load_lds_dwordx4 v[224:225], off
	s_waitcnt vmcnt(8)
	s_waitcnt lgkmcnt(0)
	s_barrier
	s_setprio 1
	v_mfma_f32_16x16x32_bf16 v[124:127], v[128:131], v[186:189], v[124:127]
	v_mfma_f32_16x16x32_bf16 v[120:123], v[136:139], v[186:189], v[120:123]
	v_mfma_f32_16x16x32_bf16 v[112:115], v[128:131], v[194:197], v[112:115]
	v_mfma_f32_16x16x32_bf16 v[104:107], v[136:139], v[194:197], v[104:107]
	v_mfma_f32_16x16x32_bf16 v[96:99], v[128:131], v[202:205], v[96:99]
	v_mfma_f32_16x16x32_bf16 v[88:91], v[136:139], v[202:205], v[88:91]
	v_mfma_f32_16x16x32_bf16 v[80:83], v[128:131], v[210:213], v[80:83]
	v_mfma_f32_16x16x32_bf16 v[72:75], v[136:139], v[210:213], v[72:75]
	v_mfma_f32_16x16x32_bf16 v[124:127], v[132:135], v[190:193], v[124:127]
	v_mfma_f32_16x16x32_bf16 v[120:123], v[140:143], v[190:193], v[120:123]
	v_mfma_f32_16x16x32_bf16 v[112:115], v[132:135], v[198:201], v[112:115]
	v_mfma_f32_16x16x32_bf16 v[104:107], v[140:143], v[198:201], v[104:107]
	v_mfma_f32_16x16x32_bf16 v[96:99], v[132:135], v[206:209], v[96:99]
	v_mfma_f32_16x16x32_bf16 v[88:91], v[140:143], v[206:209], v[88:91]
	v_mfma_f32_16x16x32_bf16 v[80:83], v[132:135], v[214:217], v[80:83]
	v_mfma_f32_16x16x32_bf16 v[72:75], v[140:143], v[214:217], v[72:75]
	v_mfma_f32_16x16x32_bf16 v[116:119], v[162:165], v[186:189], v[116:119]
	v_mfma_f32_16x16x32_bf16 v[108:111], v[178:181], v[186:189], v[108:111]
	v_mfma_f32_16x16x32_bf16 v[100:103], v[162:165], v[194:197], v[100:103]
	v_mfma_f32_16x16x32_bf16 v[92:95], v[178:181], v[194:197], v[92:95]
	v_mfma_f32_16x16x32_bf16 v[84:87], v[162:165], v[202:205], v[84:87]
	v_mfma_f32_16x16x32_bf16 v[76:79], v[178:181], v[202:205], v[76:79]
	v_mfma_f32_16x16x32_bf16 v[68:71], v[162:165], v[210:213], v[68:71]
	v_mfma_f32_16x16x32_bf16 v[64:67], v[178:181], v[210:213], v[64:67]
	v_mfma_f32_16x16x32_bf16 v[116:119], v[174:177], v[190:193], v[116:119]
	v_mfma_f32_16x16x32_bf16 v[108:111], v[182:185], v[190:193], v[108:111]
	v_mfma_f32_16x16x32_bf16 v[100:103], v[174:177], v[198:201], v[100:103]
	v_mfma_f32_16x16x32_bf16 v[92:95], v[182:185], v[198:201], v[92:95]
	v_mfma_f32_16x16x32_bf16 v[84:87], v[174:177], v[206:209], v[84:87]
	v_mfma_f32_16x16x32_bf16 v[76:79], v[182:185], v[206:209], v[76:79]
	v_mfma_f32_16x16x32_bf16 v[68:71], v[174:177], v[214:217], v[68:71]
	v_mfma_f32_16x16x32_bf16 v[64:67], v[182:185], v[214:217], v[64:67]
	s_setprio 0
	s_barrier
; #define PG8_STAGE(bufoff, gbase, voff) do { _Pragma("unroll") for (int _i = 0; _i < 2; ++_i) \
;         __builtin_amdgcn_global_load_lds((const unsigned*)((const char*)(gbase) + (voff)[_i]), (PG8_LAS unsigned*)(lds + (bufoff) + ldsw + _i * 8192), 16, 0, 0); } while (0)
; #define PG8_LDA(dst, b, h) do { _Pragma("unroll") for (int m = 0; m < 4; ++m) _Pragma("unroll") for (int k = 0; k < 2; ++k) dst[m][k] = *(const PG8_LAS bf16x8*)(lds + PG8_SA(b, h) + aoff + m * 2048 + k * 1024); } while (0)
; #define PG8_LDB(dst, b, h) do { _Pragma("unroll") for (int n = 0; n < 2; ++n) _Pragma("unroll") for (int k = 0; k < 2; ++k) dst[n][k] = *(const PG8_LAS bf16x8*)(lds + PG8_SB(b, h) + boff + n * 2048 + k * 1024); } while (0)
; #define PG8_WAIT_V(n) asm volatile("s_waitcnt vmcnt(" #n ")" ::: "memory")
; #define PG8_WAIT_L(n) asm volatile("s_waitcnt lgkmcnt(" #n ")" ::: "memory")
; #define PG8_BAR __builtin_amdgcn_s_barrier()
; template <class Epi, class Sched, bool ALIGN_EPI = false, bool SP2 = false>
; __device__ __forceinline__ void gemm_phase(PG8_LAS unsigned char* lds, const Gemm g, const Sched& S, const Epi& E, const int wave_in) {
;     ...
;         for (int t = 0; t < nt; t += 2) {
;             const bool last = (t == nt - 2);
;             const char* a1 = cA + (size_t)(t + 1) * kstep;
;             const char* a2 = last ? nA : cA + (size_t)(t + 2) * kstep; const char* b2 = last ? nB : cB + (size_t)(t + 2) * kstep;
;             const char* a3 = a2 + kstep; const char* b3 = b2 + kstep;
;             if (last && has_next) S.a_ready(nxt);
;             if constexpr (SP2) {
;             PG8_LDB(B0, 0, 0); PG8_LDB(B1, 0, 1); PG8_SCHED; PG8_LDA(At, 0, 0); PG8_STAGE(PG8_SA(1, 1), a1 + hstepA, voffA);
;             PG8_WAIT_V(8); PG8_WAIT_L(0); PG8_BAR; PG8_MMA(0, 0, At, B0); PG8_MMA(0, 1, At, B1); PG8_BAR; PG8_SCHED;
;             PG8_LDA(At, 0, 1); PG8_STAGE(PG8_SB(0, 0), b2, voffB); PG8_STAGE(PG8_SB(0, 1), b2 + hstepB, voffB); PG8_STAGE(PG8_SA(0, 0), a2, voffA);
;             PG8_WAIT_V(8); PG8_WAIT_L(0); PG8_BAR; PG8_MMA(1, 0, At, B0); PG8_MMA(1, 1, At, B1); PG8_BAR; PG8_SCHED;
;     ...
;             PG8_LDA(At, 1, 1); PG8_STAGE(PG8_SB(1, 0), b3, voffB); PG8_STAGE(PG8_SB(1, 1), b3 + hstepB, voffB); PG8_STAGE(PG8_SA(1, 0), a3, voffA);
;             PG8_WAIT_V(8); PG8_WAIT_L(0); PG8_BAR; PG8_MMA(1, 0, At, B0); PG8_MMA(1, 1, At, B1); PG8_BAR; PG8_SCHED;
	s_add_i32 s26, s61, s39
	v_lshl_add_u64 v[166:167], v[166:167], 0, s[8:9]
	s_mov_b32 m0, s26
	ds_read_b128 v[186:189], v172 offset:49152
	ds_read_b128 v[190:193], v172 offset:50176
	ds_read_b128 v[194:197], v172 offset:51200
	ds_read_b128 v[198:201], v172 offset:52224
	ds_read_b128 v[202:205], v172 offset:53248
	ds_read_b128 v[206:209], v172 offset:54272
	ds_read_b128 v[210:213], v172 offset:55296
	ds_read_b128 v[214:217], v172 offset:56320
	global_load_lds_dwordx4 v[166:167], off
	s_add_i32 m0, s26, 0x2000
	s_add_u32 s26, s28, 0x80080
	v_lshl_add_u64 v[166:167], v[218:219], 0, s[8:9]
	s_addc_u32 s27, s29, 0
	s_add_i32 s28, s62, s39
	global_load_lds_dwordx4 v[166:167], off
	v_lshl_add_u64 v[166:167], s[26:27], 0, v[146:147]
	s_mov_b32 m0, s28
	s_nop 0
	global_load_lds_dwordx4 v[166:167], off
	v_lshl_add_u64 v[166:167], s[26:27], 0, v[150:151]
	s_add_i32 m0, s28, 0x2000
	s_nop 0
	global_load_lds_dwordx4 v[166:167], off
	v_lshl_add_u64 v[166:167], v[220:221], 0, s[8:9]
	s_mov_b32 m0, s47
	s_nop 0
	global_load_lds_dwordx4 v[166:167], off
	v_lshl_add_u64 v[166:167], v[222:223], 0, s[8:9]
	s_mov_b32 m0, s48
	s_nop 0
	global_load_lds_dwordx4 v[166:167], off
	s_waitcnt vmcnt(8)
	s_waitcnt lgkmcnt(0)
	s_barrier
	s_setprio 1
	v_mfma_f32_16x16x32_bf16 v[60:63], v[128:131], v[186:189], v[60:63]
	v_mfma_f32_16x16x32_bf16 v[56:59], v[136:139], v[186:189], v[56:59]
	v_mfma_f32_16x16x32_bf16 v[48:51], v[128:131], v[194:197], v[48:51]
	v_mfma_f32_16x16x32_bf16 v[40:43], v[136:139], v[194:197], v[40:43]
	v_mfma_f32_16x16x32_bf16 v[32:35], v[128:131], v[202:205], v[32:35]
	v_mfma_f32_16x16x32_bf16 v[24:27], v[136:139], v[202:205], v[24:27]
	v_mfma_f32_16x16x32_bf16 v[16:19], v[128:131], v[210:213], v[16:19]
	v_mfma_f32_16x16x32_bf16 v[8:11], v[136:139], v[210:213], v[8:11]
	v_mfma_f32_16x16x32_bf16 v[60:63], v[132:135], v[190:193], v[60:63]
	v_mfma_f32_16x16x32_bf16 v[56:59], v[140:143], v[190:193], v[56:59]
	v_mfma_f32_16x16x32_bf16 v[48:51], v[132:135], v[198:201], v[48:51]
	v_mfma_f32_16x16x32_bf16 v[40:43], v[140:143], v[198:201], v[40:43]
	v_mfma_f32_16x16x32_bf16 v[32:35], v[132:135], v[206:209], v[32:35]
	v_mfma_f32_16x16x32_bf16 v[24:27], v[140:143], v[206:209], v[24:27]
	v_mfma_f32_16x16x32_bf16 v[16:19], v[132:135], v[214:217], v[16:19]
	v_mfma_f32_16x16x32_bf16 v[8:11], v[140:143], v[214:217], v[8:11]
	v_mfma_f32_16x16x32_bf16 v[52:55], v[162:165], v[186:189], v[52:55]
	v_mfma_f32_16x16x32_bf16 v[44:47], v[178:181], v[186:189], v[44:47]
	v_mfma_f32_16x16x32_bf16 v[36:39], v[162:165], v[194:197], v[36:39]
	v_mfma_f32_16x16x32_bf16 v[28:31], v[178:181], v[194:197], v[28:31]
	v_mfma_f32_16x16x32_bf16 v[20:23], v[162:165], v[202:205], v[20:23]
	v_mfma_f32_16x16x32_bf16 v[12:15], v[178:181], v[202:205], v[12:15]
	v_mfma_f32_16x16x32_bf16 v[4:7], v[162:165], v[210:213], v[4:7]
	v_mfma_f32_16x16x32_bf16 v[0:3], v[178:181], v[210:213], v[0:3]
	v_mfma_f32_16x16x32_bf16 v[52:55], v[174:177], v[190:193], v[52:55]
	v_mfma_f32_16x16x32_bf16 v[44:47], v[182:185], v[190:193], v[44:47]
	v_mfma_f32_16x16x32_bf16 v[36:39], v[174:177], v[198:201], v[36:39]
	v_mfma_f32_16x16x32_bf16 v[28:31], v[182:185], v[198:201], v[28:31]
	v_mfma_f32_16x16x32_bf16 v[20:23], v[174:177], v[206:209], v[20:23]
	v_mfma_f32_16x16x32_bf16 v[12:15], v[182:185], v[206:209], v[12:15]
	v_mfma_f32_16x16x32_bf16 v[4:7], v[174:177], v[214:217], v[4:7]
	v_mfma_f32_16x16x32_bf16 v[0:3], v[182:185], v[214:217], v[0:3]
	s_setprio 0
	s_barrier
	s_add_i32 s60, s60, 2
	s_add_u32 s58, s58, 0x100
	s_addc_u32 s59, s59, 0
	s_cmp_gt_u32 s60, 29
	s_mov_b64 s[26:27], s[4:5]
	s_cbranch_scc0 .LBB0_2451
	s_branch .Lkx_28
.LBB0_2451:
	ds_read_b128 v[128:131], v170
	ds_read_b128 v[132:135], v170 offset:1024
	ds_read_b128 v[136:139], v170 offset:2048
	ds_read_b128 v[140:143], v170 offset:3072
	ds_read_b128 v[162:165], v171
	ds_read_b128 v[174:177], v171 offset:1024
	ds_read_b128 v[178:181], v171 offset:2048
	ds_read_b128 v[182:185], v171 offset:3072
	s_add_u32 s4, s26, 0x100
	s_addc_u32 s5, s27, 0
	s_cmp_eq_u32 s60, 28
	s_cselect_b32 s31, s21, s5
	s_cselect_b32 s30, s20, s4
	s_cselect_b32 s29, s19, s59
	s_cselect_b32 s28, s25, s58
	v_lshl_add_u64 v[166:167], s[26:27], 0, v[154:155]
	s_add_i32 m0, s40, 0xc000
	ds_read_b128 v[186:189], v172
	ds_read_b128 v[190:193], v172 offset:1024
	ds_read_b128 v[194:197], v172 offset:2048
	ds_read_b128 v[198:201], v172 offset:3072
	ds_read_b128 v[202:205], v172 offset:4096
	ds_read_b128 v[206:209], v172 offset:5120
	ds_read_b128 v[210:213], v172 offset:6144
	ds_read_b128 v[214:217], v172 offset:7168
	global_load_lds_dwordx4 v[166:167], off
	v_lshl_add_u64 v[166:167], s[26:27], 0, v[156:157]
	s_add_i32 m0, s40, 0xe000
	s_nop 0
	global_load_lds_dwordx4 v[166:167], off
	s_waitcnt vmcnt(8)
	s_waitcnt lgkmcnt(0)
	s_barrier
; #define PG8_STAGE(bufoff, gbase, voff) do { _Pragma("unroll") for (int _i = 0; _i < 2; ++_i) \
;         __builtin_amdgcn_global_load_lds((const unsigned*)((const char*)(gbase) + (voff)[_i]), (PG8_LAS unsigned*)(lds + (bufoff) + ldsw + _i * 8192), 16, 0, 0); } while (0)
; #define PG8_LDA(dst, b, h) do { _Pragma("unroll") for (int m = 0; m < 4; ++m) _Pragma("unroll") for (int k = 0; k < 2; ++k) dst[m][k] = *(const PG8_LAS bf16x8*)(lds + PG8_SA(b, h) + aoff + m * 2048 + k * 1024); } while (0)
; #define PG8_LDB(dst, b, h) do { _Pragma("unroll") for (int n = 0; n < 2; ++n) _Pragma("unroll") for (int k = 0; k < 2; ++k) dst[n][k] = *(const PG8_LAS bf16x8*)(lds + PG8_SB(b, h) + boff + n * 2048 + k * 1024); } while (0)
; #define PG8_MMA(ai, bj, At, Bt) do { __builtin_amdgcn_s_setprio(1); _Pragma("unroll") for (int m = 0; m < 4; ++m) _Pragma("unroll") for (int n = 0; n < 2; ++n) _Pragma("unroll") for (int k = 0; k < 2; ++k) \
;         acc[ai][bj][m][n] = __builtin_amdgcn_mfma_f32_16x16x32_bf16(Bt[n][k], At[m][k], acc[ai][bj][m][n], 0, 0, 0); __builtin_amdgcn_s_setprio(0); } while (0)
; #define PG8_WAIT_V(n) asm volatile("s_waitcnt vmcnt(" #n ")" ::: "memory")
; #define PG8_WAIT_L(n) asm volatile("s_waitcnt lgkmcnt(" #n ")" ::: "memory")
; #define PG8_BAR __builtin_amdgcn_s_barrier()
; #define PG8_SCHED __builtin_amdgcn_sched_barrier(0)
; template <class Epi, class Sched, bool ALIGN_EPI = false, bool SP2 = false>
; __device__ __forceinline__ void gemm_phase(PG8_LAS unsigned char* lds, const Gemm g, const Sched& S, const Epi& E, const int wave_in) {
;     ...
;             PG8_LDB(B0, 0, 0); PG8_LDB(B1, 0, 1); PG8_SCHED; PG8_LDA(At, 0, 0); PG8_STAGE(PG8_SA(1, 1), a1 + hstepA, voffA);
;             PG8_WAIT_V(8); PG8_WAIT_L(0); PG8_BAR; PG8_MMA(0, 0, At, B0); PG8_MMA(0, 1, At, B1); PG8_BAR; PG8_SCHED;
;             PG8_LDA(At, 0, 1); PG8_STAGE(PG8_SB(0, 0), b2, voffB); PG8_STAGE(PG8_SB(0, 1), b2 + hstepB, voffB); PG8_STAGE(PG8_SA(0, 0), a2, voffA);
;             PG8_WAIT_V(8); PG8_WAIT_L(0); PG8_BAR; PG8_MMA(1, 0, At, B0); PG8_MMA(1, 1, At, B1); PG8_BAR; PG8_SCHED;
	s_setprio 1
	v_mfma_f32_16x16x32_bf16 v[124:127], v[128:131], v[186:189], v[124:127]
	v_mfma_f32_16x16x32_bf16 v[120:123], v[136:139], v[186:189], v[120:123]
	v_mfma_f32_16x16x32_bf16 v[112:115], v[128:131], v[194:197], v[112:115]
	v_mfma_f32_16x16x32_bf16 v[104:107], v[136:139], v[194:197], v[104:107]
	v_mfma_f32_16x16x32_bf16 v[96:99], v[128:131], v[202:205], v[96:99]
	v_mfma_f32_16x16x32_bf16 v[88:91], v[136:139], v[202:205], v[88:91]
	v_mfma_f32_16x16x32_bf16 v[80:83], v[128:131], v[210:213], v[80:83]
	v_mfma_f32_16x16x32_bf16 v[72:75], v[136:139], v[210:213], v[72:75]
	v_mfma_f32_16x16x32_bf16 v[124:127], v[132:135], v[190:193], v[124:127]
	v_mfma_f32_16x16x32_bf16 v[120:123], v[140:143], v[190:193], v[120:123]
	v_mfma_f32_16x16x32_bf16 v[112:115], v[132:135], v[198:201], v[112:115]
	v_mfma_f32_16x16x32_bf16 v[104:107], v[140:143], v[198:201], v[104:107]
	v_mfma_f32_16x16x32_bf16 v[96:99], v[132:135], v[206:209], v[96:99]
	v_mfma_f32_16x16x32_bf16 v[88:91], v[140:143], v[206:209], v[88:91]
	v_mfma_f32_16x16x32_bf16 v[80:83], v[132:135], v[214:217], v[80:83]
	v_mfma_f32_16x16x32_bf16 v[72:75], v[140:143], v[214:217], v[72:75]
	v_mfma_f32_16x16x32_bf16 v[116:119], v[162:165], v[186:189], v[116:119]
	v_mfma_f32_16x16x32_bf16 v[108:111], v[178:181], v[186:189], v[108:111]
	v_mfma_f32_16x16x32_bf16 v[100:103], v[162:165], v[194:197], v[100:103]
	v_mfma_f32_16x16x32_bf16 v[92:95], v[178:181], v[194:197], v[92:95]
	v_mfma_f32_16x16x32_bf16 v[84:87], v[162:165], v[202:205], v[84:87]
	v_mfma_f32_16x16x32_bf16 v[76:79], v[178:181], v[202:205], v[76:79]
	v_mfma_f32_16x16x32_bf16 v[68:71], v[162:165], v[210:213], v[68:71]
	v_mfma_f32_16x16x32_bf16 v[64:67], v[178:181], v[210:213], v[64:67]
	v_mfma_f32_16x16x32_bf16 v[116:119], v[174:177], v[190:193], v[116:119]
	v_mfma_f32_16x16x32_bf16 v[108:111], v[182:185], v[190:193], v[108:111]
	v_mfma_f32_16x16x32_bf16 v[100:103], v[174:177], v[198:201], v[100:103]
	v_mfma_f32_16x16x32_bf16 v[92:95], v[182:185], v[198:201], v[92:95]
	v_mfma_f32_16x16x32_bf16 v[84:87], v[174:177], v[206:209], v[84:87]
	v_mfma_f32_16x16x32_bf16 v[76:79], v[182:185], v[206:209], v[76:79]
	v_mfma_f32_16x16x32_bf16 v[68:71], v[174:177], v[214:217], v[68:71]
	v_mfma_f32_16x16x32_bf16 v[64:67], v[182:185], v[214:217], v[64:67]
	s_setprio 0
	s_barrier
	s_add_i32 s26, s50, s39
	v_lshl_add_u64 v[166:167], s[28:29], 0, v[146:147]
	s_mov_b32 m0, s26
	ds_read_b128 v[186:189], v172 offset:16384
	ds_read_b128 v[190:193], v172 offset:17408
	ds_read_b128 v[194:197], v172 offset:18432
	ds_read_b128 v[198:201], v172 offset:19456
	ds_read_b128 v[202:205], v172 offset:20480
	ds_read_b128 v[206:209], v172 offset:21504
	ds_read_b128 v[210:213], v172 offset:22528
	ds_read_b128 v[214:217], v172 offset:23552
	global_load_lds_dwordx4 v[166:167], off
	s_add_i32 m0, s26, 0x2000
	s_add_u32 s26, s28, 0x80000
	v_lshl_add_u64 v[218:219], s[28:29], 0, v[150:151]
	s_addc_u32 s27, s29, 0
	s_add_i32 s61, s51, s39
	global_load_lds_dwordx4 v[218:219], off
	v_lshl_add_u64 v[220:221], s[26:27], 0, v[146:147]
	s_mov_b32 m0, s61
	v_lshl_add_u64 v[222:223], s[30:31], 0, v[148:149]
	global_load_lds_dwordx4 v[220:221], off
	v_lshl_add_u64 v[220:221], s[26:27], 0, v[150:151]
	s_add_i32 m0, s61, 0x2000
	s_nop 0
	global_load_lds_dwordx4 v[220:221], off
	v_lshl_add_u64 v[220:221], s[30:31], 0, v[144:145]
	s_mov_b32 m0, s40
	s_nop 0
	global_load_lds_dwordx4 v[220:221], off
	s_mov_b32 m0, s41
	s_nop 0
	global_load_lds_dwordx4 v[222:223], off
	s_waitcnt vmcnt(8)
	s_waitcnt lgkmcnt(0)
	s_barrier
	s_setprio 1
	v_mfma_f32_16x16x32_bf16 v[60:63], v[128:131], v[186:189], v[60:63]
	v_mfma_f32_16x16x32_bf16 v[56:59], v[136:139], v[186:189], v[56:59]
	v_mfma_f32_16x16x32_bf16 v[48:51], v[128:131], v[194:197], v[48:51]
	v_mfma_f32_16x16x32_bf16 v[40:43], v[136:139], v[194:197], v[40:43]
	v_mfma_f32_16x16x32_bf16 v[32:35], v[128:131], v[202:205], v[32:35]
	v_mfma_f32_16x16x32_bf16 v[24:27], v[136:139], v[202:205], v[24:27]
	v_mfma_f32_16x16x32_bf16 v[16:19], v[128:131], v[210:213], v[16:19]
	v_mfma_f32_16x16x32_bf16 v[8:11], v[136:139], v[210:213], v[8:11]
	v_mfma_f32_16x16x32_bf16 v[60:63], v[132:135], v[190:193], v[60:63]
	v_mfma_f32_16x16x32_bf16 v[56:59], v[140:143], v[190:193], v[56:59]
	v_mfma_f32_16x16x32_bf16 v[48:51], v[132:135], v[198:201], v[48:51]
	v_mfma_f32_16x16x32_bf16 v[40:43], v[140:143], v[198:201], v[40:43]
	v_mfma_f32_16x16x32_bf16 v[32:35], v[132:135], v[206:209], v[32:35]
	v_mfma_f32_16x16x32_bf16 v[24:27], v[140:143], v[206:209], v[24:27]
	v_mfma_f32_16x16x32_bf16 v[16:19], v[132:135], v[214:217], v[16:19]
	v_mfma_f32_16x16x32_bf16 v[8:11], v[140:143], v[214:217], v[8:11]
	v_mfma_f32_16x16x32_bf16 v[52:55], v[162:165], v[186:189], v[52:55]
	v_mfma_f32_16x16x32_bf16 v[44:47], v[178:181], v[186:189], v[44:47]
	v_mfma_f32_16x16x32_bf16 v[36:39], v[162:165], v[194:197], v[36:39]
	v_mfma_f32_16x16x32_bf16 v[28:31], v[178:181], v[194:197], v[28:31]
	v_mfma_f32_16x16x32_bf16 v[20:23], v[162:165], v[202:205], v[20:23]
	v_mfma_f32_16x16x32_bf16 v[12:15], v[178:181], v[202:205], v[12:15]
	v_mfma_f32_16x16x32_bf16 v[4:7], v[162:165], v[210:213], v[4:7]
	v_mfma_f32_16x16x32_bf16 v[0:3], v[178:181], v[210:213], v[0:3]
	v_mfma_f32_16x16x32_bf16 v[52:55], v[174:177], v[190:193], v[52:55]
	v_mfma_f32_16x16x32_bf16 v[44:47], v[182:185], v[190:193], v[44:47]
	v_mfma_f32_16x16x32_bf16 v[36:39], v[174:177], v[198:201], v[36:39]
	v_mfma_f32_16x16x32_bf16 v[28:31], v[182:185], v[198:201], v[28:31]
	v_mfma_f32_16x16x32_bf16 v[20:23], v[174:177], v[206:209], v[20:23]
	v_mfma_f32_16x16x32_bf16 v[12:15], v[182:185], v[206:209], v[12:15]
	v_mfma_f32_16x16x32_bf16 v[4:7], v[174:177], v[214:217], v[4:7]
	v_mfma_f32_16x16x32_bf16 v[0:3], v[182:185], v[214:217], v[0:3]
	s_setprio 0
	s_barrier
; #define PG8_STAGE(bufoff, gbase, voff) do { _Pragma("unroll") for (int _i = 0; _i < 2; ++_i) \
;         __builtin_amdgcn_global_load_lds((const unsigned*)((const char*)(gbase) + (voff)[_i]), (PG8_LAS unsigned*)(lds + (bufoff) + ldsw + _i * 8192), 16, 0, 0); } while (0)
; #define PG8_LDA(dst, b, h) do { _Pragma("unroll") for (int m = 0; m < 4; ++m) _Pragma("unroll") for (int k = 0; k < 2; ++k) dst[m][k] = *(const PG8_LAS bf16x8*)(lds + PG8_SA(b, h) + aoff + m * 2048 + k * 1024); } while (0)
; #define PG8_LDB(dst, b, h) do { _Pragma("unroll") for (int n = 0; n < 2; ++n) _Pragma("unroll") for (int k = 0; k < 2; ++k) dst[n][k] = *(const PG8_LAS bf16x8*)(lds + PG8_SB(b, h) + boff + n * 2048 + k * 1024); } while (0)
; #define PG8_MMA(ai, bj, At, Bt) do { __builtin_amdgcn_s_setprio(1); _Pragma("unroll") for (int m = 0; m < 4; ++m) _Pragma("unroll") for (int n = 0; n < 2; ++n) _Pragma("unroll") for (int k = 0; k < 2; ++k) \
;         acc[ai][bj][m][n] = __builtin_amdgcn_mfma_f32_16x16x32_bf16(Bt[n][k], At[m][k], acc[ai][bj][m][n], 0, 0, 0); __builtin_amdgcn_s_setprio(0); } while (0)
; #define PG8_WAIT_V(n) asm volatile("s_waitcnt vmcnt(" #n ")" ::: "memory")
; #define PG8_WAIT_L(n) asm volatile("s_waitcnt lgkmcnt(" #n ")" ::: "memory")
; #define PG8_BAR __builtin_amdgcn_s_barrier()
; #define PG8_SCHED __builtin_amdgcn_sched_barrier(0)
; template <class Epi, class Sched, bool ALIGN_EPI = false, bool SP2 = false>
; __device__ __forceinline__ void gemm_phase(PG8_LAS unsigned char* lds, const Gemm g, const Sched& S, const Epi& E, const int wave_in) {
;     ...
;             PG8_LDB(B0, 1, 0); PG8_LDB(B1, 1, 1); PG8_SCHED; PG8_LDA(At, 1, 0); PG8_STAGE(PG8_SA(0, 1), a2 + hstepA, voffA);
;             PG8_WAIT_V(8); PG8_WAIT_L(0); PG8_BAR; PG8_MMA(0, 0, At, B0); PG8_MMA(0, 1, At, B1); PG8_BAR; PG8_SCHED;
;             PG8_LDA(At, 1, 1); PG8_STAGE(PG8_SB(1, 0), b3, voffB); PG8_STAGE(PG8_SB(1, 1), b3 + hstepB, voffB); PG8_STAGE(PG8_SA(1, 0), a3, voffA);
;             PG8_WAIT_V(8); PG8_WAIT_L(0); PG8_BAR; PG8_MMA(1, 0, At, B0); PG8_MMA(1, 1, At, B1); PG8_BAR; PG8_SCHED;
	s_add_i32 s61, 0, 0x18000
	s_add_i32 s62, 0, 0x1c000
	v_add_u32_e32 v140, s61, v168
	v_add_u32_e32 v173, s62, v168
	ds_read_b128 v[128:131], v140
	ds_read_b128 v[132:135], v140 offset:1024
	ds_read_b128 v[136:139], v140 offset:2048
	ds_read_b128 v[140:143], v140 offset:3072
	ds_read_b128 v[162:165], v173
	ds_read_b128 v[174:177], v173 offset:1024
	ds_read_b128 v[178:181], v173 offset:2048
	ds_read_b128 v[182:185], v173 offset:3072
	s_add_u32 s26, s30, 0x280000
	s_addc_u32 s27, s31, 0
	s_mov_b32 m0, s42
	v_lshl_add_u64 v[224:225], s[26:27], 0, v[144:145]
	ds_read_b128 v[186:189], v172 offset:32768
	ds_read_b128 v[190:193], v172 offset:33792
	ds_read_b128 v[194:197], v172 offset:34816
	ds_read_b128 v[198:201], v172 offset:35840
	ds_read_b128 v[202:205], v172 offset:36864
	ds_read_b128 v[206:209], v172 offset:37888
	ds_read_b128 v[210:213], v172 offset:38912
	ds_read_b128 v[214:217], v172 offset:39936
	global_load_lds_dwordx4 v[224:225], off
	v_lshl_add_u64 v[224:225], s[26:27], 0, v[148:149]
	s_mov_b32 m0, s43
	s_nop 0
	global_load_lds_dwordx4 v[224:225], off
	s_waitcnt vmcnt(8)
	s_waitcnt lgkmcnt(0)
	s_barrier
	s_setprio 1
	v_mfma_f32_16x16x32_bf16 v[124:127], v[128:131], v[186:189], v[124:127]
	v_mfma_f32_16x16x32_bf16 v[120:123], v[136:139], v[186:189], v[120:123]
	v_mfma_f32_16x16x32_bf16 v[112:115], v[128:131], v[194:197], v[112:115]
	v_mfma_f32_16x16x32_bf16 v[104:107], v[136:139], v[194:197], v[104:107]
	v_mfma_f32_16x16x32_bf16 v[96:99], v[128:131], v[202:205], v[96:99]
	v_mfma_f32_16x16x32_bf16 v[88:91], v[136:139], v[202:205], v[88:91]
	v_mfma_f32_16x16x32_bf16 v[80:83], v[128:131], v[210:213], v[80:83]
	v_mfma_f32_16x16x32_bf16 v[72:75], v[136:139], v[210:213], v[72:75]
	v_mfma_f32_16x16x32_bf16 v[124:127], v[132:135], v[190:193], v[124:127]
	v_mfma_f32_16x16x32_bf16 v[120:123], v[140:143], v[190:193], v[120:123]
	v_mfma_f32_16x16x32_bf16 v[112:115], v[132:135], v[198:201], v[112:115]
	v_mfma_f32_16x16x32_bf16 v[104:107], v[140:143], v[198:201], v[104:107]
	v_mfma_f32_16x16x32_bf16 v[96:99], v[132:135], v[206:209], v[96:99]
	v_mfma_f32_16x16x32_bf16 v[88:91], v[140:143], v[206:209], v[88:91]
	v_mfma_f32_16x16x32_bf16 v[80:83], v[132:135], v[214:217], v[80:83]
	v_mfma_f32_16x16x32_bf16 v[72:75], v[140:143], v[214:217], v[72:75]
	v_mfma_f32_16x16x32_bf16 v[116:119], v[162:165], v[186:189], v[116:119]
	v_mfma_f32_16x16x32_bf16 v[108:111], v[178:181], v[186:189], v[108:111]
	v_mfma_f32_16x16x32_bf16 v[100:103], v[162:165], v[194:197], v[100:103]
	v_mfma_f32_16x16x32_bf16 v[92:95], v[178:181], v[194:197], v[92:95]
	v_mfma_f32_16x16x32_bf16 v[84:87], v[162:165], v[202:205], v[84:87]
	v_mfma_f32_16x16x32_bf16 v[76:79], v[178:181], v[202:205], v[76:79]
	v_mfma_f32_16x16x32_bf16 v[68:71], v[162:165], v[210:213], v[68:71]
	v_mfma_f32_16x16x32_bf16 v[64:67], v[178:181], v[210:213], v[64:67]
	v_mfma_f32_16x16x32_bf16 v[116:119], v[174:177], v[190:193], v[116:119]
	v_mfma_f32_16x16x32_bf16 v[108:111], v[182:185], v[190:193], v[108:111]
	v_mfma_f32_16x16x32_bf16 v[100:103], v[174:177], v[198:201], v[100:103]
	v_mfma_f32_16x16x32_bf16 v[92:95], v[182:185], v[198:201], v[92:95]
	v_mfma_f32_16x16x32_bf16 v[84:87], v[174:177], v[206:209], v[84:87]
	v_mfma_f32_16x16x32_bf16 v[76:79], v[182:185], v[206:209], v[76:79]
	v_mfma_f32_16x16x32_bf16 v[68:71], v[174:177], v[214:217], v[68:71]
	v_mfma_f32_16x16x32_bf16 v[64:67], v[182:185], v[214:217], v[64:67]
	s_setprio 0
	s_barrier
	s_add_i32 s26, s61, s39
	v_lshl_add_u64 v[166:167], v[166:167], 0, s[8:9]
	s_mov_b32 m0, s26
	ds_read_b128 v[186:189], v172 offset:49152
	ds_read_b128 v[190:193], v172 offset:50176
	ds_read_b128 v[194:197], v172 offset:51200
	ds_read_b128 v[198:201], v172 offset:52224
	ds_read_b128 v[202:205], v172 offset:53248
	ds_read_b128 v[206:209], v172 offset:54272
	ds_read_b128 v[210:213], v172 offset:55296
	ds_read_b128 v[214:217], v172 offset:56320
	global_load_lds_dwordx4 v[166:167], off
	s_add_i32 m0, s26, 0x2000
	s_add_u32 s26, s28, 0x80080
	v_lshl_add_u64 v[166:167], v[218:219], 0, s[8:9]
	s_addc_u32 s27, s29, 0
	s_add_i32 s28, s62, s39
	global_load_lds_dwordx4 v[166:167], off
	v_lshl_add_u64 v[166:167], s[26:27], 0, v[146:147]
	s_mov_b32 m0, s28
	s_nop 0
	global_load_lds_dwordx4 v[166:167], off
	v_lshl_add_u64 v[166:167], s[26:27], 0, v[150:151]
	s_add_i32 m0, s28, 0x2000
	s_nop 0
	global_load_lds_dwordx4 v[166:167], off
	v_lshl_add_u64 v[166:167], v[220:221], 0, s[8:9]
	s_mov_b32 m0, s47
	s_nop 0
	global_load_lds_dwordx4 v[166:167], off
	v_lshl_add_u64 v[166:167], v[222:223], 0, s[8:9]
	s_mov_b32 m0, s48
	s_nop 0
	global_load_lds_dwordx4 v[166:167], off
	s_waitcnt vmcnt(8)
	s_waitcnt lgkmcnt(0)
	s_barrier
	s_setprio 1
	v_mfma_f32_16x16x32_bf16 v[60:63], v[128:131], v[186:189], v[60:63]
	v_mfma_f32_16x16x32_bf16 v[56:59], v[136:139], v[186:189], v[56:59]
	v_mfma_f32_16x16x32_bf16 v[48:51], v[128:131], v[194:197], v[48:51]
	v_mfma_f32_16x16x32_bf16 v[40:43], v[136:139], v[194:197], v[40:43]
	v_mfma_f32_16x16x32_bf16 v[32:35], v[128:131], v[202:205], v[32:35]
	v_mfma_f32_16x16x32_bf16 v[24:27], v[136:139], v[202:205], v[24:27]
	v_mfma_f32_16x16x32_bf16 v[16:19], v[128:131], v[210:213], v[16:19]
	v_mfma_f32_16x16x32_bf16 v[8:11], v[136:139], v[210:213], v[8:11]
	v_mfma_f32_16x16x32_bf16 v[60:63], v[132:135], v[190:193], v[60:63]
	v_mfma_f32_16x16x32_bf16 v[56:59], v[140:143], v[190:193], v[56:59]
	v_mfma_f32_16x16x32_bf16 v[48:51], v[132:135], v[198:201], v[48:51]
	v_mfma_f32_16x16x32_bf16 v[40:43], v[140:143], v[198:201], v[40:43]
	v_mfma_f32_16x16x32_bf16 v[32:35], v[132:135], v[206:209], v[32:35]
	v_mfma_f32_16x16x32_bf16 v[24:27], v[140:143], v[206:209], v[24:27]
	v_mfma_f32_16x16x32_bf16 v[16:19], v[132:135], v[214:217], v[16:19]
	v_mfma_f32_16x16x32_bf16 v[8:11], v[140:143], v[214:217], v[8:11]
	v_mfma_f32_16x16x32_bf16 v[52:55], v[162:165], v[186:189], v[52:55]
	v_mfma_f32_16x16x32_bf16 v[44:47], v[178:181], v[186:189], v[44:47]
	v_mfma_f32_16x16x32_bf16 v[36:39], v[162:165], v[194:197], v[36:39]
	v_mfma_f32_16x16x32_bf16 v[28:31], v[178:181], v[194:197], v[28:31]
	v_mfma_f32_16x16x32_bf16 v[20:23], v[162:165], v[202:205], v[20:23]
	v_mfma_f32_16x16x32_bf16 v[12:15], v[178:181], v[202:205], v[12:15]
	v_mfma_f32_16x16x32_bf16 v[4:7], v[162:165], v[210:213], v[4:7]
	v_mfma_f32_16x16x32_bf16 v[0:3], v[178:181], v[210:213], v[0:3]
	v_mfma_f32_16x16x32_bf16 v[52:55], v[174:177], v[190:193], v[52:55]
	v_mfma_f32_16x16x32_bf16 v[44:47], v[182:185], v[190:193], v[44:47]
	v_mfma_f32_16x16x32_bf16 v[36:39], v[174:177], v[198:201], v[36:39]
	v_mfma_f32_16x16x32_bf16 v[28:31], v[182:185], v[198:201], v[28:31]
	v_mfma_f32_16x16x32_bf16 v[20:23], v[174:177], v[206:209], v[20:23]
	v_mfma_f32_16x16x32_bf16 v[12:15], v[182:185], v[206:209], v[12:15]
	v_mfma_f32_16x16x32_bf16 v[4:7], v[174:177], v[214:217], v[4:7]
	v_mfma_f32_16x16x32_bf16 v[0:3], v[182:185], v[214:217], v[0:3]
	s_setprio 0
	s_barrier
	s_add_i32 s60, s60, 2
	s_add_u32 s58, s58, 0x100
	s_addc_u32 s59, s59, 0
	s_cmp_gt_u32 s60, 29
	s_mov_b64 s[26:27], s[4:5]
	s_cbranch_scc0 .LBB0_2451

;     __host__ __device__ bool next(int i, Unit& u) const { const bool ok = StaticOrder::next(i, u); u.pm = 0; u.pn = 0; return ok; }
; #define PG8_STAGE(bufoff, gbase, voff) do { _Pragma("unroll") for (int _i = 0; _i < 2; ++_i) \
;         __builtin_amdgcn_global_load_lds((const unsigned*)((const char*)(gbase) + (voff)[_i]), (PG8_LAS unsigned*)(lds + (bufoff) + ldsw + _i * 8192), 16, 0, 0); } while (0)
; #define PG8_LDA(dst, b, h) do { _Pragma("unroll") for (int m = 0; m < 4; ++m) _Pragma("unroll") for (int k = 0; k < 2; ++k) dst[m][k] = *(const PG8_LAS bf16x8*)(lds + PG8_SA(b, h) + aoff + m * 2048 + k * 1024); } while (0)
; #define PG8_LDB(dst, b, h) do { _Pragma("unroll") for (int n = 0; n < 2; ++n) _Pragma("unroll") for (int k = 0; k < 2; ++k) dst[n][k] = *(const PG8_LAS bf16x8*)(lds + PG8_SB(b, h) + boff + n * 2048 + k * 1024); } while (0)
; #define PG8_WAIT_V(n) asm volatile("s_waitcnt vmcnt(" #n ")" ::: "memory")
; #define PG8_BAR __builtin_amdgcn_s_barrier()
; template <class Epi, class Sched, bool ALIGN_EPI = false, bool SP2 = false>
; __device__ __forceinline__ void gemm_phase(PG8_LAS unsigned char* lds, const Gemm g, const Sched& S, const Epi& E, const int wave_in) {
;     ...
;         const bool has_next = S.next(ui + 1, nxt);
;         const char* nA = has_next ? (const char*)g.A + (size_t)nxt.pm * tstepA : cA; const char* nB = has_next ? (const char*)g.Bt + (size_t)nxt.pn * tstepB : cB;
;         for (int t = 0; t < nt; t += 2) {
;             const bool last = (t == nt - 2);
;             const char* a1 = cA + (size_t)(t + 1) * kstep;
;             const char* a2 = last ? nA : cA + (size_t)(t + 2) * kstep; const char* b2 = last ? nB : cB + (size_t)(t + 2) * kstep;
;             const char* a3 = a2 + kstep; const char* b3 = b2 + kstep;
;             if (last && has_next) S.a_ready(nxt);
;             if constexpr (SP2) {
;             PG8_LDB(B0, 0, 0); PG8_LDB(B1, 0, 1); PG8_SCHED; PG8_LDA(At, 0, 0); PG8_STAGE(PG8_SA(1, 1), a1 + hstepA, voffA);
;             PG8_WAIT_V(8); PG8_WAIT_L(0); PG8_BAR; PG8_MMA(0, 0, At, B0); PG8_MMA(0, 1, At, B1); PG8_BAR; PG8_SCHED;
;             PG8_LDA(At, 0, 1); PG8_STAGE(PG8_SB(0, 0), b2, voffB); PG8_STAGE(PG8_SB(0, 1), b2 + hstepB, voffB); PG8_STAGE(PG8_SA(0, 0), a2, voffA);
;             PG8_WAIT_V(8); PG8_WAIT_L(0); PG8_BAR; PG8_MMA(1, 0, At, B0); PG8_MMA(1, 1, At, B1); PG8_BAR; PG8_SCHED;
.LBB0_2576:
	s_ashr_i32 s39, s38, 31
	s_lshl_b64 s[40:41], s[38:39], 20
	s_add_u32 s40, s52, s40
	s_addc_u32 s41, s53, s41
	s_and_b64 s[42:43], s[8:9], exec
	s_cselect_b32 s11, s41, s47
	s_cselect_b32 s39, s40, s46
	s_ashr_i32 s37, s36, 31
	s_lshl_b64 s[42:43], s[36:37], 20
	s_add_u32 s42, s54, s42
	s_addc_u32 s43, s55, s43
	s_and_b64 s[50:51], s[8:9], exec
	s_cselect_b32 s37, s43, s49
	s_cselect_b32 s45, s42, s48
	s_add_u32 s46, s46, 0x80080
	s_addc_u32 s47, s47, 0
	s_add_u32 s72, s48, 0x100
	v_mov_b32_e32 v0, 0
	s_addc_u32 s73, s49, 0
	s_mov_b32 s75, -2
	s_waitcnt vmcnt(0)
	ds_read_b128 v[64:67], v189
	ds_read_b128 v[68:71], v189 offset:1024
	ds_read_b128 v[72:75], v189 offset:2048
	ds_read_b128 v[76:79], v189 offset:3072
	ds_read_b128 v[80:83], v197
	ds_read_b128 v[84:87], v197 offset:1024
	ds_read_b128 v[88:91], v197 offset:2048
	ds_read_b128 v[92:95], v197 offset:3072
	s_add_u32 s48, s46, 0xfff80080
	s_addc_u32 s49, s47, -1
	s_cmp_eq_u32 s75, 28
	s_cselect_b32 s51, s11, s49
	s_cselect_b32 s50, s39, s48
	s_cselect_b32 s49, s37, s73
	s_cselect_b32 s48, s45, s72
	v_lshl_add_u64 v[224:225], s[46:47], 0, v[206:207]
	s_add_i32 m0, s57, 0xc000
	ds_read_b128 v[96:99], v199
	ds_read_b128 v[100:103], v199 offset:1024
	ds_read_b128 v[104:107], v199 offset:2048
	ds_read_b128 v[108:111], v199 offset:3072
	ds_read_b128 v[176:179], v199 offset:4096
	ds_read_b128 v[212:215], v199 offset:5120
	ds_read_b128 v[216:219], v199 offset:6144
	ds_read_b128 v[220:223], v199 offset:7168
	global_load_lds_dwordx4 v[224:225], off
	v_lshl_add_u64 v[224:225], s[46:47], 0, v[208:209]
	s_add_i32 m0, s57, 0xe000
	s_nop 0
	global_load_lds_dwordx4 v[224:225], off
	s_waitcnt vmcnt(8)
	s_waitcnt lgkmcnt(0)
	s_barrier
	s_setprio 1
	v_mfma_f32_16x16x32_bf16 v[172:175], v[64:67], v[96:99], 0
	v_mfma_f32_16x16x32_bf16 v[164:167], v[72:75], v[96:99], 0
	v_mfma_f32_16x16x32_bf16 v[156:159], v[64:67], v[104:107], 0
	v_mfma_f32_16x16x32_bf16 v[148:151], v[72:75], v[104:107], 0
	v_mfma_f32_16x16x32_bf16 v[140:143], v[64:67], v[176:179], 0
	v_mfma_f32_16x16x32_bf16 v[132:135], v[72:75], v[176:179], 0
	v_mfma_f32_16x16x32_bf16 v[124:127], v[64:67], v[216:219], 0
	v_mfma_f32_16x16x32_bf16 v[120:123], v[72:75], v[216:219], 0
	v_mfma_f32_16x16x32_bf16 v[172:175], v[68:71], v[100:103], v[172:175]
	v_mfma_f32_16x16x32_bf16 v[164:167], v[76:79], v[100:103], v[164:167]
	v_mfma_f32_16x16x32_bf16 v[156:159], v[68:71], v[108:111], v[156:159]
	v_mfma_f32_16x16x32_bf16 v[148:151], v[76:79], v[108:111], v[148:151]
	v_mfma_f32_16x16x32_bf16 v[140:143], v[68:71], v[212:215], v[140:143]
	v_mfma_f32_16x16x32_bf16 v[132:135], v[76:79], v[212:215], v[132:135]
	v_mfma_f32_16x16x32_bf16 v[124:127], v[68:71], v[220:223], v[124:127]
	v_mfma_f32_16x16x32_bf16 v[120:123], v[76:79], v[220:223], v[120:123]
	v_mfma_f32_16x16x32_bf16 v[168:171], v[80:83], v[96:99], 0
	v_mfma_f32_16x16x32_bf16 v[96:99], v[88:91], v[96:99], 0
	v_mfma_f32_16x16x32_bf16 v[168:171], v[84:87], v[100:103], v[168:171]
	v_mfma_f32_16x16x32_bf16 v[96:99], v[92:95], v[100:103], v[96:99]
	v_mfma_f32_16x16x32_bf16 v[100:103], v[80:83], v[104:107], 0
	v_mfma_f32_16x16x32_bf16 v[104:107], v[88:91], v[104:107], 0
	v_mfma_f32_16x16x32_bf16 v[128:131], v[88:91], v[176:179], 0
	v_mfma_f32_16x16x32_bf16 v[116:119], v[80:83], v[216:219], 0
	v_mfma_f32_16x16x32_bf16 v[112:115], v[88:91], v[216:219], 0
	v_mfma_f32_16x16x32_bf16 v[100:103], v[84:87], v[108:111], v[100:103]
	v_mfma_f32_16x16x32_bf16 v[104:107], v[92:95], v[108:111], v[104:107]
	v_mfma_f32_16x16x32_bf16 v[108:111], v[80:83], v[176:179], 0
	v_mfma_f32_16x16x32_bf16 v[128:131], v[92:95], v[212:215], v[128:131]
	v_mfma_f32_16x16x32_bf16 v[116:119], v[84:87], v[220:223], v[116:119]
	v_mfma_f32_16x16x32_bf16 v[112:115], v[92:95], v[220:223], v[112:115]
	v_mfma_f32_16x16x32_bf16 v[108:111], v[84:87], v[212:215], v[108:111]
	s_setprio 0
	s_barrier
	s_add_i32 s76, s69, s56
	v_lshl_add_u64 v[232:233], s[48:49], 0, v[182:183]
	s_mov_b32 m0, s76
	ds_read_b128 v[136:139], v199 offset:16384
	ds_read_b128 v[144:147], v199 offset:17408
	ds_read_b128 v[152:155], v199 offset:18432
	ds_read_b128 v[160:163], v199 offset:19456
	ds_read_b128 v[176:179], v199 offset:20480
	ds_read_b128 v[212:215], v199 offset:21504
	ds_read_b128 v[216:219], v199 offset:22528
	ds_read_b128 v[220:223], v199 offset:23552
	global_load_lds_dwordx4 v[232:233], off
	s_add_i32 m0, s76, 0x2000
	s_add_u32 s76, s48, 0x80000
	v_lshl_add_u64 v[234:235], s[48:49], 0, v[186:187]
	s_addc_u32 s77, s49, 0
	s_add_i32 s78, s70, s56
	global_load_lds_dwordx4 v[234:235], off
	v_lshl_add_u64 v[224:225], s[76:77], 0, v[182:183]
	s_mov_b32 m0, s78
	v_lshl_add_u64 v[236:237], s[50:51], 0, v[180:181]
	global_load_lds_dwordx4 v[224:225], off
	v_lshl_add_u64 v[224:225], s[76:77], 0, v[186:187]
	s_add_i32 m0, s78, 0x2000
	v_lshl_add_u64 v[238:239], s[50:51], 0, v[184:185]
	global_load_lds_dwordx4 v[224:225], off
	s_mov_b32 m0, s57
	s_nop 0
	global_load_lds_dwordx4 v[236:237], off
	s_mov_b32 m0, s58
	s_nop 0
	global_load_lds_dwordx4 v[238:239], off
	s_waitcnt vmcnt(8)
	s_waitcnt lgkmcnt(0)
	s_barrier
; #define PG8_STAGE(bufoff, gbase, voff) do { _Pragma("unroll") for (int _i = 0; _i < 2; ++_i) \
;         __builtin_amdgcn_global_load_lds((const unsigned*)((const char*)(gbase) + (voff)[_i]), (PG8_LAS unsigned*)(lds + (bufoff) + ldsw + _i * 8192), 16, 0, 0); } while (0)
; #define PG8_LDA(dst, b, h) do { _Pragma("unroll") for (int m = 0; m < 4; ++m) _Pragma("unroll") for (int k = 0; k < 2; ++k) dst[m][k] = *(const PG8_LAS bf16x8*)(lds + PG8_SA(b, h) + aoff + m * 2048 + k * 1024); } while (0)
; #define PG8_LDB(dst, b, h) do { _Pragma("unroll") for (int n = 0; n < 2; ++n) _Pragma("unroll") for (int k = 0; k < 2; ++k) dst[n][k] = *(const PG8_LAS bf16x8*)(lds + PG8_SB(b, h) + boff + n * 2048 + k * 1024); } while (0)
; #define PG8_MMA(ai, bj, At, Bt) do { __builtin_amdgcn_s_setprio(1); _Pragma("unroll") for (int m = 0; m < 4; ++m) _Pragma("unroll") for (int n = 0; n < 2; ++n) _Pragma("unroll") for (int k = 0; k < 2; ++k) \
;         acc[ai][bj][m][n] = __builtin_amdgcn_mfma_f32_16x16x32_bf16(Bt[n][k], At[m][k], acc[ai][bj][m][n], 0, 0, 0); __builtin_amdgcn_s_setprio(0); } while (0)
; #define PG8_WAIT_V(n) asm volatile("s_waitcnt vmcnt(" #n ")" ::: "memory")
; #define PG8_WAIT_L(n) asm volatile("s_waitcnt lgkmcnt(" #n ")" ::: "memory")
; #define PG8_BAR __builtin_amdgcn_s_barrier()
; #define PG8_SCHED __builtin_amdgcn_sched_barrier(0)
; template <class Epi, class Sched, bool ALIGN_EPI = false, bool SP2 = false>
; __device__ __forceinline__ void gemm_phase(PG8_LAS unsigned char* lds, const Gemm g, const Sched& S, const Epi& E, const int wave_in) {
;     ...
;             PG8_WAIT_V(8); PG8_WAIT_L(0); PG8_BAR; PG8_MMA(0, 0, At, B0); PG8_MMA(0, 1, At, B1); PG8_BAR; PG8_SCHED;
;             PG8_LDA(At, 0, 1); PG8_STAGE(PG8_SB(0, 0), b2, voffB); PG8_STAGE(PG8_SB(0, 1), b2 + hstepB, voffB); PG8_STAGE(PG8_SA(0, 0), a2, voffA);
;             PG8_WAIT_V(8); PG8_WAIT_L(0); PG8_BAR; PG8_MMA(1, 0, At, B0); PG8_MMA(1, 1, At, B1); PG8_BAR; PG8_SCHED;
;             PG8_LDB(B0, 1, 0); PG8_LDB(B1, 1, 1); PG8_SCHED; PG8_LDA(At, 1, 0); PG8_STAGE(PG8_SA(0, 1), a2 + hstepA, voffA);
;             PG8_WAIT_V(8); PG8_WAIT_L(0); PG8_BAR; PG8_MMA(0, 0, At, B0); PG8_MMA(0, 1, At, B1); PG8_BAR; PG8_SCHED;
	s_setprio 1
	v_mfma_f32_16x16x32_bf16 v[60:63], v[64:67], v[136:139], 0
	v_mfma_f32_16x16x32_bf16 v[52:55], v[72:75], v[136:139], 0
	v_mfma_f32_16x16x32_bf16 v[44:47], v[64:67], v[152:155], 0
	v_mfma_f32_16x16x32_bf16 v[36:39], v[72:75], v[152:155], 0
	v_mfma_f32_16x16x32_bf16 v[28:31], v[64:67], v[176:179], 0
	v_mfma_f32_16x16x32_bf16 v[20:23], v[72:75], v[176:179], 0
	v_mfma_f32_16x16x32_bf16 v[12:15], v[64:67], v[216:219], 0
	v_mfma_f32_16x16x32_bf16 v[8:11], v[72:75], v[216:219], 0
	v_mfma_f32_16x16x32_bf16 v[60:63], v[68:71], v[144:147], v[60:63]
	v_mfma_f32_16x16x32_bf16 v[52:55], v[76:79], v[144:147], v[52:55]
	v_mfma_f32_16x16x32_bf16 v[44:47], v[68:71], v[160:163], v[44:47]
	v_mfma_f32_16x16x32_bf16 v[36:39], v[76:79], v[160:163], v[36:39]
	v_mfma_f32_16x16x32_bf16 v[28:31], v[68:71], v[212:215], v[28:31]
	v_mfma_f32_16x16x32_bf16 v[20:23], v[76:79], v[212:215], v[20:23]
	v_mfma_f32_16x16x32_bf16 v[12:15], v[68:71], v[220:223], v[12:15]
	v_mfma_f32_16x16x32_bf16 v[8:11], v[76:79], v[220:223], v[8:11]
	v_mfma_f32_16x16x32_bf16 v[56:59], v[80:83], v[136:139], 0
	v_mfma_f32_16x16x32_bf16 v[48:51], v[88:91], v[136:139], 0
	v_mfma_f32_16x16x32_bf16 v[40:43], v[80:83], v[152:155], 0
	v_mfma_f32_16x16x32_bf16 v[32:35], v[88:91], v[152:155], 0
	v_mfma_f32_16x16x32_bf16 v[24:27], v[80:83], v[176:179], 0
	v_mfma_f32_16x16x32_bf16 v[16:19], v[88:91], v[176:179], 0
	v_mfma_f32_16x16x32_bf16 v[4:7], v[80:83], v[216:219], 0
	v_mfma_f32_16x16x32_bf16 v[0:3], v[88:91], v[216:219], 0
	v_mfma_f32_16x16x32_bf16 v[56:59], v[84:87], v[144:147], v[56:59]
	v_mfma_f32_16x16x32_bf16 v[48:51], v[92:95], v[144:147], v[48:51]
	v_mfma_f32_16x16x32_bf16 v[40:43], v[84:87], v[160:163], v[40:43]
	v_mfma_f32_16x16x32_bf16 v[32:35], v[92:95], v[160:163], v[32:35]
	v_mfma_f32_16x16x32_bf16 v[24:27], v[84:87], v[212:215], v[24:27]
	v_mfma_f32_16x16x32_bf16 v[16:19], v[92:95], v[212:215], v[16:19]
	v_mfma_f32_16x16x32_bf16 v[4:7], v[84:87], v[220:223], v[4:7]
	v_mfma_f32_16x16x32_bf16 v[0:3], v[92:95], v[220:223], v[0:3]
	s_setprio 0
	s_barrier
	s_add_i32 s76, 0, 0x18000
	s_add_i32 s77, 0, 0x1c000
	v_add_u32_e32 v76, s76, v195
	v_add_u32_e32 v92, s77, v195
	ds_read_b128 v[64:67], v76
	ds_read_b128 v[68:71], v76 offset:1024
	ds_read_b128 v[72:75], v76 offset:2048
	ds_read_b128 v[76:79], v76 offset:3072
	ds_read_b128 v[80:83], v92
	ds_read_b128 v[84:87], v92 offset:1024
	ds_read_b128 v[88:91], v92 offset:2048
	ds_read_b128 v[92:95], v92 offset:3072
	s_add_u32 s50, s50, 0x80000
	s_addc_u32 s51, s51, 0
	s_mov_b32 m0, s59
	v_lshl_add_u64 v[152:153], s[50:51], 0, v[180:181]
	ds_read_b128 v[136:139], v199 offset:32768
	ds_read_b128 v[144:147], v199 offset:33792
	ds_read_b128 v[176:179], v199 offset:34816
	ds_read_b128 v[212:215], v199 offset:35840
	ds_read_b128 v[216:219], v199 offset:36864
	ds_read_b128 v[220:223], v199 offset:37888
	ds_read_b128 v[224:227], v199 offset:38912
	ds_read_b128 v[228:231], v199 offset:39936
	global_load_lds_dwordx4 v[152:153], off
	v_lshl_add_u64 v[152:153], s[50:51], 0, v[184:185]
	s_mov_b32 m0, s60
	s_nop 0
	global_load_lds_dwordx4 v[152:153], off
	s_waitcnt vmcnt(8)
	s_waitcnt lgkmcnt(0)
	s_barrier
	s_setprio 1
	v_mfma_f32_16x16x32_bf16 v[152:155], v[64:67], v[136:139], v[172:175]
	v_mfma_f32_16x16x32_bf16 v[172:175], v[68:71], v[144:147], v[152:155]
	v_mfma_f32_16x16x32_bf16 v[152:155], v[72:75], v[136:139], v[164:167]
	v_mfma_f32_16x16x32_bf16 v[164:167], v[76:79], v[144:147], v[152:155]
	v_mfma_f32_16x16x32_bf16 v[152:155], v[64:67], v[176:179], v[156:159]
	v_mfma_f32_16x16x32_bf16 v[148:151], v[72:75], v[176:179], v[148:151]
	v_mfma_f32_16x16x32_bf16 v[140:143], v[64:67], v[216:219], v[140:143]
	v_mfma_f32_16x16x32_bf16 v[132:135], v[72:75], v[216:219], v[132:135]
	v_mfma_f32_16x16x32_bf16 v[124:127], v[64:67], v[224:227], v[124:127]
	v_mfma_f32_16x16x32_bf16 v[120:123], v[72:75], v[224:227], v[120:123]
	v_mfma_f32_16x16x32_bf16 v[156:159], v[68:71], v[212:215], v[152:155]
	v_mfma_f32_16x16x32_bf16 v[148:151], v[76:79], v[212:215], v[148:151]
	v_mfma_f32_16x16x32_bf16 v[140:143], v[68:71], v[220:223], v[140:143]
	v_mfma_f32_16x16x32_bf16 v[132:135], v[76:79], v[220:223], v[132:135]
	v_mfma_f32_16x16x32_bf16 v[124:127], v[68:71], v[228:231], v[124:127]
	v_mfma_f32_16x16x32_bf16 v[120:123], v[76:79], v[228:231], v[120:123]
	v_mfma_f32_16x16x32_bf16 v[96:99], v[88:91], v[136:139], v[96:99]
	v_mfma_f32_16x16x32_bf16 v[152:155], v[80:83], v[136:139], v[168:171]
	v_mfma_f32_16x16x32_bf16 v[160:163], v[92:95], v[144:147], v[96:99]
	v_mfma_f32_16x16x32_bf16 v[96:99], v[80:83], v[176:179], v[100:103]
	v_mfma_f32_16x16x32_bf16 v[168:171], v[84:87], v[144:147], v[152:155]
	v_mfma_f32_16x16x32_bf16 v[152:155], v[84:87], v[212:215], v[96:99]
	v_mfma_f32_16x16x32_bf16 v[96:99], v[88:91], v[176:179], v[104:107]
	v_mfma_f32_16x16x32_bf16 v[144:147], v[92:95], v[212:215], v[96:99]
	v_mfma_f32_16x16x32_bf16 v[96:99], v[80:83], v[216:219], v[108:111]
	v_mfma_f32_16x16x32_bf16 v[136:139], v[84:87], v[220:223], v[96:99]
	v_mfma_f32_16x16x32_bf16 v[96:99], v[88:91], v[216:219], v[128:131]
	v_mfma_f32_16x16x32_bf16 v[128:131], v[92:95], v[220:223], v[96:99]
	v_mfma_f32_16x16x32_bf16 v[96:99], v[80:83], v[224:227], v[116:119]
	v_mfma_f32_16x16x32_bf16 v[116:119], v[84:87], v[228:231], v[96:99]
	v_mfma_f32_16x16x32_bf16 v[96:99], v[88:91], v[224:227], v[112:115]
	v_mfma_f32_16x16x32_bf16 v[112:115], v[92:95], v[228:231], v[96:99]
	s_setprio 0
	s_barrier
; #define PG8_STAGE(bufoff, gbase, voff) do { _Pragma("unroll") for (int _i = 0; _i < 2; ++_i) \
;         __builtin_amdgcn_global_load_lds((const unsigned*)((const char*)(gbase) + (voff)[_i]), (PG8_LAS unsigned*)(lds + (bufoff) + ldsw + _i * 8192), 16, 0, 0); } while (0)
; #define PG8_LDA(dst, b, h) do { _Pragma("unroll") for (int m = 0; m < 4; ++m) _Pragma("unroll") for (int k = 0; k < 2; ++k) dst[m][k] = *(const PG8_LAS bf16x8*)(lds + PG8_SA(b, h) + aoff + m * 2048 + k * 1024); } while (0)
; #define PG8_LDB(dst, b, h) do { _Pragma("unroll") for (int n = 0; n < 2; ++n) _Pragma("unroll") for (int k = 0; k < 2; ++k) dst[n][k] = *(const PG8_LAS bf16x8*)(lds + PG8_SB(b, h) + boff + n * 2048 + k * 1024); } while (0)
; #define PG8_WAIT_V(n) asm volatile("s_waitcnt vmcnt(" #n ")" ::: "memory")
; #define PG8_WAIT_L(n) asm volatile("s_waitcnt lgkmcnt(" #n ")" ::: "memory")
; #define PG8_BAR __builtin_amdgcn_s_barrier()
; template <class Epi, class Sched, bool ALIGN_EPI = false, bool SP2 = false>
; __device__ __forceinline__ void gemm_phase(PG8_LAS unsigned char* lds, const Gemm g, const Sched& S, const Epi& E, const int wave_in) {
;     ...
;         for (int t = 0; t < nt; t += 2) {
;             const bool last = (t == nt - 2);
;             const char* a1 = cA + (size_t)(t + 1) * kstep;
;             const char* a2 = last ? nA : cA + (size_t)(t + 2) * kstep; const char* b2 = last ? nB : cB + (size_t)(t + 2) * kstep;
;             const char* a3 = a2 + kstep; const char* b3 = b2 + kstep;
;             if (last && has_next) S.a_ready(nxt);
;             if constexpr (SP2) {
;             PG8_LDB(B0, 0, 0); PG8_LDB(B1, 0, 1); PG8_SCHED; PG8_LDA(At, 0, 0); PG8_STAGE(PG8_SA(1, 1), a1 + hstepA, voffA);
;             PG8_WAIT_V(8); PG8_WAIT_L(0); PG8_BAR; PG8_MMA(0, 0, At, B0); PG8_MMA(0, 1, At, B1); PG8_BAR; PG8_SCHED;
;             PG8_LDA(At, 0, 1); PG8_STAGE(PG8_SB(0, 0), b2, voffB); PG8_STAGE(PG8_SB(0, 1), b2 + hstepB, voffB); PG8_STAGE(PG8_SA(0, 0), a2, voffA);
;             PG8_WAIT_V(8); PG8_WAIT_L(0); PG8_BAR; PG8_MMA(1, 0, At, B0); PG8_MMA(1, 1, At, B1); PG8_BAR; PG8_SCHED;
;     ...
;             PG8_LDA(At, 1, 1); PG8_STAGE(PG8_SB(1, 0), b3, voffB); PG8_STAGE(PG8_SB(1, 1), b3 + hstepB, voffB); PG8_STAGE(PG8_SA(1, 0), a3, voffA);
;             PG8_WAIT_V(8); PG8_WAIT_L(0); PG8_BAR; PG8_MMA(1, 0, At, B0); PG8_MMA(1, 1, At, B1); PG8_BAR; PG8_SCHED;
	s_add_i32 s50, s76, s56
	v_lshl_add_u64 v[224:225], v[232:233], 0, s[20:21]
	s_mov_b32 m0, s50
	s_nop 1
	ds_read_b128 v[96:99], v199 offset:49152
	ds_read_b128 v[100:103], v199 offset:50176
	ds_read_b128 v[104:107], v199 offset:51200
	ds_read_b128 v[108:111], v199 offset:52224
	ds_read_b128 v[176:179], v199 offset:53248
	ds_read_b128 v[212:215], v199 offset:54272
	ds_read_b128 v[216:219], v199 offset:55296
	ds_read_b128 v[220:223], v199 offset:56320
	global_load_lds_dwordx4 v[224:225], off
	s_add_i32 m0, s50, 0x2000
	s_add_u32 s48, s48, 0x80080
	v_lshl_add_u64 v[224:225], v[234:235], 0, s[20:21]
	s_addc_u32 s49, s49, 0
	s_add_i32 s50, s77, s56
	global_load_lds_dwordx4 v[224:225], off
	v_lshl_add_u64 v[224:225], s[48:49], 0, v[182:183]
	s_mov_b32 m0, s50
	s_nop 0
	global_load_lds_dwordx4 v[224:225], off
	v_lshl_add_u64 v[224:225], s[48:49], 0, v[186:187]
	s_add_i32 m0, s50, 0x2000
	s_nop 0
	global_load_lds_dwordx4 v[224:225], off
	v_lshl_add_u64 v[224:225], v[236:237], 0, s[20:21]
	s_mov_b32 m0, s63
	s_nop 0
	global_load_lds_dwordx4 v[224:225], off
	v_lshl_add_u64 v[224:225], v[238:239], 0, s[20:21]
	s_mov_b32 m0, s64
	s_nop 0
	global_load_lds_dwordx4 v[224:225], off
	s_waitcnt vmcnt(8)
	s_waitcnt lgkmcnt(0)
	s_barrier
	s_setprio 1
	v_mfma_f32_16x16x32_bf16 v[60:63], v[64:67], v[96:99], v[60:63]
	v_mfma_f32_16x16x32_bf16 v[52:55], v[72:75], v[96:99], v[52:55]
	v_mfma_f32_16x16x32_bf16 v[44:47], v[64:67], v[104:107], v[44:47]
	v_mfma_f32_16x16x32_bf16 v[36:39], v[72:75], v[104:107], v[36:39]
	v_mfma_f32_16x16x32_bf16 v[28:31], v[64:67], v[176:179], v[28:31]
	v_mfma_f32_16x16x32_bf16 v[20:23], v[72:75], v[176:179], v[20:23]
	v_mfma_f32_16x16x32_bf16 v[12:15], v[64:67], v[216:219], v[12:15]
	v_mfma_f32_16x16x32_bf16 v[8:11], v[72:75], v[216:219], v[8:11]
	v_mfma_f32_16x16x32_bf16 v[60:63], v[68:71], v[100:103], v[60:63]
	v_mfma_f32_16x16x32_bf16 v[52:55], v[76:79], v[100:103], v[52:55]
	v_mfma_f32_16x16x32_bf16 v[44:47], v[68:71], v[108:111], v[44:47]
	v_mfma_f32_16x16x32_bf16 v[36:39], v[76:79], v[108:111], v[36:39]
	v_mfma_f32_16x16x32_bf16 v[28:31], v[68:71], v[212:215], v[28:31]
	v_mfma_f32_16x16x32_bf16 v[20:23], v[76:79], v[212:215], v[20:23]
	v_mfma_f32_16x16x32_bf16 v[12:15], v[68:71], v[220:223], v[12:15]
	v_mfma_f32_16x16x32_bf16 v[8:11], v[76:79], v[220:223], v[8:11]
	v_mfma_f32_16x16x32_bf16 v[56:59], v[80:83], v[96:99], v[56:59]
	v_mfma_f32_16x16x32_bf16 v[48:51], v[88:91], v[96:99], v[48:51]
	v_mfma_f32_16x16x32_bf16 v[40:43], v[80:83], v[104:107], v[40:43]
	v_mfma_f32_16x16x32_bf16 v[32:35], v[88:91], v[104:107], v[32:35]
	v_mfma_f32_16x16x32_bf16 v[24:27], v[80:83], v[176:179], v[24:27]
	v_mfma_f32_16x16x32_bf16 v[16:19], v[88:91], v[176:179], v[16:19]
	v_mfma_f32_16x16x32_bf16 v[4:7], v[80:83], v[216:219], v[4:7]
	v_mfma_f32_16x16x32_bf16 v[0:3], v[88:91], v[216:219], v[0:3]
	v_mfma_f32_16x16x32_bf16 v[56:59], v[84:87], v[100:103], v[56:59]
	v_mfma_f32_16x16x32_bf16 v[48:51], v[92:95], v[100:103], v[48:51]
	v_mfma_f32_16x16x32_bf16 v[40:43], v[84:87], v[108:111], v[40:43]
	v_mfma_f32_16x16x32_bf16 v[32:35], v[92:95], v[108:111], v[32:35]
	v_mfma_f32_16x16x32_bf16 v[24:27], v[84:87], v[212:215], v[24:27]
	v_mfma_f32_16x16x32_bf16 v[16:19], v[92:95], v[212:215], v[16:19]
	v_mfma_f32_16x16x32_bf16 v[4:7], v[84:87], v[220:223], v[4:7]
	v_mfma_f32_16x16x32_bf16 v[0:3], v[92:95], v[220:223], v[0:3]
	s_setprio 0
	s_barrier
	s_add_i32 s75, s75, 2
	s_add_u32 s46, s46, 0x100
	s_addc_u32 s47, s47, 0
	s_add_u32 s72, s72, 0x100
	s_addc_u32 s73, s73, 0
	s_cmp_gt_u32 s75, 29
	s_cbranch_scc0 .LBB0_2577
	s_branch .Lkx_30
.LBB0_2577:
	ds_read_b128 v[64:67], v189
	ds_read_b128 v[68:71], v189 offset:1024
	ds_read_b128 v[72:75], v189 offset:2048
	ds_read_b128 v[76:79], v189 offset:3072
	ds_read_b128 v[80:83], v197
	ds_read_b128 v[84:87], v197 offset:1024
	ds_read_b128 v[88:91], v197 offset:2048
	ds_read_b128 v[92:95], v197 offset:3072
	s_add_u32 s48, s46, 0xfff80080
	s_addc_u32 s49, s47, -1
	s_cmp_eq_u32 s75, 28
	s_cselect_b32 s51, s11, s49
	s_cselect_b32 s50, s39, s48
	s_cselect_b32 s49, s37, s73
	s_cselect_b32 s48, s45, s72
	v_lshl_add_u64 v[224:225], s[46:47], 0, v[206:207]
	s_add_i32 m0, s57, 0xc000
	ds_read_b128 v[96:99], v199
	ds_read_b128 v[100:103], v199 offset:1024
	ds_read_b128 v[104:107], v199 offset:2048
	ds_read_b128 v[108:111], v199 offset:3072
	ds_read_b128 v[176:179], v199 offset:4096
	ds_read_b128 v[212:215], v199 offset:5120
	ds_read_b128 v[216:219], v199 offset:6144
	ds_read_b128 v[220:223], v199 offset:7168
	global_load_lds_dwordx4 v[224:225], off
	v_lshl_add_u64 v[224:225], s[46:47], 0, v[208:209]
	s_add_i32 m0, s57, 0xe000
	s_nop 0
	global_load_lds_dwordx4 v[224:225], off
	s_waitcnt vmcnt(8)
	s_waitcnt lgkmcnt(0)
	s_barrier
; #define PG8_STAGE(bufoff, gbase, voff) do { _Pragma("unroll") for (int _i = 0; _i < 2; ++_i) \
;         __builtin_amdgcn_global_load_lds((const unsigned*)((const char*)(gbase) + (voff)[_i]), (PG8_LAS unsigned*)(lds + (bufoff) + ldsw + _i * 8192), 16, 0, 0); } while (0)
; #define PG8_LDA(dst, b, h) do { _Pragma("unroll") for (int m = 0; m < 4; ++m) _Pragma("unroll") for (int k = 0; k < 2; ++k) dst[m][k] = *(const PG8_LAS bf16x8*)(lds + PG8_SA(b, h) + aoff + m * 2048 + k * 1024); } while (0)
; #define PG8_LDB(dst, b, h) do { _Pragma("unroll") for (int n = 0; n < 2; ++n) _Pragma("unroll") for (int k = 0; k < 2; ++k) dst[n][k] = *(const PG8_LAS bf16x8*)(lds + PG8_SB(b, h) + boff + n * 2048 + k * 1024); } while (0)
; #define PG8_MMA(ai, bj, At, Bt) do { __builtin_amdgcn_s_setprio(1); _Pragma("unroll") for (int m = 0; m < 4; ++m) _Pragma("unroll") for (int n = 0; n < 2; ++n) _Pragma("unroll") for (int k = 0; k < 2; ++k) \
;         acc[ai][bj][m][n] = __builtin_amdgcn_mfma_f32_16x16x32_bf16(Bt[n][k], At[m][k], acc[ai][bj][m][n], 0, 0, 0); __builtin_amdgcn_s_setprio(0); } while (0)
; #define PG8_WAIT_V(n) asm volatile("s_waitcnt vmcnt(" #n ")" ::: "memory")
; #define PG8_WAIT_L(n) asm volatile("s_waitcnt lgkmcnt(" #n ")" ::: "memory")
; #define PG8_BAR __builtin_amdgcn_s_barrier()
; #define PG8_SCHED __builtin_amdgcn_sched_barrier(0)
; template <class Epi, class Sched, bool ALIGN_EPI = false, bool SP2 = false>
; __device__ __forceinline__ void gemm_phase(PG8_LAS unsigned char* lds, const Gemm g, const Sched& S, const Epi& E, const int wave_in) {
;     ...
;             PG8_LDB(B0, 0, 0); PG8_LDB(B1, 0, 1); PG8_SCHED; PG8_LDA(At, 0, 0); PG8_STAGE(PG8_SA(1, 1), a1 + hstepA, voffA);
;             PG8_WAIT_V(8); PG8_WAIT_L(0); PG8_BAR; PG8_MMA(0, 0, At, B0); PG8_MMA(0, 1, At, B1); PG8_BAR; PG8_SCHED;
;             PG8_LDA(At, 0, 1); PG8_STAGE(PG8_SB(0, 0), b2, voffB); PG8_STAGE(PG8_SB(0, 1), b2 + hstepB, voffB); PG8_STAGE(PG8_SA(0, 0), a2, voffA);
;             PG8_WAIT_V(8); PG8_WAIT_L(0); PG8_BAR; PG8_MMA(1, 0, At, B0); PG8_MMA(1, 1, At, B1); PG8_BAR; PG8_SCHED;
	s_setprio 1
	v_mfma_f32_16x16x32_bf16 v[172:175], v[64:67], v[96:99], v[172:175]
	v_mfma_f32_16x16x32_bf16 v[164:167], v[72:75], v[96:99], v[164:167]
	v_mfma_f32_16x16x32_bf16 v[156:159], v[64:67], v[104:107], v[156:159]
	v_mfma_f32_16x16x32_bf16 v[148:151], v[72:75], v[104:107], v[148:151]
	v_mfma_f32_16x16x32_bf16 v[140:143], v[64:67], v[176:179], v[140:143]
	v_mfma_f32_16x16x32_bf16 v[132:135], v[72:75], v[176:179], v[132:135]
	v_mfma_f32_16x16x32_bf16 v[124:127], v[64:67], v[216:219], v[124:127]
	v_mfma_f32_16x16x32_bf16 v[120:123], v[72:75], v[216:219], v[120:123]
	v_mfma_f32_16x16x32_bf16 v[172:175], v[68:71], v[100:103], v[172:175]
	v_mfma_f32_16x16x32_bf16 v[164:167], v[76:79], v[100:103], v[164:167]
	v_mfma_f32_16x16x32_bf16 v[156:159], v[68:71], v[108:111], v[156:159]
	v_mfma_f32_16x16x32_bf16 v[148:151], v[76:79], v[108:111], v[148:151]
	v_mfma_f32_16x16x32_bf16 v[140:143], v[68:71], v[212:215], v[140:143]
	v_mfma_f32_16x16x32_bf16 v[132:135], v[76:79], v[212:215], v[132:135]
	v_mfma_f32_16x16x32_bf16 v[124:127], v[68:71], v[220:223], v[124:127]
	v_mfma_f32_16x16x32_bf16 v[120:123], v[76:79], v[220:223], v[120:123]
	v_mfma_f32_16x16x32_bf16 v[168:171], v[80:83], v[96:99], v[168:171]
	v_mfma_f32_16x16x32_bf16 v[96:99], v[88:91], v[96:99], v[160:163]
	v_mfma_f32_16x16x32_bf16 v[168:171], v[84:87], v[100:103], v[168:171]
	v_mfma_f32_16x16x32_bf16 v[96:99], v[92:95], v[100:103], v[96:99]
	v_mfma_f32_16x16x32_bf16 v[100:103], v[80:83], v[104:107], v[152:155]
	v_mfma_f32_16x16x32_bf16 v[104:107], v[88:91], v[104:107], v[144:147]
	v_mfma_f32_16x16x32_bf16 v[128:131], v[88:91], v[176:179], v[128:131]
	v_mfma_f32_16x16x32_bf16 v[116:119], v[80:83], v[216:219], v[116:119]
	v_mfma_f32_16x16x32_bf16 v[112:115], v[88:91], v[216:219], v[112:115]
	v_mfma_f32_16x16x32_bf16 v[100:103], v[84:87], v[108:111], v[100:103]
	v_mfma_f32_16x16x32_bf16 v[104:107], v[92:95], v[108:111], v[104:107]
	v_mfma_f32_16x16x32_bf16 v[108:111], v[80:83], v[176:179], v[136:139]
	v_mfma_f32_16x16x32_bf16 v[128:131], v[92:95], v[212:215], v[128:131]
	v_mfma_f32_16x16x32_bf16 v[116:119], v[84:87], v[220:223], v[116:119]
	v_mfma_f32_16x16x32_bf16 v[112:115], v[92:95], v[220:223], v[112:115]
	v_mfma_f32_16x16x32_bf16 v[108:111], v[84:87], v[212:215], v[108:111]
	s_setprio 0
	s_barrier
	s_add_i32 s76, s69, s56
	v_lshl_add_u64 v[232:233], s[48:49], 0, v[182:183]
	s_mov_b32 m0, s76
	ds_read_b128 v[136:139], v199 offset:16384
	ds_read_b128 v[144:147], v199 offset:17408
	ds_read_b128 v[152:155], v199 offset:18432
	ds_read_b128 v[160:163], v199 offset:19456
	ds_read_b128 v[176:179], v199 offset:20480
	ds_read_b128 v[212:215], v199 offset:21504
	ds_read_b128 v[216:219], v199 offset:22528
	ds_read_b128 v[220:223], v199 offset:23552
	global_load_lds_dwordx4 v[232:233], off
	s_add_i32 m0, s76, 0x2000
	s_add_u32 s76, s48, 0x80000
	v_lshl_add_u64 v[234:235], s[48:49], 0, v[186:187]
	s_addc_u32 s77, s49, 0
	s_add_i32 s78, s70, s56
	global_load_lds_dwordx4 v[234:235], off
	v_lshl_add_u64 v[224:225], s[76:77], 0, v[182:183]
	s_mov_b32 m0, s78
	v_lshl_add_u64 v[236:237], s[50:51], 0, v[180:181]
	global_load_lds_dwordx4 v[224:225], off
	v_lshl_add_u64 v[224:225], s[76:77], 0, v[186:187]
	s_add_i32 m0, s78, 0x2000
	v_lshl_add_u64 v[238:239], s[50:51], 0, v[184:185]
	global_load_lds_dwordx4 v[224:225], off
	s_mov_b32 m0, s57
	s_nop 0
	global_load_lds_dwordx4 v[236:237], off
	s_mov_b32 m0, s58
	s_nop 0
	global_load_lds_dwordx4 v[238:239], off
	s_waitcnt vmcnt(8)
	s_waitcnt lgkmcnt(0)
	s_barrier
	s_setprio 1
	v_mfma_f32_16x16x32_bf16 v[60:63], v[64:67], v[136:139], v[60:63]
	v_mfma_f32_16x16x32_bf16 v[52:55], v[72:75], v[136:139], v[52:55]
	v_mfma_f32_16x16x32_bf16 v[44:47], v[64:67], v[152:155], v[44:47]
	v_mfma_f32_16x16x32_bf16 v[36:39], v[72:75], v[152:155], v[36:39]
	v_mfma_f32_16x16x32_bf16 v[28:31], v[64:67], v[176:179], v[28:31]
	v_mfma_f32_16x16x32_bf16 v[20:23], v[72:75], v[176:179], v[20:23]
	v_mfma_f32_16x16x32_bf16 v[12:15], v[64:67], v[216:219], v[12:15]
	v_mfma_f32_16x16x32_bf16 v[8:11], v[72:75], v[216:219], v[8:11]
	v_mfma_f32_16x16x32_bf16 v[60:63], v[68:71], v[144:147], v[60:63]
	v_mfma_f32_16x16x32_bf16 v[52:55], v[76:79], v[144:147], v[52:55]
	v_mfma_f32_16x16x32_bf16 v[44:47], v[68:71], v[160:163], v[44:47]
	v_mfma_f32_16x16x32_bf16 v[36:39], v[76:79], v[160:163], v[36:39]
	v_mfma_f32_16x16x32_bf16 v[28:31], v[68:71], v[212:215], v[28:31]
	v_mfma_f32_16x16x32_bf16 v[20:23], v[76:79], v[212:215], v[20:23]
	v_mfma_f32_16x16x32_bf16 v[12:15], v[68:71], v[220:223], v[12:15]
	v_mfma_f32_16x16x32_bf16 v[8:11], v[76:79], v[220:223], v[8:11]
	v_mfma_f32_16x16x32_bf16 v[56:59], v[80:83], v[136:139], v[56:59]
	v_mfma_f32_16x16x32_bf16 v[48:51], v[88:91], v[136:139], v[48:51]
	v_mfma_f32_16x16x32_bf16 v[40:43], v[80:83], v[152:155], v[40:43]
	v_mfma_f32_16x16x32_bf16 v[32:35], v[88:91], v[152:155], v[32:35]
	v_mfma_f32_16x16x32_bf16 v[24:27], v[80:83], v[176:179], v[24:27]
	v_mfma_f32_16x16x32_bf16 v[16:19], v[88:91], v[176:179], v[16:19]
	v_mfma_f32_16x16x32_bf16 v[4:7], v[80:83], v[216:219], v[4:7]
	v_mfma_f32_16x16x32_bf16 v[0:3], v[88:91], v[216:219], v[0:3]
	v_mfma_f32_16x16x32_bf16 v[56:59], v[84:87], v[144:147], v[56:59]
	v_mfma_f32_16x16x32_bf16 v[48:51], v[92:95], v[144:147], v[48:51]
	v_mfma_f32_16x16x32_bf16 v[40:43], v[84:87], v[160:163], v[40:43]
	v_mfma_f32_16x16x32_bf16 v[32:35], v[92:95], v[160:163], v[32:35]
	v_mfma_f32_16x16x32_bf16 v[24:27], v[84:87], v[212:215], v[24:27]
	v_mfma_f32_16x16x32_bf16 v[16:19], v[92:95], v[212:215], v[16:19]
	v_mfma_f32_16x16x32_bf16 v[4:7], v[84:87], v[220:223], v[4:7]
	v_mfma_f32_16x16x32_bf16 v[0:3], v[92:95], v[220:223], v[0:3]
	s_setprio 0
	s_barrier
; #define PG8_STAGE(bufoff, gbase, voff) do { _Pragma("unroll") for (int _i = 0; _i < 2; ++_i) \
;         __builtin_amdgcn_global_load_lds((const unsigned*)((const char*)(gbase) + (voff)[_i]), (PG8_LAS unsigned*)(lds + (bufoff) + ldsw + _i * 8192), 16, 0, 0); } while (0)
; #define PG8_LDA(dst, b, h) do { _Pragma("unroll") for (int m = 0; m < 4; ++m) _Pragma("unroll") for (int k = 0; k < 2; ++k) dst[m][k] = *(const PG8_LAS bf16x8*)(lds + PG8_SA(b, h) + aoff + m * 2048 + k * 1024); } while (0)
; #define PG8_LDB(dst, b, h) do { _Pragma("unroll") for (int n = 0; n < 2; ++n) _Pragma("unroll") for (int k = 0; k < 2; ++k) dst[n][k] = *(const PG8_LAS bf16x8*)(lds + PG8_SB(b, h) + boff + n * 2048 + k * 1024); } while (0)
; #define PG8_MMA(ai, bj, At, Bt) do { __builtin_amdgcn_s_setprio(1); _Pragma("unroll") for (int m = 0; m < 4; ++m) _Pragma("unroll") for (int n = 0; n < 2; ++n) _Pragma("unroll") for (int k = 0; k < 2; ++k) \
;         acc[ai][bj][m][n] = __builtin_amdgcn_mfma_f32_16x16x32_bf16(Bt[n][k], At[m][k], acc[ai][bj][m][n], 0, 0, 0); __builtin_amdgcn_s_setprio(0); } while (0)
; #define PG8_WAIT_V(n) asm volatile("s_waitcnt vmcnt(" #n ")" ::: "memory")
; #define PG8_WAIT_L(n) asm volatile("s_waitcnt lgkmcnt(" #n ")" ::: "memory")
; #define PG8_BAR __builtin_amdgcn_s_barrier()
; #define PG8_SCHED __builtin_amdgcn_sched_barrier(0)
; template <class Epi, class Sched, bool ALIGN_EPI = false, bool SP2 = false>
; __device__ __forceinline__ void gemm_phase(PG8_LAS unsigned char* lds, const Gemm g, const Sched& S, const Epi& E, const int wave_in) {
;     ...
;             PG8_LDB(B0, 1, 0); PG8_LDB(B1, 1, 1); PG8_SCHED; PG8_LDA(At, 1, 0); PG8_STAGE(PG8_SA(0, 1), a2 + hstepA, voffA);
;             PG8_WAIT_V(8); PG8_WAIT_L(0); PG8_BAR; PG8_MMA(0, 0, At, B0); PG8_MMA(0, 1, At, B1); PG8_BAR; PG8_SCHED;
;             PG8_LDA(At, 1, 1); PG8_STAGE(PG8_SB(1, 0), b3, voffB); PG8_STAGE(PG8_SB(1, 1), b3 + hstepB, voffB); PG8_STAGE(PG8_SA(1, 0), a3, voffA);
;             PG8_WAIT_V(8); PG8_WAIT_L(0); PG8_BAR; PG8_MMA(1, 0, At, B0); PG8_MMA(1, 1, At, B1); PG8_BAR; PG8_SCHED;
	s_add_i32 s76, 0, 0x18000
	s_add_i32 s77, 0, 0x1c000
	v_add_u32_e32 v76, s76, v195
	v_add_u32_e32 v92, s77, v195
	ds_read_b128 v[64:67], v76
	ds_read_b128 v[68:71], v76 offset:1024
	ds_read_b128 v[72:75], v76 offset:2048
	ds_read_b128 v[76:79], v76 offset:3072
	ds_read_b128 v[80:83], v92
	ds_read_b128 v[84:87], v92 offset:1024
	ds_read_b128 v[88:91], v92 offset:2048
	ds_read_b128 v[92:95], v92 offset:3072
	s_add_u32 s50, s50, 0x80000
	s_addc_u32 s51, s51, 0
	s_mov_b32 m0, s59
	v_lshl_add_u64 v[152:153], s[50:51], 0, v[180:181]
	ds_read_b128 v[136:139], v199 offset:32768
	ds_read_b128 v[144:147], v199 offset:33792
	ds_read_b128 v[176:179], v199 offset:34816
	ds_read_b128 v[212:215], v199 offset:35840
	ds_read_b128 v[216:219], v199 offset:36864
	ds_read_b128 v[220:223], v199 offset:37888
	ds_read_b128 v[224:227], v199 offset:38912
	ds_read_b128 v[228:231], v199 offset:39936
	global_load_lds_dwordx4 v[152:153], off
	v_lshl_add_u64 v[152:153], s[50:51], 0, v[184:185]
	s_mov_b32 m0, s60
	s_nop 0
	global_load_lds_dwordx4 v[152:153], off
	s_waitcnt vmcnt(8)
	s_waitcnt lgkmcnt(0)
	s_barrier
	s_setprio 1
	v_mfma_f32_16x16x32_bf16 v[152:155], v[64:67], v[136:139], v[172:175]
	v_mfma_f32_16x16x32_bf16 v[172:175], v[68:71], v[144:147], v[152:155]
	v_mfma_f32_16x16x32_bf16 v[152:155], v[72:75], v[136:139], v[164:167]
	v_mfma_f32_16x16x32_bf16 v[164:167], v[76:79], v[144:147], v[152:155]
	v_mfma_f32_16x16x32_bf16 v[152:155], v[64:67], v[176:179], v[156:159]
	v_mfma_f32_16x16x32_bf16 v[148:151], v[72:75], v[176:179], v[148:151]
	v_mfma_f32_16x16x32_bf16 v[140:143], v[64:67], v[216:219], v[140:143]
	v_mfma_f32_16x16x32_bf16 v[132:135], v[72:75], v[216:219], v[132:135]
	v_mfma_f32_16x16x32_bf16 v[124:127], v[64:67], v[224:227], v[124:127]
	v_mfma_f32_16x16x32_bf16 v[120:123], v[72:75], v[224:227], v[120:123]
	v_mfma_f32_16x16x32_bf16 v[156:159], v[68:71], v[212:215], v[152:155]
	v_mfma_f32_16x16x32_bf16 v[148:151], v[76:79], v[212:215], v[148:151]
	v_mfma_f32_16x16x32_bf16 v[140:143], v[68:71], v[220:223], v[140:143]
	v_mfma_f32_16x16x32_bf16 v[132:135], v[76:79], v[220:223], v[132:135]
	v_mfma_f32_16x16x32_bf16 v[124:127], v[68:71], v[228:231], v[124:127]
	v_mfma_f32_16x16x32_bf16 v[120:123], v[76:79], v[228:231], v[120:123]
	v_mfma_f32_16x16x32_bf16 v[96:99], v[88:91], v[136:139], v[96:99]
	v_mfma_f32_16x16x32_bf16 v[152:155], v[80:83], v[136:139], v[168:171]
	v_mfma_f32_16x16x32_bf16 v[160:163], v[92:95], v[144:147], v[96:99]
	v_mfma_f32_16x16x32_bf16 v[96:99], v[80:83], v[176:179], v[100:103]
	v_mfma_f32_16x16x32_bf16 v[168:171], v[84:87], v[144:147], v[152:155]
	v_mfma_f32_16x16x32_bf16 v[152:155], v[84:87], v[212:215], v[96:99]
	v_mfma_f32_16x16x32_bf16 v[96:99], v[88:91], v[176:179], v[104:107]
	v_mfma_f32_16x16x32_bf16 v[144:147], v[92:95], v[212:215], v[96:99]
	v_mfma_f32_16x16x32_bf16 v[96:99], v[80:83], v[216:219], v[108:111]
	v_mfma_f32_16x16x32_bf16 v[136:139], v[84:87], v[220:223], v[96:99]
	v_mfma_f32_16x16x32_bf16 v[96:99], v[88:91], v[216:219], v[128:131]
	v_mfma_f32_16x16x32_bf16 v[128:131], v[92:95], v[220:223], v[96:99]
	v_mfma_f32_16x16x32_bf16 v[96:99], v[80:83], v[224:227], v[116:119]
	v_mfma_f32_16x16x32_bf16 v[116:119], v[84:87], v[228:231], v[96:99]
	v_mfma_f32_16x16x32_bf16 v[96:99], v[88:91], v[224:227], v[112:115]
	v_mfma_f32_16x16x32_bf16 v[112:115], v[92:95], v[228:231], v[96:99]
	s_setprio 0
	s_barrier
	s_add_i32 s50, s76, s56
	v_lshl_add_u64 v[224:225], v[232:233], 0, s[20:21]
	s_mov_b32 m0, s50
	s_nop 1
	ds_read_b128 v[96:99], v199 offset:49152
	ds_read_b128 v[100:103], v199 offset:50176
	ds_read_b128 v[104:107], v199 offset:51200
	ds_read_b128 v[108:111], v199 offset:52224
	ds_read_b128 v[176:179], v199 offset:53248
	ds_read_b128 v[212:215], v199 offset:54272
	ds_read_b128 v[216:219], v199 offset:55296
	ds_read_b128 v[220:223], v199 offset:56320
	global_load_lds_dwordx4 v[224:225], off
	s_add_i32 m0, s50, 0x2000
	s_add_u32 s48, s48, 0x80080
	v_lshl_add_u64 v[224:225], v[234:235], 0, s[20:21]
	s_addc_u32 s49, s49, 0
	s_add_i32 s50, s77, s56
	global_load_lds_dwordx4 v[224:225], off
	v_lshl_add_u64 v[224:225], s[48:49], 0, v[182:183]
	s_mov_b32 m0, s50
	s_nop 0
	global_load_lds_dwordx4 v[224:225], off
	v_lshl_add_u64 v[224:225], s[48:49], 0, v[186:187]
	s_add_i32 m0, s50, 0x2000
	s_nop 0
	global_load_lds_dwordx4 v[224:225], off
	v_lshl_add_u64 v[224:225], v[236:237], 0, s[20:21]
	s_mov_b32 m0, s63
	s_nop 0
	global_load_lds_dwordx4 v[224:225], off
	v_lshl_add_u64 v[224:225], v[238:239], 0, s[20:21]
	s_mov_b32 m0, s64
	s_nop 0
	global_load_lds_dwordx4 v[224:225], off
	s_waitcnt vmcnt(8)
	s_waitcnt lgkmcnt(0)
	s_barrier
	s_setprio 1
	v_mfma_f32_16x16x32_bf16 v[60:63], v[64:67], v[96:99], v[60:63]
	v_mfma_f32_16x16x32_bf16 v[52:55], v[72:75], v[96:99], v[52:55]
	v_mfma_f32_16x16x32_bf16 v[44:47], v[64:67], v[104:107], v[44:47]
	v_mfma_f32_16x16x32_bf16 v[36:39], v[72:75], v[104:107], v[36:39]
	v_mfma_f32_16x16x32_bf16 v[28:31], v[64:67], v[176:179], v[28:31]
	v_mfma_f32_16x16x32_bf16 v[20:23], v[72:75], v[176:179], v[20:23]
	v_mfma_f32_16x16x32_bf16 v[12:15], v[64:67], v[216:219], v[12:15]
	v_mfma_f32_16x16x32_bf16 v[8:11], v[72:75], v[216:219], v[8:11]
	v_mfma_f32_16x16x32_bf16 v[60:63], v[68:71], v[100:103], v[60:63]
	v_mfma_f32_16x16x32_bf16 v[52:55], v[76:79], v[100:103], v[52:55]
	v_mfma_f32_16x16x32_bf16 v[44:47], v[68:71], v[108:111], v[44:47]
	v_mfma_f32_16x16x32_bf16 v[36:39], v[76:79], v[108:111], v[36:39]
	v_mfma_f32_16x16x32_bf16 v[28:31], v[68:71], v[212:215], v[28:31]
	v_mfma_f32_16x16x32_bf16 v[20:23], v[76:79], v[212:215], v[20:23]
	v_mfma_f32_16x16x32_bf16 v[12:15], v[68:71], v[220:223], v[12:15]
	v_mfma_f32_16x16x32_bf16 v[8:11], v[76:79], v[220:223], v[8:11]
	v_mfma_f32_16x16x32_bf16 v[56:59], v[80:83], v[96:99], v[56:59]
	v_mfma_f32_16x16x32_bf16 v[48:51], v[88:91], v[96:99], v[48:51]
	v_mfma_f32_16x16x32_bf16 v[40:43], v[80:83], v[104:107], v[40:43]
	v_mfma_f32_16x16x32_bf16 v[32:35], v[88:91], v[104:107], v[32:35]
	v_mfma_f32_16x16x32_bf16 v[24:27], v[80:83], v[176:179], v[24:27]
	v_mfma_f32_16x16x32_bf16 v[16:19], v[88:91], v[176:179], v[16:19]
	v_mfma_f32_16x16x32_bf16 v[4:7], v[80:83], v[216:219], v[4:7]
	v_mfma_f32_16x16x32_bf16 v[0:3], v[88:91], v[216:219], v[0:3]
	v_mfma_f32_16x16x32_bf16 v[56:59], v[84:87], v[100:103], v[56:59]
	v_mfma_f32_16x16x32_bf16 v[48:51], v[92:95], v[100:103], v[48:51]
	v_mfma_f32_16x16x32_bf16 v[40:43], v[84:87], v[108:111], v[40:43]
	v_mfma_f32_16x16x32_bf16 v[32:35], v[92:95], v[108:111], v[32:35]
	v_mfma_f32_16x16x32_bf16 v[24:27], v[84:87], v[212:215], v[24:27]
	v_mfma_f32_16x16x32_bf16 v[16:19], v[92:95], v[212:215], v[16:19]
	v_mfma_f32_16x16x32_bf16 v[4:7], v[84:87], v[220:223], v[4:7]
	v_mfma_f32_16x16x32_bf16 v[0:3], v[92:95], v[220:223], v[0:3]
	s_setprio 0
	s_barrier
	s_add_i32 s75, s75, 2
	s_add_u32 s46, s46, 0x100
	s_addc_u32 s47, s47, 0
	s_add_u32 s72, s72, 0x100
	s_addc_u32 s73, s73, 0
	s_cmp_gt_u32 s75, 29
	s_cbranch_scc0 .LBB0_2577

;     __host__ __device__ bool next(int i, Unit& u) const { const bool ok = StaticOrder::next(i, u); u.pm = 0; u.pn = 0; return ok; }
; #define PG8_STAGE(bufoff, gbase, voff) do { _Pragma("unroll") for (int _i = 0; _i < 2; ++_i) \
;         __builtin_amdgcn_global_load_lds((const unsigned*)((const char*)(gbase) + (voff)[_i]), (PG8_LAS unsigned*)(lds + (bufoff) + ldsw + _i * 8192), 16, 0, 0); } while (0)
; #define PG8_LDA(dst, b, h) do { _Pragma("unroll") for (int m = 0; m < 4; ++m) _Pragma("unroll") for (int k = 0; k < 2; ++k) dst[m][k] = *(const PG8_LAS bf16x8*)(lds + PG8_SA(b, h) + aoff + m * 2048 + k * 1024); } while (0)
; #define PG8_LDB(dst, b, h) do { _Pragma("unroll") for (int n = 0; n < 2; ++n) _Pragma("unroll") for (int k = 0; k < 2; ++k) dst[n][k] = *(const PG8_LAS bf16x8*)(lds + PG8_SB(b, h) + boff + n * 2048 + k * 1024); } while (0)
; #define PG8_WAIT_V(n) asm volatile("s_waitcnt vmcnt(" #n ")" ::: "memory")
; #define PG8_BAR __builtin_amdgcn_s_barrier()
; template <class Epi, class Sched, bool ALIGN_EPI = false, bool SP2 = false>
; __device__ __forceinline__ void gemm_phase(PG8_LAS unsigned char* lds, const Gemm g, const Sched& S, const Epi& E, const int wave_in) {
;     ...
;         const bool has_next = S.next(ui + 1, nxt);
;         const char* nA = has_next ? (const char*)g.A + (size_t)nxt.pm * tstepA : cA; const char* nB = has_next ? (const char*)g.Bt + (size_t)nxt.pn * tstepB : cB;
;         for (int t = 0; t < nt; t += 2) {
;             const bool last = (t == nt - 2);
;             const char* a1 = cA + (size_t)(t + 1) * kstep;
;             const char* a2 = last ? nA : cA + (size_t)(t + 2) * kstep; const char* b2 = last ? nB : cB + (size_t)(t + 2) * kstep;
;             const char* a3 = a2 + kstep; const char* b3 = b2 + kstep;
;             if (last && has_next) S.a_ready(nxt);
;             if constexpr (SP2) {
;             PG8_LDB(B0, 0, 0); PG8_LDB(B1, 0, 1); PG8_SCHED; PG8_LDA(At, 0, 0); PG8_STAGE(PG8_SA(1, 1), a1 + hstepA, voffA);
;             PG8_WAIT_V(8); PG8_WAIT_L(0); PG8_BAR; PG8_MMA(0, 0, At, B0); PG8_MMA(0, 1, At, B1); PG8_BAR; PG8_SCHED;
;             PG8_LDA(At, 0, 1); PG8_STAGE(PG8_SB(0, 0), b2, voffB); PG8_STAGE(PG8_SB(0, 1), b2 + hstepB, voffB); PG8_STAGE(PG8_SA(0, 0), a2, voffA);
;             PG8_WAIT_V(8); PG8_WAIT_L(0); PG8_BAR; PG8_MMA(1, 0, At, B0); PG8_MMA(1, 1, At, B1); PG8_BAR; PG8_SCHED;
.LBB0_2740:
	s_add_u32 s25, s28, 0x100
	v_mov_b32_e32 v0, 0
	s_addc_u32 s65, s29, 0
	s_mov_b32 s66, -2
	s_waitcnt vmcnt(0)
	ds_read_b128 v[128:131], v170
	ds_read_b128 v[132:135], v170 offset:1024
	ds_read_b128 v[136:139], v170 offset:2048
	ds_read_b128 v[140:143], v170 offset:3072
	ds_read_b128 v[162:165], v171
	ds_read_b128 v[174:177], v171 offset:1024
	ds_read_b128 v[178:181], v171 offset:2048
	ds_read_b128 v[182:185], v171 offset:3072
	s_add_u32 s2, s26, 0x100
	s_addc_u32 s3, s27, 0
	s_cmpk_eq_i32 s66, 0x52
	s_cselect_b32 s31, s21, s3
	s_cselect_b32 s30, s20, s2
	s_cselect_b32 s29, s23, s65
	s_cselect_b32 s28, s22, s25
	v_lshl_add_u64 v[166:167], s[26:27], 0, v[154:155]
	s_add_i32 m0, s40, 0xc000
	ds_read_b128 v[186:189], v172
	ds_read_b128 v[190:193], v172 offset:1024
	ds_read_b128 v[194:197], v172 offset:2048
	ds_read_b128 v[198:201], v172 offset:3072
	ds_read_b128 v[202:205], v172 offset:4096
	ds_read_b128 v[206:209], v172 offset:5120
	ds_read_b128 v[210:213], v172 offset:6144
	ds_read_b128 v[214:217], v172 offset:7168
	global_load_lds_dwordx4 v[166:167], off
	v_lshl_add_u64 v[166:167], s[26:27], 0, v[156:157]
	s_add_i32 m0, s40, 0xe000
	s_nop 0
	global_load_lds_dwordx4 v[166:167], off
	s_waitcnt vmcnt(8)
	s_waitcnt lgkmcnt(0)
	s_barrier
	s_setprio 1
	v_mfma_f32_16x16x32_bf16 v[124:127], v[128:131], v[186:189], 0
	v_mfma_f32_16x16x32_bf16 v[120:123], v[136:139], v[186:189], 0
	v_mfma_f32_16x16x32_bf16 v[104:107], v[128:131], v[194:197], 0
	v_mfma_f32_16x16x32_bf16 v[108:111], v[136:139], v[194:197], 0
	v_mfma_f32_16x16x32_bf16 v[88:91], v[128:131], v[202:205], 0
	v_mfma_f32_16x16x32_bf16 v[92:95], v[136:139], v[202:205], 0
	v_mfma_f32_16x16x32_bf16 v[72:75], v[128:131], v[210:213], 0
	v_mfma_f32_16x16x32_bf16 v[76:79], v[136:139], v[210:213], 0
	v_mfma_f32_16x16x32_bf16 v[124:127], v[132:135], v[190:193], v[124:127]
	v_mfma_f32_16x16x32_bf16 v[120:123], v[140:143], v[190:193], v[120:123]
	v_mfma_f32_16x16x32_bf16 v[104:107], v[132:135], v[198:201], v[104:107]
	v_mfma_f32_16x16x32_bf16 v[108:111], v[140:143], v[198:201], v[108:111]
	v_mfma_f32_16x16x32_bf16 v[88:91], v[132:135], v[206:209], v[88:91]
	v_mfma_f32_16x16x32_bf16 v[92:95], v[140:143], v[206:209], v[92:95]
	v_mfma_f32_16x16x32_bf16 v[72:75], v[132:135], v[214:217], v[72:75]
	v_mfma_f32_16x16x32_bf16 v[76:79], v[140:143], v[214:217], v[76:79]
	v_mfma_f32_16x16x32_bf16 v[112:115], v[162:165], v[186:189], 0
	v_mfma_f32_16x16x32_bf16 v[116:119], v[178:181], v[186:189], 0
	v_mfma_f32_16x16x32_bf16 v[96:99], v[162:165], v[194:197], 0
	v_mfma_f32_16x16x32_bf16 v[100:103], v[178:181], v[194:197], 0
	v_mfma_f32_16x16x32_bf16 v[80:83], v[162:165], v[202:205], 0
	v_mfma_f32_16x16x32_bf16 v[84:87], v[178:181], v[202:205], 0
	v_mfma_f32_16x16x32_bf16 v[64:67], v[162:165], v[210:213], 0
	v_mfma_f32_16x16x32_bf16 v[68:71], v[178:181], v[210:213], 0
	v_mfma_f32_16x16x32_bf16 v[112:115], v[174:177], v[190:193], v[112:115]
	v_mfma_f32_16x16x32_bf16 v[116:119], v[182:185], v[190:193], v[116:119]
	v_mfma_f32_16x16x32_bf16 v[96:99], v[174:177], v[198:201], v[96:99]
	v_mfma_f32_16x16x32_bf16 v[100:103], v[182:185], v[198:201], v[100:103]
	v_mfma_f32_16x16x32_bf16 v[80:83], v[174:177], v[206:209], v[80:83]
	v_mfma_f32_16x16x32_bf16 v[84:87], v[182:185], v[206:209], v[84:87]
	v_mfma_f32_16x16x32_bf16 v[64:67], v[174:177], v[214:217], v[64:67]
	v_mfma_f32_16x16x32_bf16 v[68:71], v[182:185], v[214:217], v[68:71]
	s_setprio 0
	s_barrier
	s_add_i32 s26, s50, s39
	v_lshl_add_u64 v[166:167], s[28:29], 0, v[146:147]
	s_mov_b32 m0, s26
	ds_read_b128 v[186:189], v172 offset:16384
	ds_read_b128 v[190:193], v172 offset:17408
	ds_read_b128 v[194:197], v172 offset:18432
	ds_read_b128 v[198:201], v172 offset:19456
	ds_read_b128 v[202:205], v172 offset:20480
	ds_read_b128 v[206:209], v172 offset:21504
	ds_read_b128 v[210:213], v172 offset:22528
	ds_read_b128 v[214:217], v172 offset:23552
	global_load_lds_dwordx4 v[166:167], off
	s_add_i32 m0, s26, 0x2000
	s_add_u32 s26, s28, 0x158000
	v_lshl_add_u64 v[218:219], s[28:29], 0, v[150:151]
	s_addc_u32 s27, s29, 0
	s_add_i32 s67, s51, s39
	global_load_lds_dwordx4 v[218:219], off
	v_lshl_add_u64 v[220:221], s[26:27], 0, v[146:147]
	s_mov_b32 m0, s67
	v_lshl_add_u64 v[222:223], s[30:31], 0, v[148:149]
	global_load_lds_dwordx4 v[220:221], off
	v_lshl_add_u64 v[220:221], s[26:27], 0, v[150:151]
	s_add_i32 m0, s67, 0x2000
	s_nop 0
	global_load_lds_dwordx4 v[220:221], off
	v_lshl_add_u64 v[220:221], s[30:31], 0, v[144:145]
	s_mov_b32 m0, s40
	s_nop 0
	global_load_lds_dwordx4 v[220:221], off
	s_mov_b32 m0, s41
	s_nop 0
	global_load_lds_dwordx4 v[222:223], off
	s_waitcnt vmcnt(8)
	s_waitcnt lgkmcnt(0)
	s_barrier
; #define PG8_STAGE(bufoff, gbase, voff) do { _Pragma("unroll") for (int _i = 0; _i < 2; ++_i) \
;         __builtin_amdgcn_global_load_lds((const unsigned*)((const char*)(gbase) + (voff)[_i]), (PG8_LAS unsigned*)(lds + (bufoff) + ldsw + _i * 8192), 16, 0, 0); } while (0)
; #define PG8_LDA(dst, b, h) do { _Pragma("unroll") for (int m = 0; m < 4; ++m) _Pragma("unroll") for (int k = 0; k < 2; ++k) dst[m][k] = *(const PG8_LAS bf16x8*)(lds + PG8_SA(b, h) + aoff + m * 2048 + k * 1024); } while (0)
; #define PG8_LDB(dst, b, h) do { _Pragma("unroll") for (int n = 0; n < 2; ++n) _Pragma("unroll") for (int k = 0; k < 2; ++k) dst[n][k] = *(const PG8_LAS bf16x8*)(lds + PG8_SB(b, h) + boff + n * 2048 + k * 1024); } while (0)
; #define PG8_MMA(ai, bj, At, Bt) do { __builtin_amdgcn_s_setprio(1); _Pragma("unroll") for (int m = 0; m < 4; ++m) _Pragma("unroll") for (int n = 0; n < 2; ++n) _Pragma("unroll") for (int k = 0; k < 2; ++k) \
;         acc[ai][bj][m][n] = __builtin_amdgcn_mfma_f32_16x16x32_bf16(Bt[n][k], At[m][k], acc[ai][bj][m][n], 0, 0, 0); __builtin_amdgcn_s_setprio(0); } while (0)
; #define PG8_BAR __builtin_amdgcn_s_barrier()
; template <class Epi, class Sched, bool ALIGN_EPI = false, bool SP2 = false>
; __device__ __forceinline__ void gemm_phase(PG8_LAS unsigned char* lds, const Gemm g, const Sched& S, const Epi& E, const int wave_in) {
;     ...
;             PG8_LDB(B0, 0, 0); PG8_LDB(B1, 0, 1); PG8_SCHED; PG8_LDA(At, 0, 0); PG8_STAGE(PG8_SA(1, 1), a1 + hstepA, voffA);
;             PG8_WAIT_V(8); PG8_WAIT_L(0); PG8_BAR; PG8_MMA(0, 0, At, B0); PG8_MMA(0, 1, At, B1); PG8_BAR; PG8_SCHED;
;             PG8_LDA(At, 0, 1); PG8_STAGE(PG8_SB(0, 0), b2, voffB); PG8_STAGE(PG8_SB(0, 1), b2 + hstepB, voffB); PG8_STAGE(PG8_SA(0, 0), a2, voffA);
;             PG8_WAIT_V(8); PG8_WAIT_L(0); PG8_BAR; PG8_MMA(1, 0, At, B0); PG8_MMA(1, 1, At, B1); PG8_BAR; PG8_SCHED;
;             PG8_LDB(B0, 1, 0); PG8_LDB(B1, 1, 1); PG8_SCHED; PG8_LDA(At, 1, 0); PG8_STAGE(PG8_SA(0, 1), a2 + hstepA, voffA);
;             PG8_WAIT_V(8); PG8_WAIT_L(0); PG8_BAR; PG8_MMA(0, 0, At, B0); PG8_MMA(0, 1, At, B1); PG8_BAR; PG8_SCHED;
;             PG8_LDA(At, 1, 1); PG8_STAGE(PG8_SB(1, 0), b3, voffB); PG8_STAGE(PG8_SB(1, 1), b3 + hstepB, voffB); PG8_STAGE(PG8_SA(1, 0), a3, voffA);
;             PG8_WAIT_V(8); PG8_WAIT_L(0); PG8_BAR; PG8_MMA(1, 0, At, B0); PG8_MMA(1, 1, At, B1); PG8_BAR; PG8_SCHED;
	s_setprio 1
	v_mfma_f32_16x16x32_bf16 v[60:63], v[128:131], v[186:189], 0
	v_mfma_f32_16x16x32_bf16 v[56:59], v[136:139], v[186:189], 0
	v_mfma_f32_16x16x32_bf16 v[40:43], v[128:131], v[194:197], 0
	v_mfma_f32_16x16x32_bf16 v[48:51], v[136:139], v[194:197], 0
	v_mfma_f32_16x16x32_bf16 v[24:27], v[128:131], v[202:205], 0
	v_mfma_f32_16x16x32_bf16 v[32:35], v[136:139], v[202:205], 0
	v_mfma_f32_16x16x32_bf16 v[8:11], v[128:131], v[210:213], 0
	v_mfma_f32_16x16x32_bf16 v[16:19], v[136:139], v[210:213], 0
	v_mfma_f32_16x16x32_bf16 v[60:63], v[132:135], v[190:193], v[60:63]
	v_mfma_f32_16x16x32_bf16 v[56:59], v[140:143], v[190:193], v[56:59]
	v_mfma_f32_16x16x32_bf16 v[40:43], v[132:135], v[198:201], v[40:43]
	v_mfma_f32_16x16x32_bf16 v[48:51], v[140:143], v[198:201], v[48:51]
	v_mfma_f32_16x16x32_bf16 v[24:27], v[132:135], v[206:209], v[24:27]
	v_mfma_f32_16x16x32_bf16 v[32:35], v[140:143], v[206:209], v[32:35]
	v_mfma_f32_16x16x32_bf16 v[8:11], v[132:135], v[214:217], v[8:11]
	v_mfma_f32_16x16x32_bf16 v[16:19], v[140:143], v[214:217], v[16:19]
	v_mfma_f32_16x16x32_bf16 v[44:47], v[162:165], v[186:189], 0
	v_mfma_f32_16x16x32_bf16 v[52:55], v[178:181], v[186:189], 0
	v_mfma_f32_16x16x32_bf16 v[28:31], v[162:165], v[194:197], 0
	v_mfma_f32_16x16x32_bf16 v[36:39], v[178:181], v[194:197], 0
	v_mfma_f32_16x16x32_bf16 v[12:15], v[162:165], v[202:205], 0
	v_mfma_f32_16x16x32_bf16 v[20:23], v[178:181], v[202:205], 0
	v_mfma_f32_16x16x32_bf16 v[4:7], v[162:165], v[210:213], 0
	v_mfma_f32_16x16x32_bf16 v[0:3], v[178:181], v[210:213], 0
	v_mfma_f32_16x16x32_bf16 v[44:47], v[174:177], v[190:193], v[44:47]
	v_mfma_f32_16x16x32_bf16 v[52:55], v[182:185], v[190:193], v[52:55]
	v_mfma_f32_16x16x32_bf16 v[28:31], v[174:177], v[198:201], v[28:31]
	v_mfma_f32_16x16x32_bf16 v[36:39], v[182:185], v[198:201], v[36:39]
	v_mfma_f32_16x16x32_bf16 v[12:15], v[174:177], v[206:209], v[12:15]
	v_mfma_f32_16x16x32_bf16 v[20:23], v[182:185], v[206:209], v[20:23]
	v_mfma_f32_16x16x32_bf16 v[4:7], v[174:177], v[214:217], v[4:7]
	v_mfma_f32_16x16x32_bf16 v[0:3], v[182:185], v[214:217], v[0:3]
	s_setprio 0
	s_barrier
	s_add_i32 s67, 0, 0x18000
	s_add_i32 s68, 0, 0x1c000
	v_add_u32_e32 v140, s67, v168
	v_add_u32_e32 v173, s68, v168
	ds_read_b128 v[128:131], v140
	ds_read_b128 v[132:135], v140 offset:1024
	ds_read_b128 v[136:139], v140 offset:2048
	ds_read_b128 v[140:143], v140 offset:3072
	ds_read_b128 v[162:165], v173
	ds_read_b128 v[174:177], v173 offset:1024
	ds_read_b128 v[178:181], v173 offset:2048
	ds_read_b128 v[182:185], v173 offset:3072
	s_add_u32 s26, s30, 0x158000
	s_addc_u32 s27, s31, 0
	s_mov_b32 m0, s42
	v_lshl_add_u64 v[224:225], s[26:27], 0, v[144:145]
	ds_read_b128 v[186:189], v172 offset:32768
	ds_read_b128 v[190:193], v172 offset:33792
	ds_read_b128 v[194:197], v172 offset:34816
	ds_read_b128 v[198:201], v172 offset:35840
	ds_read_b128 v[202:205], v172 offset:36864
	ds_read_b128 v[206:209], v172 offset:37888
	ds_read_b128 v[210:213], v172 offset:38912
	ds_read_b128 v[214:217], v172 offset:39936
	global_load_lds_dwordx4 v[224:225], off
	v_lshl_add_u64 v[224:225], s[26:27], 0, v[148:149]
	s_mov_b32 m0, s43
	s_nop 0
	global_load_lds_dwordx4 v[224:225], off
	s_waitcnt vmcnt(8)
	s_waitcnt lgkmcnt(0)
	s_barrier
	s_setprio 1
	v_mfma_f32_16x16x32_bf16 v[124:127], v[128:131], v[186:189], v[124:127]
	v_mfma_f32_16x16x32_bf16 v[120:123], v[136:139], v[186:189], v[120:123]
	v_mfma_f32_16x16x32_bf16 v[104:107], v[128:131], v[194:197], v[104:107]
	v_mfma_f32_16x16x32_bf16 v[108:111], v[136:139], v[194:197], v[108:111]
	v_mfma_f32_16x16x32_bf16 v[88:91], v[128:131], v[202:205], v[88:91]
	v_mfma_f32_16x16x32_bf16 v[92:95], v[136:139], v[202:205], v[92:95]
	v_mfma_f32_16x16x32_bf16 v[72:75], v[128:131], v[210:213], v[72:75]
	v_mfma_f32_16x16x32_bf16 v[76:79], v[136:139], v[210:213], v[76:79]
	v_mfma_f32_16x16x32_bf16 v[124:127], v[132:135], v[190:193], v[124:127]
	v_mfma_f32_16x16x32_bf16 v[120:123], v[140:143], v[190:193], v[120:123]
	v_mfma_f32_16x16x32_bf16 v[104:107], v[132:135], v[198:201], v[104:107]
	v_mfma_f32_16x16x32_bf16 v[108:111], v[140:143], v[198:201], v[108:111]
	v_mfma_f32_16x16x32_bf16 v[88:91], v[132:135], v[206:209], v[88:91]
	v_mfma_f32_16x16x32_bf16 v[92:95], v[140:143], v[206:209], v[92:95]
	v_mfma_f32_16x16x32_bf16 v[72:75], v[132:135], v[214:217], v[72:75]
	v_mfma_f32_16x16x32_bf16 v[76:79], v[140:143], v[214:217], v[76:79]
	v_mfma_f32_16x16x32_bf16 v[112:115], v[162:165], v[186:189], v[112:115]
	v_mfma_f32_16x16x32_bf16 v[116:119], v[178:181], v[186:189], v[116:119]
	v_mfma_f32_16x16x32_bf16 v[96:99], v[162:165], v[194:197], v[96:99]
	v_mfma_f32_16x16x32_bf16 v[100:103], v[178:181], v[194:197], v[100:103]
	v_mfma_f32_16x16x32_bf16 v[80:83], v[162:165], v[202:205], v[80:83]
	v_mfma_f32_16x16x32_bf16 v[84:87], v[178:181], v[202:205], v[84:87]
	v_mfma_f32_16x16x32_bf16 v[64:67], v[162:165], v[210:213], v[64:67]
	v_mfma_f32_16x16x32_bf16 v[68:71], v[178:181], v[210:213], v[68:71]
	v_mfma_f32_16x16x32_bf16 v[112:115], v[174:177], v[190:193], v[112:115]
	v_mfma_f32_16x16x32_bf16 v[116:119], v[182:185], v[190:193], v[116:119]
	v_mfma_f32_16x16x32_bf16 v[96:99], v[174:177], v[198:201], v[96:99]
	v_mfma_f32_16x16x32_bf16 v[100:103], v[182:185], v[198:201], v[100:103]
	v_mfma_f32_16x16x32_bf16 v[80:83], v[174:177], v[206:209], v[80:83]
	v_mfma_f32_16x16x32_bf16 v[84:87], v[182:185], v[206:209], v[84:87]
	v_mfma_f32_16x16x32_bf16 v[64:67], v[174:177], v[214:217], v[64:67]
	v_mfma_f32_16x16x32_bf16 v[68:71], v[182:185], v[214:217], v[68:71]
	s_setprio 0
	s_barrier
; #define PG8_STAGE(bufoff, gbase, voff) do { _Pragma("unroll") for (int _i = 0; _i < 2; ++_i) \
;         __builtin_amdgcn_global_load_lds((const unsigned*)((const char*)(gbase) + (voff)[_i]), (PG8_LAS unsigned*)(lds + (bufoff) + ldsw + _i * 8192), 16, 0, 0); } while (0)
; #define PG8_LDA(dst, b, h) do { _Pragma("unroll") for (int m = 0; m < 4; ++m) _Pragma("unroll") for (int k = 0; k < 2; ++k) dst[m][k] = *(const PG8_LAS bf16x8*)(lds + PG8_SA(b, h) + aoff + m * 2048 + k * 1024); } while (0)
; #define PG8_LDB(dst, b, h) do { _Pragma("unroll") for (int n = 0; n < 2; ++n) _Pragma("unroll") for (int k = 0; k < 2; ++k) dst[n][k] = *(const PG8_LAS bf16x8*)(lds + PG8_SB(b, h) + boff + n * 2048 + k * 1024); } while (0)
; #define PG8_BAR __builtin_amdgcn_s_barrier()
; template <class Epi, class Sched, bool ALIGN_EPI = false, bool SP2 = false>
; __device__ __forceinline__ void gemm_phase(PG8_LAS unsigned char* lds, const Gemm g, const Sched& S, const Epi& E, const int wave_in) {
;     ...
;         for (int t = 0; t < nt; t += 2) {
;             const bool last = (t == nt - 2);
;             const char* a1 = cA + (size_t)(t + 1) * kstep;
;             const char* a2 = last ? nA : cA + (size_t)(t + 2) * kstep; const char* b2 = last ? nB : cB + (size_t)(t + 2) * kstep;
;             const char* a3 = a2 + kstep; const char* b3 = b2 + kstep;
;     ...
;             PG8_LDB(B0, 0, 0); PG8_LDB(B1, 0, 1); PG8_SCHED; PG8_LDA(At, 0, 0); PG8_STAGE(PG8_SA(1, 1), a1 + hstepA, voffA);
;             PG8_WAIT_V(8); PG8_WAIT_L(0); PG8_BAR; PG8_MMA(0, 0, At, B0); PG8_MMA(0, 1, At, B1); PG8_BAR; PG8_SCHED;
;             PG8_LDA(At, 0, 1); PG8_STAGE(PG8_SB(0, 0), b2, voffB); PG8_STAGE(PG8_SB(0, 1), b2 + hstepB, voffB); PG8_STAGE(PG8_SA(0, 0), a2, voffA);
;             PG8_WAIT_V(8); PG8_WAIT_L(0); PG8_BAR; PG8_MMA(1, 0, At, B0); PG8_MMA(1, 1, At, B1); PG8_BAR; PG8_SCHED;
;             PG8_LDB(B0, 1, 0); PG8_LDB(B1, 1, 1); PG8_SCHED; PG8_LDA(At, 1, 0); PG8_STAGE(PG8_SA(0, 1), a2 + hstepA, voffA);
;             PG8_WAIT_V(8); PG8_WAIT_L(0); PG8_BAR; PG8_MMA(0, 0, At, B0); PG8_MMA(0, 1, At, B1); PG8_BAR; PG8_SCHED;
;             PG8_LDA(At, 1, 1); PG8_STAGE(PG8_SB(1, 0), b3, voffB); PG8_STAGE(PG8_SB(1, 1), b3 + hstepB, voffB); PG8_STAGE(PG8_SA(1, 0), a3, voffA);
;             PG8_WAIT_V(8); PG8_WAIT_L(0); PG8_BAR; PG8_MMA(1, 0, At, B0); PG8_MMA(1, 1, At, B1); PG8_BAR; PG8_SCHED;
	s_add_i32 s26, s67, s39
	v_lshl_add_u64 v[166:167], v[166:167], 0, s[6:7]
	s_mov_b32 m0, s26
	ds_read_b128 v[186:189], v172 offset:49152
	ds_read_b128 v[190:193], v172 offset:50176
	ds_read_b128 v[194:197], v172 offset:51200
	ds_read_b128 v[198:201], v172 offset:52224
	ds_read_b128 v[202:205], v172 offset:53248
	ds_read_b128 v[206:209], v172 offset:54272
	ds_read_b128 v[210:213], v172 offset:55296
	ds_read_b128 v[214:217], v172 offset:56320
	global_load_lds_dwordx4 v[166:167], off
	s_add_i32 m0, s26, 0x2000
	s_add_u32 s26, s28, 0x158080
	v_lshl_add_u64 v[166:167], v[218:219], 0, s[6:7]
	s_addc_u32 s27, s29, 0
	s_add_i32 s28, s68, s39
	global_load_lds_dwordx4 v[166:167], off
	v_lshl_add_u64 v[166:167], s[26:27], 0, v[146:147]
	s_mov_b32 m0, s28
	s_nop 0
	global_load_lds_dwordx4 v[166:167], off
	v_lshl_add_u64 v[166:167], s[26:27], 0, v[150:151]
	s_add_i32 m0, s28, 0x2000
	s_nop 0
	global_load_lds_dwordx4 v[166:167], off
	v_lshl_add_u64 v[166:167], v[220:221], 0, s[6:7]
	s_mov_b32 m0, s48
	s_nop 0
	global_load_lds_dwordx4 v[166:167], off
	v_lshl_add_u64 v[166:167], v[222:223], 0, s[6:7]
	s_mov_b32 m0, s49
	s_nop 0
	global_load_lds_dwordx4 v[166:167], off
	s_waitcnt vmcnt(8)
	s_waitcnt lgkmcnt(0)
	s_barrier
	s_setprio 1
	v_mfma_f32_16x16x32_bf16 v[60:63], v[128:131], v[186:189], v[60:63]
	v_mfma_f32_16x16x32_bf16 v[56:59], v[136:139], v[186:189], v[56:59]
	v_mfma_f32_16x16x32_bf16 v[40:43], v[128:131], v[194:197], v[40:43]
	v_mfma_f32_16x16x32_bf16 v[48:51], v[136:139], v[194:197], v[48:51]
	v_mfma_f32_16x16x32_bf16 v[24:27], v[128:131], v[202:205], v[24:27]
	v_mfma_f32_16x16x32_bf16 v[32:35], v[136:139], v[202:205], v[32:35]
	v_mfma_f32_16x16x32_bf16 v[8:11], v[128:131], v[210:213], v[8:11]
	v_mfma_f32_16x16x32_bf16 v[16:19], v[136:139], v[210:213], v[16:19]
	v_mfma_f32_16x16x32_bf16 v[60:63], v[132:135], v[190:193], v[60:63]
	v_mfma_f32_16x16x32_bf16 v[56:59], v[140:143], v[190:193], v[56:59]
	v_mfma_f32_16x16x32_bf16 v[40:43], v[132:135], v[198:201], v[40:43]
	v_mfma_f32_16x16x32_bf16 v[48:51], v[140:143], v[198:201], v[48:51]
	v_mfma_f32_16x16x32_bf16 v[24:27], v[132:135], v[206:209], v[24:27]
	v_mfma_f32_16x16x32_bf16 v[32:35], v[140:143], v[206:209], v[32:35]
	v_mfma_f32_16x16x32_bf16 v[8:11], v[132:135], v[214:217], v[8:11]
	v_mfma_f32_16x16x32_bf16 v[16:19], v[140:143], v[214:217], v[16:19]
	v_mfma_f32_16x16x32_bf16 v[44:47], v[162:165], v[186:189], v[44:47]
	v_mfma_f32_16x16x32_bf16 v[52:55], v[178:181], v[186:189], v[52:55]
	v_mfma_f32_16x16x32_bf16 v[28:31], v[162:165], v[194:197], v[28:31]
	v_mfma_f32_16x16x32_bf16 v[36:39], v[178:181], v[194:197], v[36:39]
	v_mfma_f32_16x16x32_bf16 v[12:15], v[162:165], v[202:205], v[12:15]
	v_mfma_f32_16x16x32_bf16 v[20:23], v[178:181], v[202:205], v[20:23]
	v_mfma_f32_16x16x32_bf16 v[4:7], v[162:165], v[210:213], v[4:7]
	v_mfma_f32_16x16x32_bf16 v[0:3], v[178:181], v[210:213], v[0:3]
	v_mfma_f32_16x16x32_bf16 v[44:47], v[174:177], v[190:193], v[44:47]
	v_mfma_f32_16x16x32_bf16 v[52:55], v[182:185], v[190:193], v[52:55]
	v_mfma_f32_16x16x32_bf16 v[28:31], v[174:177], v[198:201], v[28:31]
	v_mfma_f32_16x16x32_bf16 v[36:39], v[182:185], v[198:201], v[36:39]
	v_mfma_f32_16x16x32_bf16 v[12:15], v[174:177], v[206:209], v[12:15]
	v_mfma_f32_16x16x32_bf16 v[20:23], v[182:185], v[206:209], v[20:23]
	v_mfma_f32_16x16x32_bf16 v[4:7], v[174:177], v[214:217], v[4:7]
	v_mfma_f32_16x16x32_bf16 v[0:3], v[182:185], v[214:217], v[0:3]
	s_setprio 0
	s_barrier
	s_add_i32 s66, s66, 2
	s_add_u32 s25, s25, 0x100
	s_addc_u32 s65, s65, 0
	s_cmpk_gt_u32 s66, 0x53
	s_mov_b64 s[26:27], s[2:3]
	s_cbranch_scc0 .LBB0_2741
	s_branch .Lkx_32
.LBB0_2741:
	ds_read_b128 v[128:131], v170
	ds_read_b128 v[132:135], v170 offset:1024
	ds_read_b128 v[136:139], v170 offset:2048
	ds_read_b128 v[140:143], v170 offset:3072
	ds_read_b128 v[162:165], v171
	ds_read_b128 v[174:177], v171 offset:1024
	ds_read_b128 v[178:181], v171 offset:2048
	ds_read_b128 v[182:185], v171 offset:3072
	s_add_u32 s2, s26, 0x100
	s_addc_u32 s3, s27, 0
	s_cmpk_eq_i32 s66, 0x52
	s_cselect_b32 s31, s21, s3
	s_cselect_b32 s30, s20, s2
	s_cselect_b32 s29, s23, s65
	s_cselect_b32 s28, s22, s25
	v_lshl_add_u64 v[166:167], s[26:27], 0, v[154:155]
	s_add_i32 m0, s40, 0xc000
	ds_read_b128 v[186:189], v172
	ds_read_b128 v[190:193], v172 offset:1024
	ds_read_b128 v[194:197], v172 offset:2048
	ds_read_b128 v[198:201], v172 offset:3072
	ds_read_b128 v[202:205], v172 offset:4096
	ds_read_b128 v[206:209], v172 offset:5120
	ds_read_b128 v[210:213], v172 offset:6144
	ds_read_b128 v[214:217], v172 offset:7168
	global_load_lds_dwordx4 v[166:167], off
	v_lshl_add_u64 v[166:167], s[26:27], 0, v[156:157]
	s_add_i32 m0, s40, 0xe000
	s_nop 0
	global_load_lds_dwordx4 v[166:167], off
	s_waitcnt vmcnt(8)
	s_waitcnt lgkmcnt(0)
	s_barrier
; #define PG8_STAGE(bufoff, gbase, voff) do { _Pragma("unroll") for (int _i = 0; _i < 2; ++_i) \
;         __builtin_amdgcn_global_load_lds((const unsigned*)((const char*)(gbase) + (voff)[_i]), (PG8_LAS unsigned*)(lds + (bufoff) + ldsw + _i * 8192), 16, 0, 0); } while (0)
; #define PG8_LDA(dst, b, h) do { _Pragma("unroll") for (int m = 0; m < 4; ++m) _Pragma("unroll") for (int k = 0; k < 2; ++k) dst[m][k] = *(const PG8_LAS bf16x8*)(lds + PG8_SA(b, h) + aoff + m * 2048 + k * 1024); } while (0)
; #define PG8_LDB(dst, b, h) do { _Pragma("unroll") for (int n = 0; n < 2; ++n) _Pragma("unroll") for (int k = 0; k < 2; ++k) dst[n][k] = *(const PG8_LAS bf16x8*)(lds + PG8_SB(b, h) + boff + n * 2048 + k * 1024); } while (0)
; #define PG8_MMA(ai, bj, At, Bt) do { __builtin_amdgcn_s_setprio(1); _Pragma("unroll") for (int m = 0; m < 4; ++m) _Pragma("unroll") for (int n = 0; n < 2; ++n) _Pragma("unroll") for (int k = 0; k < 2; ++k) \
;         acc[ai][bj][m][n] = __builtin_amdgcn_mfma_f32_16x16x32_bf16(Bt[n][k], At[m][k], acc[ai][bj][m][n], 0, 0, 0); __builtin_amdgcn_s_setprio(0); } while (0)
; #define PG8_BAR __builtin_amdgcn_s_barrier()
; template <class Epi, class Sched, bool ALIGN_EPI = false, bool SP2 = false>
; __device__ __forceinline__ void gemm_phase(PG8_LAS unsigned char* lds, const Gemm g, const Sched& S, const Epi& E, const int wave_in) {
;     ...
;             PG8_LDB(B0, 0, 0); PG8_LDB(B1, 0, 1); PG8_SCHED; PG8_LDA(At, 0, 0); PG8_STAGE(PG8_SA(1, 1), a1 + hstepA, voffA);
;             PG8_WAIT_V(8); PG8_WAIT_L(0); PG8_BAR; PG8_MMA(0, 0, At, B0); PG8_MMA(0, 1, At, B1); PG8_BAR; PG8_SCHED;
;             PG8_LDA(At, 0, 1); PG8_STAGE(PG8_SB(0, 0), b2, voffB); PG8_STAGE(PG8_SB(0, 1), b2 + hstepB, voffB); PG8_STAGE(PG8_SA(0, 0), a2, voffA);
;             PG8_WAIT_V(8); PG8_WAIT_L(0); PG8_BAR; PG8_MMA(1, 0, At, B0); PG8_MMA(1, 1, At, B1); PG8_BAR; PG8_SCHED;
;             PG8_LDB(B0, 1, 0); PG8_LDB(B1, 1, 1); PG8_SCHED; PG8_LDA(At, 1, 0); PG8_STAGE(PG8_SA(0, 1), a2 + hstepA, voffA);
;             PG8_WAIT_V(8); PG8_WAIT_L(0); PG8_BAR; PG8_MMA(0, 0, At, B0); PG8_MMA(0, 1, At, B1); PG8_BAR; PG8_SCHED;
;             PG8_LDA(At, 1, 1); PG8_STAGE(PG8_SB(1, 0), b3, voffB); PG8_STAGE(PG8_SB(1, 1), b3 + hstepB, voffB); PG8_STAGE(PG8_SA(1, 0), a3, voffA);
;             PG8_WAIT_V(8); PG8_WAIT_L(0); PG8_BAR; PG8_MMA(1, 0, At, B0); PG8_MMA(1, 1, At, B1); PG8_BAR; PG8_SCHED;
	s_setprio 1
	v_mfma_f32_16x16x32_bf16 v[124:127], v[128:131], v[186:189], v[124:127]
	v_mfma_f32_16x16x32_bf16 v[120:123], v[136:139], v[186:189], v[120:123]
	v_mfma_f32_16x16x32_bf16 v[104:107], v[128:131], v[194:197], v[104:107]
	v_mfma_f32_16x16x32_bf16 v[108:111], v[136:139], v[194:197], v[108:111]
	v_mfma_f32_16x16x32_bf16 v[88:91], v[128:131], v[202:205], v[88:91]
	v_mfma_f32_16x16x32_bf16 v[92:95], v[136:139], v[202:205], v[92:95]
	v_mfma_f32_16x16x32_bf16 v[72:75], v[128:131], v[210:213], v[72:75]
	v_mfma_f32_16x16x32_bf16 v[76:79], v[136:139], v[210:213], v[76:79]
	v_mfma_f32_16x16x32_bf16 v[124:127], v[132:135], v[190:193], v[124:127]
	v_mfma_f32_16x16x32_bf16 v[120:123], v[140:143], v[190:193], v[120:123]
	v_mfma_f32_16x16x32_bf16 v[104:107], v[132:135], v[198:201], v[104:107]
	v_mfma_f32_16x16x32_bf16 v[108:111], v[140:143], v[198:201], v[108:111]
	v_mfma_f32_16x16x32_bf16 v[88:91], v[132:135], v[206:209], v[88:91]
	v_mfma_f32_16x16x32_bf16 v[92:95], v[140:143], v[206:209], v[92:95]
	v_mfma_f32_16x16x32_bf16 v[72:75], v[132:135], v[214:217], v[72:75]
	v_mfma_f32_16x16x32_bf16 v[76:79], v[140:143], v[214:217], v[76:79]
	v_mfma_f32_16x16x32_bf16 v[112:115], v[162:165], v[186:189], v[112:115]
	v_mfma_f32_16x16x32_bf16 v[116:119], v[178:181], v[186:189], v[116:119]
	v_mfma_f32_16x16x32_bf16 v[96:99], v[162:165], v[194:197], v[96:99]
	v_mfma_f32_16x16x32_bf16 v[100:103], v[178:181], v[194:197], v[100:103]
	v_mfma_f32_16x16x32_bf16 v[80:83], v[162:165], v[202:205], v[80:83]
	v_mfma_f32_16x16x32_bf16 v[84:87], v[178:181], v[202:205], v[84:87]
	v_mfma_f32_16x16x32_bf16 v[64:67], v[162:165], v[210:213], v[64:67]
	v_mfma_f32_16x16x32_bf16 v[68:71], v[178:181], v[210:213], v[68:71]
	v_mfma_f32_16x16x32_bf16 v[112:115], v[174:177], v[190:193], v[112:115]
	v_mfma_f32_16x16x32_bf16 v[116:119], v[182:185], v[190:193], v[116:119]
	v_mfma_f32_16x16x32_bf16 v[96:99], v[174:177], v[198:201], v[96:99]
	v_mfma_f32_16x16x32_bf16 v[100:103], v[182:185], v[198:201], v[100:103]
	v_mfma_f32_16x16x32_bf16 v[80:83], v[174:177], v[206:209], v[80:83]
	v_mfma_f32_16x16x32_bf16 v[84:87], v[182:185], v[206:209], v[84:87]
	v_mfma_f32_16x16x32_bf16 v[64:67], v[174:177], v[214:217], v[64:67]
	v_mfma_f32_16x16x32_bf16 v[68:71], v[182:185], v[214:217], v[68:71]
	s_setprio 0
	s_barrier
	s_add_i32 s26, s50, s39
	v_lshl_add_u64 v[166:167], s[28:29], 0, v[146:147]
	s_mov_b32 m0, s26
	ds_read_b128 v[186:189], v172 offset:16384
	ds_read_b128 v[190:193], v172 offset:17408
	ds_read_b128 v[194:197], v172 offset:18432
	ds_read_b128 v[198:201], v172 offset:19456
	ds_read_b128 v[202:205], v172 offset:20480
	ds_read_b128 v[206:209], v172 offset:21504
	ds_read_b128 v[210:213], v172 offset:22528
	ds_read_b128 v[214:217], v172 offset:23552
	global_load_lds_dwordx4 v[166:167], off
	s_add_i32 m0, s26, 0x2000
	s_add_u32 s26, s28, 0x158000
	v_lshl_add_u64 v[218:219], s[28:29], 0, v[150:151]
	s_addc_u32 s27, s29, 0
	s_add_i32 s67, s51, s39
	global_load_lds_dwordx4 v[218:219], off
	v_lshl_add_u64 v[220:221], s[26:27], 0, v[146:147]
	s_mov_b32 m0, s67
	v_lshl_add_u64 v[222:223], s[30:31], 0, v[148:149]
	global_load_lds_dwordx4 v[220:221], off
	v_lshl_add_u64 v[220:221], s[26:27], 0, v[150:151]
	s_add_i32 m0, s67, 0x2000
	s_nop 0
	global_load_lds_dwordx4 v[220:221], off
	v_lshl_add_u64 v[220:221], s[30:31], 0, v[144:145]
	s_mov_b32 m0, s40
	s_nop 0
	global_load_lds_dwordx4 v[220:221], off
	s_mov_b32 m0, s41
	s_nop 0
	global_load_lds_dwordx4 v[222:223], off
	s_waitcnt vmcnt(8)
	s_waitcnt lgkmcnt(0)
	s_barrier
	s_setprio 1
	v_mfma_f32_16x16x32_bf16 v[60:63], v[128:131], v[186:189], v[60:63]
	v_mfma_f32_16x16x32_bf16 v[56:59], v[136:139], v[186:189], v[56:59]
	v_mfma_f32_16x16x32_bf16 v[40:43], v[128:131], v[194:197], v[40:43]
	v_mfma_f32_16x16x32_bf16 v[48:51], v[136:139], v[194:197], v[48:51]
	v_mfma_f32_16x16x32_bf16 v[24:27], v[128:131], v[202:205], v[24:27]
	v_mfma_f32_16x16x32_bf16 v[32:35], v[136:139], v[202:205], v[32:35]
	v_mfma_f32_16x16x32_bf16 v[8:11], v[128:131], v[210:213], v[8:11]
	v_mfma_f32_16x16x32_bf16 v[16:19], v[136:139], v[210:213], v[16:19]
	v_mfma_f32_16x16x32_bf16 v[60:63], v[132:135], v[190:193], v[60:63]
	v_mfma_f32_16x16x32_bf16 v[56:59], v[140:143], v[190:193], v[56:59]
	v_mfma_f32_16x16x32_bf16 v[40:43], v[132:135], v[198:201], v[40:43]
	v_mfma_f32_16x16x32_bf16 v[48:51], v[140:143], v[198:201], v[48:51]
	v_mfma_f32_16x16x32_bf16 v[24:27], v[132:135], v[206:209], v[24:27]
	v_mfma_f32_16x16x32_bf16 v[32:35], v[140:143], v[206:209], v[32:35]
	v_mfma_f32_16x16x32_bf16 v[8:11], v[132:135], v[214:217], v[8:11]
	v_mfma_f32_16x16x32_bf16 v[16:19], v[140:143], v[214:217], v[16:19]
	v_mfma_f32_16x16x32_bf16 v[44:47], v[162:165], v[186:189], v[44:47]
	v_mfma_f32_16x16x32_bf16 v[52:55], v[178:181], v[186:189], v[52:55]
	v_mfma_f32_16x16x32_bf16 v[28:31], v[162:165], v[194:197], v[28:31]
	v_mfma_f32_16x16x32_bf16 v[36:39], v[178:181], v[194:197], v[36:39]
	v_mfma_f32_16x16x32_bf16 v[12:15], v[162:165], v[202:205], v[12:15]
	v_mfma_f32_16x16x32_bf16 v[20:23], v[178:181], v[202:205], v[20:23]
	v_mfma_f32_16x16x32_bf16 v[4:7], v[162:165], v[210:213], v[4:7]
	v_mfma_f32_16x16x32_bf16 v[0:3], v[178:181], v[210:213], v[0:3]
	v_mfma_f32_16x16x32_bf16 v[44:47], v[174:177], v[190:193], v[44:47]
	v_mfma_f32_16x16x32_bf16 v[52:55], v[182:185], v[190:193], v[52:55]
	v_mfma_f32_16x16x32_bf16 v[28:31], v[174:177], v[198:201], v[28:31]
	v_mfma_f32_16x16x32_bf16 v[36:39], v[182:185], v[198:201], v[36:39]
	v_mfma_f32_16x16x32_bf16 v[12:15], v[174:177], v[206:209], v[12:15]
	v_mfma_f32_16x16x32_bf16 v[20:23], v[182:185], v[206:209], v[20:23]
	v_mfma_f32_16x16x32_bf16 v[4:7], v[174:177], v[214:217], v[4:7]
	v_mfma_f32_16x16x32_bf16 v[0:3], v[182:185], v[214:217], v[0:3]
	s_setprio 0
	s_barrier
; #define PG8_STAGE(bufoff, gbase, voff) do { _Pragma("unroll") for (int _i = 0; _i < 2; ++_i) \
;         __builtin_amdgcn_global_load_lds((const unsigned*)((const char*)(gbase) + (voff)[_i]), (PG8_LAS unsigned*)(lds + (bufoff) + ldsw + _i * 8192), 16, 0, 0); } while (0)
; #define PG8_LDA(dst, b, h) do { _Pragma("unroll") for (int m = 0; m < 4; ++m) _Pragma("unroll") for (int k = 0; k < 2; ++k) dst[m][k] = *(const PG8_LAS bf16x8*)(lds + PG8_SA(b, h) + aoff + m * 2048 + k * 1024); } while (0)
; #define PG8_LDB(dst, b, h) do { _Pragma("unroll") for (int n = 0; n < 2; ++n) _Pragma("unroll") for (int k = 0; k < 2; ++k) dst[n][k] = *(const PG8_LAS bf16x8*)(lds + PG8_SB(b, h) + boff + n * 2048 + k * 1024); } while (0)
; #define PG8_WAIT_V(n) asm volatile("s_waitcnt vmcnt(" #n ")" ::: "memory")
; #define PG8_WAIT_L(n) asm volatile("s_waitcnt lgkmcnt(" #n ")" ::: "memory")
; #define PG8_BAR __builtin_amdgcn_s_barrier()
; #define PG8_SCHED __builtin_amdgcn_sched_barrier(0)
; template <class Epi, class Sched, bool ALIGN_EPI = false, bool SP2 = false>
; __device__ __forceinline__ void gemm_phase(PG8_LAS unsigned char* lds, const Gemm g, const Sched& S, const Epi& E, const int wave_in) {
;     ...
;         for (int t = 0; t < nt; t += 2) {
;             const bool last = (t == nt - 2);
;             const char* a1 = cA + (size_t)(t + 1) * kstep;
;             const char* a2 = last ? nA : cA + (size_t)(t + 2) * kstep; const char* b2 = last ? nB : cB + (size_t)(t + 2) * kstep;
;             const char* a3 = a2 + kstep; const char* b3 = b2 + kstep;
;     ...
;             PG8_LDA(At, 0, 1); PG8_STAGE(PG8_SB(0, 0), b2, voffB); PG8_STAGE(PG8_SB(0, 1), b2 + hstepB, voffB); PG8_STAGE(PG8_SA(0, 0), a2, voffA);
;             PG8_WAIT_V(8); PG8_WAIT_L(0); PG8_BAR; PG8_MMA(1, 0, At, B0); PG8_MMA(1, 1, At, B1); PG8_BAR; PG8_SCHED;
;             PG8_LDB(B0, 1, 0); PG8_LDB(B1, 1, 1); PG8_SCHED; PG8_LDA(At, 1, 0); PG8_STAGE(PG8_SA(0, 1), a2 + hstepA, voffA);
;             PG8_WAIT_V(8); PG8_WAIT_L(0); PG8_BAR; PG8_MMA(0, 0, At, B0); PG8_MMA(0, 1, At, B1); PG8_BAR; PG8_SCHED;
;             PG8_LDA(At, 1, 1); PG8_STAGE(PG8_SB(1, 0), b3, voffB); PG8_STAGE(PG8_SB(1, 1), b3 + hstepB, voffB); PG8_STAGE(PG8_SA(1, 0), a3, voffA);
;             PG8_WAIT_V(8); PG8_WAIT_L(0); PG8_BAR; PG8_MMA(1, 0, At, B0); PG8_MMA(1, 1, At, B1); PG8_BAR; PG8_SCHED;
	s_add_i32 s67, 0, 0x18000
	s_add_i32 s68, 0, 0x1c000
	v_add_u32_e32 v140, s67, v168
	v_add_u32_e32 v173, s68, v168
	ds_read_b128 v[128:131], v140
	ds_read_b128 v[132:135], v140 offset:1024
	ds_read_b128 v[136:139], v140 offset:2048
	ds_read_b128 v[140:143], v140 offset:3072
	ds_read_b128 v[162:165], v173
	ds_read_b128 v[174:177], v173 offset:1024
	ds_read_b128 v[178:181], v173 offset:2048
	ds_read_b128 v[182:185], v173 offset:3072
	s_add_u32 s26, s30, 0x158000
	s_addc_u32 s27, s31, 0
	s_mov_b32 m0, s42
	v_lshl_add_u64 v[224:225], s[26:27], 0, v[144:145]
	ds_read_b128 v[186:189], v172 offset:32768
	ds_read_b128 v[190:193], v172 offset:33792
	ds_read_b128 v[194:197], v172 offset:34816
	ds_read_b128 v[198:201], v172 offset:35840
	ds_read_b128 v[202:205], v172 offset:36864
	ds_read_b128 v[206:209], v172 offset:37888
	ds_read_b128 v[210:213], v172 offset:38912
	ds_read_b128 v[214:217], v172 offset:39936
	global_load_lds_dwordx4 v[224:225], off
	v_lshl_add_u64 v[224:225], s[26:27], 0, v[148:149]
	s_mov_b32 m0, s43
	s_nop 0
	global_load_lds_dwordx4 v[224:225], off
	s_waitcnt vmcnt(8)
	s_waitcnt lgkmcnt(0)
	s_barrier
	s_setprio 1
	v_mfma_f32_16x16x32_bf16 v[124:127], v[128:131], v[186:189], v[124:127]
	v_mfma_f32_16x16x32_bf16 v[120:123], v[136:139], v[186:189], v[120:123]
	v_mfma_f32_16x16x32_bf16 v[104:107], v[128:131], v[194:197], v[104:107]
	v_mfma_f32_16x16x32_bf16 v[108:111], v[136:139], v[194:197], v[108:111]
	v_mfma_f32_16x16x32_bf16 v[88:91], v[128:131], v[202:205], v[88:91]
	v_mfma_f32_16x16x32_bf16 v[92:95], v[136:139], v[202:205], v[92:95]
	v_mfma_f32_16x16x32_bf16 v[72:75], v[128:131], v[210:213], v[72:75]
	v_mfma_f32_16x16x32_bf16 v[76:79], v[136:139], v[210:213], v[76:79]
	v_mfma_f32_16x16x32_bf16 v[124:127], v[132:135], v[190:193], v[124:127]
	v_mfma_f32_16x16x32_bf16 v[120:123], v[140:143], v[190:193], v[120:123]
	v_mfma_f32_16x16x32_bf16 v[104:107], v[132:135], v[198:201], v[104:107]
	v_mfma_f32_16x16x32_bf16 v[108:111], v[140:143], v[198:201], v[108:111]
	v_mfma_f32_16x16x32_bf16 v[88:91], v[132:135], v[206:209], v[88:91]
	v_mfma_f32_16x16x32_bf16 v[92:95], v[140:143], v[206:209], v[92:95]
	v_mfma_f32_16x16x32_bf16 v[72:75], v[132:135], v[214:217], v[72:75]
	v_mfma_f32_16x16x32_bf16 v[76:79], v[140:143], v[214:217], v[76:79]
	v_mfma_f32_16x16x32_bf16 v[112:115], v[162:165], v[186:189], v[112:115]
	v_mfma_f32_16x16x32_bf16 v[116:119], v[178:181], v[186:189], v[116:119]
	v_mfma_f32_16x16x32_bf16 v[96:99], v[162:165], v[194:197], v[96:99]
	v_mfma_f32_16x16x32_bf16 v[100:103], v[178:181], v[194:197], v[100:103]
	v_mfma_f32_16x16x32_bf16 v[80:83], v[162:165], v[202:205], v[80:83]
	v_mfma_f32_16x16x32_bf16 v[84:87], v[178:181], v[202:205], v[84:87]
	v_mfma_f32_16x16x32_bf16 v[64:67], v[162:165], v[210:213], v[64:67]
	v_mfma_f32_16x16x32_bf16 v[68:71], v[178:181], v[210:213], v[68:71]
	v_mfma_f32_16x16x32_bf16 v[112:115], v[174:177], v[190:193], v[112:115]
	v_mfma_f32_16x16x32_bf16 v[116:119], v[182:185], v[190:193], v[116:119]
	v_mfma_f32_16x16x32_bf16 v[96:99], v[174:177], v[198:201], v[96:99]
	v_mfma_f32_16x16x32_bf16 v[100:103], v[182:185], v[198:201], v[100:103]
	v_mfma_f32_16x16x32_bf16 v[80:83], v[174:177], v[206:209], v[80:83]
	v_mfma_f32_16x16x32_bf16 v[84:87], v[182:185], v[206:209], v[84:87]
	v_mfma_f32_16x16x32_bf16 v[64:67], v[174:177], v[214:217], v[64:67]
	v_mfma_f32_16x16x32_bf16 v[68:71], v[182:185], v[214:217], v[68:71]
	s_setprio 0
	s_barrier
	s_add_i32 s26, s67, s39
	v_lshl_add_u64 v[166:167], v[166:167], 0, s[6:7]
	s_mov_b32 m0, s26
	ds_read_b128 v[186:189], v172 offset:49152
	ds_read_b128 v[190:193], v172 offset:50176
	ds_read_b128 v[194:197], v172 offset:51200
	ds_read_b128 v[198:201], v172 offset:52224
	ds_read_b128 v[202:205], v172 offset:53248
	ds_read_b128 v[206:209], v172 offset:54272
	ds_read_b128 v[210:213], v172 offset:55296
	ds_read_b128 v[214:217], v172 offset:56320
	global_load_lds_dwordx4 v[166:167], off
	s_add_i32 m0, s26, 0x2000
	s_add_u32 s26, s28, 0x158080
	v_lshl_add_u64 v[166:167], v[218:219], 0, s[6:7]
	s_addc_u32 s27, s29, 0
	s_add_i32 s28, s68, s39
	global_load_lds_dwordx4 v[166:167], off
	v_lshl_add_u64 v[166:167], s[26:27], 0, v[146:147]
	s_mov_b32 m0, s28
	s_nop 0
	global_load_lds_dwordx4 v[166:167], off
	v_lshl_add_u64 v[166:167], s[26:27], 0, v[150:151]
	s_add_i32 m0, s28, 0x2000
	s_nop 0
	global_load_lds_dwordx4 v[166:167], off
	v_lshl_add_u64 v[166:167], v[220:221], 0, s[6:7]
	s_mov_b32 m0, s48
	s_nop 0
	global_load_lds_dwordx4 v[166:167], off
	v_lshl_add_u64 v[166:167], v[222:223], 0, s[6:7]
	s_mov_b32 m0, s49
	s_nop 0
	global_load_lds_dwordx4 v[166:167], off
	s_waitcnt vmcnt(8)
	s_waitcnt lgkmcnt(0)
	s_barrier
	s_setprio 1
	v_mfma_f32_16x16x32_bf16 v[60:63], v[128:131], v[186:189], v[60:63]
	v_mfma_f32_16x16x32_bf16 v[56:59], v[136:139], v[186:189], v[56:59]
	v_mfma_f32_16x16x32_bf16 v[40:43], v[128:131], v[194:197], v[40:43]
	v_mfma_f32_16x16x32_bf16 v[48:51], v[136:139], v[194:197], v[48:51]
	v_mfma_f32_16x16x32_bf16 v[24:27], v[128:131], v[202:205], v[24:27]
	v_mfma_f32_16x16x32_bf16 v[32:35], v[136:139], v[202:205], v[32:35]
	v_mfma_f32_16x16x32_bf16 v[8:11], v[128:131], v[210:213], v[8:11]
	v_mfma_f32_16x16x32_bf16 v[16:19], v[136:139], v[210:213], v[16:19]
	v_mfma_f32_16x16x32_bf16 v[60:63], v[132:135], v[190:193], v[60:63]
	v_mfma_f32_16x16x32_bf16 v[56:59], v[140:143], v[190:193], v[56:59]
	v_mfma_f32_16x16x32_bf16 v[40:43], v[132:135], v[198:201], v[40:43]
	v_mfma_f32_16x16x32_bf16 v[48:51], v[140:143], v[198:201], v[48:51]
	v_mfma_f32_16x16x32_bf16 v[24:27], v[132:135], v[206:209], v[24:27]
	v_mfma_f32_16x16x32_bf16 v[32:35], v[140:143], v[206:209], v[32:35]
	v_mfma_f32_16x16x32_bf16 v[8:11], v[132:135], v[214:217], v[8:11]
	v_mfma_f32_16x16x32_bf16 v[16:19], v[140:143], v[214:217], v[16:19]
	v_mfma_f32_16x16x32_bf16 v[44:47], v[162:165], v[186:189], v[44:47]
	v_mfma_f32_16x16x32_bf16 v[52:55], v[178:181], v[186:189], v[52:55]
	v_mfma_f32_16x16x32_bf16 v[28:31], v[162:165], v[194:197], v[28:31]
	v_mfma_f32_16x16x32_bf16 v[36:39], v[178:181], v[194:197], v[36:39]
	v_mfma_f32_16x16x32_bf16 v[12:15], v[162:165], v[202:205], v[12:15]
	v_mfma_f32_16x16x32_bf16 v[20:23], v[178:181], v[202:205], v[20:23]
	v_mfma_f32_16x16x32_bf16 v[4:7], v[162:165], v[210:213], v[4:7]
	v_mfma_f32_16x16x32_bf16 v[0:3], v[178:181], v[210:213], v[0:3]
	v_mfma_f32_16x16x32_bf16 v[44:47], v[174:177], v[190:193], v[44:47]
	v_mfma_f32_16x16x32_bf16 v[52:55], v[182:185], v[190:193], v[52:55]
	v_mfma_f32_16x16x32_bf16 v[28:31], v[174:177], v[198:201], v[28:31]
	v_mfma_f32_16x16x32_bf16 v[36:39], v[182:185], v[198:201], v[36:39]
	v_mfma_f32_16x16x32_bf16 v[12:15], v[174:177], v[206:209], v[12:15]
	v_mfma_f32_16x16x32_bf16 v[20:23], v[182:185], v[206:209], v[20:23]
	v_mfma_f32_16x16x32_bf16 v[4:7], v[174:177], v[214:217], v[4:7]
	v_mfma_f32_16x16x32_bf16 v[0:3], v[182:185], v[214:217], v[0:3]
	s_setprio 0
	s_barrier
	s_add_i32 s66, s66, 2
	s_add_u32 s25, s25, 0x100
	s_addc_u32 s65, s65, 0
	s_cmpk_gt_u32 s66, 0x53
	s_mov_b64 s[26:27], s[2:3]
	s_cbranch_scc0 .LBB0_2741
